# all memory-op hoisting regenerated with hazard/wait-order fixes; 2 grid barriers removed (same-WG dependency); epilogue load batching
# speedup vs baseline: 1.0248x; 1.0154x over previous
.LBB0_14:
	s_mov_b32 s10, 0x78787879
	v_mul_hi_i32 v3, v2, s10
	v_ashrrev_i32_e32 v4, 3, v3
	v_lshrrev_b32_e32 v5, 31, v3
	v_ashrrev_i32_e32 v3, 9, v3
	v_add_u32_e32 v3, v3, v5
	v_add_u32_e32 v8, v4, v5
	v_lshl_or_b32 v4, v3, 7, s75
	v_ashrrev_i32_e32 v5, 31, v4
	v_lshl_add_u64 v[148:149], v[4:5], 2, s[26:27]
	global_load_dword v3, v[148:149], off
	v_ashrrev_i32_e32 v5, 31, v8
	v_lshrrev_b32_e32 v5, 26, v5
	v_add_u32_e32 v5, v8, v5
	v_and_b32_e32 v5, 0xffffffc0, v5
	v_sub_u32_e32 v5, v8, v5
	v_lshl_add_u32 v4, v4, 6, v5
	v_ashrrev_i32_e32 v5, 31, v4
	v_lshlrev_b64 v[4:5], 2, v[4:5]
	v_lshl_add_u64 v[148:149], s[24:25], 0, v[4:5]
	global_load_dword v150, v[148:149], off
	v_lshl_add_u64 v[4:5], s[22:23], 0, v[4:5]
	global_load_dword v5, v[4:5], off
	s_movk_i32 s10, 0xffef
	s_waitcnt vmcnt(2)
	v_mad_u64_u32 v[6:7], s[10:11], v8, s10, v[2:3]
	v_mul_f32_e32 v4, 0x3fb8aa3b, v3
	v_fma_f32 v7, v3, s40, -v4
	v_rndne_f32_e32 v8, v4
	v_fmac_f32_e32 v7, 0x32a5705f, v3
	v_sub_f32_e32 v4, v4, v8
	v_add_f32_e32 v4, v4, v7
	v_cvt_i32_f32_e32 v8, v8
	v_exp_f32_e32 v4, v4
	v_cvt_f32_i32_e32 v6, v6
	v_cmp_ngt_f32_e32 vcc, s41, v3
	v_ldexp_f32 v4, v4, v8
	s_nop 0
	v_cndmask_b32_e32 v4, 0, v4, vcc
	v_cmp_nlt_f32_e32 vcc, s42, v3
	s_waitcnt vmcnt(1)
	v_mul_f32_e32 v9, v150, v6
	v_cndmask_b32_e32 v7, v69, v4, vcc
	v_mul_f32_e32 v3, v7, v9
	v_and_b32_e32 v4, 0x7fffffff, v3
	v_cmp_nlt_f32_e64 s[10:11], |v3|, s43
	s_and_saveexec_b64 s[12:13], s[10:11]
	s_xor_b64 s[34:35], exec, s[12:13]
	s_cbranch_execz .LBB0_16
	v_lshrrev_b32_e32 v8, 23, v4
	v_add_u32_e32 v8, 0xffffff88, v8
	v_cmp_lt_u32_e32 vcc, 63, v8
	v_mov_b32_e32 v11, v0
	v_mov_b32_e32 v13, v0
	v_cndmask_b32_e32 v9, 0, v70, vcc
	v_add_u32_e32 v8, v9, v8
	v_cmp_lt_u32_e64 s[10:11], 31, v8
	v_mov_b32_e32 v15, v0
	v_mov_b32_e32 v17, v0
	v_cndmask_b32_e64 v9, 0, v71, s[10:11]
	v_add_u32_e32 v8, v9, v8
	v_cmp_lt_u32_e64 s[12:13], 31, v8
	v_mov_b32_e32 v19, v0
	v_mov_b32_e32 v21, v0
	v_cndmask_b32_e64 v9, 0, v71, s[12:13]
	v_add_u32_e32 v22, v9, v8
	v_and_b32_e32 v8, 0x7fffff, v4
	v_or_b32_e32 v23, 0x800000, v8
	v_mad_u64_u32 v[8:9], s[14:15], v23, s60, 0
	v_mov_b32_e32 v10, v9
	v_mad_u64_u32 v[10:11], s[14:15], v23, s61, v[10:11]
	v_mov_b32_e32 v12, v11
	v_mad_u64_u32 v[12:13], s[14:15], v23, s62, v[12:13]
	v_mov_b32_e32 v14, v13
	v_mad_u64_u32 v[14:15], s[14:15], v23, s63, v[14:15]
	v_mov_b32_e32 v16, v15
	v_mad_u64_u32 v[16:17], s[14:15], v23, s64, v[16:17]
	v_mov_b32_e32 v18, v17
	v_mad_u64_u32 v[18:19], s[14:15], v23, s65, v[18:19]
	v_mov_b32_e32 v20, v19
	v_mad_u64_u32 v[20:21], s[14:15], v23, s66, v[20:21]
	v_cndmask_b32_e32 v9, v18, v14, vcc
	v_cndmask_b32_e32 v11, v20, v16, vcc
	v_cndmask_b32_e32 v15, v21, v18, vcc
	v_cndmask_b32_e64 v13, v11, v9, s[10:11]
	v_cndmask_b32_e64 v11, v15, v11, s[10:11]
	v_cndmask_b32_e32 v15, v16, v12, vcc
	v_cndmask_b32_e64 v9, v9, v15, s[10:11]
	v_cndmask_b32_e32 v10, v14, v10, vcc
	v_cndmask_b32_e64 v11, v11, v13, s[12:13]
	v_cndmask_b32_e64 v13, v13, v9, s[12:13]
	v_sub_u32_e32 v16, 32, v22
	v_cndmask_b32_e64 v14, v15, v10, s[10:11]
	v_alignbit_b32 v17, v11, v13, v16
	v_cmp_eq_u32_e64 s[14:15], 0, v22
	v_cndmask_b32_e64 v9, v9, v14, s[12:13]
	v_alignbit_b32 v15, v13, v9, v16
	v_cndmask_b32_e64 v11, v17, v11, s[14:15]
	v_cndmask_b32_e32 v8, v12, v8, vcc
	v_cndmask_b32_e64 v13, v15, v13, s[14:15]
	v_bfe_u32 v18, v11, 29, 1
	v_cndmask_b32_e64 v8, v10, v8, s[10:11]
	v_alignbit_b32 v15, v11, v13, 30
	v_sub_u32_e32 v19, 0, v18
	v_cndmask_b32_e64 v8, v14, v8, s[12:13]
	v_xor_b32_e32 v15, v15, v19
	v_alignbit_b32 v10, v9, v8, v16
	v_cndmask_b32_e64 v9, v10, v9, s[14:15]
	v_ffbh_u32_e32 v12, v15
	v_alignbit_b32 v10, v13, v9, 30
	v_min_u32_e32 v12, 32, v12
	v_alignbit_b32 v8, v9, v8, 30
	v_xor_b32_e32 v10, v10, v19
	v_sub_u32_e32 v13, 31, v12
	v_xor_b32_e32 v8, v8, v19
	v_alignbit_b32 v14, v15, v10, v13
	v_alignbit_b32 v8, v10, v8, v13
	v_alignbit_b32 v9, v14, v8, 9
	v_ffbh_u32_e32 v10, v9
	v_min_u32_e32 v10, 32, v10
	v_lshrrev_b32_e32 v17, 29, v11
	v_not_b32_e32 v13, v10
	v_alignbit_b32 v8, v9, v8, v13
	v_lshlrev_b32_e32 v9, 31, v17
	v_or_b32_e32 v13, 0x33000000, v9
	v_add_lshl_u32 v10, v10, v12, 23
	v_lshrrev_b32_e32 v8, 9, v8
	v_sub_u32_e32 v10, v13, v10
	v_or_b32_e32 v9, 0.5, v9
	v_lshlrev_b32_e32 v12, 23, v12
	v_or_b32_e32 v8, v10, v8
	v_lshrrev_b32_e32 v10, 9, v14
	v_sub_u32_e32 v9, v9, v12
	v_or_b32_e32 v9, v10, v9
	v_mul_f32_e32 v10, 0x3fc90fda, v9
	v_fma_f32 v12, v9, s67, -v10
	v_fmac_f32_e32 v12, 0x33a22168, v9
	v_fmac_f32_e32 v12, 0x3fc90fda, v8
	v_lshrrev_b32_e32 v9, 30, v11
	v_add_f32_e32 v8, v10, v12
	v_add_u32_e32 v9, v18, v9

.LBB0_21:
	v_ashrrev_i32_e32 v7, 31, v6
	v_lshrrev_b32_e32 v2, 22, v7
	v_add_u32_e32 v2, v6, v2
	v_ashrrev_i32_e32 v2, 10, v2
	v_lshl_or_b32 v2, v2, 7, s75
	v_ashrrev_i32_e32 v3, 31, v2
	v_lshl_add_u64 v[148:149], v[2:3], 2, s[26:27]
	global_load_dword v150, v[148:149], off
	v_lshrrev_b32_e32 v3, 28, v7
	v_add_u32_e32 v3, v6, v3
	v_ashrrev_i32_e32 v11, 4, v3
	v_ashrrev_i32_e32 v3, 31, v3
	v_lshrrev_b32_e32 v3, 26, v3
	v_add_u32_e32 v3, v11, v3
	v_and_b32_e32 v3, 0xffffffc0, v3
	v_sub_u32_e32 v3, v11, v3
	v_lshl_add_u32 v4, v2, 6, v3
	v_ashrrev_i32_e32 v5, 31, v4
	v_lshlrev_b64 v[8:9], 2, v[4:5]
	v_lshl_add_u64 v[2:3], s[24:25], 0, v[8:9]
	global_load_dword v3, v[2:3], off
	v_lshl_add_u64 v[8:9], s[22:23], 0, v[8:9]
	global_load_dword v2, v[8:9], off
	s_waitcnt vmcnt(3)
	s_waitcnt vmcnt(2)
	v_mul_f32_e32 v7, 0x3fb8aa3b, v150
	v_fma_f32 v8, v150, s40, -v7
	v_rndne_f32_e32 v9, v7
	v_fmac_f32_e32 v8, 0x32a5705f, v150
	v_sub_f32_e32 v7, v7, v9
	v_add_f32_e32 v7, v7, v8
	v_cvt_i32_f32_e32 v9, v9
	v_exp_f32_e32 v7, v7
	v_cmp_ngt_f32_e32 vcc, s41, v150
	v_ldexp_f32 v7, v7, v9
	s_nop 0
	v_cndmask_b32_e32 v7, 0, v7, vcc
	v_cmp_nlt_f32_e32 vcc, s42, v150
	s_nop 1
	v_cndmask_b32_e32 v9, v69, v7, vcc
	s_waitcnt vmcnt(1)
	v_mul_f32_e32 v7, v3, v9
	v_and_b32_e32 v8, 0x7fffffff, v7
	v_cmp_nlt_f32_e64 s[10:11], |v7|, s43
	s_and_saveexec_b64 s[12:13], s[10:11]
	s_xor_b64 s[38:39], exec, s[12:13]
	s_cbranch_execz .LBB0_23
	v_lshrrev_b32_e32 v10, 23, v8
	v_add_u32_e32 v10, 0xffffff88, v10
	v_cmp_lt_u32_e32 vcc, 63, v10
	v_mov_b32_e32 v15, v0
	v_mov_b32_e32 v17, v0
	v_cndmask_b32_e32 v12, 0, v70, vcc
	v_add_u32_e32 v10, v12, v10
	v_cmp_lt_u32_e64 s[10:11], 31, v10
	v_mov_b32_e32 v19, v0
	v_mov_b32_e32 v21, v0
	v_cndmask_b32_e64 v12, 0, v71, s[10:11]
	v_add_u32_e32 v10, v12, v10
	v_cmp_lt_u32_e64 s[12:13], 31, v10
	v_mov_b32_e32 v23, v0
	v_mov_b32_e32 v25, v0
	v_cndmask_b32_e64 v12, 0, v71, s[12:13]
	v_add_u32_e32 v10, v12, v10
	v_and_b32_e32 v12, 0x7fffff, v8
	v_or_b32_e32 v26, 0x800000, v12
	v_mad_u64_u32 v[12:13], s[14:15], v26, s60, 0
	v_mov_b32_e32 v14, v13
	v_mad_u64_u32 v[14:15], s[14:15], v26, s61, v[14:15]
	v_mov_b32_e32 v16, v15
	v_mad_u64_u32 v[16:17], s[14:15], v26, s62, v[16:17]
	v_mov_b32_e32 v18, v17
	v_mad_u64_u32 v[18:19], s[14:15], v26, s63, v[18:19]
	v_mov_b32_e32 v20, v19
	v_mad_u64_u32 v[20:21], s[14:15], v26, s64, v[20:21]
	v_mov_b32_e32 v22, v21
	v_mad_u64_u32 v[22:23], s[14:15], v26, s65, v[22:23]
	v_mov_b32_e32 v24, v23
	v_mad_u64_u32 v[24:25], s[14:15], v26, s66, v[24:25]
	v_cndmask_b32_e32 v13, v22, v18, vcc
	v_cndmask_b32_e32 v15, v24, v20, vcc
	v_cndmask_b32_e32 v19, v25, v22, vcc
	v_cndmask_b32_e64 v17, v15, v13, s[10:11]
	v_cndmask_b32_e64 v15, v19, v15, s[10:11]
	v_cndmask_b32_e32 v19, v20, v16, vcc
	v_cndmask_b32_e64 v13, v13, v19, s[10:11]
	v_sub_u32_e32 v20, 32, v10
	v_cmp_eq_u32_e64 s[14:15], 0, v10
	v_cndmask_b32_e32 v10, v18, v14, vcc
	v_cndmask_b32_e64 v15, v15, v17, s[12:13]
	v_cndmask_b32_e64 v17, v17, v13, s[12:13]
	v_cndmask_b32_e64 v14, v19, v10, s[10:11]
	v_alignbit_b32 v21, v15, v17, v20
	v_cndmask_b32_e64 v13, v13, v14, s[12:13]
	v_cndmask_b32_e64 v15, v21, v15, s[14:15]
	v_alignbit_b32 v18, v17, v13, v20
	v_cndmask_b32_e32 v12, v16, v12, vcc
	v_cndmask_b32_e64 v17, v18, v17, s[14:15]
	v_bfe_u32 v21, v15, 29, 1
	v_cndmask_b32_e64 v10, v10, v12, s[10:11]
	v_alignbit_b32 v18, v15, v17, 30
	v_sub_u32_e32 v22, 0, v21
	v_cndmask_b32_e64 v10, v14, v10, s[12:13]
	v_xor_b32_e32 v18, v18, v22
	v_alignbit_b32 v12, v13, v10, v20
	v_cndmask_b32_e64 v12, v12, v13, s[14:15]
	v_ffbh_u32_e32 v14, v18
	v_alignbit_b32 v13, v17, v12, 30
	v_min_u32_e32 v14, 32, v14
	v_alignbit_b32 v10, v12, v10, 30
	v_xor_b32_e32 v13, v13, v22
	v_sub_u32_e32 v16, 31, v14
	v_xor_b32_e32 v10, v10, v22
	v_alignbit_b32 v17, v18, v13, v16
	v_alignbit_b32 v10, v13, v10, v16
	v_alignbit_b32 v12, v17, v10, 9
	v_ffbh_u32_e32 v13, v12
	v_min_u32_e32 v13, 32, v13
	v_lshrrev_b32_e32 v19, 29, v15
	v_not_b32_e32 v16, v13
	v_alignbit_b32 v10, v12, v10, v16
	v_lshlrev_b32_e32 v12, 31, v19
	v_or_b32_e32 v16, 0x33000000, v12
	v_add_lshl_u32 v13, v13, v14, 23
	v_lshrrev_b32_e32 v10, 9, v10
	v_sub_u32_e32 v13, v16, v13
	v_or_b32_e32 v12, 0.5, v12
	v_lshlrev_b32_e32 v14, 23, v14
	v_or_b32_e32 v10, v13, v10
	v_lshrrev_b32_e32 v13, 9, v17
	v_sub_u32_e32 v12, v12, v14
	v_or_b32_e32 v12, v13, v12
	v_mul_f32_e32 v13, 0x3fc90fda, v12
	v_fma_f32 v14, v12, s67, -v13
	v_fmac_f32_e32 v14, 0x33a22168, v12
	v_fmac_f32_e32 v14, 0x3fc90fda, v10
	v_lshrrev_b32_e32 v12, 30, v15
	v_add_f32_e32 v10, v13, v14
	v_add_u32_e32 v12, v21, v12

.LBB0_28:
	ds_read2_b64 v[148:151], v1 offset1:17
	ds_read_b128 v[22:25], v73
	ds_read_b128 v[26:29], v73 offset:16
	ds_read_b128 v[30:33], v73 offset:32
	ds_read_b128 v[34:37], v73 offset:48
	ds_read_b128 v[38:41], v73 offset:64
	ds_read_b128 v[42:45], v73 offset:80
	ds_read_b128 v[46:49], v73 offset:96
	ds_read_b128 v[74:77], v73 offset:112
	ds_read_b128 v[78:81], v73 offset:128
	ds_read_b128 v[82:85], v73 offset:144
	ds_read_b128 v[86:89], v73 offset:160
	ds_read_b128 v[90:93], v73 offset:176
	ds_read_b128 v[94:97], v73 offset:192
	ds_read_b128 v[98:101], v73 offset:208
	s_waitcnt lgkmcnt(14)
	ds_read_b128 v[102:105], v73 offset:224
	s_waitcnt lgkmcnt(14)
	ds_read_b128 v[106:109], v73 offset:240
	s_waitcnt lgkmcnt(15)
	v_add_u32_e32 v110, s10, v63
	s_waitcnt lgkmcnt(14)
	ds_read2_b64 v[110:113], v110 offset1:1
	s_waitcnt lgkmcnt(14)
	v_xor_b32_e32 v116, 0x80000000, v149
	v_mov_b32_e32 v117, v148
	v_xor_b32_e32 v114, 0x80000000, v151
	v_mov_b32_e32 v115, v150
	v_mov_b32_e32 v118, v22
	v_mov_b32_e32 v22, v26
	v_mov_b32_e32 v26, v30
	s_waitcnt lgkmcnt(13)
	v_mov_b32_e32 v30, v34
	s_waitcnt lgkmcnt(12)
	v_mov_b32_e32 v34, v38
	s_waitcnt lgkmcnt(11)
	v_mov_b32_e32 v38, v42
	s_waitcnt lgkmcnt(10)
	v_mov_b32_e32 v42, v46
	s_waitcnt lgkmcnt(9)
	v_mov_b32_e32 v46, v74
	s_waitcnt lgkmcnt(8)
	v_mov_b32_e32 v74, v78
	s_waitcnt lgkmcnt(7)
	v_mov_b32_e32 v78, v82
	s_waitcnt lgkmcnt(6)
	v_mov_b32_e32 v82, v86
	s_waitcnt lgkmcnt(5)
	v_mov_b32_e32 v86, v90
	s_waitcnt lgkmcnt(4)
	v_mov_b32_e32 v90, v94
	s_waitcnt lgkmcnt(3)
	v_mov_b32_e32 v94, v98
	s_waitcnt lgkmcnt(2)
	v_mov_b32_e32 v98, v102
	s_waitcnt lgkmcnt(1)
	v_mov_b32_e32 v102, v106
	s_waitcnt lgkmcnt(0)
	v_mov_b32_e32 v106, v113
	v_pk_mul_f32 v[116:117], v[110:111], v[116:117] op_sel:[1,0]
	v_mov_b32_e32 v119, v24
	v_mov_b32_e32 v24, v23
	v_mov_b32_e32 v23, v28
	v_mov_b32_e32 v28, v27
	v_mov_b32_e32 v27, v32
	v_mov_b32_e32 v32, v31
	v_mov_b32_e32 v31, v36
	v_mov_b32_e32 v36, v35
	v_mov_b32_e32 v35, v40
	v_mov_b32_e32 v40, v39
	v_mov_b32_e32 v39, v44
	v_mov_b32_e32 v44, v43
	v_mov_b32_e32 v43, v48
	v_mov_b32_e32 v48, v47
	v_mov_b32_e32 v47, v76
	v_mov_b32_e32 v76, v75
	v_mov_b32_e32 v75, v80
	v_mov_b32_e32 v80, v79
	v_mov_b32_e32 v79, v84
	v_mov_b32_e32 v84, v83
	v_mov_b32_e32 v83, v88
	v_mov_b32_e32 v88, v87
	v_mov_b32_e32 v87, v92
	v_mov_b32_e32 v92, v91
	v_mov_b32_e32 v91, v96
	v_mov_b32_e32 v96, v95
	v_mov_b32_e32 v95, v100
	v_mov_b32_e32 v100, v99
	v_mov_b32_e32 v99, v104
	v_mov_b32_e32 v104, v103
	v_mov_b32_e32 v103, v108
	v_mov_b32_e32 v108, v107
	v_pk_mul_f32 v[106:107], v[106:107], v[114:115] op_sel_hi:[0,1]
	v_pk_fma_f32 v[18:19], v[110:111], v[148:149], v[116:117] op_sel_hi:[0,1,1]
	v_pk_fma_f32 v[20:21], v[112:113], v[150:151], v[106:107] op_sel_hi:[0,1,1]
	v_pk_mul_f32 v[24:25], v[24:25], v[18:19] op_sel:[0,1]
	v_pk_mul_f32 v[28:29], v[28:29], v[18:19] op_sel:[0,1]
	v_pk_mul_f32 v[32:33], v[18:19], v[32:33] op_sel:[1,0]
	v_pk_mul_f32 v[36:37], v[18:19], v[36:37] op_sel:[1,0]
	v_pk_mul_f32 v[40:41], v[18:19], v[40:41] op_sel:[1,0]
	v_pk_mul_f32 v[44:45], v[18:19], v[44:45] op_sel:[1,0]
	v_pk_mul_f32 v[48:49], v[18:19], v[48:49] op_sel:[1,0]
	v_pk_mul_f32 v[76:77], v[18:19], v[76:77] op_sel:[1,0]
	v_pk_fma_f32 v[24:25], v[118:119], v[18:19], v[24:25] op_sel_hi:[1,0,1] neg_lo:[0,0,1] neg_hi:[0,0,1]
	v_pk_fma_f32 v[22:23], v[22:23], v[18:19], v[28:29] op_sel_hi:[1,0,1] neg_lo:[0,0,1] neg_hi:[0,0,1]
	v_pk_fma_f32 v[26:27], v[18:19], v[26:27], v[32:33] op_sel_hi:[0,1,1] neg_lo:[0,0,1] neg_hi:[0,0,1]
	v_pk_fma_f32 v[28:29], v[18:19], v[30:31], v[36:37] op_sel_hi:[0,1,1] neg_lo:[0,0,1] neg_hi:[0,0,1]
	v_pk_fma_f32 v[30:31], v[18:19], v[34:35], v[40:41] op_sel_hi:[0,1,1] neg_lo:[0,0,1] neg_hi:[0,0,1]
	v_pk_fma_f32 v[32:33], v[18:19], v[38:39], v[44:45] op_sel_hi:[0,1,1] neg_lo:[0,0,1] neg_hi:[0,0,1]
	v_pk_fma_f32 v[34:35], v[18:19], v[42:43], v[48:49] op_sel_hi:[0,1,1] neg_lo:[0,0,1] neg_hi:[0,0,1]
	v_pk_fma_f32 v[18:19], v[18:19], v[46:47], v[76:77] op_sel_hi:[0,1,1] neg_lo:[0,0,1] neg_hi:[0,0,1]
	v_pk_mul_f32 v[36:37], v[80:81], v[20:21] op_sel:[0,1]
	v_pk_mul_f32 v[38:39], v[84:85], v[20:21] op_sel:[0,1]
	v_pk_mul_f32 v[40:41], v[20:21], v[88:89] op_sel:[1,0]
	v_pk_mul_f32 v[42:43], v[20:21], v[92:93] op_sel:[1,0]
	v_pk_mul_f32 v[44:45], v[20:21], v[96:97] op_sel:[1,0]
	v_pk_mul_f32 v[46:47], v[20:21], v[100:101] op_sel:[1,0]
	v_pk_mul_f32 v[48:49], v[20:21], v[104:105] op_sel:[1,0]
	v_pk_mul_f32 v[76:77], v[20:21], v[108:109] op_sel:[1,0]
	s_add_i32 s10, s10, 16
	v_pk_add_f32 v[2:3], v[2:3], v[24:25]
	v_pk_add_f32 v[4:5], v[4:5], v[22:23]
	v_pk_add_f32 v[14:15], v[14:15], v[26:27]
	v_pk_add_f32 v[16:17], v[16:17], v[28:29]
	v_pk_add_f32 v[10:11], v[10:11], v[30:31]
	v_pk_add_f32 v[12:13], v[12:13], v[32:33]
	v_pk_add_f32 v[6:7], v[6:7], v[34:35]
	v_pk_add_f32 v[8:9], v[8:9], v[18:19]
	v_pk_fma_f32 v[18:19], v[74:75], v[20:21], v[36:37] op_sel_hi:[1,0,1] neg_lo:[0,0,1] neg_hi:[0,0,1]
	v_pk_fma_f32 v[22:23], v[78:79], v[20:21], v[38:39] op_sel_hi:[1,0,1] neg_lo:[0,0,1] neg_hi:[0,0,1]
	v_pk_fma_f32 v[24:25], v[20:21], v[82:83], v[40:41] op_sel_hi:[0,1,1] neg_lo:[0,0,1] neg_hi:[0,0,1]
	v_pk_fma_f32 v[26:27], v[20:21], v[86:87], v[42:43] op_sel_hi:[0,1,1] neg_lo:[0,0,1] neg_hi:[0,0,1]
	v_pk_fma_f32 v[28:29], v[20:21], v[90:91], v[44:45] op_sel_hi:[0,1,1] neg_lo:[0,0,1] neg_hi:[0,0,1]
	v_pk_fma_f32 v[30:31], v[20:21], v[94:95], v[46:47] op_sel_hi:[0,1,1] neg_lo:[0,0,1] neg_hi:[0,0,1]
	v_pk_fma_f32 v[32:33], v[20:21], v[98:99], v[48:49] op_sel_hi:[0,1,1] neg_lo:[0,0,1] neg_hi:[0,0,1]
	v_pk_fma_f32 v[20:21], v[20:21], v[102:103], v[76:77] op_sel_hi:[0,1,1] neg_lo:[0,0,1] neg_hi:[0,0,1]
	v_add_u32_e32 v73, 0x100, v73
	v_add_u32_e32 v1, 0x110, v1
	s_cmpk_lg_i32 s10, 0x200
	v_pk_add_f32 v[2:3], v[2:3], v[18:19]
	v_pk_add_f32 v[4:5], v[4:5], v[22:23]
	v_pk_add_f32 v[14:15], v[14:15], v[24:25]
	v_pk_add_f32 v[16:17], v[16:17], v[26:27]
	v_pk_add_f32 v[10:11], v[10:11], v[28:29]
	v_pk_add_f32 v[12:13], v[12:13], v[30:31]
	v_pk_add_f32 v[6:7], v[6:7], v[32:33]
	v_pk_add_f32 v[8:9], v[8:9], v[20:21]
	s_cbranch_scc1 .LBB0_28
	ds_write_b128 v68, v[2:5] offset:50432
	ds_write_b128 v68, v[14:17] offset:50448
	ds_write_b128 v68, v[10:13] offset:50464
	ds_write_b128 v68, v[6:9] offset:50480
	s_lshl_b32 s22, s75, 8
	v_lshlrev_b32_e32 v2, 1, v54
	s_waitcnt lgkmcnt(0)
	s_barrier
	s_and_saveexec_b64 s[12:13], s[4:5]
	s_cbranch_execz .LBB0_32
	s_load_dwordx16 s[44:59], s[0:1], 0x160
	s_and_b64 s[10:11], s[20:21], exec
	v_mov_b32_e32 v3, v0
	v_mov_b32_e32 v1, v51
	s_waitcnt lgkmcnt(0)
	s_cselect_b32 s11, s57, s51
	s_cselect_b32 s10, s56, s50
	s_lshl_b32 s14, s22, 9
	s_add_u32 s10, s10, s14
	s_addc_u32 s11, s11, 0
	v_lshl_add_u64 v[4:5], s[10:11], 0, v[2:3]
	s_mov_b64 s[14:15], 0
.LBB0_31:
	v_ashrrev_i32_e32 v148, 10, v1
	s_movk_i32 s10, 0x400
	v_bfe_u32 v3, v1, 4, 6
	s_nop 1
	v_lshl_or_b32 v149, v148, 6, v3
	s_nop 1
	v_lshl_add_u32 v36, v149, 7, 0
	ds_read_b128 v[152:155], v36 offset:17424
	ds_read_b128 v[156:159], v36 offset:17440
	ds_read_b128 v[160:163], v36 offset:17456
	ds_read_b128 v[164:167], v36 offset:17472
	ds_read_b128 v[168:171], v36 offset:17488
	ds_read_b128 v[172:175], v36 offset:17504
	ds_read_b128 v[176:179], v36 offset:17520
	v_cmp_gt_u32_e64 s[10:11], s10, v1
	v_add_u32_e32 v7, 0x200, v1
	s_nop 0
	v_cndmask_b32_e64 v8, v53, v55, s[10:11]
	s_movk_i32 s10, 0x88
	v_lshl_or_b32 v34, v148, 7, v3
	v_lshlrev_b32_e32 v3, 3, v8
	v_mul_lo_u32 v6, v149, s10
	v_cmp_lt_i32_e32 vcc, s72, v1
	v_mov_b32_e32 v1, v7
	v_ashrrev_i32_e32 v35, 31, v34
	v_add3_u32 v3, 0, v6, v3
	s_nop 0
	v_lshlrev_b64 v[38:39], 9, v[34:35]
	ds_read_b128 v[34:37], v36 offset:17408
	s_nop 0
	ds_read_b64 v[40:41], v3
	s_waitcnt lgkmcnt(9)
	s_waitcnt lgkmcnt(8)
	v_xor_b32_e32 v44, 0x80000000, v153
	v_mov_b32_e32 v45, v152
	v_xor_b32_e32 v46, 0x80000000, v155
	v_mov_b32_e32 v47, v154
	s_waitcnt lgkmcnt(7)
	v_xor_b32_e32 v48, 0x80000000, v157
	v_mov_b32_e32 v49, v156
	v_xor_b32_e32 v74, 0x80000000, v159
	v_mov_b32_e32 v75, v158
	s_waitcnt lgkmcnt(6)
	v_xor_b32_e32 v76, 0x80000000, v161
	v_mov_b32_e32 v77, v160
	v_xor_b32_e32 v78, 0x80000000, v163
	v_mov_b32_e32 v79, v162
	s_waitcnt lgkmcnt(5)
	v_xor_b32_e32 v80, 0x80000000, v165
	v_mov_b32_e32 v81, v164
	v_xor_b32_e32 v82, 0x80000000, v167
	v_mov_b32_e32 v83, v166
	s_waitcnt lgkmcnt(4)
	v_xor_b32_e32 v84, 0x80000000, v169
	v_mov_b32_e32 v85, v168
	v_xor_b32_e32 v86, 0x80000000, v171
	v_mov_b32_e32 v87, v170
	s_waitcnt lgkmcnt(3)
	v_xor_b32_e32 v88, 0x80000000, v173
	v_mov_b32_e32 v89, v172
	v_xor_b32_e32 v90, 0x80000000, v175
	v_mov_b32_e32 v91, v174
	s_waitcnt lgkmcnt(2)
	v_xor_b32_e32 v92, 0x80000000, v177
	v_mov_b32_e32 v93, v176
	v_xor_b32_e32 v94, 0x80000000, v179
	v_mov_b32_e32 v95, v178
	s_waitcnt lgkmcnt(1)
	v_xor_b32_e32 v96, 0x80000000, v35
	v_mov_b32_e32 v97, v34
	v_xor_b32_e32 v98, 0x80000000, v37
	v_mov_b32_e32 v99, v36
	s_waitcnt lgkmcnt(0)
	v_pk_mul_f32 v[44:45], v[40:41], v[44:45] op_sel:[1,0]
	v_pk_mul_f32 v[46:47], v[40:41], v[46:47] op_sel:[1,0]
	v_pk_mul_f32 v[48:49], v[40:41], v[48:49] op_sel:[1,0]
	v_pk_mul_f32 v[74:75], v[40:41], v[74:75] op_sel:[1,0]
	v_pk_mul_f32 v[76:77], v[40:41], v[76:77] op_sel:[1,0]
	v_pk_mul_f32 v[78:79], v[40:41], v[78:79] op_sel:[1,0]
	v_pk_mul_f32 v[80:81], v[40:41], v[80:81] op_sel:[1,0]
	v_pk_mul_f32 v[82:83], v[40:41], v[82:83] op_sel:[1,0]
	v_pk_mul_f32 v[84:85], v[40:41], v[84:85] op_sel:[1,0]
	v_pk_mul_f32 v[86:87], v[40:41], v[86:87] op_sel:[1,0]
	v_pk_mul_f32 v[88:89], v[40:41], v[88:89] op_sel:[1,0]
	v_pk_mul_f32 v[90:91], v[40:41], v[90:91] op_sel:[1,0]
	v_pk_mul_f32 v[92:93], v[40:41], v[92:93] op_sel:[1,0]
	v_pk_mul_f32 v[94:95], v[40:41], v[94:95] op_sel:[1,0]
	v_lshl_add_u64 v[38:39], v[4:5], 0, v[38:39]
	v_pk_mul_f32 v[96:97], v[40:41], v[96:97] op_sel:[1,0]
	v_pk_mul_f32 v[98:99], v[40:41], v[98:99] op_sel:[1,0]
	v_pk_fma_f32 v[44:45], v[40:41], v[152:153], v[44:45] op_sel_hi:[0,1,1]
	v_pk_fma_f32 v[8:9], v[40:41], v[154:155], v[46:47] op_sel_hi:[0,1,1]
	v_pk_fma_f32 v[46:47], v[40:41], v[156:157], v[48:49] op_sel_hi:[0,1,1]
	v_pk_fma_f32 v[12:13], v[40:41], v[158:159], v[74:75] op_sel_hi:[0,1,1]
	v_pk_fma_f32 v[14:15], v[40:41], v[160:161], v[76:77] op_sel_hi:[0,1,1]
	v_pk_fma_f32 v[16:17], v[40:41], v[162:163], v[78:79] op_sel_hi:[0,1,1]
	v_pk_fma_f32 v[18:19], v[40:41], v[164:165], v[80:81] op_sel_hi:[0,1,1]
	v_pk_fma_f32 v[20:21], v[40:41], v[166:167], v[82:83] op_sel_hi:[0,1,1]
	v_pk_fma_f32 v[22:23], v[40:41], v[168:169], v[84:85] op_sel_hi:[0,1,1]
	v_pk_fma_f32 v[24:25], v[40:41], v[170:171], v[86:87] op_sel_hi:[0,1,1]
	v_pk_fma_f32 v[26:27], v[40:41], v[172:173], v[88:89] op_sel_hi:[0,1,1]
	v_pk_fma_f32 v[28:29], v[40:41], v[174:175], v[90:91] op_sel_hi:[0,1,1]
	v_pk_fma_f32 v[30:31], v[40:41], v[176:177], v[92:93] op_sel_hi:[0,1,1]
	v_pk_fma_f32 v[32:33], v[40:41], v[178:179], v[94:95] op_sel_hi:[0,1,1]
	s_or_b64 s[14:15], vcc, s[14:15]
	v_add_co_u32_e32 v42, vcc, 0x8000, v38
	v_pk_fma_f32 v[34:35], v[40:41], v[34:35], v[96:97] op_sel_hi:[0,1,1]
	v_pk_fma_f32 v[36:37], v[40:41], v[36:37], v[98:99] op_sel_hi:[0,1,1]
	v_cvt_pk_bf16_f32 v7, v44, v8
	v_cvt_pk_bf16_f32 v11, v45, v9
	v_cvt_pk_bf16_f32 v8, v46, v12
	v_cvt_pk_bf16_f32 v12, v47, v13
	v_cvt_pk_bf16_f32 v9, v14, v16
	v_cvt_pk_bf16_f32 v13, v15, v17
	v_cvt_pk_bf16_f32 v14, v18, v20
	v_cvt_pk_bf16_f32 v15, v22, v24
	v_cvt_pk_bf16_f32 v16, v26, v28
	v_cvt_pk_bf16_f32 v17, v30, v32
	v_addc_co_u32_e32 v43, vcc, 0, v39, vcc
	v_cvt_pk_bf16_f32 v18, v19, v21
	v_cvt_pk_bf16_f32 v19, v23, v25
	v_cvt_pk_bf16_f32 v20, v27, v29
	v_cvt_pk_bf16_f32 v21, v31, v33
	v_cvt_pk_bf16_f32 v6, v34, v36
	v_cvt_pk_bf16_f32 v10, v35, v37
	global_store_dwordx4 v[38:39], v[14:17], off offset:16
	global_store_dwordx4 v[42:43], v[18:21], off offset:16
	global_store_dwordx4 v[38:39], v[6:9], off
	global_store_dwordx4 v[42:43], v[10:13], off
	s_andn2_b64 exec, exec, s[14:15]
	s_cbranch_execnz .LBB0_31

.LBB0_35:
	v_mov_b32_e32 v2, v0
	v_mov_b32_e32 v3, v0
	v_mov_b32_e32 v4, v0
	v_mov_b32_e32 v5, v0
	v_mov_b32_e32 v6, v0
	v_mov_b32_e32 v7, v0
	v_mov_b32_e32 v8, v0
	v_mov_b32_e32 v9, v0
	v_mov_b32_e32 v10, v0
	v_mov_b32_e32 v11, v0
	v_mov_b32_e32 v12, v0
	v_mov_b32_e32 v13, v0
	v_mov_b32_e32 v14, v0
	v_mov_b32_e32 v15, v0
	v_bfe_u32 v21, v20, 4, 4
	v_ashrrev_i32_e32 v22, 8, v20
	v_mov_b32_e32 v1, v0
	v_mov_b64_e32 v[16:17], v[14:15]
	v_cmp_ge_i32_e32 vcc, v22, v53
	v_lshlrev_b32_e32 v23, 6, v21
	v_mov_b64_e32 v[14:15], v[12:13]
	v_mov_b64_e32 v[12:13], v[10:11]
	v_mov_b64_e32 v[10:11], v[8:9]
	v_mov_b64_e32 v[8:9], v[6:7]
	v_mov_b64_e32 v[6:7], v[4:5]
	v_mov_b64_e32 v[4:5], v[2:3]
	v_mov_b64_e32 v[2:3], v[0:1]
	s_and_saveexec_b64 s[22:23], vcc
	s_cbranch_execz .LBB0_37
	v_sub_u32_e32 v1, v22, v53
	v_lshlrev_b32_e32 v1, 10, v1
	v_add3_u32 v1, 0, v1, v23
	ds_read_b128 v[148:151], v1 offset:50480
	ds_read_b128 v[152:155], v1 offset:50464
	ds_read_b128 v[156:159], v1 offset:50448
	ds_read_b128 v[160:163], v1 offset:50432
	s_waitcnt lgkmcnt(4)
	s_waitcnt lgkmcnt(3)
	v_pk_add_f32 v[16:17], v[150:151], 0 op_sel_hi:[1,0]
	s_waitcnt lgkmcnt(2)
	v_pk_add_f32 v[12:13], v[154:155], 0 op_sel_hi:[1,0]
	s_waitcnt lgkmcnt(1)
	v_pk_add_f32 v[8:9], v[158:159], 0 op_sel_hi:[1,0]
	s_waitcnt lgkmcnt(0)
	v_pk_add_f32 v[4:5], v[162:163], 0 op_sel_hi:[1,0]
	v_pk_add_f32 v[14:15], v[148:149], 0 op_sel_hi:[1,0]
	v_pk_add_f32 v[10:11], v[152:153], 0 op_sel_hi:[1,0]
	v_pk_add_f32 v[6:7], v[156:157], 0 op_sel_hi:[1,0]
	v_pk_add_f32 v[2:3], v[160:161], 0 op_sel_hi:[1,0]
.LBB0_37:
	s_or_b64 exec, exec, s[22:23]
	v_cmp_ge_i32_e32 vcc, v53, v22
	s_and_saveexec_b64 s[22:23], vcc
	s_cbranch_execz .LBB0_39
	v_sub_u32_e32 v1, v53, v22
	v_lshl_or_b32 v1, v1, 10, v23
	v_add_u32_e32 v1, 0, v1
	v_add_u32_e32 v1, 0x4000, v1
	ds_read_b128 v[148:151], v1 offset:50480
	ds_read_b128 v[152:155], v1 offset:50464
	ds_read_b128 v[156:159], v1 offset:50448
	ds_read_b128 v[36:39], v1 offset:50432
	s_waitcnt lgkmcnt(4)
	s_waitcnt lgkmcnt(3)
	v_pk_add_f32 v[16:17], v[16:17], v[150:151]
	s_waitcnt lgkmcnt(2)
	v_pk_add_f32 v[12:13], v[12:13], v[154:155]
	s_waitcnt lgkmcnt(1)
	v_pk_add_f32 v[8:9], v[8:9], v[158:159]
	s_waitcnt lgkmcnt(0)
	v_pk_add_f32 v[4:5], v[4:5], v[38:39]
	v_pk_add_f32 v[14:15], v[14:15], v[148:149]
	v_pk_add_f32 v[10:11], v[10:11], v[152:153]
	v_pk_add_f32 v[6:7], v[6:7], v[156:157]
	v_pk_add_f32 v[2:3], v[2:3], v[36:37]

.LBB0_42:
	v_bfe_u32 v3, v1, 3, 1
	v_bfe_u32 v2, v1, 4, 4
	s_nop 1
	v_lshl_or_b32 v148, v3, 4, v2
	v_lshlrev_b32_e32 v149, 6, v3
	s_nop 0
	v_mad_u32_u24 v150, v148, s33, v60
	v_or_b32_e32 v151, v149, v58
	v_ashrrev_i32_e32 v4, 8, v1
	v_cmp_lt_i32_e32 vcc, s73, v1
	v_add_u32_e32 v5, 0x200, v1
	v_add_u32_e32 v6, 1, v4
	v_sub_u32_e32 v7, 16, v4
	s_or_b64 s[14:15], vcc, s[14:15]
	v_cmp_eq_u32_e32 vcc, 0, v3
	v_lshl_or_b32 v2, v4, 4, v2
	v_mov_b32_e32 v1, v5
	v_cndmask_b32_e32 v4, v7, v6, vcc
	s_nop 1
	v_lshlrev_b32_e32 v152, 3, v4
	v_mul_u32_u24_e32 v153, 17, v151
	v_add_u32_e32 v154, 0x8420, v150
	v_add_u32_e32 v155, 0, v152
	v_or_b32_e32 v6, v149, v56
	v_or_b32_e32 v7, v149, v57
	v_or_b32_e32 v9, v149, v59
	v_lshlrev_b32_e32 v18, 8, v3
	v_ashrrev_i32_e32 v3, 31, v2
	v_add_u32_e32 v4, 0x8400, v150
	v_mul_u32_u24_e32 v6, 17, v6
	v_mul_u32_u24_e32 v7, 17, v7
	v_mul_u32_u24_e32 v16, 17, v9
	v_add_u32_e32 v12, 0x8410, v150
	v_add_u32_e32 v15, 0x8430, v150
	v_lshlrev_b64 v[10:11], 10, v[2:3]
	ds_read2_b64 v[2:5], v4 offset1:1
	s_nop 0
	ds_read2_b64 v[148:151], v154 offset1:1
	v_lshlrev_b32_e32 v156, 3, v6
	v_lshlrev_b32_e32 v157, 3, v7
	v_lshlrev_b32_e32 v158, 3, v153
	v_add_u32_e32 v159, v155, v156
	v_add_u32_e32 v160, v155, v157
	v_add3_u32 v161, 0, v157, v152
	v_add_u32_e32 v162, v155, v158
	v_add3_u32 v163, 0, v158, v152
	v_lshlrev_b32_e32 v29, 3, v16
	v_mov_b32_e32 v19, v0
	v_lshl_add_u64 v[22:23], s[12:13], 0, v[10:11]
	v_add3_u32 v26, 0, v156, v152
	v_add_u32_e32 v35, v155, v29
	v_add3_u32 v36, 0, v29, v152
	ds_read2_b64 v[10:13], v12 offset1:1
	s_nop 0
	ds_read2_b64 v[14:17], v15 offset1:1
	s_nop 0
	ds_read_b64 v[152:153], v159
	ds_read_b64 v[154:155], v26 offset:136
	ds_read_b64 v[156:157], v160
	ds_read_b64 v[164:165], v161 offset:136
	ds_read_b64 v[166:167], v162
	ds_read_b64 v[168:169], v163 offset:136
	v_lshl_add_u64 v[18:19], v[22:23], 0, v[18:19]
	ds_read_b64 v[34:35], v35
	s_nop 0
	ds_read_b64 v[36:37], v36 offset:136
	v_lshlrev_b32_e32 v20, 1, v56
	v_mov_b32_e32 v21, v0
	v_lshl_add_u64 v[18:19], v[18:19], 0, v[20:21]
	s_waitcnt lgkmcnt(11)
	v_mov_b32_e32 v20, v5
	s_waitcnt lgkmcnt(8)
	s_waitcnt lgkmcnt(6)
	v_xor_b32_e32 v46, 0x80000000, v155
	v_mov_b32_e32 v47, v154
	v_mov_b32_e32 v40, v13
	v_xor_b32_e32 v44, 0x80000000, v153
	v_mov_b32_e32 v45, v152
	s_waitcnt lgkmcnt(5)
	v_xor_b32_e32 v48, 0x80000000, v157
	v_mov_b32_e32 v49, v156
	s_waitcnt lgkmcnt(4)
	v_xor_b32_e32 v74, 0x80000000, v165
	v_mov_b32_e32 v75, v164
	v_pk_mul_f32 v[20:21], v[20:21], v[46:47] op_sel_hi:[0,1]
	v_mov_b32_e32 v38, v151
	v_mov_b32_e32 v42, v17
	s_waitcnt lgkmcnt(3)
	v_xor_b32_e32 v76, 0x80000000, v167
	v_mov_b32_e32 v77, v166
	s_waitcnt lgkmcnt(2)
	v_xor_b32_e32 v78, 0x80000000, v169
	v_mov_b32_e32 v79, v168
	s_waitcnt lgkmcnt(1)
	v_xor_b32_e32 v80, 0x80000000, v35
	v_mov_b32_e32 v81, v34
	s_waitcnt lgkmcnt(0)
	v_xor_b32_e32 v82, 0x80000000, v37
	v_mov_b32_e32 v83, v36
	v_pk_mul_f32 v[44:45], v[2:3], v[44:45] op_sel:[1,0]
	v_pk_mul_f32 v[46:47], v[10:11], v[48:49] op_sel:[1,0]
	v_pk_mul_f32 v[40:41], v[40:41], v[74:75] op_sel_hi:[0,1]
	v_pk_fma_f32 v[4:5], v[4:5], v[154:155], v[20:21] op_sel_hi:[0,1,1]
	v_pk_mul_f32 v[48:49], v[148:149], v[76:77] op_sel:[1,0]
	v_pk_mul_f32 v[38:39], v[38:39], v[78:79] op_sel_hi:[0,1]
	v_pk_mul_f32 v[74:75], v[14:15], v[80:81] op_sel:[1,0]
	v_pk_mul_f32 v[42:43], v[42:43], v[82:83] op_sel_hi:[0,1]
	v_pk_fma_f32 v[2:3], v[2:3], v[152:153], v[44:45] op_sel_hi:[0,1,1]
	v_pk_fma_f32 v[10:11], v[10:11], v[156:157], v[46:47] op_sel_hi:[0,1,1]
	v_pk_fma_f32 v[12:13], v[12:13], v[164:165], v[40:41] op_sel_hi:[0,1,1]
	v_pk_add_f32 v[20:21], v[4:5], 0 neg_lo:[1,1] neg_hi:[1,1]
	v_pk_fma_f32 v[6:7], v[148:149], v[166:167], v[48:49] op_sel_hi:[0,1,1]
	v_pk_fma_f32 v[8:9], v[150:151], v[168:169], v[38:39] op_sel_hi:[0,1,1]
	v_pk_fma_f32 v[14:15], v[14:15], v[34:35], v[74:75] op_sel_hi:[0,1,1]
	v_pk_fma_f32 v[16:17], v[16:17], v[36:37], v[42:43] op_sel_hi:[0,1,1]
	v_xor_b32_e32 v22, 0x80000000, v3
	v_cvt_pk_bf16_f32 v3, v10, v12
	v_xor_b32_e32 v20, 0x80000000, v11
	v_pk_add_f32 v[10:11], v[12:13], 0 neg_lo:[1,1] neg_hi:[1,1]
	v_cvt_pk_bf16_f32 v2, v2, v4
	v_cvt_pk_bf16_f32 v4, v6, v8
	v_xor_b32_e32 v10, 0x80000000, v7
	v_pk_add_f32 v[8:9], v[8:9], 0 neg_lo:[1,1] neg_hi:[1,1]
	v_cvt_pk_bf16_f32 v5, v14, v16
	v_xor_b32_e32 v14, 0x80000000, v15
	v_pk_add_f32 v[12:13], v[16:17], 0 neg_lo:[1,1] neg_hi:[1,1]
	v_cvt_pk_bf16_f32 v6, v22, v21
	v_cvt_pk_bf16_f32 v7, v20, v11
	v_cvt_pk_bf16_f32 v8, v10, v9
	v_cvt_pk_bf16_f32 v9, v14, v13
	global_store_dwordx4 v[18:19], v[2:5], off offset:512
	global_store_dwordx4 v[18:19], v[6:9], off offset:640
	s_andn2_b64 exec, exec, s[14:15]
	s_cbranch_execnz .LBB0_42
	s_branch .LBB0_10

.LBB0_47:
	global_load_dwordx4 v[148:151], v[18:19], off
	s_mov_b32 s0, 0xfffdc000
	v_add_co_u32_e64 v38, s[0:1], s0, v18
	v_add_co_u32_e32 v42, vcc, 0xfffd0000, v18
	s_nop 0
	v_addc_co_u32_e64 v39, s[0:1], -1, v19, s[0:1]
	s_mov_b32 s0, 0xfffe8000
	s_nop 0
	v_add_co_u32_e64 v26, s[0:1], s0, v18
	v_addc_co_u32_e32 v43, vcc, -1, v19, vcc
	s_nop 0
	v_addc_co_u32_e64 v27, s[0:1], -1, v19, s[0:1]
	s_mov_b32 s0, 0xffff4000
	s_nop 0
	v_add_co_u32_e64 v30, s[0:1], s0, v18
	s_nop 1
	v_addc_co_u32_e64 v31, s[0:1], -1, v19, s[0:1]
	s_mov_b32 s0, 0xc000
	s_nop 0
	v_add_co_u32_e64 v34, s[0:1], s0, v18
	v_readlane_b32 s4, v23, s5
	s_nop 0
	v_addc_co_u32_e64 v35, s[0:1], 0, v19, s[0:1]
	s_mov_b32 s0, 0x18000
	s_nop 0
	v_add_co_u32_e64 v46, s[0:1], s0, v18
	v_readlane_b32 s6, v24, s5
	s_nop 0
	v_addc_co_u32_e64 v47, s[0:1], 0, v19, s[0:1]
	s_mov_b32 s0, 0x24000
	s_nop 0
	v_add_co_u32_e64 v50, s[0:1], s0, v18
	s_add_i32 s7, s5, 2
	s_nop 0
	v_addc_co_u32_e64 v51, s[0:1], 0, v19, s[0:1]
	global_load_dwordx4 v[26:29], v[26:27], off
	s_nop 0
	global_load_dwordx4 v[30:33], v[30:31], off
	s_nop 0
	global_load_dwordx4 v[34:37], v[34:35], off
	s_nop 0
	global_load_dwordx4 v[38:41], v[38:39], off
	s_nop 0
	global_load_dwordx4 v[42:45], v[42:43], off
	s_nop 0
	global_load_dwordx4 v[46:49], v[46:47], off
	s_nop 0
	global_load_dwordx4 v[50:53], v[50:51], off
	v_readlane_b32 s0, v25, s5
	s_add_i32 s1, s5, 1
	s_add_i32 s15, s5, 3
	s_add_i32 s18, s5, 4
	s_add_i32 s19, s5, 5
	s_add_i32 s21, s5, 6
	s_add_i32 s23, s5, 7
	s_add_i32 s5, s5, 8
	v_readlane_b32 s14, v23, s1
	v_readlane_b32 s20, v24, s1
	v_readlane_b32 s22, v25, s1
	v_readlane_b32 s24, v23, s7
	v_readlane_b32 s26, v24, s7
	v_readlane_b32 s28, v25, s7
	v_readlane_b32 s30, v23, s15
	v_readlane_b32 s34, v24, s15
	v_readlane_b32 s36, v25, s15
	v_readlane_b32 s38, v23, s18
	v_readlane_b32 s40, v24, s18
	v_readlane_b32 s42, v25, s18
	v_readlane_b32 s60, v23, s19
	v_readlane_b32 s62, v24, s19
	v_readlane_b32 s64, v25, s19
	v_readlane_b32 s66, v23, s21
	v_readlane_b32 s68, v24, s21
	v_readlane_b32 s70, v25, s21
	v_readlane_b32 s72, v23, s23
	v_readlane_b32 s74, v24, s23
	v_readlane_b32 s18, v25, s23
	s_mov_b64 vcc, 0x60000
	s_cmp_eq_u32 s5, 64
	v_lshl_add_u64 v[18:19], v[18:19], 0, vcc
	s_waitcnt vmcnt(2)
	v_pk_fma_f32 v[2:3], v[44:45], s[4:5], v[2:3] op_sel_hi:[1,0,1]
	v_pk_fma_f32 v[0:1], v[42:43], s[4:5], v[0:1] op_sel_hi:[1,0,1]
	v_pk_fma_f32 v[10:11], v[44:45], s[6:7], v[10:11] op_sel_hi:[1,0,1]
	v_pk_fma_f32 v[8:9], v[42:43], s[6:7], v[8:9] op_sel_hi:[1,0,1]
	v_pk_fma_f32 v[6:7], v[44:45], s[0:1], v[6:7] op_sel_hi:[1,0,1]
	v_pk_fma_f32 v[4:5], v[42:43], s[0:1], v[4:5] op_sel_hi:[1,0,1]
	v_pk_fma_f32 v[2:3], v[40:41], s[14:15], v[2:3] op_sel_hi:[1,0,1]
	v_pk_fma_f32 v[0:1], v[38:39], s[14:15], v[0:1] op_sel_hi:[1,0,1]
	v_pk_fma_f32 v[10:11], v[40:41], s[20:21], v[10:11] op_sel_hi:[1,0,1]
	v_pk_fma_f32 v[8:9], v[38:39], s[20:21], v[8:9] op_sel_hi:[1,0,1]
	v_pk_fma_f32 v[6:7], v[40:41], s[22:23], v[6:7] op_sel_hi:[1,0,1]
	v_pk_fma_f32 v[4:5], v[38:39], s[22:23], v[4:5] op_sel_hi:[1,0,1]
	v_pk_fma_f32 v[2:3], v[28:29], s[24:25], v[2:3] op_sel_hi:[1,0,1]
	v_pk_fma_f32 v[0:1], v[26:27], s[24:25], v[0:1] op_sel_hi:[1,0,1]
	v_pk_fma_f32 v[10:11], v[28:29], s[26:27], v[10:11] op_sel_hi:[1,0,1]
	v_pk_fma_f32 v[8:9], v[26:27], s[26:27], v[8:9] op_sel_hi:[1,0,1]
	v_pk_fma_f32 v[6:7], v[28:29], s[28:29], v[6:7] op_sel_hi:[1,0,1]
	v_pk_fma_f32 v[4:5], v[26:27], s[28:29], v[4:5] op_sel_hi:[1,0,1]
	v_pk_fma_f32 v[2:3], v[32:33], s[30:31], v[2:3] op_sel_hi:[1,0,1]
	v_pk_fma_f32 v[0:1], v[30:31], s[30:31], v[0:1] op_sel_hi:[1,0,1]
	v_pk_fma_f32 v[10:11], v[32:33], s[34:35], v[10:11] op_sel_hi:[1,0,1]
	v_pk_fma_f32 v[8:9], v[30:31], s[34:35], v[8:9] op_sel_hi:[1,0,1]
	v_pk_fma_f32 v[6:7], v[32:33], s[36:37], v[6:7] op_sel_hi:[1,0,1]
	v_pk_fma_f32 v[4:5], v[30:31], s[36:37], v[4:5] op_sel_hi:[1,0,1]
	v_pk_fma_f32 v[2:3], v[150:151], s[38:39], v[2:3] op_sel_hi:[1,0,1]
	v_pk_fma_f32 v[0:1], v[148:149], s[38:39], v[0:1] op_sel_hi:[1,0,1]
	v_pk_fma_f32 v[10:11], v[150:151], s[40:41], v[10:11] op_sel_hi:[1,0,1]
	v_pk_fma_f32 v[8:9], v[148:149], s[40:41], v[8:9] op_sel_hi:[1,0,1]
	v_pk_fma_f32 v[6:7], v[150:151], s[42:43], v[6:7] op_sel_hi:[1,0,1]
	v_pk_fma_f32 v[4:5], v[148:149], s[42:43], v[4:5] op_sel_hi:[1,0,1]
	v_pk_fma_f32 v[2:3], v[36:37], s[60:61], v[2:3] op_sel_hi:[1,0,1]
	v_pk_fma_f32 v[0:1], v[34:35], s[60:61], v[0:1] op_sel_hi:[1,0,1]
	v_pk_fma_f32 v[10:11], v[36:37], s[62:63], v[10:11] op_sel_hi:[1,0,1]
	v_pk_fma_f32 v[8:9], v[34:35], s[62:63], v[8:9] op_sel_hi:[1,0,1]
	v_pk_fma_f32 v[6:7], v[36:37], s[64:65], v[6:7] op_sel_hi:[1,0,1]
	v_pk_fma_f32 v[4:5], v[34:35], s[64:65], v[4:5] op_sel_hi:[1,0,1]
	s_waitcnt vmcnt(1)
	v_pk_fma_f32 v[2:3], v[48:49], s[66:67], v[2:3] op_sel_hi:[1,0,1]
	v_pk_fma_f32 v[0:1], v[46:47], s[66:67], v[0:1] op_sel_hi:[1,0,1]
	v_pk_fma_f32 v[10:11], v[48:49], s[68:69], v[10:11] op_sel_hi:[1,0,1]
	v_pk_fma_f32 v[8:9], v[46:47], s[68:69], v[8:9] op_sel_hi:[1,0,1]
	v_pk_fma_f32 v[6:7], v[48:49], s[70:71], v[6:7] op_sel_hi:[1,0,1]
	v_pk_fma_f32 v[4:5], v[46:47], s[70:71], v[4:5] op_sel_hi:[1,0,1]
	s_waitcnt vmcnt(0)
	v_pk_fma_f32 v[2:3], v[52:53], s[72:73], v[2:3] op_sel_hi:[1,0,1]
	v_pk_fma_f32 v[0:1], v[50:51], s[72:73], v[0:1] op_sel_hi:[1,0,1]
	v_pk_fma_f32 v[10:11], v[52:53], s[74:75], v[10:11] op_sel_hi:[1,0,1]
	v_pk_fma_f32 v[8:9], v[50:51], s[74:75], v[8:9] op_sel_hi:[1,0,1]
	v_pk_fma_f32 v[6:7], v[52:53], s[18:19], v[6:7] op_sel_hi:[1,0,1]
	v_pk_fma_f32 v[4:5], v[50:51], s[18:19], v[4:5] op_sel_hi:[1,0,1]
	s_cbranch_scc0 .LBB0_47
	s_lshl_b32 s0, s12, 2
	s_add_i32 s0, s0, s13
	v_readlane_b32 s52, v240, 22
	s_mul_i32 s1, s0, 3
	s_mul_i32 s0, s0, 0x24000
	v_readlane_b32 s54, v240, 24
	s_mul_hi_i32 s1, s1, 0xc000
	v_readlane_b32 s55, v240, 25
	s_add_u32 s0, s54, s0
	s_addc_u32 s1, s55, s1
	v_lshl_add_u64 v[12:13], v[16:17], 2, s[0:1]
	global_store_dwordx4 v[12:13], v[0:3], off
	v_readlane_b32 s0, v238, 3
	s_add_i32 s11, s11, s0
	v_add_co_u32_e32 v0, vcc, 0xc000, v12
	v_readlane_b32 s53, v240, 23
	s_nop 0
	v_addc_co_u32_e32 v1, vcc, 0, v13, vcc
	global_store_dwordx4 v[0:1], v[8:11], off
	v_add_co_u32_e32 v0, vcc, 0x18000, v12
	v_readlane_b32 s56, v240, 26
	v_readlane_b32 s57, v240, 27
	v_readlane_b32 s60, v240, 30
	v_readlane_b32 s61, v240, 31
	v_readlane_b32 s62, v240, 32
	v_readlane_b32 s63, v240, 33
	v_readlane_b32 s66, v240, 36
	v_readlane_b32 s67, v240, 37
	v_addc_co_u32_e32 v1, vcc, 0, v13, vcc
	s_cmpk_gt_i32 s11, 0x17ff
	v_readlane_b32 s58, v240, 28
	v_readlane_b32 s59, v240, 29
	v_readlane_b32 s64, v240, 34
	v_readlane_b32 s65, v240, 35
	v_readlane_b32 s1, v238, 4
	global_store_dwordx4 v[0:1], v[4:7], off
	s_cbranch_scc0 .LBB0_46

.LBB0_104:
	v_lshl_add_u64 v[18:19], v[2:3], 0, s[8:9]
	global_load_dword v20, v[18:19], off
	v_add_co_u32_e32 v8, vcc, 0x90000, v18
	s_mov_b64 s[0:1], vcc
	v_add_co_u32_e32 v10, vcc, 0x120000, v18
	v_addc_co_u32_e64 v9, s[0:1], 0, v19, s[0:1]
	global_load_dword v21, v[8:9], off
	s_mov_b64 s[0:1], vcc
	v_add_co_u32_e32 v12, vcc, 0x1b0000, v18
	v_addc_co_u32_e64 v11, s[0:1], 0, v19, s[0:1]
	global_load_dword v22, v[10:11], off
	s_mov_b64 s[0:1], vcc
	v_add_co_u32_e32 v8, vcc, 0x240000, v18
	v_addc_co_u32_e64 v13, s[0:1], 0, v19, s[0:1]
	global_load_dword v23, v[12:13], off
	s_mov_b64 s[0:1], vcc
	v_add_co_u32_e32 v10, vcc, 0x2d0000, v18
	v_addc_co_u32_e64 v9, s[0:1], 0, v19, s[0:1]
	s_nop 0
	s_mov_b64 s[0:1], vcc
	v_addc_co_u32_e64 v11, s[0:1], 0, v19, s[0:1]
	global_load_dword v8, v[8:9], off
	s_nop 0
	global_load_dword v24, v[10:11], off
	v_add_co_u32_e32 v12, vcc, 0x360000, v18
	s_mov_b64 s[0:1], vcc
	s_nop 0
	v_add_co_u32_e32 v6, vcc, 0x3f0000, v18
	v_addc_co_u32_e64 v13, s[0:1], 0, v19, s[0:1]
	global_load_dword v25, v[12:13], off
	v_addc_co_u32_e32 v7, vcc, 0, v19, vcc
	global_load_dword v6, v[6:7], off
	s_add_u32 s8, s8, 0x480000
	s_addc_u32 s9, s9, 0
	s_cmp_eq_u32 s8, 0x1200000
	s_waitcnt vmcnt(8)
	s_waitcnt vmcnt(7)
	v_add_f32_e32 v4, v4, v20
	s_waitcnt vmcnt(6)
	v_add_f32_e32 v4, v4, v21
	s_waitcnt vmcnt(5)
	v_add_f32_e32 v4, v4, v22
	s_waitcnt vmcnt(4)
	v_add_f32_e32 v4, v4, v23
	s_waitcnt vmcnt(3)
	v_add_f32_e32 v4, v4, v8
	s_waitcnt vmcnt(2)
	v_add_f32_e32 v4, v4, v24
	s_waitcnt vmcnt(1)
	v_add_f32_e32 v4, v4, v25
	s_waitcnt vmcnt(0)
	v_add_f32_e32 v4, v4, v6
	s_cbranch_scc0 .LBB0_104
	v_lshl_add_u64 v[2:3], v[0:1], 2, s[52:53]
	v_add_u32_e32 v0, s2, v0
	s_mov_b32 s0, 0x23fff
	v_cmp_lt_i32_e32 vcc, s0, v0
	s_or_b64 s[6:7], vcc, s[6:7]
	global_store_dword v[2:3], v4, off
	s_andn2_b64 exec, exec, s[6:7]
	s_cbranch_execnz .LBB0_103

.LBB0_207:
	s_and_b64 s[4:5], s[4:5], exec
	s_cselect_b32 s5, s6, 2
	s_mul_i32 s4, s10, 0x110
	s_ashr_i32 s6, s8, 4
	s_add_i32 s4, s4, s6
	s_cmpk_gt_i32 s3, 0x1fff
	s_cselect_b64 s[6:7], -1, 0
	s_and_b64 s[6:7], s[0:1], s[6:7]
	s_and_b64 s[6:7], s[6:7], exec
	v_readlane_b32 s12, v239, 3
	s_cselect_b32 s7, 0, s11
	s_cselect_b32 s6, s9, s3
	v_readlane_b32 s13, v239, 4
	v_readlane_b32 s16, v239, 7
	v_readlane_b32 s17, v239, 8
	s_cselect_b32 s9, s17, s13
	s_cselect_b32 s10, s16, s12
	s_lshl_b64 s[6:7], s[6:7], 13
	s_add_u32 s6, s10, s6
	s_addc_u32 s7, s9, s7
	v_lshl_add_u64 v[156:157], s[6:7], 0, v[106:107]
	global_load_dwordx4 v[60:63], v[156:157], off
	global_load_dwordx4 v[64:67], v[156:157], off offset:1024
	global_load_dwordx4 v[56:59], v[156:157], off offset:2048
	global_load_dwordx4 v[48:51], v[156:157], off offset:3072
	v_add_co_u32_e32 v32, vcc, s2, v156
	s_mul_hi_i32 s7, s5, 0xc000
	s_nop 0
	v_addc_co_u32_e32 v33, vcc, 0, v157, vcc
	global_load_dwordx4 v[44:47], v[32:33], off
	global_load_dwordx4 v[40:43], v[32:33], off offset:1024
	global_load_dwordx4 v[36:39], v[32:33], off offset:2048
	global_load_dwordx4 v[32:35], v[32:33], off offset:3072
	s_mul_i32 s5, s5, 0xc000
	s_add_u32 s6, s52, s5
	s_addc_u32 s7, s53, s7
	v_lshl_add_u64 v[156:157], s[6:7], 0, v[106:107]
	global_load_dwordx4 v[76:79], v[156:157], off
	global_load_dwordx4 v[72:75], v[156:157], off offset:1024
	global_load_dwordx4 v[68:71], v[156:157], off offset:2048
	global_load_dwordx4 v[52:55], v[156:157], off offset:3072
	s_movk_i32 s5, 0x3000
	v_add_co_u32_e32 v134, vcc, s5, v156
	s_mov_b64 s[6:7], 0x2000
	s_nop 0
	v_lshl_add_u64 v[158:159], v[156:157], 0, s[6:7]
	global_load_dwordx4 v[110:113], v[158:159], off offset:1024
	global_load_dwordx4 v[114:117], v[158:159], off offset:2048
	global_load_dwordx4 v[118:121], v[158:159], off offset:3072
	v_addc_co_u32_e32 v135, vcc, 0, v157, vcc
	global_load_dwordx4 v[122:125], v[134:135], off offset:-4096
	global_load_dwordx4 v[126:129], v[134:135], off
	global_load_dwordx4 v[130:133], v[134:135], off offset:1024
	global_load_dwordx4 v[84:87], v[134:135], off offset:2048
	global_load_dwordx4 v[80:83], v[134:135], off offset:3072
	v_add_co_u32_e32 v146, vcc, s2, v156
	s_mov_b32 s5, 0x800000
	s_nop 0
	v_addc_co_u32_e32 v147, vcc, 0, v157, vcc
	v_readlane_b32 s14, v239, 5
	v_readlane_b32 s15, v239, 6
	v_readlane_b32 s18, v239, 9
	v_readlane_b32 s19, v239, 10
	v_readlane_b32 s20, v239, 11
	v_readlane_b32 s21, v239, 12
	v_readlane_b32 s22, v239, 13
	v_readlane_b32 s23, v239, 14
	v_readlane_b32 s24, v239, 15
	v_readlane_b32 s25, v239, 16
	v_readlane_b32 s26, v239, 17
	v_readlane_b32 s27, v239, 18
	s_waitcnt vmcnt(19)
	v_mul_f32_e32 v109, v61, v61
	s_waitcnt vmcnt(18)
	v_mul_f32_e32 v152, v65, v65
	s_waitcnt vmcnt(17)
	v_mul_f32_e32 v153, v57, v57
	v_fmac_f32_e32 v109, v60, v60
	v_fmac_f32_e32 v152, v64, v64
	s_waitcnt vmcnt(16)
	v_mul_f32_e32 v154, v49, v49
	v_fmac_f32_e32 v153, v56, v56
	s_waitcnt vmcnt(15)
	v_mov_b32_e32 v136, v45
	s_waitcnt vmcnt(14)
	v_mov_b32_e32 v137, v41
	v_fmac_f32_e32 v109, v62, v62
	v_fmac_f32_e32 v152, v66, v66
	v_fmac_f32_e32 v154, v48, v48
	v_mov_b32_e32 v134, v44
	v_mov_b32_e32 v135, v40
	v_pk_mul_f32 v[136:137], v[136:137], v[136:137]
	v_fmac_f32_e32 v153, v58, v58
	v_fmac_f32_e32 v109, v63, v63
	v_fmac_f32_e32 v152, v67, v67
	s_waitcnt vmcnt(13)
	v_mov_b32_e32 v140, v37
	s_waitcnt vmcnt(12)
	v_mov_b32_e32 v141, v33
	v_mov_b32_e32 v142, v46
	v_mov_b32_e32 v143, v42
	v_fmac_f32_e32 v154, v50, v50
	v_pk_fma_f32 v[134:135], v[134:135], v[134:135], v[136:137]
	v_fmac_f32_e32 v153, v59, v59
	v_add_f32_e32 v109, v109, v152
	v_mov_b32_e32 v138, v36
	v_mov_b32_e32 v139, v32
	v_mov_b32_e32 v144, v47
	v_mov_b32_e32 v145, v43
	v_pk_mul_f32 v[140:141], v[140:141], v[140:141]
	v_fmac_f32_e32 v154, v51, v51
	v_pk_fma_f32 v[134:135], v[142:143], v[142:143], v[134:135]
	v_add_f32_e32 v109, v109, v153
	v_mov_b32_e32 v148, v38
	v_mov_b32_e32 v149, v34
	v_pk_fma_f32 v[136:137], v[138:139], v[138:139], v[140:141]
	v_pk_fma_f32 v[134:135], v[144:145], v[144:145], v[134:135]
	v_add_f32_e32 v109, v109, v154
	v_mov_b32_e32 v150, v39
	v_mov_b32_e32 v151, v35
	v_pk_fma_f32 v[136:137], v[148:149], v[148:149], v[136:137]
	v_add_f32_e32 v109, v109, v134
	v_pk_fma_f32 v[136:137], v[150:151], v[150:151], v[136:137]
	v_add_f32_e32 v109, v109, v135
	v_add_f32_e32 v109, v109, v136
	v_add_f32_e32 v109, v109, v137
	global_load_dwordx4 v[134:137], v[146:147], off
	global_load_dwordx4 v[138:141], v[146:147], off offset:1024
	global_load_dwordx4 v[142:145], v[146:147], off offset:2048
	global_load_dwordx4 v[146:149], v[146:147], off offset:3072
	v_mbcnt_lo_u32_b32 v150, -1, 0
	v_mbcnt_hi_u32_b32 v150, -1, v150
	s_waitcnt vmcnt(11)
	v_pk_add_f32 v[110:111], v[110:111], 1.0 op_sel_hi:[1,0]
	s_waitcnt vmcnt(8)
	v_pk_add_f32 v[122:123], v[122:123], 1.0 op_sel_hi:[1,0]
	v_lshlrev_b32_e32 v150, 2, v150
	s_nop 1
	v_xor_b32_e32 v155, 16, v150
	v_xor_b32_e32 v151, 0x80, v150
	ds_bpermute_b32 v151, v151, v109
	v_pk_add_f32 v[124:125], v[124:125], 1.0 op_sel_hi:[1,0]
	v_pk_add_f32 v[112:113], v[112:113], 1.0 op_sel_hi:[1,0]
	s_waitcnt lgkmcnt(0)
	v_add_f32_e32 v109, v109, v151
	v_xor_b32_e32 v151, 64, v150
	ds_bpermute_b32 v151, v151, v109
	s_waitcnt lgkmcnt(0)
	v_add_f32_e32 v109, v109, v151
	v_xor_b32_e32 v151, 32, v150
	ds_bpermute_b32 v151, v151, v109
	s_waitcnt lgkmcnt(0)
	v_add_f32_e32 v109, v109, v151
	ds_bpermute_b32 v156, v155, v109
	v_xor_b32_e32 v157, 8, v150
	v_xor_b32_e32 v150, 4, v150
	s_waitcnt lgkmcnt(0)
	v_add_f32_e32 v109, v109, v156
	ds_bpermute_b32 v151, v157, v109
	s_waitcnt lgkmcnt(0)
	v_add_f32_e32 v109, v109, v151
	ds_bpermute_b32 v150, v150, v109
	s_waitcnt lgkmcnt(0)
	v_add_f32_e32 v109, v109, v150
	v_fmamk_f32 v109, v109, 0x3a000000, v108
	v_mul_f32_e32 v150, 0x4b800000, v109
	v_cmp_gt_f32_e32 vcc, s5, v109
	s_ashr_i32 s5, s4, 31
	s_lshl_b64 s[4:5], s[4:5], 10
	v_cndmask_b32_e32 v109, v109, v150, vcc
	v_rsq_f32_e32 v109, v109
	s_add_u32 s4, s62, s4
	s_addc_u32 s5, s63, s5
	s_lshl_b32 s6, s8, 5
	v_mul_f32_e32 v150, 0x45800000, v109
	v_cndmask_b32_e32 v150, v109, v150, vcc
	v_pk_mul_f32 v[64:65], v[64:65], v[150:151] op_sel_hi:[1,0]
	v_pk_mul_f32 v[60:61], v[60:61], v[150:151] op_sel_hi:[1,0]
	v_pk_mul_f32 v[62:63], v[62:63], v[150:151] op_sel_hi:[1,0]
	v_pk_mul_f32 v[56:57], v[56:57], v[150:151] op_sel_hi:[1,0]
	v_pk_mul_f32 v[64:65], v[4:5], v[64:65]
	s_and_b32 s6, s6, 0x1e0
	v_pk_mul_f32 v[60:61], v[0:1], v[60:61]
	v_pk_mul_f32 v[62:63], v[2:3], v[62:63]
	v_pk_fma_f32 v[64:65], v[110:111], v[64:65], v[72:73]
	v_pk_mul_f32 v[56:57], v[8:9], v[56:57]
	v_pk_add_f32 v[72:73], v[114:115], 1.0 op_sel_hi:[1,0]
	v_pk_mul_f32 v[58:59], v[58:59], v[150:151] op_sel_hi:[1,0]
	s_add_u32 s4, s4, s6
	v_pk_fma_f32 v[60:61], v[122:123], v[60:61], v[76:77]
	v_pk_fma_f32 v[62:63], v[124:125], v[62:63], v[78:79]
	v_pk_fma_f32 v[56:57], v[72:73], v[56:57], v[68:69]
	v_pk_add_f32 v[68:69], v[116:117], 1.0 op_sel_hi:[1,0]
	v_pk_mul_f32 v[58:59], v[10:11], v[58:59]
	s_addc_u32 s5, s5, 0
	v_pk_fma_f32 v[58:59], v[68:69], v[58:59], v[70:71]
	v_cvt_pk_bf16_f32 v60, v60, v61
	v_cvt_pk_bf16_f32 v61, v62, v63
	v_lshl_add_u64 v[62:63], s[4:5], 0, v[88:89]
	v_cvt_pk_bf16_f32 v56, v56, v57
	v_cvt_pk_bf16_f32 v57, v58, v59
	v_lshl_add_u64 v[58:59], v[62:63], 0, v[94:95]
	v_pk_mul_f32 v[48:49], v[48:49], v[150:151] op_sel_hi:[1,0]
	global_store_dwordx2 v[58:59], v[56:57], off
	v_pk_mul_f32 v[48:49], v[12:13], v[48:49]
	v_pk_add_f32 v[56:57], v[118:119], 1.0 op_sel_hi:[1,0]
	v_pk_mul_f32 v[50:51], v[50:51], v[150:151] op_sel_hi:[1,0]
	v_pk_fma_f32 v[48:49], v[56:57], v[48:49], v[52:53]
	v_pk_mul_f32 v[50:51], v[14:15], v[50:51]
	v_pk_add_f32 v[52:53], v[120:121], 1.0 op_sel_hi:[1,0]
	v_cvt_pk_bf16_f32 v48, v48, v49
	v_pk_fma_f32 v[50:51], v[52:53], v[50:51], v[54:55]
	v_pk_mul_f32 v[44:45], v[44:45], v[150:151] op_sel_hi:[1,0]
	v_cvt_pk_bf16_f32 v49, v50, v51
	v_lshl_add_u64 v[50:51], v[62:63], 0, v[96:97]
	global_store_dwordx2 v[50:51], v[48:49], off
	v_pk_mul_f32 v[44:45], v[16:17], v[44:45]
	s_waitcnt vmcnt(9)
	v_pk_add_f32 v[48:49], v[126:127], 1.0 op_sel_hi:[1,0]
	v_pk_mul_f32 v[46:47], v[46:47], v[150:151] op_sel_hi:[1,0]
	s_waitcnt vmcnt(5)
	v_pk_fma_f32 v[44:45], v[48:49], v[44:45], v[134:135]
	v_pk_mul_f32 v[46:47], v[18:19], v[46:47]
	v_pk_add_f32 v[48:49], v[128:129], 1.0 op_sel_hi:[1,0]
	v_cvt_pk_bf16_f32 v44, v44, v45
	v_pk_fma_f32 v[46:47], v[48:49], v[46:47], v[136:137]
	v_pk_mul_f32 v[40:41], v[40:41], v[150:151] op_sel_hi:[1,0]
	v_cvt_pk_bf16_f32 v45, v46, v47
	v_lshl_add_u64 v[46:47], v[62:63], 0, v[98:99]
	global_store_dwordx2 v[46:47], v[44:45], off
	v_pk_mul_f32 v[40:41], v[20:21], v[40:41]
	v_pk_add_f32 v[44:45], v[130:131], 1.0 op_sel_hi:[1,0]
	v_pk_mul_f32 v[42:43], v[42:43], v[150:151] op_sel_hi:[1,0]
	s_waitcnt vmcnt(5)
	v_pk_fma_f32 v[40:41], v[44:45], v[40:41], v[138:139]
	v_pk_mul_f32 v[42:43], v[22:23], v[42:43]
	v_pk_add_f32 v[44:45], v[132:133], 1.0 op_sel_hi:[1,0]
	v_cvt_pk_bf16_f32 v40, v40, v41
	v_pk_fma_f32 v[42:43], v[44:45], v[42:43], v[140:141]
	v_pk_mul_f32 v[36:37], v[36:37], v[150:151] op_sel_hi:[1,0]
	v_cvt_pk_bf16_f32 v41, v42, v43
	v_lshl_add_u64 v[42:43], v[62:63], 0, v[100:101]
	global_store_dwordx2 v[42:43], v[40:41], off
	v_pk_mul_f32 v[36:37], v[24:25], v[36:37]
	v_pk_add_f32 v[40:41], v[84:85], 1.0 op_sel_hi:[1,0]
	v_pk_mul_f32 v[38:39], v[38:39], v[150:151] op_sel_hi:[1,0]
	s_waitcnt vmcnt(5)
	v_pk_fma_f32 v[36:37], v[40:41], v[36:37], v[142:143]
	v_pk_mul_f32 v[38:39], v[26:27], v[38:39]
	v_pk_add_f32 v[40:41], v[86:87], 1.0 op_sel_hi:[1,0]
	v_cvt_pk_bf16_f32 v36, v36, v37
	v_pk_fma_f32 v[38:39], v[40:41], v[38:39], v[144:145]
	v_pk_mul_f32 v[32:33], v[32:33], v[150:151] op_sel_hi:[1,0]
	v_cvt_pk_bf16_f32 v37, v38, v39
	v_lshl_add_u64 v[38:39], v[62:63], 0, v[102:103]
	v_pk_mul_f32 v[66:67], v[66:67], v[150:151] op_sel_hi:[1,0]
	global_store_dwordx2 v[38:39], v[36:37], off
	v_pk_mul_f32 v[32:33], v[28:29], v[32:33]
	v_pk_add_f32 v[36:37], v[80:81], 1.0 op_sel_hi:[1,0]
	v_pk_mul_f32 v[34:35], v[34:35], v[150:151] op_sel_hi:[1,0]
	v_pk_mul_f32 v[66:67], v[6:7], v[66:67]
	s_waitcnt vmcnt(5)
	v_pk_fma_f32 v[32:33], v[36:37], v[32:33], v[146:147]
	v_pk_mul_f32 v[34:35], v[30:31], v[34:35]
	v_pk_add_f32 v[36:37], v[82:83], 1.0 op_sel_hi:[1,0]
	v_readlane_b32 s4, v238, 3
	v_pk_fma_f32 v[66:67], v[112:113], v[66:67], v[74:75]
	v_lshl_add_u64 v[68:69], v[62:63], 0, v[90:91]
	v_pk_fma_f32 v[34:35], v[36:37], v[34:35], v[148:149]
	s_add_i32 s3, s3, s4
	global_store_dwordx2 v[68:69], v[60:61], off
	v_cvt_pk_bf16_f32 v60, v64, v65
	v_cvt_pk_bf16_f32 v61, v66, v67
	v_lshl_add_u64 v[64:65], v[62:63], 0, v[92:93]
	v_cvt_pk_bf16_f32 v32, v32, v33
	v_cvt_pk_bf16_f32 v33, v34, v35
	v_lshl_add_u64 v[34:35], v[62:63], 0, v[104:105]
	s_cmpk_lt_i32 s3, 0x2200
	global_store_dwordx2 v[64:65], v[60:61], off
	v_readlane_b32 s5, v238, 4
	global_store_dwordx2 v[34:35], v[32:33], off
	s_cbranch_scc0 .LBB0_212

.LBB0_271:
	s_or_b64 exec, exec, s[6:7]
	s_lshr_b32 s14, s35, 3
	s_ashr_i32 s8, s35, 7
	s_lshl_b32 s6, s25, 17
	s_add_u32 s6, s64, s6
	s_addc_u32 s7, s65, 0
	s_mul_i32 s25, s25, 0x88100
	s_add_u32 s9, s62, s25
	s_addc_u32 s10, s63, 0
	s_mul_i32 s36, s8, 0x44000
	s_mul_hi_i32 s25, s8, 0x44000
	s_add_u32 s22, s9, s36
	s_addc_u32 s23, s10, s25
	v_lshl_add_u64 v[0:1], s[22:23], 0, v[80:81]
	v_lshl_add_u64 v[0:1], v[0:1], 0, v[74:75]
	global_load_dwordx4 v[110:113], v[0:1], off
	v_lshl_add_u64 v[0:1], s[6:7], 0, v[76:77]
	v_lshl_add_u64 v[32:33], v[0:1], 0, v[106:107]
	global_load_dwordx4 v[52:55], v[32:33], off
	v_lshl_add_u64 v[0:1], s[6:7], 0, v[78:79]
	v_lshl_add_u64 v[60:61], v[0:1], 0, v[106:107]
	global_load_dwordx4 v[56:59], v[60:61], off
	global_load_dwordx4 v[44:47], v[32:33], off offset:64
	global_load_dwordx4 v[48:51], v[60:61], off offset:64
	global_load_dwordx4 v[36:39], v[32:33], off offset:128
	global_load_dwordx4 v[40:43], v[60:61], off offset:128
	global_load_dwordx4 v[24:27], v[32:33], off offset:192
	global_load_dwordx4 v[28:31], v[60:61], off offset:192
	global_load_dwordx4 v[16:19], v[32:33], off offset:256
	global_load_dwordx4 v[20:23], v[60:61], off offset:256
	global_load_dwordx4 v[12:15], v[32:33], off offset:320
	global_load_dwordx4 v[0:3], v[60:61], off offset:320
	global_load_dwordx4 v[8:11], v[32:33], off offset:384
	global_load_dwordx4 v[4:7], v[60:61], off offset:384
	s_nop 0
	global_load_dwordx4 v[32:35], v[32:33], off offset:448
	v_add_u32_e32 v163, s16, v150
	global_load_dwordx4 v[60:63], v[60:61], off offset:448
	s_waitcnt lgkmcnt(0)
	s_barrier
	s_waitcnt vmcnt(17)
	v_mul_f32_e32 v67, 0x41800000, v67
	v_mul_f32_e32 v70, v68, v68
	v_mul_f32_e32 v126, v65, v67
	v_xor_b32_e32 v109, v66, v64
	v_fmamk_f32 v65, v70, 0xb94c1982, v157
	v_fmamk_f32 v66, v70, 0x37d75334, v158
	v_mul_f32_e32 v67, 0x3fb8aa3b, v126
	v_fmaak_f32 v65, v70, v65, 0xbe2aaa9d
	v_fmaak_f32 v66, v70, v66, 0x3d2aabf7
	v_fma_f32 v127, v126, s30, -v67
	v_rndne_f32_e32 v128, v67
	v_lshlrev_b32_e32 v71, 30, v69
	v_and_b32_e32 v69, 1, v69
	v_mul_f32_e32 v65, v70, v65
	v_fmaak_f32 v66, v70, v66, 0xbf000004
	v_fmac_f32_e32 v127, 0x32a5705f, v126
	v_sub_f32_e32 v67, v67, v128
	v_fmac_f32_e32 v68, v68, v65
	v_fma_f32 v65, v70, v66, 1.0
	v_add_f32_e32 v66, v67, v127
	v_cmp_eq_u32_e64 s[6:7], 0, v69
	v_and_b32_e32 v71, 0x80000000, v71
	v_cvt_i32_f32_e32 v128, v128
	v_cndmask_b32_e64 v70, v65, v68, s[6:7]
	v_xor_b32_e32 v70, v109, v70
	v_xor_b32_e32 v70, v70, v71
	s_cmp_eq_u32 s2, 1
	s_waitcnt vmcnt(16)
	ds_write_b128 v73, v[110:113]
	ds_write_b128 v73, v[110:113] offset:8448
	s_waitcnt lgkmcnt(0)
	s_barrier
	ds_read_b128 v[168:171], v163
	ds_read_b128 v[172:175], v163 offset:64
	ds_read_b128 v[176:179], v163 offset:128
	ds_read_b128 v[180:183], v163 offset:192
	ds_read_b128 v[184:187], v163 offset:256
	ds_read_b128 v[188:191], v163 offset:320
	s_waitcnt vmcnt(15) lgkmcnt(6)
	s_waitcnt lgkmcnt(5)
	v_mfma_f32_16x16x32_bf16 v[118:121], v[168:171], v[52:55], 0
	s_waitcnt vmcnt(14)
	v_mfma_f32_16x16x32_bf16 v[110:113], v[168:171], v[56:59], 0
	s_waitcnt vmcnt(13)
	s_waitcnt lgkmcnt(4)
	v_mfma_f32_16x16x32_bf16 v[118:121], v[172:175], v[44:47], v[118:121]
	s_waitcnt vmcnt(12)
	v_mfma_f32_16x16x32_bf16 v[110:113], v[172:175], v[48:51], v[110:113]
	s_waitcnt vmcnt(11)
	s_waitcnt lgkmcnt(3)
	v_mfma_f32_16x16x32_bf16 v[118:121], v[176:179], v[36:39], v[118:121]
	s_waitcnt vmcnt(10)
	v_mfma_f32_16x16x32_bf16 v[110:113], v[176:179], v[40:43], v[110:113]
	s_waitcnt vmcnt(9)
	s_waitcnt lgkmcnt(2)
	v_mfma_f32_16x16x32_bf16 v[118:121], v[180:183], v[24:27], v[118:121]
	s_waitcnt vmcnt(8)
	v_mfma_f32_16x16x32_bf16 v[110:113], v[180:183], v[28:31], v[110:113]
	s_waitcnt vmcnt(7)
	s_waitcnt lgkmcnt(1)
	v_mfma_f32_16x16x32_bf16 v[118:121], v[184:187], v[16:19], v[118:121]
	s_waitcnt vmcnt(6)
	v_mfma_f32_16x16x32_bf16 v[110:113], v[184:187], v[20:23], v[110:113]
	v_xor_b32_e32 v122, 0x80000000, v68
	v_exp_f32_e32 v124, v66
	ds_read_b128 v[66:69], v163 offset:384
	ds_read_b128 v[168:171], v163 offset:448
	s_waitcnt vmcnt(5)
	s_waitcnt lgkmcnt(2)
	v_mfma_f32_16x16x32_bf16 v[118:121], v[188:191], v[12:15], v[118:121]
	v_cndmask_b32_e64 v65, v122, v65, s[6:7]
	s_movk_i32 s6, 0x1f8
	v_xor_b32_e32 v65, v65, v71
	s_waitcnt vmcnt(4)
	v_mfma_f32_16x16x32_bf16 v[110:113], v[188:191], v[0:3], v[110:113]
	v_cmp_class_f32_e64 s[6:7], v64, s6
	s_waitcnt vmcnt(3) lgkmcnt(1)
	v_mfma_f32_16x16x32_bf16 v[118:121], v[66:69], v[8:11], v[118:121]
	v_cndmask_b32_e64 v122, v162, v65, s[6:7]
	v_cndmask_b32_e64 v123, v162, v70, s[6:7]
	v_ldexp_f32 v70, v124, v128
	s_waitcnt vmcnt(2)
	v_mfma_f32_16x16x32_bf16 v[64:67], v[66:69], v[4:7], v[110:113]
	v_cmp_ngt_f32_e64 s[6:7], s31, v126
	s_nop 1
	v_cndmask_b32_e64 v68, 0, v70, s[6:7]
	v_cmp_nlt_f32_e64 s[6:7], s34, v126
	s_waitcnt vmcnt(0)
	s_waitcnt lgkmcnt(0)
	v_mfma_f32_16x16x32_bf16 v[64:67], v[168:171], v[60:63], v[64:67]
	v_cndmask_b32_e64 v110, v159, v68, s[6:7]
	s_cselect_b64 s[6:7], -1, 0
	v_mfma_f32_16x16x32_bf16 v[68:71], v[168:171], v[32:35], v[118:121]
	s_cmp_eq_u32 s2, 2
	s_cselect_b64 s[8:9], -1, 0
	s_cmp_eq_u32 s2, 3
	s_nop 1
	v_cndmask_b32_e64 v112, v64, v65, s[6:7]
	v_cndmask_b32_e64 v112, v112, v66, s[8:9]
	s_nop 0
	v_cndmask_b32_e64 v109, v68, v69, s[6:7]
	s_cselect_b64 s[6:7], -1, 0
	s_cmp_eq_u32 s3, 1
	v_cndmask_b32_e64 v109, v109, v70, s[8:9]
	s_cselect_b64 s[8:9], -1, 0
	s_cmp_eq_u32 s3, 2
	v_cndmask_b32_e64 v120, v109, v71, s[6:7]
	v_cndmask_b32_e64 v121, v112, v67, s[6:7]
	s_cselect_b64 s[6:7], -1, 0
	s_cmp_eq_u32 s3, 3
	v_cndmask_b32_e64 v113, v68, v69, s[8:9]
	v_cndmask_b32_e64 v109, v64, v65, s[8:9]
	s_cselect_b64 s[8:9], -1, 0
	s_cmp_eq_u32 s26, 1
	v_cndmask_b32_e64 v112, v113, v70, s[6:7]
	v_cndmask_b32_e64 v109, v109, v66, s[6:7]
	s_cselect_b64 s[6:7], -1, 0
	s_cmp_eq_u32 s26, 2
	v_cndmask_b32_e64 v136, v112, v71, s[8:9]
	v_cndmask_b32_e64 v112, v68, v69, s[6:7]
	v_cndmask_b32_e64 v137, v109, v67, s[8:9]
	s_cselect_b64 s[8:9], -1, 0
	s_cmp_eq_u32 s26, 3
	v_cndmask_b32_e64 v109, v112, v70, s[8:9]
	s_cselect_b64 s[10:11], -1, 0
	s_cmp_eq_u32 s27, 1
	v_cndmask_b32_e64 v131, v109, v71, s[10:11]
	v_cndmask_b32_e64 v109, v64, v65, s[6:7]
	s_cselect_b64 s[6:7], -1, 0
	s_cmp_eq_u32 s27, 2
	v_cndmask_b32_e64 v109, v109, v66, s[8:9]
	v_cndmask_b32_e64 v68, v68, v69, s[6:7]
	s_cselect_b64 s[8:9], -1, 0
	s_cmp_eq_u32 s27, 3
	v_cndmask_b32_e64 v64, v64, v65, s[6:7]
	v_cndmask_b32_e64 v130, v109, v67, s[10:11]
	v_cndmask_b32_e64 v68, v68, v70, s[8:9]
	s_cselect_b64 s[10:11], -1, 0
	v_cndmask_b32_e64 v64, v64, v66, s[8:9]
	v_pk_mul_f32 v[110:111], v[110:111], v[122:123] op_sel_hi:[0,1]
	v_cndmask_b32_e64 v70, v68, v71, s[10:11]
	v_cndmask_b32_e64 v71, v64, v67, s[10:11]
	v_mov_b32_e32 v66, v121
	v_mov_b32_e32 v67, v120
	v_pk_mul_f32 v[64:65], v[110:111], v[120:121]
	v_pk_mul_f32 v[66:67], v[110:111], v[66:67]
	v_sub_f32_e32 v64, v64, v65
	v_add_f32_e32 v65, v67, v66
	v_add_f32_e32 v66, v137, v65
	v_add_f32_e32 v64, v136, v64
	v_pk_mul_f32 v[66:67], v[110:111], v[66:67] op_sel_hi:[1,0]
	v_xor_b32_e32 v112, 0x80000000, v111
	v_pk_fma_f32 v[68:69], v[110:111], v[64:65], v[66:67] op_sel:[1,0,0] op_sel_hi:[0,1,1]
	v_pk_fma_f32 v[64:65], v[110:111], v[64:65], v[66:67] op_sel:[1,0,0] op_sel_hi:[0,0,1] neg_lo:[0,0,1] neg_hi:[0,0,1]
	v_mov_b32_e32 v69, v65
	v_pk_add_f32 v[64:65], v[130:131], v[68:69]
	v_mov_b32_e32 v113, v110
	v_pk_mul_f32 v[66:67], v[110:111], v[64:65] op_sel:[0,1] op_sel_hi:[1,0]
	v_pk_mul_f32 v[64:65], v[110:111], v[64:65]
	v_sub_f32_e32 v66, v66, v67
	v_add_f32_e32 v64, v64, v65
	v_add_f32_e32 v64, v71, v64
	ds_bpermute_b32 v123, v153, v64
	ds_bpermute_b32 v119, v154, v64
	ds_bpermute_b32 v117, v155, v64
	ds_bpermute_b32 v125, v156, v64
	v_add_f32_e32 v66, v70, v66
	ds_bpermute_b32 v122, v153, v66
	ds_bpermute_b32 v118, v154, v66
	ds_bpermute_b32 v116, v155, v66
	ds_bpermute_b32 v124, v156, v66
	v_lshl_add_u64 v[64:65], s[22:23], 0, v[74:75]
	s_nop 1
	v_lshl_add_u64 v[66:67], v[64:65], 0, v[82:83]
	v_lshl_add_u64 v[68:69], v[64:65], 0, v[84:85]
	global_load_dwordx4 v[64:67], v[66:67], off
	s_nop 0
	global_load_dwordx4 v[68:71], v[68:69], off
	v_pk_mul_f32 v[112:113], v[110:111], v[112:113] op_sel:[1,0]
	v_pk_mov_b32 v[114:115], v[110:111], v[110:111] op_sel:[1,0]
	v_pk_fma_f32 v[112:113], v[110:111], v[110:111], v[112:113] op_sel_hi:[0,1,1]
	v_xor_b32_e32 v126, 0x80000000, v113
	v_mov_b32_e32 v127, v112
	v_pk_mul_f32 v[126:127], v[112:113], v[126:127] op_sel:[1,0]
	v_cmp_lt_i32_e64 s[6:7], 0, v151
	v_pk_fma_f32 v[112:113], v[112:113], v[112:113], v[126:127] op_sel_hi:[1,0,1]
	s_mov_b64 s[8:9], 0
	v_mul_f32_e32 v109, 0, v112
	v_mul_f32_e32 v127, 0, v113
	v_sub_f32_e32 v126, v109, v127
	v_fmac_f32_e32 v127, 0, v112
	s_waitcnt lgkmcnt(3)
	v_pk_add_f32 v[122:123], v[126:127], v[122:123]
	s_and_saveexec_b64 s[10:11], s[6:7]
	s_xor_b64 s[10:11], exec, s[10:11]
	s_cbranch_execz .LBB0_275
	v_cmp_eq_u32_e64 s[6:7], 1, v151
	s_mov_b64 s[8:9], -1
	s_and_saveexec_b64 s[12:13], s[6:7]
	s_xor_b64 s[8:9], exec, -1
	v_mov_b32_e32 v133, v123
	v_mov_b32_e32 v132, v122
	s_or_b64 exec, exec, s[12:13]
	s_and_b64 s[8:9], s[8:9], exec

.LBB0_281:
	s_add_i32 s8, s36, -2
	s_and_b32 s8, s8, 2
	s_add_i32 s8, s8, s0
	s_mulk_i32 s8, 0x2100
	v_add_u32_e32 v109, s8, v150
	ds_read_b128 v[168:171], v109
	ds_read_b128 v[172:175], v109 offset:64
	ds_read_b128 v[176:179], v109 offset:128
	ds_read_b128 v[180:183], v109 offset:192
	ds_read_b128 v[184:187], v109 offset:256
	ds_read_b128 v[188:191], v109 offset:320
	ds_read_b128 v[192:195], v109 offset:448
	ds_read_b128 v[196:199], v109 offset:384
	s_cmp_eq_u32 s2, 1
	s_cselect_b64 s[8:9], -1, 0
	s_cmp_eq_u32 s2, 2
	s_waitcnt lgkmcnt(8)
	s_waitcnt lgkmcnt(7)
	v_mfma_f32_16x16x32_bf16 v[136:139], v[168:171], v[52:55], 0
	s_cselect_b64 s[10:11], -1, 0
	s_cmp_eq_u32 s2, 3
	s_cselect_b64 s[12:13], -1, 0
	v_mfma_f32_16x16x32_bf16 v[64:67], v[168:171], v[56:59], 0
	s_cmp_eq_u32 s3, 1
	s_waitcnt lgkmcnt(6)
	v_mfma_f32_16x16x32_bf16 v[136:139], v[172:175], v[44:47], v[136:139]
	v_mfma_f32_16x16x32_bf16 v[64:67], v[172:175], v[48:51], v[64:67]
	s_waitcnt lgkmcnt(5)
	v_mfma_f32_16x16x32_bf16 v[136:139], v[176:179], v[36:39], v[136:139]
	v_mfma_f32_16x16x32_bf16 v[64:67], v[176:179], v[40:43], v[64:67]
	s_waitcnt lgkmcnt(4)
	v_mfma_f32_16x16x32_bf16 v[68:71], v[180:183], v[24:27], v[136:139]
	v_mfma_f32_16x16x32_bf16 v[64:67], v[180:183], v[28:31], v[64:67]
	s_waitcnt lgkmcnt(3)
	v_mfma_f32_16x16x32_bf16 v[68:71], v[184:187], v[16:19], v[68:71]
	v_mfma_f32_16x16x32_bf16 v[64:67], v[184:187], v[20:23], v[64:67]
	s_waitcnt lgkmcnt(2)
	v_mfma_f32_16x16x32_bf16 v[68:71], v[188:191], v[12:15], v[68:71]
	v_mfma_f32_16x16x32_bf16 v[64:67], v[188:191], v[0:3], v[64:67]
	s_waitcnt lgkmcnt(0)
	v_mfma_f32_16x16x32_bf16 v[68:71], v[196:199], v[8:11], v[68:71]
	v_mfma_f32_16x16x32_bf16 v[64:67], v[196:199], v[4:7], v[64:67]
	v_mfma_f32_16x16x32_bf16 v[68:71], v[192:195], v[32:35], v[68:71]
	v_mfma_f32_16x16x32_bf16 v[64:67], v[192:195], v[60:63], v[64:67]
	s_nop 6
	v_cndmask_b32_e64 v109, v68, v69, s[8:9]
	v_cndmask_b32_e64 v109, v109, v70, s[10:11]
	v_cndmask_b32_e64 v138, v109, v71, s[12:13]
	v_cndmask_b32_e64 v109, v64, v65, s[8:9]
	v_cndmask_b32_e64 v109, v109, v66, s[10:11]
	s_cselect_b64 s[8:9], -1, 0
	s_cmp_eq_u32 s3, 2
	v_cndmask_b32_e64 v139, v109, v67, s[12:13]
	v_cndmask_b32_e64 v109, v68, v69, s[8:9]
	s_cselect_b64 s[10:11], -1, 0
	s_cmp_eq_u32 s3, 3
	v_cndmask_b32_e64 v109, v109, v70, s[10:11]
	s_cselect_b64 s[12:13], -1, 0
	s_cmp_eq_u32 s26, 1
	v_cndmask_b32_e64 v121, v109, v71, s[12:13]
	v_cndmask_b32_e64 v109, v64, v65, s[8:9]
	s_cselect_b64 s[8:9], -1, 0
	s_cmp_eq_u32 s26, 2
	v_cndmask_b32_e64 v109, v109, v66, s[10:11]
	v_cndmask_b32_e64 v136, v68, v69, s[8:9]
	s_cselect_b64 s[10:11], -1, 0
	s_cmp_eq_u32 s26, 3
	v_cndmask_b32_e64 v109, v109, v67, s[12:13]
	v_cndmask_b32_e64 v136, v136, v70, s[10:11]
	s_cselect_b64 s[12:13], -1, 0
	s_cmp_eq_u32 s27, 1
	v_cndmask_b32_e64 v137, v136, v71, s[12:13]
	v_cndmask_b32_e64 v136, v64, v65, s[8:9]
	s_cselect_b64 s[8:9], -1, 0
	s_cmp_eq_u32 s27, 2
	v_cndmask_b32_e64 v136, v136, v66, s[10:11]
	v_cndmask_b32_e64 v68, v68, v69, s[8:9]
	s_cselect_b64 s[10:11], -1, 0
	s_cmp_eq_u32 s27, 3
	v_cndmask_b32_e64 v64, v64, v65, s[8:9]
	v_cndmask_b32_e64 v136, v136, v67, s[12:13]
	v_cndmask_b32_e64 v68, v68, v70, s[10:11]
	s_cselect_b64 s[12:13], -1, 0
	v_cndmask_b32_e64 v64, v64, v66, s[10:11]
	v_cndmask_b32_e64 v70, v68, v71, s[12:13]
	v_cndmask_b32_e64 v71, v64, v67, s[12:13]
	v_mov_b32_e32 v66, v139
	v_mov_b32_e32 v67, v138
	v_pk_mul_f32 v[64:65], v[110:111], v[138:139]
	v_pk_mul_f32 v[66:67], v[110:111], v[66:67]
	v_sub_f32_e32 v64, v64, v65
	v_add_f32_e32 v65, v67, v66
	v_add_f32_e32 v66, v109, v65
	v_add_f32_e32 v64, v121, v64
	v_pk_mul_f32 v[66:67], v[110:111], v[66:67] op_sel_hi:[1,0]
	v_cmp_lt_i32_e64 s[8:9], 0, v151
	v_pk_fma_f32 v[68:69], v[114:115], v[64:65], v[66:67]
	v_pk_fma_f32 v[64:65], v[114:115], v[64:65], v[66:67] op_sel_hi:[1,0,1] neg_lo:[0,0,1] neg_hi:[0,0,1]
	s_mov_b64 s[10:11], 0
	v_mov_b32_e32 v69, v65
	v_pk_add_f32 v[64:65], v[136:137], v[68:69]
	s_nop 0
	v_pk_mul_f32 v[66:67], v[110:111], v[64:65] op_sel:[0,1] op_sel_hi:[1,0]
	v_pk_mul_f32 v[64:65], v[110:111], v[64:65]
	v_sub_f32_e32 v66, v66, v67
	v_add_f32_e32 v64, v64, v65
	v_add_f32_e32 v66, v70, v66
	ds_bpermute_b32 v146, v153, v66
	v_add_f32_e32 v64, v71, v64
	ds_bpermute_b32 v147, v153, v64
	ds_bpermute_b32 v144, v154, v66
	ds_bpermute_b32 v145, v154, v64
	ds_bpermute_b32 v142, v155, v66
	ds_bpermute_b32 v143, v155, v64
	ds_bpermute_b32 v140, v156, v66
	ds_bpermute_b32 v141, v156, v64
	global_load_dwordx4 v[64:67], v[134:135], off
	global_load_dwordx4 v[68:71], v[132:133], off
	s_and_saveexec_b64 s[12:13], s[8:9]
	s_xor_b64 s[12:13], exec, s[12:13]
	s_cbranch_execz .LBB0_285
	v_cmp_eq_u32_e64 s[8:9], 1, v151
	s_mov_b64 s[10:11], -1
	s_and_saveexec_b64 s[24:25], s[8:9]
	s_xor_b64 s[10:11], exec, -1
	s_or_b64 exec, exec, s[24:25]
	s_and_b64 s[10:11], s[10:11], exec

.LBB0_289:
	ds_read_b128 v[168:171], v163
	ds_read_b128 v[64:67], v163 offset:64
	s_cmp_eq_u32 s2, 1
	s_cselect_b64 s[8:9], -1, 0
	s_cmp_eq_u32 s2, 2
	s_cselect_b64 s[10:11], -1, 0
	s_cmp_eq_u32 s2, 3
	s_cselect_b64 s[12:13], -1, 0
	s_cmp_eq_u32 s3, 1
	s_waitcnt lgkmcnt(2)
	s_waitcnt lgkmcnt(1)
	v_mfma_f32_16x16x32_bf16 v[52:55], v[168:171], v[52:55], 0
	v_mfma_f32_16x16x32_bf16 v[56:59], v[168:171], v[56:59], 0
	s_waitcnt lgkmcnt(0)
	v_mfma_f32_16x16x32_bf16 v[44:47], v[64:67], v[44:47], v[52:55]
	s_nop 4
	ds_read_b128 v[52:55], v163 offset:128
	s_waitcnt lgkmcnt(0)
	v_mfma_f32_16x16x32_bf16 v[36:39], v[52:55], v[36:39], v[44:47]
	ds_read_b128 v[44:47], v163 offset:192
	s_waitcnt lgkmcnt(0)
	v_mfma_f32_16x16x32_bf16 v[24:27], v[44:47], v[24:27], v[36:39]
	s_nop 4
	ds_read_b128 v[36:39], v163 offset:256
	s_waitcnt lgkmcnt(0)
	v_mfma_f32_16x16x32_bf16 v[16:19], v[36:39], v[16:19], v[24:27]
	ds_read_b128 v[24:27], v163 offset:320
	v_mfma_f32_16x16x32_bf16 v[48:51], v[64:67], v[48:51], v[56:59]
	v_mfma_f32_16x16x32_bf16 v[40:43], v[52:55], v[40:43], v[48:51]
	s_waitcnt lgkmcnt(0)
	v_mfma_f32_16x16x32_bf16 v[12:15], v[24:27], v[12:15], v[16:19]
	s_nop 2
	ds_read_b128 v[16:19], v163 offset:384
	ds_read_b128 v[168:171], v163 offset:448
	v_mfma_f32_16x16x32_bf16 v[28:31], v[44:47], v[28:31], v[40:43]
	v_mfma_f32_16x16x32_bf16 v[20:23], v[36:39], v[20:23], v[28:31]
	s_waitcnt lgkmcnt(1)
	v_mfma_f32_16x16x32_bf16 v[8:11], v[16:19], v[8:11], v[12:15]
	v_mfma_f32_16x16x32_bf16 v[0:3], v[24:27], v[0:3], v[20:23]
	v_mfma_f32_16x16x32_bf16 v[0:3], v[16:19], v[4:7], v[0:3]
	s_waitcnt lgkmcnt(0)
	v_mfma_f32_16x16x32_bf16 v[8:11], v[168:171], v[32:35], v[8:11]
	v_mfma_f32_16x16x32_bf16 v[12:15], v[168:171], v[60:63], v[0:3]
	s_nop 6
	v_cndmask_b32_e64 v28, v8, v9, s[8:9]
	v_cndmask_b32_e64 v0, v12, v13, s[8:9]
	v_cndmask_b32_e64 v0, v0, v14, s[10:11]
	s_cselect_b64 s[8:9], -1, 0
	s_cmp_eq_u32 s3, 2
	v_cndmask_b32_e64 v20, v28, v10, s[10:11]
	v_cndmask_b32_e64 v4, v0, v15, s[12:13]
	v_cndmask_b32_e64 v0, v8, v9, s[8:9]
	s_cselect_b64 s[10:11], -1, 0
	s_cmp_eq_u32 s3, 3
	v_cndmask_b32_e64 v6, v20, v11, s[12:13]
	v_cndmask_b32_e64 v0, v0, v10, s[10:11]
	s_cselect_b64 s[12:13], -1, 0
	v_cndmask_b32_e64 v3, v0, v11, s[12:13]
	v_cndmask_b32_e64 v0, v12, v13, s[8:9]
	s_cmp_eq_u32 s26, 1
	v_cndmask_b32_e64 v0, v0, v14, s[10:11]
	s_cselect_b64 s[8:9], -1, 0
	s_cmp_eq_u32 s26, 2
	v_cndmask_b32_e64 v2, v0, v15, s[12:13]
	v_cndmask_b32_e64 v0, v8, v9, s[8:9]
	s_cselect_b64 s[10:11], -1, 0
	s_cmp_eq_u32 s26, 3
	v_cndmask_b32_e64 v0, v0, v10, s[10:11]
	s_cselect_b64 s[12:13], -1, 0
	s_cmp_eq_u32 s27, 1
	v_cndmask_b32_e64 v1, v0, v11, s[12:13]
	v_cndmask_b32_e64 v0, v12, v13, s[8:9]
	s_cselect_b64 s[8:9], -1, 0
	s_cmp_eq_u32 s27, 2
	v_cndmask_b32_e64 v0, v0, v14, s[10:11]
	v_cndmask_b32_e64 v5, v8, v9, s[8:9]
	s_cselect_b64 s[10:11], -1, 0
	s_cmp_eq_u32 s27, 3
	v_cndmask_b32_e64 v0, v0, v15, s[12:13]
	v_cndmask_b32_e64 v5, v5, v10, s[10:11]
	s_cselect_b64 s[12:13], -1, 0
	v_cndmask_b32_e64 v7, v12, v13, s[8:9]
	v_cndmask_b32_e64 v5, v5, v11, s[12:13]
	v_cndmask_b32_e64 v7, v7, v14, s[10:11]
	v_cndmask_b32_e64 v7, v7, v15, s[12:13]
	v_pk_mul_f32 v[8:9], v[110:111], v[4:5] op_sel_hi:[1,0]
	v_cmp_lt_i32_e64 s[8:9], 0, v151
	v_pk_fma_f32 v[10:11], v[114:115], v[6:7], v[8:9]
	v_pk_fma_f32 v[8:9], v[114:115], v[6:7], v[8:9] op_sel_hi:[1,0,1] neg_lo:[0,0,1] neg_hi:[0,0,1]
	s_mov_b64 s[10:11], 0
	v_mov_b32_e32 v11, v9
	v_pk_add_f32 v[8:9], v[2:3], v[10:11]
	s_nop 0
	v_pk_mul_f32 v[10:11], v[128:129], v[8:9] op_sel:[0,1] op_sel_hi:[1,0]
	s_nop 0
	v_pk_fma_f32 v[12:13], v[126:127], v[8:9], v[10:11]
	v_pk_fma_f32 v[8:9], v[126:127], v[8:9], v[10:11] neg_lo:[0,0,1] neg_hi:[0,0,1]
	s_nop 0
	v_mov_b32_e32 v13, v9
	v_pk_add_f32 v[8:9], v[0:1], v[12:13]
	s_nop 0
	v_pk_mul_f32 v[10:11], v[110:111], v[8:9] op_sel:[0,1] op_sel_hi:[1,0]
	v_pk_mul_f32 v[8:9], v[110:111], v[8:9]
	v_sub_f32_e32 v10, v10, v11
	v_add_f32_e32 v8, v8, v9
	v_add_f32_e32 v5, v5, v10
	ds_bpermute_b32 v12, v153, v5
	v_add_f32_e32 v7, v7, v8
	ds_bpermute_b32 v13, v153, v7
	ds_bpermute_b32 v10, v154, v5
	ds_bpermute_b32 v11, v154, v7
	ds_bpermute_b32 v8, v155, v5
	ds_bpermute_b32 v9, v155, v7
	s_and_saveexec_b64 s[12:13], s[8:9]
	s_xor_b64 s[12:13], exec, s[12:13]
	s_cbranch_execz .LBB0_293
	v_cmp_eq_u32_e64 s[8:9], 1, v151
	s_mov_b64 s[10:11], -1
	s_and_saveexec_b64 s[24:25], s[8:9]
	s_xor_b64 s[10:11], exec, -1
	s_or_b64 exec, exec, s[24:25]
	s_and_b64 s[10:11], s[10:11], exec

.LBB0_297:
	s_waitcnt vmcnt(0)
	s_barrier
	v_mbcnt_lo_u32_b32 v0, -1, 0
	v_mbcnt_hi_u32_b32 v0, -1, v0
	v_readlane_b32 s1, v240, 44
	v_sub_u32_e32 v0, 0, v0
	s_nop 0
	v_cmp_eq_u32_e32 vcc, s1, v0
	s_and_saveexec_b64 s[4:5], vcc
	s_branch .LBB0_349
	s_add_i32 s1, 0, 0x22100
	v_mov_b32_e32 v0, s1
	s_waitcnt vmcnt(0) expcnt(0) lgkmcnt(0)
	ds_read_b32 v2, v0
	s_add_i32 s1, 0, 0x22104
	v_mov_b32_e32 v0, s1
	ds_read_b32 v0, v0
	s_waitcnt lgkmcnt(1)
	v_cmp_ne_u32_e32 vcc, 0, v2
	s_cbranch_vccnz .LBB0_313
	v_readlane_b32 s6, v240, 47
	v_readlane_b32 s7, v240, 48
	s_load_dword s1, s[6:7], 0x14
	s_load_dwordx2 s[2:3], s[6:7], 0x4
	v_mov_b32_e32 v16, 0
	s_waitcnt lgkmcnt(0)
	s_lshr_b32 s8, s1, 16
	s_and_b32 s1, s1, 0xffff
	s_cmp_lg_u32 s1, 0
	s_cselect_b64 s[6:7], -1, 0
	s_cmp_lg_u64 s[6:7], 0
	s_addc_u32 s1, s2, 0
	s_cmp_lg_u32 s8, 0
	s_cselect_b64 s[6:7], -1, 0
	s_cmp_lg_u64 s[6:7], 0
	s_addc_u32 s2, s3, 0
	s_add_u32 s6, s96, 0x1000
	s_addc_u32 s7, s97, 0
	s_add_u32 s8, s96, 0x1100
	s_addc_u32 s9, s97, 0
	s_add_u32 s10, s96, 0x1200
	s_addc_u32 s11, s97, 0
	s_mul_i32 s1, s1, s33
	s_add_u32 s12, s96, 0x1300
	s_mul_i32 s1, s1, s2
	s_addc_u32 s13, s97, 0
	s_mov_b32 s2, 1
	s_branch .LBB0_301

.LBB0_352:
	s_add_i32 s28, s29, 1
	s_bitcmp1_b32 s29, 0
	s_cselect_b32 s29, 0x4100, 0
	v_add_u32_e32 v202, s29, v157
	ds_read_b128 v[224:227], v202
	ds_read_b128 v[228:231], v202 offset:64
	ds_read_b128 v[232:235], v202 offset:128
	global_load_dwordx4 v[128:131], v[150:151], off
	v_add_co_u32_e32 v152, vcc, 0xffffe000, v150
	s_waitcnt lgkmcnt(3)
	s_waitcnt lgkmcnt(2)
	v_mfma_f32_16x16x32_bf16 v[186:189], v[224:227], v[112:115], 0
	v_addc_co_u32_e32 v153, vcc, -1, v151, vcc
	v_add_u32_e32 v194, s27, v158
	v_mfma_f32_16x16x32_bf16 v[178:181], v[224:227], v[124:127], 0
	ds_read_b128 v[224:227], v202 offset:192
	v_mov_b32_e32 v198, s26
	v_mov_b32_e32 v199, s25
	v_cmp_gt_i32_e32 vcc, s1, v194
	s_waitcnt lgkmcnt(2)
	v_mfma_f32_16x16x32_bf16 v[186:189], v[228:231], v[104:107], v[186:189]
	v_add_u32_e32 v195, s27, v177
	v_add_u32_e32 v196, s27, v176
	v_cndmask_b32_e32 v197, v198, v199, vcc
	v_mfma_f32_16x16x32_bf16 v[178:181], v[228:231], v[120:123], v[178:181]
	ds_read_b128 v[228:231], v202 offset:256
	v_add_u32_e32 v200, 1, v194
	v_add_u32_e32 v201, 0x2001, v195
	s_waitcnt lgkmcnt(2)
	v_mfma_f32_16x16x32_bf16 v[186:189], v[232:235], v[96:99], v[186:189]
	v_add_u32_e32 v203, 0xffffff01, v196
	v_add_u32_e32 v204, 16, v194
	v_add_u32_e32 v205, 17, v194
	v_mfma_f32_16x16x32_bf16 v[178:181], v[232:235], v[116:119], v[178:181]
	ds_read_b128 v[232:235], v202 offset:320
	v_add_u32_e32 v207, 0x2011, v195
	v_add_u32_e32 v208, 0xffffff11, v196
	v_add_u32_e32 v211, 32, v194
	s_waitcnt lgkmcnt(2)
	v_mfma_f32_16x16x32_bf16 v[182:185], v[224:227], v[88:91], v[186:189]
	v_add_u32_e32 v209, 33, v194
	v_add_u32_e32 v210, 0x2021, v195
	v_add_u32_e32 v212, 0xffffff21, v196
	v_mfma_f32_16x16x32_bf16 v[178:181], v[224:227], v[108:111], v[178:181]
	ds_read_b128 v[224:227], v202 offset:384
	v_add_u32_e32 v213, 48, v194
	v_add_u32_e32 v214, 49, v194
	s_waitcnt lgkmcnt(2)
	v_mfma_f32_16x16x32_bf16 v[182:185], v[228:231], v[80:83], v[182:185]
	v_add_u32_e32 v215, 0x2031, v195
	v_add_u32_e32 v216, 0xffffff31, v196
	v_cmp_gt_i32_e32 vcc, s1, v200
	v_mfma_f32_16x16x32_bf16 v[178:181], v[228:231], v[100:103], v[178:181]
	ds_read_b128 v[228:231], v202 offset:448
	global_load_dwordx4 v[186:189], v[152:153], off
	v_add_u32_e32 v152, v194, v197
	v_cndmask_b32_e32 v206, v203, v201, vcc
	s_waitcnt lgkmcnt(2)
	v_mfma_f32_16x16x32_bf16 v[182:185], v[232:235], v[72:75], v[182:185]
	v_cmp_gt_i32_e32 vcc, s1, v204
	s_bitcmp1_b32 s28, 0
	s_cselect_b32 s29, 0x4100, 0
	v_mfma_f32_16x16x32_bf16 v[178:181], v[232:235], v[92:95], v[178:181]
	ds_read_b128 v[232:235], v202 offset:512
	v_cndmask_b32_e32 v200, v198, v199, vcc
	v_cmp_gt_i32_e32 vcc, s1, v205
	s_waitcnt lgkmcnt(2)
	v_mfma_f32_16x16x32_bf16 v[182:185], v[224:227], v[64:67], v[182:185]
	v_cndmask_b32_e32 v208, v208, v207, vcc
	v_cmp_gt_i32_e32 vcc, s1, v211
	v_ashrrev_i32_e32 v207, 31, v206
	v_mfma_f32_16x16x32_bf16 v[178:181], v[224:227], v[84:87], v[178:181]
	ds_read_b128 v[224:227], v202 offset:576
	v_cndmask_b32_e32 v201, v198, v199, vcc
	v_cmp_gt_i32_e32 vcc, s1, v209
	v_ashrrev_i32_e32 v209, 31, v208
	s_waitcnt lgkmcnt(2)
	v_mfma_f32_16x16x32_bf16 v[182:185], v[228:231], v[56:59], v[182:185]
	v_cndmask_b32_e32 v210, v212, v210, vcc
	v_cmp_gt_i32_e32 vcc, s1, v213
	v_lshlrev_b64 v[206:207], 12, v[206:207]
	v_mfma_f32_16x16x32_bf16 v[178:181], v[228:231], v[76:79], v[178:181]
	ds_read_b128 v[228:231], v202 offset:640
	v_cndmask_b32_e32 v198, v198, v199, vcc
	v_cmp_gt_i32_e32 vcc, s1, v214
	s_waitcnt lgkmcnt(2)
	v_mfma_f32_16x16x32_bf16 v[182:185], v[232:235], v[52:55], v[182:185]
	v_cndmask_b32_e32 v212, v216, v215, vcc
	v_add_u32_e32 v214, v204, v200
	v_add_u32_e32 v216, v211, v201
	v_mfma_f32_16x16x32_bf16 v[178:181], v[232:235], v[68:71], v[178:181]
	ds_read_b128 v[232:235], v202 offset:704
	v_add_u32_e32 v218, v213, v198
	v_ashrrev_i32_e32 v211, 31, v210
	v_ashrrev_i32_e32 v215, 31, v214
	s_waitcnt lgkmcnt(2)
	v_mfma_f32_16x16x32_bf16 v[182:185], v[224:227], v[44:47], v[182:185]
	v_lshlrev_b64 v[208:209], 12, v[208:209]
	v_ashrrev_i32_e32 v217, 31, v216
	v_ashrrev_i32_e32 v219, 31, v218
	v_mfma_f32_16x16x32_bf16 v[178:181], v[224:227], v[60:63], v[178:181]
	ds_read_b128 v[224:227], v202 offset:768
	v_ashrrev_i32_e32 v213, 31, v212
	s_add_i32 s29, s29, 0
	s_waitcnt lgkmcnt(2)
	v_mfma_f32_16x16x32_bf16 v[182:185], v[228:231], v[36:39], v[182:185]
	v_ashrrev_i32_e32 v153, 31, v152
	v_lshlrev_b64 v[152:153], 12, v[152:153]
	v_lshl_add_u64 v[152:153], v[148:149], 0, v[152:153]
	v_mfma_f32_16x16x32_bf16 v[178:181], v[228:231], v[48:51], v[178:181]
	ds_read_b128 v[228:231], v202 offset:832
	s_mov_b64 s[30:31], 0x4000
	s_addk_i32 s27, 0x100
	s_waitcnt lgkmcnt(2)
	v_mfma_f32_16x16x32_bf16 v[182:185], v[232:235], v[28:31], v[182:185]
	v_lshl_add_u64 v[150:151], v[150:151], 0, s[30:31]
	s_cmpk_eq_i32 s27, 0x1000
	v_mfma_f32_16x16x32_bf16 v[178:181], v[232:235], v[40:43], v[178:181]
	ds_read_b128 v[232:235], v202 offset:896
	ds_read_b128 v[202:205], v202 offset:960
	s_waitcnt lgkmcnt(3)
	v_mfma_f32_16x16x32_bf16 v[182:185], v[224:227], v[20:23], v[182:185]
	v_mfma_f32_16x16x32_bf16 v[178:181], v[224:227], v[32:35], v[178:181]
	v_lshlrev_b64 v[190:191], 12, v[210:211]
	v_lshlrev_b64 v[210:211], 12, v[218:219]
	v_lshlrev_b64 v[192:193], 12, v[212:213]
	s_waitcnt lgkmcnt(2)
	v_mfma_f32_16x16x32_bf16 v[182:185], v[228:231], v[12:15], v[182:185]
	v_add3_u32 v212, s29, v175, v136
	s_waitcnt vmcnt(1)
	ds_write_b128 v212, v[128:131]
	v_add3_u32 v213, s29, v154, v136
	v_mfma_f32_16x16x32_bf16 v[178:181], v[228:231], v[24:27], v[178:181]
	v_lshl_add_u64 v[198:199], v[148:149], 0, v[206:207]
	v_lshlrev_b64 v[200:201], 12, v[214:215]
	v_lshl_add_u64 v[206:207], v[148:149], 0, v[208:209]
	s_waitcnt lgkmcnt(2)
	v_mfma_f32_16x16x32_bf16 v[182:185], v[232:235], v[4:7], v[182:185]
	v_lshlrev_b64 v[208:209], 12, v[216:217]
	v_lshl_add_u64 v[190:191], v[148:149], 0, v[190:191]
	v_lshl_add_u64 v[192:193], v[148:149], 0, v[192:193]
	v_mfma_f32_16x16x32_bf16 v[178:181], v[232:235], v[16:19], v[178:181]
	v_lshl_add_u64 v[194:195], v[148:149], 0, v[200:201]
	v_lshl_add_u64 v[196:197], v[148:149], 0, v[208:209]
	v_lshl_add_u64 v[200:201], v[148:149], 0, v[210:211]
	s_waitcnt lgkmcnt(1)
	v_mfma_f32_16x16x32_bf16 v[182:185], v[202:205], v[0:3], v[182:185]
	s_waitcnt vmcnt(0)
	ds_write_b128 v213, v[186:189]
	s_mov_b32 s29, s28
	v_mfma_f32_16x16x32_bf16 v[178:181], v[202:205], v[8:11], v[178:181]
	s_nop 3
	v_mul_f32_e32 v202, 0x3d372713, v182
	s_nop 2
	v_mul_f32_e32 v204, 0x3d372713, v178
	v_mul_f32_e32 v208, 0x3d372713, v183
	v_mul_f32_e32 v210, 0x3d372713, v179
	v_mul_f32_e32 v214, 0x3d372713, v184
	v_mul_f32_e32 v216, 0x3d372713, v180
	v_mul_f32_e32 v218, 0x3d372713, v185
	v_mul_f32_e32 v220, 0x3d372713, v181
	v_mul_f32_e32 v202, v182, v202
	v_mul_f32_e32 v203, 0.5, v182
	v_mul_f32_e32 v204, v178, v204
	v_mul_f32_e32 v208, v183, v208
	v_mul_f32_e32 v210, v179, v210
	v_mul_f32_e32 v214, v184, v214
	v_mul_f32_e32 v216, v180, v216
	v_mul_f32_e32 v218, v185, v218
	v_mul_f32_e32 v220, v181, v220
	v_fma_f32 v182, v182, v202, v182
	v_mul_f32_e32 v205, 0.5, v178
	v_mul_f32_e32 v209, 0.5, v183
	v_mul_f32_e32 v211, 0.5, v179
	v_mul_f32_e32 v215, 0.5, v184
	v_mul_f32_e32 v217, 0.5, v180
	v_mul_f32_e32 v219, 0.5, v185
	v_mul_f32_e32 v221, 0.5, v181
	v_fma_f32 v178, v178, v204, v178
	v_fma_f32 v183, v183, v208, v183
	v_fma_f32 v179, v179, v210, v179
	v_fma_f32 v184, v184, v214, v184
	v_fma_f32 v180, v180, v216, v180
	v_fma_f32 v185, v185, v218, v185
	v_fma_f32 v181, v181, v220, v181
	v_mul_f32_e32 v182, 0x3f4c422a, v182
	v_mul_f32_e32 v178, 0x3f4c422a, v178
	v_mul_f32_e32 v183, 0x3f4c422a, v183
	v_mul_f32_e32 v179, 0x3f4c422a, v179
	v_mul_f32_e32 v184, 0x3f4c422a, v184
	v_mul_f32_e32 v180, 0x3f4c422a, v180
	v_mul_f32_e32 v185, 0x3f4c422a, v185
	v_mul_f32_e32 v181, 0x3f4c422a, v181
	v_add_f32_e32 v128, v182, v182
	v_add_f32_e32 v129, v178, v178
	v_add_f32_e32 v130, v183, v183
	v_add_f32_e32 v131, v179, v179
	v_add_f32_e32 v178, v184, v184
	v_add_f32_e32 v179, v180, v180
	v_add_f32_e32 v180, v185, v185
	v_add_f32_e32 v181, v181, v181
	v_mul_f32_e32 v128, 0x3fb8aa3b, v128
	v_mul_f32_e32 v129, 0x3fb8aa3b, v129
	v_mul_f32_e32 v130, 0x3fb8aa3b, v130
	v_mul_f32_e32 v131, 0x3fb8aa3b, v131
	v_mul_f32_e32 v178, 0x3fb8aa3b, v178
	v_mul_f32_e32 v179, 0x3fb8aa3b, v179
	v_mul_f32_e32 v180, 0x3fb8aa3b, v180
	v_mul_f32_e32 v181, 0x3fb8aa3b, v181
	v_exp_f32_e32 v128, v128
	v_exp_f32_e32 v129, v129
	v_exp_f32_e32 v130, v130
	v_exp_f32_e32 v131, v131
	v_exp_f32_e32 v178, v178
	v_exp_f32_e32 v179, v179
	v_exp_f32_e32 v180, v180
	v_exp_f32_e32 v181, v181
	v_add_f32_e32 v128, 1.0, v128
	v_add_f32_e32 v129, 1.0, v129
	v_add_f32_e32 v130, 1.0, v130
	v_add_f32_e32 v131, 1.0, v131
	v_add_f32_e32 v178, 1.0, v178
	v_add_f32_e32 v179, 1.0, v179
	v_add_f32_e32 v180, 1.0, v180
	v_add_f32_e32 v181, 1.0, v181
	v_rcp_f32_e32 v128, v128
	v_rcp_f32_e32 v129, v129
	v_rcp_f32_e32 v130, v130
	v_rcp_f32_e32 v131, v131
	v_rcp_f32_e32 v178, v178
	v_rcp_f32_e32 v179, v179
	v_rcp_f32_e32 v180, v180
	v_rcp_f32_e32 v181, v181
	v_fma_f32 v128, v128, -2.0, 1.0
	v_fma_f32 v129, v129, -2.0, 1.0
	v_fma_f32 v130, v130, -2.0, 1.0
	v_fma_f32 v131, v131, -2.0, 1.0
	v_fma_f32 v178, v178, -2.0, 1.0
	v_fma_f32 v179, v179, -2.0, 1.0
	v_fma_f32 v180, v180, -2.0, 1.0
	v_fma_f32 v181, v181, -2.0, 1.0
	v_add_f32_e32 v128, 1.0, v128
	v_add_f32_e32 v129, 1.0, v129
	v_add_f32_e32 v130, 1.0, v130
	v_add_f32_e32 v131, 1.0, v131
	v_add_f32_e32 v178, 1.0, v178
	v_add_f32_e32 v179, 1.0, v179
	v_add_f32_e32 v180, 1.0, v180
	v_add_f32_e32 v181, 1.0, v181
	v_mul_f32_e32 v128, v203, v128
	v_mul_f32_e32 v129, v205, v129
	v_mul_f32_e32 v130, v209, v130
	v_mul_f32_e32 v131, v211, v131
	v_mul_f32_e32 v178, v215, v178
	v_mul_f32_e32 v179, v217, v179
	v_mul_f32_e32 v180, v219, v180
	v_mul_f32_e32 v181, v221, v181
	v_cvt_pk_bf16_f32 v128, v128, s0
	v_cvt_pk_bf16_f32 v129, v129, s0
	v_cvt_pk_bf16_f32 v130, v130, s0
	v_cvt_pk_bf16_f32 v131, v131, s0
	v_cvt_pk_bf16_f32 v178, v178, s0
	v_cvt_pk_bf16_f32 v179, v179, s0
	v_cvt_pk_bf16_f32 v180, v180, s0
	v_cvt_pk_bf16_f32 v181, v181, s0
	global_store_short v[152:153], v128, off
	global_store_short v[198:199], v129, off
	global_store_short v[194:195], v130, off
	global_store_short v[206:207], v131, off
	global_store_short v[196:197], v178, off
	global_store_short v[190:191], v179, off
	global_store_short v[200:201], v180, off
	global_store_short v[192:193], v181, off
	s_waitcnt lgkmcnt(0)
	s_barrier
	s_cbranch_scc0 .LBB0_352
	ds_read_b128 v[224:227], v157
	ds_read_b128 v[128:131], v157 offset:64
	s_add_i32 s24, s24, s33
	s_add_i32 s2, s2, s3
	s_cmpk_gt_i32 s24, 0xff
	s_waitcnt lgkmcnt(2)
	s_waitcnt lgkmcnt(1)
	v_mfma_f32_16x16x32_bf16 v[112:115], v[224:227], v[112:115], 0
	v_mfma_f32_16x16x32_bf16 v[124:127], v[224:227], v[124:127], 0
	s_waitcnt lgkmcnt(0)
	v_mfma_f32_16x16x32_bf16 v[104:107], v[128:131], v[104:107], v[112:115]
	s_nop 0
	v_mfma_f32_16x16x32_bf16 v[112:115], v[128:131], v[120:123], v[124:127]
	ds_read_b128 v[120:123], v157 offset:128
	s_waitcnt lgkmcnt(0)
	v_mfma_f32_16x16x32_bf16 v[96:99], v[120:123], v[96:99], v[104:107]
	v_mfma_f32_16x16x32_bf16 v[104:107], v[120:123], v[116:119], v[112:115]
	s_nop 3
	ds_read_b128 v[112:115], v157 offset:192
	s_waitcnt lgkmcnt(0)
	v_mfma_f32_16x16x32_bf16 v[88:91], v[112:115], v[88:91], v[96:99]
	v_mfma_f32_16x16x32_bf16 v[96:99], v[112:115], v[108:111], v[104:107]
	ds_read_b128 v[104:107], v157 offset:256
	s_waitcnt lgkmcnt(0)
	v_mfma_f32_16x16x32_bf16 v[80:83], v[104:107], v[80:83], v[88:91]
	s_nop 2
	v_mfma_f32_16x16x32_bf16 v[88:91], v[104:107], v[100:103], v[96:99]
	s_nop 0
	ds_read_b128 v[96:99], v157 offset:320
	s_waitcnt lgkmcnt(0)
	v_mfma_f32_16x16x32_bf16 v[72:75], v[96:99], v[72:75], v[80:83]
	v_mfma_f32_16x16x32_bf16 v[80:83], v[96:99], v[92:95], v[88:91]
	s_nop 2
	ds_read_b128 v[88:91], v157 offset:384
	s_waitcnt lgkmcnt(0)
	v_mfma_f32_16x16x32_bf16 v[64:67], v[88:91], v[64:67], v[72:75]
	v_mfma_f32_16x16x32_bf16 v[72:75], v[88:91], v[84:87], v[80:83]
	s_nop 0
	ds_read_b128 v[80:83], v157 offset:448
	s_waitcnt lgkmcnt(0)
	v_mfma_f32_16x16x32_bf16 v[56:59], v[80:83], v[56:59], v[64:67]
	s_nop 1
	v_mfma_f32_16x16x32_bf16 v[64:67], v[80:83], v[76:79], v[72:75]
	s_nop 0
	ds_read_b128 v[72:75], v157 offset:512
	s_waitcnt lgkmcnt(0)
	v_mfma_f32_16x16x32_bf16 v[52:55], v[72:75], v[52:55], v[56:59]
	v_mfma_f32_16x16x32_bf16 v[56:59], v[72:75], v[68:71], v[64:67]
	s_nop 2
	ds_read_b128 v[64:67], v157 offset:576
	s_waitcnt lgkmcnt(0)
	v_mfma_f32_16x16x32_bf16 v[44:47], v[64:67], v[44:47], v[52:55]
	v_mfma_f32_16x16x32_bf16 v[52:55], v[64:67], v[60:63], v[56:59]
	s_nop 0
	ds_read_b128 v[56:59], v157 offset:640
	s_waitcnt lgkmcnt(0)
	v_mfma_f32_16x16x32_bf16 v[36:39], v[56:59], v[36:39], v[44:47]
	s_nop 1
	v_mfma_f32_16x16x32_bf16 v[44:47], v[56:59], v[48:51], v[52:55]
	ds_read_b128 v[48:51], v157 offset:704
	s_waitcnt lgkmcnt(0)
	v_mfma_f32_16x16x32_bf16 v[28:31], v[48:51], v[28:31], v[36:39]
	v_mfma_f32_16x16x32_bf16 v[36:39], v[48:51], v[40:43], v[44:47]
	ds_read_b128 v[40:43], v157 offset:768
	s_waitcnt lgkmcnt(0)
	v_mfma_f32_16x16x32_bf16 v[20:23], v[40:43], v[20:23], v[28:31]
	v_mfma_f32_16x16x32_bf16 v[28:31], v[40:43], v[32:35], v[36:39]
	ds_read_b128 v[32:35], v157 offset:832
	s_waitcnt lgkmcnt(0)
	v_mfma_f32_16x16x32_bf16 v[12:15], v[32:35], v[12:15], v[20:23]
	v_mfma_f32_16x16x32_bf16 v[20:23], v[32:35], v[24:27], v[28:31]
	ds_read_b128 v[24:27], v157 offset:896
	s_waitcnt lgkmcnt(0)
	v_mfma_f32_16x16x32_bf16 v[4:7], v[24:27], v[4:7], v[12:15]
	v_mfma_f32_16x16x32_bf16 v[12:15], v[24:27], v[16:19], v[20:23]
	ds_read_b128 v[16:19], v157 offset:960
	s_waitcnt lgkmcnt(0)
	v_mfma_f32_16x16x32_bf16 v[4:7], v[16:19], v[0:3], v[4:7]
	v_mfma_f32_16x16x32_bf16 v[0:3], v[16:19], v[8:11], v[12:15]
	v_add_u32_e32 v8, s25, v159
	v_add_u32_e32 v9, s22, v160
	v_cndmask_b32_e64 v8, v9, v8, s[4:5]
	s_nop 3
	v_mul_f32_e32 v9, 0x3d372713, v4
	v_mul_f32_e32 v9, v4, v9
	v_fma_f32 v9, v4, v9, v4
	v_mul_f32_e32 v9, 0x3f4c422a, v9
	v_add_f32_e32 v9, v9, v9
	v_mul_f32_e32 v9, 0x3fb8aa3b, v9
	v_exp_f32_e32 v9, v9
	v_mul_f32_e32 v4, 0.5, v4
	v_add_f32_e32 v9, 1.0, v9
	v_rcp_f32_e32 v9, v9
	s_nop 0
	v_fma_f32 v9, v9, -2.0, 1.0
	v_add_f32_e32 v9, 1.0, v9
	v_mul_f32_e32 v4, v4, v9
	v_ashrrev_i32_e32 v9, 31, v8
	v_lshlrev_b64 v[8:9], 12, v[8:9]
	v_cvt_pk_bf16_f32 v4, v4, s0
	v_lshl_add_u64 v[8:9], v[148:149], 0, v[8:9]
	global_store_short v[8:9], v4, off
	v_add_u32_e32 v4, s25, v161
	v_add_u32_e32 v8, s22, v162
	v_cndmask_b32_e64 v8, v8, v4, s[6:7]
	v_mul_f32_e32 v4, 0x3d372713, v0
	v_mul_f32_e32 v4, v0, v4
	v_fma_f32 v4, v0, v4, v0
	v_mul_f32_e32 v4, 0x3f4c422a, v4
	v_add_f32_e32 v4, v4, v4
	v_mul_f32_e32 v4, 0x3fb8aa3b, v4
	v_exp_f32_e32 v4, v4
	v_mul_f32_e32 v0, 0.5, v0
	v_ashrrev_i32_e32 v9, 31, v8
	v_lshlrev_b64 v[8:9], 12, v[8:9]
	v_add_f32_e32 v4, 1.0, v4
	v_rcp_f32_e32 v4, v4
	v_lshl_add_u64 v[8:9], v[148:149], 0, v[8:9]
	v_fma_f32 v4, v4, -2.0, 1.0
	v_add_f32_e32 v4, 1.0, v4
	v_mul_f32_e32 v0, v0, v4
	v_cvt_pk_bf16_f32 v0, v0, s0
	global_store_short v[8:9], v0, off
	v_add_u32_e32 v0, s25, v163
	v_add_u32_e32 v4, s22, v164
	v_cndmask_b32_e64 v4, v4, v0, s[8:9]
	v_mul_f32_e32 v0, 0x3d372713, v5
	v_mul_f32_e32 v0, v5, v0
	v_fma_f32 v0, v5, v0, v5
	v_mul_f32_e32 v0, 0x3f4c422a, v0
	v_add_f32_e32 v0, v0, v0
	v_mul_f32_e32 v0, 0x3fb8aa3b, v0
	v_exp_f32_e32 v0, v0
	v_mul_f32_e32 v5, 0.5, v5
	v_add_f32_e32 v0, 1.0, v0
	v_rcp_f32_e32 v0, v0
	s_nop 0
	v_fma_f32 v0, v0, -2.0, 1.0
	v_add_f32_e32 v0, 1.0, v0
	v_mul_f32_e32 v0, v5, v0
	v_ashrrev_i32_e32 v5, 31, v4
	v_lshlrev_b64 v[4:5], 12, v[4:5]
	v_cvt_pk_bf16_f32 v0, v0, s0
	v_lshl_add_u64 v[4:5], v[148:149], 0, v[4:5]
	global_store_short v[4:5], v0, off
	v_add_u32_e32 v0, s25, v165
	v_add_u32_e32 v4, s22, v166
	v_cndmask_b32_e64 v0, v4, v0, s[10:11]
	v_mul_f32_e32 v4, 0x3d372713, v1
	v_mul_f32_e32 v4, v1, v4
	v_fma_f32 v4, v1, v4, v1
	v_mul_f32_e32 v4, 0x3f4c422a, v4
	v_add_f32_e32 v4, v4, v4
	v_mul_f32_e32 v4, 0x3fb8aa3b, v4
	v_exp_f32_e32 v4, v4
	v_mul_f32_e32 v1, 0.5, v1
	v_add_f32_e32 v4, 1.0, v4
	v_rcp_f32_e32 v4, v4
	s_nop 0
	v_fma_f32 v4, v4, -2.0, 1.0
	v_add_f32_e32 v4, 1.0, v4
	v_mul_f32_e32 v1, v1, v4
	v_cvt_pk_bf16_f32 v4, v1, s0
	v_ashrrev_i32_e32 v1, 31, v0
	v_lshlrev_b64 v[0:1], 12, v[0:1]
	v_lshl_add_u64 v[0:1], v[148:149], 0, v[0:1]
	global_store_short v[0:1], v4, off
	v_add_u32_e32 v0, s25, v167
	v_add_u32_e32 v1, s22, v168
	v_cndmask_b32_e64 v0, v1, v0, s[12:13]
	v_mul_f32_e32 v1, 0x3d372713, v6
	v_mul_f32_e32 v1, v6, v1
	v_fma_f32 v1, v6, v1, v6
	v_mul_f32_e32 v1, 0x3f4c422a, v1
	v_add_f32_e32 v1, v1, v1
	v_mul_f32_e32 v1, 0x3fb8aa3b, v1
	v_exp_f32_e32 v1, v1
	v_mul_f32_e32 v4, 0.5, v6
	v_add_f32_e32 v1, 1.0, v1
	v_rcp_f32_e32 v1, v1
	s_nop 0
	v_fma_f32 v1, v1, -2.0, 1.0
	v_add_f32_e32 v1, 1.0, v1
	v_mul_f32_e32 v1, v4, v1
	v_cvt_pk_bf16_f32 v4, v1, s0
	v_ashrrev_i32_e32 v1, 31, v0
	v_lshlrev_b64 v[0:1], 12, v[0:1]
	v_lshl_add_u64 v[0:1], v[148:149], 0, v[0:1]
	global_store_short v[0:1], v4, off
	v_add_u32_e32 v0, s25, v169
	v_add_u32_e32 v1, s22, v170
	v_cndmask_b32_e64 v0, v1, v0, s[14:15]
	v_mul_f32_e32 v1, 0x3d372713, v2
	v_mul_f32_e32 v1, v2, v1
	v_fma_f32 v1, v2, v1, v2
	v_mul_f32_e32 v1, 0x3f4c422a, v1
	v_add_f32_e32 v1, v1, v1
	v_mul_f32_e32 v1, 0x3fb8aa3b, v1
	v_exp_f32_e32 v1, v1
	v_mul_f32_e32 v2, 0.5, v2
	v_add_f32_e32 v1, 1.0, v1
	v_rcp_f32_e32 v1, v1
	s_nop 0
	v_fma_f32 v1, v1, -2.0, 1.0
	v_add_f32_e32 v1, 1.0, v1
	v_mul_f32_e32 v1, v2, v1
	v_cvt_pk_bf16_f32 v2, v1, s0
	v_ashrrev_i32_e32 v1, 31, v0
	v_lshlrev_b64 v[0:1], 12, v[0:1]
	v_lshl_add_u64 v[0:1], v[148:149], 0, v[0:1]
	global_store_short v[0:1], v2, off
	v_add_u32_e32 v0, s25, v171
	v_add_u32_e32 v1, s22, v172
	v_cndmask_b32_e64 v0, v1, v0, s[16:17]
	v_mul_f32_e32 v1, 0x3d372713, v7
	v_mul_f32_e32 v1, v7, v1
	v_fma_f32 v1, v7, v1, v7
	v_mul_f32_e32 v1, 0x3f4c422a, v1
	v_add_f32_e32 v1, v1, v1
	v_mul_f32_e32 v1, 0x3fb8aa3b, v1
	v_exp_f32_e32 v1, v1
	v_mul_f32_e32 v2, 0.5, v7
	v_add_f32_e32 v1, 1.0, v1
	v_rcp_f32_e32 v1, v1
	s_nop 0
	v_fma_f32 v1, v1, -2.0, 1.0
	v_add_f32_e32 v1, 1.0, v1
	v_mul_f32_e32 v1, v2, v1
	v_cvt_pk_bf16_f32 v2, v1, s0
	v_ashrrev_i32_e32 v1, 31, v0
	v_lshlrev_b64 v[0:1], 12, v[0:1]
	v_lshl_add_u64 v[0:1], v[148:149], 0, v[0:1]
	global_store_short v[0:1], v2, off
	v_add_u32_e32 v0, s25, v173
	v_add_u32_e32 v1, s22, v174
	v_cndmask_b32_e64 v0, v1, v0, s[18:19]
	v_mul_f32_e32 v1, 0x3d372713, v3
	v_mul_f32_e32 v1, v3, v1
	v_fma_f32 v1, v3, v1, v3
	v_mul_f32_e32 v1, 0x3f4c422a, v1
	v_add_f32_e32 v1, v1, v1
	v_mul_f32_e32 v1, 0x3fb8aa3b, v1
	v_exp_f32_e32 v1, v1
	v_mul_f32_e32 v2, 0.5, v3
	v_add_f32_e32 v1, 1.0, v1
	v_rcp_f32_e32 v1, v1
	s_nop 0
	v_fma_f32 v1, v1, -2.0, 1.0
	v_add_f32_e32 v1, 1.0, v1
	v_mul_f32_e32 v1, v2, v1
	v_cvt_pk_bf16_f32 v2, v1, s0
	v_ashrrev_i32_e32 v1, 31, v0
	v_lshlrev_b64 v[0:1], 12, v[0:1]
	v_lshl_add_u64 v[0:1], v[148:149], 0, v[0:1]
	global_store_short v[0:1], v2, off
	s_waitcnt lgkmcnt(0)
	s_barrier
	s_cbranch_scc0 .LBB0_351

.LBB0_413:
	ds_read_b128 v[128:131], v171
	ds_read_b128 v[132:135], v171 offset:1024
	ds_read_b128 v[136:139], v171 offset:2048
	ds_read_b128 v[152:155], v171 offset:3072
	s_add_u32 s24, s22, 0x100
	s_addc_u32 s25, s23, 0
	s_cmp_eq_u32 s65, 28
	s_cselect_b32 s29, s13, s25
	s_cselect_b32 s28, s61, s24
	s_cselect_b32 s27, s11, s64
	s_cselect_b32 s26, s62, s63
	v_lshl_add_u64 v[194:195], s[22:23], 0, v[144:145]
	s_add_i32 m0, s31, 0xc000
	ds_read_b128 v[156:159], v172
	ds_read_b128 v[160:163], v172 offset:1024
	ds_read_b128 v[164:167], v172 offset:2048
	ds_read_b128 v[174:177], v172 offset:3072
	ds_read_b128 v[178:181], v172 offset:4096
	ds_read_b128 v[182:185], v172 offset:5120
	ds_read_b128 v[186:189], v172 offset:6144
	ds_read_b128 v[190:193], v172 offset:7168
	global_load_lds_dwordx4 v[194:195], off
	v_lshl_add_u64 v[194:195], s[22:23], 0, v[146:147]
	s_add_i32 m0, s31, 0xe000
	s_nop 0
	global_load_lds_dwordx4 v[194:195], off
	s_waitcnt lgkmcnt(8)
	s_barrier
	s_waitcnt lgkmcnt(0)
	s_setprio 1
	s_waitcnt lgkmcnt(0)
	v_mfma_f32_16x16x32_bf16 v[124:127], v[128:131], v[156:159], v[124:127]
	v_mfma_f32_16x16x32_bf16 v[120:123], v[136:139], v[156:159], v[120:123]
	v_mfma_f32_16x16x32_bf16 v[116:119], v[128:131], v[164:167], v[116:119]
	v_mfma_f32_16x16x32_bf16 v[112:115], v[136:139], v[164:167], v[112:115]
	v_mfma_f32_16x16x32_bf16 v[108:111], v[128:131], v[178:181], v[108:111]
	v_mfma_f32_16x16x32_bf16 v[104:107], v[136:139], v[178:181], v[104:107]
	v_mfma_f32_16x16x32_bf16 v[100:103], v[128:131], v[186:189], v[100:103]
	v_mfma_f32_16x16x32_bf16 v[96:99], v[136:139], v[186:189], v[96:99]
	v_mfma_f32_16x16x32_bf16 v[124:127], v[132:135], v[160:163], v[124:127]
	v_mfma_f32_16x16x32_bf16 v[120:123], v[152:155], v[160:163], v[120:123]
	v_mfma_f32_16x16x32_bf16 v[116:119], v[132:135], v[174:177], v[116:119]
	v_mfma_f32_16x16x32_bf16 v[112:115], v[152:155], v[174:177], v[112:115]
	v_mfma_f32_16x16x32_bf16 v[108:111], v[132:135], v[182:185], v[108:111]
	v_mfma_f32_16x16x32_bf16 v[104:107], v[152:155], v[182:185], v[104:107]
	v_mfma_f32_16x16x32_bf16 v[100:103], v[132:135], v[190:193], v[100:103]
	v_mfma_f32_16x16x32_bf16 v[96:99], v[152:155], v[190:193], v[96:99]
	s_setprio 0
	s_barrier
	s_add_i32 s22, s47, s2
	v_lshl_add_u64 v[210:211], s[26:27], 0, v[142:143]
	s_mov_b32 m0, s22
	ds_read_b128 v[194:197], v173
	ds_read_b128 v[198:201], v173 offset:1024
	ds_read_b128 v[202:205], v173 offset:2048
	ds_read_b128 v[206:209], v173 offset:3072
	global_load_lds_dwordx4 v[210:211], off
	v_lshl_add_u64 v[212:213], s[26:27], 0, v[140:141]
	s_add_i32 m0, s22, 0x2000
	s_nop 0
	global_load_lds_dwordx4 v[212:213], off
	s_barrier
	s_waitcnt lgkmcnt(0)
	s_setprio 1
	s_waitcnt lgkmcnt(0)
	v_mfma_f32_16x16x32_bf16 v[64:67], v[194:197], v[156:159], v[64:67]
	v_mfma_f32_16x16x32_bf16 v[68:71], v[202:205], v[156:159], v[68:71]
	v_mfma_f32_16x16x32_bf16 v[48:51], v[194:197], v[164:167], v[48:51]
	v_mfma_f32_16x16x32_bf16 v[52:55], v[202:205], v[164:167], v[52:55]
	v_mfma_f32_16x16x32_bf16 v[40:43], v[194:197], v[178:181], v[40:43]
	v_mfma_f32_16x16x32_bf16 v[44:47], v[202:205], v[178:181], v[44:47]
	v_mfma_f32_16x16x32_bf16 v[32:35], v[194:197], v[186:189], v[32:35]
	v_mfma_f32_16x16x32_bf16 v[36:39], v[202:205], v[186:189], v[36:39]
	v_mfma_f32_16x16x32_bf16 v[64:67], v[198:201], v[160:163], v[64:67]
	v_mfma_f32_16x16x32_bf16 v[68:71], v[206:209], v[160:163], v[68:71]
	v_mfma_f32_16x16x32_bf16 v[48:51], v[198:201], v[174:177], v[48:51]
	v_mfma_f32_16x16x32_bf16 v[52:55], v[206:209], v[174:177], v[52:55]
	v_mfma_f32_16x16x32_bf16 v[40:43], v[198:201], v[182:185], v[40:43]
	v_mfma_f32_16x16x32_bf16 v[44:47], v[206:209], v[182:185], v[44:47]
	v_mfma_f32_16x16x32_bf16 v[32:35], v[198:201], v[190:193], v[32:35]
	v_mfma_f32_16x16x32_bf16 v[36:39], v[206:209], v[190:193], v[36:39]
	s_setprio 0
	s_mov_b32 m0, s31
	v_lshl_add_u64 v[214:215], s[28:29], 0, v[142:143]
	s_barrier
	ds_read_b128 v[156:159], v172 offset:16384
	ds_read_b128 v[160:163], v172 offset:17408
	ds_read_b128 v[164:167], v172 offset:18432
	ds_read_b128 v[174:177], v172 offset:19456
	ds_read_b128 v[178:181], v172 offset:20480
	ds_read_b128 v[182:185], v172 offset:21504
	ds_read_b128 v[186:189], v172 offset:22528
	ds_read_b128 v[190:193], v172 offset:23552
	global_load_lds_dwordx4 v[214:215], off
	v_lshl_add_u64 v[216:217], s[28:29], 0, v[140:141]
	s_mov_b32 m0, s34
	s_nop 0
	global_load_lds_dwordx4 v[216:217], off
	s_barrier
	s_waitcnt lgkmcnt(0)
	s_setprio 1
	s_waitcnt lgkmcnt(0)
	v_mfma_f32_16x16x32_bf16 v[92:95], v[128:131], v[156:159], v[92:95]
	v_mfma_f32_16x16x32_bf16 v[88:91], v[136:139], v[156:159], v[88:91]
	v_mfma_f32_16x16x32_bf16 v[84:87], v[128:131], v[164:167], v[84:87]
	v_mfma_f32_16x16x32_bf16 v[80:83], v[136:139], v[164:167], v[80:83]
	v_mfma_f32_16x16x32_bf16 v[76:79], v[128:131], v[178:181], v[76:79]
	v_mfma_f32_16x16x32_bf16 v[72:75], v[136:139], v[178:181], v[72:75]
	v_mfma_f32_16x16x32_bf16 v[60:63], v[128:131], v[186:189], v[60:63]
	v_mfma_f32_16x16x32_bf16 v[56:59], v[136:139], v[186:189], v[56:59]
	v_mfma_f32_16x16x32_bf16 v[92:95], v[132:135], v[160:163], v[92:95]
	v_mfma_f32_16x16x32_bf16 v[88:91], v[152:155], v[160:163], v[88:91]
	v_mfma_f32_16x16x32_bf16 v[84:87], v[132:135], v[174:177], v[84:87]
	v_mfma_f32_16x16x32_bf16 v[80:83], v[152:155], v[174:177], v[80:83]
	v_mfma_f32_16x16x32_bf16 v[76:79], v[132:135], v[182:185], v[76:79]
	v_mfma_f32_16x16x32_bf16 v[72:75], v[152:155], v[182:185], v[72:75]
	v_mfma_f32_16x16x32_bf16 v[60:63], v[132:135], v[190:193], v[60:63]
	v_mfma_f32_16x16x32_bf16 v[56:59], v[152:155], v[190:193], v[56:59]
	s_setprio 0
	s_barrier
	s_add_u32 s22, s26, 0x80000
	s_addc_u32 s23, s27, 0
	s_add_i32 s66, s60, s2
	v_lshl_add_u64 v[128:129], s[22:23], 0, v[142:143]
	s_mov_b32 m0, s66
	s_nop 0
	global_load_lds_dwordx4 v[128:129], off
	v_lshl_add_u64 v[128:129], s[22:23], 0, v[140:141]
	s_add_i32 m0, s66, 0x2000
	s_nop 0
	global_load_lds_dwordx4 v[128:129], off
	s_waitcnt vmcnt(6)
	s_barrier
	s_setprio 1
	v_mfma_f32_16x16x32_bf16 v[24:27], v[194:197], v[156:159], v[24:27]
	v_mfma_f32_16x16x32_bf16 v[28:31], v[202:205], v[156:159], v[28:31]
	v_mfma_f32_16x16x32_bf16 v[16:19], v[194:197], v[164:167], v[16:19]
	v_mfma_f32_16x16x32_bf16 v[20:23], v[202:205], v[164:167], v[20:23]
	v_mfma_f32_16x16x32_bf16 v[8:11], v[194:197], v[178:181], v[8:11]
	v_mfma_f32_16x16x32_bf16 v[12:15], v[202:205], v[178:181], v[12:15]
	v_mfma_f32_16x16x32_bf16 v[4:7], v[194:197], v[186:189], v[4:7]
	v_mfma_f32_16x16x32_bf16 v[0:3], v[202:205], v[186:189], v[0:3]
	v_mfma_f32_16x16x32_bf16 v[24:27], v[198:201], v[160:163], v[24:27]
	v_mfma_f32_16x16x32_bf16 v[28:31], v[206:209], v[160:163], v[28:31]
	v_mfma_f32_16x16x32_bf16 v[16:19], v[198:201], v[174:177], v[16:19]
	v_mfma_f32_16x16x32_bf16 v[20:23], v[206:209], v[174:177], v[20:23]
	v_mfma_f32_16x16x32_bf16 v[8:11], v[198:201], v[182:185], v[8:11]
	v_mfma_f32_16x16x32_bf16 v[12:15], v[206:209], v[182:185], v[12:15]
	v_mfma_f32_16x16x32_bf16 v[4:7], v[198:201], v[190:193], v[4:7]
	v_mfma_f32_16x16x32_bf16 v[0:3], v[206:209], v[190:193], v[0:3]
	s_setprio 0
	s_add_i32 s66, 0, 0x18000
	v_add_u32_e32 v152, s66, v169
	s_barrier
	ds_read_b128 v[128:131], v152
	ds_read_b128 v[132:135], v152 offset:1024
	ds_read_b128 v[136:139], v152 offset:2048
	ds_read_b128 v[152:155], v152 offset:3072
	s_add_u32 s22, s28, 0x80000
	s_addc_u32 s23, s29, 0
	s_mov_b32 m0, s35
	v_lshl_add_u64 v[194:195], s[22:23], 0, v[142:143]
	ds_read_b128 v[156:159], v172 offset:32768
	ds_read_b128 v[160:163], v172 offset:33792
	ds_read_b128 v[164:167], v172 offset:34816
	ds_read_b128 v[174:177], v172 offset:35840
	ds_read_b128 v[178:181], v172 offset:36864
	ds_read_b128 v[182:185], v172 offset:37888
	ds_read_b128 v[186:189], v172 offset:38912
	ds_read_b128 v[190:193], v172 offset:39936
	global_load_lds_dwordx4 v[194:195], off
	v_lshl_add_u64 v[194:195], s[22:23], 0, v[140:141]
	s_mov_b32 m0, s36
	s_nop 0
	global_load_lds_dwordx4 v[194:195], off
	s_waitcnt lgkmcnt(8)
	s_barrier
	s_waitcnt lgkmcnt(0)
	s_setprio 1
	s_waitcnt lgkmcnt(0)
	v_mfma_f32_16x16x32_bf16 v[124:127], v[128:131], v[156:159], v[124:127]
	v_mfma_f32_16x16x32_bf16 v[120:123], v[136:139], v[156:159], v[120:123]
	v_mfma_f32_16x16x32_bf16 v[116:119], v[128:131], v[164:167], v[116:119]
	v_mfma_f32_16x16x32_bf16 v[112:115], v[136:139], v[164:167], v[112:115]
	v_mfma_f32_16x16x32_bf16 v[108:111], v[128:131], v[178:181], v[108:111]
	v_mfma_f32_16x16x32_bf16 v[104:107], v[136:139], v[178:181], v[104:107]
	v_mfma_f32_16x16x32_bf16 v[100:103], v[128:131], v[186:189], v[100:103]
	v_mfma_f32_16x16x32_bf16 v[96:99], v[136:139], v[186:189], v[96:99]
	v_mfma_f32_16x16x32_bf16 v[124:127], v[132:135], v[160:163], v[124:127]
	v_mfma_f32_16x16x32_bf16 v[120:123], v[152:155], v[160:163], v[120:123]
	v_mfma_f32_16x16x32_bf16 v[116:119], v[132:135], v[174:177], v[116:119]
	v_mfma_f32_16x16x32_bf16 v[112:115], v[152:155], v[174:177], v[112:115]
	v_mfma_f32_16x16x32_bf16 v[108:111], v[132:135], v[182:185], v[108:111]
	v_mfma_f32_16x16x32_bf16 v[104:107], v[152:155], v[182:185], v[104:107]
	v_mfma_f32_16x16x32_bf16 v[100:103], v[132:135], v[190:193], v[100:103]
	v_mfma_f32_16x16x32_bf16 v[96:99], v[152:155], v[190:193], v[96:99]
	s_setprio 0
	s_barrier
	s_add_i32 s28, 0, 0x1c000
	s_add_i32 s22, s66, s2
	v_add_u32_e32 v206, s28, v169
	v_lshl_add_u64 v[210:211], v[210:211], 0, s[6:7]
	s_mov_b32 m0, s22
	ds_read_b128 v[194:197], v206
	ds_read_b128 v[198:201], v206 offset:1024
	ds_read_b128 v[202:205], v206 offset:2048
	ds_read_b128 v[206:209], v206 offset:3072
	global_load_lds_dwordx4 v[210:211], off
	v_lshl_add_u64 v[210:211], v[212:213], 0, s[6:7]
	s_add_i32 m0, s22, 0x2000
	s_nop 0
	global_load_lds_dwordx4 v[210:211], off
	s_barrier
	s_waitcnt lgkmcnt(0)
	s_setprio 1
	s_waitcnt lgkmcnt(0)
	v_mfma_f32_16x16x32_bf16 v[64:67], v[194:197], v[156:159], v[64:67]
	v_mfma_f32_16x16x32_bf16 v[68:71], v[202:205], v[156:159], v[68:71]
	v_mfma_f32_16x16x32_bf16 v[48:51], v[194:197], v[164:167], v[48:51]
	v_mfma_f32_16x16x32_bf16 v[52:55], v[202:205], v[164:167], v[52:55]
	v_mfma_f32_16x16x32_bf16 v[40:43], v[194:197], v[178:181], v[40:43]
	v_mfma_f32_16x16x32_bf16 v[44:47], v[202:205], v[178:181], v[44:47]
	v_mfma_f32_16x16x32_bf16 v[32:35], v[194:197], v[186:189], v[32:35]
	v_mfma_f32_16x16x32_bf16 v[36:39], v[202:205], v[186:189], v[36:39]
	v_mfma_f32_16x16x32_bf16 v[64:67], v[198:201], v[160:163], v[64:67]
	v_mfma_f32_16x16x32_bf16 v[68:71], v[206:209], v[160:163], v[68:71]
	v_mfma_f32_16x16x32_bf16 v[48:51], v[198:201], v[174:177], v[48:51]
	v_mfma_f32_16x16x32_bf16 v[52:55], v[206:209], v[174:177], v[52:55]
	v_mfma_f32_16x16x32_bf16 v[40:43], v[198:201], v[182:185], v[40:43]
	v_mfma_f32_16x16x32_bf16 v[44:47], v[206:209], v[182:185], v[44:47]
	v_mfma_f32_16x16x32_bf16 v[32:35], v[198:201], v[190:193], v[32:35]
	v_mfma_f32_16x16x32_bf16 v[36:39], v[206:209], v[190:193], v[36:39]
	s_setprio 0
	s_mov_b32 m0, s38
	v_lshl_add_u64 v[210:211], v[214:215], 0, s[6:7]
	s_barrier
	ds_read_b128 v[156:159], v172 offset:49152
	ds_read_b128 v[160:163], v172 offset:50176
	ds_read_b128 v[164:167], v172 offset:51200
	ds_read_b128 v[174:177], v172 offset:52224
	ds_read_b128 v[178:181], v172 offset:53248
	ds_read_b128 v[182:185], v172 offset:54272
	ds_read_b128 v[186:189], v172 offset:55296
	ds_read_b128 v[190:193], v172 offset:56320
	global_load_lds_dwordx4 v[210:211], off
	v_lshl_add_u64 v[210:211], v[216:217], 0, s[6:7]
	s_mov_b32 m0, s39
	s_nop 0
	global_load_lds_dwordx4 v[210:211], off
	s_barrier
	s_waitcnt lgkmcnt(0)
	s_setprio 1
	s_waitcnt lgkmcnt(0)
	v_mfma_f32_16x16x32_bf16 v[92:95], v[128:131], v[156:159], v[92:95]
	v_mfma_f32_16x16x32_bf16 v[88:91], v[136:139], v[156:159], v[88:91]
	v_mfma_f32_16x16x32_bf16 v[84:87], v[128:131], v[164:167], v[84:87]
	v_mfma_f32_16x16x32_bf16 v[80:83], v[136:139], v[164:167], v[80:83]
	v_mfma_f32_16x16x32_bf16 v[76:79], v[128:131], v[178:181], v[76:79]
	v_mfma_f32_16x16x32_bf16 v[72:75], v[136:139], v[178:181], v[72:75]
	v_mfma_f32_16x16x32_bf16 v[60:63], v[128:131], v[186:189], v[60:63]
	v_mfma_f32_16x16x32_bf16 v[56:59], v[136:139], v[186:189], v[56:59]
	v_mfma_f32_16x16x32_bf16 v[92:95], v[132:135], v[160:163], v[92:95]
	v_mfma_f32_16x16x32_bf16 v[88:91], v[152:155], v[160:163], v[88:91]
	v_mfma_f32_16x16x32_bf16 v[84:87], v[132:135], v[174:177], v[84:87]
	v_mfma_f32_16x16x32_bf16 v[80:83], v[152:155], v[174:177], v[80:83]
	v_mfma_f32_16x16x32_bf16 v[76:79], v[132:135], v[182:185], v[76:79]
	v_mfma_f32_16x16x32_bf16 v[72:75], v[152:155], v[182:185], v[72:75]
	v_mfma_f32_16x16x32_bf16 v[60:63], v[132:135], v[190:193], v[60:63]
	v_mfma_f32_16x16x32_bf16 v[56:59], v[152:155], v[190:193], v[56:59]
	s_setprio 0
	s_barrier
	s_add_u32 s22, s26, 0x80080
	s_addc_u32 s23, s27, 0
	s_add_i32 s26, s28, s2
	v_lshl_add_u64 v[128:129], s[22:23], 0, v[142:143]
	s_mov_b32 m0, s26
	s_nop 0
	global_load_lds_dwordx4 v[128:129], off
	v_lshl_add_u64 v[128:129], s[22:23], 0, v[140:141]
	s_add_i32 m0, s26, 0x2000
	s_nop 0
	global_load_lds_dwordx4 v[128:129], off
	s_waitcnt vmcnt(6)
	s_barrier
	s_setprio 1
	v_mfma_f32_16x16x32_bf16 v[24:27], v[194:197], v[156:159], v[24:27]
	v_mfma_f32_16x16x32_bf16 v[28:31], v[202:205], v[156:159], v[28:31]
	v_mfma_f32_16x16x32_bf16 v[16:19], v[194:197], v[164:167], v[16:19]
	v_mfma_f32_16x16x32_bf16 v[20:23], v[202:205], v[164:167], v[20:23]
	v_mfma_f32_16x16x32_bf16 v[8:11], v[194:197], v[178:181], v[8:11]
	v_mfma_f32_16x16x32_bf16 v[12:15], v[202:205], v[178:181], v[12:15]
	v_mfma_f32_16x16x32_bf16 v[4:7], v[194:197], v[186:189], v[4:7]
	v_mfma_f32_16x16x32_bf16 v[0:3], v[202:205], v[186:189], v[0:3]
	v_mfma_f32_16x16x32_bf16 v[24:27], v[198:201], v[160:163], v[24:27]
	v_mfma_f32_16x16x32_bf16 v[28:31], v[206:209], v[160:163], v[28:31]
	v_mfma_f32_16x16x32_bf16 v[16:19], v[198:201], v[174:177], v[16:19]
	v_mfma_f32_16x16x32_bf16 v[20:23], v[206:209], v[174:177], v[20:23]
	v_mfma_f32_16x16x32_bf16 v[8:11], v[198:201], v[182:185], v[8:11]
	v_mfma_f32_16x16x32_bf16 v[12:15], v[206:209], v[182:185], v[12:15]
	v_mfma_f32_16x16x32_bf16 v[4:7], v[198:201], v[190:193], v[4:7]
	v_mfma_f32_16x16x32_bf16 v[0:3], v[206:209], v[190:193], v[0:3]
	s_setprio 0
	s_add_i32 s65, s65, 2
	s_add_u32 s63, s63, 0x100
	s_addc_u32 s64, s64, 0
	s_cmp_gt_u32 s65, 29
	s_mov_b64 s[22:23], s[24:25]
	s_barrier
	s_cbranch_scc0 .LBB0_413
	v_lshl_or_b32 v154, s19, 7, v170
	v_ashrrev_i32_e32 v155, 31, v154
	v_lshlrev_b64 v[184:185], 2, v[154:155]
	v_readlane_b32 s64, v240, 49
	v_lshl_add_u64 v[128:129], s[8:9], 0, v[184:185]
	v_readlane_b32 s72, v240, 57
	v_readlane_b32 s73, v240, 58
	s_nop 1
	v_lshl_add_u64 v[186:187], s[72:73], 0, v[184:185]
	global_load_dwordx4 v[128:131], v[128:129], off
	s_nop 0
	global_load_dwordx4 v[188:191], v[186:187], off
	s_cmp_lt_u32 s18, 32
	s_movk_i32 s11, 0x3000
	s_cselect_b32 s11, s11, 0x6000
	s_cmp_gt_i32 s18, 15
	s_cselect_b32 s11, s11, 0
	v_lshl_add_u32 v166, s18, 8, v168
	s_lshl_b32 s11, s11, 2
	v_readlane_b32 s65, v240, 50
	v_readlane_b32 s66, v240, 51
	v_readlane_b32 s67, v240, 52
	v_readlane_b32 s68, v240, 53
	v_readlane_b32 s69, v240, 54
	v_readlane_b32 s70, v240, 55
	v_readlane_b32 s71, v240, 56
	v_readlane_b32 s74, v240, 59
	v_readlane_b32 s75, v240, 60
	v_readlane_b32 s76, v240, 61
	v_readlane_b32 s77, v240, 62
	v_readlane_b32 s78, v240, 63
	v_readlane_b32 s79, v239, 0
	v_ashrrev_i32_e32 v167, 31, v166
	s_add_u32 s22, s41, s11
	v_lshlrev_b64 v[138:139], 11, v[166:167]
	s_addc_u32 s23, s42, 0
	v_readlane_b32 s64, v239, 3
	v_lshl_add_u64 v[138:139], v[138:139], 0, v[154:155]
	s_nop 1
	v_lshlrev_b64 v[192:193], 2, v[138:139]
	v_lshl_add_u64 v[194:195], s[22:23], 0, v[184:185]
	global_load_dwordx4 v[196:199], v[194:195], off
	s_cmp_lt_i32 s18, 32
	v_readlane_b32 s65, v239, 4
	s_nop 1
	s_cselect_b32 s19, s65, s46
	s_cselect_b32 s18, s64, s43
	s_nop 0
	v_lshl_add_u64 v[184:185], s[18:19], 0, v[192:193]
	global_load_dwordx4 v[200:203], v[184:185], off
	v_readlane_b32 s66, v239, 5
	v_readlane_b32 s67, v239, 6
	v_readlane_b32 s68, v239, 7
	v_readlane_b32 s69, v239, 8
	v_readlane_b32 s70, v239, 9
	v_readlane_b32 s71, v239, 10
	v_readlane_b32 s72, v239, 11
	v_readlane_b32 s73, v239, 12
	v_readlane_b32 s74, v239, 13
	v_readlane_b32 s75, v239, 14
	v_readlane_b32 s76, v239, 15
	v_readlane_b32 s77, v239, 16
	v_readlane_b32 s78, v239, 17
	v_readlane_b32 s79, v239, 18
	v_or_b32_e32 v160, 16, v166
	v_ashrrev_i32_e32 v161, 31, v160
	v_readlane_b32 s64, v240, 22
	v_lshlrev_b64 v[160:161], 11, v[160:161]
	s_nop 1
	v_lshl_add_u64 v[204:205], v[160:161], 0, v[154:155]
	s_nop 1
	v_lshlrev_b64 v[206:207], 2, v[204:205]
	v_lshl_add_u64 v[208:209], s[18:19], 0, v[206:207]
	global_load_dwordx4 v[212:215], v[208:209], off
	v_readlane_b32 s68, v240, 26
	v_readlane_b32 s69, v240, 27
	v_readlane_b32 s70, v240, 28
	v_readlane_b32 s71, v240, 29
	v_readlane_b32 s72, v240, 30
	v_readlane_b32 s73, v240, 31
	v_readlane_b32 s74, v240, 32
	v_readlane_b32 s75, v240, 33
	v_readlane_b32 s76, v240, 34
	v_readlane_b32 s77, v240, 35
	v_readlane_b32 s78, v240, 36
	v_readlane_b32 s79, v240, 37
	s_mov_b64 s[48:49], s[68:69]
	v_lshl_add_u64 v[160:161], s[48:49], 0, v[192:193]
	s_mov_b64 s[22:23], 0x100000
	s_mov_b64 s[24:25], s[16:17]
	s_and_b64 vcc, exec, s[4:5]
	v_readlane_b32 s65, v240, 23
	v_readlane_b32 s66, v240, 24
	v_readlane_b32 s67, v240, 25
	s_mov_b64 s[50:51], s[70:71]
	s_waitcnt vmcnt(4)
	v_add_f32_e32 v167, v120, v128
	v_add_f32_e32 v180, v121, v129
	v_add_f32_e32 v181, v122, v130
	v_add_f32_e32 v182, v123, v131
	s_waitcnt vmcnt(3)
	v_pk_add_f32 v[120:121], v[126:127], v[190:191]
	v_pk_add_f32 v[122:123], v[124:125], v[188:189]
	v_mul_f32_e32 v124, 0xbfb8aa3b, v167
	v_mul_f32_e32 v125, 0xbfb8aa3b, v180
	v_mul_f32_e32 v126, 0xbfb8aa3b, v181
	v_mul_f32_e32 v127, 0xbfb8aa3b, v182
	v_exp_f32_e32 v124, v124
	v_exp_f32_e32 v125, v125
	v_exp_f32_e32 v126, v126
	v_exp_f32_e32 v127, v127
	v_add_f32_e32 v124, 1.0, v124
	v_add_f32_e32 v125, 1.0, v125
	v_add_f32_e32 v126, 1.0, v126
	v_add_f32_e32 v127, 1.0, v127
	v_rcp_f32_e32 v124, v124
	v_rcp_f32_e32 v126, v126
	v_rcp_f32_e32 v127, v127
	v_rcp_f32_e32 v125, v125
	v_add_f32_e32 v167, v112, v128
	s_mov_b64 s[52:53], s[72:73]
	s_mov_b64 s[54:55], s[74:75]
	s_mov_b64 s[56:57], s[76:77]
	s_mov_b64 s[58:59], s[78:79]
	s_waitcnt vmcnt(2)
	v_pk_mul_f32 v[120:121], v[198:199], v[120:121]
	v_pk_mul_f32 v[180:181], v[196:197], v[122:123]
	s_waitcnt vmcnt(1)
	v_pk_fma_f32 v[122:123], v[120:121], v[126:127], v[202:203]
	v_pk_fma_f32 v[120:121], v[180:181], v[124:125], v[200:201]
	global_store_dwordx4 v[160:161], v[120:123], off
	v_add_f32_e32 v176, v113, v129
	s_nop 0
	v_or_b32_e32 v120, 32, v166
	v_ashrrev_i32_e32 v121, 31, v120
	v_lshlrev_b64 v[120:121], 11, v[120:121]
	v_lshl_add_u64 v[120:121], v[120:121], 0, v[154:155]
	v_lshlrev_b64 v[200:201], 2, v[120:121]
	s_nop 1
	v_lshl_add_u64 v[202:203], s[18:19], 0, v[200:201]
	global_load_dwordx4 v[216:219], v[202:203], off
	v_lshl_add_u64 v[120:121], s[48:49], 0, v[206:207]
	v_add_f32_e32 v177, v114, v130
	v_add_f32_e32 v178, v115, v131
	v_pk_add_f32 v[112:113], v[118:119], v[190:191]
	v_pk_add_f32 v[114:115], v[116:117], v[188:189]
	v_mul_f32_e32 v116, 0xbfb8aa3b, v167
	v_mul_f32_e32 v117, 0xbfb8aa3b, v176
	v_mul_f32_e32 v118, 0xbfb8aa3b, v177
	v_mul_f32_e32 v119, 0xbfb8aa3b, v178
	v_exp_f32_e32 v116, v116
	v_exp_f32_e32 v117, v117
	v_exp_f32_e32 v118, v118
	v_exp_f32_e32 v119, v119
	v_add_f32_e32 v116, 1.0, v116
	v_add_f32_e32 v117, 1.0, v117
	v_add_f32_e32 v118, 1.0, v118
	v_add_f32_e32 v119, 1.0, v119
	v_rcp_f32_e32 v116, v116
	v_rcp_f32_e32 v117, v117
	v_rcp_f32_e32 v118, v118
	v_rcp_f32_e32 v119, v119
	v_pk_mul_f32 v[176:177], v[198:199], v[112:113]
	v_pk_mul_f32 v[112:113], v[196:197], v[114:115]
	s_waitcnt vmcnt(2)
	s_nop 0
	v_pk_fma_f32 v[112:113], v[112:113], v[116:117], v[212:213]
	v_pk_fma_f32 v[114:115], v[176:177], v[118:119], v[214:215]
	global_store_dwordx4 v[120:121], v[112:115], off
	v_add_f32_e32 v126, v104, v128
	s_nop 0
	v_or_b32_e32 v112, 48, v166
	v_ashrrev_i32_e32 v113, 31, v112
	v_lshlrev_b64 v[112:113], 11, v[112:113]
	v_lshl_add_u64 v[112:113], v[112:113], 0, v[154:155]
	s_nop 1
	v_lshlrev_b64 v[204:205], 2, v[112:113]
	s_nop 0
	v_lshl_add_u64 v[206:207], s[18:19], 0, v[204:205]
	global_load_dwordx4 v[212:215], v[206:207], off
	v_lshl_add_u64 v[210:211], v[192:193], 0, s[22:23]
	v_add_f32_e32 v127, v105, v129
	v_add_f32_e32 v155, v106, v130
	v_add_f32_e32 v166, v107, v131
	v_pk_add_f32 v[104:105], v[110:111], v[190:191]
	v_pk_add_f32 v[106:107], v[108:109], v[188:189]
	v_mul_f32_e32 v108, 0xbfb8aa3b, v126
	v_mul_f32_e32 v109, 0xbfb8aa3b, v127
	v_mul_f32_e32 v110, 0xbfb8aa3b, v155
	v_mul_f32_e32 v111, 0xbfb8aa3b, v166
	v_exp_f32_e32 v108, v108
	v_exp_f32_e32 v109, v109
	v_exp_f32_e32 v110, v110
	v_exp_f32_e32 v111, v111
	v_add_f32_e32 v108, 1.0, v108
	v_add_f32_e32 v109, 1.0, v109
	v_add_f32_e32 v110, 1.0, v110
	v_add_f32_e32 v111, 1.0, v111
	v_rcp_f32_e32 v108, v108
	v_rcp_f32_e32 v109, v109
	v_rcp_f32_e32 v110, v110
	v_rcp_f32_e32 v111, v111
	v_pk_mul_f32 v[126:127], v[198:199], v[104:105]
	v_pk_mul_f32 v[104:105], v[196:197], v[106:107]
	v_lshl_add_u64 v[112:113], s[48:49], 0, v[200:201]
	v_lshl_add_u64 v[200:201], s[18:19], 0, v[210:211]
	s_waitcnt vmcnt(2)
	v_pk_fma_f32 v[104:105], v[104:105], v[108:109], v[216:217]
	v_pk_fma_f32 v[106:107], v[126:127], v[110:111], v[218:219]
	global_load_dwordx4 v[216:219], v[200:201], off
	global_store_dwordx4 v[112:113], v[104:107], off
	v_add_f32_e32 v118, v96, v128
	s_nop 0
	v_lshl_add_u64 v[104:105], s[48:49], 0, v[204:205]
	v_add_f32_e32 v119, v97, v129
	v_add_f32_e32 v124, v98, v130
	v_add_f32_e32 v125, v99, v131
	v_pk_add_f32 v[96:97], v[102:103], v[190:191]
	v_pk_add_f32 v[98:99], v[100:101], v[188:189]
	v_mul_f32_e32 v100, 0xbfb8aa3b, v118
	v_mul_f32_e32 v101, 0xbfb8aa3b, v119
	v_mul_f32_e32 v102, 0xbfb8aa3b, v124
	v_mul_f32_e32 v103, 0xbfb8aa3b, v125
	v_exp_f32_e32 v100, v100
	v_exp_f32_e32 v101, v101
	v_exp_f32_e32 v102, v102
	v_exp_f32_e32 v103, v103
	v_add_f32_e32 v100, 1.0, v100
	v_add_f32_e32 v101, 1.0, v101
	v_add_f32_e32 v102, 1.0, v102
	v_add_f32_e32 v103, 1.0, v103
	v_rcp_f32_e32 v100, v100
	v_rcp_f32_e32 v101, v101
	v_rcp_f32_e32 v102, v102
	v_rcp_f32_e32 v103, v103
	v_pk_mul_f32 v[118:119], v[198:199], v[96:97]
	v_pk_mul_f32 v[96:97], v[196:197], v[98:99]
	s_mov_b64 s[22:23], 0x120000
	s_nop 0
	v_lshl_add_u64 v[204:205], v[192:193], 0, s[22:23]
	s_waitcnt vmcnt(2)
	v_pk_fma_f32 v[96:97], v[96:97], v[100:101], v[212:213]
	v_pk_fma_f32 v[98:99], v[118:119], v[102:103], v[214:215]
	v_lshl_add_u64 v[212:213], s[18:19], 0, v[204:205]
	global_store_dwordx4 v[104:105], v[96:99], off
	v_add_f32_e32 v110, v88, v128
	s_nop 0
	v_lshl_add_u64 v[96:97], s[48:49], 0, v[210:211]
	global_load_dwordx4 v[220:223], v[212:213], off
	v_add_f32_e32 v111, v89, v129
	v_add_f32_e32 v116, v90, v130
	v_add_f32_e32 v117, v91, v131
	v_pk_add_f32 v[88:89], v[94:95], v[190:191]
	v_pk_add_f32 v[90:91], v[92:93], v[188:189]
	v_mul_f32_e32 v92, 0xbfb8aa3b, v110
	v_mul_f32_e32 v93, 0xbfb8aa3b, v111
	v_mul_f32_e32 v94, 0xbfb8aa3b, v116
	v_mul_f32_e32 v95, 0xbfb8aa3b, v117
	v_exp_f32_e32 v92, v92
	v_exp_f32_e32 v93, v93
	v_exp_f32_e32 v94, v94
	v_exp_f32_e32 v95, v95
	v_add_f32_e32 v92, 1.0, v92
	v_add_f32_e32 v93, 1.0, v93
	v_add_f32_e32 v94, 1.0, v94
	v_add_f32_e32 v95, 1.0, v95
	v_rcp_f32_e32 v92, v92
	v_rcp_f32_e32 v93, v93
	v_rcp_f32_e32 v94, v94
	v_rcp_f32_e32 v95, v95
	v_pk_mul_f32 v[110:111], v[198:199], v[88:89]
	v_pk_mul_f32 v[88:89], v[196:197], v[90:91]
	s_mov_b64 s[22:23], 0x140000
	s_waitcnt vmcnt(3)
	v_pk_fma_f32 v[88:89], v[88:89], v[92:93], v[216:217]
	v_pk_fma_f32 v[90:91], v[110:111], v[94:95], v[218:219]
	v_lshl_add_u64 v[210:211], v[192:193], 0, s[22:23]
	global_store_dwordx4 v[96:97], v[88:91], off
	v_add_f32_e32 v102, v80, v128
	s_nop 0
	v_lshl_add_u64 v[88:89], s[48:49], 0, v[204:205]
	v_lshl_add_u64 v[204:205], s[18:19], 0, v[210:211]
	v_add_f32_e32 v103, v81, v129
	v_add_f32_e32 v108, v82, v130
	v_add_f32_e32 v109, v83, v131
	v_pk_add_f32 v[80:81], v[86:87], v[190:191]
	v_pk_add_f32 v[82:83], v[84:85], v[188:189]
	v_mul_f32_e32 v84, 0xbfb8aa3b, v102
	v_mul_f32_e32 v85, 0xbfb8aa3b, v103
	v_mul_f32_e32 v86, 0xbfb8aa3b, v108
	v_mul_f32_e32 v87, 0xbfb8aa3b, v109
	v_exp_f32_e32 v84, v84
	v_exp_f32_e32 v85, v85
	v_exp_f32_e32 v86, v86
	v_exp_f32_e32 v87, v87
	v_add_f32_e32 v84, 1.0, v84
	v_add_f32_e32 v85, 1.0, v85
	v_add_f32_e32 v86, 1.0, v86
	v_add_f32_e32 v87, 1.0, v87
	v_rcp_f32_e32 v84, v84
	v_rcp_f32_e32 v85, v85
	v_rcp_f32_e32 v86, v86
	v_rcp_f32_e32 v87, v87
	v_pk_mul_f32 v[102:103], v[198:199], v[80:81]
	v_pk_mul_f32 v[80:81], v[196:197], v[82:83]
	s_mov_b64 s[22:23], 0x160000
	s_waitcnt vmcnt(1)
	v_pk_fma_f32 v[80:81], v[80:81], v[84:85], v[220:221]
	v_pk_fma_f32 v[82:83], v[102:103], v[86:87], v[222:223]
	global_load_dwordx4 v[216:219], v[204:205], off
	global_store_dwordx4 v[88:89], v[80:83], off
	v_add_f32_e32 v94, v72, v128
	s_nop 0
	v_lshl_add_u64 v[80:81], s[48:49], 0, v[210:211]
	v_lshl_add_u64 v[210:211], v[192:193], 0, s[22:23]
	v_add_f32_e32 v95, v73, v129
	v_add_f32_e32 v100, v74, v130
	v_add_f32_e32 v101, v75, v131
	v_pk_add_f32 v[72:73], v[78:79], v[190:191]
	v_pk_add_f32 v[74:75], v[76:77], v[188:189]
	v_mul_f32_e32 v76, 0xbfb8aa3b, v94
	v_mul_f32_e32 v77, 0xbfb8aa3b, v95
	v_mul_f32_e32 v78, 0xbfb8aa3b, v100
	v_mul_f32_e32 v79, 0xbfb8aa3b, v101
	v_exp_f32_e32 v76, v76
	v_exp_f32_e32 v77, v77
	v_exp_f32_e32 v78, v78
	v_exp_f32_e32 v79, v79
	v_add_f32_e32 v76, 1.0, v76
	v_add_f32_e32 v77, 1.0, v77
	v_add_f32_e32 v78, 1.0, v78
	v_add_f32_e32 v79, 1.0, v79
	v_rcp_f32_e32 v76, v76
	v_rcp_f32_e32 v77, v77
	v_rcp_f32_e32 v78, v78
	v_rcp_f32_e32 v79, v79
	v_pk_mul_f32 v[94:95], v[198:199], v[72:73]
	v_pk_mul_f32 v[72:73], v[196:197], v[74:75]
	v_lshl_add_u64 v[192:193], s[18:19], 0, v[210:211]
	s_mov_b32 s19, s10
	s_mov_b64 s[22:23], s[14:15]
	s_mov_b32 s18, s12
	s_waitcnt vmcnt(1)
	v_pk_fma_f32 v[72:73], v[72:73], v[76:77], v[216:217]
	v_pk_fma_f32 v[74:75], v[94:95], v[78:79], v[218:219]
	global_load_dwordx4 v[216:219], v[192:193], off
	v_or_b32_e32 v76, 64, v154
	v_ashrrev_i32_e32 v77, 31, v76
	global_store_dwordx4 v[80:81], v[72:75], off
	v_add_f32_e32 v84, v56, v128
	v_add_f32_e32 v85, v57, v129
	v_add_f32_e32 v86, v58, v130
	v_add_f32_e32 v87, v59, v131
	v_pk_add_f32 v[56:57], v[62:63], v[190:191]
	v_pk_add_f32 v[58:59], v[60:61], v[188:189]
	v_lshl_add_u64 v[188:189], v[76:77], 2, s[8:9]
	v_mul_f32_e32 v60, 0xbfb8aa3b, v84
	v_mul_f32_e32 v61, 0xbfb8aa3b, v85
	v_mul_f32_e32 v62, 0xbfb8aa3b, v86
	v_mul_f32_e32 v63, 0xbfb8aa3b, v87
	v_exp_f32_e32 v60, v60
	v_exp_f32_e32 v61, v61
	v_exp_f32_e32 v62, v62
	v_exp_f32_e32 v63, v63
	v_add_f32_e32 v60, 1.0, v60
	v_add_f32_e32 v61, 1.0, v61
	v_add_f32_e32 v62, 1.0, v62
	v_add_f32_e32 v63, 1.0, v63
	v_rcp_f32_e32 v60, v60
	v_rcp_f32_e32 v61, v61
	v_rcp_f32_e32 v62, v62
	v_rcp_f32_e32 v63, v63
	v_pk_mul_f32 v[84:85], v[198:199], v[56:57]
	v_pk_mul_f32 v[56:57], v[196:197], v[58:59]
	global_load_dwordx4 v[196:199], v[188:189], off
	v_lshl_add_u64 v[76:77], s[48:49], 0, v[210:211]
	global_load_dwordx4 v[220:223], v[186:187], off offset:256
	s_waitcnt vmcnt(3)
	v_pk_fma_f32 v[56:57], v[56:57], v[60:61], v[216:217]
	v_pk_fma_f32 v[58:59], v[84:85], v[62:63], v[218:219]
	global_load_dwordx4 v[216:219], v[194:195], off offset:256
	global_store_dwordx4 v[76:77], v[56:59], off
	global_load_dwordx4 v[188:191], v[184:185], off offset:256
	global_load_dwordx4 v[224:227], v[208:209], off offset:256
	global_load_dwordx4 v[184:187], v[202:203], off offset:256
	global_load_dwordx4 v[228:231], v[206:207], off offset:256
	s_waitcnt vmcnt(7)
	v_add_f32_e32 v68, v68, v196
	v_add_f32_e32 v69, v69, v197
	v_add_f32_e32 v70, v70, v198
	v_add_f32_e32 v71, v71, v199
	v_mul_f32_e32 v68, 0xbfb8aa3b, v68
	v_mul_f32_e32 v69, 0xbfb8aa3b, v69
	v_mul_f32_e32 v70, 0xbfb8aa3b, v70
	v_mul_f32_e32 v71, 0xbfb8aa3b, v71
	v_exp_f32_e32 v68, v68
	v_exp_f32_e32 v69, v69
	v_exp_f32_e32 v70, v70
	v_exp_f32_e32 v71, v71
	v_add_f32_e32 v68, 1.0, v68
	v_add_f32_e32 v69, 1.0, v69
	v_add_f32_e32 v70, 1.0, v70
	v_add_f32_e32 v71, 1.0, v71
	v_rcp_f32_e32 v68, v68
	v_rcp_f32_e32 v70, v70
	v_rcp_f32_e32 v71, v71
	v_rcp_f32_e32 v69, v69
	s_waitcnt vmcnt(6)
	v_pk_add_f32 v[66:67], v[66:67], v[222:223]
	v_pk_add_f32 v[64:65], v[64:65], v[220:221]
	s_waitcnt vmcnt(5)
	v_pk_mul_f32 v[66:67], v[218:219], v[66:67]
	v_pk_mul_f32 v[64:65], v[216:217], v[64:65]
	s_waitcnt vmcnt(3)
	v_pk_fma_f32 v[66:67], v[66:67], v[70:71], v[190:191]
	v_pk_fma_f32 v[64:65], v[64:65], v[68:69], v[188:189]
	global_load_dwordx4 v[188:191], v[200:201], off offset:256
	global_store_dwordx4 v[160:161], v[64:67], off offset:256
	v_add_f32_e32 v52, v52, v196
	global_load_dwordx4 v[208:211], v[212:213], off offset:256
	v_add_f32_e32 v53, v53, v197
	v_add_f32_e32 v54, v54, v198
	v_add_f32_e32 v55, v55, v199
	v_mul_f32_e32 v52, 0xbfb8aa3b, v52
	v_mul_f32_e32 v53, 0xbfb8aa3b, v53
	v_mul_f32_e32 v54, 0xbfb8aa3b, v54
	v_mul_f32_e32 v55, 0xbfb8aa3b, v55
	v_exp_f32_e32 v52, v52
	v_exp_f32_e32 v53, v53
	v_exp_f32_e32 v54, v54
	v_exp_f32_e32 v55, v55
	v_add_f32_e32 v52, 1.0, v52
	v_add_f32_e32 v53, 1.0, v53
	v_add_f32_e32 v54, 1.0, v54
	v_add_f32_e32 v55, 1.0, v55
	v_rcp_f32_e32 v52, v52
	v_rcp_f32_e32 v53, v53
	v_rcp_f32_e32 v54, v54
	v_rcp_f32_e32 v55, v55
	v_pk_add_f32 v[50:51], v[50:51], v[222:223]
	v_pk_add_f32 v[48:49], v[48:49], v[220:221]
	v_pk_mul_f32 v[50:51], v[218:219], v[50:51]
	v_pk_mul_f32 v[48:49], v[216:217], v[48:49]
	v_add_f32_e32 v44, v44, v196
	v_add_f32_e32 v45, v45, v197
	v_add_f32_e32 v46, v46, v198
	v_add_f32_e32 v47, v47, v199
	v_mul_f32_e32 v44, 0xbfb8aa3b, v44
	v_mul_f32_e32 v45, 0xbfb8aa3b, v45
	v_mul_f32_e32 v46, 0xbfb8aa3b, v46
	v_mul_f32_e32 v47, 0xbfb8aa3b, v47
	v_exp_f32_e32 v44, v44
	v_exp_f32_e32 v45, v45
	v_exp_f32_e32 v46, v46
	v_exp_f32_e32 v47, v47
	v_add_f32_e32 v44, 1.0, v44
	v_add_f32_e32 v45, 1.0, v45
	v_add_f32_e32 v46, 1.0, v46
	v_add_f32_e32 v47, 1.0, v47
	v_rcp_f32_e32 v44, v44
	v_rcp_f32_e32 v45, v45
	v_rcp_f32_e32 v46, v46
	v_rcp_f32_e32 v47, v47
	v_pk_add_f32 v[42:43], v[42:43], v[222:223]
	v_pk_add_f32 v[40:41], v[40:41], v[220:221]
	v_pk_mul_f32 v[42:43], v[218:219], v[42:43]
	v_pk_mul_f32 v[40:41], v[216:217], v[40:41]
	v_add_f32_e32 v36, v36, v196
	v_add_f32_e32 v37, v37, v197
	v_add_f32_e32 v38, v38, v198
	v_add_f32_e32 v39, v39, v199
	v_mul_f32_e32 v36, 0xbfb8aa3b, v36
	v_mul_f32_e32 v37, 0xbfb8aa3b, v37
	v_mul_f32_e32 v38, 0xbfb8aa3b, v38
	v_mul_f32_e32 v39, 0xbfb8aa3b, v39
	v_exp_f32_e32 v36, v36
	v_exp_f32_e32 v37, v37
	v_exp_f32_e32 v38, v38
	v_exp_f32_e32 v39, v39
	v_add_f32_e32 v36, 1.0, v36
	v_add_f32_e32 v37, 1.0, v37
	v_add_f32_e32 v38, 1.0, v38
	v_add_f32_e32 v39, 1.0, v39
	v_rcp_f32_e32 v36, v36
	v_rcp_f32_e32 v37, v37
	v_rcp_f32_e32 v38, v38
	v_rcp_f32_e32 v39, v39
	v_pk_add_f32 v[34:35], v[34:35], v[222:223]
	v_pk_add_f32 v[32:33], v[32:33], v[220:221]
	v_pk_mul_f32 v[34:35], v[218:219], v[34:35]
	v_pk_mul_f32 v[32:33], v[216:217], v[32:33]
	v_add_f32_e32 v28, v28, v196
	v_add_f32_e32 v29, v29, v197
	v_add_f32_e32 v30, v30, v198
	v_add_f32_e32 v31, v31, v199
	v_mul_f32_e32 v28, 0xbfb8aa3b, v28
	v_mul_f32_e32 v29, 0xbfb8aa3b, v29
	v_mul_f32_e32 v30, 0xbfb8aa3b, v30
	s_waitcnt vmcnt(5)
	v_pk_fma_f32 v[48:49], v[48:49], v[52:53], v[224:225]
	v_pk_fma_f32 v[50:51], v[50:51], v[54:55], v[226:227]
	global_load_dwordx4 v[224:227], v[204:205], off offset:256
	global_store_dwordx4 v[120:121], v[48:51], off offset:256
	v_mul_f32_e32 v31, 0xbfb8aa3b, v31
	global_load_dwordx4 v[232:235], v[192:193], off offset:256
	v_exp_f32_e32 v28, v28
	v_exp_f32_e32 v29, v29
	v_exp_f32_e32 v30, v30
	v_exp_f32_e32 v31, v31
	v_add_f32_e32 v28, 1.0, v28
	v_add_f32_e32 v29, 1.0, v29
	v_add_f32_e32 v30, 1.0, v30
	v_add_f32_e32 v31, 1.0, v31
	v_rcp_f32_e32 v28, v28
	v_rcp_f32_e32 v29, v29
	v_rcp_f32_e32 v30, v30
	v_rcp_f32_e32 v31, v31
	v_pk_add_f32 v[26:27], v[26:27], v[222:223]
	v_pk_add_f32 v[24:25], v[24:25], v[220:221]
	v_pk_mul_f32 v[26:27], v[218:219], v[26:27]
	v_pk_mul_f32 v[24:25], v[216:217], v[24:25]
	v_add_f32_e32 v20, v20, v196
	v_add_f32_e32 v21, v21, v197
	v_add_f32_e32 v22, v22, v198
	v_add_f32_e32 v23, v23, v199
	v_mul_f32_e32 v20, 0xbfb8aa3b, v20
	v_mul_f32_e32 v21, 0xbfb8aa3b, v21
	v_mul_f32_e32 v22, 0xbfb8aa3b, v22
	v_mul_f32_e32 v23, 0xbfb8aa3b, v23
	v_exp_f32_e32 v20, v20
	v_exp_f32_e32 v21, v21
	v_exp_f32_e32 v22, v22
	v_exp_f32_e32 v23, v23
	v_add_f32_e32 v20, 1.0, v20
	v_add_f32_e32 v21, 1.0, v21
	v_add_f32_e32 v22, 1.0, v22
	v_add_f32_e32 v23, 1.0, v23
	v_rcp_f32_e32 v20, v20
	v_rcp_f32_e32 v21, v21
	v_rcp_f32_e32 v22, v22
	v_rcp_f32_e32 v23, v23
	v_pk_add_f32 v[18:19], v[18:19], v[222:223]
	v_pk_add_f32 v[16:17], v[16:17], v[220:221]
	v_pk_mul_f32 v[18:19], v[218:219], v[18:19]
	v_pk_mul_f32 v[16:17], v[216:217], v[16:17]
	v_add_f32_e32 v12, v12, v196
	v_add_f32_e32 v13, v13, v197
	v_add_f32_e32 v14, v14, v198
	v_add_f32_e32 v15, v15, v199
	v_mul_f32_e32 v12, 0xbfb8aa3b, v12
	v_mul_f32_e32 v13, 0xbfb8aa3b, v13
	v_mul_f32_e32 v14, 0xbfb8aa3b, v14
	v_mul_f32_e32 v15, 0xbfb8aa3b, v15
	v_exp_f32_e32 v12, v12
	v_exp_f32_e32 v13, v13
	v_exp_f32_e32 v14, v14
	v_exp_f32_e32 v15, v15
	v_add_f32_e32 v12, 1.0, v12
	v_add_f32_e32 v13, 1.0, v13
	v_add_f32_e32 v14, 1.0, v14
	v_add_f32_e32 v15, 1.0, v15
	v_rcp_f32_e32 v12, v12
	v_rcp_f32_e32 v13, v13
	v_rcp_f32_e32 v14, v14
	v_rcp_f32_e32 v15, v15
	v_pk_add_f32 v[10:11], v[10:11], v[222:223]
	v_pk_add_f32 v[8:9], v[8:9], v[220:221]
	v_pk_mul_f32 v[10:11], v[218:219], v[10:11]
	v_pk_mul_f32 v[8:9], v[216:217], v[8:9]
	s_waitcnt vmcnt(7)
	v_pk_fma_f32 v[40:41], v[40:41], v[44:45], v[184:185]
	v_pk_fma_f32 v[42:43], v[42:43], v[46:47], v[186:187]
	global_store_dwordx4 v[112:113], v[40:43], off offset:256
	s_waitcnt vmcnt(7)
	v_pk_fma_f32 v[32:33], v[32:33], v[36:37], v[228:229]
	v_pk_fma_f32 v[34:35], v[34:35], v[38:39], v[230:231]
	global_store_dwordx4 v[104:105], v[32:35], off offset:256
	s_waitcnt vmcnt(7)
	v_pk_fma_f32 v[24:25], v[24:25], v[28:29], v[188:189]
	v_pk_fma_f32 v[26:27], v[26:27], v[30:31], v[190:191]
	global_store_dwordx4 v[96:97], v[24:27], off offset:256
	s_waitcnt vmcnt(6)
	v_pk_fma_f32 v[16:17], v[16:17], v[20:21], v[208:209]
	v_pk_fma_f32 v[18:19], v[18:19], v[22:23], v[210:211]
	global_store_dwordx4 v[88:89], v[16:19], off offset:256
	s_waitcnt vmcnt(6)
	v_pk_fma_f32 v[8:9], v[8:9], v[12:13], v[224:225]
	v_pk_fma_f32 v[10:11], v[10:11], v[14:15], v[226:227]
	global_store_dwordx4 v[80:81], v[8:11], off offset:256
	v_add_f32_e32 v12, v0, v196
	v_add_f32_e32 v13, v1, v197
	v_add_f32_e32 v14, v2, v198
	v_add_f32_e32 v15, v3, v199
	v_pk_add_f32 v[0:1], v[6:7], v[222:223]
	v_pk_add_f32 v[2:3], v[4:5], v[220:221]
	v_mul_f32_e32 v4, 0xbfb8aa3b, v12
	v_mul_f32_e32 v5, 0xbfb8aa3b, v13
	v_mul_f32_e32 v6, 0xbfb8aa3b, v14
	v_mul_f32_e32 v7, 0xbfb8aa3b, v15
	v_exp_f32_e32 v4, v4
	v_exp_f32_e32 v5, v5
	v_exp_f32_e32 v6, v6
	v_exp_f32_e32 v7, v7
	v_add_f32_e32 v4, 1.0, v4
	v_add_f32_e32 v5, 1.0, v5
	v_add_f32_e32 v6, 1.0, v6
	v_add_f32_e32 v7, 1.0, v7
	v_rcp_f32_e32 v4, v4
	v_rcp_f32_e32 v5, v5
	v_rcp_f32_e32 v6, v6
	v_rcp_f32_e32 v7, v7
	v_pk_mul_f32 v[12:13], v[218:219], v[0:1]
	v_pk_mul_f32 v[0:1], v[216:217], v[2:3]
	s_waitcnt vmcnt(5)
	v_pk_fma_f32 v[2:3], v[12:13], v[6:7], v[234:235]
	v_pk_fma_f32 v[0:1], v[0:1], v[4:5], v[232:233]
	global_store_dwordx4 v[76:77], v[0:3], off offset:256
	s_cbranch_vccz .LBB0_410
	s_waitcnt vmcnt(0)
	s_cmpk_gt_u32 s1, 0xff
	s_cbranch_scc1 .LBB0_417
	s_barrier

.LBB0_545:
	global_load_dwordx4 v[28:31], v[44:45], off offset:-4096
	global_load_dwordx4 v[24:27], v[44:45], off offset:-3072
	global_load_dwordx4 v[20:23], v[44:45], off offset:-2048
	global_load_dwordx4 v[16:19], v[44:45], off offset:-1024
	global_load_dwordx4 v[12:15], v[44:45], off
	global_load_dwordx4 v[8:11], v[44:45], off offset:1024
	global_load_dwordx4 v[4:7], v[44:45], off offset:2048
	global_load_dwordx4 v[0:3], v[44:45], off offset:3072
	s_and_b64 vcc, exec, s[6:7]
	s_waitcnt vmcnt(7)
	v_mul_f32_e32 v49, v29, v29
	s_waitcnt vmcnt(6) lgkmcnt(0)
	v_mul_f32_e32 v50, v25, v25
	v_fmac_f32_e32 v49, v28, v28
	v_fmac_f32_e32 v50, v24, v24
	v_fmac_f32_e32 v49, v30, v30
	v_fmac_f32_e32 v50, v26, v26
	v_fmac_f32_e32 v49, v31, v31
	v_fmac_f32_e32 v50, v27, v27
	v_add_f32_e32 v49, v49, v50
	s_waitcnt vmcnt(5)
	v_mul_f32_e32 v50, v21, v21
	v_fmac_f32_e32 v50, v20, v20
	v_fmac_f32_e32 v50, v22, v22
	v_fmac_f32_e32 v50, v23, v23
	v_add_f32_e32 v49, v49, v50
	s_waitcnt vmcnt(4)
	v_mul_f32_e32 v50, v17, v17
	v_fmac_f32_e32 v50, v16, v16
	v_fmac_f32_e32 v50, v18, v18
	v_fmac_f32_e32 v50, v19, v19
	v_add_f32_e32 v49, v49, v50
	s_waitcnt vmcnt(3)
	v_mul_f32_e32 v50, v13, v13
	v_fmac_f32_e32 v50, v12, v12
	v_fmac_f32_e32 v50, v14, v14
	v_fmac_f32_e32 v50, v15, v15
	v_add_f32_e32 v49, v49, v50
	s_waitcnt vmcnt(2)
	v_mul_f32_e32 v50, v9, v9
	v_fmac_f32_e32 v50, v8, v8
	v_fmac_f32_e32 v50, v10, v10
	v_fmac_f32_e32 v50, v11, v11
	v_add_f32_e32 v49, v49, v50
	s_waitcnt vmcnt(1)
	v_mul_f32_e32 v50, v5, v5
	v_fmac_f32_e32 v50, v4, v4
	v_fmac_f32_e32 v50, v6, v6
	v_fmac_f32_e32 v50, v7, v7
	v_add_f32_e32 v49, v49, v50
	s_waitcnt vmcnt(0)
	v_mul_f32_e32 v50, v1, v1
	v_fmac_f32_e32 v50, v0, v0
	v_fmac_f32_e32 v50, v2, v2
	v_fmac_f32_e32 v50, v3, v3
	v_add_f32_e32 v49, v49, v50
	v_mbcnt_lo_u32_b32 v50, -1, 0
	v_mbcnt_hi_u32_b32 v50, -1, v50
	s_nop 0
	v_lshlrev_b32_e32 v50, 2, v50
	v_xor_b32_e32 v51, 0x80, v50
	ds_bpermute_b32 v51, v51, v49
	s_waitcnt lgkmcnt(0)
	v_add_f32_e32 v49, v49, v51
	v_xor_b32_e32 v51, 64, v50
	ds_bpermute_b32 v51, v51, v49
	s_waitcnt lgkmcnt(0)
	v_add_f32_e32 v49, v49, v51
	v_xor_b32_e32 v51, 32, v50
	ds_bpermute_b32 v51, v51, v49
	s_waitcnt lgkmcnt(0)
	v_add_f32_e32 v49, v49, v51
	v_xor_b32_e32 v51, 16, v50
	ds_bpermute_b32 v51, v51, v49
	s_waitcnt lgkmcnt(0)
	v_add_f32_e32 v49, v49, v51
	v_xor_b32_e32 v51, 8, v50
	ds_bpermute_b32 v51, v51, v49
	v_xor_b32_e32 v50, 4, v50
	s_waitcnt lgkmcnt(0)
	v_add_f32_e32 v49, v49, v51
	ds_bpermute_b32 v50, v50, v49
	s_cbranch_vccnz .LBB0_544
	s_ashr_i32 s2, s1, 31
	s_lshr_b32 s2, s2, 20
	s_add_i32 s2, s1, s2
	s_ashr_i32 s2, s2, 12
	s_cmpk_lt_i32 s1, 0x2000
	s_cselect_b32 s2, s2, 2
	s_mul_hi_i32 s3, s2, 0xc000
	s_mul_i32 s2, s2, 0xc000
	s_add_u32 s2, s52, s2
	s_addc_u32 s3, s53, s3
	v_lshl_add_u64 v[74:75], v[32:33], 2, s[2:3]
	s_mov_b32 s2, 0x9000
	v_add_co_u32_e32 v66, vcc, s2, v74
	s_movk_i32 s2, 0x7000
	s_nop 0
	v_addc_co_u32_e32 v67, vcc, 0, v75, vcc
	global_load_dwordx4 v[76:79], v[66:67], off offset:-4096
	global_load_dwordx4 v[80:83], v[34:35], off
	v_add_co_u32_e32 v68, vcc, s2, v74
	s_nop 1
	v_addc_co_u32_e32 v69, vcc, 0, v75, vcc
	global_load_dwordx4 v[84:87], v[68:69], off offset:-4096
	s_waitcnt lgkmcnt(0)
	v_add_f32_e32 v49, v49, v50
	v_fmamk_f32 v49, v49, 0x3a000000, v48
	s_mov_b32 s2, 0x800000
	v_mul_f32_e32 v50, 0x4b800000, v49
	v_cmp_gt_f32_e32 vcc, s2, v49
	s_mov_b64 s[2:3], 0x8000
	v_lshl_add_u64 v[88:89], v[74:75], 0, s[2:3]
	global_load_dwordx4 v[92:95], v[88:89], off offset:1024
	global_load_dwordx4 v[96:99], v[34:35], off offset:1024
	v_cndmask_b32_e32 v49, v49, v50, vcc
	v_rsq_f32_e32 v49, v49
	s_mov_b64 s[2:3], 0x6000
	s_nop 0
	v_lshl_add_u64 v[90:91], v[74:75], 0, s[2:3]
	global_load_dwordx4 v[100:103], v[90:91], off offset:1024
	global_load_dwordx4 v[104:107], v[88:89], off offset:2048
	global_load_dwordx4 v[108:111], v[34:35], off offset:2048
	global_load_dwordx4 v[112:115], v[90:91], off offset:2048
	global_load_dwordx4 v[116:119], v[88:89], off offset:3072
	global_load_dwordx4 v[120:123], v[34:35], off offset:3072
	global_load_dwordx4 v[124:127], v[90:91], off offset:3072
	global_load_dwordx4 v[128:131], v[66:67], off
	global_load_dwordx4 v[132:135], v[36:37], off
	global_load_dwordx4 v[136:139], v[68:69], off
	global_load_dwordx4 v[140:143], v[66:67], off offset:1024
	global_load_dwordx4 v[144:147], v[38:39], off
	global_load_dwordx4 v[148:151], v[68:69], off offset:1024
	global_load_dwordx4 v[152:155], v[66:67], off offset:2048
	global_load_dwordx4 v[156:159], v[40:41], off
	global_load_dwordx4 v[160:163], v[68:69], off offset:2048
	global_load_dwordx4 v[164:167], v[66:67], off offset:3072
	global_load_dwordx4 v[168:171], v[42:43], off
	global_load_dwordx4 v[172:175], v[68:69], off offset:3072
	v_mul_f32_e32 v50, 0x45800000, v49
	v_cndmask_b32_e32 v70, v49, v50, vcc
	v_pk_mul_f32 v[28:29], v[28:29], v[70:71] op_sel_hi:[1,0]
	v_pk_mul_f32 v[30:31], v[30:31], v[70:71] op_sel_hi:[1,0]
	v_pk_mul_f32 v[24:25], v[24:25], v[70:71] op_sel_hi:[1,0]
	v_pk_mul_f32 v[26:27], v[26:27], v[70:71] op_sel_hi:[1,0]
	v_pk_mul_f32 v[20:21], v[20:21], v[70:71] op_sel_hi:[1,0]
	v_pk_mul_f32 v[22:23], v[22:23], v[70:71] op_sel_hi:[1,0]
	v_pk_mul_f32 v[16:17], v[16:17], v[70:71] op_sel_hi:[1,0]
	v_pk_mul_f32 v[18:19], v[18:19], v[70:71] op_sel_hi:[1,0]
	v_pk_mul_f32 v[12:13], v[12:13], v[70:71] op_sel_hi:[1,0]
	v_pk_mul_f32 v[14:15], v[14:15], v[70:71] op_sel_hi:[1,0]
	v_pk_mul_f32 v[8:9], v[8:9], v[70:71] op_sel_hi:[1,0]
	v_pk_mul_f32 v[10:11], v[10:11], v[70:71] op_sel_hi:[1,0]
	v_pk_mul_f32 v[4:5], v[4:5], v[70:71] op_sel_hi:[1,0]
	v_pk_mul_f32 v[6:7], v[6:7], v[70:71] op_sel_hi:[1,0]
	v_pk_mul_f32 v[0:1], v[0:1], v[70:71] op_sel_hi:[1,0]
	v_pk_mul_f32 v[2:3], v[2:3], v[70:71] op_sel_hi:[1,0]
	s_waitcnt vmcnt(24)
	s_waitcnt vmcnt(23)
	v_pk_add_f32 v[50:51], v[76:77], 1.0 op_sel_hi:[1,0]
	s_waitcnt vmcnt(22)
	v_pk_mul_f32 v[28:29], v[28:29], v[80:81]
	v_pk_mul_f32 v[30:31], v[30:31], v[82:83]
	v_pk_add_f32 v[52:53], v[78:79], 1.0 op_sel_hi:[1,0]
	s_waitcnt vmcnt(21)
	v_pk_fma_f32 v[28:29], v[50:51], v[28:29], v[84:85]
	v_pk_fma_f32 v[30:31], v[52:53], v[30:31], v[86:87]
	v_cvt_pk_bf16_f32 v28, v28, v29
	v_cvt_pk_bf16_f32 v29, v30, v31
	global_store_dwordx2 v[46:47], v[28:29], off offset:-2048
	s_waitcnt vmcnt(21)
	s_nop 0
	v_pk_add_f32 v[28:29], v[92:93], 1.0 op_sel_hi:[1,0]
	s_waitcnt vmcnt(20)
	v_pk_mul_f32 v[24:25], v[24:25], v[96:97]
	v_pk_add_f32 v[30:31], v[94:95], 1.0 op_sel_hi:[1,0]
	v_pk_mul_f32 v[26:27], v[26:27], v[98:99]
	s_waitcnt vmcnt(19)
	v_pk_fma_f32 v[24:25], v[28:29], v[24:25], v[100:101]
	v_pk_fma_f32 v[26:27], v[30:31], v[26:27], v[102:103]
	v_cvt_pk_bf16_f32 v24, v24, v25
	v_cvt_pk_bf16_f32 v25, v26, v27
	global_store_dwordx2 v[46:47], v[24:25], off offset:-1536
	s_waitcnt vmcnt(19)
	s_nop 0
	v_pk_add_f32 v[24:25], v[104:105], 1.0 op_sel_hi:[1,0]
	s_waitcnt vmcnt(18)
	v_pk_mul_f32 v[20:21], v[20:21], v[108:109]
	v_pk_add_f32 v[26:27], v[106:107], 1.0 op_sel_hi:[1,0]
	v_pk_mul_f32 v[22:23], v[22:23], v[110:111]
	s_waitcnt vmcnt(17)
	v_pk_fma_f32 v[20:21], v[24:25], v[20:21], v[112:113]
	v_pk_fma_f32 v[22:23], v[26:27], v[22:23], v[114:115]
	v_cvt_pk_bf16_f32 v20, v20, v21
	v_cvt_pk_bf16_f32 v21, v22, v23
	global_store_dwordx2 v[46:47], v[20:21], off offset:-1024
	s_waitcnt vmcnt(17)
	s_nop 0
	v_pk_add_f32 v[20:21], v[116:117], 1.0 op_sel_hi:[1,0]
	s_waitcnt vmcnt(16)
	v_pk_mul_f32 v[16:17], v[16:17], v[120:121]
	v_pk_add_f32 v[22:23], v[118:119], 1.0 op_sel_hi:[1,0]
	v_pk_mul_f32 v[18:19], v[18:19], v[122:123]
	s_waitcnt vmcnt(15)
	v_pk_fma_f32 v[16:17], v[20:21], v[16:17], v[124:125]
	v_pk_fma_f32 v[18:19], v[22:23], v[18:19], v[126:127]
	v_cvt_pk_bf16_f32 v16, v16, v17
	v_cvt_pk_bf16_f32 v17, v18, v19
	global_store_dwordx2 v[46:47], v[16:17], off offset:-512
	s_waitcnt vmcnt(15)
	s_nop 0
	v_pk_add_f32 v[16:17], v[128:129], 1.0 op_sel_hi:[1,0]
	s_waitcnt vmcnt(14)
	v_pk_mul_f32 v[12:13], v[12:13], v[132:133]
	v_pk_add_f32 v[18:19], v[130:131], 1.0 op_sel_hi:[1,0]
	v_pk_mul_f32 v[14:15], v[14:15], v[134:135]
	s_waitcnt vmcnt(13)
	v_pk_fma_f32 v[12:13], v[16:17], v[12:13], v[136:137]
	v_pk_fma_f32 v[14:15], v[18:19], v[14:15], v[138:139]
	v_cvt_pk_bf16_f32 v12, v12, v13
	v_cvt_pk_bf16_f32 v13, v14, v15
	global_store_dwordx2 v[46:47], v[12:13], off
	s_waitcnt vmcnt(13)
	s_nop 0
	v_pk_add_f32 v[12:13], v[140:141], 1.0 op_sel_hi:[1,0]
	s_waitcnt vmcnt(12)
	v_pk_mul_f32 v[8:9], v[8:9], v[144:145]
	v_pk_add_f32 v[14:15], v[142:143], 1.0 op_sel_hi:[1,0]
	v_pk_mul_f32 v[10:11], v[10:11], v[146:147]
	s_waitcnt vmcnt(11)
	v_pk_fma_f32 v[8:9], v[12:13], v[8:9], v[148:149]
	v_pk_fma_f32 v[10:11], v[14:15], v[10:11], v[150:151]
	v_cvt_pk_bf16_f32 v8, v8, v9
	v_cvt_pk_bf16_f32 v9, v10, v11
	global_store_dwordx2 v[46:47], v[8:9], off offset:512
	s_waitcnt vmcnt(11)
	s_nop 0
	v_pk_add_f32 v[8:9], v[152:153], 1.0 op_sel_hi:[1,0]
	s_waitcnt vmcnt(10)
	v_pk_mul_f32 v[4:5], v[4:5], v[156:157]
	v_pk_add_f32 v[10:11], v[154:155], 1.0 op_sel_hi:[1,0]
	v_pk_mul_f32 v[6:7], v[6:7], v[158:159]
	s_waitcnt vmcnt(9)
	v_pk_fma_f32 v[4:5], v[8:9], v[4:5], v[160:161]
	v_pk_fma_f32 v[6:7], v[10:11], v[6:7], v[162:163]
	v_cvt_pk_bf16_f32 v4, v4, v5
	v_cvt_pk_bf16_f32 v5, v6, v7
	global_store_dwordx2 v[46:47], v[4:5], off offset:1024
	s_waitcnt vmcnt(9)
	s_nop 0
	v_pk_add_f32 v[4:5], v[164:165], 1.0 op_sel_hi:[1,0]
	s_waitcnt vmcnt(8)
	v_pk_mul_f32 v[0:1], v[0:1], v[168:169]
	v_pk_add_f32 v[6:7], v[166:167], 1.0 op_sel_hi:[1,0]
	v_pk_mul_f32 v[2:3], v[2:3], v[170:171]
	s_waitcnt vmcnt(7)
	v_pk_fma_f32 v[0:1], v[4:5], v[0:1], v[172:173]
	v_pk_fma_f32 v[2:3], v[6:7], v[2:3], v[174:175]
	v_cvt_pk_bf16_f32 v0, v0, v1
	v_cvt_pk_bf16_f32 v1, v2, v3
	global_store_dwordx2 v[46:47], v[0:1], off offset:1536
	s_branch .LBB0_544

.LBB0_758:
	global_load_dwordx4 v[28:31], v[80:81], off offset:-4096
	global_load_dwordx4 v[24:27], v[80:81], off offset:-3072
	global_load_dwordx4 v[20:23], v[80:81], off offset:-2048
	global_load_dwordx4 v[16:19], v[80:81], off offset:-1024
	global_load_dwordx4 v[12:15], v[80:81], off
	global_load_dwordx4 v[8:11], v[80:81], off offset:1024
	global_load_dwordx4 v[4:7], v[80:81], off offset:2048
	global_load_dwordx4 v[0:3], v[80:81], off offset:3072
	s_cmpk_lt_i32 s2, 0x2000
	s_cbranch_scc1 .LBB0_760
	s_add_i32 s12, s2, 0xffffe000
	s_lshl_b64 s[4:5], s[12:13], 13
	v_lshl_add_u64 v[180:181], v[58:59], 0, s[4:5]
	global_load_dwordx4 v[184:187], v[180:181], off
	v_add_co_u32_e32 v32, vcc, 0x400000, v180
	s_nop 1
	v_addc_co_u32_e32 v33, vcc, 0, v181, vcc
	global_load_dwordx4 v[188:191], v[32:33], off
	v_add_co_u32_e32 v34, vcc, 0x800000, v180
	s_waitcnt lgkmcnt(0)
	s_nop 0
	v_addc_co_u32_e32 v35, vcc, 0, v181, vcc
	global_load_dwordx4 v[192:195], v[34:35], off
	v_add_co_u32_e32 v36, vcc, 0xc00000, v180
	s_nop 1
	v_addc_co_u32_e32 v37, vcc, 0, v181, vcc
	global_load_dwordx4 v[196:199], v[36:37], off
	v_add_co_u32_e32 v38, vcc, 0x1000000, v180
	s_nop 1
	v_addc_co_u32_e32 v39, vcc, 0, v181, vcc
	global_load_dwordx4 v[200:203], v[38:39], off
	v_add_co_u32_e32 v40, vcc, 0x1400000, v180
	s_nop 1
	v_addc_co_u32_e32 v41, vcc, 0, v181, vcc
	global_load_dwordx4 v[204:207], v[40:41], off
	v_add_co_u32_e32 v42, vcc, 0x1800000, v180
	s_nop 1
	v_addc_co_u32_e32 v43, vcc, 0, v181, vcc
	global_load_dwordx4 v[208:211], v[42:43], off
	v_add_co_u32_e32 v44, vcc, 0x1c00000, v180
	s_nop 1
	v_addc_co_u32_e32 v45, vcc, 0, v181, vcc
	global_load_dwordx4 v[212:215], v[44:45], off
	v_add_co_u32_e32 v46, vcc, 0x2000000, v180
	s_nop 1
	v_addc_co_u32_e32 v47, vcc, 0, v181, vcc
	global_load_dwordx4 v[216:219], v[46:47], off
	v_add_co_u32_e32 v48, vcc, 0x2400000, v180
	s_nop 1
	v_addc_co_u32_e32 v49, vcc, 0, v181, vcc
	global_load_dwordx4 v[220:223], v[48:49], off
	v_add_co_u32_e32 v50, vcc, 0x2800000, v180
	s_nop 1
	v_addc_co_u32_e32 v51, vcc, 0, v181, vcc
	global_load_dwordx4 v[224:227], v[50:51], off
	global_load_dwordx4 v[228:231], v[60:61], off
	global_load_dwordx4 v[232:235], v[180:181], off offset:1024
	s_mov_b32 s3, 0x401000
	s_waitcnt vmcnt(13)
	s_waitcnt vmcnt(12)
	v_pk_add_f32 v[54:55], v[186:187], 0 op_sel_hi:[1,0]
	v_pk_add_f32 v[52:53], v[184:185], 0 op_sel_hi:[1,0]
	global_load_dwordx4 v[184:187], v[32:33], off offset:1024
	s_waitcnt vmcnt(12)
	v_pk_add_f32 v[54:55], v[54:55], v[190:191]
	v_pk_add_f32 v[52:53], v[52:53], v[188:189]
	global_load_dwordx4 v[188:191], v[34:35], off offset:1024
	s_waitcnt vmcnt(12)
	v_pk_add_f32 v[54:55], v[54:55], v[194:195]
	v_pk_add_f32 v[52:53], v[52:53], v[192:193]
	global_load_dwordx4 v[192:195], v[36:37], off offset:1024
	s_waitcnt vmcnt(12)
	v_pk_add_f32 v[54:55], v[54:55], v[198:199]
	v_pk_add_f32 v[52:53], v[52:53], v[196:197]
	global_load_dwordx4 v[196:199], v[38:39], off offset:1024
	s_waitcnt vmcnt(12)
	v_pk_add_f32 v[54:55], v[54:55], v[202:203]
	v_pk_add_f32 v[52:53], v[52:53], v[200:201]
	global_load_dwordx4 v[200:203], v[40:41], off offset:1024
	s_waitcnt vmcnt(12)
	v_pk_add_f32 v[54:55], v[54:55], v[206:207]
	v_pk_add_f32 v[52:53], v[52:53], v[204:205]
	global_load_dwordx4 v[204:207], v[42:43], off offset:1024
	s_waitcnt vmcnt(12)
	v_pk_add_f32 v[54:55], v[54:55], v[210:211]
	v_pk_add_f32 v[52:53], v[52:53], v[208:209]
	global_load_dwordx4 v[208:211], v[44:45], off offset:1024
	s_waitcnt vmcnt(12)
	v_pk_add_f32 v[54:55], v[54:55], v[214:215]
	v_pk_add_f32 v[52:53], v[52:53], v[212:213]
	global_load_dwordx4 v[212:215], v[46:47], off offset:1024
	s_waitcnt vmcnt(12)
	v_pk_add_f32 v[54:55], v[54:55], v[218:219]
	v_pk_add_f32 v[52:53], v[52:53], v[216:217]
	global_load_dwordx4 v[216:219], v[48:49], off offset:1024
	s_waitcnt vmcnt(12)
	v_pk_add_f32 v[54:55], v[54:55], v[222:223]
	v_pk_add_f32 v[52:53], v[52:53], v[220:221]
	global_load_dwordx4 v[220:223], v[50:51], off offset:1024
	s_waitcnt vmcnt(12)
	v_pk_add_f32 v[86:87], v[54:55], v[226:227]
	v_pk_add_f32 v[88:89], v[52:53], v[224:225]
	global_load_dwordx4 v[224:227], v[60:61], off offset:1024
	s_waitcnt vmcnt(12)
	v_pk_fma_f32 v[30:31], v[86:87], v[230:231], v[30:31]
	v_pk_fma_f32 v[28:29], v[88:89], v[228:229], v[28:29]
	global_load_dwordx4 v[228:231], v[180:181], off offset:2048
	global_store_dwordx4 v[80:81], v[28:31], off offset:-4096
	s_waitcnt vmcnt(13)
	v_pk_add_f32 v[54:55], v[234:235], 0 op_sel_hi:[1,0]
	v_pk_add_f32 v[52:53], v[232:233], 0 op_sel_hi:[1,0]
	global_load_dwordx4 v[232:235], v[32:33], off offset:2048
	s_waitcnt vmcnt(13)
	v_pk_add_f32 v[54:55], v[54:55], v[186:187]
	v_pk_add_f32 v[52:53], v[52:53], v[184:185]
	global_load_dwordx4 v[184:187], v[34:35], off offset:2048
	s_waitcnt vmcnt(13)
	v_pk_add_f32 v[54:55], v[54:55], v[190:191]
	v_pk_add_f32 v[52:53], v[52:53], v[188:189]
	global_load_dwordx4 v[188:191], v[36:37], off offset:2048
	s_waitcnt vmcnt(13)
	v_pk_add_f32 v[54:55], v[54:55], v[194:195]
	v_pk_add_f32 v[52:53], v[52:53], v[192:193]
	global_load_dwordx4 v[192:195], v[38:39], off offset:2048
	s_waitcnt vmcnt(13)
	v_pk_add_f32 v[54:55], v[54:55], v[198:199]
	v_pk_add_f32 v[52:53], v[52:53], v[196:197]
	global_load_dwordx4 v[196:199], v[40:41], off offset:2048
	s_waitcnt vmcnt(13)
	v_pk_add_f32 v[54:55], v[54:55], v[202:203]
	v_pk_add_f32 v[52:53], v[52:53], v[200:201]
	global_load_dwordx4 v[200:203], v[42:43], off offset:2048
	s_waitcnt vmcnt(13)
	v_pk_add_f32 v[54:55], v[54:55], v[206:207]
	v_pk_add_f32 v[52:53], v[52:53], v[204:205]
	global_load_dwordx4 v[204:207], v[44:45], off offset:2048
	s_waitcnt vmcnt(13)
	v_pk_add_f32 v[54:55], v[54:55], v[210:211]
	v_pk_add_f32 v[52:53], v[52:53], v[208:209]
	global_load_dwordx4 v[208:211], v[46:47], off offset:2048
	s_waitcnt vmcnt(13)
	v_pk_add_f32 v[54:55], v[54:55], v[214:215]
	v_pk_add_f32 v[52:53], v[52:53], v[212:213]
	global_load_dwordx4 v[212:215], v[48:49], off offset:2048
	s_waitcnt vmcnt(13)
	v_pk_add_f32 v[54:55], v[54:55], v[218:219]
	v_pk_add_f32 v[52:53], v[52:53], v[216:217]
	global_load_dwordx4 v[216:219], v[50:51], off offset:2048
	s_waitcnt vmcnt(13)
	v_pk_add_f32 v[86:87], v[54:55], v[222:223]
	v_pk_add_f32 v[88:89], v[52:53], v[220:221]
	global_load_dwordx4 v[220:223], v[60:61], off offset:2048
	s_waitcnt vmcnt(13)
	v_pk_fma_f32 v[26:27], v[86:87], v[226:227], v[26:27]
	v_pk_fma_f32 v[24:25], v[88:89], v[224:225], v[24:25]
	global_load_dwordx4 v[224:227], v[180:181], off offset:3072
	global_store_dwordx4 v[80:81], v[24:27], off offset:-3072
	s_waitcnt vmcnt(14)
	v_pk_add_f32 v[54:55], v[230:231], 0 op_sel_hi:[1,0]
	v_pk_add_f32 v[52:53], v[228:229], 0 op_sel_hi:[1,0]
	global_load_dwordx4 v[228:231], v[32:33], off offset:3072
	s_waitcnt vmcnt(13)
	v_pk_add_f32 v[54:55], v[54:55], v[234:235]
	v_pk_add_f32 v[52:53], v[52:53], v[232:233]
	s_waitcnt vmcnt(12)
	v_pk_add_f32 v[54:55], v[54:55], v[186:187]
	v_pk_add_f32 v[52:53], v[52:53], v[184:185]
	s_waitcnt vmcnt(11)
	v_pk_add_f32 v[54:55], v[54:55], v[190:191]
	v_pk_add_f32 v[52:53], v[52:53], v[188:189]
	s_waitcnt vmcnt(10)
	v_pk_add_f32 v[54:55], v[54:55], v[194:195]
	v_pk_add_f32 v[52:53], v[52:53], v[192:193]
	s_waitcnt vmcnt(9)
	v_pk_add_f32 v[54:55], v[54:55], v[198:199]
	v_pk_add_f32 v[52:53], v[52:53], v[196:197]
	s_waitcnt vmcnt(8)
	v_pk_add_f32 v[54:55], v[54:55], v[202:203]
	v_pk_add_f32 v[52:53], v[52:53], v[200:201]
	s_waitcnt vmcnt(7)
	v_pk_add_f32 v[54:55], v[54:55], v[206:207]
	v_pk_add_f32 v[52:53], v[52:53], v[204:205]
	s_waitcnt vmcnt(6)
	v_pk_add_f32 v[54:55], v[54:55], v[210:211]
	v_pk_add_f32 v[52:53], v[52:53], v[208:209]
	s_waitcnt vmcnt(5)
	v_pk_add_f32 v[54:55], v[54:55], v[214:215]
	v_pk_add_f32 v[52:53], v[52:53], v[212:213]
	s_waitcnt vmcnt(4)
	v_pk_add_f32 v[86:87], v[54:55], v[218:219]
	v_pk_add_f32 v[88:89], v[52:53], v[216:217]
	s_waitcnt vmcnt(3)
	v_pk_fma_f32 v[22:23], v[86:87], v[222:223], v[22:23]
	v_pk_fma_f32 v[20:21], v[88:89], v[220:221], v[20:21]
	global_store_dwordx4 v[80:81], v[20:23], off offset:-2048
	global_load_dwordx4 v[32:35], v[34:35], off offset:3072
	s_nop 0
	global_load_dwordx4 v[184:187], v[36:37], off offset:3072
	global_load_dwordx4 v[36:39], v[38:39], off offset:3072
	s_nop 0
	global_load_dwordx4 v[188:191], v[40:41], off offset:3072
	global_load_dwordx4 v[40:43], v[42:43], off offset:3072
	s_nop 0
	global_load_dwordx4 v[192:195], v[44:45], off offset:3072
	global_load_dwordx4 v[44:47], v[46:47], off offset:3072
	s_nop 0
	global_load_dwordx4 v[196:199], v[48:49], off offset:3072
	global_load_dwordx4 v[48:51], v[50:51], off offset:3072
	s_nop 0
	global_load_dwordx4 v[200:203], v[60:61], off offset:3072
	s_waitcnt vmcnt(13)
	v_pk_add_f32 v[54:55], v[226:227], 0 op_sel_hi:[1,0]
	v_pk_add_f32 v[52:53], v[224:225], 0 op_sel_hi:[1,0]
	s_waitcnt vmcnt(11)
	v_pk_add_f32 v[54:55], v[54:55], v[230:231]
	v_pk_add_f32 v[52:53], v[52:53], v[228:229]
	s_waitcnt vmcnt(9)
	v_pk_add_f32 v[34:35], v[54:55], v[34:35]
	v_pk_add_f32 v[32:33], v[52:53], v[32:33]
	s_waitcnt vmcnt(8)
	v_pk_add_f32 v[34:35], v[34:35], v[186:187]
	v_pk_add_f32 v[32:33], v[32:33], v[184:185]
	s_waitcnt vmcnt(7)
	v_pk_add_f32 v[34:35], v[34:35], v[38:39]
	v_pk_add_f32 v[32:33], v[32:33], v[36:37]
	s_waitcnt vmcnt(6)
	v_pk_add_f32 v[34:35], v[34:35], v[190:191]
	v_pk_add_f32 v[32:33], v[32:33], v[188:189]
	s_waitcnt vmcnt(5)
	v_pk_add_f32 v[34:35], v[34:35], v[42:43]
	v_pk_add_f32 v[32:33], v[32:33], v[40:41]
	s_waitcnt vmcnt(4)
	v_pk_add_f32 v[34:35], v[34:35], v[194:195]
	v_pk_add_f32 v[32:33], v[32:33], v[192:193]
	s_waitcnt vmcnt(3)
	v_pk_add_f32 v[34:35], v[34:35], v[46:47]
	v_pk_add_f32 v[32:33], v[32:33], v[44:45]
	s_waitcnt vmcnt(2)
	v_pk_add_f32 v[34:35], v[34:35], v[198:199]
	v_pk_add_f32 v[32:33], v[32:33], v[196:197]
	s_waitcnt vmcnt(1)
	v_pk_add_f32 v[36:37], v[34:35], v[50:51]
	v_pk_add_f32 v[38:39], v[32:33], v[48:49]
	v_add_co_u32_e32 v86, vcc, s1, v180
	s_waitcnt vmcnt(0)
	v_pk_fma_f32 v[18:19], v[36:37], v[202:203], v[18:19]
	v_addc_co_u32_e32 v87, vcc, 0, v181, vcc
	global_load_dwordx4 v[184:187], v[86:87], off
	v_add_co_u32_e32 v88, vcc, s3, v180
	s_mov_b32 s3, 0x801000
	s_nop 0
	v_addc_co_u32_e32 v89, vcc, 0, v181, vcc
	global_load_dwordx4 v[188:191], v[88:89], off
	v_add_co_u32_e32 v90, vcc, s3, v180
	s_mov_b32 s3, 0xc01000
	s_nop 0
	v_addc_co_u32_e32 v91, vcc, 0, v181, vcc
	global_load_dwordx4 v[192:195], v[90:91], off
	v_add_co_u32_e32 v92, vcc, s3, v180
	s_mov_b32 s3, 0x1001000
	s_nop 0
	v_addc_co_u32_e32 v93, vcc, 0, v181, vcc
	global_load_dwordx4 v[196:199], v[92:93], off
	v_add_co_u32_e32 v94, vcc, s3, v180
	s_mov_b32 s3, 0x1401000
	s_nop 0
	v_addc_co_u32_e32 v95, vcc, 0, v181, vcc
	global_load_dwordx4 v[204:207], v[94:95], off
	v_pk_fma_f32 v[16:17], v[38:39], v[200:201], v[16:17]
	v_add_co_u32_e32 v96, vcc, s3, v180
	global_store_dwordx4 v[80:81], v[16:19], off offset:-1024
	s_nop 0
	v_addc_co_u32_e32 v97, vcc, 0, v181, vcc
	global_load_dwordx4 v[200:203], v[96:97], off
	s_mov_b32 s3, 0x1801000
	s_nop 0
	v_add_co_u32_e32 v98, vcc, s3, v180
	s_nop 1
	v_addc_co_u32_e32 v99, vcc, 0, v181, vcc
	global_load_dwordx4 v[208:211], v[98:99], off
	s_mov_b32 s3, 0x1c01000
	v_add_co_u32_e32 v100, vcc, s3, v180
	s_nop 1
	v_addc_co_u32_e32 v101, vcc, 0, v181, vcc
	global_load_dwordx4 v[212:215], v[100:101], off
	s_mov_b32 s3, 0x2001000
	v_add_co_u32_e32 v102, vcc, s3, v180
	s_nop 1
	v_addc_co_u32_e32 v103, vcc, 0, v181, vcc
	global_load_dwordx4 v[216:219], v[102:103], off
	s_mov_b32 s3, 0x2401000
	v_add_co_u32_e32 v104, vcc, s3, v180
	s_nop 1
	v_addc_co_u32_e32 v105, vcc, 0, v181, vcc
	global_load_dwordx4 v[220:223], v[104:105], off
	s_mov_b32 s3, 0x2801000
	v_add_co_u32_e32 v84, vcc, s3, v180
	s_nop 1
	v_addc_co_u32_e32 v85, vcc, 0, v181, vcc
	global_load_dwordx4 v[180:183], v[84:85], off
	global_load_dwordx4 v[224:227], v[64:65], off
	global_load_dwordx4 v[228:231], v[86:87], off offset:1024
	global_load_dwordx4 v[232:235], v[88:89], off offset:1024
	s_waitcnt vmcnt(14)
	v_pk_add_f32 v[34:35], v[186:187], 0 op_sel_hi:[1,0]
	v_pk_add_f32 v[32:33], v[184:185], 0 op_sel_hi:[1,0]
	global_load_dwordx4 v[184:187], v[90:91], off offset:1024
	s_waitcnt vmcnt(14)
	v_pk_add_f32 v[34:35], v[34:35], v[190:191]
	v_pk_add_f32 v[32:33], v[32:33], v[188:189]
	global_load_dwordx4 v[188:191], v[92:93], off offset:1024
	s_waitcnt vmcnt(14)
	v_pk_add_f32 v[34:35], v[34:35], v[194:195]
	v_pk_add_f32 v[32:33], v[32:33], v[192:193]
	global_load_dwordx4 v[192:195], v[94:95], off offset:1024
	s_waitcnt vmcnt(14)
	v_pk_add_f32 v[34:35], v[34:35], v[198:199]
	v_pk_add_f32 v[32:33], v[32:33], v[196:197]
	global_load_dwordx4 v[196:199], v[96:97], off offset:1024
	s_waitcnt vmcnt(14)
	v_pk_add_f32 v[34:35], v[34:35], v[206:207]
	v_pk_add_f32 v[32:33], v[32:33], v[204:205]
	global_load_dwordx4 v[204:207], v[98:99], off offset:1024
	s_waitcnt vmcnt(13)
	v_pk_add_f32 v[34:35], v[34:35], v[202:203]
	v_pk_add_f32 v[32:33], v[32:33], v[200:201]
	global_load_dwordx4 v[200:203], v[100:101], off offset:1024
	s_waitcnt vmcnt(13)
	v_pk_add_f32 v[34:35], v[34:35], v[210:211]
	v_pk_add_f32 v[32:33], v[32:33], v[208:209]
	global_load_dwordx4 v[208:211], v[102:103], off offset:1024
	s_waitcnt vmcnt(13)
	v_pk_add_f32 v[34:35], v[34:35], v[214:215]
	v_pk_add_f32 v[32:33], v[32:33], v[212:213]
	global_load_dwordx4 v[212:215], v[104:105], off offset:1024
	s_waitcnt vmcnt(13)
	v_pk_add_f32 v[34:35], v[34:35], v[218:219]
	v_pk_add_f32 v[32:33], v[32:33], v[216:217]
	global_load_dwordx4 v[216:219], v[84:85], off offset:1024
	s_waitcnt vmcnt(13)
	v_pk_add_f32 v[34:35], v[34:35], v[222:223]
	v_pk_add_f32 v[32:33], v[32:33], v[220:221]
	global_load_dwordx4 v[220:223], v[66:67], off
	s_waitcnt vmcnt(13)
	v_pk_add_f32 v[36:37], v[34:35], v[182:183]
	v_pk_add_f32 v[38:39], v[32:33], v[180:181]
	global_load_dwordx4 v[180:183], v[86:87], off offset:2048
	s_waitcnt vmcnt(13)
	v_pk_fma_f32 v[14:15], v[36:37], v[226:227], v[14:15]
	v_pk_fma_f32 v[12:13], v[38:39], v[224:225], v[12:13]
	global_load_dwordx4 v[224:227], v[88:89], off offset:2048
	global_store_dwordx4 v[80:81], v[12:15], off
	s_waitcnt vmcnt(14)
	v_pk_add_f32 v[34:35], v[230:231], 0 op_sel_hi:[1,0]
	v_pk_add_f32 v[32:33], v[228:229], 0 op_sel_hi:[1,0]
	global_load_dwordx4 v[228:231], v[90:91], off offset:2048
	s_waitcnt vmcnt(14)
	v_pk_add_f32 v[34:35], v[34:35], v[234:235]
	v_pk_add_f32 v[32:33], v[32:33], v[232:233]
	global_load_dwordx4 v[232:235], v[92:93], off offset:2048
	s_waitcnt vmcnt(14)
	v_pk_add_f32 v[34:35], v[34:35], v[186:187]
	v_pk_add_f32 v[32:33], v[32:33], v[184:185]
	global_load_dwordx4 v[184:187], v[94:95], off offset:2048
	s_waitcnt vmcnt(14)
	v_pk_add_f32 v[34:35], v[34:35], v[190:191]
	v_pk_add_f32 v[32:33], v[32:33], v[188:189]
	global_load_dwordx4 v[188:191], v[96:97], off offset:2048
	s_waitcnt vmcnt(14)
	v_pk_add_f32 v[34:35], v[34:35], v[194:195]
	v_pk_add_f32 v[32:33], v[32:33], v[192:193]
	global_load_dwordx4 v[192:195], v[98:99], off offset:2048
	s_waitcnt vmcnt(14)
	v_pk_add_f32 v[34:35], v[34:35], v[198:199]
	v_pk_add_f32 v[32:33], v[32:33], v[196:197]
	global_load_dwordx4 v[196:199], v[100:101], off offset:2048
	s_waitcnt vmcnt(14)
	v_pk_add_f32 v[34:35], v[34:35], v[206:207]
	v_pk_add_f32 v[32:33], v[32:33], v[204:205]
	global_load_dwordx4 v[204:207], v[102:103], off offset:2048
	s_waitcnt vmcnt(14)
	v_pk_add_f32 v[34:35], v[34:35], v[202:203]
	v_pk_add_f32 v[32:33], v[32:33], v[200:201]
	global_load_dwordx4 v[200:203], v[104:105], off offset:2048
	s_waitcnt vmcnt(14)
	v_pk_add_f32 v[34:35], v[34:35], v[210:211]
	v_pk_add_f32 v[32:33], v[32:33], v[208:209]
	global_load_dwordx4 v[208:211], v[84:85], off offset:2048
	s_waitcnt vmcnt(14)
	v_pk_add_f32 v[34:35], v[34:35], v[214:215]
	v_pk_add_f32 v[32:33], v[32:33], v[212:213]
	global_load_dwordx4 v[212:215], v[68:69], off
	s_waitcnt vmcnt(14)
	v_pk_add_f32 v[36:37], v[34:35], v[218:219]
	v_pk_add_f32 v[38:39], v[32:33], v[216:217]
	global_load_dwordx4 v[216:219], v[86:87], off offset:3072
	s_waitcnt vmcnt(14)
	v_pk_fma_f32 v[10:11], v[36:37], v[222:223], v[10:11]
	v_pk_fma_f32 v[8:9], v[38:39], v[220:221], v[8:9]
	global_load_dwordx4 v[220:223], v[88:89], off offset:3072
	global_store_dwordx4 v[80:81], v[8:11], off offset:1024
	s_waitcnt vmcnt(15)
	v_pk_add_f32 v[34:35], v[182:183], 0 op_sel_hi:[1,0]
	v_pk_add_f32 v[32:33], v[180:181], 0 op_sel_hi:[1,0]
	global_load_dwordx4 v[180:183], v[90:91], off offset:3072
	s_waitcnt vmcnt(15)
	v_pk_add_f32 v[34:35], v[34:35], v[226:227]
	v_pk_add_f32 v[32:33], v[32:33], v[224:225]
	global_load_dwordx4 v[224:227], v[92:93], off offset:3072
	s_waitcnt vmcnt(14)
	v_pk_add_f32 v[34:35], v[34:35], v[230:231]
	v_pk_add_f32 v[32:33], v[32:33], v[228:229]
	global_load_dwordx4 v[228:231], v[94:95], off offset:3072
	s_waitcnt vmcnt(14)
	v_pk_add_f32 v[34:35], v[34:35], v[234:235]
	v_pk_add_f32 v[32:33], v[32:33], v[232:233]
	global_load_dwordx4 v[232:235], v[96:97], off offset:3072
	s_waitcnt vmcnt(14)
	v_pk_add_f32 v[34:35], v[34:35], v[186:187]
	v_pk_add_f32 v[32:33], v[32:33], v[184:185]
	global_load_dwordx4 v[184:187], v[98:99], off offset:3072
	s_waitcnt vmcnt(14)
	v_pk_add_f32 v[34:35], v[34:35], v[190:191]
	v_pk_add_f32 v[32:33], v[32:33], v[188:189]
	global_load_dwordx4 v[188:191], v[100:101], off offset:3072
	s_waitcnt vmcnt(14)
	v_pk_add_f32 v[34:35], v[34:35], v[194:195]
	v_pk_add_f32 v[32:33], v[32:33], v[192:193]
	global_load_dwordx4 v[192:195], v[102:103], off offset:3072
	s_waitcnt vmcnt(14)
	v_pk_add_f32 v[34:35], v[34:35], v[198:199]
	v_pk_add_f32 v[32:33], v[32:33], v[196:197]
	global_load_dwordx4 v[196:199], v[104:105], off offset:3072
	s_waitcnt vmcnt(14)
	v_pk_add_f32 v[34:35], v[34:35], v[206:207]
	v_pk_add_f32 v[32:33], v[32:33], v[204:205]
	global_load_dwordx4 v[204:207], v[84:85], off offset:3072
	s_waitcnt vmcnt(14)
	v_pk_add_f32 v[34:35], v[34:35], v[202:203]
	v_pk_add_f32 v[32:33], v[32:33], v[200:201]
	global_load_dwordx4 v[200:203], v[70:71], off
	s_waitcnt vmcnt(14)
	v_pk_add_f32 v[36:37], v[34:35], v[210:211]
	v_pk_add_f32 v[38:39], v[32:33], v[208:209]
	s_waitcnt vmcnt(13)
	v_pk_fma_f32 v[6:7], v[36:37], v[214:215], v[6:7]
	v_pk_fma_f32 v[4:5], v[38:39], v[212:213], v[4:5]
	global_store_dwordx4 v[80:81], v[4:7], off offset:2048
	s_waitcnt vmcnt(13)
	v_pk_add_f32 v[34:35], v[218:219], 0 op_sel_hi:[1,0]
	v_pk_add_f32 v[32:33], v[216:217], 0 op_sel_hi:[1,0]
	s_waitcnt vmcnt(12)
	v_pk_add_f32 v[34:35], v[34:35], v[222:223]
	v_pk_add_f32 v[32:33], v[32:33], v[220:221]
	s_waitcnt vmcnt(10)
	v_pk_add_f32 v[34:35], v[34:35], v[182:183]
	v_pk_add_f32 v[32:33], v[32:33], v[180:181]
	s_waitcnt vmcnt(9)
	v_pk_add_f32 v[34:35], v[34:35], v[226:227]
	v_pk_add_f32 v[32:33], v[32:33], v[224:225]
	s_waitcnt vmcnt(8)
	v_pk_add_f32 v[34:35], v[34:35], v[230:231]
	v_pk_add_f32 v[32:33], v[32:33], v[228:229]
	s_waitcnt vmcnt(7)
	v_pk_add_f32 v[34:35], v[34:35], v[234:235]
	v_pk_add_f32 v[32:33], v[32:33], v[232:233]
	s_waitcnt vmcnt(6)
	v_pk_add_f32 v[34:35], v[34:35], v[186:187]
	v_pk_add_f32 v[32:33], v[32:33], v[184:185]
	s_waitcnt vmcnt(5)
	v_pk_add_f32 v[34:35], v[34:35], v[190:191]
	v_pk_add_f32 v[32:33], v[32:33], v[188:189]
	s_waitcnt vmcnt(4)
	v_pk_add_f32 v[34:35], v[34:35], v[194:195]
	v_pk_add_f32 v[32:33], v[32:33], v[192:193]
	s_waitcnt vmcnt(3)
	v_pk_add_f32 v[34:35], v[34:35], v[198:199]
	v_pk_add_f32 v[32:33], v[32:33], v[196:197]
	s_waitcnt vmcnt(2)
	v_pk_add_f32 v[36:37], v[34:35], v[206:207]
	v_pk_add_f32 v[38:39], v[32:33], v[204:205]
	s_waitcnt vmcnt(1)
	v_pk_fma_f32 v[2:3], v[36:37], v[202:203], v[2:3]
	v_pk_fma_f32 v[0:1], v[38:39], v[200:201], v[0:1]
	global_store_dwordx4 v[80:81], v[0:3], off offset:3072
.LBB0_760:
	s_waitcnt vmcnt(7)
	v_mul_f32_e32 v32, v29, v29
	s_waitcnt vmcnt(6)
	v_mul_f32_e32 v33, v25, v25
	v_fmac_f32_e32 v32, v28, v28
	v_fmac_f32_e32 v33, v24, v24
	v_fmac_f32_e32 v32, v30, v30
	v_fmac_f32_e32 v33, v26, v26
	v_fmac_f32_e32 v32, v31, v31
	v_fmac_f32_e32 v33, v27, v27
	v_add_f32_e32 v32, v32, v33
	s_waitcnt vmcnt(5)
	v_mul_f32_e32 v33, v21, v21
	v_fmac_f32_e32 v33, v20, v20
	v_fmac_f32_e32 v33, v22, v22
	v_fmac_f32_e32 v33, v23, v23
	v_add_f32_e32 v32, v33, v32
	s_waitcnt vmcnt(4)
	v_mul_f32_e32 v33, v17, v17
	v_fmac_f32_e32 v33, v16, v16
	v_fmac_f32_e32 v33, v18, v18
	v_fmac_f32_e32 v33, v19, v19
	v_add_f32_e32 v32, v33, v32
	s_waitcnt vmcnt(3)
	v_mul_f32_e32 v33, v13, v13
	v_fmac_f32_e32 v33, v12, v12
	v_fmac_f32_e32 v33, v14, v14
	v_fmac_f32_e32 v33, v15, v15
	v_add_f32_e32 v32, v33, v32
	s_waitcnt vmcnt(2)
	v_mul_f32_e32 v33, v9, v9
	v_fmac_f32_e32 v33, v8, v8
	v_fmac_f32_e32 v33, v10, v10
	v_fmac_f32_e32 v33, v11, v11
	v_add_f32_e32 v32, v33, v32
	s_waitcnt vmcnt(1)
	v_mul_f32_e32 v33, v5, v5
	v_fmac_f32_e32 v33, v4, v4
	v_fmac_f32_e32 v33, v6, v6
	v_fmac_f32_e32 v33, v7, v7
	v_add_f32_e32 v32, v33, v32
	s_waitcnt vmcnt(0)
	v_mul_f32_e32 v33, v1, v1
	v_fmac_f32_e32 v33, v0, v0
	v_fmac_f32_e32 v33, v2, v2
	v_fmac_f32_e32 v33, v3, v3
	v_add_f32_e32 v32, v33, v32
	v_mbcnt_lo_u32_b32 v33, -1, 0
	v_mbcnt_hi_u32_b32 v33, -1, v33
	s_andn2_b64 vcc, exec, s[6:7]
	v_lshlrev_b32_e32 v33, 2, v33
	s_nop 1
	v_xor_b32_e32 v107, 4, v33
	v_xor_b32_e32 v34, 0x80, v33
	ds_bpermute_b32 v34, v34, v32
	s_waitcnt lgkmcnt(0)
	v_add_f32_e32 v32, v32, v34
	v_xor_b32_e32 v34, 64, v33
	ds_bpermute_b32 v34, v34, v32
	s_waitcnt lgkmcnt(0)
	v_add_f32_e32 v32, v32, v34
	v_xor_b32_e32 v34, 32, v33
	ds_bpermute_b32 v34, v34, v32
	s_waitcnt lgkmcnt(0)
	v_add_f32_e32 v32, v32, v34
	v_xor_b32_e32 v34, 16, v33
	ds_bpermute_b32 v34, v34, v32
	s_waitcnt lgkmcnt(0)
	v_add_f32_e32 v32, v32, v34
	v_xor_b32_e32 v34, 8, v33
	ds_bpermute_b32 v34, v34, v32
	s_waitcnt lgkmcnt(0)
	v_add_f32_e32 v34, v32, v34
	ds_bpermute_b32 v35, v107, v34
	s_cbranch_vccnz .LBB0_757
	s_ashr_i32 s3, s2, 31
	s_lshr_b32 s3, s3, 20
	s_add_i32 s3, s2, s3
	s_ashr_i32 s3, s3, 12
	s_cmpk_lt_i32 s2, 0x2000
	s_cselect_b32 s3, s3, 2
	s_mul_hi_i32 s5, s3, 0xc000
	s_mul_i32 s3, s3, 0xc000
	s_add_u32 s4, s14, s3
	s_addc_u32 s5, s15, s5
	v_lshl_add_u64 v[180:181], v[56:57], 2, s[4:5]
	global_load_dwordx4 v[184:187], v[62:63], off
	s_movk_i32 s3, 0x3000
	v_add_co_u32_e32 v32, vcc, s3, v180
	s_nop 1
	v_addc_co_u32_e32 v33, vcc, 0, v181, vcc
	global_load_dwordx4 v[188:191], v[32:33], off offset:-4096
	global_load_dwordx4 v[192:195], v[180:181], off
	s_waitcnt lgkmcnt(0)
	v_add_f32_e32 v34, v34, v35
	v_fmamk_f32 v34, v34, 0x3a000000, v106
	s_mov_b32 s3, 0x800000
	v_mul_f32_e32 v35, 0x4b800000, v34
	v_cmp_gt_f32_e32 vcc, s3, v34
	s_mov_b64 s[4:5], 0x2000
	v_lshl_add_u64 v[182:183], v[180:181], 0, s[4:5]
	global_load_dwordx4 v[196:199], v[182:183], off offset:1024
	global_load_dwordx4 v[200:203], v[62:63], off offset:1024
	global_load_dwordx4 v[204:207], v[180:181], off offset:1024
	global_load_dwordx4 v[208:211], v[182:183], off offset:2048
	global_load_dwordx4 v[212:215], v[62:63], off offset:2048
	global_load_dwordx4 v[216:219], v[180:181], off offset:2048
	global_load_dwordx4 v[220:223], v[182:183], off offset:3072
	global_load_dwordx4 v[224:227], v[62:63], off offset:3072
	global_load_dwordx4 v[228:231], v[180:181], off offset:3072
	global_load_dwordx4 v[232:235], v[32:33], off
	v_cndmask_b32_e32 v34, v34, v35, vcc
	v_rsq_f32_e32 v34, v34
	s_nop 0
	v_mul_f32_e32 v35, 0x45800000, v34
	v_cndmask_b32_e32 v34, v34, v35, vcc
	v_pk_mul_f32 v[28:29], v[28:29], v[34:35] op_sel_hi:[1,0]
	v_pk_mul_f32 v[30:31], v[30:31], v[34:35] op_sel_hi:[1,0]
	v_pk_mul_f32 v[24:25], v[24:25], v[34:35] op_sel_hi:[1,0]
	v_pk_mul_f32 v[26:27], v[26:27], v[34:35] op_sel_hi:[1,0]
	v_pk_mul_f32 v[20:21], v[20:21], v[34:35] op_sel_hi:[1,0]
	v_pk_mul_f32 v[22:23], v[22:23], v[34:35] op_sel_hi:[1,0]
	v_pk_mul_f32 v[16:17], v[16:17], v[34:35] op_sel_hi:[1,0]
	v_pk_mul_f32 v[18:19], v[18:19], v[34:35] op_sel_hi:[1,0]
	v_pk_mul_f32 v[12:13], v[12:13], v[34:35] op_sel_hi:[1,0]
	v_pk_mul_f32 v[14:15], v[14:15], v[34:35] op_sel_hi:[1,0]
	v_pk_mul_f32 v[8:9], v[8:9], v[34:35] op_sel_hi:[1,0]
	v_pk_mul_f32 v[10:11], v[10:11], v[34:35] op_sel_hi:[1,0]
	v_pk_mul_f32 v[4:5], v[4:5], v[34:35] op_sel_hi:[1,0]
	v_pk_mul_f32 v[6:7], v[6:7], v[34:35] op_sel_hi:[1,0]
	v_pk_mul_f32 v[0:1], v[0:1], v[34:35] op_sel_hi:[1,0]
	v_pk_mul_f32 v[2:3], v[2:3], v[34:35] op_sel_hi:[1,0]
	s_waitcnt vmcnt(13)
	s_waitcnt vmcnt(12)
	v_pk_mul_f32 v[28:29], v[28:29], v[184:185]
	v_pk_mul_f32 v[30:31], v[30:31], v[186:187]
	global_load_dwordx4 v[184:187], v[72:73], off
	s_waitcnt vmcnt(12)
	v_pk_add_f32 v[36:37], v[188:189], 1.0 op_sel_hi:[1,0]
	v_pk_add_f32 v[38:39], v[190:191], 1.0 op_sel_hi:[1,0]
	s_waitcnt vmcnt(11)
	v_pk_fma_f32 v[28:29], v[36:37], v[28:29], v[192:193]
	v_pk_fma_f32 v[30:31], v[38:39], v[30:31], v[194:195]
	v_cvt_pk_bf16_f32 v28, v28, v29
	v_cvt_pk_bf16_f32 v29, v30, v31
	global_store_dwordx2 v[82:83], v[28:29], off offset:-2048
	s_waitcnt vmcnt(11)
	s_nop 0
	v_pk_add_f32 v[28:29], v[196:197], 1.0 op_sel_hi:[1,0]
	s_waitcnt vmcnt(10)
	v_pk_mul_f32 v[24:25], v[24:25], v[200:201]
	v_pk_add_f32 v[30:31], v[198:199], 1.0 op_sel_hi:[1,0]
	v_pk_mul_f32 v[26:27], v[26:27], v[202:203]
	s_waitcnt vmcnt(9)
	v_pk_fma_f32 v[24:25], v[28:29], v[24:25], v[204:205]
	v_pk_fma_f32 v[26:27], v[30:31], v[26:27], v[206:207]
	v_cvt_pk_bf16_f32 v24, v24, v25
	v_cvt_pk_bf16_f32 v25, v26, v27
	global_store_dwordx2 v[82:83], v[24:25], off offset:-1536
	s_waitcnt vmcnt(9)
	s_nop 0
	v_pk_add_f32 v[24:25], v[208:209], 1.0 op_sel_hi:[1,0]
	s_waitcnt vmcnt(8)
	v_pk_mul_f32 v[20:21], v[20:21], v[212:213]
	v_pk_add_f32 v[26:27], v[210:211], 1.0 op_sel_hi:[1,0]
	v_pk_mul_f32 v[22:23], v[22:23], v[214:215]
	s_waitcnt vmcnt(7)
	v_pk_fma_f32 v[20:21], v[24:25], v[20:21], v[216:217]
	v_pk_fma_f32 v[22:23], v[26:27], v[22:23], v[218:219]
	v_cvt_pk_bf16_f32 v20, v20, v21
	v_cvt_pk_bf16_f32 v21, v22, v23
	global_store_dwordx2 v[82:83], v[20:21], off offset:-1024
	s_waitcnt vmcnt(7)
	s_nop 0
	v_pk_add_f32 v[20:21], v[220:221], 1.0 op_sel_hi:[1,0]
	s_waitcnt vmcnt(6)
	v_pk_mul_f32 v[16:17], v[16:17], v[224:225]
	v_pk_add_f32 v[22:23], v[222:223], 1.0 op_sel_hi:[1,0]
	v_pk_mul_f32 v[18:19], v[18:19], v[226:227]
	s_waitcnt vmcnt(5)
	v_pk_fma_f32 v[16:17], v[20:21], v[16:17], v[228:229]
	v_pk_fma_f32 v[18:19], v[22:23], v[18:19], v[230:231]
	v_cvt_pk_bf16_f32 v16, v16, v17
	v_cvt_pk_bf16_f32 v17, v18, v19
	global_store_dwordx2 v[82:83], v[16:17], off offset:-512
	v_add_co_u32_e32 v28, vcc, s1, v180
	s_nop 1
	v_addc_co_u32_e32 v29, vcc, 0, v181, vcc
	global_load_dwordx4 v[180:183], v[28:29], off
	global_load_dwordx4 v[188:191], v[32:33], off offset:1024
	global_load_dwordx4 v[192:195], v[74:75], off
	global_load_dwordx4 v[196:199], v[28:29], off offset:1024
	global_load_dwordx4 v[200:203], v[32:33], off offset:2048
	global_load_dwordx4 v[204:207], v[76:77], off
	global_load_dwordx4 v[208:211], v[28:29], off offset:2048
	global_load_dwordx4 v[212:215], v[32:33], off offset:3072
	global_load_dwordx4 v[216:219], v[78:79], off
	global_load_dwordx4 v[220:223], v[28:29], off offset:3072
	s_waitcnt vmcnt(15)
	v_pk_add_f32 v[16:17], v[232:233], 1.0 op_sel_hi:[1,0]
	s_waitcnt vmcnt(14)
	v_pk_mul_f32 v[12:13], v[12:13], v[184:185]
	v_pk_add_f32 v[18:19], v[234:235], 1.0 op_sel_hi:[1,0]
	v_pk_mul_f32 v[14:15], v[14:15], v[186:187]
	s_waitcnt vmcnt(9)
	v_pk_fma_f32 v[12:13], v[16:17], v[12:13], v[180:181]
	v_pk_fma_f32 v[14:15], v[18:19], v[14:15], v[182:183]
	v_cvt_pk_bf16_f32 v12, v12, v13
	v_cvt_pk_bf16_f32 v13, v14, v15
	global_store_dwordx2 v[82:83], v[12:13], off
	s_waitcnt vmcnt(9)
	s_nop 0
	v_pk_add_f32 v[12:13], v[188:189], 1.0 op_sel_hi:[1,0]
	s_waitcnt vmcnt(8)
	v_pk_mul_f32 v[8:9], v[8:9], v[192:193]
	v_pk_add_f32 v[14:15], v[190:191], 1.0 op_sel_hi:[1,0]
	v_pk_mul_f32 v[10:11], v[10:11], v[194:195]
	s_waitcnt vmcnt(7)
	v_pk_fma_f32 v[8:9], v[12:13], v[8:9], v[196:197]
	v_pk_fma_f32 v[10:11], v[14:15], v[10:11], v[198:199]
	v_cvt_pk_bf16_f32 v8, v8, v9
	v_cvt_pk_bf16_f32 v9, v10, v11
	global_store_dwordx2 v[82:83], v[8:9], off offset:512
	s_waitcnt vmcnt(7)
	s_nop 0
	v_pk_add_f32 v[8:9], v[200:201], 1.0 op_sel_hi:[1,0]
	s_waitcnt vmcnt(6)
	v_pk_mul_f32 v[4:5], v[4:5], v[204:205]
	v_pk_add_f32 v[10:11], v[202:203], 1.0 op_sel_hi:[1,0]
	v_pk_mul_f32 v[6:7], v[6:7], v[206:207]
	s_waitcnt vmcnt(5)
	v_pk_fma_f32 v[4:5], v[8:9], v[4:5], v[208:209]
	v_pk_fma_f32 v[6:7], v[10:11], v[6:7], v[210:211]
	v_cvt_pk_bf16_f32 v4, v4, v5
	v_cvt_pk_bf16_f32 v5, v6, v7
	global_store_dwordx2 v[82:83], v[4:5], off offset:1024
	s_waitcnt vmcnt(5)
	s_nop 0
	v_pk_add_f32 v[4:5], v[212:213], 1.0 op_sel_hi:[1,0]
	s_waitcnt vmcnt(4)
	v_pk_mul_f32 v[0:1], v[0:1], v[216:217]
	v_pk_add_f32 v[6:7], v[214:215], 1.0 op_sel_hi:[1,0]
	v_pk_mul_f32 v[2:3], v[2:3], v[218:219]
	s_waitcnt vmcnt(3)
	v_pk_fma_f32 v[0:1], v[4:5], v[0:1], v[220:221]
	v_pk_fma_f32 v[2:3], v[6:7], v[2:3], v[222:223]
	v_cvt_pk_bf16_f32 v0, v0, v1
	v_cvt_pk_bf16_f32 v1, v2, v3
	global_store_dwordx2 v[82:83], v[0:1], off offset:1536
	s_branch .LBB0_757

.LBB0_765:
	s_add_i32 s3, s4, s33
	s_cmpk_gt_i32 s3, 0x17f
	s_cselect_b64 s[6:7], -1, 0
	v_add_u32_e32 v66, v89, v90
	s_and_b64 vcc, exec, s[6:7]
	s_barrier
	s_waitcnt vmcnt(15)
	ds_write_b128 v66, v[0:3]
	s_waitcnt vmcnt(14)
	ds_write_b128 v66, v[4:7] offset:8256
	s_waitcnt vmcnt(13)
	ds_write_b128 v66, v[8:11] offset:16512
	s_waitcnt vmcnt(12)
	ds_write_b128 v66, v[12:15] offset:24768
	s_waitcnt vmcnt(11)
	ds_write_b128 v66, v[16:19] offset:33024
	s_waitcnt vmcnt(10)
	ds_write_b128 v66, v[20:23] offset:41280
	s_waitcnt vmcnt(9)
	ds_write_b128 v93, v[24:27]
	s_waitcnt vmcnt(8)
	ds_write_b128 v93, v[28:31] offset:8256
	s_waitcnt vmcnt(7)
	ds_write_b128 v93, v[32:35] offset:16512
	s_waitcnt vmcnt(6)
	ds_write_b128 v93, v[36:39] offset:24768
	s_waitcnt vmcnt(5)
	ds_write_b128 v93, v[40:43] offset:33024
	s_waitcnt vmcnt(4)
	ds_write_b128 v93, v[44:47] offset:41280
	s_waitcnt vmcnt(3)
	ds_write_b128 v93, v[48:51] offset:49536
	s_waitcnt vmcnt(2)
	ds_write_b128 v93, v[52:55] offset:57792
	s_waitcnt vmcnt(1)
	ds_write_b128 v94, v[56:59] offset:57792
	s_waitcnt vmcnt(0)
	ds_write_b128 v95, v[60:63] offset:57792
	s_waitcnt lgkmcnt(0)
	s_barrier
	s_cbranch_vccnz .LBB0_767
	s_mul_hi_i32 s5, s3, 0x2aaaaaab
	s_lshr_b32 s8, s5, 31
	s_ashr_i32 s5, s5, 1
	s_add_i32 s5, s5, s8
	s_lshl_b32 s10, s5, 6
	s_mul_i32 s5, s5, 12
	s_sub_i32 s5, s3, s5
	v_lshl_or_b32 v0, s5, 9, v73
	v_cmp_gt_i32_e32 vcc, s2, v0
	v_readlane_b32 s12, v240, 49
	v_readlane_b32 s22, v240, 59
	v_cndmask_b32_e32 v0, 0, v0, vcc
	v_readlane_b32 s23, v240, 60
	v_ashrrev_i32_e32 v1, 31, v0
	v_add_u32_e32 v2, s10, v72
	v_mov_b64_e32 v[56:57], s[22:23]
	v_mad_i64_i32 v[2:3], s[8:9], v2, s1, v[56:57]
	v_lshlrev_b64 v[58:59], 2, v[0:1]
	v_lshl_add_u64 v[0:1], v[2:3], 0, v[58:59]
	v_add_u32_e32 v2, s10, v74
	v_add_u32_e32 v8, s10, v75
	v_add_u32_e32 v10, s10, v76
	v_add_u32_e32 v16, s10, v77
	v_add_u32_e32 v18, s10, v78
	v_add_u32_e32 v24, s10, v79
	v_add_u32_e32 v26, s10, v80
	v_add_u32_e32 v32, s10, v81
	v_add_u32_e32 v34, s10, v82
	v_add_u32_e32 v40, s10, v83
	v_add_u32_e32 v42, s10, v84
	v_add_u32_e32 v48, s10, v85
	v_add_u32_e32 v50, s10, v86
	v_add_u32_e32 v60, s10, v87
	v_add_u32_e32 v62, s10, v88
	v_mad_i64_i32 v[2:3], s[8:9], v2, s1, v[56:57]
	v_mad_i64_i32 v[8:9], s[8:9], v8, s1, v[56:57]
	v_mad_i64_i32 v[10:11], s[8:9], v10, s1, v[56:57]
	v_mad_i64_i32 v[16:17], s[8:9], v16, s1, v[56:57]
	v_mad_i64_i32 v[18:19], s[8:9], v18, s1, v[56:57]
	v_mad_i64_i32 v[24:25], s[8:9], v24, s1, v[56:57]
	v_mad_i64_i32 v[26:27], s[8:9], v26, s1, v[56:57]
	v_mad_i64_i32 v[32:33], s[8:9], v32, s1, v[56:57]
	v_mad_i64_i32 v[34:35], s[8:9], v34, s1, v[56:57]
	v_mad_i64_i32 v[40:41], s[8:9], v40, s1, v[56:57]
	v_mad_i64_i32 v[42:43], s[8:9], v42, s1, v[56:57]
	v_mad_i64_i32 v[48:49], s[8:9], v48, s1, v[56:57]
	v_mad_i64_i32 v[50:51], s[8:9], v50, s1, v[56:57]
	v_mad_i64_i32 v[60:61], s[8:9], v60, s1, v[56:57]
	v_mad_i64_i32 v[56:57], s[8:9], v62, s1, v[56:57]
	v_lshl_add_u64 v[4:5], v[2:3], 0, v[58:59]
	v_lshl_add_u64 v[8:9], v[8:9], 0, v[58:59]
	v_lshl_add_u64 v[12:13], v[10:11], 0, v[58:59]
	v_lshl_add_u64 v[16:17], v[16:17], 0, v[58:59]
	v_lshl_add_u64 v[20:21], v[18:19], 0, v[58:59]
	v_lshl_add_u64 v[24:25], v[24:25], 0, v[58:59]
	v_lshl_add_u64 v[28:29], v[26:27], 0, v[58:59]
	v_lshl_add_u64 v[32:33], v[32:33], 0, v[58:59]
	v_lshl_add_u64 v[36:37], v[34:35], 0, v[58:59]
	v_lshl_add_u64 v[40:41], v[40:41], 0, v[58:59]
	v_lshl_add_u64 v[44:45], v[42:43], 0, v[58:59]
	v_lshl_add_u64 v[48:49], v[48:49], 0, v[58:59]
	v_lshl_add_u64 v[52:53], v[50:51], 0, v[58:59]
	v_lshl_add_u64 v[60:61], v[60:61], 0, v[58:59]
	v_lshl_add_u64 v[62:63], v[56:57], 0, v[58:59]
	global_load_dwordx4 v[0:3], v[0:1], off
	s_nop 0
	global_load_dwordx4 v[4:7], v[4:5], off
	s_nop 0
	global_load_dwordx4 v[8:11], v[8:9], off
	s_nop 0
	global_load_dwordx4 v[12:15], v[12:13], off
	s_nop 0
	global_load_dwordx4 v[16:19], v[16:17], off
	s_nop 0
	global_load_dwordx4 v[20:23], v[20:21], off
	s_nop 0
	global_load_dwordx4 v[24:27], v[24:25], off
	s_nop 0
	global_load_dwordx4 v[28:31], v[28:29], off
	s_nop 0
	global_load_dwordx4 v[32:35], v[32:33], off
	s_nop 0
	global_load_dwordx4 v[36:39], v[36:37], off
	s_nop 0
	global_load_dwordx4 v[40:43], v[40:41], off
	s_nop 0
	global_load_dwordx4 v[44:47], v[44:45], off
	s_nop 0
	global_load_dwordx4 v[48:51], v[48:49], off
	s_nop 0
	global_load_dwordx4 v[52:55], v[52:53], off
	s_nop 0
	global_load_dwordx4 v[56:59], v[60:61], off
	global_load_dwordx4 v[60:63], v[62:63], off
	v_readlane_b32 s13, v240, 50
	v_readlane_b32 s14, v240, 51
	v_readlane_b32 s15, v240, 52
	v_readlane_b32 s16, v240, 53
	v_readlane_b32 s17, v240, 54
	v_readlane_b32 s18, v240, 55
	v_readlane_b32 s19, v240, 56
	v_readlane_b32 s20, v240, 57
	v_readlane_b32 s21, v240, 58
	v_readlane_b32 s24, v240, 61
	v_readlane_b32 s25, v240, 62
	v_readlane_b32 s26, v240, 63
	v_readlane_b32 s27, v239, 0

.LBB0_814:
	v_ashrrev_i32_e32 v9, 31, v1
	v_mov_b32_e32 v8, v1
	v_ashrrev_i32_e32 v11, 31, v0
	v_mov_b32_e32 v10, v0
	v_lshl_add_u64 v[10:11], v[10:11], 2, s[18:19]
	global_load_dword v107, v[10:11], off
	v_lshl_add_u64 v[8:9], v[8:9], 2, s[18:19]
	global_load_dword v8, v[8:9], off
	v_add_u32_e32 v10, 0x400, v1
	v_ashrrev_i32_e32 v11, 31, v10
	v_lshl_add_u64 v[10:11], v[10:11], 2, s[18:19]
	v_add_u32_e32 v6, -8, v6
	s_add_i32 s1, s1, 16
	v_cmp_eq_u32_e32 vcc, 0, v6
	s_or_b64 s[12:13], vcc, s[12:13]
	s_waitcnt vmcnt(0)
	ds_write2st64_b32 v7, v107, v8 offset1:8
	v_add_u32_e32 v8, 0x400, v0
	v_ashrrev_i32_e32 v9, 31, v8
	v_lshl_add_u64 v[8:9], v[8:9], 2, s[18:19]
	global_load_dword v107, v[8:9], off
	global_load_dword v162, v[10:11], off
	v_add_u32_e32 v10, 0x800, v1
	v_ashrrev_i32_e32 v11, 31, v10
	v_lshl_add_u64 v[10:11], v[10:11], 2, s[18:19]
	s_waitcnt vmcnt(0)
	ds_write2st64_b32 v7, v107, v162 offset0:16 offset1:24
	v_add_u32_e32 v8, 0x800, v0
	v_ashrrev_i32_e32 v9, 31, v8
	v_lshl_add_u64 v[8:9], v[8:9], 2, s[18:19]
	global_load_dword v107, v[8:9], off
	global_load_dword v162, v[10:11], off
	v_add_u32_e32 v10, 0xc00, v1
	v_ashrrev_i32_e32 v11, 31, v10
	v_lshl_add_u64 v[10:11], v[10:11], 2, s[18:19]
	s_waitcnt vmcnt(0)
	ds_write2st64_b32 v7, v107, v162 offset0:32 offset1:40
	v_add_u32_e32 v8, 0xc00, v0
	v_ashrrev_i32_e32 v9, 31, v8
	v_lshl_add_u64 v[8:9], v[8:9], 2, s[18:19]
	global_load_dword v107, v[8:9], off
	global_load_dword v162, v[10:11], off
	v_add_u32_e32 v10, 0x1000, v1
	v_ashrrev_i32_e32 v11, 31, v10
	v_lshl_add_u64 v[10:11], v[10:11], 2, s[18:19]
	s_waitcnt vmcnt(0)
	ds_write2st64_b32 v7, v107, v162 offset0:48 offset1:56
	v_add_u32_e32 v8, 0x1000, v0
	v_ashrrev_i32_e32 v9, 31, v8
	v_lshl_add_u64 v[8:9], v[8:9], 2, s[18:19]
	global_load_dword v107, v[8:9], off
	global_load_dword v162, v[10:11], off
	v_add_u32_e32 v10, 0x1400, v1
	v_ashrrev_i32_e32 v11, 31, v10
	v_lshl_add_u64 v[10:11], v[10:11], 2, s[18:19]
	s_waitcnt vmcnt(0)
	ds_write2st64_b32 v7, v107, v162 offset0:64 offset1:72
	v_add_u32_e32 v8, 0x1400, v0
	v_ashrrev_i32_e32 v9, 31, v8
	v_lshl_add_u64 v[8:9], v[8:9], 2, s[18:19]
	global_load_dword v107, v[8:9], off
	global_load_dword v162, v[10:11], off
	v_add_u32_e32 v10, 0x1800, v1
	v_ashrrev_i32_e32 v11, 31, v10
	v_lshl_add_u64 v[10:11], v[10:11], 2, s[18:19]
	s_waitcnt vmcnt(0)
	ds_write2st64_b32 v7, v107, v162 offset0:80 offset1:88
	v_add_u32_e32 v8, 0x1800, v0
	v_ashrrev_i32_e32 v9, 31, v8
	v_lshl_add_u64 v[8:9], v[8:9], 2, s[18:19]
	global_load_dword v107, v[8:9], off
	global_load_dword v162, v[10:11], off
	v_add_u32_e32 v10, 0x1c00, v1
	v_ashrrev_i32_e32 v11, 31, v10
	v_lshl_add_u64 v[10:11], v[10:11], 2, s[18:19]
	v_add_u32_e32 v1, 0x2000, v1
	s_waitcnt vmcnt(0)
	ds_write2st64_b32 v7, v107, v162 offset0:96 offset1:104
	v_add_u32_e32 v8, 0x1c00, v0
	v_ashrrev_i32_e32 v9, 31, v8
	v_lshl_add_u64 v[8:9], v[8:9], 2, s[18:19]
	global_load_dword v107, v[8:9], off
	global_load_dword v162, v[10:11], off
	v_add_u32_e32 v0, 0x2000, v0
	s_waitcnt vmcnt(0)
	ds_write2st64_b32 v7, v107, v162 offset0:112 offset1:120
	v_add_u32_e32 v7, 0x8000, v7
	v_mov_b32_e32 v8, s1
	s_andn2_b64 exec, exec, s[12:13]
	s_cbranch_execnz .LBB0_814
	s_or_b64 exec, exec, s[12:13]

.LBB0_827:
	v_ashrrev_i32_e32 v11, 31, v0
	v_mov_b32_e32 v10, v0
	v_ashrrev_i32_e32 v9, 31, v1
	v_mov_b32_e32 v8, v1
	v_lshlrev_b64 v[10:11], 2, v[10:11]
	s_nop 0
	v_lshl_add_u64 v[180:181], s[22:23], 0, v[10:11]
	s_waitcnt vmcnt(12)
	v_lshlrev_b64 v[8:9], 2, v[8:9]
	v_lshl_add_u64 v[182:183], s[22:23], 0, v[8:9]
	global_load_dword v107, v[180:181], off
	global_load_dword v162, v[182:183], off
	v_lshl_add_u64 v[10:11], s[26:27], 0, v[10:11]
	global_load_dword v180, v[10:11], off
	v_lshl_add_u64 v[8:9], s[26:27], 0, v[8:9]
	v_add_u32_e32 v6, -4, v6
	s_waitcnt vmcnt(14)
	v_add_u32_e32 v16, 0x4000, v7
	s_add_i32 s1, s1, 8
	v_cmp_eq_u32_e32 vcc, 0, v6
	s_or_b64 s[12:13], vcc, s[12:13]
	s_waitcnt vmcnt(3)
	s_waitcnt vmcnt(1)
	ds_write2st64_b32 v7, v107, v162 offset1:8
	global_load_dword v8, v[8:9], off
	v_add_u32_e32 v10, 0x400, v1
	v_ashrrev_i32_e32 v11, 31, v10
	v_lshlrev_b64 v[10:11], 2, v[10:11]
	v_lshl_add_u64 v[182:183], s[22:23], 0, v[10:11]
	v_lshl_add_u64 v[10:11], s[26:27], 0, v[10:11]
	s_waitcnt vmcnt(0)
	ds_write2st64_b32 v7, v180, v8 offset0:64 offset1:72
	v_add_u32_e32 v8, 0x400, v0
	v_ashrrev_i32_e32 v9, 31, v8
	v_lshlrev_b64 v[8:9], 2, v[8:9]
	v_lshl_add_u64 v[180:181], s[22:23], 0, v[8:9]
	global_load_dword v107, v[180:181], off
	global_load_dword v162, v[182:183], off
	v_lshl_add_u64 v[8:9], s[26:27], 0, v[8:9]
	global_load_dword v180, v[8:9], off
	global_load_dword v181, v[10:11], off
	s_waitcnt vmcnt(2)
	ds_write2st64_b32 v7, v107, v162 offset0:16 offset1:24
	v_add_u32_e32 v10, 0x800, v1
	v_ashrrev_i32_e32 v11, 31, v10
	v_lshlrev_b64 v[10:11], 2, v[10:11]
	v_lshl_add_u64 v[182:183], s[22:23], 0, v[10:11]
	v_lshl_add_u64 v[10:11], s[26:27], 0, v[10:11]
	s_waitcnt vmcnt(0)
	ds_write2st64_b32 v7, v180, v181 offset0:80 offset1:88
	v_add_u32_e32 v8, 0x800, v0
	v_ashrrev_i32_e32 v9, 31, v8
	v_lshlrev_b64 v[8:9], 2, v[8:9]
	v_lshl_add_u64 v[180:181], s[22:23], 0, v[8:9]
	global_load_dword v107, v[180:181], off
	global_load_dword v162, v[182:183], off
	v_lshl_add_u64 v[8:9], s[26:27], 0, v[8:9]
	global_load_dword v180, v[8:9], off
	global_load_dword v181, v[10:11], off
	s_waitcnt vmcnt(2)
	ds_write2st64_b32 v7, v107, v162 offset0:32 offset1:40
	v_add_u32_e32 v10, 0xc00, v1
	v_ashrrev_i32_e32 v11, 31, v10
	v_lshlrev_b64 v[10:11], 2, v[10:11]
	v_lshl_add_u64 v[182:183], s[22:23], 0, v[10:11]
	v_lshl_add_u64 v[10:11], s[26:27], 0, v[10:11]
	v_add_u32_e32 v1, 0x1000, v1
	s_waitcnt vmcnt(0)
	ds_write2st64_b32 v7, v180, v181 offset0:96 offset1:104
	v_add_u32_e32 v8, 0xc00, v0
	v_ashrrev_i32_e32 v9, 31, v8
	v_lshlrev_b64 v[8:9], 2, v[8:9]
	v_lshl_add_u64 v[180:181], s[22:23], 0, v[8:9]
	global_load_dword v107, v[180:181], off
	global_load_dword v162, v[182:183], off
	v_lshl_add_u64 v[8:9], s[26:27], 0, v[8:9]
	global_load_dword v180, v[8:9], off
	global_load_dword v181, v[10:11], off
	v_add_u32_e32 v0, 0x1000, v0
	s_waitcnt vmcnt(2)
	ds_write2st64_b32 v7, v107, v162 offset0:48 offset1:56
	s_waitcnt vmcnt(0)
	ds_write2st64_b32 v7, v180, v181 offset0:112 offset1:120
	v_mov_b32_e32 v8, s1
	v_mov_b32_e32 v7, v16
	s_andn2_b64 exec, exec, s[12:13]
	s_cbranch_execnz .LBB0_827
	s_or_b64 exec, exec, s[12:13]

.LBB0_831:
	v_ashrrev_i32_e32 v9, 31, v0
	v_mov_b32_e32 v8, v0
	v_ashrrev_i32_e32 v7, 31, v1
	v_mov_b32_e32 v6, v1
	v_lshlrev_b64 v[8:9], 2, v[8:9]
	v_lshl_add_u64 v[10:11], s[18:19], 0, v[8:9]
	v_lshlrev_b64 v[6:7], 2, v[6:7]
	s_nop 0
	v_lshl_add_u64 v[180:181], s[18:19], 0, v[6:7]
	s_waitcnt vmcnt(12)
	global_load_dword v10, v[10:11], off
	s_nop 0
	global_load_dword v107, v[180:181], off
	v_lshl_add_u64 v[8:9], s[22:23], 0, v[8:9]
	v_lshl_add_u64 v[6:7], s[22:23], 0, v[6:7]
	v_add_u32_e32 v3, -1, v3
	v_cmp_eq_u32_e32 vcc, 0, v3
	v_add_u32_e32 v1, 0x400, v1
	v_add_u32_e32 v0, 0x400, v0
	s_or_b64 s[12:13], vcc, s[12:13]
	s_waitcnt vmcnt(1)
	s_waitcnt vmcnt(0)
	ds_write2st64_b32 v5, v10, v107 offset1:8
	global_load_dword v8, v[8:9], off
	s_nop 0
	global_load_dword v6, v[6:7], off
	s_waitcnt vmcnt(0)
	ds_write2st64_b32 v5, v8, v6 offset0:64 offset1:72
	v_add_u32_e32 v5, 0x1000, v5
	s_andn2_b64 exec, exec, s[12:13]
	s_cbranch_execnz .LBB0_831

.LBB0_839:
	global_load_dword v15, v[2:3], off
	global_load_dword v18, v[4:5], off
	ds_read_b32 v21, v27 offset:4096
	v_add_u32_e32 v14, s1, v26
	s_movk_i32 s6, 0x1000
	v_cmp_gt_i32_e32 vcc, s6, v14
	v_add_u32_e32 v0, 0xfffff000, v14
	s_nop 0
	v_cndmask_b32_e32 v0, v0, v14, vcc
	v_cndmask_b32_e32 v22, v30, v31, vcc
	v_cvt_f64_i32_e32 v[16:17], v0
	v_mul_f64 v[24:25], v[6:7], v[16:17]
	v_cvt_f64_u32_e32 v[38:39], v22
	s_waitcnt vmcnt(7)
	v_div_scale_f64 v[40:41], s[6:7], v[38:39], v[38:39], v[24:25]
	v_rcp_f64_e32 v[42:43], v[40:41]
	s_waitcnt vmcnt(6)
	v_fma_f64 v[44:45], -v[40:41], v[42:43], 1.0
	v_fmac_f64_e32 v[42:43], v[42:43], v[44:45]
	v_fma_f64 v[44:45], -v[40:41], v[42:43], 1.0
	v_fmac_f64_e32 v[42:43], v[42:43], v[44:45]
	v_div_scale_f64 v[44:45], vcc, v[24:25], v[38:39], v[24:25]
	v_mul_f64 v[46:47], v[44:45], v[42:43]
	v_fma_f64 v[40:41], -v[40:41], v[46:47], v[44:45]
	s_nop 1
	v_div_fmas_f64 v[40:41], v[40:41], v[42:43], v[46:47]
	v_div_fixup_f64 v[24:25], v[40:41], v[38:39], v[24:25]
	v_floor_f64_e32 v[38:39], v[24:25]
	v_add_f64 v[24:25], v[24:25], -v[38:39]
	v_mul_f64 v[24:25], v[24:25], s[12:13]
	v_cvt_f32_f64_e32 v19, v[24:25]
	v_and_b32_e32 v20, 0x7fffffff, v19
	v_lshrrev_b32_e32 v0, 23, v20
	v_and_b32_e32 v23, 0x7fffff, v20
	v_cmp_nlt_f32_e64 s[18:19], |v19|, s2
	v_add_u32_e32 v37, 0xffffff88, v0
	v_or_b32_e32 v25, 0x800000, v23
	s_and_saveexec_b64 s[6:7], s[18:19]
	s_xor_b64 s[20:21], exec, s[6:7]
	s_cbranch_execz .LBB0_841
	v_cmp_lt_u32_e32 vcc, 63, v37
	v_mad_u64_u32 v[38:39], s[10:11], v25, s3, 0
	s_nop 0
	v_cndmask_b32_e32 v0, 0, v34, vcc
	v_add_u32_e32 v0, v0, v37
	v_cmp_lt_u32_e64 s[6:7], 31, v0
	s_nop 1
	v_cndmask_b32_e64 v23, 0, v35, s[6:7]
	v_add_u32_e32 v0, v23, v0
	v_cmp_lt_u32_e64 s[8:9], 31, v0
	s_nop 1
	v_cndmask_b32_e64 v23, 0, v35, s[8:9]
	v_add_u32_e32 v23, v23, v0
	v_mov_b32_e32 v0, v39
	v_mad_u64_u32 v[40:41], s[10:11], v25, s4, v[0:1]
	v_mov_b32_e32 v0, v41
	v_mad_u64_u32 v[42:43], s[10:11], v25, s5, v[0:1]
	v_mov_b32_e32 v0, v43
	v_mad_u64_u32 v[44:45], s[10:11], v25, s22, v[0:1]
	v_mov_b32_e32 v0, v45
	v_mad_u64_u32 v[46:47], s[10:11], v25, s23, v[0:1]
	v_mov_b32_e32 v0, v47
	s_waitcnt vmcnt(5)
	v_mad_u64_u32 v[48:49], s[10:11], v25, s24, v[0:1]
	v_mov_b32_e32 v0, v49
	v_mad_u64_u32 v[50:51], s[10:11], v25, s25, v[0:1]
	v_cndmask_b32_e32 v24, v48, v44, vcc
	v_cndmask_b32_e32 v0, v50, v46, vcc
	v_cndmask_b32_e32 v41, v51, v48, vcc
	v_cndmask_b32_e64 v39, v0, v24, s[6:7]
	v_cndmask_b32_e64 v0, v41, v0, s[6:7]
	v_cndmask_b32_e32 v41, v46, v42, vcc
	v_cndmask_b32_e64 v24, v24, v41, s[6:7]
	v_sub_u32_e32 v43, 32, v23
	v_cmp_eq_u32_e64 s[10:11], 0, v23
	v_cndmask_b32_e32 v23, v44, v40, vcc
	v_cndmask_b32_e64 v0, v0, v39, s[8:9]
	v_cndmask_b32_e64 v39, v39, v24, s[8:9]
	v_cndmask_b32_e64 v40, v41, v23, s[6:7]
	v_alignbit_b32 v45, v0, v39, v43
	v_cndmask_b32_e64 v24, v24, v40, s[8:9]
	v_cndmask_b32_e32 v38, v42, v38, vcc
	v_cndmask_b32_e64 v0, v45, v0, s[10:11]
	v_alignbit_b32 v41, v39, v24, v43
	v_cndmask_b32_e64 v23, v23, v38, s[6:7]
	v_cndmask_b32_e64 v39, v41, v39, s[10:11]
	v_bfe_u32 v45, v0, 29, 1
	v_cndmask_b32_e64 v23, v40, v23, s[8:9]
	v_alignbit_b32 v41, v0, v39, 30
	v_sub_u32_e32 v46, 0, v45
	v_alignbit_b32 v38, v24, v23, v43
	v_xor_b32_e32 v41, v41, v46
	v_cndmask_b32_e64 v24, v38, v24, s[10:11]
	v_alignbit_b32 v38, v39, v24, 30
	v_ffbh_u32_e32 v39, v41
	v_min_u32_e32 v39, 32, v39
	v_alignbit_b32 v23, v24, v23, 30
	v_xor_b32_e32 v38, v38, v46
	v_sub_u32_e32 v40, 31, v39
	v_xor_b32_e32 v23, v23, v46
	v_alignbit_b32 v41, v41, v38, v40
	v_alignbit_b32 v23, v38, v23, v40
	v_alignbit_b32 v24, v41, v23, 9
	v_ffbh_u32_e32 v38, v24
	v_min_u32_e32 v38, 32, v38
	v_lshrrev_b32_e32 v44, 29, v0
	v_not_b32_e32 v40, v38
	v_alignbit_b32 v23, v24, v23, v40
	v_lshlrev_b32_e32 v24, 31, v44
	v_or_b32_e32 v40, 0x33000000, v24
	v_add_lshl_u32 v38, v38, v39, 23
	v_lshrrev_b32_e32 v23, 9, v23
	v_sub_u32_e32 v38, v40, v38
	v_or_b32_e32 v24, 0.5, v24
	v_lshlrev_b32_e32 v39, 23, v39
	v_or_b32_e32 v23, v38, v23
	v_lshrrev_b32_e32 v38, 9, v41
	v_sub_u32_e32 v24, v24, v39
	v_or_b32_e32 v24, v38, v24
	v_mul_f32_e32 v38, 0x3fc90fda, v24
	v_fma_f32 v39, v24, s26, -v38
	v_fmac_f32_e32 v39, 0x33a22168, v24
	v_fmac_f32_e32 v39, 0x3fc90fda, v23
	v_lshrrev_b32_e32 v0, 30, v0
	v_add_f32_e32 v24, v38, v39
	v_add_u32_e32 v23, v45, v0

.LBB0_847:
	s_or_b64 exec, exec, s[6:7]
	s_nop 4
	ds_read2st64_b32 v[180:181], v27 offset0:17 offset1:18
	ds_read2st64_b32 v[182:183], v27 offset0:19 offset1:20
	ds_read2st64_b32 v[184:185], v27 offset0:21 offset1:22
	ds_read2st64_b32 v[186:187], v27 offset0:23 offset1:24
	ds_read2st64_b32 v[188:189], v27 offset0:33 offset1:34
	ds_read2st64_b32 v[190:191], v27 offset0:35 offset1:36
	ds_read2st64_b32 v[192:193], v27 offset0:37 offset1:38
	ds_read2st64_b32 v[194:195], v27 offset0:39 offset1:40
	ds_read2st64_b32 v[196:197], v27 offset0:25 offset1:26
	ds_read2st64_b32 v[198:199], v27 offset0:41 offset1:42
	ds_read2st64_b32 v[200:201], v27 offset0:27 offset1:28
	ds_read2st64_b32 v[202:203], v27 offset0:29 offset1:30
	ds_read2st64_b32 v[204:205], v27 offset0:31 offset1:32
	ds_read2st64_b32 v[206:207], v27 offset0:43 offset1:44
	ds_read2st64_b32 v[208:209], v27 offset0:45 offset1:46
	s_waitcnt lgkmcnt(14)
	ds_read2st64_b32 v[210:211], v27 offset0:47 offset1:48
	v_mul_f32_e32 v25, v24, v24
	v_fmamk_f32 v37, v25, 0xb94c1982, v32
	v_fmaak_f32 v37, v25, v37, 0xbe2aaa9d
	v_mul_f32_e32 v37, v25, v37
	v_add_u32_e32 v22, -1, v22
	v_fmac_f32_e32 v24, v24, v37
	v_fmamk_f32 v37, v25, 0x37d75334, v33
	v_cvt_f64_u32_e32 v[40:41], v22
	v_fmaak_f32 v37, v25, v37, 0x3d2aabf7
	v_div_scale_f64 v[42:43], s[6:7], v[40:41], v[40:41], v[16:17]
	v_fmaak_f32 v37, v25, v37, 0xbf000004
	v_rcp_f64_e32 v[44:45], v[42:43]
	v_fma_f32 v25, v25, v37, 1.0
	v_and_b32_e32 v37, 1, v23
	v_cmp_eq_u32_e32 vcc, 0, v37
	v_lshlrev_b32_e32 v23, 30, v23
	s_brev_b32 s6, 1
	v_cndmask_b32_e64 v22, -v24, v25, vcc
	v_bitop3_b32 v37, v23, v22, s6 bitop3:0x6c
	v_fma_f64 v[22:23], -v[42:43], v[44:45], 1.0
	v_fmac_f64_e32 v[44:45], v[44:45], v[22:23]
	v_fma_f64 v[22:23], -v[42:43], v[44:45], 1.0
	v_fmac_f64_e32 v[44:45], v[44:45], v[22:23]
	v_div_scale_f64 v[22:23], vcc, v[16:17], v[40:41], v[16:17]
	v_mul_f64 v[24:25], v[22:23], v[44:45]
	v_fma_f64 v[22:23], -v[42:43], v[24:25], v[22:23]
	s_nop 1
	v_div_fmas_f64 v[22:23], v[22:23], v[44:45], v[24:25]
	v_div_fixup_f64 v[22:23], v[22:23], v[40:41], v[16:17]
	s_waitcnt vmcnt(1)
	v_cvt_f64_f32_e32 v[16:17], v15
	v_mul_f32_e32 v15, v38, v38
	s_waitcnt vmcnt(0)
	v_cvt_f64_f32_e32 v[24:25], v18
	v_fmamk_f32 v18, v15, 0xb94c1982, v32
	v_fmaak_f32 v18, v15, v18, 0xbe2aaa9d
	v_mul_f32_e32 v18, v15, v18
	v_fmac_f32_e32 v38, v38, v18
	v_fmamk_f32 v18, v15, 0x37d75334, v33
	v_fmaak_f32 v18, v15, v18, 0x3d2aabf7
	v_fmaak_f32 v18, v15, v18, 0xbf000004
	v_fma_f32 v15, v15, v18, 1.0
	v_and_b32_e32 v18, 1, v0
	v_lshlrev_b32_e32 v0, 30, v0
	s_waitcnt lgkmcnt(15)
	v_cvt_f64_f32_e32 v[40:41], v21
	v_cmp_eq_u32_e32 vcc, 0, v18
	v_and_b32_e32 v0, 0x80000000, v0
	v_xor_b32_e32 v18, v20, v19
	v_fmac_f64_e32 v[24:25], v[22:23], v[40:41]
	v_cndmask_b32_e32 v15, v15, v38, vcc
	v_xor_b32_e32 v0, v18, v0
	v_cmp_class_f32_e64 vcc, v19, s29
	s_nop 0
	v_xor_b32_e32 v0, v0, v15
	v_cndmask_b32_e32 v0, v36, v0, vcc
	v_cndmask_b32_e32 v15, v36, v37, vcc
	v_readlane_b32 s7, v0, 0
	v_readlane_b32 s6, v15, 0
	s_waitcnt lgkmcnt(11)
	v_cvt_f64_f32_e32 v[54:55], v188
	v_cvt_f64_f32_e32 v[46:47], s7
	v_cvt_f64_f32_e32 v[20:21], s6
	v_cvt_f64_f32_e32 v[42:43], v180
	v_mul_f64 v[46:47], v[46:47], v[54:55]
	v_readlane_b32 s7, v0, 1
	s_nop 0
	v_fma_f64 v[20:21], v[20:21], v[42:43], -v[46:47]
	v_readlane_b32 s6, v15, 1
	v_cvt_f64_f32_e32 v[42:43], s7
	v_cvt_f64_f32_e32 v[44:45], v189
	v_add_f64 v[20:21], v[24:25], v[20:21]
	v_cvt_f64_f32_e32 v[24:25], s6
	v_cvt_f64_f32_e32 v[18:19], v181
	v_mul_f64 v[42:43], v[42:43], v[44:45]
	v_readlane_b32 s7, v0, 2
	v_fma_f64 v[18:19], v[24:25], v[18:19], -v[42:43]
	v_readlane_b32 s6, v15, 2
	v_cvt_f64_f32_e32 v[42:43], s7
	s_waitcnt lgkmcnt(10)
	v_cvt_f64_f32_e32 v[44:45], v190
	v_add_f64 v[18:19], v[20:21], v[18:19]
	v_cvt_f64_f32_e32 v[20:21], s6
	v_cvt_f64_f32_e32 v[24:25], v182
	v_mul_f64 v[42:43], v[42:43], v[44:45]
	v_readlane_b32 s7, v0, 3
	v_fma_f64 v[20:21], v[20:21], v[24:25], -v[42:43]
	v_readlane_b32 s6, v15, 3
	v_cvt_f64_f32_e32 v[24:25], s7
	v_cvt_f64_f32_e32 v[42:43], v191
	v_add_f64 v[18:19], v[18:19], v[20:21]
	v_cvt_f64_f32_e32 v[20:21], s6
	v_cvt_f64_f32_e32 v[22:23], v183
	v_mul_f64 v[24:25], v[24:25], v[42:43]
	v_readlane_b32 s7, v0, 4
	v_fma_f64 v[20:21], v[20:21], v[22:23], -v[24:25]
	v_readlane_b32 s6, v15, 4
	v_cvt_f64_f32_e32 v[24:25], s7
	s_waitcnt lgkmcnt(9)
	v_cvt_f64_f32_e32 v[42:43], v192
	v_add_f64 v[18:19], v[18:19], v[20:21]
	v_cvt_f64_f32_e32 v[20:21], s6
	v_cvt_f64_f32_e32 v[22:23], v184
	v_mul_f64 v[24:25], v[24:25], v[42:43]
	v_readlane_b32 s7, v0, 5
	v_fma_f64 v[20:21], v[20:21], v[22:23], -v[24:25]
	v_readlane_b32 s6, v15, 5
	v_cvt_f64_f32_e32 v[22:23], v185
	v_cvt_f64_f32_e32 v[24:25], s7
	v_cvt_f64_f32_e32 v[38:39], v193
	v_add_f64 v[18:19], v[18:19], v[20:21]
	v_cvt_f64_f32_e32 v[20:21], s6
	v_mul_f64 v[24:25], v[24:25], v[38:39]
	v_readlane_b32 s7, v0, 6
	v_fma_f64 v[20:21], v[20:21], v[22:23], -v[24:25]
	v_readlane_b32 s6, v15, 6
	v_cvt_f64_f32_e32 v[24:25], s7
	s_waitcnt lgkmcnt(8)
	v_cvt_f64_f32_e32 v[38:39], v194
	v_add_f64 v[18:19], v[18:19], v[20:21]
	v_cvt_f64_f32_e32 v[20:21], s6
	v_cvt_f64_f32_e32 v[22:23], v186
	v_mul_f64 v[24:25], v[24:25], v[38:39]
	v_readlane_b32 s7, v0, 7
	v_fma_f64 v[20:21], v[20:21], v[22:23], -v[24:25]
	v_readlane_b32 s6, v15, 7
	v_cvt_f64_f32_e32 v[24:25], s7
	v_cvt_f64_f32_e32 v[38:39], v195
	v_add_f64 v[18:19], v[18:19], v[20:21]
	v_cvt_f64_f32_e32 v[20:21], s6
	v_cvt_f64_f32_e32 v[22:23], v187
	v_mul_f64 v[24:25], v[24:25], v[38:39]
	v_fma_f64 v[20:21], v[20:21], v[22:23], -v[24:25]
	v_add_f64 v[18:19], v[18:19], v[20:21]
	v_readlane_b32 s7, v0, 8
	v_readlane_b32 s6, v15, 8
	v_readlane_b32 s9, v0, 9
	v_cvt_f64_f32_e32 v[50:51], s7
	s_waitcnt lgkmcnt(6)
	v_cvt_f64_f32_e32 v[58:59], v199
	v_cvt_f64_f32_e32 v[22:23], v198
	v_readlane_b32 s8, v15, 9
	v_cvt_f64_f32_e32 v[24:25], s6
	v_cvt_f64_f32_e32 v[46:47], v196
	v_cvt_f64_f32_e32 v[48:49], s9
	v_mul_f64 v[22:23], v[50:51], v[22:23]
	v_cvt_f64_f32_e32 v[38:39], s8
	v_cvt_f64_f32_e32 v[20:21], v197
	v_mul_f64 v[48:49], v[48:49], v[58:59]
	v_fma_f64 v[22:23], v[24:25], v[46:47], -v[22:23]
	v_readlane_b32 s7, v0, 10
	v_readlane_b32 s9, v0, 11
	v_fma_f64 v[20:21], v[38:39], v[20:21], -v[48:49]
	v_add_f64 v[18:19], v[18:19], v[22:23]
	v_readlane_b32 s6, v15, 10
	v_readlane_b32 s8, v15, 11
	s_waitcnt lgkmcnt(5)
	v_cvt_f64_f32_e32 v[24:25], v200
	v_cvt_f64_f32_e32 v[38:39], v201
	v_cvt_f64_f32_e32 v[40:41], s9
	v_cvt_f64_f32_e32 v[46:47], s7
	s_waitcnt lgkmcnt(2)
	v_cvt_f64_f32_e32 v[48:49], v207
	v_cvt_f64_f32_e32 v[50:51], v206
	v_add_f64 v[18:19], v[18:19], v[20:21]
	v_cvt_f64_f32_e32 v[20:21], s6
	v_cvt_f64_f32_e32 v[22:23], s8
	v_mul_f64 v[46:47], v[46:47], v[50:51]
	v_mul_f64 v[40:41], v[40:41], v[48:49]
	v_readlane_b32 s7, v0, 12
	v_fma_f64 v[22:23], v[22:23], v[38:39], -v[40:41]
	v_fma_f64 v[20:21], v[20:21], v[24:25], -v[46:47]
	v_readlane_b32 s6, v15, 12
	v_readlane_b32 s9, v0, 13
	v_cvt_f64_f32_e32 v[24:25], v202
	v_cvt_f64_f32_e32 v[38:39], v203
	v_cvt_f64_f32_e32 v[42:43], s7
	s_waitcnt lgkmcnt(1)
	v_cvt_f64_f32_e32 v[48:49], v208
	v_add_f64 v[18:19], v[18:19], v[20:21]
	v_readlane_b32 s8, v15, 13
	v_cvt_f64_f32_e32 v[20:21], s6
	v_cvt_f64_f32_e32 v[40:41], s9
	v_cvt_f64_f32_e32 v[46:47], v209
	v_mul_f64 v[42:43], v[42:43], v[48:49]
	v_readlane_b32 s7, v0, 14
	v_add_f64 v[18:19], v[18:19], v[22:23]
	v_cvt_f64_f32_e32 v[22:23], s8
	v_mul_f64 v[40:41], v[40:41], v[46:47]
	v_fma_f64 v[20:21], v[20:21], v[24:25], -v[42:43]
	v_readlane_b32 s6, v15, 14
	v_readlane_b32 s9, v0, 15
	v_cvt_f64_f32_e32 v[42:43], s7
	s_waitcnt lgkmcnt(0)
	v_cvt_f64_f32_e32 v[46:47], v210
	v_fma_f64 v[22:23], v[22:23], v[38:39], -v[40:41]
	v_add_f64 v[18:19], v[18:19], v[20:21]
	v_readlane_b32 s8, v15, 15
	v_cvt_f64_f32_e32 v[20:21], s6
	v_cvt_f64_f32_e32 v[24:25], v204
	v_cvt_f64_f32_e32 v[38:39], v205
	v_cvt_f64_f32_e32 v[40:41], s9
	v_cvt_f64_f32_e32 v[44:45], v211
	v_mul_f64 v[42:43], v[42:43], v[46:47]
	v_add_f64 v[18:19], v[18:19], v[22:23]
	v_cvt_f64_f32_e32 v[22:23], s8
	v_mul_f64 v[40:41], v[40:41], v[44:45]
	v_fma_f64 v[20:21], v[20:21], v[24:25], -v[42:43]
	v_fma_f64 v[22:23], v[22:23], v[38:39], -v[40:41]
	v_add_f64 v[18:19], v[18:19], v[20:21]
	v_add_f64 v[18:19], v[18:19], v[22:23]
	v_mul_f64 v[18:19], v[18:19], v[16:17]
	v_mul_f64 v[20:21], v[18:19], s[16:17]
	v_rndne_f64_e32 v[20:21], v[20:21]
	v_fmac_f64_e32 v[18:19], s[14:15], v[20:21]
	v_cvt_f32_f64_e32 v15, v[18:19]
	v_and_b32_e32 v18, 0x7fffffff, v15
	v_cmp_nlt_f32_e64 s[6:7], |v15|, s2
	s_and_saveexec_b64 s[8:9], s[6:7]
	s_xor_b64 s[18:19], exec, s[8:9]
	s_cbranch_execz .LBB0_849
	v_lshrrev_b32_e32 v0, 23, v18
	v_add_u32_e32 v0, 0xffffff88, v0
	v_cmp_lt_u32_e32 vcc, 63, v0
	s_nop 1
	v_cndmask_b32_e32 v19, 0, v34, vcc
	v_add_u32_e32 v0, v19, v0
	v_cmp_lt_u32_e64 s[6:7], 31, v0
	s_nop 1
	v_cndmask_b32_e64 v19, 0, v35, s[6:7]
	v_add_u32_e32 v0, v19, v0
	v_cmp_lt_u32_e64 s[8:9], 31, v0
	s_nop 1
	v_cndmask_b32_e64 v19, 0, v35, s[8:9]
	v_add_u32_e32 v19, v19, v0
	v_and_b32_e32 v0, 0x7fffff, v18
	v_or_b32_e32 v37, 0x800000, v0
	v_mad_u64_u32 v[20:21], s[10:11], v37, s3, 0
	v_mov_b32_e32 v0, v21
	v_mad_u64_u32 v[22:23], s[10:11], v37, s4, v[0:1]
	v_mov_b32_e32 v0, v23
	v_mad_u64_u32 v[24:25], s[10:11], v37, s5, v[0:1]
	v_mov_b32_e32 v0, v25
	v_mad_u64_u32 v[38:39], s[10:11], v37, s22, v[0:1]
	v_mov_b32_e32 v0, v39
	v_mad_u64_u32 v[40:41], s[10:11], v37, s23, v[0:1]
	v_mov_b32_e32 v0, v41
	v_mad_u64_u32 v[42:43], s[10:11], v37, s24, v[0:1]
	v_mov_b32_e32 v0, v43
	v_mad_u64_u32 v[44:45], s[10:11], v37, s25, v[0:1]
	v_cndmask_b32_e32 v21, v42, v38, vcc
	v_cndmask_b32_e32 v0, v44, v40, vcc
	v_cndmask_b32_e32 v25, v45, v42, vcc
	v_cndmask_b32_e64 v23, v0, v21, s[6:7]
	v_cndmask_b32_e64 v0, v25, v0, s[6:7]
	v_cndmask_b32_e32 v25, v40, v24, vcc
	v_cndmask_b32_e64 v21, v21, v25, s[6:7]
	v_sub_u32_e32 v37, 32, v19
	v_cmp_eq_u32_e64 s[10:11], 0, v19
	v_cndmask_b32_e32 v19, v38, v22, vcc
	v_cndmask_b32_e64 v0, v0, v23, s[8:9]
	v_cndmask_b32_e64 v23, v23, v21, s[8:9]
	v_cndmask_b32_e64 v22, v25, v19, s[6:7]
	v_alignbit_b32 v39, v0, v23, v37
	v_cndmask_b32_e64 v21, v21, v22, s[8:9]
	v_cndmask_b32_e64 v0, v39, v0, s[10:11]
	v_alignbit_b32 v25, v23, v21, v37
	v_cndmask_b32_e32 v20, v24, v20, vcc
	v_cndmask_b32_e64 v23, v25, v23, s[10:11]
	v_bfe_u32 v39, v0, 29, 1
	v_cndmask_b32_e64 v19, v19, v20, s[6:7]
	v_alignbit_b32 v25, v0, v23, 30
	v_sub_u32_e32 v40, 0, v39
	v_cndmask_b32_e64 v19, v22, v19, s[8:9]
	v_xor_b32_e32 v25, v25, v40
	v_alignbit_b32 v20, v21, v19, v37
	v_cndmask_b32_e64 v20, v20, v21, s[10:11]
	v_ffbh_u32_e32 v22, v25
	v_alignbit_b32 v21, v23, v20, 30
	v_min_u32_e32 v22, 32, v22
	v_alignbit_b32 v19, v20, v19, 30
	v_xor_b32_e32 v21, v21, v40
	v_sub_u32_e32 v23, 31, v22
	v_xor_b32_e32 v19, v19, v40
	v_alignbit_b32 v24, v25, v21, v23
	v_alignbit_b32 v19, v21, v19, v23
	v_alignbit_b32 v20, v24, v19, 9
	v_ffbh_u32_e32 v21, v20
	v_min_u32_e32 v21, 32, v21
	v_lshrrev_b32_e32 v38, 29, v0
	v_not_b32_e32 v23, v21
	v_alignbit_b32 v19, v20, v19, v23
	v_lshlrev_b32_e32 v20, 31, v38
	v_or_b32_e32 v23, 0x33000000, v20
	v_add_lshl_u32 v21, v21, v22, 23
	v_lshrrev_b32_e32 v19, 9, v19
	v_sub_u32_e32 v21, v23, v21
	v_or_b32_e32 v20, 0.5, v20
	v_lshlrev_b32_e32 v22, 23, v22
	v_or_b32_e32 v19, v21, v19
	v_lshrrev_b32_e32 v21, 9, v24
	v_sub_u32_e32 v20, v20, v22
	v_or_b32_e32 v20, v21, v20
	v_mul_f32_e32 v21, 0x3fc90fda, v20
	v_fma_f32 v22, v20, s26, -v21
	v_fmac_f32_e32 v22, 0x33a22168, v20
	v_fmac_f32_e32 v22, 0x3fc90fda, v19
	v_lshrrev_b32_e32 v0, 30, v0
	v_add_f32_e32 v19, v21, v22
	v_add_u32_e32 v0, v39, v0
.LBB0_849:
	s_andn2_saveexec_b64 s[6:7], s[18:19]
	v_mul_f32_e64 v0, |v15|, s27
	v_rndne_f32_e32 v20, v0
	v_cvt_i32_f32_e32 v0, v20
	v_fma_f32 v19, v20, s28, |v15|
	v_fmac_f32_e32 v19, 0xb3a22168, v20
	v_fmac_f32_e32 v19, 0xa7c234c4, v20
	s_or_b64 exec, exec, s[6:7]
	v_mul_f32_e32 v20, v19, v19
	v_fmamk_f32 v21, v20, 0xb94c1982, v32
	v_fmaak_f32 v21, v20, v21, 0xbe2aaa9d
	v_mul_f32_e32 v21, v20, v21
	v_fmac_f32_e32 v19, v19, v21
	v_fmamk_f32 v21, v20, 0x37d75334, v33
	v_fmaak_f32 v21, v20, v21, 0x3d2aabf7
	v_fmaak_f32 v21, v20, v21, 0xbf000004
	v_fma_f32 v20, v20, v21, 1.0
	v_and_b32_e32 v21, 1, v0
	v_lshlrev_b32_e32 v0, 30, v0
	v_cmp_eq_u32_e32 vcc, 0, v21
	v_and_b32_e32 v0, 0x80000000, v0
	v_xor_b32_e32 v18, v18, v15
	v_cndmask_b32_e32 v19, v20, v19, vcc
	v_xor_b32_e32 v0, v18, v0
	v_xor_b32_e32 v0, v0, v19
	v_cmp_class_f32_e64 vcc, v15, s29
	s_nop 1
	v_cndmask_b32_e32 v0, v36, v0, vcc
	v_cvt_f64_f32_e32 v[18:19], v0
	ds_write_b64 v29, v[18:19]
	s_waitcnt lgkmcnt(0)
	s_barrier
	ds_read_b128 v[180:183], v28
	ds_read_b128 v[184:187], v28 offset:16
	ds_read_b128 v[188:191], v28 offset:32
	ds_read_b128 v[192:195], v28 offset:48
	ds_read2st64_b32 v[196:197], v27 offset0:49 offset1:50
	ds_read2st64_b32 v[198:199], v27 offset0:51 offset1:52
	ds_read2st64_b32 v[200:201], v27 offset0:53 offset1:54
	ds_read2st64_b32 v[202:203], v27 offset0:55 offset1:56
	ds_read_b128 v[204:207], v28 offset:64
	ds_read2st64_b32 v[208:209], v27 offset0:57 offset1:58
	ds_read_b128 v[212:215], v28 offset:80
	ds_read2st64_b32 v[210:211], v27 offset0:59 offset1:60
	ds_read_b128 v[216:219], v28 offset:96
	ds_read2st64_b32 v[220:221], v27 offset0:61 offset1:62
	ds_read_b128 v[224:227], v28 offset:112
	s_waitcnt lgkmcnt(14)
	ds_read2st64_b32 v[222:223], v27 offset0:63 offset1:64
	global_load_dword v107, v[8:9], off
	s_waitcnt lgkmcnt(14)
	ds_read_b128 v[228:231], v28 offset:128
	s_waitcnt lgkmcnt(14)
	ds_read2st64_b32 v[232:233], v27 offset0:65 offset1:66
	s_waitcnt lgkmcnt(15)
	s_waitcnt lgkmcnt(13)
	v_cvt_f64_f32_e32 v[50:51], v196
	s_waitcnt vmcnt(1)
	s_waitcnt vmcnt(0)
	v_cvt_f64_f32_e32 v[18:19], v107
	v_fmac_f64_e32 v[18:19], v[180:181], v[50:51]
	v_cvt_f64_f32_e32 v[20:21], v197
	s_nop 0
	v_fma_f64 v[20:21], v[182:183], v[20:21], 0
	ds_read_b128 v[180:183], v28 offset:144
	ds_read2st64_b32 v[196:197], v27 offset0:67 offset1:68
	s_waitcnt lgkmcnt(14)
	v_cvt_f64_f32_e32 v[22:23], v198
	v_fma_f64 v[22:23], v[184:185], v[22:23], 0
	v_cvt_f64_f32_e32 v[24:25], v199
	s_nop 0
	v_fma_f64 v[24:25], v[186:187], v[24:25], 0
	ds_read_b128 v[184:187], v28 offset:160
	s_waitcnt lgkmcnt(14)
	ds_read2st64_b32 v[198:199], v27 offset0:69 offset1:70
	v_cvt_f64_f32_e32 v[40:41], v200
	v_cvt_f64_f32_e32 v[38:39], v201
	s_nop 0
	v_fmac_f64_e32 v[20:21], v[190:191], v[38:39]
	v_fmac_f64_e32 v[18:19], v[188:189], v[40:41]
	s_waitcnt lgkmcnt(14)
	ds_read_b128 v[188:191], v28 offset:176
	s_waitcnt lgkmcnt(14)
	ds_read2st64_b32 v[200:201], v27 offset0:71 offset1:72
	v_cvt_f64_f32_e32 v[40:41], v202
	v_cvt_f64_f32_e32 v[38:39], v203
	s_nop 0
	v_fmac_f64_e32 v[22:23], v[192:193], v[40:41]
	v_fmac_f64_e32 v[24:25], v[194:195], v[38:39]
	s_waitcnt lgkmcnt(14)
	ds_read_b128 v[192:195], v28 offset:192
	s_waitcnt lgkmcnt(14)
	ds_read2st64_b32 v[202:203], v27 offset0:73 offset1:74
	v_cvt_f64_f32_e32 v[44:45], v208
	v_fmac_f64_e32 v[18:19], v[204:205], v[44:45]
	v_cvt_f64_f32_e32 v[38:39], v209
	s_nop 0
	v_fmac_f64_e32 v[20:21], v[206:207], v[38:39]
	s_waitcnt lgkmcnt(14)
	ds_read_b128 v[204:207], v28 offset:208
	s_waitcnt lgkmcnt(14)
	ds_read2st64_b32 v[208:209], v27 offset0:75 offset1:76
	v_cvt_f64_f32_e32 v[44:45], v210
	v_fmac_f64_e32 v[22:23], v[212:213], v[44:45]
	v_cvt_f64_f32_e32 v[38:39], v211
	s_nop 0
	v_fmac_f64_e32 v[24:25], v[214:215], v[38:39]
	s_waitcnt lgkmcnt(14)
	ds_read_b128 v[212:215], v28 offset:224
	s_waitcnt lgkmcnt(14)
	ds_read2st64_b32 v[210:211], v27 offset0:77 offset1:78
	v_cvt_f64_f32_e32 v[44:45], v220
	v_fmac_f64_e32 v[18:19], v[216:217], v[44:45]
	v_cvt_f64_f32_e32 v[38:39], v221
	s_nop 0
	v_fmac_f64_e32 v[20:21], v[218:219], v[38:39]
	s_waitcnt lgkmcnt(14)
	ds_read_b128 v[216:219], v28 offset:240
	s_waitcnt lgkmcnt(14)
	ds_read2st64_b32 v[220:221], v27 offset0:79 offset1:80
	v_cvt_f64_f32_e32 v[44:45], v222
	v_fmac_f64_e32 v[22:23], v[224:225], v[44:45]
	v_cvt_f64_f32_e32 v[38:39], v223
	s_nop 0
	v_fmac_f64_e32 v[24:25], v[226:227], v[38:39]
	s_waitcnt lgkmcnt(14)
	ds_read_b128 v[224:227], v28 offset:256
	s_waitcnt lgkmcnt(14)
	ds_read2st64_b32 v[222:223], v27 offset0:81 offset1:82
	v_cvt_f64_f32_e32 v[44:45], v232
	v_fmac_f64_e32 v[18:19], v[228:229], v[44:45]
	v_cvt_f64_f32_e32 v[38:39], v233
	s_waitcnt lgkmcnt(14)
	ds_read_b128 v[232:235], v28 offset:272
	s_waitcnt lgkmcnt(14)
	ds_read2st64_b32 v[236:237], v27 offset0:83 offset1:84
	v_fmac_f64_e32 v[20:21], v[230:231], v[38:39]
	s_waitcnt lgkmcnt(14)
	ds_read_b128 v[228:231], v28 offset:288
	v_cvt_f64_f32_e32 v[44:45], v196
	v_fmac_f64_e32 v[22:23], v[180:181], v[44:45]
	v_cvt_f64_f32_e32 v[38:39], v197
	s_waitcnt lgkmcnt(14)
	ds_read2st64_b32 v[196:197], v27 offset0:85 offset1:86
	v_fmac_f64_e32 v[24:25], v[182:183], v[38:39]
	s_waitcnt lgkmcnt(14)
	ds_read_b128 v[180:183], v28 offset:304
	v_cvt_f64_f32_e32 v[44:45], v198
	v_fmac_f64_e32 v[18:19], v[184:185], v[44:45]
	v_cvt_f64_f32_e32 v[38:39], v199
	s_waitcnt lgkmcnt(14)
	ds_read2st64_b32 v[198:199], v27 offset0:87 offset1:88
	v_fmac_f64_e32 v[20:21], v[186:187], v[38:39]
	s_waitcnt lgkmcnt(14)
	ds_read_b128 v[184:187], v28 offset:320
	v_cvt_f64_f32_e32 v[44:45], v200
	v_fmac_f64_e32 v[22:23], v[188:189], v[44:45]
	v_cvt_f64_f32_e32 v[38:39], v201
	s_waitcnt lgkmcnt(14)
	ds_read2st64_b32 v[200:201], v27 offset0:89 offset1:90
	v_fmac_f64_e32 v[24:25], v[190:191], v[38:39]
	s_waitcnt lgkmcnt(14)
	ds_read_b128 v[188:191], v28 offset:336
	v_cvt_f64_f32_e32 v[44:45], v202
	v_fmac_f64_e32 v[18:19], v[192:193], v[44:45]
	v_cvt_f64_f32_e32 v[38:39], v203
	s_waitcnt lgkmcnt(14)
	ds_read2st64_b32 v[202:203], v27 offset0:91 offset1:92
	v_fmac_f64_e32 v[20:21], v[194:195], v[38:39]
	s_waitcnt lgkmcnt(14)
	ds_read_b128 v[192:195], v28 offset:352
	v_cvt_f64_f32_e32 v[44:45], v208
	v_fmac_f64_e32 v[22:23], v[204:205], v[44:45]
	v_cvt_f64_f32_e32 v[38:39], v209
	s_waitcnt lgkmcnt(14)
	ds_read2st64_b32 v[208:209], v27 offset0:93 offset1:94
	v_fmac_f64_e32 v[24:25], v[206:207], v[38:39]
	s_waitcnt lgkmcnt(14)
	ds_read_b128 v[204:207], v28 offset:368
	v_cvt_f64_f32_e32 v[44:45], v210
	v_fmac_f64_e32 v[18:19], v[212:213], v[44:45]
	v_cvt_f64_f32_e32 v[38:39], v211
	s_waitcnt lgkmcnt(14)
	ds_read2st64_b32 v[210:211], v27 offset0:95 offset1:96
	v_fmac_f64_e32 v[20:21], v[214:215], v[38:39]
	s_waitcnt lgkmcnt(14)
	ds_read_b128 v[212:215], v28 offset:384
	v_cvt_f64_f32_e32 v[44:45], v220
	v_fmac_f64_e32 v[22:23], v[216:217], v[44:45]
	v_cvt_f64_f32_e32 v[38:39], v221
	s_waitcnt lgkmcnt(14)
	ds_read2st64_b32 v[220:221], v27 offset0:97 offset1:98
	v_fmac_f64_e32 v[24:25], v[218:219], v[38:39]
	s_waitcnt lgkmcnt(14)
	ds_read_b128 v[216:219], v28 offset:400
	v_cvt_f64_f32_e32 v[44:45], v222
	v_fmac_f64_e32 v[18:19], v[224:225], v[44:45]
	v_cvt_f64_f32_e32 v[38:39], v223
	s_waitcnt lgkmcnt(14)
	ds_read2st64_b32 v[222:223], v27 offset0:99 offset1:100
	v_fmac_f64_e32 v[20:21], v[226:227], v[38:39]
	s_waitcnt lgkmcnt(14)
	ds_read_b128 v[224:227], v28 offset:416
	v_cvt_f64_f32_e32 v[44:45], v236
	v_fmac_f64_e32 v[22:23], v[232:233], v[44:45]
	v_cvt_f64_f32_e32 v[38:39], v237
	s_waitcnt lgkmcnt(14)
	ds_read2st64_b32 v[236:237], v27 offset0:101 offset1:102
	v_fmac_f64_e32 v[24:25], v[234:235], v[38:39]
	s_waitcnt lgkmcnt(14)
	ds_read_b128 v[232:235], v28 offset:432
	v_cvt_f64_f32_e32 v[44:45], v196
	v_fmac_f64_e32 v[18:19], v[228:229], v[44:45]
	v_cvt_f64_f32_e32 v[38:39], v197
	s_waitcnt lgkmcnt(14)
	ds_read2st64_b32 v[196:197], v27 offset0:103 offset1:104
	v_fmac_f64_e32 v[20:21], v[230:231], v[38:39]
	s_waitcnt lgkmcnt(14)
	ds_read_b128 v[228:231], v28 offset:448
	v_cvt_f64_f32_e32 v[44:45], v198
	v_fmac_f64_e32 v[22:23], v[180:181], v[44:45]
	v_cvt_f64_f32_e32 v[38:39], v199
	s_waitcnt lgkmcnt(14)
	ds_read2st64_b32 v[198:199], v27 offset0:105 offset1:106
	v_fmac_f64_e32 v[24:25], v[182:183], v[38:39]
	s_waitcnt lgkmcnt(14)
	ds_read_b128 v[180:183], v28 offset:464
	v_cvt_f64_f32_e32 v[44:45], v200
	v_fmac_f64_e32 v[18:19], v[184:185], v[44:45]
	v_cvt_f64_f32_e32 v[38:39], v201
	s_waitcnt lgkmcnt(14)
	ds_read2st64_b32 v[200:201], v27 offset0:107 offset1:108
	v_fmac_f64_e32 v[20:21], v[186:187], v[38:39]
	s_waitcnt lgkmcnt(14)
	ds_read_b128 v[184:187], v28 offset:480
	v_cvt_f64_f32_e32 v[44:45], v202
	v_fmac_f64_e32 v[22:23], v[188:189], v[44:45]
	v_cvt_f64_f32_e32 v[38:39], v203
	s_waitcnt lgkmcnt(14)
	ds_read2st64_b32 v[202:203], v27 offset0:109 offset1:110
	v_fmac_f64_e32 v[24:25], v[190:191], v[38:39]
	s_waitcnt lgkmcnt(14)
	ds_read_b128 v[188:191], v28 offset:496
	v_cvt_f64_f32_e32 v[44:45], v208
	v_fmac_f64_e32 v[18:19], v[192:193], v[44:45]
	v_cvt_f64_f32_e32 v[38:39], v209
	s_waitcnt lgkmcnt(14)
	ds_read2st64_b32 v[208:209], v27 offset0:111 offset1:112
	v_fmac_f64_e32 v[20:21], v[194:195], v[38:39]
	v_cvt_f64_f32_e32 v[44:45], v210
	v_fmac_f64_e32 v[22:23], v[204:205], v[44:45]
	v_cvt_f64_f32_e32 v[38:39], v211
	s_nop 0
	v_fmac_f64_e32 v[24:25], v[206:207], v[38:39]
	s_waitcnt lgkmcnt(14)
	v_cvt_f64_f32_e32 v[44:45], v220
	v_fmac_f64_e32 v[18:19], v[212:213], v[44:45]
	v_cvt_f64_f32_e32 v[38:39], v221
	v_fmac_f64_e32 v[20:21], v[214:215], v[38:39]
	s_waitcnt lgkmcnt(12)
	v_cvt_f64_f32_e32 v[44:45], v222
	v_fmac_f64_e32 v[22:23], v[216:217], v[44:45]
	v_cvt_f64_f32_e32 v[38:39], v223
	v_fmac_f64_e32 v[24:25], v[218:219], v[38:39]
	s_waitcnt lgkmcnt(10)
	v_cvt_f64_f32_e32 v[44:45], v236
	v_fmac_f64_e32 v[18:19], v[224:225], v[44:45]
	v_cvt_f64_f32_e32 v[38:39], v237
	v_fmac_f64_e32 v[20:21], v[226:227], v[38:39]
	s_waitcnt lgkmcnt(8)
	v_cvt_f64_f32_e32 v[44:45], v196
	v_fmac_f64_e32 v[22:23], v[232:233], v[44:45]
	v_cvt_f64_f32_e32 v[38:39], v197
	v_fmac_f64_e32 v[24:25], v[234:235], v[38:39]
	s_waitcnt lgkmcnt(6)
	v_cvt_f64_f32_e32 v[44:45], v198
	v_fmac_f64_e32 v[18:19], v[228:229], v[44:45]
	v_cvt_f64_f32_e32 v[38:39], v199
	v_fmac_f64_e32 v[20:21], v[230:231], v[38:39]
	s_waitcnt lgkmcnt(4)
	v_cvt_f64_f32_e32 v[44:45], v200
	v_fmac_f64_e32 v[22:23], v[180:181], v[44:45]
	v_cvt_f64_f32_e32 v[38:39], v201
	v_fmac_f64_e32 v[24:25], v[182:183], v[38:39]
	s_waitcnt lgkmcnt(2)
	v_cvt_f64_f32_e32 v[44:45], v202
	v_fmac_f64_e32 v[18:19], v[184:185], v[44:45]
	v_cvt_f64_f32_e32 v[38:39], v203
	v_fmac_f64_e32 v[20:21], v[186:187], v[38:39]
	s_nop 1
	v_add_f64 v[18:19], v[18:19], v[20:21]
	s_waitcnt lgkmcnt(0)
	v_cvt_f64_f32_e32 v[44:45], v208
	v_fmac_f64_e32 v[22:23], v[188:189], v[44:45]
	v_cvt_f64_f32_e32 v[38:39], v209
	v_fmac_f64_e32 v[24:25], v[190:191], v[38:39]
	v_add_f64 v[20:21], v[22:23], v[24:25]
	v_add_f64 v[18:19], v[18:19], v[20:21]
	v_mul_f64 v[18:19], v[18:19], v[16:17]
	v_mul_f64 v[20:21], v[18:19], s[16:17]
	v_rndne_f64_e32 v[20:21], v[20:21]
	v_fmac_f64_e32 v[18:19], s[14:15], v[20:21]
	v_cvt_f32_f64_e32 v15, v[18:19]
	v_and_b32_e32 v18, 0x7fffffff, v15
	v_cmp_nlt_f32_e64 s[6:7], |v15|, s2
	s_and_saveexec_b64 s[8:9], s[6:7]
	s_xor_b64 s[18:19], exec, s[8:9]
	s_cbranch_execz .LBB0_853
	v_lshrrev_b32_e32 v0, 23, v18
	v_add_u32_e32 v0, 0xffffff88, v0
	v_cmp_lt_u32_e32 vcc, 63, v0
	s_nop 1
	v_cndmask_b32_e32 v19, 0, v34, vcc
	v_add_u32_e32 v0, v19, v0
	v_cmp_lt_u32_e64 s[6:7], 31, v0
	s_nop 1
	v_cndmask_b32_e64 v19, 0, v35, s[6:7]
	v_add_u32_e32 v0, v19, v0
	v_cmp_lt_u32_e64 s[8:9], 31, v0
	s_nop 1
	v_cndmask_b32_e64 v19, 0, v35, s[8:9]
	v_add_u32_e32 v19, v19, v0
	v_and_b32_e32 v0, 0x7fffff, v18
	v_or_b32_e32 v37, 0x800000, v0
	v_mad_u64_u32 v[20:21], s[10:11], v37, s3, 0
	v_mov_b32_e32 v0, v21
	v_mad_u64_u32 v[22:23], s[10:11], v37, s4, v[0:1]
	v_mov_b32_e32 v0, v23
	v_mad_u64_u32 v[24:25], s[10:11], v37, s5, v[0:1]
	v_mov_b32_e32 v0, v25
	v_mad_u64_u32 v[38:39], s[10:11], v37, s22, v[0:1]
	v_mov_b32_e32 v0, v39
	v_mad_u64_u32 v[40:41], s[10:11], v37, s23, v[0:1]
	v_mov_b32_e32 v0, v41
	v_mad_u64_u32 v[42:43], s[10:11], v37, s24, v[0:1]
	v_mov_b32_e32 v0, v43
	v_mad_u64_u32 v[44:45], s[10:11], v37, s25, v[0:1]
	v_cndmask_b32_e32 v21, v42, v38, vcc
	v_cndmask_b32_e32 v0, v44, v40, vcc
	v_cndmask_b32_e32 v25, v45, v42, vcc
	v_cndmask_b32_e64 v23, v0, v21, s[6:7]
	v_cndmask_b32_e64 v0, v25, v0, s[6:7]
	v_cndmask_b32_e32 v25, v40, v24, vcc
	v_cndmask_b32_e64 v21, v21, v25, s[6:7]
	v_sub_u32_e32 v37, 32, v19
	v_cmp_eq_u32_e64 s[10:11], 0, v19
	v_cndmask_b32_e32 v19, v38, v22, vcc
	v_cndmask_b32_e64 v0, v0, v23, s[8:9]
	v_cndmask_b32_e64 v23, v23, v21, s[8:9]
	v_cndmask_b32_e64 v22, v25, v19, s[6:7]
	v_alignbit_b32 v39, v0, v23, v37
	v_cndmask_b32_e64 v21, v21, v22, s[8:9]
	v_cndmask_b32_e64 v0, v39, v0, s[10:11]
	v_alignbit_b32 v25, v23, v21, v37
	v_cndmask_b32_e32 v20, v24, v20, vcc
	v_cndmask_b32_e64 v23, v25, v23, s[10:11]
	v_bfe_u32 v39, v0, 29, 1
	v_cndmask_b32_e64 v19, v19, v20, s[6:7]
	v_alignbit_b32 v25, v0, v23, 30
	v_sub_u32_e32 v40, 0, v39
	v_cndmask_b32_e64 v19, v22, v19, s[8:9]
	v_xor_b32_e32 v25, v25, v40
	v_alignbit_b32 v20, v21, v19, v37
	v_cndmask_b32_e64 v20, v20, v21, s[10:11]
	v_ffbh_u32_e32 v22, v25
	v_alignbit_b32 v21, v23, v20, 30
	v_min_u32_e32 v22, 32, v22
	v_alignbit_b32 v19, v20, v19, 30
	v_xor_b32_e32 v21, v21, v40
	v_sub_u32_e32 v23, 31, v22
	v_xor_b32_e32 v19, v19, v40
	v_alignbit_b32 v24, v25, v21, v23
	v_alignbit_b32 v19, v21, v19, v23
	v_alignbit_b32 v20, v24, v19, 9
	v_ffbh_u32_e32 v21, v20
	v_min_u32_e32 v21, 32, v21
	v_lshrrev_b32_e32 v38, 29, v0
	v_not_b32_e32 v23, v21
	v_alignbit_b32 v19, v20, v19, v23
	v_lshlrev_b32_e32 v20, 31, v38
	v_or_b32_e32 v23, 0x33000000, v20
	v_add_lshl_u32 v21, v21, v22, 23
	v_lshrrev_b32_e32 v19, 9, v19
	v_sub_u32_e32 v21, v23, v21
	v_or_b32_e32 v20, 0.5, v20
	v_lshlrev_b32_e32 v22, 23, v22
	v_or_b32_e32 v19, v21, v19
	v_lshrrev_b32_e32 v21, 9, v24
	v_sub_u32_e32 v20, v20, v22
	v_or_b32_e32 v20, v21, v20
	v_mul_f32_e32 v21, 0x3fc90fda, v20
	v_fma_f32 v22, v20, s26, -v21
	v_fmac_f32_e32 v22, 0x33a22168, v20
	v_fmac_f32_e32 v22, 0x3fc90fda, v19
	v_lshrrev_b32_e32 v0, 30, v0
	v_add_f32_e32 v19, v21, v22
	v_add_u32_e32 v0, v39, v0
.LBB0_853:
	s_andn2_saveexec_b64 s[6:7], s[18:19]
	v_mul_f32_e64 v0, |v15|, s27
	v_rndne_f32_e32 v20, v0
	v_cvt_i32_f32_e32 v0, v20
	v_fma_f32 v19, v20, s28, |v15|
	v_fmac_f32_e32 v19, 0xb3a22168, v20
	v_fmac_f32_e32 v19, 0xa7c234c4, v20
	s_or_b64 exec, exec, s[6:7]
	v_mul_f32_e32 v20, v19, v19
	v_fmamk_f32 v21, v20, 0xb94c1982, v32
	v_fmaak_f32 v21, v20, v21, 0xbe2aaa9d
	v_mul_f32_e32 v21, v20, v21
	v_fmac_f32_e32 v19, v19, v21
	v_fmamk_f32 v21, v20, 0x37d75334, v33
	v_fmaak_f32 v21, v20, v21, 0x3d2aabf7
	v_fmaak_f32 v21, v20, v21, 0xbf000004
	v_fma_f32 v20, v20, v21, 1.0
	v_and_b32_e32 v21, 1, v0
	v_lshlrev_b32_e32 v0, 30, v0
	v_cmp_eq_u32_e32 vcc, 0, v21
	v_and_b32_e32 v0, 0x80000000, v0
	v_xor_b32_e32 v18, v18, v15
	v_cndmask_b32_e32 v19, v20, v19, vcc
	v_xor_b32_e32 v0, v18, v0
	v_xor_b32_e32 v0, v0, v19
	v_cmp_class_f32_e64 vcc, v15, s29
	s_barrier
	s_nop 0
	v_cndmask_b32_e32 v0, v36, v0, vcc
	v_cvt_f64_f32_e32 v[18:19], v0
	ds_write_b64 v29, v[18:19]
	s_waitcnt lgkmcnt(0)
	s_barrier
	ds_read_b128 v[180:183], v28
	ds_read_b128 v[184:187], v28 offset:16
	ds_read_b128 v[188:191], v28 offset:32
	ds_read_b128 v[192:195], v28 offset:48
	ds_read2st64_b32 v[196:197], v27 offset0:113 offset1:114
	ds_read2st64_b32 v[198:199], v27 offset0:115 offset1:116
	ds_read2st64_b32 v[200:201], v27 offset0:117 offset1:118
	ds_read2st64_b32 v[202:203], v27 offset0:119 offset1:120
	ds_read_b128 v[204:207], v28 offset:64
	ds_read2st64_b32 v[208:209], v27 offset0:121 offset1:122
	ds_read_b128 v[212:215], v28 offset:80
	ds_read2st64_b32 v[210:211], v27 offset0:123 offset1:124
	ds_read_b128 v[216:219], v28 offset:96
	ds_read2st64_b32 v[220:221], v27 offset0:125 offset1:126
	ds_read_b128 v[224:227], v28 offset:112
	s_waitcnt lgkmcnt(14)
	ds_read2st64_b32 v[222:223], v27 offset0:127 offset1:128
	global_load_dword v107, v[10:11], off
	s_waitcnt lgkmcnt(14)
	ds_read_b128 v[228:231], v28 offset:128
	s_waitcnt lgkmcnt(14)
	ds_read2st64_b32 v[232:233], v27 offset0:129 offset1:130
	s_waitcnt lgkmcnt(15)
	s_waitcnt lgkmcnt(13)
	v_cvt_f64_f32_e32 v[50:51], v196
	s_waitcnt vmcnt(1)
	s_waitcnt vmcnt(0)
	v_cvt_f64_f32_e32 v[18:19], v107
	v_fmac_f64_e32 v[18:19], v[180:181], v[50:51]
	v_cvt_f64_f32_e32 v[20:21], v197
	s_nop 0
	v_fma_f64 v[20:21], v[182:183], v[20:21], 0
	ds_read_b128 v[180:183], v28 offset:144
	ds_read2st64_b32 v[196:197], v27 offset0:131 offset1:132
	s_waitcnt lgkmcnt(14)
	v_cvt_f64_f32_e32 v[22:23], v198
	v_fma_f64 v[22:23], v[184:185], v[22:23], 0
	v_cvt_f64_f32_e32 v[24:25], v199
	s_nop 0
	v_fma_f64 v[24:25], v[186:187], v[24:25], 0
	ds_read_b128 v[184:187], v28 offset:160
	s_waitcnt lgkmcnt(14)
	ds_read2st64_b32 v[198:199], v27 offset0:133 offset1:134
	v_cvt_f64_f32_e32 v[40:41], v200
	v_cvt_f64_f32_e32 v[38:39], v201
	s_nop 0
	v_fmac_f64_e32 v[20:21], v[190:191], v[38:39]
	v_fmac_f64_e32 v[18:19], v[188:189], v[40:41]
	s_waitcnt lgkmcnt(14)
	ds_read_b128 v[188:191], v28 offset:176
	s_waitcnt lgkmcnt(14)
	ds_read2st64_b32 v[200:201], v27 offset0:135 offset1:136
	v_cvt_f64_f32_e32 v[40:41], v202
	v_cvt_f64_f32_e32 v[38:39], v203
	s_nop 0
	v_fmac_f64_e32 v[22:23], v[192:193], v[40:41]
	v_fmac_f64_e32 v[24:25], v[194:195], v[38:39]
	s_waitcnt lgkmcnt(14)
	ds_read_b128 v[192:195], v28 offset:192
	s_waitcnt lgkmcnt(14)
	ds_read2st64_b32 v[202:203], v27 offset0:137 offset1:138
	v_cvt_f64_f32_e32 v[44:45], v208
	v_fmac_f64_e32 v[18:19], v[204:205], v[44:45]
	v_cvt_f64_f32_e32 v[38:39], v209
	s_nop 0
	v_fmac_f64_e32 v[20:21], v[206:207], v[38:39]
	s_waitcnt lgkmcnt(14)
	ds_read_b128 v[204:207], v28 offset:208
	s_waitcnt lgkmcnt(14)
	ds_read2st64_b32 v[208:209], v27 offset0:139 offset1:140
	v_cvt_f64_f32_e32 v[44:45], v210
	v_fmac_f64_e32 v[22:23], v[212:213], v[44:45]
	v_cvt_f64_f32_e32 v[38:39], v211
	s_nop 0
	v_fmac_f64_e32 v[24:25], v[214:215], v[38:39]
	s_waitcnt lgkmcnt(14)
	ds_read_b128 v[212:215], v28 offset:224
	s_waitcnt lgkmcnt(14)
	ds_read2st64_b32 v[210:211], v27 offset0:141 offset1:142
	v_cvt_f64_f32_e32 v[44:45], v220
	v_fmac_f64_e32 v[18:19], v[216:217], v[44:45]
	v_cvt_f64_f32_e32 v[38:39], v221
	s_nop 0
	v_fmac_f64_e32 v[20:21], v[218:219], v[38:39]
	s_waitcnt lgkmcnt(14)
	ds_read_b128 v[216:219], v28 offset:240
	s_waitcnt lgkmcnt(14)
	ds_read2st64_b32 v[220:221], v27 offset0:143 offset1:144
	v_cvt_f64_f32_e32 v[44:45], v222
	v_fmac_f64_e32 v[22:23], v[224:225], v[44:45]
	v_cvt_f64_f32_e32 v[38:39], v223
	s_nop 0
	v_fmac_f64_e32 v[24:25], v[226:227], v[38:39]
	s_waitcnt lgkmcnt(14)
	ds_read_b128 v[224:227], v28 offset:256
	s_waitcnt lgkmcnt(14)
	ds_read2st64_b32 v[222:223], v27 offset0:145 offset1:146
	v_cvt_f64_f32_e32 v[44:45], v232
	v_fmac_f64_e32 v[18:19], v[228:229], v[44:45]
	v_cvt_f64_f32_e32 v[38:39], v233
	s_waitcnt lgkmcnt(14)
	ds_read_b128 v[232:235], v28 offset:272
	s_waitcnt lgkmcnt(14)
	ds_read2st64_b32 v[236:237], v27 offset0:147 offset1:148
	v_fmac_f64_e32 v[20:21], v[230:231], v[38:39]
	s_waitcnt lgkmcnt(14)
	ds_read_b128 v[228:231], v28 offset:288
	v_cvt_f64_f32_e32 v[44:45], v196
	v_fmac_f64_e32 v[22:23], v[180:181], v[44:45]
	v_cvt_f64_f32_e32 v[38:39], v197
	s_waitcnt lgkmcnt(14)
	ds_read2st64_b32 v[196:197], v27 offset0:149 offset1:150
	v_fmac_f64_e32 v[24:25], v[182:183], v[38:39]
	s_waitcnt lgkmcnt(14)
	ds_read_b128 v[180:183], v28 offset:304
	v_cvt_f64_f32_e32 v[44:45], v198
	v_fmac_f64_e32 v[18:19], v[184:185], v[44:45]
	v_cvt_f64_f32_e32 v[38:39], v199
	s_waitcnt lgkmcnt(14)
	ds_read2st64_b32 v[198:199], v27 offset0:151 offset1:152
	v_fmac_f64_e32 v[20:21], v[186:187], v[38:39]
	s_waitcnt lgkmcnt(14)
	ds_read_b128 v[184:187], v28 offset:320
	v_cvt_f64_f32_e32 v[44:45], v200
	v_fmac_f64_e32 v[22:23], v[188:189], v[44:45]
	v_cvt_f64_f32_e32 v[38:39], v201
	s_waitcnt lgkmcnt(14)
	ds_read2st64_b32 v[200:201], v27 offset0:153 offset1:154
	v_fmac_f64_e32 v[24:25], v[190:191], v[38:39]
	s_waitcnt lgkmcnt(14)
	ds_read_b128 v[188:191], v28 offset:336
	v_cvt_f64_f32_e32 v[44:45], v202
	v_fmac_f64_e32 v[18:19], v[192:193], v[44:45]
	v_cvt_f64_f32_e32 v[38:39], v203
	s_waitcnt lgkmcnt(14)
	ds_read2st64_b32 v[202:203], v27 offset0:155 offset1:156
	v_fmac_f64_e32 v[20:21], v[194:195], v[38:39]
	s_waitcnt lgkmcnt(14)
	ds_read_b128 v[192:195], v28 offset:352
	v_cvt_f64_f32_e32 v[44:45], v208
	v_fmac_f64_e32 v[22:23], v[204:205], v[44:45]
	v_cvt_f64_f32_e32 v[38:39], v209
	s_waitcnt lgkmcnt(14)
	ds_read2st64_b32 v[208:209], v27 offset0:157 offset1:158
	v_fmac_f64_e32 v[24:25], v[206:207], v[38:39]
	s_waitcnt lgkmcnt(14)
	ds_read_b128 v[204:207], v28 offset:368
	v_cvt_f64_f32_e32 v[44:45], v210
	v_fmac_f64_e32 v[18:19], v[212:213], v[44:45]
	v_cvt_f64_f32_e32 v[38:39], v211
	s_waitcnt lgkmcnt(14)
	ds_read2st64_b32 v[210:211], v27 offset0:159 offset1:160
	v_fmac_f64_e32 v[20:21], v[214:215], v[38:39]
	s_waitcnt lgkmcnt(14)
	ds_read_b128 v[212:215], v28 offset:384
	v_cvt_f64_f32_e32 v[44:45], v220
	v_fmac_f64_e32 v[22:23], v[216:217], v[44:45]
	v_cvt_f64_f32_e32 v[38:39], v221
	s_waitcnt lgkmcnt(14)
	ds_read2st64_b32 v[220:221], v27 offset0:161 offset1:162
	v_fmac_f64_e32 v[24:25], v[218:219], v[38:39]
	s_waitcnt lgkmcnt(14)
	ds_read_b128 v[216:219], v28 offset:400
	v_cvt_f64_f32_e32 v[44:45], v222
	v_fmac_f64_e32 v[18:19], v[224:225], v[44:45]
	v_cvt_f64_f32_e32 v[38:39], v223
	s_waitcnt lgkmcnt(14)
	ds_read2st64_b32 v[222:223], v27 offset0:163 offset1:164
	v_fmac_f64_e32 v[20:21], v[226:227], v[38:39]
	s_waitcnt lgkmcnt(14)
	ds_read_b128 v[224:227], v28 offset:416
	v_cvt_f64_f32_e32 v[44:45], v236
	v_fmac_f64_e32 v[22:23], v[232:233], v[44:45]
	v_cvt_f64_f32_e32 v[38:39], v237
	s_waitcnt lgkmcnt(14)
	ds_read2st64_b32 v[236:237], v27 offset0:165 offset1:166
	v_fmac_f64_e32 v[24:25], v[234:235], v[38:39]
	s_waitcnt lgkmcnt(14)
	ds_read_b128 v[232:235], v28 offset:432
	v_cvt_f64_f32_e32 v[44:45], v196
	v_fmac_f64_e32 v[18:19], v[228:229], v[44:45]
	v_cvt_f64_f32_e32 v[38:39], v197
	s_waitcnt lgkmcnt(14)
	ds_read2st64_b32 v[196:197], v27 offset0:167 offset1:168
	v_fmac_f64_e32 v[20:21], v[230:231], v[38:39]
	s_waitcnt lgkmcnt(14)
	ds_read_b128 v[228:231], v28 offset:448
	v_cvt_f64_f32_e32 v[44:45], v198
	v_fmac_f64_e32 v[22:23], v[180:181], v[44:45]
	v_cvt_f64_f32_e32 v[38:39], v199
	s_waitcnt lgkmcnt(14)
	ds_read2st64_b32 v[198:199], v27 offset0:169 offset1:170
	v_fmac_f64_e32 v[24:25], v[182:183], v[38:39]
	s_waitcnt lgkmcnt(14)
	ds_read_b128 v[180:183], v28 offset:464
	v_cvt_f64_f32_e32 v[44:45], v200
	v_fmac_f64_e32 v[18:19], v[184:185], v[44:45]
	v_cvt_f64_f32_e32 v[38:39], v201
	s_waitcnt lgkmcnt(14)
	ds_read2st64_b32 v[200:201], v27 offset0:171 offset1:172
	v_fmac_f64_e32 v[20:21], v[186:187], v[38:39]
	s_waitcnt lgkmcnt(14)
	ds_read_b128 v[184:187], v28 offset:480
	v_cvt_f64_f32_e32 v[44:45], v202
	v_fmac_f64_e32 v[22:23], v[188:189], v[44:45]
	v_cvt_f64_f32_e32 v[38:39], v203
	s_waitcnt lgkmcnt(14)
	ds_read2st64_b32 v[202:203], v27 offset0:173 offset1:174
	v_fmac_f64_e32 v[24:25], v[190:191], v[38:39]
	s_waitcnt lgkmcnt(14)
	ds_read_b128 v[188:191], v28 offset:496
	v_cvt_f64_f32_e32 v[44:45], v208
	v_fmac_f64_e32 v[18:19], v[192:193], v[44:45]
	v_cvt_f64_f32_e32 v[38:39], v209
	s_waitcnt lgkmcnt(14)
	ds_read2st64_b32 v[208:209], v27 offset0:175 offset1:176
	v_fmac_f64_e32 v[20:21], v[194:195], v[38:39]
	v_cvt_f64_f32_e32 v[44:45], v210
	v_fmac_f64_e32 v[22:23], v[204:205], v[44:45]
	v_cvt_f64_f32_e32 v[38:39], v211
	s_nop 0
	v_fmac_f64_e32 v[24:25], v[206:207], v[38:39]
	s_waitcnt lgkmcnt(14)
	v_cvt_f64_f32_e32 v[44:45], v220
	v_fmac_f64_e32 v[18:19], v[212:213], v[44:45]
	v_cvt_f64_f32_e32 v[38:39], v221
	v_fmac_f64_e32 v[20:21], v[214:215], v[38:39]
	s_waitcnt lgkmcnt(12)
	v_cvt_f64_f32_e32 v[44:45], v222
	v_fmac_f64_e32 v[22:23], v[216:217], v[44:45]
	v_cvt_f64_f32_e32 v[38:39], v223
	v_fmac_f64_e32 v[24:25], v[218:219], v[38:39]
	s_waitcnt lgkmcnt(10)
	v_cvt_f64_f32_e32 v[44:45], v236
	v_fmac_f64_e32 v[18:19], v[224:225], v[44:45]
	v_cvt_f64_f32_e32 v[38:39], v237
	v_fmac_f64_e32 v[20:21], v[226:227], v[38:39]
	s_waitcnt lgkmcnt(8)
	v_cvt_f64_f32_e32 v[44:45], v196
	v_fmac_f64_e32 v[22:23], v[232:233], v[44:45]
	v_cvt_f64_f32_e32 v[38:39], v197
	v_fmac_f64_e32 v[24:25], v[234:235], v[38:39]
	s_waitcnt lgkmcnt(6)
	v_cvt_f64_f32_e32 v[44:45], v198
	v_fmac_f64_e32 v[18:19], v[228:229], v[44:45]
	v_cvt_f64_f32_e32 v[38:39], v199
	v_fmac_f64_e32 v[20:21], v[230:231], v[38:39]
	s_waitcnt lgkmcnt(4)
	v_cvt_f64_f32_e32 v[44:45], v200
	v_fmac_f64_e32 v[22:23], v[180:181], v[44:45]
	v_cvt_f64_f32_e32 v[38:39], v201
	v_fmac_f64_e32 v[24:25], v[182:183], v[38:39]
	s_waitcnt lgkmcnt(2)
	v_cvt_f64_f32_e32 v[44:45], v202
	v_fmac_f64_e32 v[18:19], v[184:185], v[44:45]
	v_cvt_f64_f32_e32 v[38:39], v203
	v_fmac_f64_e32 v[20:21], v[186:187], v[38:39]
	s_nop 1
	v_add_f64 v[18:19], v[18:19], v[20:21]
	s_waitcnt lgkmcnt(0)
	v_cvt_f64_f32_e32 v[44:45], v208
	v_fmac_f64_e32 v[22:23], v[188:189], v[44:45]
	v_cvt_f64_f32_e32 v[38:39], v209
	v_fmac_f64_e32 v[24:25], v[190:191], v[38:39]
	v_add_f64 v[20:21], v[22:23], v[24:25]
	v_add_f64 v[18:19], v[18:19], v[20:21]
	v_mul_f64 v[16:17], v[18:19], v[16:17]
	v_mul_f64 v[18:19], v[16:17], s[16:17]
	v_rndne_f64_e32 v[18:19], v[18:19]
	v_fmac_f64_e32 v[16:17], s[14:15], v[18:19]
	v_cvt_f32_f64_e32 v15, v[16:17]
	v_and_b32_e32 v16, 0x7fffffff, v15
	v_cmp_nlt_f32_e64 s[6:7], |v15|, s2
	s_and_saveexec_b64 s[8:9], s[6:7]
	s_xor_b64 s[18:19], exec, s[8:9]
	s_cbranch_execz .LBB0_857
	v_lshrrev_b32_e32 v0, 23, v16
	v_add_u32_e32 v0, 0xffffff88, v0
	v_cmp_lt_u32_e32 vcc, 63, v0
	s_nop 1
	v_cndmask_b32_e32 v17, 0, v34, vcc
	v_add_u32_e32 v0, v17, v0
	v_cmp_lt_u32_e64 s[6:7], 31, v0
	s_nop 1
	v_cndmask_b32_e64 v17, 0, v35, s[6:7]
	v_add_u32_e32 v0, v17, v0
	v_cmp_lt_u32_e64 s[8:9], 31, v0
	s_nop 1
	v_cndmask_b32_e64 v17, 0, v35, s[8:9]
	v_add_u32_e32 v17, v17, v0
	v_and_b32_e32 v0, 0x7fffff, v16
	v_or_b32_e32 v37, 0x800000, v0
	v_mad_u64_u32 v[18:19], s[10:11], v37, s3, 0
	v_mov_b32_e32 v0, v19
	v_mad_u64_u32 v[20:21], s[10:11], v37, s4, v[0:1]
	v_mov_b32_e32 v0, v21
	v_mad_u64_u32 v[22:23], s[10:11], v37, s5, v[0:1]
	v_mov_b32_e32 v0, v23
	v_mad_u64_u32 v[24:25], s[10:11], v37, s22, v[0:1]
	v_mov_b32_e32 v0, v25
	v_mad_u64_u32 v[38:39], s[10:11], v37, s23, v[0:1]
	v_mov_b32_e32 v0, v39
	v_mad_u64_u32 v[40:41], s[10:11], v37, s24, v[0:1]
	v_mov_b32_e32 v0, v41
	v_mad_u64_u32 v[42:43], s[10:11], v37, s25, v[0:1]
	v_cndmask_b32_e32 v19, v40, v24, vcc
	v_cndmask_b32_e32 v0, v42, v38, vcc
	v_cndmask_b32_e32 v23, v43, v40, vcc
	v_cndmask_b32_e64 v21, v0, v19, s[6:7]
	v_cndmask_b32_e64 v0, v23, v0, s[6:7]
	v_cndmask_b32_e32 v23, v38, v22, vcc
	v_cndmask_b32_e64 v19, v19, v23, s[6:7]
	v_sub_u32_e32 v25, 32, v17
	v_cmp_eq_u32_e64 s[10:11], 0, v17
	v_cndmask_b32_e32 v17, v24, v20, vcc
	v_cndmask_b32_e64 v0, v0, v21, s[8:9]
	v_cndmask_b32_e64 v21, v21, v19, s[8:9]
	v_cndmask_b32_e64 v20, v23, v17, s[6:7]
	v_alignbit_b32 v37, v0, v21, v25
	v_cndmask_b32_e64 v19, v19, v20, s[8:9]
	v_cndmask_b32_e64 v0, v37, v0, s[10:11]
	v_alignbit_b32 v23, v21, v19, v25
	v_cndmask_b32_e32 v18, v22, v18, vcc
	v_cndmask_b32_e64 v21, v23, v21, s[10:11]
	v_bfe_u32 v37, v0, 29, 1
	v_cndmask_b32_e64 v17, v17, v18, s[6:7]
	v_alignbit_b32 v23, v0, v21, 30
	v_sub_u32_e32 v38, 0, v37
	v_cndmask_b32_e64 v17, v20, v17, s[8:9]
	v_xor_b32_e32 v23, v23, v38
	v_alignbit_b32 v18, v19, v17, v25
	v_cndmask_b32_e64 v18, v18, v19, s[10:11]
	v_ffbh_u32_e32 v20, v23
	v_alignbit_b32 v19, v21, v18, 30
	v_min_u32_e32 v20, 32, v20
	v_alignbit_b32 v17, v18, v17, 30
	v_xor_b32_e32 v19, v19, v38
	v_sub_u32_e32 v21, 31, v20
	v_xor_b32_e32 v17, v17, v38
	v_alignbit_b32 v22, v23, v19, v21
	v_alignbit_b32 v17, v19, v17, v21
	v_alignbit_b32 v18, v22, v17, 9
	v_ffbh_u32_e32 v19, v18
	v_min_u32_e32 v19, 32, v19
	v_lshrrev_b32_e32 v24, 29, v0
	v_not_b32_e32 v21, v19
	v_alignbit_b32 v17, v18, v17, v21
	v_lshlrev_b32_e32 v18, 31, v24
	v_or_b32_e32 v21, 0x33000000, v18
	v_add_lshl_u32 v19, v19, v20, 23
	v_lshrrev_b32_e32 v17, 9, v17
	v_sub_u32_e32 v19, v21, v19
	v_or_b32_e32 v18, 0.5, v18
	v_lshlrev_b32_e32 v20, 23, v20
	v_or_b32_e32 v17, v19, v17
	v_lshrrev_b32_e32 v19, 9, v22
	v_sub_u32_e32 v18, v18, v20
	v_or_b32_e32 v18, v19, v18
	v_mul_f32_e32 v19, 0x3fc90fda, v18
	v_fma_f32 v20, v18, s26, -v19
	v_fmac_f32_e32 v20, 0x33a22168, v18
	v_fmac_f32_e32 v20, 0x3fc90fda, v17
	v_lshrrev_b32_e32 v0, 30, v0
	v_add_f32_e32 v17, v19, v20
	v_add_u32_e32 v0, v37, v0

.LBB0_1571:
	v_readlane_b32 s4, v239, 35
	s_lshl_b64 s[60:61], s[40:41], 2
	v_readlane_b32 s6, v239, 37
	v_readlane_b32 s8, v239, 39
	v_readlane_b32 s7, v239, 38
	v_readlane_b32 s9, v239, 40
	s_add_u32 s8, s6, s60
	s_waitcnt lgkmcnt(0)
	s_barrier
	v_readlane_b32 s5, v239, 36
	v_readlane_b32 s10, v239, 41
	v_readlane_b32 s11, v239, 42
	v_readlane_b32 s12, v239, 43
	v_readlane_b32 s13, v239, 44
	v_readlane_b32 s14, v239, 45
	v_readlane_b32 s15, v239, 46
	v_readlane_b32 s16, v239, 47
	v_readlane_b32 s17, v239, 48
	v_readlane_b32 s18, v239, 49
	v_readlane_b32 s19, v239, 50
	s_addc_u32 s9, s7, s61
	global_load_dword v66, v39, s[8:9]
	global_load_dword v3, v43, s[8:9]
	v_readlane_b32 s4, v240, 22
	s_mul_i32 s23, s40, 0x8800
	v_readlane_b32 s8, v240, 26
	v_readlane_b32 s12, v240, 30
	s_mul_hi_i32 s41, s40, 0x8800
	v_readlane_b32 s9, v240, 27
	v_readlane_b32 s13, v240, 31
	s_add_u32 s8, s12, s23
	s_addc_u32 s9, s13, s41
	v_lshl_add_u64 v[4:5], v[64:65], 2, s[8:9]
	v_add_co_u32_e32 v0, vcc, s94, v4
	global_load_dwordx3 v[56:58], v[4:5], off offset:-4
	global_load_dwordx3 v[52:54], v[4:5], off offset:2044
	v_addc_co_u32_e32 v1, vcc, 0, v5, vcc
	v_add_co_u32_e32 v8, vcc, s1, v4
	v_mov_b32_e32 v114, v64
	s_nop 0
	v_addc_co_u32_e32 v9, vcc, 0, v5, vcc
	v_add_co_u32_e32 v10, vcc, s69, v4
	global_load_dwordx3 v[60:62], v[0:1], off offset:4092
	global_load_dwordx3 v[48:50], v[8:9], off offset:2044
	v_addc_co_u32_e32 v11, vcc, 0, v5, vcc
	global_load_dwordx3 v[40:42], v[8:9], off offset:4092
	global_load_dwordx3 v[36:38], v[10:11], off offset:2044
	v_add_co_u32_e32 v8, vcc, s24, v4
	v_mov_b32_e32 v100, 0
	s_nop 0
	v_addc_co_u32_e32 v9, vcc, 0, v5, vcc
	global_load_dwordx3 v[32:34], v[8:9], off offset:2044
	global_load_dwordx3 v[28:30], v[10:11], off offset:4092
	v_add_co_u32_e32 v10, vcc, s73, v4
	v_mov_b32_e32 v101, 0
	s_nop 0
	v_addc_co_u32_e32 v11, vcc, 0, v5, vcc
	global_load_dwordx3 v[24:26], v[8:9], off offset:4092
	global_load_dwordx3 v[20:22], v[10:11], off offset:2044
	v_add_co_u32_e32 v8, vcc, s46, v4
	v_mov_b32_e32 v74, 0
	s_nop 0
	v_addc_co_u32_e32 v9, vcc, 0, v5, vcc
	global_load_dwordx3 v[16:18], v[8:9], off offset:2044
	global_load_dwordx3 v[12:14], v[10:11], off offset:4092
	global_load_dwordx3 v[44:46], v[4:5], off offset:4092
	s_nop 0
	global_load_dwordx3 v[0:2], v[0:1], off offset:2044
	v_add_co_u32_e32 v4, vcc, s47, v4
	v_mov_b32_e32 v75, v100
	s_nop 0
	v_addc_co_u32_e32 v5, vcc, 0, v5, vcc
	global_load_dwordx3 v[8:10], v[8:9], off offset:4092
	s_nop 0
	global_load_dwordx3 v[4:6], v[4:5], off offset:2044
	v_mov_b32_e32 v82, v100
	v_add_u32_e32 v23, 0x1000, v114
	v_lshl_add_u32 v122, v114, 3, s3
	v_ashrrev_i32_e32 v23, 4, v23
	v_lshl_add_u32 v116, v23, 3, v122
	v_add_u32_e32 v23, 0x1200, v114
	v_ashrrev_i32_e32 v23, 4, v23
	v_lshl_add_u32 v113, v23, 3, v122
	v_add_u32_e32 v23, 0x1400, v114
	v_ashrrev_i32_e32 v23, 4, v23
	v_lshl_add_u32 v111, v23, 3, v122
	v_add_u32_e32 v23, 0x1600, v114
	v_ashrrev_i32_e32 v23, 4, v23
	v_add_u32_e32 v112, 0x200, v114
	v_lshl_add_u32 v108, v23, 3, v122
	v_add_u32_e32 v23, 0x1800, v114
	v_ashrrev_i32_e32 v11, 4, v112
	v_add_u32_e32 v110, 0x400, v114
	v_ashrrev_i32_e32 v23, 4, v23
	v_lshl_add_u32 v109, v11, 3, v122
	v_ashrrev_i32_e32 v11, 4, v110
	v_add_u32_e32 v107, 0x600, v114
	v_lshl_add_u32 v105, v23, 3, v122
	v_add_u32_e32 v23, 0x1a00, v114
	v_lshl_add_u32 v106, v11, 3, v122
	v_ashrrev_i32_e32 v11, 4, v107
	v_add_u32_e32 v104, 0x800, v114
	v_ashrrev_i32_e32 v23, 4, v23
	v_lshl_add_u32 v103, v11, 3, v122
	v_ashrrev_i32_e32 v11, 4, v104
	v_add_u32_e32 v67, 0xa00, v114
	v_lshl_add_u32 v102, v23, 3, v122
	v_add_u32_e32 v23, 0x1c00, v114
	v_lshl_add_u32 v65, v11, 3, v122
	v_ashrrev_i32_e32 v11, 4, v67
	v_add_u32_e32 v31, 0xc00, v114
	v_ashrrev_i32_e32 v23, 4, v23
	v_lshl_add_u32 v27, v11, 3, v122
	v_ashrrev_i32_e32 v11, 4, v31
	v_add_u32_e32 v19, 0xe00, v114
	v_lshl_add_u32 v63, v23, 3, v122
	v_add_u32_e32 v23, 0x1e00, v114
	v_ashrrev_i32_e32 v115, 4, v114
	v_lshl_add_u32 v15, v11, 3, v122
	v_ashrrev_i32_e32 v11, 4, v19
	v_ashrrev_i32_e32 v23, 4, v23
	v_cmp_gt_i32_e32 vcc, s70, v114
	v_lshl_add_u32 v117, v115, 3, v122
	v_lshl_add_u32 v11, v11, 3, v122
	v_lshl_add_u32 v23, v23, 3, v122
	v_mov_b32_e32 v83, v100
	v_mov_b32_e32 v90, v100
	v_mov_b32_e32 v91, v100
	v_mov_b32_e32 v96, v100
	v_mov_b32_e32 v97, v100
	v_mov_b32_e32 v72, v100
	v_mov_b32_e32 v73, v100
	v_mov_b32_e32 v80, v100
	v_mov_b32_e32 v81, v100
	v_mov_b32_e32 v88, v100
	v_mov_b32_e32 v89, v100
	v_mov_b32_e32 v94, v100
	v_mov_b32_e32 v95, v100
	v_mov_b32_e32 v70, v100
	v_mov_b32_e32 v71, v100
	v_mov_b32_e32 v78, v100
	v_mov_b32_e32 v79, v100
	v_mov_b32_e32 v86, v100
	v_mov_b32_e32 v87, v100
	v_mov_b32_e32 v92, v100
	v_mov_b32_e32 v93, v100
	v_mov_b32_e32 v68, v100
	v_mov_b32_e32 v69, v100
	v_mov_b32_e32 v76, v100
	v_mov_b32_e32 v77, v100
	v_mov_b32_e32 v84, v100
	v_mov_b32_e32 v85, v100
	v_mov_b32_e32 v98, v100
	v_mov_b32_e32 v99, v100
	v_readlane_b32 s5, v240, 23
	v_readlane_b32 s6, v240, 24
	v_readlane_b32 s7, v240, 25
	v_readlane_b32 s10, v240, 28
	v_readlane_b32 s11, v240, 29
	v_readlane_b32 s14, v240, 32
	v_readlane_b32 s15, v240, 33
	v_readlane_b32 s16, v240, 34
	v_readlane_b32 s17, v240, 35
	v_readlane_b32 s18, v240, 36
	v_readlane_b32 s19, v240, 37
	s_and_saveexec_b64 s[8:9], vcc
	s_cbranch_execz .LBB0_1573
	ds_read_b64 v[172:173], v117
	ds_read_b64 v[174:175], v109 offset:4096
	ds_read_b64 v[176:177], v106 offset:8192
	ds_read_b64 v[178:179], v103 offset:12288
	ds_read_b64 v[180:181], v65 offset:16384
	ds_read_b64 v[182:183], v27 offset:20480
	ds_read_b64 v[184:185], v15 offset:24576
	ds_read_b64 v[186:187], v11 offset:28672
	ds_read_b64 v[188:189], v116 offset:32768
	ds_read_b64 v[190:191], v113 offset:36864
	ds_read_b64 v[192:193], v111 offset:40960
	ds_read_b64 v[194:195], v108 offset:45056
	ds_read_b64 v[196:197], v105 offset:49152
	ds_read_b64 v[198:199], v102 offset:53248
	ds_read_b64 v[200:201], v63 offset:57344
	s_waitcnt lgkmcnt(14)
	ds_read_b64 v[202:203], v23 offset:61440
	s_waitcnt lgkmcnt(15)
	s_waitcnt lgkmcnt(7)
	v_pk_add_f32 v[100:101], v[172:173], v[188:189]
	v_pk_add_f32 v[124:125], v[172:173], v[188:189] neg_lo:[0,1] neg_hi:[0,1]
	s_waitcnt lgkmcnt(3)
	v_pk_add_f32 v[68:69], v[180:181], v[196:197]
	v_pk_add_f32 v[76:77], v[180:181], v[196:197] neg_lo:[0,1] neg_hi:[0,1]
	v_pk_add_f32 v[84:85], v[100:101], v[68:69]
	v_pk_add_f32 v[92:93], v[100:101], v[68:69] neg_lo:[0,1] neg_hi:[0,1]
	v_pk_add_f32 v[68:69], v[174:175], v[190:191]
	v_pk_add_f32 v[126:127], v[174:175], v[190:191] neg_lo:[0,1] neg_hi:[0,1]
	s_waitcnt lgkmcnt(2)
	v_pk_add_f32 v[70:71], v[182:183], v[198:199]
	v_pk_add_f32 v[78:79], v[182:183], v[198:199] neg_lo:[0,1] neg_hi:[0,1]
	v_pk_add_f32 v[86:87], v[68:69], v[70:71]
	v_pk_add_f32 v[94:95], v[68:69], v[70:71] neg_lo:[0,1] neg_hi:[0,1]
	v_pk_add_f32 v[68:69], v[176:177], v[192:193]
	s_waitcnt lgkmcnt(1)
	v_pk_add_f32 v[70:71], v[184:185], v[200:201]
	v_pk_add_f32 v[130:131], v[176:177], v[192:193] neg_lo:[0,1] neg_hi:[0,1]
	v_pk_add_f32 v[72:73], v[184:185], v[200:201] neg_lo:[0,1] neg_hi:[0,1]
	v_pk_add_f32 v[80:81], v[68:69], v[70:71]
	v_pk_add_f32 v[88:89], v[68:69], v[70:71] neg_lo:[0,1] neg_hi:[0,1]
	v_pk_add_f32 v[68:69], v[178:179], v[194:195]
	s_waitcnt lgkmcnt(0)
	v_pk_add_f32 v[70:71], v[186:187], v[202:203]
	v_xor_b32_e32 v97, 0x80000000, v72
	v_mov_b32_e32 v96, v73
	v_pk_add_f32 v[134:135], v[178:179], v[194:195] neg_lo:[0,1] neg_hi:[0,1]
	v_pk_add_f32 v[72:73], v[186:187], v[202:203] neg_lo:[0,1] neg_hi:[0,1]
	v_pk_add_f32 v[74:75], v[68:69], v[70:71]
	v_xor_b32_e32 v129, 0x80000000, v78
	v_mov_b32_e32 v128, v79
	v_pk_add_f32 v[90:91], v[68:69], v[70:71] neg_lo:[0,1] neg_hi:[0,1]
	v_xor_b32_e32 v99, 0x80000000, v72
	v_mov_b32_e32 v98, v73
	v_pk_add_f32 v[68:69], v[84:85], v[80:81]
	v_pk_add_f32 v[70:71], v[86:87], v[74:75]
	v_pk_add_f32 v[72:73], v[86:87], v[74:75] neg_lo:[0,1] neg_hi:[0,1]
	v_pk_add_f32 v[78:79], v[126:127], v[128:129]
	v_pk_add_f32 v[80:81], v[84:85], v[80:81] neg_lo:[0,1] neg_hi:[0,1]
	v_pk_add_f32 v[74:75], v[68:69], v[70:71]
	v_pk_add_f32 v[70:71], v[68:69], v[70:71] neg_lo:[0,1] neg_hi:[0,1]
	v_xor_b32_e32 v69, 0x80000000, v72
	v_mov_b32_e32 v68, v73
	s_mov_b32 s29, s26
	v_pk_add_f32 v[132:133], v[130:131], v[96:97]
	v_pk_add_f32 v[82:83], v[134:135], v[98:99]
	v_pk_add_f32 v[72:73], v[80:81], v[68:69]
	v_pk_add_f32 v[68:69], v[80:81], v[68:69] neg_lo:[0,1] neg_hi:[0,1]
	v_pk_mul_f32 v[80:81], v[78:79], s[28:29] op_sel:[1,0]
	s_mov_b32 s10, s26
	s_mov_b32 s11, s28
	v_xor_b32_e32 v101, 0x80000000, v76
	v_mov_b32_e32 v100, v77
	v_pk_fma_f32 v[78:79], v[78:79], s[26:27], v[80:81] op_sel_hi:[0,1,1]
	v_mul_f32_e32 v80, 0x3f3504f3, v133
	s_mov_b32 s29, s34
	v_pk_mul_f32 v[84:85], v[82:83], s[10:11] op_sel:[1,0]
	v_pk_add_f32 v[76:77], v[124:125], v[100:101]
	v_pk_fma_f32 v[80:81], v[132:133], s[30:31], v[80:81] op_sel_hi:[0,1,0]
	v_pk_fma_f32 v[82:83], v[82:83], s[28:29], v[84:85] op_sel_hi:[0,1,1]
	v_pk_add_f32 v[84:85], v[76:77], v[80:81]
	v_pk_add_f32 v[76:77], v[76:77], v[80:81] neg_lo:[0,1] neg_hi:[0,1]
	v_pk_add_f32 v[80:81], v[78:79], v[82:83]
	v_pk_add_f32 v[86:87], v[78:79], v[82:83] neg_lo:[0,1] neg_hi:[0,1]
	s_mov_b32 s37, s20
	v_pk_add_f32 v[82:83], v[84:85], v[80:81]
	v_pk_add_f32 v[78:79], v[84:85], v[80:81] neg_lo:[0,1] neg_hi:[0,1]
	v_xor_b32_e32 v85, 0x80000000, v86
	v_mov_b32_e32 v84, v87
	v_pk_mul_f32 v[86:87], v[88:89], s[36:37] op_sel:[1,0]
	v_pk_add_f32 v[80:81], v[76:77], v[84:85]
	v_pk_add_f32 v[76:77], v[76:77], v[84:85] neg_lo:[0,1] neg_hi:[0,1]
	v_mul_f32_e32 v84, 0x3f3504f3, v95
	v_pk_fma_f32 v[86:87], v[88:89], s[20:21], v[86:87] op_sel_hi:[0,1,1]
	v_mul_f32_e32 v88, 0xbf3504f3, v90
	v_pk_fma_f32 v[84:85], v[94:95], s[30:31], v[84:85] op_sel_hi:[0,1,0]
	v_pk_fma_f32 v[88:89], v[90:91], s[30:31], v[88:89] op_sel:[1,0,0] op_sel_hi:[1,1,0]
	v_pk_add_f32 v[94:95], v[92:93], v[86:87]
	v_pk_add_f32 v[92:93], v[92:93], v[86:87] neg_lo:[0,1] neg_hi:[0,1]
	v_pk_add_f32 v[86:87], v[84:85], v[88:89]
	v_pk_add_f32 v[84:85], v[84:85], v[88:89] neg_lo:[0,1] neg_hi:[0,1]
	v_pk_add_f32 v[90:91], v[94:95], v[86:87]
	v_pk_add_f32 v[86:87], v[94:95], v[86:87] neg_lo:[0,1] neg_hi:[0,1]
	v_xor_b32_e32 v95, 0x80000000, v84
	v_mov_b32_e32 v94, v85
	v_pk_add_f32 v[88:89], v[92:93], v[94:95]
	v_pk_add_f32 v[84:85], v[92:93], v[94:95] neg_lo:[0,1] neg_hi:[0,1]
	v_pk_add_f32 v[92:93], v[134:135], v[98:99] neg_lo:[0,1] neg_hi:[0,1]
	s_mov_b32 s12, s27
	s_mov_b32 s13, s34
	s_mov_b32 s35, s28
	v_pk_mul_f32 v[94:95], v[92:93], s[12:13] op_sel:[1,0]
	v_pk_add_f32 v[98:99], v[126:127], v[128:129] neg_lo:[0,1] neg_hi:[0,1]
	v_pk_fma_f32 v[92:93], v[92:93], s[34:35], v[94:95] op_sel_hi:[0,1,1]
	v_pk_add_f32 v[94:95], v[124:125], v[100:101] neg_lo:[0,1] neg_hi:[0,1]
	v_pk_mul_f32 v[100:101], v[98:99], s[10:11] op_sel:[1,0]
	v_pk_add_f32 v[96:97], v[130:131], v[96:97] neg_lo:[0,1] neg_hi:[0,1]
	v_pk_fma_f32 v[98:99], v[98:99], s[28:29], v[100:101] op_sel_hi:[0,1,1]
	v_mul_f32_e32 v100, 0xbf3504f3, v96
	v_pk_fma_f32 v[96:97], v[96:97], s[30:31], v[100:101] op_sel:[1,0,0] op_sel_hi:[1,1,0]
	s_nop 0
	v_pk_add_f32 v[100:101], v[94:95], v[96:97]
	v_pk_add_f32 v[124:125], v[94:95], v[96:97] neg_lo:[0,1] neg_hi:[0,1]
	v_pk_add_f32 v[94:95], v[98:99], v[92:93]
	v_pk_add_f32 v[98:99], v[98:99], v[92:93] neg_lo:[0,1] neg_hi:[0,1]
	v_pk_add_f32 v[96:97], v[100:101], v[94:95]
	v_pk_add_f32 v[92:93], v[100:101], v[94:95] neg_lo:[0,1] neg_hi:[0,1]
	v_xor_b32_e32 v101, 0x80000000, v98
	v_mov_b32_e32 v100, v99
	v_pk_add_f32 v[94:95], v[124:125], v[100:101]
	v_pk_add_f32 v[100:101], v[124:125], v[100:101] neg_lo:[0,1] neg_hi:[0,1]
	s_nop 0
	v_mov_b32_e32 v98, v100
	v_mov_b32_e32 v99, v101

.LBB0_1575:
	s_or_b64 exec, exec, s[8:9]
	s_waitcnt lgkmcnt(0)
	s_barrier
	s_and_saveexec_b64 s[8:9], vcc
	s_cbranch_execz .LBB0_1577
	ds_read_b64 v[172:173], v23 offset:61440
	ds_read_b64 v[174:175], v63 offset:57344
	ds_read_b64 v[176:177], v102 offset:53248
	ds_read_b64 v[178:179], v105 offset:49152
	ds_read_b64 v[180:181], v108 offset:45056
	ds_read_b64 v[182:183], v111 offset:40960
	ds_read_b64 v[184:185], v117
	ds_read_b64 v[186:187], v109 offset:4096
	ds_read_b64 v[188:189], v106 offset:8192
	ds_read_b64 v[190:191], v103 offset:12288
	ds_read_b64 v[192:193], v65 offset:16384
	ds_read_b64 v[194:195], v27 offset:20480
	ds_read_b64 v[196:197], v15 offset:24576
	ds_read_b64 v[198:199], v11 offset:28672
	ds_read_b64 v[200:201], v116 offset:32768
	v_and_b32_e32 v68, 15, v114
	v_cvt_f32_ubyte0_e32 v68, v68
	v_mul_f32_e32 v68, 0x3b800000, v68
	v_cos_f32_e32 v84, v68
	v_sin_f32_e32 v92, v68
	s_mov_b32 s29, s26
	v_mov_b32_e32 v93, v84
	v_xor_b32_e32 v85, 0x80000000, v92
	v_pk_mul_f32 v[68:69], v[92:93], v[92:93] op_sel_hi:[1,0] neg_lo:[0,1] neg_hi:[0,1]
	s_mov_b32 s10, s26
	v_pk_fma_f32 v[90:91], v[84:85], v[84:85], v[68:69] op_sel_hi:[1,0,1]
	s_mov_b32 s11, s28
	v_pk_mul_f32 v[68:69], v[92:93], v[90:91] op_sel:[0,1]
	s_mov_b32 s37, s20
	v_pk_fma_f32 v[86:87], v[84:85], v[90:91], v[68:69] op_sel_hi:[1,0,1]
	s_mov_b32 s12, s27
	v_pk_mul_f32 v[68:69], v[92:93], v[86:87] op_sel:[0,1]
	s_mov_b32 s13, s34
	v_pk_fma_f32 v[82:83], v[84:85], v[86:87], v[68:69] op_sel_hi:[1,0,1]
	s_mov_b32 s35, s28
	v_pk_mul_f32 v[68:69], v[92:93], v[82:83] op_sel:[0,1]
	s_nop 0
	v_pk_fma_f32 v[80:81], v[84:85], v[82:83], v[68:69] op_sel_hi:[1,0,1]
	s_nop 0
	v_pk_mul_f32 v[68:69], v[92:93], v[80:81] op_sel:[0,1]
	s_nop 0
	v_pk_fma_f32 v[78:79], v[84:85], v[80:81], v[68:69] op_sel_hi:[1,0,1]
	s_nop 0
	v_pk_mul_f32 v[68:69], v[92:93], v[78:79] op_sel:[0,1]
	s_nop 0
	v_pk_fma_f32 v[76:77], v[84:85], v[78:79], v[68:69] op_sel_hi:[1,0,1]
	s_nop 0
	v_pk_mul_f32 v[68:69], v[92:93], v[76:77] op_sel:[0,1]
	s_nop 0
	v_pk_fma_f32 v[70:71], v[84:85], v[76:77], v[68:69] op_sel_hi:[1,0,1]
	s_nop 0
	v_pk_mul_f32 v[68:69], v[92:93], v[70:71] op_sel:[0,1]
	s_nop 0
	v_pk_fma_f32 v[68:69], v[84:85], v[70:71], v[68:69] op_sel_hi:[1,0,1]
	s_nop 0
	v_pk_mul_f32 v[72:73], v[92:93], v[68:69] op_sel:[0,1]
	s_nop 0
	v_pk_fma_f32 v[96:97], v[84:85], v[68:69], v[72:73] op_sel_hi:[1,0,1]
	s_nop 0
	v_pk_mul_f32 v[72:73], v[92:93], v[96:97] op_sel:[0,1]
	s_nop 0
	v_pk_fma_f32 v[94:95], v[84:85], v[96:97], v[72:73] op_sel_hi:[1,0,1]
	s_nop 0
	v_pk_mul_f32 v[72:73], v[92:93], v[94:95] op_sel:[0,1]
	s_nop 0
	v_pk_fma_f32 v[98:99], v[84:85], v[94:95], v[72:73] op_sel_hi:[1,0,1]
	s_nop 0
	v_pk_mul_f32 v[72:73], v[92:93], v[98:99] op_sel:[0,1]
	s_nop 0
	v_pk_fma_f32 v[88:89], v[84:85], v[98:99], v[72:73] op_sel_hi:[1,0,1]
	s_nop 0
	v_pk_mul_f32 v[72:73], v[92:93], v[88:89] op_sel:[0,1]
	s_nop 0
	v_pk_fma_f32 v[74:75], v[84:85], v[88:89], v[72:73] op_sel_hi:[1,0,1]
	s_nop 0
	v_pk_mul_f32 v[72:73], v[92:93], v[74:75] op_sel:[0,1]
	s_nop 0
	v_pk_fma_f32 v[72:73], v[84:85], v[74:75], v[72:73] op_sel_hi:[1,0,1]
	s_nop 0
	v_xor_b32_e32 v122, 0x80000000, v73
	v_mov_b32_e32 v123, v72
	s_waitcnt lgkmcnt(15)
	s_waitcnt lgkmcnt(14)
	v_pk_mul_f32 v[122:123], v[122:123], v[172:173] op_sel:[0,1]
	s_nop 0
	v_pk_fma_f32 v[72:73], v[72:73], v[172:173], v[122:123] op_sel_hi:[1,0,1]
	ds_read_b64 v[172:173], v113 offset:36864
	v_xor_b32_e32 v122, 0x80000000, v75
	v_mov_b32_e32 v123, v74
	s_waitcnt lgkmcnt(14)
	v_pk_mul_f32 v[122:123], v[122:123], v[174:175] op_sel:[0,1]
	s_nop 0
	v_pk_fma_f32 v[74:75], v[74:75], v[174:175], v[122:123] op_sel_hi:[1,0,1]
	v_xor_b32_e32 v122, 0x80000000, v89
	v_mov_b32_e32 v123, v88
	s_waitcnt lgkmcnt(13)
	v_pk_mul_f32 v[122:123], v[122:123], v[176:177] op_sel:[0,1]
	s_nop 0
	v_pk_fma_f32 v[88:89], v[88:89], v[176:177], v[122:123] op_sel_hi:[1,0,1]
	v_xor_b32_e32 v122, 0x80000000, v99
	v_mov_b32_e32 v123, v98
	s_waitcnt lgkmcnt(12)
	v_pk_mul_f32 v[122:123], v[122:123], v[178:179] op_sel:[0,1]
	s_nop 0
	v_pk_fma_f32 v[98:99], v[98:99], v[178:179], v[122:123] op_sel_hi:[1,0,1]
	v_xor_b32_e32 v122, 0x80000000, v95
	v_mov_b32_e32 v123, v94
	s_waitcnt lgkmcnt(11)
	v_pk_mul_f32 v[122:123], v[122:123], v[180:181] op_sel:[0,1]
	s_nop 0
	v_pk_fma_f32 v[94:95], v[94:95], v[180:181], v[122:123] op_sel_hi:[1,0,1]
	v_xor_b32_e32 v122, 0x80000000, v97
	v_mov_b32_e32 v123, v96
	s_waitcnt lgkmcnt(10)
	v_pk_mul_f32 v[122:123], v[122:123], v[182:183] op_sel:[0,1]
	s_nop 0
	v_pk_fma_f32 v[96:97], v[96:97], v[182:183], v[122:123] op_sel_hi:[1,0,1]
	s_waitcnt lgkmcnt(8)
	v_pk_mul_f32 v[92:93], v[92:93], v[186:187] op_sel:[0,1]
	s_nop 0
	v_pk_fma_f32 v[92:93], v[84:85], v[186:187], v[92:93] op_sel_hi:[1,0,1]
	v_xor_b32_e32 v122, 0x80000000, v91
	v_mov_b32_e32 v123, v90
	s_waitcnt lgkmcnt(7)
	v_pk_mul_f32 v[122:123], v[122:123], v[188:189] op_sel:[0,1]
	s_nop 0
	v_pk_fma_f32 v[90:91], v[90:91], v[188:189], v[122:123] op_sel_hi:[1,0,1]
	v_xor_b32_e32 v122, 0x80000000, v87
	v_mov_b32_e32 v123, v86
	s_waitcnt lgkmcnt(6)
	v_pk_mul_f32 v[122:123], v[122:123], v[190:191] op_sel:[0,1]
	s_nop 0
	v_pk_fma_f32 v[84:85], v[86:87], v[190:191], v[122:123] op_sel_hi:[1,0,1]
	v_xor_b32_e32 v122, 0x80000000, v83
	v_mov_b32_e32 v123, v82
	s_waitcnt lgkmcnt(5)
	v_pk_mul_f32 v[122:123], v[122:123], v[192:193] op_sel:[0,1]
	s_nop 0
	v_pk_fma_f32 v[82:83], v[82:83], v[192:193], v[122:123] op_sel_hi:[1,0,1]
	v_xor_b32_e32 v122, 0x80000000, v81
	v_mov_b32_e32 v123, v80
	s_waitcnt lgkmcnt(4)
	v_pk_mul_f32 v[122:123], v[122:123], v[194:195] op_sel:[0,1]
	s_nop 0
	v_pk_fma_f32 v[80:81], v[80:81], v[194:195], v[122:123] op_sel_hi:[1,0,1]
	v_xor_b32_e32 v122, 0x80000000, v79
	v_mov_b32_e32 v123, v78
	s_waitcnt lgkmcnt(3)
	v_pk_mul_f32 v[122:123], v[122:123], v[196:197] op_sel:[0,1]
	s_nop 0
	v_pk_fma_f32 v[78:79], v[78:79], v[196:197], v[122:123] op_sel_hi:[1,0,1]
	v_xor_b32_e32 v122, 0x80000000, v77
	v_mov_b32_e32 v123, v76
	s_waitcnt lgkmcnt(2)
	v_pk_mul_f32 v[122:123], v[122:123], v[198:199] op_sel:[0,1]
	s_nop 0
	v_pk_fma_f32 v[76:77], v[76:77], v[198:199], v[122:123] op_sel_hi:[1,0,1]
	v_xor_b32_e32 v122, 0x80000000, v71
	v_mov_b32_e32 v123, v70
	s_waitcnt lgkmcnt(1)
	v_pk_mul_f32 v[122:123], v[122:123], v[200:201] op_sel:[0,1]
	s_nop 0
	v_pk_fma_f32 v[70:71], v[70:71], v[200:201], v[122:123] op_sel_hi:[1,0,1]
	v_xor_b32_e32 v122, 0x80000000, v69
	v_mov_b32_e32 v123, v68
	s_waitcnt lgkmcnt(0)
	v_pk_mul_f32 v[122:123], v[122:123], v[172:173] op_sel:[0,1]
	s_nop 0
	v_pk_fma_f32 v[68:69], v[68:69], v[172:173], v[122:123] op_sel_hi:[1,0,1]
	v_pk_add_f32 v[86:87], v[184:185], v[70:71]
	v_pk_add_f32 v[100:101], v[184:185], v[70:71] neg_lo:[0,1] neg_hi:[0,1]
	v_pk_add_f32 v[70:71], v[98:99], v[82:83]
	v_pk_add_f32 v[82:83], v[82:83], v[98:99] neg_lo:[0,1] neg_hi:[0,1]
	v_pk_add_f32 v[98:99], v[70:71], v[86:87]
	v_pk_add_f32 v[86:87], v[86:87], v[70:71] neg_lo:[0,1] neg_hi:[0,1]
	v_pk_add_f32 v[70:71], v[92:93], v[68:69]
	v_pk_add_f32 v[92:93], v[92:93], v[68:69] neg_lo:[0,1] neg_hi:[0,1]
	v_pk_add_f32 v[68:69], v[88:89], v[80:81]
	v_pk_add_f32 v[80:81], v[80:81], v[88:89] neg_lo:[0,1] neg_hi:[0,1]
	v_pk_add_f32 v[88:89], v[68:69], v[70:71]
	v_pk_add_f32 v[124:125], v[70:71], v[68:69] neg_lo:[0,1] neg_hi:[0,1]
	v_pk_add_f32 v[68:69], v[96:97], v[90:91]
	v_pk_add_f32 v[70:71], v[74:75], v[78:79]
	v_pk_add_f32 v[96:97], v[90:91], v[96:97] neg_lo:[0,1] neg_hi:[0,1]
	v_pk_add_f32 v[74:75], v[78:79], v[74:75] neg_lo:[0,1] neg_hi:[0,1]
	v_pk_add_f32 v[78:79], v[68:69], v[70:71]
	v_pk_add_f32 v[90:91], v[68:69], v[70:71] neg_lo:[0,1] neg_hi:[0,1]
	v_pk_add_f32 v[68:69], v[94:95], v[84:85]
	v_pk_add_f32 v[70:71], v[72:73], v[76:77]
	v_xor_b32_e32 v129, 0x80000000, v74
	v_mov_b32_e32 v128, v75
	v_pk_add_f32 v[72:73], v[76:77], v[72:73] neg_lo:[0,1] neg_hi:[0,1]
	v_pk_add_f32 v[74:75], v[68:69], v[70:71]
	v_xor_b32_e32 v127, 0x80000000, v80
	v_mov_b32_e32 v126, v81
	v_pk_add_f32 v[94:95], v[84:85], v[94:95] neg_lo:[0,1] neg_hi:[0,1]
	v_pk_add_f32 v[84:85], v[68:69], v[70:71] neg_lo:[0,1] neg_hi:[0,1]
	v_xor_b32_e32 v133, 0x80000000, v72
	v_mov_b32_e32 v132, v73
	v_pk_add_f32 v[68:69], v[78:79], v[98:99]
	v_pk_add_f32 v[70:71], v[74:75], v[88:89]
	v_pk_add_f32 v[72:73], v[88:89], v[74:75] neg_lo:[0,1] neg_hi:[0,1]
	v_pk_add_f32 v[80:81], v[126:127], v[92:93]
	v_pk_add_f32 v[78:79], v[98:99], v[78:79] neg_lo:[0,1] neg_hi:[0,1]
	v_pk_add_f32 v[74:75], v[68:69], v[70:71]
	v_pk_add_f32 v[70:71], v[68:69], v[70:71] neg_lo:[0,1] neg_hi:[0,1]
	v_xor_b32_e32 v69, 0x80000000, v72
	v_mov_b32_e32 v68, v73
	v_pk_add_f32 v[130:131], v[96:97], v[128:129]
	v_pk_add_f32 v[76:77], v[94:95], v[132:133]
	v_pk_add_f32 v[72:73], v[78:79], v[68:69]
	v_pk_add_f32 v[68:69], v[78:79], v[68:69] neg_lo:[0,1] neg_hi:[0,1]
	v_pk_mul_f32 v[78:79], v[80:81], s[28:29] op_sel:[1,0]
	v_xor_b32_e32 v123, 0x80000000, v82
	v_mov_b32_e32 v122, v83
	v_pk_fma_f32 v[78:79], v[80:81], s[26:27], v[78:79] op_sel_hi:[0,1,1]
	v_mul_f32_e32 v80, 0x3f3504f3, v131
	s_mov_b32 s29, s34
	v_pk_mul_f32 v[88:89], v[76:77], s[10:11] op_sel:[1,0]
	v_pk_add_f32 v[82:83], v[122:123], v[100:101]
	v_pk_fma_f32 v[80:81], v[130:131], s[30:31], v[80:81] op_sel_hi:[0,1,0]
	v_pk_fma_f32 v[76:77], v[76:77], s[28:29], v[88:89] op_sel_hi:[0,1,1]
	v_pk_add_f32 v[88:89], v[82:83], v[80:81]
	v_pk_add_f32 v[98:99], v[82:83], v[80:81] neg_lo:[0,1] neg_hi:[0,1]
	v_pk_add_f32 v[80:81], v[78:79], v[76:77]
	v_pk_add_f32 v[76:77], v[78:79], v[76:77] neg_lo:[0,1] neg_hi:[0,1]
	v_pk_add_f32 v[82:83], v[88:89], v[80:81]
	v_pk_add_f32 v[78:79], v[88:89], v[80:81] neg_lo:[0,1] neg_hi:[0,1]
	v_xor_b32_e32 v89, 0x80000000, v76
	v_mov_b32_e32 v88, v77
	v_pk_add_f32 v[80:81], v[98:99], v[88:89]
	v_pk_add_f32 v[76:77], v[98:99], v[88:89] neg_lo:[0,1] neg_hi:[0,1]
	v_pk_mul_f32 v[98:99], v[90:91], s[36:37] op_sel:[1,0]
	v_mul_f32_e32 v88, 0x3f3504f3, v125
	v_pk_fma_f32 v[90:91], v[90:91], s[20:21], v[98:99] op_sel_hi:[0,1,1]
	v_mul_f32_e32 v98, 0xbf3504f3, v84
	v_pk_fma_f32 v[88:89], v[124:125], s[30:31], v[88:89] op_sel_hi:[0,1,0]
	v_pk_fma_f32 v[84:85], v[84:85], s[30:31], v[98:99] op_sel:[1,0,0] op_sel_hi:[1,1,0]
	v_pk_add_f32 v[98:99], v[86:87], v[90:91]
	v_pk_add_f32 v[124:125], v[86:87], v[90:91] neg_lo:[0,1] neg_hi:[0,1]
	v_pk_add_f32 v[86:87], v[84:85], v[88:89]
	v_pk_add_f32 v[84:85], v[88:89], v[84:85] neg_lo:[0,1] neg_hi:[0,1]
	v_pk_add_f32 v[90:91], v[98:99], v[86:87]
	v_pk_add_f32 v[86:87], v[98:99], v[86:87] neg_lo:[0,1] neg_hi:[0,1]
	v_xor_b32_e32 v99, 0x80000000, v84
	v_mov_b32_e32 v98, v85
	v_pk_add_f32 v[94:95], v[94:95], v[132:133] neg_lo:[0,1] neg_hi:[0,1]
	v_pk_add_f32 v[88:89], v[124:125], v[98:99]
	v_pk_add_f32 v[84:85], v[124:125], v[98:99] neg_lo:[0,1] neg_hi:[0,1]
	v_pk_mul_f32 v[98:99], v[94:95], s[12:13] op_sel:[1,0]
	v_pk_add_f32 v[92:93], v[92:93], v[126:127] neg_lo:[0,1] neg_hi:[0,1]
	v_pk_fma_f32 v[94:95], v[94:95], s[34:35], v[98:99] op_sel_hi:[0,1,1]
	v_pk_add_f32 v[98:99], v[100:101], v[122:123] neg_lo:[0,1] neg_hi:[0,1]
	v_pk_mul_f32 v[100:101], v[92:93], s[10:11] op_sel:[1,0]
	v_pk_add_f32 v[96:97], v[96:97], v[128:129] neg_lo:[0,1] neg_hi:[0,1]
	v_pk_fma_f32 v[92:93], v[92:93], s[28:29], v[100:101] op_sel_hi:[0,1,1]
	v_mul_f32_e32 v100, 0xbf3504f3, v96
	v_pk_fma_f32 v[96:97], v[96:97], s[30:31], v[100:101] op_sel:[1,0,0] op_sel_hi:[1,1,0]
	v_pk_add_f32 v[122:123], v[92:93], v[94:95]
	v_pk_add_f32 v[100:101], v[98:99], v[96:97]
	v_pk_add_f32 v[94:95], v[92:93], v[94:95] neg_lo:[0,1] neg_hi:[0,1]
	v_pk_add_f32 v[98:99], v[98:99], v[96:97] neg_lo:[0,1] neg_hi:[0,1]
	v_pk_add_f32 v[96:97], v[100:101], v[122:123]
	v_pk_add_f32 v[92:93], v[100:101], v[122:123] neg_lo:[0,1] neg_hi:[0,1]
	v_xor_b32_e32 v101, 0x80000000, v94
	v_mov_b32_e32 v100, v95
	v_pk_add_f32 v[94:95], v[98:99], v[100:101]
	v_pk_add_f32 v[98:99], v[98:99], v[100:101] neg_lo:[0,1] neg_hi:[0,1]

.LBB0_1579:
	s_or_b64 exec, exec, s[8:9]
	s_waitcnt lgkmcnt(0)
	s_barrier
	s_and_saveexec_b64 s[8:9], vcc
	s_cbranch_execz .LBB0_1581
	ds_read_b64 v[172:173], v23 offset:61440
	ds_read_b64 v[174:175], v63 offset:57344
	ds_read_b64 v[176:177], v102 offset:53248
	ds_read_b64 v[178:179], v105 offset:49152
	ds_read_b64 v[180:181], v108 offset:45056
	ds_read_b64 v[182:183], v111 offset:40960
	ds_read_b64 v[184:185], v117
	ds_read_b64 v[186:187], v109 offset:4096
	ds_read_b64 v[188:189], v106 offset:8192
	ds_read_b64 v[190:191], v103 offset:12288
	ds_read_b64 v[192:193], v65 offset:16384
	ds_read_b64 v[194:195], v27 offset:20480
	ds_read_b64 v[196:197], v15 offset:24576
	ds_read_b64 v[198:199], v11 offset:28672
	ds_read_b64 v[200:201], v116 offset:32768
	v_cvt_f32_ubyte0_e32 v68, v114
	v_mul_f32_e32 v68, 0x39800000, v68
	v_cos_f32_e32 v84, v68
	v_sin_f32_e32 v92, v68
	s_mov_b32 s29, s26
	v_mov_b32_e32 v93, v84
	v_xor_b32_e32 v85, 0x80000000, v92
	v_pk_mul_f32 v[68:69], v[92:93], v[92:93] op_sel_hi:[1,0] neg_lo:[0,1] neg_hi:[0,1]
	s_mov_b32 s10, s26
	v_pk_fma_f32 v[90:91], v[84:85], v[84:85], v[68:69] op_sel_hi:[1,0,1]
	s_mov_b32 s11, s28
	v_pk_mul_f32 v[68:69], v[92:93], v[90:91] op_sel:[0,1]
	s_mov_b32 s37, s20
	v_pk_fma_f32 v[86:87], v[84:85], v[90:91], v[68:69] op_sel_hi:[1,0,1]
	s_mov_b32 s12, s27
	v_pk_mul_f32 v[68:69], v[92:93], v[86:87] op_sel:[0,1]
	s_mov_b32 s13, s34
	v_pk_fma_f32 v[82:83], v[84:85], v[86:87], v[68:69] op_sel_hi:[1,0,1]
	s_mov_b32 s35, s28
	v_pk_mul_f32 v[68:69], v[92:93], v[82:83] op_sel:[0,1]
	s_nop 0
	v_pk_fma_f32 v[80:81], v[84:85], v[82:83], v[68:69] op_sel_hi:[1,0,1]
	s_nop 0
	v_pk_mul_f32 v[68:69], v[92:93], v[80:81] op_sel:[0,1]
	s_nop 0
	v_pk_fma_f32 v[78:79], v[84:85], v[80:81], v[68:69] op_sel_hi:[1,0,1]
	s_nop 0
	v_pk_mul_f32 v[68:69], v[92:93], v[78:79] op_sel:[0,1]
	s_nop 0
	v_pk_fma_f32 v[76:77], v[84:85], v[78:79], v[68:69] op_sel_hi:[1,0,1]
	s_nop 0
	v_pk_mul_f32 v[68:69], v[92:93], v[76:77] op_sel:[0,1]
	s_nop 0
	v_pk_fma_f32 v[70:71], v[84:85], v[76:77], v[68:69] op_sel_hi:[1,0,1]
	s_nop 0
	v_pk_mul_f32 v[68:69], v[92:93], v[70:71] op_sel:[0,1]
	s_nop 0
	v_pk_fma_f32 v[68:69], v[84:85], v[70:71], v[68:69] op_sel_hi:[1,0,1]
	s_nop 0
	v_pk_mul_f32 v[72:73], v[92:93], v[68:69] op_sel:[0,1]
	s_nop 0
	v_pk_fma_f32 v[96:97], v[84:85], v[68:69], v[72:73] op_sel_hi:[1,0,1]
	s_nop 0
	v_pk_mul_f32 v[72:73], v[92:93], v[96:97] op_sel:[0,1]
	s_nop 0
	v_pk_fma_f32 v[94:95], v[84:85], v[96:97], v[72:73] op_sel_hi:[1,0,1]
	s_nop 0
	v_pk_mul_f32 v[72:73], v[92:93], v[94:95] op_sel:[0,1]
	s_nop 0
	v_pk_fma_f32 v[98:99], v[84:85], v[94:95], v[72:73] op_sel_hi:[1,0,1]
	s_nop 0
	v_pk_mul_f32 v[72:73], v[92:93], v[98:99] op_sel:[0,1]
	s_nop 0
	v_pk_fma_f32 v[88:89], v[84:85], v[98:99], v[72:73] op_sel_hi:[1,0,1]
	s_nop 0
	v_pk_mul_f32 v[72:73], v[92:93], v[88:89] op_sel:[0,1]
	s_nop 0
	v_pk_fma_f32 v[74:75], v[84:85], v[88:89], v[72:73] op_sel_hi:[1,0,1]
	s_nop 0
	v_pk_mul_f32 v[72:73], v[92:93], v[74:75] op_sel:[0,1]
	s_nop 0
	v_pk_fma_f32 v[72:73], v[84:85], v[74:75], v[72:73] op_sel_hi:[1,0,1]
	s_nop 0
	v_xor_b32_e32 v124, 0x80000000, v73
	v_mov_b32_e32 v125, v72
	s_waitcnt lgkmcnt(15)
	s_waitcnt lgkmcnt(14)
	v_pk_mul_f32 v[124:125], v[124:125], v[172:173] op_sel:[0,1]
	s_nop 0
	v_pk_fma_f32 v[72:73], v[72:73], v[172:173], v[124:125] op_sel_hi:[1,0,1]
	ds_read_b64 v[172:173], v113 offset:36864
	v_xor_b32_e32 v124, 0x80000000, v75
	v_mov_b32_e32 v125, v74
	s_waitcnt lgkmcnt(14)
	v_pk_mul_f32 v[124:125], v[124:125], v[174:175] op_sel:[0,1]
	s_nop 0
	v_pk_fma_f32 v[74:75], v[74:75], v[174:175], v[124:125] op_sel_hi:[1,0,1]
	v_xor_b32_e32 v124, 0x80000000, v89
	v_mov_b32_e32 v125, v88
	s_waitcnt lgkmcnt(13)
	v_pk_mul_f32 v[124:125], v[124:125], v[176:177] op_sel:[0,1]
	s_nop 0
	v_pk_fma_f32 v[88:89], v[88:89], v[176:177], v[124:125] op_sel_hi:[1,0,1]
	v_xor_b32_e32 v124, 0x80000000, v99
	v_mov_b32_e32 v125, v98
	s_waitcnt lgkmcnt(12)
	v_pk_mul_f32 v[124:125], v[124:125], v[178:179] op_sel:[0,1]
	s_nop 0
	v_pk_fma_f32 v[98:99], v[98:99], v[178:179], v[124:125] op_sel_hi:[1,0,1]
	v_xor_b32_e32 v124, 0x80000000, v95
	v_mov_b32_e32 v125, v94
	s_waitcnt lgkmcnt(11)
	v_pk_mul_f32 v[124:125], v[124:125], v[180:181] op_sel:[0,1]
	s_nop 0
	v_pk_fma_f32 v[94:95], v[94:95], v[180:181], v[124:125] op_sel_hi:[1,0,1]
	v_xor_b32_e32 v124, 0x80000000, v97
	v_mov_b32_e32 v125, v96
	s_waitcnt lgkmcnt(10)
	v_pk_mul_f32 v[124:125], v[124:125], v[182:183] op_sel:[0,1]
	s_nop 0
	v_pk_fma_f32 v[96:97], v[96:97], v[182:183], v[124:125] op_sel_hi:[1,0,1]
	s_waitcnt lgkmcnt(8)
	v_pk_mul_f32 v[92:93], v[92:93], v[186:187] op_sel:[0,1]
	s_nop 0
	v_pk_fma_f32 v[92:93], v[84:85], v[186:187], v[92:93] op_sel_hi:[1,0,1]
	v_xor_b32_e32 v124, 0x80000000, v91
	v_mov_b32_e32 v125, v90
	s_waitcnt lgkmcnt(7)
	v_pk_mul_f32 v[124:125], v[124:125], v[188:189] op_sel:[0,1]
	s_nop 0
	v_pk_fma_f32 v[90:91], v[90:91], v[188:189], v[124:125] op_sel_hi:[1,0,1]
	v_xor_b32_e32 v124, 0x80000000, v87
	v_mov_b32_e32 v125, v86
	s_waitcnt lgkmcnt(6)
	v_pk_mul_f32 v[124:125], v[124:125], v[190:191] op_sel:[0,1]
	s_nop 0
	v_pk_fma_f32 v[84:85], v[86:87], v[190:191], v[124:125] op_sel_hi:[1,0,1]
	v_xor_b32_e32 v124, 0x80000000, v83
	v_mov_b32_e32 v125, v82
	s_waitcnt lgkmcnt(5)
	v_pk_mul_f32 v[124:125], v[124:125], v[192:193] op_sel:[0,1]
	s_nop 0
	v_pk_fma_f32 v[82:83], v[82:83], v[192:193], v[124:125] op_sel_hi:[1,0,1]
	v_xor_b32_e32 v124, 0x80000000, v81
	v_mov_b32_e32 v125, v80
	s_waitcnt lgkmcnt(4)
	v_pk_mul_f32 v[124:125], v[124:125], v[194:195] op_sel:[0,1]
	s_nop 0
	v_pk_fma_f32 v[80:81], v[80:81], v[194:195], v[124:125] op_sel_hi:[1,0,1]
	v_xor_b32_e32 v124, 0x80000000, v79
	v_mov_b32_e32 v125, v78
	s_waitcnt lgkmcnt(3)
	v_pk_mul_f32 v[124:125], v[124:125], v[196:197] op_sel:[0,1]
	s_nop 0
	v_pk_fma_f32 v[78:79], v[78:79], v[196:197], v[124:125] op_sel_hi:[1,0,1]
	v_xor_b32_e32 v124, 0x80000000, v77
	v_mov_b32_e32 v125, v76
	s_waitcnt lgkmcnt(2)
	v_pk_mul_f32 v[124:125], v[124:125], v[198:199] op_sel:[0,1]
	s_nop 0
	v_pk_fma_f32 v[76:77], v[76:77], v[198:199], v[124:125] op_sel_hi:[1,0,1]
	v_xor_b32_e32 v124, 0x80000000, v71
	v_mov_b32_e32 v125, v70
	s_waitcnt lgkmcnt(1)
	v_pk_mul_f32 v[124:125], v[124:125], v[200:201] op_sel:[0,1]
	s_nop 0
	v_pk_fma_f32 v[70:71], v[70:71], v[200:201], v[124:125] op_sel_hi:[1,0,1]
	v_xor_b32_e32 v124, 0x80000000, v69
	v_mov_b32_e32 v125, v68
	s_waitcnt lgkmcnt(0)
	v_pk_mul_f32 v[124:125], v[124:125], v[172:173] op_sel:[0,1]
	s_nop 0
	v_pk_fma_f32 v[68:69], v[68:69], v[172:173], v[124:125] op_sel_hi:[1,0,1]
	v_pk_add_f32 v[86:87], v[184:185], v[70:71]
	v_pk_add_f32 v[100:101], v[184:185], v[70:71] neg_lo:[0,1] neg_hi:[0,1]
	v_pk_add_f32 v[70:71], v[98:99], v[82:83]
	v_pk_add_f32 v[82:83], v[82:83], v[98:99] neg_lo:[0,1] neg_hi:[0,1]
	v_pk_add_f32 v[98:99], v[70:71], v[86:87]
	v_pk_add_f32 v[86:87], v[86:87], v[70:71] neg_lo:[0,1] neg_hi:[0,1]
	v_pk_add_f32 v[70:71], v[92:93], v[68:69]
	v_pk_add_f32 v[92:93], v[92:93], v[68:69] neg_lo:[0,1] neg_hi:[0,1]
	v_pk_add_f32 v[68:69], v[88:89], v[80:81]
	v_pk_add_f32 v[80:81], v[80:81], v[88:89] neg_lo:[0,1] neg_hi:[0,1]
	v_pk_add_f32 v[88:89], v[68:69], v[70:71]
	v_pk_add_f32 v[126:127], v[70:71], v[68:69] neg_lo:[0,1] neg_hi:[0,1]
	v_pk_add_f32 v[68:69], v[96:97], v[90:91]
	v_pk_add_f32 v[70:71], v[74:75], v[78:79]
	v_pk_add_f32 v[96:97], v[90:91], v[96:97] neg_lo:[0,1] neg_hi:[0,1]
	v_pk_add_f32 v[74:75], v[78:79], v[74:75] neg_lo:[0,1] neg_hi:[0,1]
	v_pk_add_f32 v[78:79], v[68:69], v[70:71]
	v_pk_add_f32 v[90:91], v[68:69], v[70:71] neg_lo:[0,1] neg_hi:[0,1]
	v_pk_add_f32 v[68:69], v[94:95], v[84:85]
	v_pk_add_f32 v[70:71], v[72:73], v[76:77]
	v_xor_b32_e32 v131, 0x80000000, v74
	v_mov_b32_e32 v130, v75
	v_pk_add_f32 v[72:73], v[76:77], v[72:73] neg_lo:[0,1] neg_hi:[0,1]
	v_pk_add_f32 v[74:75], v[68:69], v[70:71]
	v_xor_b32_e32 v129, 0x80000000, v80
	v_mov_b32_e32 v128, v81
	v_pk_add_f32 v[94:95], v[84:85], v[94:95] neg_lo:[0,1] neg_hi:[0,1]
	v_pk_add_f32 v[84:85], v[68:69], v[70:71] neg_lo:[0,1] neg_hi:[0,1]
	v_xor_b32_e32 v135, 0x80000000, v72
	v_mov_b32_e32 v134, v73
	v_pk_add_f32 v[68:69], v[78:79], v[98:99]
	v_pk_add_f32 v[70:71], v[74:75], v[88:89]
	v_pk_add_f32 v[72:73], v[88:89], v[74:75] neg_lo:[0,1] neg_hi:[0,1]
	v_pk_add_f32 v[80:81], v[128:129], v[92:93]
	v_pk_add_f32 v[78:79], v[98:99], v[78:79] neg_lo:[0,1] neg_hi:[0,1]
	v_pk_add_f32 v[74:75], v[68:69], v[70:71]
	v_pk_add_f32 v[70:71], v[68:69], v[70:71] neg_lo:[0,1] neg_hi:[0,1]
	v_xor_b32_e32 v69, 0x80000000, v72
	v_mov_b32_e32 v68, v73
	v_pk_add_f32 v[132:133], v[96:97], v[130:131]
	v_pk_add_f32 v[76:77], v[94:95], v[134:135]
	v_pk_add_f32 v[72:73], v[78:79], v[68:69]
	v_pk_add_f32 v[68:69], v[78:79], v[68:69] neg_lo:[0,1] neg_hi:[0,1]
	v_pk_mul_f32 v[78:79], v[80:81], s[28:29] op_sel:[1,0]
	v_xor_b32_e32 v125, 0x80000000, v82
	v_mov_b32_e32 v124, v83
	v_pk_fma_f32 v[78:79], v[80:81], s[26:27], v[78:79] op_sel_hi:[0,1,1]
	v_mul_f32_e32 v80, 0x3f3504f3, v133
	s_mov_b32 s29, s34
	v_pk_mul_f32 v[88:89], v[76:77], s[10:11] op_sel:[1,0]
	v_pk_add_f32 v[82:83], v[124:125], v[100:101]
	v_pk_fma_f32 v[80:81], v[132:133], s[30:31], v[80:81] op_sel_hi:[0,1,0]
	v_pk_fma_f32 v[76:77], v[76:77], s[28:29], v[88:89] op_sel_hi:[0,1,1]
	v_pk_add_f32 v[88:89], v[82:83], v[80:81]
	v_pk_add_f32 v[98:99], v[82:83], v[80:81] neg_lo:[0,1] neg_hi:[0,1]
	v_pk_add_f32 v[80:81], v[78:79], v[76:77]
	v_pk_add_f32 v[76:77], v[78:79], v[76:77] neg_lo:[0,1] neg_hi:[0,1]
	v_pk_add_f32 v[82:83], v[88:89], v[80:81]
	v_pk_add_f32 v[78:79], v[88:89], v[80:81] neg_lo:[0,1] neg_hi:[0,1]
	v_xor_b32_e32 v89, 0x80000000, v76
	v_mov_b32_e32 v88, v77
	v_pk_add_f32 v[80:81], v[98:99], v[88:89]
	v_pk_add_f32 v[76:77], v[98:99], v[88:89] neg_lo:[0,1] neg_hi:[0,1]
	v_pk_mul_f32 v[98:99], v[90:91], s[36:37] op_sel:[1,0]
	v_mul_f32_e32 v88, 0x3f3504f3, v127
	v_pk_fma_f32 v[90:91], v[90:91], s[20:21], v[98:99] op_sel_hi:[0,1,1]
	v_mul_f32_e32 v98, 0xbf3504f3, v84
	v_pk_fma_f32 v[88:89], v[126:127], s[30:31], v[88:89] op_sel_hi:[0,1,0]
	v_pk_fma_f32 v[84:85], v[84:85], s[30:31], v[98:99] op_sel:[1,0,0] op_sel_hi:[1,1,0]
	v_pk_add_f32 v[98:99], v[86:87], v[90:91]
	v_pk_add_f32 v[126:127], v[86:87], v[90:91] neg_lo:[0,1] neg_hi:[0,1]
	v_pk_add_f32 v[86:87], v[84:85], v[88:89]
	v_pk_add_f32 v[84:85], v[88:89], v[84:85] neg_lo:[0,1] neg_hi:[0,1]
	v_pk_add_f32 v[90:91], v[98:99], v[86:87]
	v_pk_add_f32 v[86:87], v[98:99], v[86:87] neg_lo:[0,1] neg_hi:[0,1]
	v_xor_b32_e32 v99, 0x80000000, v84
	v_mov_b32_e32 v98, v85
	v_pk_add_f32 v[94:95], v[94:95], v[134:135] neg_lo:[0,1] neg_hi:[0,1]
	v_pk_add_f32 v[88:89], v[126:127], v[98:99]
	v_pk_add_f32 v[84:85], v[126:127], v[98:99] neg_lo:[0,1] neg_hi:[0,1]
	v_pk_mul_f32 v[98:99], v[94:95], s[12:13] op_sel:[1,0]
	v_pk_add_f32 v[92:93], v[92:93], v[128:129] neg_lo:[0,1] neg_hi:[0,1]
	v_pk_fma_f32 v[94:95], v[94:95], s[34:35], v[98:99] op_sel_hi:[0,1,1]
	v_pk_add_f32 v[98:99], v[100:101], v[124:125] neg_lo:[0,1] neg_hi:[0,1]
	v_pk_mul_f32 v[100:101], v[92:93], s[10:11] op_sel:[1,0]
	v_pk_add_f32 v[96:97], v[96:97], v[130:131] neg_lo:[0,1] neg_hi:[0,1]
	v_pk_fma_f32 v[92:93], v[92:93], s[28:29], v[100:101] op_sel_hi:[0,1,1]
	v_mul_f32_e32 v100, 0xbf3504f3, v96
	v_pk_fma_f32 v[96:97], v[96:97], s[30:31], v[100:101] op_sel:[1,0,0] op_sel_hi:[1,1,0]
	v_pk_add_f32 v[124:125], v[92:93], v[94:95]
	v_pk_add_f32 v[100:101], v[98:99], v[96:97]
	v_pk_add_f32 v[94:95], v[92:93], v[94:95] neg_lo:[0,1] neg_hi:[0,1]
	v_pk_add_f32 v[98:99], v[98:99], v[96:97] neg_lo:[0,1] neg_hi:[0,1]
	v_pk_add_f32 v[96:97], v[100:101], v[124:125]
	v_pk_add_f32 v[92:93], v[100:101], v[124:125] neg_lo:[0,1] neg_hi:[0,1]
	v_xor_b32_e32 v101, 0x80000000, v94
	v_mov_b32_e32 v100, v95
	v_pk_add_f32 v[94:95], v[98:99], v[100:101]
	v_pk_add_f32 v[98:99], v[98:99], v[100:101] neg_lo:[0,1] neg_hi:[0,1]

.LBB0_1583:
	s_or_b64 exec, exec, s[8:9]
	s_waitcnt lgkmcnt(0)
	s_barrier
	s_and_saveexec_b64 s[8:9], vcc
	s_cbranch_execz .LBB0_1585
	ds_read_b64 v[172:173], v116 offset:32768
	v_cvt_f32_i32_e32 v70, v114
	v_lshlrev_b32_e32 v71, 3, v115
	v_lshlrev_b32_e32 v73, 3, v114
	v_mul_f32_e32 v72, 0x39000000, v70
	v_sin_f32_e32 v70, v72
	v_cos_f32_e32 v72, v72
	v_add3_u32 v76, s3, v71, v73
	ds_read_b64 v[174:175], v76
	v_xor_b32_e32 v73, 0x80000000, v70
	v_mov_b32_e32 v71, v72
	s_waitcnt lgkmcnt(2)
	s_waitcnt lgkmcnt(1)
	v_pk_mul_f32 v[70:71], v[70:71], v[172:173] op_sel:[0,1]
	v_cvt_f32_i32_e32 v67, v67
	v_pk_fma_f32 v[68:69], v[72:73], v[172:173], v[70:71] op_sel_hi:[1,0,1]
	v_cvt_f32_i32_e32 v72, v112
	s_waitcnt lgkmcnt(0)
	v_pk_add_f32 v[70:71], v[174:175], v[68:69]
	v_pk_add_f32 v[68:69], v[174:175], v[68:69] neg_lo:[0,1] neg_hi:[0,1]
	ds_write_b64 v76, v[70:71]
	ds_write_b64 v116, v[68:69] offset:32768
	ds_read_b64 v[172:173], v113 offset:36864
	ds_read_b64 v[174:175], v109 offset:4096
	v_mul_f32_e32 v69, 0x39000000, v72
	v_cos_f32_e32 v68, v69
	v_sin_f32_e32 v70, v69
	v_cvt_f32_i32_e32 v31, v31
	v_mov_b32_e32 v71, v68
	v_xor_b32_e32 v69, 0x80000000, v70
	s_waitcnt lgkmcnt(1)
	v_pk_mul_f32 v[70:71], v[70:71], v[172:173] op_sel:[0,1]
	v_cvt_f32_i32_e32 v19, v19
	v_pk_fma_f32 v[68:69], v[68:69], v[172:173], v[70:71] op_sel_hi:[1,0,1]
	v_cvt_f32_i32_e32 v72, v110
	s_waitcnt lgkmcnt(0)
	v_pk_add_f32 v[70:71], v[174:175], v[68:69]
	v_pk_add_f32 v[68:69], v[174:175], v[68:69] neg_lo:[0,1] neg_hi:[0,1]
	ds_write_b64 v109, v[70:71] offset:4096
	ds_write_b64 v113, v[68:69] offset:36864
	ds_read_b64 v[172:173], v111 offset:40960
	ds_read_b64 v[174:175], v106 offset:8192
	v_mul_f32_e32 v69, 0x39000000, v72
	v_cos_f32_e32 v68, v69
	v_sin_f32_e32 v70, v69
	s_nop 0
	v_mov_b32_e32 v71, v68
	v_xor_b32_e32 v69, 0x80000000, v70
	s_waitcnt lgkmcnt(1)
	v_pk_mul_f32 v[70:71], v[70:71], v[172:173] op_sel:[0,1]
	s_nop 0
	v_pk_fma_f32 v[68:69], v[68:69], v[172:173], v[70:71] op_sel_hi:[1,0,1]
	v_cvt_f32_i32_e32 v72, v107
	s_waitcnt lgkmcnt(0)
	v_pk_add_f32 v[70:71], v[174:175], v[68:69]
	v_pk_add_f32 v[68:69], v[174:175], v[68:69] neg_lo:[0,1] neg_hi:[0,1]
	ds_write_b64 v106, v[70:71] offset:8192
	ds_write_b64 v111, v[68:69] offset:40960
	ds_read_b64 v[172:173], v108 offset:45056
	ds_read_b64 v[174:175], v103 offset:12288
	v_mul_f32_e32 v69, 0x39000000, v72
	v_cos_f32_e32 v68, v69
	v_sin_f32_e32 v70, v69
	s_nop 0
	v_mov_b32_e32 v71, v68
	v_xor_b32_e32 v69, 0x80000000, v70
	s_waitcnt lgkmcnt(1)
	v_pk_mul_f32 v[70:71], v[70:71], v[172:173] op_sel:[0,1]
	s_nop 0
	v_pk_fma_f32 v[68:69], v[68:69], v[172:173], v[70:71] op_sel_hi:[1,0,1]
	v_cvt_f32_i32_e32 v72, v104
	s_waitcnt lgkmcnt(0)
	v_pk_add_f32 v[70:71], v[174:175], v[68:69]
	v_pk_add_f32 v[68:69], v[174:175], v[68:69] neg_lo:[0,1] neg_hi:[0,1]
	ds_write_b64 v103, v[70:71] offset:12288
	ds_write_b64 v108, v[68:69] offset:45056
	ds_read_b64 v[172:173], v105 offset:49152
	ds_read_b64 v[174:175], v65 offset:16384
	v_mul_f32_e32 v69, 0x39000000, v72
	v_cos_f32_e32 v68, v69
	v_sin_f32_e32 v70, v69
	s_nop 0
	v_mov_b32_e32 v71, v68
	v_xor_b32_e32 v69, 0x80000000, v70
	s_waitcnt lgkmcnt(1)
	v_pk_mul_f32 v[70:71], v[70:71], v[172:173] op_sel:[0,1]
	s_nop 0
	v_pk_fma_f32 v[68:69], v[68:69], v[172:173], v[70:71] op_sel_hi:[1,0,1]
	s_waitcnt lgkmcnt(0)
	v_pk_add_f32 v[70:71], v[174:175], v[68:69]
	ds_write_b64 v65, v[70:71] offset:16384
	v_pk_add_f32 v[68:69], v[174:175], v[68:69] neg_lo:[0,1] neg_hi:[0,1]
	v_mul_f32_e32 v65, 0x39000000, v67
	ds_write_b64 v105, v[68:69] offset:49152
	ds_read_b64 v[172:173], v102 offset:53248
	ds_read_b64 v[174:175], v27 offset:20480
	v_cos_f32_e32 v68, v65
	v_sin_f32_e32 v70, v65
	s_nop 0
	v_mov_b32_e32 v71, v68
	v_xor_b32_e32 v69, 0x80000000, v70
	s_waitcnt lgkmcnt(1)
	v_pk_mul_f32 v[70:71], v[70:71], v[172:173] op_sel:[0,1]
	s_nop 0
	v_pk_fma_f32 v[68:69], v[68:69], v[172:173], v[70:71] op_sel_hi:[1,0,1]
	s_waitcnt lgkmcnt(0)
	v_pk_add_f32 v[70:71], v[174:175], v[68:69]
	ds_write_b64 v27, v[70:71] offset:20480
	v_pk_add_f32 v[68:69], v[174:175], v[68:69] neg_lo:[0,1] neg_hi:[0,1]
	v_mul_f32_e32 v27, 0x39000000, v31
	ds_write_b64 v102, v[68:69] offset:53248
	ds_read_b64 v[172:173], v63 offset:57344
	ds_read_b64 v[174:175], v15 offset:24576
	v_cos_f32_e32 v68, v27
	v_sin_f32_e32 v70, v27
	s_nop 0
	v_mov_b32_e32 v71, v68
	v_xor_b32_e32 v69, 0x80000000, v70
	s_waitcnt lgkmcnt(1)
	v_pk_mul_f32 v[70:71], v[70:71], v[172:173] op_sel:[0,1]
	s_nop 0
	v_pk_fma_f32 v[68:69], v[68:69], v[172:173], v[70:71] op_sel_hi:[1,0,1]
	s_waitcnt lgkmcnt(0)
	v_pk_add_f32 v[70:71], v[174:175], v[68:69]
	ds_write_b64 v15, v[70:71] offset:24576
	v_pk_add_f32 v[68:69], v[174:175], v[68:69] neg_lo:[0,1] neg_hi:[0,1]
	v_mul_f32_e32 v15, 0x39000000, v19
	ds_write_b64 v63, v[68:69] offset:57344
	ds_read_b64 v[72:73], v23 offset:61440
	ds_read_b64 v[74:75], v11 offset:28672
	v_cos_f32_e32 v68, v15
	v_sin_f32_e32 v70, v15
	s_nop 0
	v_mov_b32_e32 v71, v68
	v_xor_b32_e32 v69, 0x80000000, v70
	s_waitcnt lgkmcnt(1)
	v_pk_mul_f32 v[70:71], v[70:71], v[72:73] op_sel:[0,1]
	s_nop 0
	v_pk_fma_f32 v[68:69], v[68:69], v[72:73], v[70:71] op_sel_hi:[1,0,1]
	s_waitcnt lgkmcnt(0)
	v_pk_add_f32 v[70:71], v[74:75], v[68:69]
	v_pk_add_f32 v[68:69], v[74:75], v[68:69] neg_lo:[0,1] neg_hi:[0,1]
	ds_write_b64 v11, v[70:71] offset:28672
	ds_write_b64 v23, v[68:69] offset:61440
.LBB0_1585:
	s_or_b64 exec, exec, s[8:9]
	v_readlane_b32 s4, v240, 49
	v_readlane_b32 s18, v240, 63
	v_readlane_b32 s5, v240, 50
	v_readlane_b32 s6, v240, 51
	v_readlane_b32 s7, v240, 52
	v_readlane_b32 s8, v240, 53
	v_readlane_b32 s9, v240, 54
	v_readlane_b32 s10, v240, 55
	v_readlane_b32 s11, v240, 56
	v_readlane_b32 s12, v240, 57
	v_readlane_b32 s13, v240, 58
	v_readlane_b32 s14, v240, 59
	v_readlane_b32 s15, v240, 60
	v_readlane_b32 s16, v240, 61
	v_readlane_b32 s17, v240, 62
	v_readlane_b32 s19, v239, 0
	s_add_u32 s62, s18, s60
	s_addc_u32 s63, s19, s61
	v_readlane_b32 s4, v239, 19
	v_readlane_b32 s5, v239, 20
	s_add_u32 s64, s4, s60
	s_addc_u32 s65, s5, s61
	s_waitcnt lgkmcnt(0)
	s_barrier
	global_load_dword v84, v39, s[62:63]
	global_load_dword v85, v47, s[62:63]
	global_load_dword v11, v51, s[62:63]
	global_load_dword v15, v39, s[64:65]
	v_readlane_b32 s6, v239, 21
	v_readlane_b32 s7, v239, 22
	v_cmp_lt_i32_e32 vcc, 0, v64
	v_cmp_gt_i32_e64 s[6:7], s51, v64
	v_readlane_b32 s8, v239, 23
	s_waitcnt vmcnt(19)
	v_cndmask_b32_e32 v19, 0, v56, vcc
	v_readlane_b32 s9, v239, 24
	v_readlane_b32 s10, v239, 25
	v_readlane_b32 s11, v239, 26
	v_readlane_b32 s12, v239, 27
	v_readlane_b32 s13, v239, 28
	v_readlane_b32 s14, v239, 29
	v_readlane_b32 s15, v239, 30
	v_readlane_b32 s16, v239, 31
	v_readlane_b32 s17, v239, 32
	v_readlane_b32 s18, v239, 33
	v_readlane_b32 s19, v239, 34
	s_waitcnt vmcnt(0)
	v_fma_f32 v82, v57, v85, v15
	v_fmac_f32_e32 v82, v84, v19
	v_cndmask_b32_e64 v19, 0, v58, s[6:7]
	v_fmac_f32_e32 v82, v19, v11
	v_fma_f32 v83, v61, v85, v15
	v_cndmask_b32_e32 v19, 0, v60, vcc
	v_fmac_f32_e32 v83, v84, v19
	v_cndmask_b32_e64 v19, 0, v62, s[6:7]
	v_fmac_f32_e32 v83, v19, v11
	v_cmp_gt_i32_e32 vcc, s69, v64
	v_lshlrev_b32_e32 v19, 3, v64
	s_and_saveexec_b64 s[6:7], vcc
	v_ashrrev_i32_e32 v23, 4, v64
	v_lshlrev_b32_e32 v23, 3, v23
	v_add3_u32 v23, 0, v23, v19
	ds_write_b64 v23, v[82:83]
	s_or_b64 exec, exec, s[6:7]
	s_movk_i32 s4, 0xfe00
	v_cmp_lt_i32_e32 vcc, s4, v64
	s_movk_i32 s4, 0xdff
	v_cmp_gt_i32_e64 s[6:7], s4, v64
	v_cndmask_b32_e32 v52, 0, v52, vcc
	v_pk_mul_f32 v[52:53], v[84:85], v[52:53]
	v_cndmask_b32_e32 v48, 0, v48, vcc
	v_add_f32_e32 v23, v53, v15
	v_add_f32_e32 v80, v52, v23
	v_cndmask_b32_e64 v23, 0, v54, s[6:7]
	v_pk_mul_f32 v[48:49], v[84:85], v[48:49]
	v_fmac_f32_e32 v80, v23, v11
	v_add_f32_e32 v23, v49, v15
	v_add_f32_e32 v81, v48, v23
	v_cndmask_b32_e64 v23, 0, v50, s[6:7]
	v_fmac_f32_e32 v81, v23, v11
	v_cmp_gt_i32_e32 vcc, s95, v64
	s_and_saveexec_b64 s[6:7], vcc
	v_add_u32_e32 v23, 0x200, v64
	v_ashrrev_i32_e32 v23, 4, v23
	v_lshlrev_b32_e32 v23, 3, v23
	v_add3_u32 v23, 0, v23, v19
	ds_write_b64 v23, v[80:81] offset:4096
	s_or_b64 exec, exec, s[6:7]
	s_movk_i32 s4, 0xfc00
	v_cmp_lt_i32_e32 vcc, s4, v64
	s_movk_i32 s4, 0xbff
	v_cmp_gt_i32_e64 s[6:7], s4, v64
	v_cndmask_b32_e32 v44, 0, v44, vcc
	v_pk_mul_f32 v[44:45], v[84:85], v[44:45]
	v_cndmask_b32_e32 v40, 0, v40, vcc
	v_add_f32_e32 v23, v45, v15
	v_add_f32_e32 v78, v44, v23
	v_cndmask_b32_e64 v23, 0, v46, s[6:7]
	v_pk_mul_f32 v[40:41], v[84:85], v[40:41]
	v_fmac_f32_e32 v78, v23, v11
	v_add_f32_e32 v23, v41, v15
	v_add_f32_e32 v79, v40, v23
	v_cndmask_b32_e64 v23, 0, v42, s[6:7]
	v_fmac_f32_e32 v79, v23, v11
	v_cmp_gt_i32_e32 vcc, s75, v64
	s_and_saveexec_b64 s[6:7], vcc
	v_add_u32_e32 v23, 0x400, v64
	v_ashrrev_i32_e32 v23, 4, v23
	v_lshlrev_b32_e32 v23, 3, v23
	v_add3_u32 v23, 0, v23, v19
	ds_write_b64 v23, v[78:79] offset:8192
	s_or_b64 exec, exec, s[6:7]
	s_movk_i32 s4, 0xfa00
	v_cmp_lt_i32_e32 vcc, s4, v64
	s_movk_i32 s4, 0x9ff
	v_cmp_gt_i32_e64 s[6:7], s4, v64
	v_cndmask_b32_e32 v36, 0, v36, vcc
	v_pk_mul_f32 v[36:37], v[84:85], v[36:37]
	v_cndmask_b32_e32 v32, 0, v32, vcc
	v_add_f32_e32 v23, v37, v15
	v_add_f32_e32 v76, v36, v23
	v_cndmask_b32_e64 v23, 0, v38, s[6:7]
	v_pk_mul_f32 v[32:33], v[84:85], v[32:33]
	v_fmac_f32_e32 v76, v23, v11
	v_add_f32_e32 v23, v33, v15
	v_add_f32_e32 v77, v32, v23
	v_cndmask_b32_e64 v23, 0, v34, s[6:7]
	v_fmac_f32_e32 v77, v23, v11
	v_cmp_gt_i32_e32 vcc, s74, v64
	s_and_saveexec_b64 s[6:7], vcc
	v_add_u32_e32 v23, 0x600, v64
	v_ashrrev_i32_e32 v23, 4, v23
	v_lshlrev_b32_e32 v23, 3, v23
	v_add3_u32 v23, 0, v23, v19
	ds_write_b64 v23, v[76:77] offset:12288
	s_or_b64 exec, exec, s[6:7]
	s_movk_i32 s4, 0xf800
	v_cmp_lt_i32_e32 vcc, s4, v64
	v_cmp_gt_i32_e64 s[6:7], s43, v64
	s_nop 0
	v_cndmask_b32_e32 v28, 0, v28, vcc
	v_pk_mul_f32 v[28:29], v[84:85], v[28:29]
	v_cndmask_b32_e32 v24, 0, v24, vcc
	v_add_f32_e32 v23, v29, v15
	v_add_f32_e32 v74, v28, v23
	v_cndmask_b32_e64 v23, 0, v30, s[6:7]
	v_pk_mul_f32 v[24:25], v[84:85], v[24:25]
	v_fmac_f32_e32 v74, v23, v11
	v_add_f32_e32 v23, v25, v15
	v_add_f32_e32 v75, v24, v23
	v_cndmask_b32_e64 v23, 0, v26, s[6:7]
	v_fmac_f32_e32 v75, v23, v11
	v_cmp_gt_i32_e32 vcc, s68, v64
	s_and_saveexec_b64 s[6:7], vcc
	v_add_u32_e32 v23, 0x800, v64
	v_ashrrev_i32_e32 v23, 4, v23
	v_lshlrev_b32_e32 v23, 3, v23
	v_add3_u32 v23, 0, v23, v19
	ds_write_b64 v23, v[74:75] offset:16384
	s_or_b64 exec, exec, s[6:7]
	s_movk_i32 s4, 0xf600
	v_cmp_lt_i32_e32 vcc, s4, v64
	s_movk_i32 s4, 0x5ff
	v_cmp_gt_i32_e64 s[6:7], s4, v64
	v_cndmask_b32_e32 v20, 0, v20, vcc
	v_cndmask_b32_e32 v16, 0, v16, vcc
	v_pk_mul_f32 v[20:21], v[84:85], v[20:21]
	v_pk_mul_f32 v[16:17], v[84:85], v[16:17]
	v_add_f32_e32 v21, v21, v15
	v_add_f32_e32 v17, v17, v15
	v_add_f32_e32 v72, v20, v21
	v_cndmask_b32_e64 v20, 0, v22, s[6:7]
	v_add_f32_e32 v73, v16, v17
	v_cndmask_b32_e64 v16, 0, v18, s[6:7]
	v_fmac_f32_e32 v72, v20, v11
	v_fmac_f32_e32 v73, v16, v11
	v_cmp_gt_i32_e32 vcc, s72, v64
	s_and_saveexec_b64 s[6:7], vcc
	v_add_u32_e32 v16, 0xa00, v64
	v_ashrrev_i32_e32 v16, 4, v16
	v_lshlrev_b32_e32 v16, 3, v16
	v_add3_u32 v16, 0, v16, v19
	ds_write_b64 v16, v[72:73] offset:20480
	s_or_b64 exec, exec, s[6:7]
	s_movk_i32 s4, 0xf400
	v_cmp_lt_i32_e32 vcc, s4, v64
	s_movk_i32 s4, 0x3ff
	v_cmp_gt_i32_e64 s[6:7], s4, v64
	v_cndmask_b32_e32 v12, 0, v12, vcc
	v_cndmask_b32_e32 v8, 0, v8, vcc
	v_pk_mul_f32 v[12:13], v[84:85], v[12:13]
	v_pk_mul_f32 v[8:9], v[84:85], v[8:9]
	v_add_f32_e32 v13, v13, v15
	v_add_f32_e32 v9, v9, v15
	v_add_f32_e32 v68, v12, v13
	v_cndmask_b32_e64 v12, 0, v14, s[6:7]
	v_add_f32_e32 v69, v8, v9
	v_cndmask_b32_e64 v8, 0, v10, s[6:7]
	v_fmac_f32_e32 v68, v12, v11
	v_fmac_f32_e32 v69, v8, v11
	v_cmp_gt_i32_e32 vcc, s71, v64
	s_and_saveexec_b64 s[6:7], vcc
	v_add_u32_e32 v8, 0xc00, v64
	v_ashrrev_i32_e32 v8, 4, v8
	v_lshlrev_b32_e32 v8, 3, v8
	v_add3_u32 v8, 0, v8, v19
	ds_write_b64 v8, v[68:69] offset:24576
	s_or_b64 exec, exec, s[6:7]
	s_movk_i32 s4, 0xf200
	v_cmp_lt_i32_e32 vcc, s4, v64
	v_cmp_gt_i32_e64 s[6:7], s25, v64
	s_nop 0
	v_cndmask_b32_e32 v0, 0, v0, vcc
	v_cndmask_b32_e32 v4, 0, v4, vcc
	v_pk_mul_f32 v[4:5], v[84:85], v[4:5]
	v_pk_mul_f32 v[0:1], v[84:85], v[0:1]
	v_add_f32_e32 v5, v5, v15
	v_add_f32_e32 v1, v1, v15
	v_cndmask_b32_e64 v2, 0, v2, s[6:7]
	v_cndmask_b32_e64 v6, 0, v6, s[6:7]
	v_add_f32_e32 v71, v4, v5
	v_add_f32_e32 v70, v0, v1
	v_fmac_f32_e32 v70, v2, v11
	v_fmac_f32_e32 v71, v6, v11
	v_cmp_gt_i32_e32 vcc, s70, v64
	s_and_saveexec_b64 s[6:7], vcc
	v_add_u32_e32 v0, 0xe00, v64
	v_ashrrev_i32_e32 v0, 4, v0
	v_lshlrev_b32_e32 v0, 3, v0
	v_add3_u32 v0, 0, v0, v19
	ds_write_b64 v0, v[70:71] offset:28672
	s_or_b64 exec, exec, s[6:7]
	v_readlane_b32 s76, v240, 22
	v_readlane_b32 s80, v240, 26
	v_readlane_b32 s81, v240, 27
	v_readlane_b32 s82, v240, 28
	v_readlane_b32 s83, v240, 29
	v_readlane_b32 s84, v240, 30
	v_readlane_b32 s85, v240, 31
	v_readlane_b32 s86, v240, 32
	v_readlane_b32 s87, v240, 33
	v_readlane_b32 s88, v240, 34
	v_readlane_b32 s89, v240, 35
	v_readlane_b32 s90, v240, 36
	v_readlane_b32 s91, v240, 37
	s_mov_b64 s[8:9], s[80:81]
	s_mul_hi_i32 s7, s2, 0x8800
	s_mul_i32 s2, s2, 0x8800
	s_mov_b64 s[12:13], s[84:85]
	s_add_u32 s6, s12, s2
	s_addc_u32 s7, s13, s7
	v_ashrrev_i32_e32 v65, 31, v64
	v_lshl_add_u64 v[4:5], v[64:65], 2, s[6:7]
	v_add_co_u32_e32 v0, vcc, s94, v4
	global_load_dwordx3 v[56:58], v[4:5], off offset:-4
	global_load_dwordx3 v[48:50], v[4:5], off offset:2044
	v_addc_co_u32_e32 v1, vcc, 0, v5, vcc
	v_add_co_u32_e32 v8, vcc, s1, v4
	v_mov_b32_e32 v128, v64
	s_nop 0
	v_addc_co_u32_e32 v9, vcc, 0, v5, vcc
	v_add_co_u32_e32 v10, vcc, s69, v4
	global_load_dwordx3 v[60:62], v[0:1], off offset:4092
	global_load_dwordx3 v[52:54], v[8:9], off offset:2044
	v_addc_co_u32_e32 v11, vcc, 0, v5, vcc
	global_load_dwordx3 v[40:42], v[8:9], off offset:4092
	global_load_dwordx3 v[32:34], v[10:11], off offset:2044
	v_add_co_u32_e32 v8, vcc, s24, v4
	v_mov_b32_e32 v116, 0
	s_nop 0
	v_addc_co_u32_e32 v9, vcc, 0, v5, vcc
	global_load_dwordx3 v[36:38], v[8:9], off offset:2044
	global_load_dwordx3 v[24:26], v[10:11], off offset:4092
	v_add_co_u32_e32 v10, vcc, s73, v4
	v_mov_b32_e32 v117, 0
	s_nop 0
	v_addc_co_u32_e32 v11, vcc, 0, v5, vcc
	v_add_co_u32_e32 v12, vcc, s46, v4
	global_load_dwordx3 v[28:30], v[8:9], off offset:4092
	global_load_dwordx3 v[16:18], v[10:11], off offset:2044
	v_addc_co_u32_e32 v13, vcc, 0, v5, vcc
	global_load_dwordx3 v[20:22], v[12:13], off offset:2044
	s_nop 0
	global_load_dwordx3 v[8:10], v[10:11], off offset:4092
	s_nop 0
	global_load_dwordx3 v[44:46], v[4:5], off offset:4092
	s_nop 0
	global_load_dwordx3 v[0:2], v[0:1], off offset:2044
	v_add_co_u32_e32 v4, vcc, s47, v4
	v_mov_b32_e32 v90, 0
	s_nop 0
	v_addc_co_u32_e32 v5, vcc, 0, v5, vcc
	global_load_dwordx3 v[12:14], v[12:13], off offset:4092
	s_nop 0
	global_load_dwordx3 v[4:6], v[4:5], off offset:2044
	s_waitcnt lgkmcnt(0)
	s_barrier
	v_mov_b32_e32 v91, v116
	v_add_u32_e32 v126, 0x200, v128
	v_lshl_add_u32 v129, v128, 3, 0
	v_ashrrev_i32_e32 v11, 4, v126
	v_add_u32_e32 v125, 0x400, v128
	v_lshl_add_u32 v124, v11, 3, v129
	v_ashrrev_i32_e32 v11, 4, v125
	v_add_u32_e32 v123, 0x600, v128
	v_lshl_add_u32 v122, v11, 3, v129
	v_ashrrev_i32_e32 v11, 4, v123
	v_add_u32_e32 v67, 0x800, v128
	v_lshl_add_u32 v65, v11, 3, v129
	v_ashrrev_i32_e32 v11, 4, v67
	v_add_u32_e32 v63, 0xa00, v128
	v_lshl_add_u32 v31, v11, 3, v129
	v_ashrrev_i32_e32 v11, 4, v63
	v_add_u32_e32 v27, 0xc00, v128
	v_lshl_add_u32 v23, v11, 3, v129
	v_ashrrev_i32_e32 v11, 4, v27
	v_add_u32_e32 v19, 0xe00, v128
	v_ashrrev_i32_e32 v127, 4, v128
	v_lshl_add_u32 v15, v11, 3, v129
	v_ashrrev_i32_e32 v11, 4, v19
	v_cmp_gt_i32_e32 vcc, s70, v128
	v_lshl_add_u32 v136, v127, 3, v129
	v_lshl_add_u32 v11, v11, 3, v129
	v_mov_b32_e32 v98, v116
	v_mov_b32_e32 v99, v116
	v_mov_b32_e32 v106, v116
	v_mov_b32_e32 v107, v116
	v_mov_b32_e32 v112, v116
	v_mov_b32_e32 v113, v116
	v_mov_b32_e32 v88, v116
	v_mov_b32_e32 v89, v116
	v_mov_b32_e32 v96, v116
	v_mov_b32_e32 v97, v116
	v_mov_b32_e32 v104, v116
	v_mov_b32_e32 v105, v116
	v_mov_b32_e32 v110, v116
	v_mov_b32_e32 v111, v116
	v_mov_b32_e32 v86, v116
	v_mov_b32_e32 v87, v116
	v_mov_b32_e32 v94, v116
	v_mov_b32_e32 v95, v116
	v_mov_b32_e32 v102, v116
	v_mov_b32_e32 v103, v116
	v_mov_b32_e32 v108, v116
	v_mov_b32_e32 v109, v116
	v_mov_b32_e32 v84, v116
	v_mov_b32_e32 v85, v116
	v_mov_b32_e32 v92, v116
	v_mov_b32_e32 v93, v116
	v_mov_b32_e32 v100, v116
	v_mov_b32_e32 v101, v116
	v_mov_b32_e32 v114, v116
	v_mov_b32_e32 v115, v116
	v_readlane_b32 s77, v240, 23
	v_readlane_b32 s78, v240, 24
	v_readlane_b32 s79, v240, 25
	s_mov_b64 s[10:11], s[82:83]
	s_mov_b64 s[14:15], s[86:87]
	s_mov_b64 s[16:17], s[88:89]
	s_mov_b64 s[18:19], s[90:91]
	s_and_saveexec_b64 s[6:7], vcc
	s_xor_b64 s[6:7], exec, s[6:7]
	s_cbranch_execz .LBB0_1603
	ds_read_b64 v[172:173], v136
	ds_read_b64 v[174:175], v124 offset:4096
	ds_read_b64 v[176:177], v122 offset:8192
	ds_read_b64 v[178:179], v65 offset:12288
	ds_read_b64 v[180:181], v31 offset:16384
	ds_read_b64 v[182:183], v23 offset:20480
	ds_read_b64 v[184:185], v15 offset:24576
	ds_read_b64 v[186:187], v11 offset:28672
	s_waitcnt lgkmcnt(8)
	s_waitcnt lgkmcnt(7)
	v_pk_add_f32 v[92:93], v[172:173], 0 op_sel_hi:[1,0]
	s_waitcnt lgkmcnt(3)
	v_pk_add_f32 v[94:95], v[180:181], 0 op_sel_hi:[1,0]
	v_xor_b32_e32 v117, 0x80000000, v180
	v_pk_add_f32 v[96:97], v[92:93], v[94:95]
	v_pk_add_f32 v[100:101], v[92:93], v[94:95] neg_lo:[0,1] neg_hi:[0,1]
	v_mov_b32_e32 v116, v181
	v_pk_add_f32 v[84:85], v[174:175], 0 op_sel_hi:[1,0]
	s_waitcnt lgkmcnt(2)
	v_pk_add_f32 v[94:95], v[182:183], 0 op_sel_hi:[1,0]
	v_xor_b32_e32 v131, 0x80000000, v182
	v_pk_add_f32 v[98:99], v[84:85], v[94:95]
	v_pk_add_f32 v[102:103], v[84:85], v[94:95] neg_lo:[0,1] neg_hi:[0,1]
	v_mov_b32_e32 v130, v183
	v_pk_add_f32 v[84:85], v[176:177], 0 op_sel_hi:[1,0]
	s_waitcnt lgkmcnt(1)
	v_pk_add_f32 v[86:87], v[184:185], 0 op_sel_hi:[1,0]
	v_xor_b32_e32 v133, 0x80000000, v184
	v_pk_add_f32 v[104:105], v[84:85], v[86:87]
	v_pk_add_f32 v[106:107], v[84:85], v[86:87] neg_lo:[0,1] neg_hi:[0,1]
	v_pk_add_f32 v[84:85], v[178:179], 0 op_sel_hi:[1,0]
	s_waitcnt lgkmcnt(0)
	v_pk_add_f32 v[86:87], v[186:187], 0 op_sel_hi:[1,0]
	v_mov_b32_e32 v132, v185
	v_pk_add_f32 v[88:89], v[84:85], v[86:87]
	v_pk_add_f32 v[138:139], v[84:85], v[86:87] neg_lo:[0,1] neg_hi:[0,1]
	v_pk_add_f32 v[84:85], v[96:97], v[104:105]
	v_pk_add_f32 v[86:87], v[98:99], v[88:89]
	v_pk_add_f32 v[88:89], v[98:99], v[88:89] neg_lo:[0,1] neg_hi:[0,1]
	v_pk_add_f32 v[94:95], v[174:175], v[130:131]
	v_xor_b32_e32 v141, 0x80000000, v186
	v_mov_b32_e32 v140, v187
	v_pk_add_f32 v[96:97], v[96:97], v[104:105] neg_lo:[0,1] neg_hi:[0,1]
	v_pk_add_f32 v[90:91], v[84:85], v[86:87]
	v_pk_add_f32 v[86:87], v[84:85], v[86:87] neg_lo:[0,1] neg_hi:[0,1]
	v_xor_b32_e32 v85, 0x80000000, v88
	v_mov_b32_e32 v84, v89
	s_mov_b32 s29, s26
	v_pk_add_f32 v[134:135], v[176:177], v[132:133]
	v_pk_add_f32 v[142:143], v[178:179], v[140:141]
	v_pk_add_f32 v[88:89], v[96:97], v[84:85]
	v_pk_add_f32 v[84:85], v[96:97], v[84:85] neg_lo:[0,1] neg_hi:[0,1]
	v_pk_mul_f32 v[96:97], v[94:95], s[28:29] op_sel:[1,0]
	s_mov_b32 s8, s26
	s_mov_b32 s9, s28
	v_pk_fma_f32 v[94:95], v[94:95], s[26:27], v[96:97] op_sel_hi:[0,1,1]
	v_mul_f32_e32 v96, 0x3f3504f3, v135
	s_mov_b32 s29, s34
	v_pk_mul_f32 v[98:99], v[142:143], s[8:9] op_sel:[1,0]
	v_pk_add_f32 v[92:93], v[172:173], v[116:117]
	v_pk_fma_f32 v[96:97], v[134:135], s[30:31], v[96:97] op_sel_hi:[0,1,0]
	v_pk_fma_f32 v[98:99], v[142:143], s[28:29], v[98:99] op_sel_hi:[0,1,1]
	v_pk_add_f32 v[104:105], v[92:93], v[96:97]
	v_pk_add_f32 v[92:93], v[92:93], v[96:97] neg_lo:[0,1] neg_hi:[0,1]
	v_pk_add_f32 v[96:97], v[94:95], v[98:99]
	v_pk_add_f32 v[134:135], v[94:95], v[98:99] neg_lo:[0,1] neg_hi:[0,1]
	v_pk_add_f32 v[98:99], v[104:105], v[96:97]
	v_pk_add_f32 v[94:95], v[104:105], v[96:97] neg_lo:[0,1] neg_hi:[0,1]
	v_xor_b32_e32 v105, 0x80000000, v134
	v_mov_b32_e32 v104, v135
	v_pk_add_f32 v[96:97], v[92:93], v[104:105]
	v_pk_add_f32 v[92:93], v[92:93], v[104:105] neg_lo:[0,1] neg_hi:[0,1]
	v_mul_f32_e32 v104, 0x3f3504f3, v103
	s_mov_b32 s37, s20
	v_pk_fma_f32 v[102:103], v[102:103], s[30:31], v[104:105] op_sel_hi:[0,1,0]
	v_pk_mul_f32 v[104:105], v[106:107], s[36:37] op_sel:[1,0]
	v_pk_add_f32 v[110:111], v[174:175], v[130:131] neg_lo:[0,1] neg_hi:[0,1]
	v_pk_fma_f32 v[104:105], v[106:107], s[20:21], v[104:105] op_sel_hi:[0,1,1]
	v_mul_f32_e32 v106, 0xbf3504f3, v138
	v_pk_fma_f32 v[106:107], v[138:139], s[30:31], v[106:107] op_sel:[1,0,0] op_sel_hi:[1,1,0]
	v_pk_add_f32 v[134:135], v[100:101], v[104:105]
	v_pk_add_f32 v[100:101], v[100:101], v[104:105] neg_lo:[0,1] neg_hi:[0,1]
	v_pk_add_f32 v[104:105], v[102:103], v[106:107]
	v_pk_add_f32 v[138:139], v[102:103], v[106:107] neg_lo:[0,1] neg_hi:[0,1]
	v_pk_add_f32 v[106:107], v[134:135], v[104:105]
	v_pk_add_f32 v[102:103], v[134:135], v[104:105] neg_lo:[0,1] neg_hi:[0,1]
	v_xor_b32_e32 v135, 0x80000000, v138
	v_mov_b32_e32 v134, v139
	v_pk_add_f32 v[114:115], v[178:179], v[140:141] neg_lo:[0,1] neg_hi:[0,1]
	s_mov_b32 s10, s27
	s_mov_b32 s11, s34
	v_pk_add_f32 v[108:109], v[172:173], v[116:117] neg_lo:[0,1] neg_hi:[0,1]
	v_pk_mul_f32 v[116:117], v[110:111], s[8:9] op_sel:[1,0]
	v_pk_add_f32 v[112:113], v[176:177], v[132:133] neg_lo:[0,1] neg_hi:[0,1]
	v_pk_add_f32 v[104:105], v[100:101], v[134:135]
	v_pk_add_f32 v[100:101], v[100:101], v[134:135] neg_lo:[0,1] neg_hi:[0,1]
	s_mov_b32 s35, s28
	v_pk_mul_f32 v[134:135], v[114:115], s[10:11] op_sel:[1,0]
	v_pk_fma_f32 v[110:111], v[110:111], s[28:29], v[116:117] op_sel_hi:[0,1,1]
	v_mul_f32_e32 v116, 0xbf3504f3, v112
	v_pk_fma_f32 v[114:115], v[114:115], s[34:35], v[134:135] op_sel_hi:[0,1,1]
	v_pk_fma_f32 v[112:113], v[112:113], s[30:31], v[116:117] op_sel:[1,0,0] op_sel_hi:[1,1,0]
	s_nop 0
	v_pk_add_f32 v[116:117], v[108:109], v[112:113]
	v_pk_add_f32 v[130:131], v[108:109], v[112:113] neg_lo:[0,1] neg_hi:[0,1]
	v_pk_add_f32 v[108:109], v[110:111], v[114:115]
	v_pk_add_f32 v[110:111], v[110:111], v[114:115] neg_lo:[0,1] neg_hi:[0,1]
	v_pk_add_f32 v[112:113], v[116:117], v[108:109]
	v_xor_b32_e32 v115, 0x80000000, v110
	v_mov_b32_e32 v114, v111
	v_pk_add_f32 v[108:109], v[116:117], v[108:109] neg_lo:[0,1] neg_hi:[0,1]
	v_pk_add_f32 v[116:117], v[130:131], v[114:115] neg_lo:[0,1] neg_hi:[0,1]
	v_pk_add_f32 v[110:111], v[130:131], v[114:115]
	v_mov_b32_e32 v114, v116
	v_mov_b32_e32 v115, v117

.LBB0_1605:
	s_or_b64 exec, exec, s[6:7]
	v_add_u32_e32 v116, 0x1000, v128
	v_ashrrev_i32_e32 v116, 4, v116
	v_lshlrev_b32_e32 v116, 3, v116
	v_lshlrev_b32_e32 v135, 3, v128
	v_add3_u32 v134, 0, v116, v135
	v_add_u32_e32 v116, 0x1200, v128
	v_ashrrev_i32_e32 v116, 4, v116
	v_lshlrev_b32_e32 v116, 3, v116
	v_add3_u32 v133, 0, v116, v135
	v_add_u32_e32 v116, 0x1400, v128
	v_ashrrev_i32_e32 v116, 4, v116
	v_lshlrev_b32_e32 v116, 3, v116
	v_add3_u32 v132, 0, v116, v135
	v_add_u32_e32 v116, 0x1600, v128
	v_ashrrev_i32_e32 v116, 4, v116
	v_lshlrev_b32_e32 v116, 3, v116
	v_add3_u32 v131, 0, v116, v135
	v_add_u32_e32 v116, 0x1800, v128
	v_ashrrev_i32_e32 v116, 4, v116
	v_lshlrev_b32_e32 v116, 3, v116
	v_add3_u32 v130, 0, v116, v135
	v_add_u32_e32 v116, 0x1a00, v128
	v_ashrrev_i32_e32 v116, 4, v116
	v_lshlrev_b32_e32 v116, 3, v116
	v_add3_u32 v129, 0, v116, v135
	v_add_u32_e32 v116, 0x1c00, v128
	v_ashrrev_i32_e32 v116, 4, v116
	v_lshlrev_b32_e32 v116, 3, v116
	v_add3_u32 v117, 0, v116, v135
	v_add_u32_e32 v116, 0x1e00, v128
	v_ashrrev_i32_e32 v116, 4, v116
	s_waitcnt lgkmcnt(0)
	s_barrier
	v_lshlrev_b32_e32 v116, 3, v116
	v_add3_u32 v116, 0, v116, v135
	s_and_saveexec_b64 s[6:7], vcc
	s_cbranch_execz .LBB0_1607
	ds_read_b64 v[172:173], v136
	ds_read_b64 v[174:175], v124 offset:4096
	ds_read_b64 v[176:177], v122 offset:8192
	ds_read_b64 v[178:179], v65 offset:12288
	ds_read_b64 v[180:181], v31 offset:16384
	ds_read_b64 v[182:183], v23 offset:20480
	ds_read_b64 v[184:185], v15 offset:24576
	ds_read_b64 v[186:187], v11 offset:28672
	ds_read_b64 v[188:189], v134 offset:32768
	ds_read_b64 v[190:191], v133 offset:36864
	ds_read_b64 v[192:193], v132 offset:40960
	ds_read_b64 v[194:195], v131 offset:45056
	ds_read_b64 v[196:197], v130 offset:49152
	ds_read_b64 v[198:199], v129 offset:53248
	ds_read_b64 v[200:201], v117 offset:57344
	v_and_b32_e32 v108, 15, v128
	v_cvt_f32_ubyte0_e32 v108, v108
	v_mul_f32_e32 v109, 0x3b800000, v108
	v_cos_f32_e32 v108, v109
	v_sin_f32_e32 v110, v109
	s_waitcnt lgkmcnt(14)
	ds_read_b64 v[202:203], v116 offset:61440
	v_mov_b32_e32 v111, v108
	v_xor_b32_e32 v109, 0x80000000, v110
	v_pk_mul_f32 v[142:143], v[110:111], v[110:111] op_sel_hi:[1,0] neg_lo:[0,1] neg_hi:[0,1]
	s_mov_b32 s29, s26
	v_pk_fma_f32 v[142:143], v[108:109], v[108:109], v[142:143] op_sel_hi:[1,0,1]
	s_mov_b32 s8, s26
	v_pk_mul_f32 v[144:145], v[110:111], v[142:143] op_sel:[0,1]
	s_mov_b32 s9, s28
	v_pk_fma_f32 v[144:145], v[108:109], v[142:143], v[144:145] op_sel_hi:[1,0,1]
	s_mov_b32 s37, s20
	v_pk_mul_f32 v[146:147], v[110:111], v[144:145] op_sel:[0,1]
	s_mov_b32 s10, s27
	v_pk_fma_f32 v[146:147], v[108:109], v[144:145], v[146:147] op_sel_hi:[1,0,1]
	s_mov_b32 s11, s34
	v_pk_mul_f32 v[148:149], v[110:111], v[146:147] op_sel:[0,1]
	s_mov_b32 s35, s28
	v_pk_fma_f32 v[148:149], v[108:109], v[146:147], v[148:149] op_sel_hi:[1,0,1]
	s_nop 0
	v_pk_mul_f32 v[150:151], v[110:111], v[148:149] op_sel:[0,1]
	s_nop 0
	v_pk_fma_f32 v[150:151], v[108:109], v[148:149], v[150:151] op_sel_hi:[1,0,1]
	s_nop 0
	v_pk_mul_f32 v[152:153], v[110:111], v[150:151] op_sel:[0,1]
	s_nop 0
	v_pk_fma_f32 v[152:153], v[108:109], v[150:151], v[152:153] op_sel_hi:[1,0,1]
	s_nop 0
	v_pk_mul_f32 v[154:155], v[110:111], v[152:153] op_sel:[0,1]
	s_nop 0
	v_pk_fma_f32 v[154:155], v[108:109], v[152:153], v[154:155] op_sel_hi:[1,0,1]
	s_nop 0
	v_pk_mul_f32 v[156:157], v[110:111], v[154:155] op_sel:[0,1]
	s_nop 0
	v_pk_fma_f32 v[156:157], v[108:109], v[154:155], v[156:157] op_sel_hi:[1,0,1]
	s_nop 0
	v_pk_mul_f32 v[158:159], v[110:111], v[156:157] op_sel:[0,1]
	s_nop 0
	v_pk_fma_f32 v[158:159], v[108:109], v[156:157], v[158:159] op_sel_hi:[1,0,1]
	s_nop 0
	v_pk_mul_f32 v[160:161], v[110:111], v[158:159] op_sel:[0,1]
	s_nop 0
	v_pk_fma_f32 v[160:161], v[108:109], v[158:159], v[160:161] op_sel_hi:[1,0,1]
	s_nop 0
	v_pk_mul_f32 v[162:163], v[110:111], v[160:161] op_sel:[0,1]
	s_nop 0
	v_pk_fma_f32 v[162:163], v[108:109], v[160:161], v[162:163] op_sel_hi:[1,0,1]
	s_nop 0
	v_pk_mul_f32 v[164:165], v[110:111], v[162:163] op_sel:[0,1]
	s_nop 0
	v_pk_fma_f32 v[164:165], v[108:109], v[162:163], v[164:165] op_sel_hi:[1,0,1]
	s_nop 0
	v_pk_mul_f32 v[166:167], v[110:111], v[164:165] op_sel:[0,1]
	s_nop 0
	v_pk_fma_f32 v[166:167], v[108:109], v[164:165], v[166:167] op_sel_hi:[1,0,1]
	s_nop 0
	v_pk_mul_f32 v[168:169], v[110:111], v[166:167] op_sel:[0,1]
	s_waitcnt lgkmcnt(15)
	s_waitcnt lgkmcnt(14)
	v_pk_mul_f32 v[110:111], v[110:111], v[174:175] op_sel:[0,1]
	v_pk_fma_f32 v[168:169], v[108:109], v[166:167], v[168:169] op_sel_hi:[1,0,1]
	v_pk_fma_f32 v[86:87], v[108:109], v[174:175], v[110:111] op_sel_hi:[1,0,1]
	v_xor_b32_e32 v170, 0x80000000, v169
	v_mov_b32_e32 v171, v168
	s_waitcnt lgkmcnt(0)
	v_pk_mul_f32 v[170:171], v[170:171], v[202:203] op_sel:[0,1]
	s_nop 0
	v_pk_fma_f32 v[140:141], v[168:169], v[202:203], v[170:171] op_sel_hi:[1,0,1]
	v_xor_b32_e32 v168, 0x80000000, v167
	v_mov_b32_e32 v169, v166
	v_pk_mul_f32 v[168:169], v[168:169], v[200:201] op_sel:[0,1]
	s_nop 0
	v_pk_fma_f32 v[138:139], v[166:167], v[200:201], v[168:169] op_sel_hi:[1,0,1]
	v_xor_b32_e32 v166, 0x80000000, v165
	v_mov_b32_e32 v167, v164
	v_pk_mul_f32 v[166:167], v[166:167], v[198:199] op_sel:[0,1]
	s_nop 0
	v_pk_fma_f32 v[114:115], v[164:165], v[198:199], v[166:167] op_sel_hi:[1,0,1]
	v_xor_b32_e32 v164, 0x80000000, v163
	v_mov_b32_e32 v165, v162
	v_pk_mul_f32 v[164:165], v[164:165], v[196:197] op_sel:[0,1]
	s_nop 0
	v_pk_fma_f32 v[112:113], v[162:163], v[196:197], v[164:165] op_sel_hi:[1,0,1]
	v_xor_b32_e32 v162, 0x80000000, v161
	v_mov_b32_e32 v163, v160
	v_pk_mul_f32 v[162:163], v[162:163], v[194:195] op_sel:[0,1]
	s_nop 0
	v_pk_fma_f32 v[106:107], v[160:161], v[194:195], v[162:163] op_sel_hi:[1,0,1]
	v_xor_b32_e32 v160, 0x80000000, v159
	v_mov_b32_e32 v161, v158
	v_pk_mul_f32 v[160:161], v[160:161], v[192:193] op_sel:[0,1]
	s_nop 0
	v_pk_fma_f32 v[104:105], v[158:159], v[192:193], v[160:161] op_sel_hi:[1,0,1]
	v_xor_b32_e32 v158, 0x80000000, v157
	v_mov_b32_e32 v159, v156
	v_pk_mul_f32 v[158:159], v[158:159], v[190:191] op_sel:[0,1]
	s_nop 0
	v_pk_fma_f32 v[102:103], v[156:157], v[190:191], v[158:159] op_sel_hi:[1,0,1]
	v_xor_b32_e32 v156, 0x80000000, v155
	v_mov_b32_e32 v157, v154
	v_pk_mul_f32 v[156:157], v[156:157], v[188:189] op_sel:[0,1]
	s_nop 0
	v_pk_fma_f32 v[100:101], v[154:155], v[188:189], v[156:157] op_sel_hi:[1,0,1]
	v_xor_b32_e32 v154, 0x80000000, v153
	v_mov_b32_e32 v155, v152
	v_pk_mul_f32 v[154:155], v[154:155], v[186:187] op_sel:[0,1]
	v_pk_add_f32 v[108:109], v[172:173], v[100:101]
	v_pk_fma_f32 v[98:99], v[152:153], v[186:187], v[154:155] op_sel_hi:[1,0,1]
	v_xor_b32_e32 v152, 0x80000000, v151
	v_mov_b32_e32 v153, v150
	v_pk_mul_f32 v[152:153], v[152:153], v[184:185] op_sel:[0,1]
	v_pk_add_f32 v[110:111], v[172:173], v[100:101] neg_lo:[0,1] neg_hi:[0,1]
	v_pk_fma_f32 v[96:97], v[150:151], v[184:185], v[152:153] op_sel_hi:[1,0,1]
	v_xor_b32_e32 v150, 0x80000000, v149
	v_mov_b32_e32 v151, v148
	v_pk_mul_f32 v[150:151], v[150:151], v[182:183] op_sel:[0,1]
	s_nop 0
	v_pk_fma_f32 v[94:95], v[148:149], v[182:183], v[150:151] op_sel_hi:[1,0,1]
	v_xor_b32_e32 v148, 0x80000000, v147
	v_mov_b32_e32 v149, v146
	v_pk_mul_f32 v[148:149], v[148:149], v[180:181] op_sel:[0,1]
	s_nop 0
	v_pk_fma_f32 v[92:93], v[146:147], v[180:181], v[148:149] op_sel_hi:[1,0,1]
	v_xor_b32_e32 v146, 0x80000000, v145
	v_mov_b32_e32 v147, v144
	v_pk_mul_f32 v[146:147], v[146:147], v[178:179] op_sel:[0,1]
	v_pk_add_f32 v[84:85], v[92:93], v[112:113]
	v_pk_fma_f32 v[90:91], v[144:145], v[178:179], v[146:147] op_sel_hi:[1,0,1]
	v_xor_b32_e32 v144, 0x80000000, v143
	v_mov_b32_e32 v145, v142
	v_pk_mul_f32 v[144:145], v[144:145], v[176:177] op_sel:[0,1]
	v_pk_add_f32 v[100:101], v[108:109], v[84:85]
	v_pk_fma_f32 v[88:89], v[142:143], v[176:177], v[144:145] op_sel_hi:[1,0,1]
	v_pk_add_f32 v[108:109], v[108:109], v[84:85] neg_lo:[0,1] neg_hi:[0,1]
	v_pk_add_f32 v[84:85], v[86:87], v[102:103]
	v_pk_add_f32 v[142:143], v[86:87], v[102:103] neg_lo:[0,1] neg_hi:[0,1]
	v_pk_add_f32 v[86:87], v[94:95], v[114:115]
	v_pk_add_f32 v[94:95], v[94:95], v[114:115] neg_lo:[0,1] neg_hi:[0,1]
	v_pk_add_f32 v[102:103], v[84:85], v[86:87]
	v_pk_add_f32 v[114:115], v[84:85], v[86:87] neg_lo:[0,1] neg_hi:[0,1]
	v_pk_add_f32 v[84:85], v[88:89], v[104:105]
	v_pk_add_f32 v[86:87], v[96:97], v[138:139]
	v_pk_add_f32 v[146:147], v[88:89], v[104:105] neg_lo:[0,1] neg_hi:[0,1]
	v_pk_add_f32 v[88:89], v[96:97], v[138:139] neg_lo:[0,1] neg_hi:[0,1]
	v_pk_add_f32 v[96:97], v[84:85], v[86:87]
	v_pk_add_f32 v[104:105], v[84:85], v[86:87] neg_lo:[0,1] neg_hi:[0,1]
	v_pk_add_f32 v[84:85], v[90:91], v[106:107]
	v_pk_add_f32 v[86:87], v[98:99], v[140:141]
	v_xor_b32_e32 v139, 0x80000000, v88
	v_mov_b32_e32 v138, v89
	v_pk_add_f32 v[150:151], v[90:91], v[106:107] neg_lo:[0,1] neg_hi:[0,1]
	v_pk_add_f32 v[88:89], v[98:99], v[140:141] neg_lo:[0,1] neg_hi:[0,1]
	v_pk_add_f32 v[90:91], v[84:85], v[86:87]
	v_xor_b32_e32 v145, 0x80000000, v94
	v_mov_b32_e32 v144, v95
	v_pk_add_f32 v[106:107], v[84:85], v[86:87] neg_lo:[0,1] neg_hi:[0,1]
	v_xor_b32_e32 v141, 0x80000000, v88
	v_mov_b32_e32 v140, v89
	v_pk_add_f32 v[84:85], v[100:101], v[96:97]
	v_pk_add_f32 v[86:87], v[102:103], v[90:91]
	v_pk_add_f32 v[88:89], v[102:103], v[90:91] neg_lo:[0,1] neg_hi:[0,1]
	v_pk_add_f32 v[94:95], v[142:143], v[144:145]
	v_pk_add_f32 v[96:97], v[100:101], v[96:97] neg_lo:[0,1] neg_hi:[0,1]
	v_pk_add_f32 v[90:91], v[84:85], v[86:87]
	v_pk_add_f32 v[86:87], v[84:85], v[86:87] neg_lo:[0,1] neg_hi:[0,1]
	v_xor_b32_e32 v85, 0x80000000, v88
	v_mov_b32_e32 v84, v89
	v_pk_add_f32 v[92:93], v[92:93], v[112:113] neg_lo:[0,1] neg_hi:[0,1]
	v_pk_add_f32 v[148:149], v[146:147], v[138:139]
	v_pk_add_f32 v[98:99], v[150:151], v[140:141]
	v_pk_add_f32 v[88:89], v[96:97], v[84:85]
	v_pk_add_f32 v[84:85], v[96:97], v[84:85] neg_lo:[0,1] neg_hi:[0,1]
	v_pk_mul_f32 v[96:97], v[94:95], s[28:29] op_sel:[1,0]
	v_xor_b32_e32 v113, 0x80000000, v92
	v_mov_b32_e32 v112, v93
	v_pk_fma_f32 v[94:95], v[94:95], s[26:27], v[96:97] op_sel_hi:[0,1,1]
	v_mul_f32_e32 v96, 0x3f3504f3, v149
	s_mov_b32 s29, s34
	v_pk_mul_f32 v[100:101], v[98:99], s[8:9] op_sel:[1,0]
	v_pk_add_f32 v[92:93], v[110:111], v[112:113]
	v_pk_fma_f32 v[96:97], v[148:149], s[30:31], v[96:97] op_sel_hi:[0,1,0]
	v_pk_fma_f32 v[98:99], v[98:99], s[28:29], v[100:101] op_sel_hi:[0,1,1]
	v_pk_add_f32 v[100:101], v[92:93], v[96:97]
	v_pk_add_f32 v[92:93], v[92:93], v[96:97] neg_lo:[0,1] neg_hi:[0,1]
	v_pk_add_f32 v[96:97], v[94:95], v[98:99]
	v_pk_add_f32 v[102:103], v[94:95], v[98:99] neg_lo:[0,1] neg_hi:[0,1]
	v_pk_add_f32 v[98:99], v[100:101], v[96:97]
	v_pk_add_f32 v[94:95], v[100:101], v[96:97] neg_lo:[0,1] neg_hi:[0,1]
	v_xor_b32_e32 v101, 0x80000000, v102
	v_mov_b32_e32 v100, v103
	v_pk_mul_f32 v[102:103], v[104:105], s[36:37] op_sel:[1,0]
	v_pk_add_f32 v[96:97], v[92:93], v[100:101]
	v_pk_add_f32 v[92:93], v[92:93], v[100:101] neg_lo:[0,1] neg_hi:[0,1]
	v_mul_f32_e32 v100, 0x3f3504f3, v115
	v_pk_fma_f32 v[102:103], v[104:105], s[20:21], v[102:103] op_sel_hi:[0,1,1]
	v_mul_f32_e32 v104, 0xbf3504f3, v106
	v_pk_fma_f32 v[100:101], v[114:115], s[30:31], v[100:101] op_sel_hi:[0,1,0]
	v_pk_fma_f32 v[104:105], v[106:107], s[30:31], v[104:105] op_sel:[1,0,0] op_sel_hi:[1,1,0]
	v_pk_add_f32 v[114:115], v[108:109], v[102:103]
	v_pk_add_f32 v[108:109], v[108:109], v[102:103] neg_lo:[0,1] neg_hi:[0,1]
	v_pk_add_f32 v[102:103], v[100:101], v[104:105]
	v_pk_add_f32 v[100:101], v[100:101], v[104:105] neg_lo:[0,1] neg_hi:[0,1]
	v_pk_add_f32 v[106:107], v[114:115], v[102:103]
	v_pk_add_f32 v[102:103], v[114:115], v[102:103] neg_lo:[0,1] neg_hi:[0,1]
	v_xor_b32_e32 v115, 0x80000000, v100
	v_mov_b32_e32 v114, v101
	v_pk_add_f32 v[104:105], v[108:109], v[114:115]
	v_pk_add_f32 v[100:101], v[108:109], v[114:115] neg_lo:[0,1] neg_hi:[0,1]
	v_pk_add_f32 v[108:109], v[150:151], v[140:141] neg_lo:[0,1] neg_hi:[0,1]
	v_pk_add_f32 v[110:111], v[110:111], v[112:113] neg_lo:[0,1] neg_hi:[0,1]
	v_pk_mul_f32 v[114:115], v[108:109], s[10:11] op_sel:[1,0]
	v_pk_add_f32 v[112:113], v[142:143], v[144:145] neg_lo:[0,1] neg_hi:[0,1]
	v_pk_fma_f32 v[108:109], v[108:109], s[34:35], v[114:115] op_sel_hi:[0,1,1]
	v_pk_mul_f32 v[114:115], v[112:113], s[8:9] op_sel:[1,0]
	s_nop 0
	v_pk_fma_f32 v[112:113], v[112:113], s[28:29], v[114:115] op_sel_hi:[0,1,1]
	v_pk_add_f32 v[114:115], v[146:147], v[138:139] neg_lo:[0,1] neg_hi:[0,1]
	v_pk_add_f32 v[140:141], v[112:113], v[108:109] neg_lo:[0,1] neg_hi:[0,1]
	v_mul_f32_e32 v138, 0xbf3504f3, v114
	v_pk_fma_f32 v[114:115], v[114:115], s[30:31], v[138:139] op_sel:[1,0,0] op_sel_hi:[1,1,0]
	s_nop 0
	v_pk_add_f32 v[138:139], v[110:111], v[114:115]
	v_pk_add_f32 v[114:115], v[110:111], v[114:115] neg_lo:[0,1] neg_hi:[0,1]
	v_pk_add_f32 v[110:111], v[112:113], v[108:109]
	s_nop 0
	v_pk_add_f32 v[112:113], v[138:139], v[110:111]
	v_pk_add_f32 v[108:109], v[138:139], v[110:111] neg_lo:[0,1] neg_hi:[0,1]
	v_xor_b32_e32 v139, 0x80000000, v140
	v_mov_b32_e32 v138, v141
	v_pk_add_f32 v[110:111], v[114:115], v[138:139]
	v_pk_add_f32 v[114:115], v[114:115], v[138:139] neg_lo:[0,1] neg_hi:[0,1]

.LBB0_1609:
	s_or_b64 exec, exec, s[6:7]
	s_waitcnt lgkmcnt(0)
	s_barrier
	s_and_saveexec_b64 s[6:7], vcc
	s_cbranch_execz .LBB0_1611
	ds_read_b64 v[172:173], v136
	ds_read_b64 v[174:175], v124 offset:4096
	ds_read_b64 v[176:177], v122 offset:8192
	ds_read_b64 v[178:179], v65 offset:12288
	ds_read_b64 v[180:181], v31 offset:16384
	ds_read_b64 v[182:183], v23 offset:20480
	ds_read_b64 v[184:185], v15 offset:24576
	ds_read_b64 v[186:187], v11 offset:28672
	ds_read_b64 v[188:189], v134 offset:32768
	ds_read_b64 v[190:191], v133 offset:36864
	ds_read_b64 v[192:193], v132 offset:40960
	ds_read_b64 v[194:195], v131 offset:45056
	ds_read_b64 v[196:197], v130 offset:49152
	ds_read_b64 v[198:199], v129 offset:53248
	ds_read_b64 v[200:201], v117 offset:57344
	v_cvt_f32_ubyte0_e32 v108, v128
	v_mul_f32_e32 v109, 0x39800000, v108
	v_cos_f32_e32 v108, v109
	v_sin_f32_e32 v110, v109
	s_waitcnt lgkmcnt(14)
	ds_read_b64 v[202:203], v116 offset:61440
	v_mov_b32_e32 v111, v108
	v_xor_b32_e32 v109, 0x80000000, v110
	v_pk_mul_f32 v[142:143], v[110:111], v[110:111] op_sel_hi:[1,0] neg_lo:[0,1] neg_hi:[0,1]
	s_mov_b32 s29, s26
	v_pk_fma_f32 v[142:143], v[108:109], v[108:109], v[142:143] op_sel_hi:[1,0,1]
	s_mov_b32 s8, s26
	v_pk_mul_f32 v[144:145], v[110:111], v[142:143] op_sel:[0,1]
	s_mov_b32 s9, s28
	v_pk_fma_f32 v[144:145], v[108:109], v[142:143], v[144:145] op_sel_hi:[1,0,1]
	s_mov_b32 s37, s20
	v_pk_mul_f32 v[146:147], v[110:111], v[144:145] op_sel:[0,1]
	s_mov_b32 s10, s27
	v_pk_fma_f32 v[146:147], v[108:109], v[144:145], v[146:147] op_sel_hi:[1,0,1]
	s_mov_b32 s11, s34
	v_pk_mul_f32 v[148:149], v[110:111], v[146:147] op_sel:[0,1]
	s_mov_b32 s35, s28
	v_pk_fma_f32 v[148:149], v[108:109], v[146:147], v[148:149] op_sel_hi:[1,0,1]
	s_nop 0
	v_pk_mul_f32 v[150:151], v[110:111], v[148:149] op_sel:[0,1]
	s_nop 0
	v_pk_fma_f32 v[150:151], v[108:109], v[148:149], v[150:151] op_sel_hi:[1,0,1]
	s_nop 0
	v_pk_mul_f32 v[152:153], v[110:111], v[150:151] op_sel:[0,1]
	s_nop 0
	v_pk_fma_f32 v[152:153], v[108:109], v[150:151], v[152:153] op_sel_hi:[1,0,1]
	s_nop 0
	v_pk_mul_f32 v[154:155], v[110:111], v[152:153] op_sel:[0,1]
	s_nop 0
	v_pk_fma_f32 v[154:155], v[108:109], v[152:153], v[154:155] op_sel_hi:[1,0,1]
	s_nop 0
	v_pk_mul_f32 v[156:157], v[110:111], v[154:155] op_sel:[0,1]
	s_nop 0
	v_pk_fma_f32 v[156:157], v[108:109], v[154:155], v[156:157] op_sel_hi:[1,0,1]
	s_nop 0
	v_pk_mul_f32 v[158:159], v[110:111], v[156:157] op_sel:[0,1]
	s_nop 0
	v_pk_fma_f32 v[158:159], v[108:109], v[156:157], v[158:159] op_sel_hi:[1,0,1]
	s_nop 0
	v_pk_mul_f32 v[160:161], v[110:111], v[158:159] op_sel:[0,1]
	s_nop 0
	v_pk_fma_f32 v[160:161], v[108:109], v[158:159], v[160:161] op_sel_hi:[1,0,1]
	s_nop 0
	v_pk_mul_f32 v[162:163], v[110:111], v[160:161] op_sel:[0,1]
	s_nop 0
	v_pk_fma_f32 v[162:163], v[108:109], v[160:161], v[162:163] op_sel_hi:[1,0,1]
	s_nop 0
	v_pk_mul_f32 v[164:165], v[110:111], v[162:163] op_sel:[0,1]
	s_nop 0
	v_pk_fma_f32 v[164:165], v[108:109], v[162:163], v[164:165] op_sel_hi:[1,0,1]
	s_nop 0
	v_pk_mul_f32 v[166:167], v[110:111], v[164:165] op_sel:[0,1]
	s_nop 0
	v_pk_fma_f32 v[166:167], v[108:109], v[164:165], v[166:167] op_sel_hi:[1,0,1]
	s_nop 0
	v_pk_mul_f32 v[168:169], v[110:111], v[166:167] op_sel:[0,1]
	s_waitcnt lgkmcnt(15)
	s_waitcnt lgkmcnt(14)
	v_pk_mul_f32 v[110:111], v[110:111], v[174:175] op_sel:[0,1]
	v_pk_fma_f32 v[168:169], v[108:109], v[166:167], v[168:169] op_sel_hi:[1,0,1]
	v_pk_fma_f32 v[86:87], v[108:109], v[174:175], v[110:111] op_sel_hi:[1,0,1]
	v_xor_b32_e32 v170, 0x80000000, v169
	v_mov_b32_e32 v171, v168
	s_waitcnt lgkmcnt(0)
	v_pk_mul_f32 v[170:171], v[170:171], v[202:203] op_sel:[0,1]
	s_nop 0
	v_pk_fma_f32 v[140:141], v[168:169], v[202:203], v[170:171] op_sel_hi:[1,0,1]
	v_xor_b32_e32 v168, 0x80000000, v167
	v_mov_b32_e32 v169, v166
	v_pk_mul_f32 v[168:169], v[168:169], v[200:201] op_sel:[0,1]
	s_nop 0
	v_pk_fma_f32 v[138:139], v[166:167], v[200:201], v[168:169] op_sel_hi:[1,0,1]
	v_xor_b32_e32 v166, 0x80000000, v165
	v_mov_b32_e32 v167, v164
	v_pk_mul_f32 v[166:167], v[166:167], v[198:199] op_sel:[0,1]
	s_nop 0
	v_pk_fma_f32 v[114:115], v[164:165], v[198:199], v[166:167] op_sel_hi:[1,0,1]
	v_xor_b32_e32 v164, 0x80000000, v163
	v_mov_b32_e32 v165, v162
	v_pk_mul_f32 v[164:165], v[164:165], v[196:197] op_sel:[0,1]
	s_nop 0
	v_pk_fma_f32 v[112:113], v[162:163], v[196:197], v[164:165] op_sel_hi:[1,0,1]
	v_xor_b32_e32 v162, 0x80000000, v161
	v_mov_b32_e32 v163, v160
	v_pk_mul_f32 v[162:163], v[162:163], v[194:195] op_sel:[0,1]
	s_nop 0
	v_pk_fma_f32 v[106:107], v[160:161], v[194:195], v[162:163] op_sel_hi:[1,0,1]
	v_xor_b32_e32 v160, 0x80000000, v159
	v_mov_b32_e32 v161, v158
	v_pk_mul_f32 v[160:161], v[160:161], v[192:193] op_sel:[0,1]
	s_nop 0
	v_pk_fma_f32 v[104:105], v[158:159], v[192:193], v[160:161] op_sel_hi:[1,0,1]
	v_xor_b32_e32 v158, 0x80000000, v157
	v_mov_b32_e32 v159, v156
	v_pk_mul_f32 v[158:159], v[158:159], v[190:191] op_sel:[0,1]
	s_nop 0
	v_pk_fma_f32 v[102:103], v[156:157], v[190:191], v[158:159] op_sel_hi:[1,0,1]
	v_xor_b32_e32 v156, 0x80000000, v155
	v_mov_b32_e32 v157, v154
	v_pk_mul_f32 v[156:157], v[156:157], v[188:189] op_sel:[0,1]
	s_nop 0
	v_pk_fma_f32 v[100:101], v[154:155], v[188:189], v[156:157] op_sel_hi:[1,0,1]
	v_xor_b32_e32 v154, 0x80000000, v153
	v_mov_b32_e32 v155, v152
	v_pk_mul_f32 v[154:155], v[154:155], v[186:187] op_sel:[0,1]
	v_pk_add_f32 v[108:109], v[172:173], v[100:101]
	v_pk_fma_f32 v[98:99], v[152:153], v[186:187], v[154:155] op_sel_hi:[1,0,1]
	v_xor_b32_e32 v152, 0x80000000, v151
	v_mov_b32_e32 v153, v150
	v_pk_mul_f32 v[152:153], v[152:153], v[184:185] op_sel:[0,1]
	v_pk_add_f32 v[110:111], v[172:173], v[100:101] neg_lo:[0,1] neg_hi:[0,1]
	v_pk_fma_f32 v[96:97], v[150:151], v[184:185], v[152:153] op_sel_hi:[1,0,1]
	v_xor_b32_e32 v150, 0x80000000, v149
	v_mov_b32_e32 v151, v148
	v_pk_mul_f32 v[150:151], v[150:151], v[182:183] op_sel:[0,1]
	s_nop 0
	v_pk_fma_f32 v[94:95], v[148:149], v[182:183], v[150:151] op_sel_hi:[1,0,1]
	v_xor_b32_e32 v148, 0x80000000, v147
	v_mov_b32_e32 v149, v146
	v_pk_mul_f32 v[148:149], v[148:149], v[180:181] op_sel:[0,1]
	s_nop 0
	v_pk_fma_f32 v[92:93], v[146:147], v[180:181], v[148:149] op_sel_hi:[1,0,1]
	v_xor_b32_e32 v146, 0x80000000, v145
	v_mov_b32_e32 v147, v144
	v_pk_mul_f32 v[146:147], v[146:147], v[178:179] op_sel:[0,1]
	v_pk_add_f32 v[84:85], v[92:93], v[112:113]
	v_pk_fma_f32 v[90:91], v[144:145], v[178:179], v[146:147] op_sel_hi:[1,0,1]
	v_xor_b32_e32 v144, 0x80000000, v143
	v_mov_b32_e32 v145, v142
	v_pk_mul_f32 v[144:145], v[144:145], v[176:177] op_sel:[0,1]
	v_pk_add_f32 v[100:101], v[108:109], v[84:85]
	v_pk_fma_f32 v[88:89], v[142:143], v[176:177], v[144:145] op_sel_hi:[1,0,1]
	v_pk_add_f32 v[108:109], v[108:109], v[84:85] neg_lo:[0,1] neg_hi:[0,1]
	v_pk_add_f32 v[84:85], v[86:87], v[102:103]
	v_pk_add_f32 v[142:143], v[86:87], v[102:103] neg_lo:[0,1] neg_hi:[0,1]
	v_pk_add_f32 v[86:87], v[94:95], v[114:115]
	v_pk_add_f32 v[94:95], v[94:95], v[114:115] neg_lo:[0,1] neg_hi:[0,1]
	v_pk_add_f32 v[102:103], v[84:85], v[86:87]
	v_pk_add_f32 v[114:115], v[84:85], v[86:87] neg_lo:[0,1] neg_hi:[0,1]
	v_pk_add_f32 v[84:85], v[88:89], v[104:105]
	v_pk_add_f32 v[86:87], v[96:97], v[138:139]
	v_pk_add_f32 v[146:147], v[88:89], v[104:105] neg_lo:[0,1] neg_hi:[0,1]
	v_pk_add_f32 v[88:89], v[96:97], v[138:139] neg_lo:[0,1] neg_hi:[0,1]
	v_pk_add_f32 v[96:97], v[84:85], v[86:87]
	v_pk_add_f32 v[104:105], v[84:85], v[86:87] neg_lo:[0,1] neg_hi:[0,1]
	v_pk_add_f32 v[84:85], v[90:91], v[106:107]
	v_pk_add_f32 v[86:87], v[98:99], v[140:141]
	v_xor_b32_e32 v139, 0x80000000, v88
	v_mov_b32_e32 v138, v89
	v_pk_add_f32 v[150:151], v[90:91], v[106:107] neg_lo:[0,1] neg_hi:[0,1]
	v_pk_add_f32 v[88:89], v[98:99], v[140:141] neg_lo:[0,1] neg_hi:[0,1]
	v_pk_add_f32 v[90:91], v[84:85], v[86:87]
	v_xor_b32_e32 v145, 0x80000000, v94
	v_mov_b32_e32 v144, v95
	v_pk_add_f32 v[106:107], v[84:85], v[86:87] neg_lo:[0,1] neg_hi:[0,1]
	v_xor_b32_e32 v141, 0x80000000, v88
	v_mov_b32_e32 v140, v89
	v_pk_add_f32 v[84:85], v[100:101], v[96:97]
	v_pk_add_f32 v[86:87], v[102:103], v[90:91]
	v_pk_add_f32 v[88:89], v[102:103], v[90:91] neg_lo:[0,1] neg_hi:[0,1]
	v_pk_add_f32 v[94:95], v[142:143], v[144:145]
	v_pk_add_f32 v[96:97], v[100:101], v[96:97] neg_lo:[0,1] neg_hi:[0,1]
	v_pk_add_f32 v[90:91], v[84:85], v[86:87]
	v_pk_add_f32 v[86:87], v[84:85], v[86:87] neg_lo:[0,1] neg_hi:[0,1]
	v_xor_b32_e32 v85, 0x80000000, v88
	v_mov_b32_e32 v84, v89
	v_pk_add_f32 v[92:93], v[92:93], v[112:113] neg_lo:[0,1] neg_hi:[0,1]
	v_pk_add_f32 v[148:149], v[146:147], v[138:139]
	v_pk_add_f32 v[98:99], v[150:151], v[140:141]
	v_pk_add_f32 v[88:89], v[96:97], v[84:85]
	v_pk_add_f32 v[84:85], v[96:97], v[84:85] neg_lo:[0,1] neg_hi:[0,1]
	v_pk_mul_f32 v[96:97], v[94:95], s[28:29] op_sel:[1,0]
	v_xor_b32_e32 v113, 0x80000000, v92
	v_mov_b32_e32 v112, v93
	v_pk_fma_f32 v[94:95], v[94:95], s[26:27], v[96:97] op_sel_hi:[0,1,1]
	v_mul_f32_e32 v96, 0x3f3504f3, v149
	s_mov_b32 s29, s34
	v_pk_mul_f32 v[100:101], v[98:99], s[8:9] op_sel:[1,0]
	v_pk_add_f32 v[92:93], v[110:111], v[112:113]
	v_pk_fma_f32 v[96:97], v[148:149], s[30:31], v[96:97] op_sel_hi:[0,1,0]
	v_pk_fma_f32 v[98:99], v[98:99], s[28:29], v[100:101] op_sel_hi:[0,1,1]
	v_pk_add_f32 v[100:101], v[92:93], v[96:97]
	v_pk_add_f32 v[92:93], v[92:93], v[96:97] neg_lo:[0,1] neg_hi:[0,1]
	v_pk_add_f32 v[96:97], v[94:95], v[98:99]
	v_pk_add_f32 v[102:103], v[94:95], v[98:99] neg_lo:[0,1] neg_hi:[0,1]
	v_pk_add_f32 v[98:99], v[100:101], v[96:97]
	v_pk_add_f32 v[94:95], v[100:101], v[96:97] neg_lo:[0,1] neg_hi:[0,1]
	v_xor_b32_e32 v101, 0x80000000, v102
	v_mov_b32_e32 v100, v103
	v_pk_mul_f32 v[102:103], v[104:105], s[36:37] op_sel:[1,0]
	v_pk_add_f32 v[96:97], v[92:93], v[100:101]
	v_pk_add_f32 v[92:93], v[92:93], v[100:101] neg_lo:[0,1] neg_hi:[0,1]
	v_mul_f32_e32 v100, 0x3f3504f3, v115
	v_pk_fma_f32 v[102:103], v[104:105], s[20:21], v[102:103] op_sel_hi:[0,1,1]
	v_mul_f32_e32 v104, 0xbf3504f3, v106
	v_pk_fma_f32 v[100:101], v[114:115], s[30:31], v[100:101] op_sel_hi:[0,1,0]
	v_pk_fma_f32 v[104:105], v[106:107], s[30:31], v[104:105] op_sel:[1,0,0] op_sel_hi:[1,1,0]
	v_pk_add_f32 v[114:115], v[108:109], v[102:103]
	v_pk_add_f32 v[108:109], v[108:109], v[102:103] neg_lo:[0,1] neg_hi:[0,1]
	v_pk_add_f32 v[102:103], v[100:101], v[104:105]
	v_pk_add_f32 v[100:101], v[100:101], v[104:105] neg_lo:[0,1] neg_hi:[0,1]
	v_pk_add_f32 v[106:107], v[114:115], v[102:103]
	v_pk_add_f32 v[102:103], v[114:115], v[102:103] neg_lo:[0,1] neg_hi:[0,1]
	v_xor_b32_e32 v115, 0x80000000, v100
	v_mov_b32_e32 v114, v101
	v_pk_add_f32 v[104:105], v[108:109], v[114:115]
	v_pk_add_f32 v[100:101], v[108:109], v[114:115] neg_lo:[0,1] neg_hi:[0,1]
	v_pk_add_f32 v[108:109], v[150:151], v[140:141] neg_lo:[0,1] neg_hi:[0,1]
	v_pk_add_f32 v[110:111], v[110:111], v[112:113] neg_lo:[0,1] neg_hi:[0,1]
	v_pk_mul_f32 v[114:115], v[108:109], s[10:11] op_sel:[1,0]
	v_pk_add_f32 v[112:113], v[142:143], v[144:145] neg_lo:[0,1] neg_hi:[0,1]
	v_pk_fma_f32 v[108:109], v[108:109], s[34:35], v[114:115] op_sel_hi:[0,1,1]
	v_pk_mul_f32 v[114:115], v[112:113], s[8:9] op_sel:[1,0]
	s_nop 0
	v_pk_fma_f32 v[112:113], v[112:113], s[28:29], v[114:115] op_sel_hi:[0,1,1]
	v_pk_add_f32 v[114:115], v[146:147], v[138:139] neg_lo:[0,1] neg_hi:[0,1]
	v_pk_add_f32 v[140:141], v[112:113], v[108:109] neg_lo:[0,1] neg_hi:[0,1]
	v_mul_f32_e32 v136, 0xbf3504f3, v114
	v_pk_fma_f32 v[114:115], v[114:115], s[30:31], v[136:137] op_sel:[1,0,0] op_sel_hi:[1,1,0]
	s_nop 0
	v_pk_add_f32 v[138:139], v[110:111], v[114:115]
	v_pk_add_f32 v[114:115], v[110:111], v[114:115] neg_lo:[0,1] neg_hi:[0,1]
	v_pk_add_f32 v[110:111], v[112:113], v[108:109]
	s_nop 0
	v_pk_add_f32 v[112:113], v[138:139], v[110:111]
	v_pk_add_f32 v[108:109], v[138:139], v[110:111] neg_lo:[0,1] neg_hi:[0,1]
	v_xor_b32_e32 v139, 0x80000000, v140
	v_mov_b32_e32 v138, v141
	v_pk_add_f32 v[110:111], v[114:115], v[138:139]
	v_pk_add_f32 v[114:115], v[114:115], v[138:139] neg_lo:[0,1] neg_hi:[0,1]

.LBB0_1613:
	s_or_b64 exec, exec, s[6:7]
	s_waitcnt lgkmcnt(0)
	s_barrier
	s_and_saveexec_b64 s[6:7], vcc
	s_cbranch_execz .LBB0_1615
	ds_read_b64 v[172:173], v134 offset:32768
	v_cvt_f32_i32_e32 v86, v128
	v_lshlrev_b32_e32 v87, 3, v127
	v_add3_u32 v92, 0, v87, v135
	ds_read_b64 v[174:175], v92
	v_mul_f32_e32 v88, 0x39000000, v86
	v_sin_f32_e32 v86, v88
	v_cos_f32_e32 v88, v88
	v_cvt_f32_i32_e32 v67, v67
	v_xor_b32_e32 v89, 0x80000000, v86
	v_mov_b32_e32 v87, v88
	s_waitcnt lgkmcnt(2)
	s_waitcnt lgkmcnt(1)
	v_pk_mul_f32 v[86:87], v[86:87], v[172:173] op_sel:[0,1]
	v_cvt_f32_i32_e32 v63, v63
	v_pk_fma_f32 v[84:85], v[88:89], v[172:173], v[86:87] op_sel_hi:[1,0,1]
	v_cvt_f32_i32_e32 v88, v126
	s_waitcnt lgkmcnt(0)
	v_pk_add_f32 v[86:87], v[174:175], v[84:85]
	v_pk_add_f32 v[84:85], v[174:175], v[84:85] neg_lo:[0,1] neg_hi:[0,1]
	ds_write_b64 v92, v[86:87]
	ds_write_b64 v134, v[84:85] offset:32768
	ds_read_b64 v[172:173], v133 offset:36864
	ds_read_b64 v[174:175], v124 offset:4096
	v_mul_f32_e32 v85, 0x39000000, v88
	v_cos_f32_e32 v84, v85
	v_sin_f32_e32 v86, v85
	v_cvt_f32_i32_e32 v27, v27
	v_mov_b32_e32 v87, v84
	v_xor_b32_e32 v85, 0x80000000, v86
	s_waitcnt lgkmcnt(1)
	v_pk_mul_f32 v[86:87], v[86:87], v[172:173] op_sel:[0,1]
	v_cvt_f32_i32_e32 v19, v19
	v_pk_fma_f32 v[84:85], v[84:85], v[172:173], v[86:87] op_sel_hi:[1,0,1]
	v_cvt_f32_i32_e32 v88, v125
	s_waitcnt lgkmcnt(0)
	v_pk_add_f32 v[86:87], v[174:175], v[84:85]
	v_pk_add_f32 v[84:85], v[174:175], v[84:85] neg_lo:[0,1] neg_hi:[0,1]
	ds_write_b64 v124, v[86:87] offset:4096
	ds_write_b64 v133, v[84:85] offset:36864
	ds_read_b64 v[172:173], v132 offset:40960
	ds_read_b64 v[174:175], v122 offset:8192
	v_mul_f32_e32 v85, 0x39000000, v88
	v_cos_f32_e32 v84, v85
	v_sin_f32_e32 v86, v85
	s_nop 0
	v_mov_b32_e32 v87, v84
	v_xor_b32_e32 v85, 0x80000000, v86
	s_waitcnt lgkmcnt(1)
	v_pk_mul_f32 v[86:87], v[86:87], v[172:173] op_sel:[0,1]
	s_nop 0
	v_pk_fma_f32 v[84:85], v[84:85], v[172:173], v[86:87] op_sel_hi:[1,0,1]
	v_cvt_f32_i32_e32 v88, v123
	s_waitcnt lgkmcnt(0)
	v_pk_add_f32 v[86:87], v[174:175], v[84:85]
	v_pk_add_f32 v[84:85], v[174:175], v[84:85] neg_lo:[0,1] neg_hi:[0,1]
	ds_write_b64 v122, v[86:87] offset:8192
	ds_write_b64 v132, v[84:85] offset:40960
	ds_read_b64 v[172:173], v131 offset:45056
	ds_read_b64 v[174:175], v65 offset:12288
	v_mul_f32_e32 v85, 0x39000000, v88
	v_cos_f32_e32 v84, v85
	v_sin_f32_e32 v86, v85
	s_nop 0
	v_mov_b32_e32 v87, v84
	v_xor_b32_e32 v85, 0x80000000, v86
	s_waitcnt lgkmcnt(1)
	v_pk_mul_f32 v[86:87], v[86:87], v[172:173] op_sel:[0,1]
	s_nop 0
	v_pk_fma_f32 v[84:85], v[84:85], v[172:173], v[86:87] op_sel_hi:[1,0,1]
	s_waitcnt lgkmcnt(0)
	v_pk_add_f32 v[86:87], v[174:175], v[84:85]
	ds_write_b64 v65, v[86:87] offset:12288
	v_pk_add_f32 v[84:85], v[174:175], v[84:85] neg_lo:[0,1] neg_hi:[0,1]
	v_mul_f32_e32 v65, 0x39000000, v67
	ds_write_b64 v131, v[84:85] offset:45056
	ds_read_b64 v[172:173], v130 offset:49152
	ds_read_b64 v[174:175], v31 offset:16384
	v_cos_f32_e32 v84, v65
	v_sin_f32_e32 v86, v65
	s_nop 0
	v_mov_b32_e32 v87, v84
	v_xor_b32_e32 v85, 0x80000000, v86
	s_waitcnt lgkmcnt(1)
	v_pk_mul_f32 v[86:87], v[86:87], v[172:173] op_sel:[0,1]
	s_nop 0
	v_pk_fma_f32 v[84:85], v[84:85], v[172:173], v[86:87] op_sel_hi:[1,0,1]
	s_waitcnt lgkmcnt(0)
	v_pk_add_f32 v[86:87], v[174:175], v[84:85]
	ds_write_b64 v31, v[86:87] offset:16384
	v_pk_add_f32 v[84:85], v[174:175], v[84:85] neg_lo:[0,1] neg_hi:[0,1]
	v_mul_f32_e32 v31, 0x39000000, v63
	ds_write_b64 v130, v[84:85] offset:49152
	ds_read_b64 v[172:173], v129 offset:53248
	ds_read_b64 v[174:175], v23 offset:20480
	v_cos_f32_e32 v84, v31
	v_sin_f32_e32 v86, v31
	s_nop 0
	v_mov_b32_e32 v87, v84
	v_xor_b32_e32 v85, 0x80000000, v86
	s_waitcnt lgkmcnt(1)
	v_pk_mul_f32 v[86:87], v[86:87], v[172:173] op_sel:[0,1]
	s_nop 0
	v_pk_fma_f32 v[84:85], v[84:85], v[172:173], v[86:87] op_sel_hi:[1,0,1]
	s_waitcnt lgkmcnt(0)
	v_pk_add_f32 v[86:87], v[174:175], v[84:85]
	ds_write_b64 v23, v[86:87] offset:20480
	v_pk_add_f32 v[84:85], v[174:175], v[84:85] neg_lo:[0,1] neg_hi:[0,1]
	v_mul_f32_e32 v23, 0x39000000, v27
	ds_write_b64 v129, v[84:85] offset:53248
	ds_read_b64 v[172:173], v117 offset:57344
	ds_read_b64 v[174:175], v15 offset:24576
	v_cos_f32_e32 v84, v23
	v_sin_f32_e32 v86, v23
	s_nop 0
	v_mov_b32_e32 v87, v84
	v_xor_b32_e32 v85, 0x80000000, v86
	s_waitcnt lgkmcnt(1)
	v_pk_mul_f32 v[86:87], v[86:87], v[172:173] op_sel:[0,1]
	s_nop 0
	v_pk_fma_f32 v[84:85], v[84:85], v[172:173], v[86:87] op_sel_hi:[1,0,1]
	s_waitcnt lgkmcnt(0)
	v_pk_add_f32 v[86:87], v[174:175], v[84:85]
	ds_write_b64 v15, v[86:87] offset:24576
	v_pk_add_f32 v[84:85], v[174:175], v[84:85] neg_lo:[0,1] neg_hi:[0,1]
	v_mul_f32_e32 v15, 0x39000000, v19
	ds_write_b64 v117, v[84:85] offset:57344
	ds_read_b64 v[88:89], v116 offset:61440
	ds_read_b64 v[90:91], v11 offset:28672
	v_cos_f32_e32 v84, v15
	v_sin_f32_e32 v86, v15
	s_nop 0
	v_mov_b32_e32 v87, v84
	v_xor_b32_e32 v85, 0x80000000, v86
	s_waitcnt lgkmcnt(1)
	v_pk_mul_f32 v[86:87], v[86:87], v[88:89] op_sel:[0,1]
	s_nop 0
	v_pk_fma_f32 v[84:85], v[84:85], v[88:89], v[86:87] op_sel_hi:[1,0,1]
	s_waitcnt lgkmcnt(0)
	v_pk_add_f32 v[86:87], v[90:91], v[84:85]
	v_pk_add_f32 v[84:85], v[90:91], v[84:85] neg_lo:[0,1] neg_hi:[0,1]
	ds_write_b64 v11, v[86:87] offset:28672
	ds_write_b64 v116, v[84:85] offset:61440

.LBB0_1617:
	v_ashrrev_i32_e32 v19, 4, v15
	v_add_lshl_u32 v19, v15, v19, 3
	v_add_u32_e32 v23, s3, v19
	ds_read_b64 v[172:173], v23
	v_and_b32_e32 v23, 0x1fff, v11
	v_lshrrev_b32_e32 v27, 1, v11
	v_and_b32_e32 v27, 0xff8, v27
	v_lshlrev_b32_e32 v23, 3, v23
	v_add3_u32 v23, s3, v27, v23
	ds_read_b64 v[174:175], v23
	v_add_u32_e32 v19, 0, v19
	ds_read_b64 v[88:89], v19
	v_cmp_lt_i32_e32 vcc, s22, v15
	v_add_u32_e32 v11, 0xfffffe00, v11
	s_or_b64 s[8:9], vcc, s[8:9]
	s_waitcnt lgkmcnt(3)
	s_waitcnt lgkmcnt(1)
	v_pk_add_f32 v[90:91], v[172:173], v[174:175]
	v_pk_add_f32 v[86:87], v[172:173], v[174:175] neg_lo:[0,1] neg_hi:[0,1]
	s_nop 0
	v_mov_b32_e32 v91, v87
	v_pk_mul_f32 v[86:87], v[90:91], 0.5 op_sel_hi:[1,0]
	s_nop 0
	v_pk_mul_f32 v[86:87], v[84:85], v[86:87]
	s_nop 0
	v_xor_b32_e32 v90, 0x80000000, v87
	v_mov_b32_e32 v91, v86
	s_waitcnt lgkmcnt(0)
	v_pk_mul_f32 v[90:91], v[88:89], v[90:91] op_sel:[1,0]
	s_nop 0
	v_pk_fma_f32 v[86:87], v[88:89], v[86:87], v[90:91] op_sel_hi:[0,1,1]
	ds_write_b64 v19, v[86:87]
	v_add_u32_e32 v19, 0x200, v15
	v_mov_b32_e32 v15, v19
	s_andn2_b64 exec, exec, s[8:9]
	s_cbranch_execnz .LBB0_1617
.LBB0_1618:
	s_or_b64 exec, exec, s[6:7]
	v_mov_b32_e32 v132, v64
	s_waitcnt lgkmcnt(0)
	s_barrier
	v_mov_b32_e32 v116, 0
	v_add_u32_e32 v31, 0x1000, v132
	v_lshl_add_u32 v137, v132, 3, 0
	v_ashrrev_i32_e32 v31, 4, v31
	v_lshl_add_u32 v135, v31, 3, v137
	v_add_u32_e32 v31, 0x1200, v132
	v_ashrrev_i32_e32 v31, 4, v31
	v_lshl_add_u32 v134, v31, 3, v137
	v_add_u32_e32 v31, 0x1400, v132
	v_ashrrev_i32_e32 v31, 4, v31
	v_lshl_add_u32 v131, v31, 3, v137
	v_add_u32_e32 v31, 0x1600, v132
	v_ashrrev_i32_e32 v31, 4, v31
	v_add_u32_e32 v130, 0x200, v132
	v_lshl_add_u32 v129, v31, 3, v137
	v_add_u32_e32 v31, 0x1800, v132
	v_ashrrev_i32_e32 v11, 4, v130
	v_add_u32_e32 v128, 0x400, v132
	v_ashrrev_i32_e32 v31, 4, v31
	v_lshl_add_u32 v127, v11, 3, v137
	v_ashrrev_i32_e32 v11, 4, v128
	v_add_u32_e32 v125, 0x600, v132
	v_lshl_add_u32 v126, v31, 3, v137
	v_add_u32_e32 v31, 0x1a00, v132
	v_lshl_add_u32 v124, v11, 3, v137
	v_ashrrev_i32_e32 v11, 4, v125
	v_add_u32_e32 v122, 0x800, v132
	v_ashrrev_i32_e32 v31, 4, v31
	v_lshl_add_u32 v67, v11, 3, v137
	v_ashrrev_i32_e32 v11, 4, v122
	v_add_u32_e32 v63, 0xa00, v132
	v_lshl_add_u32 v123, v31, 3, v137
	v_add_u32_e32 v31, 0x1c00, v132
	v_lshl_add_u32 v59, v11, 3, v137
	v_ashrrev_i32_e32 v11, 4, v63
	v_add_u32_e32 v27, 0xc00, v132
	v_ashrrev_i32_e32 v31, 4, v31
	v_lshl_add_u32 v23, v11, 3, v137
	v_ashrrev_i32_e32 v11, 4, v27
	v_add_u32_e32 v19, 0xe00, v132
	v_lshl_add_u32 v65, v31, 3, v137
	v_add_u32_e32 v31, 0x1e00, v132
	v_ashrrev_i32_e32 v133, 4, v132
	v_lshl_add_u32 v15, v11, 3, v137
	v_ashrrev_i32_e32 v11, 4, v19
	v_ashrrev_i32_e32 v31, 4, v31
	v_cmp_gt_i32_e32 vcc, s70, v132
	v_lshl_add_u32 v136, v133, 3, v137
	v_lshl_add_u32 v11, v11, 3, v137
	v_lshl_add_u32 v31, v31, 3, v137
	v_mov_b32_e32 v117, 0
	v_mov_b32_e32 v88, 0
	v_mov_b32_e32 v89, v116
	v_mov_b32_e32 v96, v116
	v_mov_b32_e32 v97, v116
	v_mov_b32_e32 v104, v116
	v_mov_b32_e32 v105, v116
	v_mov_b32_e32 v110, v116
	v_mov_b32_e32 v111, v116
	v_mov_b32_e32 v90, v116
	v_mov_b32_e32 v91, v116
	v_mov_b32_e32 v98, v116
	v_mov_b32_e32 v99, v116
	v_mov_b32_e32 v106, v116
	v_mov_b32_e32 v107, v116
	v_mov_b32_e32 v112, v116
	v_mov_b32_e32 v113, v116
	v_mov_b32_e32 v86, v116
	v_mov_b32_e32 v87, v116
	v_mov_b32_e32 v94, v116
	v_mov_b32_e32 v95, v116
	v_mov_b32_e32 v102, v116
	v_mov_b32_e32 v103, v116
	v_mov_b32_e32 v108, v116
	v_mov_b32_e32 v109, v116
	v_mov_b32_e32 v84, v116
	v_mov_b32_e32 v85, v116
	v_mov_b32_e32 v92, v116
	v_mov_b32_e32 v93, v116
	v_mov_b32_e32 v100, v116
	v_mov_b32_e32 v101, v116
	v_mov_b32_e32 v114, v116
	v_mov_b32_e32 v115, v116
	s_and_saveexec_b64 s[6:7], vcc
	s_cbranch_execz .LBB0_1620
	ds_read_b64 v[172:173], v136
	ds_read_b64 v[174:175], v127 offset:4096
	ds_read_b64 v[176:177], v124 offset:8192
	ds_read_b64 v[178:179], v67 offset:12288
	ds_read_b64 v[180:181], v59 offset:16384
	ds_read_b64 v[182:183], v23 offset:20480
	ds_read_b64 v[184:185], v15 offset:24576
	ds_read_b64 v[186:187], v11 offset:28672
	ds_read_b64 v[188:189], v135 offset:32768
	ds_read_b64 v[190:191], v134 offset:36864
	ds_read_b64 v[192:193], v131 offset:40960
	ds_read_b64 v[194:195], v129 offset:45056
	ds_read_b64 v[196:197], v126 offset:49152
	ds_read_b64 v[198:199], v123 offset:53248
	ds_read_b64 v[200:201], v65 offset:57344
	s_waitcnt lgkmcnt(14)
	ds_read_b64 v[202:203], v31 offset:61440
	s_waitcnt lgkmcnt(15)
	s_waitcnt lgkmcnt(7)
	v_pk_add_f32 v[116:117], v[172:173], v[188:189]
	v_pk_add_f32 v[138:139], v[172:173], v[188:189] neg_lo:[0,1] neg_hi:[0,1]
	s_waitcnt lgkmcnt(3)
	v_pk_add_f32 v[84:85], v[180:181], v[196:197]
	v_pk_add_f32 v[92:93], v[180:181], v[196:197] neg_lo:[0,1] neg_hi:[0,1]
	v_pk_add_f32 v[100:101], v[116:117], v[84:85]
	v_pk_add_f32 v[108:109], v[116:117], v[84:85] neg_lo:[0,1] neg_hi:[0,1]
	v_pk_add_f32 v[84:85], v[174:175], v[190:191]
	v_pk_add_f32 v[140:141], v[174:175], v[190:191] neg_lo:[0,1] neg_hi:[0,1]
	s_waitcnt lgkmcnt(2)
	v_pk_add_f32 v[86:87], v[182:183], v[198:199]
	v_pk_add_f32 v[94:95], v[182:183], v[198:199] neg_lo:[0,1] neg_hi:[0,1]
	v_pk_add_f32 v[102:103], v[84:85], v[86:87]
	v_pk_add_f32 v[110:111], v[84:85], v[86:87] neg_lo:[0,1] neg_hi:[0,1]
	v_pk_add_f32 v[84:85], v[176:177], v[192:193]
	s_waitcnt lgkmcnt(1)
	v_pk_add_f32 v[86:87], v[184:185], v[200:201]
	v_pk_add_f32 v[144:145], v[176:177], v[192:193] neg_lo:[0,1] neg_hi:[0,1]
	v_pk_add_f32 v[88:89], v[184:185], v[200:201] neg_lo:[0,1] neg_hi:[0,1]
	v_pk_add_f32 v[96:97], v[84:85], v[86:87]
	v_pk_add_f32 v[104:105], v[84:85], v[86:87] neg_lo:[0,1] neg_hi:[0,1]
	v_pk_add_f32 v[84:85], v[178:179], v[194:195]
	s_waitcnt lgkmcnt(0)
	v_pk_add_f32 v[86:87], v[186:187], v[202:203]
	v_pk_add_f32 v[148:149], v[178:179], v[194:195] neg_lo:[0,1] neg_hi:[0,1]
	v_pk_add_f32 v[90:91], v[84:85], v[86:87]
	v_xor_b32_e32 v143, 0x80000000, v94
	v_mov_b32_e32 v142, v95
	v_xor_b32_e32 v113, 0x80000000, v88
	v_mov_b32_e32 v112, v89
	v_pk_add_f32 v[88:89], v[186:187], v[202:203] neg_lo:[0,1] neg_hi:[0,1]
	v_pk_add_f32 v[106:107], v[84:85], v[86:87] neg_lo:[0,1] neg_hi:[0,1]
	v_pk_add_f32 v[86:87], v[102:103], v[90:91]
	v_pk_add_f32 v[90:91], v[102:103], v[90:91] neg_lo:[0,1] neg_hi:[0,1]
	v_pk_add_f32 v[94:95], v[140:141], v[142:143] neg_lo:[0,1] neg_hi:[0,1]
	v_xor_b32_e32 v115, 0x80000000, v88
	v_mov_b32_e32 v114, v89
	v_pk_add_f32 v[84:85], v[100:101], v[96:97]
	v_pk_add_f32 v[96:97], v[100:101], v[96:97] neg_lo:[0,1] neg_hi:[0,1]
	v_xor_b32_e32 v101, 0x80000000, v90
	v_mov_b32_e32 v100, v91
	s_mov_b32 s10, s27
	s_mov_b32 s11, s26
	v_pk_add_f32 v[146:147], v[144:145], v[112:113] neg_lo:[0,1] neg_hi:[0,1]
	v_pk_add_f32 v[98:99], v[148:149], v[114:115] neg_lo:[0,1] neg_hi:[0,1]
	v_pk_add_f32 v[88:89], v[84:85], v[86:87]
	v_pk_add_f32 v[86:87], v[84:85], v[86:87] neg_lo:[0,1] neg_hi:[0,1]
	v_pk_add_f32 v[84:85], v[96:97], v[100:101]
	v_pk_add_f32 v[90:91], v[96:97], v[100:101] neg_lo:[0,1] neg_hi:[0,1]
	s_mov_b32 s8, s26
	s_mov_b32 s9, s28
	v_pk_mul_f32 v[96:97], v[94:95], s[10:11] op_sel:[1,0]
	s_mov_b32 s35, s28
	v_xor_b32_e32 v117, 0x80000000, v92
	v_mov_b32_e32 v116, v93
	v_pk_fma_f32 v[94:95], v[94:95], s[8:9], v[96:97] op_sel_hi:[0,1,1]
	v_mul_f32_e32 v96, 0x3f3504f3, v146
	s_mov_b32 s8, s31
	s_mov_b32 s9, s30
	s_mov_b32 s29, s26
	v_pk_mul_f32 v[100:101], v[98:99], s[34:35] op_sel:[1,0]
	v_pk_add_f32 v[92:93], v[138:139], v[116:117] neg_lo:[0,1] neg_hi:[0,1]
	v_pk_fma_f32 v[96:97], v[146:147], s[8:9], v[96:97] op_sel:[1,0,0] op_sel_hi:[1,1,0]
	v_pk_fma_f32 v[98:99], v[98:99], s[28:29], v[100:101] op_sel_hi:[0,1,1]
	v_pk_add_f32 v[100:101], v[92:93], v[96:97]
	v_pk_add_f32 v[102:103], v[92:93], v[96:97] neg_lo:[0,1] neg_hi:[0,1]
	v_pk_add_f32 v[92:93], v[94:95], v[98:99]
	v_pk_add_f32 v[98:99], v[94:95], v[98:99] neg_lo:[0,1] neg_hi:[0,1]
	v_pk_add_f32 v[96:97], v[100:101], v[92:93]
	v_pk_add_f32 v[94:95], v[100:101], v[92:93] neg_lo:[0,1] neg_hi:[0,1]
	v_xor_b32_e32 v101, 0x80000000, v98
	v_mov_b32_e32 v100, v99
	s_mov_b32 s12, s21
	s_mov_b32 s13, s20
	v_pk_add_f32 v[92:93], v[102:103], v[100:101]
	v_pk_add_f32 v[98:99], v[102:103], v[100:101] neg_lo:[0,1] neg_hi:[0,1]
	s_mov_b32 s10, s20
	s_mov_b32 s11, s36
	v_pk_mul_f32 v[102:103], v[104:105], s[12:13] op_sel:[1,0]
	v_mul_f32_e32 v100, 0x3f3504f3, v110
	v_pk_fma_f32 v[102:103], v[104:105], s[10:11], v[102:103] op_sel_hi:[0,1,1]
	v_mul_f32_e32 v104, 0xbf3504f3, v107
	v_pk_fma_f32 v[100:101], v[110:111], s[8:9], v[100:101] op_sel:[1,0,0] op_sel_hi:[1,1,0]
	v_pk_fma_f32 v[104:105], v[106:107], s[8:9], v[104:105] op_sel_hi:[0,1,0]
	v_pk_add_f32 v[106:107], v[108:109], v[102:103]
	v_pk_add_f32 v[108:109], v[108:109], v[102:103] neg_lo:[0,1] neg_hi:[0,1]
	v_pk_add_f32 v[102:103], v[100:101], v[104:105]
	v_pk_add_f32 v[100:101], v[100:101], v[104:105] neg_lo:[0,1] neg_hi:[0,1]
	v_pk_add_f32 v[104:105], v[106:107], v[102:103]
	v_pk_add_f32 v[102:103], v[106:107], v[102:103] neg_lo:[0,1] neg_hi:[0,1]
	v_xor_b32_e32 v107, 0x80000000, v100
	v_mov_b32_e32 v106, v101
	v_pk_add_f32 v[100:101], v[108:109], v[106:107]
	v_pk_add_f32 v[106:107], v[108:109], v[106:107] neg_lo:[0,1] neg_hi:[0,1]
	v_pk_add_f32 v[108:109], v[148:149], v[114:115]
	s_mov_b32 s12, s28
	s_mov_b32 s13, s34
	s_mov_b32 s10, s34
	s_mov_b32 s11, s27
	v_pk_mul_f32 v[110:111], v[108:109], s[12:13] op_sel:[1,0]
	v_pk_add_f32 v[114:115], v[140:141], v[142:143]
	v_pk_fma_f32 v[108:109], v[108:109], s[10:11], v[110:111] op_sel_hi:[0,1,1]
	v_pk_add_f32 v[110:111], v[138:139], v[116:117]
	v_pk_mul_f32 v[116:117], v[114:115], s[34:35] op_sel:[1,0]
	v_pk_add_f32 v[112:113], v[144:145], v[112:113]
	v_pk_fma_f32 v[114:115], v[114:115], s[28:29], v[116:117] op_sel_hi:[0,1,1]
	v_mul_f32_e32 v116, 0xbf3504f3, v113
	v_pk_fma_f32 v[112:113], v[112:113], s[8:9], v[116:117] op_sel_hi:[0,1,0]
	v_pk_add_f32 v[116:117], v[110:111], v[112:113]
	v_pk_add_f32 v[138:139], v[114:115], v[108:109]
	v_pk_add_f32 v[114:115], v[114:115], v[108:109] neg_lo:[0,1] neg_hi:[0,1]
	v_pk_add_f32 v[112:113], v[110:111], v[112:113] neg_lo:[0,1] neg_hi:[0,1]
	v_pk_add_f32 v[110:111], v[116:117], v[138:139]
	v_pk_add_f32 v[108:109], v[116:117], v[138:139] neg_lo:[0,1] neg_hi:[0,1]
	v_xor_b32_e32 v139, 0x80000000, v114
	v_mov_b32_e32 v138, v115
	v_pk_add_f32 v[116:117], v[112:113], v[138:139]
	v_pk_add_f32 v[112:113], v[112:113], v[138:139] neg_lo:[0,1] neg_hi:[0,1]
	v_mov_b32_e32 v114, v116
	v_mov_b32_e32 v115, v117

.LBB0_1622:
	s_or_b64 exec, exec, s[6:7]
	s_waitcnt lgkmcnt(0)
	s_barrier
	s_and_saveexec_b64 s[6:7], vcc
	s_cbranch_execz .LBB0_1624
	ds_read_b64 v[172:173], v31 offset:61440
	ds_read_b64 v[174:175], v65 offset:57344
	ds_read_b64 v[176:177], v123 offset:53248
	ds_read_b64 v[178:179], v126 offset:49152
	ds_read_b64 v[180:181], v129 offset:45056
	ds_read_b64 v[182:183], v131 offset:40960
	ds_read_b64 v[184:185], v136
	ds_read_b64 v[186:187], v127 offset:4096
	ds_read_b64 v[188:189], v124 offset:8192
	ds_read_b64 v[190:191], v67 offset:12288
	ds_read_b64 v[192:193], v59 offset:16384
	ds_read_b64 v[194:195], v23 offset:20480
	ds_read_b64 v[196:197], v15 offset:24576
	ds_read_b64 v[198:199], v11 offset:28672
	ds_read_b64 v[200:201], v135 offset:32768
	v_and_b32_e32 v84, 15, v132
	v_cvt_f32_ubyte0_e32 v84, v84
	v_mul_f32_e32 v84, 0x3b800000, v84
	v_cos_f32_e32 v98, v84
	v_sin_f32_e32 v99, v84
	s_mov_b32 s10, s27
	v_mov_b32_e32 v101, v98
	v_xor_b32_e32 v100, 0x80000000, v99
	v_mov_b32_e32 v84, v99
	v_pk_mul_f32 v[84:85], v[100:101], v[84:85] op_sel_hi:[1,0]
	s_mov_b32 s11, s26
	v_pk_fma_f32 v[106:107], v[98:99], v[98:99], v[84:85] op_sel_hi:[1,0,1]
	s_mov_b32 s8, s26
	v_pk_mul_f32 v[84:85], v[100:101], v[106:107] op_sel:[0,1]
	s_mov_b32 s9, s28
	v_pk_fma_f32 v[110:111], v[98:99], v[106:107], v[84:85] op_sel_hi:[1,0,1]
	s_mov_b32 s35, s28
	v_pk_mul_f32 v[84:85], v[100:101], v[110:111] op_sel:[0,1]
	s_mov_b32 s29, s26
	v_pk_fma_f32 v[112:113], v[98:99], v[110:111], v[84:85] op_sel_hi:[1,0,1]
	s_mov_b32 s12, s21
	v_pk_mul_f32 v[84:85], v[100:101], v[112:113] op_sel:[0,1]
	s_mov_b32 s13, s20
	v_pk_fma_f32 v[114:115], v[98:99], v[112:113], v[84:85] op_sel_hi:[1,0,1]
	s_nop 0
	v_pk_mul_f32 v[84:85], v[100:101], v[114:115] op_sel:[0,1]
	s_nop 0
	v_pk_fma_f32 v[116:117], v[98:99], v[114:115], v[84:85] op_sel_hi:[1,0,1]
	s_nop 0
	v_pk_mul_f32 v[84:85], v[100:101], v[116:117] op_sel:[0,1]
	s_nop 0
	v_pk_fma_f32 v[138:139], v[98:99], v[116:117], v[84:85] op_sel_hi:[1,0,1]
	s_nop 0
	v_pk_mul_f32 v[84:85], v[100:101], v[138:139] op_sel:[0,1]
	s_nop 0
	v_pk_fma_f32 v[102:103], v[98:99], v[138:139], v[84:85] op_sel_hi:[1,0,1]
	s_nop 0
	v_pk_mul_f32 v[84:85], v[100:101], v[102:103] op_sel:[0,1]
	s_nop 0
	v_pk_fma_f32 v[86:87], v[98:99], v[102:103], v[84:85] op_sel_hi:[1,0,1]
	s_nop 0
	v_pk_mul_f32 v[84:85], v[100:101], v[86:87] op_sel:[0,1]
	s_nop 0
	v_pk_fma_f32 v[96:97], v[98:99], v[86:87], v[84:85] op_sel_hi:[1,0,1]
	s_nop 0
	v_pk_mul_f32 v[84:85], v[100:101], v[96:97] op_sel:[0,1]
	s_nop 0
	v_pk_fma_f32 v[92:93], v[98:99], v[96:97], v[84:85] op_sel_hi:[1,0,1]
	s_nop 0
	v_pk_mul_f32 v[84:85], v[100:101], v[92:93] op_sel:[0,1]
	s_nop 0
	v_pk_fma_f32 v[94:95], v[98:99], v[92:93], v[84:85] op_sel_hi:[1,0,1]
	s_nop 0
	v_pk_mul_f32 v[84:85], v[100:101], v[94:95] op_sel:[0,1]
	s_nop 0
	v_pk_fma_f32 v[90:91], v[98:99], v[94:95], v[84:85] op_sel_hi:[1,0,1]
	s_nop 0
	v_pk_mul_f32 v[84:85], v[100:101], v[90:91] op_sel:[0,1]
	s_nop 0
	v_pk_fma_f32 v[88:89], v[98:99], v[90:91], v[84:85] op_sel_hi:[1,0,1]
	s_nop 0
	v_pk_mul_f32 v[84:85], v[100:101], v[88:89] op_sel:[0,1]
	s_nop 0
	v_pk_fma_f32 v[84:85], v[98:99], v[88:89], v[84:85] op_sel_hi:[1,0,1]
	s_nop 0
	v_xor_b32_e32 v108, 0x80000000, v85
	v_mov_b32_e32 v109, v84
	s_waitcnt lgkmcnt(15)
	s_waitcnt lgkmcnt(14)
	v_pk_mul_f32 v[108:109], v[108:109], v[172:173] op_sel:[0,1]
	s_nop 0
	v_pk_fma_f32 v[84:85], v[84:85], v[172:173], v[108:109] op_sel_hi:[1,0,1]
	ds_read_b64 v[172:173], v134 offset:36864
	v_xor_b32_e32 v108, 0x80000000, v89
	v_mov_b32_e32 v109, v88
	s_waitcnt lgkmcnt(14)
	v_pk_mul_f32 v[108:109], v[108:109], v[174:175] op_sel:[0,1]
	s_nop 0
	v_pk_fma_f32 v[88:89], v[88:89], v[174:175], v[108:109] op_sel_hi:[1,0,1]
	v_xor_b32_e32 v108, 0x80000000, v91
	v_mov_b32_e32 v109, v90
	s_waitcnt lgkmcnt(13)
	v_pk_mul_f32 v[108:109], v[108:109], v[176:177] op_sel:[0,1]
	s_nop 0
	v_pk_fma_f32 v[90:91], v[90:91], v[176:177], v[108:109] op_sel_hi:[1,0,1]
	v_xor_b32_e32 v108, 0x80000000, v95
	v_mov_b32_e32 v109, v94
	s_waitcnt lgkmcnt(12)
	v_pk_mul_f32 v[108:109], v[108:109], v[178:179] op_sel:[0,1]
	s_nop 0
	v_pk_fma_f32 v[94:95], v[94:95], v[178:179], v[108:109] op_sel_hi:[1,0,1]
	v_xor_b32_e32 v108, 0x80000000, v93
	v_mov_b32_e32 v109, v92
	s_waitcnt lgkmcnt(11)
	v_pk_mul_f32 v[108:109], v[108:109], v[180:181] op_sel:[0,1]
	s_nop 0
	v_pk_fma_f32 v[92:93], v[92:93], v[180:181], v[108:109] op_sel_hi:[1,0,1]
	v_xor_b32_e32 v108, 0x80000000, v97
	v_mov_b32_e32 v109, v96
	s_waitcnt lgkmcnt(10)
	v_pk_mul_f32 v[108:109], v[108:109], v[182:183] op_sel:[0,1]
	s_nop 0
	v_pk_fma_f32 v[96:97], v[96:97], v[182:183], v[108:109] op_sel_hi:[1,0,1]
	s_waitcnt lgkmcnt(8)
	v_pk_mul_f32 v[100:101], v[100:101], v[186:187] op_sel:[0,1]
	s_nop 0
	v_pk_fma_f32 v[104:105], v[98:99], v[186:187], v[100:101] op_sel_hi:[1,0,1]
	v_xor_b32_e32 v100, 0x80000000, v107
	v_mov_b32_e32 v101, v106
	s_waitcnt lgkmcnt(7)
	v_pk_mul_f32 v[100:101], v[100:101], v[188:189] op_sel:[0,1]
	s_nop 0
	v_pk_fma_f32 v[100:101], v[106:107], v[188:189], v[100:101] op_sel_hi:[1,0,1]
	v_xor_b32_e32 v106, 0x80000000, v111
	v_mov_b32_e32 v107, v110
	v_pk_add_f32 v[144:145], v[100:101], v[96:97] neg_lo:[0,1] neg_hi:[0,1]
	s_waitcnt lgkmcnt(6)
	v_pk_mul_f32 v[106:107], v[106:107], v[190:191] op_sel:[0,1]
	s_nop 0
	v_pk_fma_f32 v[98:99], v[110:111], v[190:191], v[106:107] op_sel_hi:[1,0,1]
	v_xor_b32_e32 v110, 0x80000000, v113
	v_mov_b32_e32 v111, v112
	v_pk_add_f32 v[148:149], v[98:99], v[92:93] neg_lo:[0,1] neg_hi:[0,1]
	s_waitcnt lgkmcnt(5)
	v_pk_mul_f32 v[110:111], v[110:111], v[192:193] op_sel:[0,1]
	s_nop 0
	v_pk_fma_f32 v[110:111], v[112:113], v[192:193], v[110:111] op_sel_hi:[1,0,1]
	v_xor_b32_e32 v112, 0x80000000, v115
	v_mov_b32_e32 v113, v114
	s_waitcnt lgkmcnt(4)
	v_pk_mul_f32 v[112:113], v[112:113], v[194:195] op_sel:[0,1]
	s_nop 0
	v_pk_fma_f32 v[112:113], v[114:115], v[194:195], v[112:113] op_sel_hi:[1,0,1]
	v_xor_b32_e32 v114, 0x80000000, v117
	v_mov_b32_e32 v115, v116
	s_waitcnt lgkmcnt(3)
	v_pk_mul_f32 v[114:115], v[114:115], v[196:197] op_sel:[0,1]
	s_nop 0
	v_pk_fma_f32 v[114:115], v[116:117], v[196:197], v[114:115] op_sel_hi:[1,0,1]
	v_xor_b32_e32 v116, 0x80000000, v139
	v_mov_b32_e32 v117, v138
	s_waitcnt lgkmcnt(2)
	v_pk_mul_f32 v[116:117], v[116:117], v[198:199] op_sel:[0,1]
	s_nop 0
	v_pk_fma_f32 v[106:107], v[138:139], v[198:199], v[116:117] op_sel_hi:[1,0,1]
	v_xor_b32_e32 v138, 0x80000000, v103
	v_mov_b32_e32 v139, v102
	s_waitcnt lgkmcnt(1)
	v_pk_mul_f32 v[138:139], v[138:139], v[200:201] op_sel:[0,1]
	s_nop 0
	v_pk_fma_f32 v[102:103], v[102:103], v[200:201], v[138:139] op_sel_hi:[1,0,1]
	v_xor_b32_e32 v138, 0x80000000, v87
	v_mov_b32_e32 v139, v86
	s_waitcnt lgkmcnt(0)
	v_pk_mul_f32 v[138:139], v[138:139], v[172:173] op_sel:[0,1]
	s_nop 0
	v_pk_fma_f32 v[86:87], v[86:87], v[172:173], v[138:139] op_sel_hi:[1,0,1]
	v_pk_add_f32 v[116:117], v[184:185], v[102:103]
	v_pk_add_f32 v[138:139], v[104:105], v[86:87]
	v_pk_add_f32 v[140:141], v[104:105], v[86:87] neg_lo:[0,1] neg_hi:[0,1]
	v_pk_add_f32 v[86:87], v[90:91], v[112:113]
	v_pk_add_f32 v[90:91], v[112:113], v[90:91] neg_lo:[0,1] neg_hi:[0,1]
	v_pk_add_f32 v[104:105], v[86:87], v[138:139]
	v_pk_add_f32 v[112:113], v[138:139], v[86:87] neg_lo:[0,1] neg_hi:[0,1]
	v_xor_b32_e32 v139, 0x80000000, v90
	v_mov_b32_e32 v138, v91
	v_pk_add_f32 v[86:87], v[96:97], v[100:101]
	v_pk_add_f32 v[90:91], v[88:89], v[114:115]
	v_pk_add_f32 v[88:89], v[114:115], v[88:89] neg_lo:[0,1] neg_hi:[0,1]
	v_pk_add_f32 v[96:97], v[86:87], v[90:91]
	v_pk_add_f32 v[100:101], v[86:87], v[90:91] neg_lo:[0,1] neg_hi:[0,1]
	v_xor_b32_e32 v115, 0x80000000, v88
	v_mov_b32_e32 v114, v89
	v_pk_add_f32 v[86:87], v[92:93], v[98:99]
	v_pk_add_f32 v[88:89], v[84:85], v[106:107]
	v_pk_add_f32 v[108:109], v[184:185], v[102:103] neg_lo:[0,1] neg_hi:[0,1]
	v_pk_add_f32 v[102:103], v[94:95], v[110:111]
	v_pk_add_f32 v[90:91], v[86:87], v[88:89]
	v_pk_add_f32 v[94:95], v[110:111], v[94:95] neg_lo:[0,1] neg_hi:[0,1]
	v_pk_add_f32 v[110:111], v[102:103], v[116:117]
	v_pk_add_f32 v[84:85], v[106:107], v[84:85] neg_lo:[0,1] neg_hi:[0,1]
	v_pk_add_f32 v[106:107], v[86:87], v[88:89] neg_lo:[0,1] neg_hi:[0,1]
	v_pk_add_f32 v[86:87], v[90:91], v[104:105]
	v_pk_add_f32 v[90:91], v[104:105], v[90:91] neg_lo:[0,1] neg_hi:[0,1]
	v_pk_add_f32 v[142:143], v[140:141], v[138:139] neg_lo:[0,1] neg_hi:[0,1]
	v_xor_b32_e32 v151, 0x80000000, v84
	v_mov_b32_e32 v150, v85
	v_pk_add_f32 v[84:85], v[96:97], v[110:111]
	v_pk_add_f32 v[96:97], v[110:111], v[96:97] neg_lo:[0,1] neg_hi:[0,1]
	v_xor_b32_e32 v99, 0x80000000, v90
	v_mov_b32_e32 v98, v91
	v_pk_add_f32 v[146:147], v[144:145], v[114:115] neg_lo:[0,1] neg_hi:[0,1]
	v_pk_add_f32 v[92:93], v[148:149], v[150:151] neg_lo:[0,1] neg_hi:[0,1]
	v_pk_add_f32 v[88:89], v[84:85], v[86:87]
	v_pk_add_f32 v[86:87], v[84:85], v[86:87] neg_lo:[0,1] neg_hi:[0,1]
	v_pk_add_f32 v[84:85], v[96:97], v[98:99]
	v_pk_add_f32 v[90:91], v[96:97], v[98:99] neg_lo:[0,1] neg_hi:[0,1]
	v_pk_mul_f32 v[96:97], v[142:143], s[10:11] op_sel:[1,0]
	v_pk_add_f32 v[102:103], v[116:117], v[102:103] neg_lo:[0,1] neg_hi:[0,1]
	v_xor_b32_e32 v117, 0x80000000, v94
	v_mov_b32_e32 v116, v95
	v_pk_fma_f32 v[96:97], v[142:143], s[8:9], v[96:97] op_sel_hi:[0,1,1]
	v_mul_f32_e32 v98, 0x3f3504f3, v146
	s_mov_b32 s8, s31
	s_mov_b32 s9, s30
	v_pk_mul_f32 v[104:105], v[92:93], s[34:35] op_sel:[1,0]
	v_pk_add_f32 v[94:95], v[108:109], v[116:117] neg_lo:[0,1] neg_hi:[0,1]
	v_pk_fma_f32 v[98:99], v[146:147], s[8:9], v[98:99] op_sel:[1,0,0] op_sel_hi:[1,1,0]
	v_pk_fma_f32 v[92:93], v[92:93], s[28:29], v[104:105] op_sel_hi:[0,1,1]
	v_pk_add_f32 v[104:105], v[94:95], v[98:99]
	v_pk_add_f32 v[98:99], v[94:95], v[98:99] neg_lo:[0,1] neg_hi:[0,1]
	v_pk_add_f32 v[94:95], v[96:97], v[92:93]
	v_pk_add_f32 v[92:93], v[96:97], v[92:93] neg_lo:[0,1] neg_hi:[0,1]
	v_pk_add_f32 v[96:97], v[104:105], v[94:95]
	v_pk_add_f32 v[94:95], v[104:105], v[94:95] neg_lo:[0,1] neg_hi:[0,1]
	v_xor_b32_e32 v105, 0x80000000, v92
	v_mov_b32_e32 v104, v93
	s_mov_b32 s10, s20
	s_mov_b32 s11, s36
	v_pk_mul_f32 v[110:111], v[100:101], s[12:13] op_sel:[1,0]
	v_pk_add_f32 v[92:93], v[98:99], v[104:105]
	v_pk_add_f32 v[98:99], v[98:99], v[104:105] neg_lo:[0,1] neg_hi:[0,1]
	v_mul_f32_e32 v104, 0x3f3504f3, v112
	v_pk_fma_f32 v[100:101], v[100:101], s[10:11], v[110:111] op_sel_hi:[0,1,1]
	v_mul_f32_e32 v110, 0xbf3504f3, v107
	v_pk_fma_f32 v[104:105], v[112:113], s[8:9], v[104:105] op_sel:[1,0,0] op_sel_hi:[1,1,0]
	v_pk_fma_f32 v[106:107], v[106:107], s[8:9], v[110:111] op_sel_hi:[0,1,0]
	v_pk_add_f32 v[110:111], v[102:103], v[100:101]
	v_pk_add_f32 v[112:113], v[102:103], v[100:101] neg_lo:[0,1] neg_hi:[0,1]
	v_pk_add_f32 v[100:101], v[106:107], v[104:105]
	v_pk_add_f32 v[106:107], v[104:105], v[106:107] neg_lo:[0,1] neg_hi:[0,1]
	v_pk_add_f32 v[104:105], v[110:111], v[100:101]
	v_pk_add_f32 v[102:103], v[110:111], v[100:101] neg_lo:[0,1] neg_hi:[0,1]
	v_xor_b32_e32 v111, 0x80000000, v106
	v_mov_b32_e32 v110, v107
	v_pk_add_f32 v[100:101], v[112:113], v[110:111]
	v_pk_add_f32 v[106:107], v[112:113], v[110:111] neg_lo:[0,1] neg_hi:[0,1]
	v_pk_add_f32 v[110:111], v[148:149], v[150:151]
	s_mov_b32 s12, s28
	s_mov_b32 s13, s34
	s_mov_b32 s10, s34
	s_mov_b32 s11, s27
	v_pk_mul_f32 v[112:113], v[110:111], s[12:13] op_sel:[1,0]
	v_pk_add_f32 v[108:109], v[116:117], v[108:109]
	v_pk_fma_f32 v[110:111], v[110:111], s[10:11], v[112:113] op_sel_hi:[0,1,1]
	v_pk_add_f32 v[112:113], v[138:139], v[140:141]
	v_pk_add_f32 v[114:115], v[144:145], v[114:115]
	v_pk_mul_f32 v[116:117], v[112:113], s[34:35] op_sel:[1,0]
	s_nop 0
	v_pk_fma_f32 v[112:113], v[112:113], s[28:29], v[116:117] op_sel_hi:[0,1,1]
	v_mul_f32_e32 v116, 0xbf3504f3, v115
	v_pk_fma_f32 v[114:115], v[114:115], s[8:9], v[116:117] op_sel_hi:[0,1,0]
	v_pk_add_f32 v[116:117], v[108:109], v[114:115]
	v_pk_add_f32 v[138:139], v[108:109], v[114:115] neg_lo:[0,1] neg_hi:[0,1]
	v_pk_add_f32 v[108:109], v[112:113], v[110:111]
	v_pk_add_f32 v[112:113], v[112:113], v[110:111] neg_lo:[0,1] neg_hi:[0,1]
	v_pk_add_f32 v[110:111], v[116:117], v[108:109]
	v_pk_add_f32 v[108:109], v[116:117], v[108:109] neg_lo:[0,1] neg_hi:[0,1]
	v_xor_b32_e32 v117, 0x80000000, v112
	v_mov_b32_e32 v116, v113
	v_pk_add_f32 v[114:115], v[138:139], v[116:117]
	v_pk_add_f32 v[112:113], v[138:139], v[116:117] neg_lo:[0,1] neg_hi:[0,1]

.LBB0_1626:
	s_or_b64 exec, exec, s[6:7]
	s_waitcnt lgkmcnt(0)
	s_barrier
	s_and_saveexec_b64 s[6:7], vcc
	s_cbranch_execz .LBB0_1628
	ds_read_b64 v[172:173], v31 offset:61440
	ds_read_b64 v[174:175], v65 offset:57344
	ds_read_b64 v[176:177], v123 offset:53248
	ds_read_b64 v[178:179], v126 offset:49152
	ds_read_b64 v[180:181], v129 offset:45056
	ds_read_b64 v[182:183], v131 offset:40960
	ds_read_b64 v[184:185], v136
	ds_read_b64 v[186:187], v127 offset:4096
	ds_read_b64 v[188:189], v124 offset:8192
	ds_read_b64 v[190:191], v67 offset:12288
	ds_read_b64 v[192:193], v59 offset:16384
	ds_read_b64 v[194:195], v23 offset:20480
	ds_read_b64 v[196:197], v15 offset:24576
	ds_read_b64 v[198:199], v11 offset:28672
	ds_read_b64 v[200:201], v135 offset:32768
	v_cvt_f32_ubyte0_e32 v84, v132
	v_mul_f32_e32 v84, 0x39800000, v84
	v_cos_f32_e32 v98, v84
	v_sin_f32_e32 v99, v84
	s_mov_b32 s10, s27
	v_mov_b32_e32 v101, v98
	v_xor_b32_e32 v100, 0x80000000, v99
	v_mov_b32_e32 v84, v99
	v_pk_mul_f32 v[84:85], v[100:101], v[84:85] op_sel_hi:[1,0]
	s_mov_b32 s11, s26
	v_pk_fma_f32 v[106:107], v[98:99], v[98:99], v[84:85] op_sel_hi:[1,0,1]
	s_mov_b32 s8, s26
	v_pk_mul_f32 v[84:85], v[100:101], v[106:107] op_sel:[0,1]
	s_mov_b32 s9, s28
	v_pk_fma_f32 v[110:111], v[98:99], v[106:107], v[84:85] op_sel_hi:[1,0,1]
	s_mov_b32 s35, s28
	v_pk_mul_f32 v[84:85], v[100:101], v[110:111] op_sel:[0,1]
	s_mov_b32 s29, s26
	v_pk_fma_f32 v[112:113], v[98:99], v[110:111], v[84:85] op_sel_hi:[1,0,1]
	s_mov_b32 s12, s21
	v_pk_mul_f32 v[84:85], v[100:101], v[112:113] op_sel:[0,1]
	s_mov_b32 s13, s20
	v_pk_fma_f32 v[114:115], v[98:99], v[112:113], v[84:85] op_sel_hi:[1,0,1]
	s_nop 0
	v_pk_mul_f32 v[84:85], v[100:101], v[114:115] op_sel:[0,1]
	s_nop 0
	v_pk_fma_f32 v[138:139], v[98:99], v[114:115], v[84:85] op_sel_hi:[1,0,1]
	s_nop 0
	v_pk_mul_f32 v[84:85], v[100:101], v[138:139] op_sel:[0,1]
	s_nop 0
	v_pk_fma_f32 v[140:141], v[98:99], v[138:139], v[84:85] op_sel_hi:[1,0,1]
	s_nop 0
	v_pk_mul_f32 v[84:85], v[100:101], v[140:141] op_sel:[0,1]
	v_mov_b32_e32 v137, v140
	v_pk_fma_f32 v[102:103], v[98:99], v[140:141], v[84:85] op_sel_hi:[1,0,1]
	s_nop 0
	v_pk_mul_f32 v[84:85], v[100:101], v[102:103] op_sel:[0,1]
	s_nop 0
	v_pk_fma_f32 v[86:87], v[98:99], v[102:103], v[84:85] op_sel_hi:[1,0,1]
	s_nop 0
	v_pk_mul_f32 v[84:85], v[100:101], v[86:87] op_sel:[0,1]
	s_nop 0
	v_pk_fma_f32 v[96:97], v[98:99], v[86:87], v[84:85] op_sel_hi:[1,0,1]
	s_nop 0
	v_pk_mul_f32 v[84:85], v[100:101], v[96:97] op_sel:[0,1]
	s_nop 0
	v_pk_fma_f32 v[92:93], v[98:99], v[96:97], v[84:85] op_sel_hi:[1,0,1]
	s_nop 0
	v_pk_mul_f32 v[84:85], v[100:101], v[92:93] op_sel:[0,1]
	s_nop 0
	v_pk_fma_f32 v[94:95], v[98:99], v[92:93], v[84:85] op_sel_hi:[1,0,1]
	s_nop 0
	v_pk_mul_f32 v[84:85], v[100:101], v[94:95] op_sel:[0,1]
	s_nop 0
	v_pk_fma_f32 v[90:91], v[98:99], v[94:95], v[84:85] op_sel_hi:[1,0,1]
	s_nop 0
	v_pk_mul_f32 v[84:85], v[100:101], v[90:91] op_sel:[0,1]
	s_nop 0
	v_pk_fma_f32 v[88:89], v[98:99], v[90:91], v[84:85] op_sel_hi:[1,0,1]
	s_nop 0
	v_pk_mul_f32 v[84:85], v[100:101], v[88:89] op_sel:[0,1]
	s_nop 0
	v_pk_fma_f32 v[84:85], v[98:99], v[88:89], v[84:85] op_sel_hi:[1,0,1]
	s_nop 0
	v_xor_b32_e32 v108, 0x80000000, v85
	v_mov_b32_e32 v109, v84
	s_waitcnt lgkmcnt(15)
	s_waitcnt lgkmcnt(14)
	v_pk_mul_f32 v[108:109], v[108:109], v[172:173] op_sel:[0,1]
	s_nop 0
	v_pk_fma_f32 v[84:85], v[84:85], v[172:173], v[108:109] op_sel_hi:[1,0,1]
	ds_read_b64 v[172:173], v134 offset:36864
	v_xor_b32_e32 v108, 0x80000000, v89
	v_mov_b32_e32 v109, v88
	s_waitcnt lgkmcnt(14)
	v_pk_mul_f32 v[108:109], v[108:109], v[174:175] op_sel:[0,1]
	s_nop 0
	v_pk_fma_f32 v[88:89], v[88:89], v[174:175], v[108:109] op_sel_hi:[1,0,1]
	v_xor_b32_e32 v108, 0x80000000, v91
	v_mov_b32_e32 v109, v90
	s_waitcnt lgkmcnt(13)
	v_pk_mul_f32 v[108:109], v[108:109], v[176:177] op_sel:[0,1]
	s_nop 0
	v_pk_fma_f32 v[90:91], v[90:91], v[176:177], v[108:109] op_sel_hi:[1,0,1]
	v_xor_b32_e32 v108, 0x80000000, v95
	v_mov_b32_e32 v109, v94
	s_waitcnt lgkmcnt(12)
	v_pk_mul_f32 v[108:109], v[108:109], v[178:179] op_sel:[0,1]
	s_nop 0
	v_pk_fma_f32 v[94:95], v[94:95], v[178:179], v[108:109] op_sel_hi:[1,0,1]
	v_xor_b32_e32 v108, 0x80000000, v93
	v_mov_b32_e32 v109, v92
	s_waitcnt lgkmcnt(11)
	v_pk_mul_f32 v[108:109], v[108:109], v[180:181] op_sel:[0,1]
	s_nop 0
	v_pk_fma_f32 v[92:93], v[92:93], v[180:181], v[108:109] op_sel_hi:[1,0,1]
	v_xor_b32_e32 v108, 0x80000000, v97
	v_mov_b32_e32 v109, v96
	s_waitcnt lgkmcnt(10)
	v_pk_mul_f32 v[108:109], v[108:109], v[182:183] op_sel:[0,1]
	s_nop 0
	v_pk_fma_f32 v[96:97], v[96:97], v[182:183], v[108:109] op_sel_hi:[1,0,1]
	v_xor_b32_e32 v136, 0x80000000, v141
	s_waitcnt lgkmcnt(8)
	v_pk_mul_f32 v[100:101], v[100:101], v[186:187] op_sel:[0,1]
	s_nop 0
	v_pk_fma_f32 v[104:105], v[98:99], v[186:187], v[100:101] op_sel_hi:[1,0,1]
	v_xor_b32_e32 v100, 0x80000000, v107
	v_mov_b32_e32 v101, v106
	s_waitcnt lgkmcnt(7)
	v_pk_mul_f32 v[100:101], v[100:101], v[188:189] op_sel:[0,1]
	s_nop 0
	v_pk_fma_f32 v[100:101], v[106:107], v[188:189], v[100:101] op_sel_hi:[1,0,1]
	v_xor_b32_e32 v106, 0x80000000, v111
	v_mov_b32_e32 v107, v110
	v_pk_add_f32 v[144:145], v[100:101], v[96:97] neg_lo:[0,1] neg_hi:[0,1]
	s_waitcnt lgkmcnt(6)
	v_pk_mul_f32 v[106:107], v[106:107], v[190:191] op_sel:[0,1]
	s_nop 0
	v_pk_fma_f32 v[98:99], v[110:111], v[190:191], v[106:107] op_sel_hi:[1,0,1]
	v_xor_b32_e32 v110, 0x80000000, v113
	v_mov_b32_e32 v111, v112
	v_pk_add_f32 v[148:149], v[98:99], v[92:93] neg_lo:[0,1] neg_hi:[0,1]
	s_waitcnt lgkmcnt(5)
	v_pk_mul_f32 v[110:111], v[110:111], v[192:193] op_sel:[0,1]
	s_nop 0
	v_pk_fma_f32 v[110:111], v[112:113], v[192:193], v[110:111] op_sel_hi:[1,0,1]
	v_xor_b32_e32 v112, 0x80000000, v115
	v_mov_b32_e32 v113, v114
	s_waitcnt lgkmcnt(4)
	v_pk_mul_f32 v[112:113], v[112:113], v[194:195] op_sel:[0,1]
	s_nop 0
	v_pk_fma_f32 v[112:113], v[114:115], v[194:195], v[112:113] op_sel_hi:[1,0,1]
	v_xor_b32_e32 v114, 0x80000000, v139
	v_mov_b32_e32 v115, v138
	s_waitcnt lgkmcnt(3)
	v_pk_mul_f32 v[114:115], v[114:115], v[196:197] op_sel:[0,1]
	s_nop 0
	v_pk_fma_f32 v[114:115], v[138:139], v[196:197], v[114:115] op_sel_hi:[1,0,1]
	v_xor_b32_e32 v138, 0x80000000, v103
	v_mov_b32_e32 v139, v102
	s_waitcnt lgkmcnt(2)
	v_pk_mul_f32 v[136:137], v[136:137], v[198:199] op_sel:[0,1]
	s_nop 0
	v_pk_fma_f32 v[106:107], v[140:141], v[198:199], v[136:137] op_sel_hi:[1,0,1]
	s_waitcnt lgkmcnt(1)
	v_pk_mul_f32 v[138:139], v[138:139], v[200:201] op_sel:[0,1]
	s_nop 0
	v_pk_fma_f32 v[102:103], v[102:103], v[200:201], v[138:139] op_sel_hi:[1,0,1]
	v_xor_b32_e32 v138, 0x80000000, v87
	v_mov_b32_e32 v139, v86
	s_waitcnt lgkmcnt(0)
	v_pk_mul_f32 v[138:139], v[138:139], v[172:173] op_sel:[0,1]
	s_nop 0
	v_pk_fma_f32 v[86:87], v[86:87], v[172:173], v[138:139] op_sel_hi:[1,0,1]
	v_pk_add_f32 v[136:137], v[184:185], v[102:103]
	v_pk_add_f32 v[138:139], v[104:105], v[86:87]
	v_pk_add_f32 v[140:141], v[104:105], v[86:87] neg_lo:[0,1] neg_hi:[0,1]
	v_pk_add_f32 v[86:87], v[90:91], v[112:113]
	v_pk_add_f32 v[90:91], v[112:113], v[90:91] neg_lo:[0,1] neg_hi:[0,1]
	v_pk_add_f32 v[104:105], v[86:87], v[138:139]
	v_pk_add_f32 v[112:113], v[138:139], v[86:87] neg_lo:[0,1] neg_hi:[0,1]
	v_xor_b32_e32 v139, 0x80000000, v90
	v_mov_b32_e32 v138, v91
	v_pk_add_f32 v[86:87], v[96:97], v[100:101]
	v_pk_add_f32 v[90:91], v[88:89], v[114:115]
	v_pk_add_f32 v[88:89], v[114:115], v[88:89] neg_lo:[0,1] neg_hi:[0,1]
	v_pk_add_f32 v[96:97], v[86:87], v[90:91]
	v_pk_add_f32 v[100:101], v[86:87], v[90:91] neg_lo:[0,1] neg_hi:[0,1]
	v_xor_b32_e32 v115, 0x80000000, v88
	v_mov_b32_e32 v114, v89
	v_pk_add_f32 v[86:87], v[92:93], v[98:99]
	v_pk_add_f32 v[88:89], v[84:85], v[106:107]
	v_pk_add_f32 v[108:109], v[184:185], v[102:103] neg_lo:[0,1] neg_hi:[0,1]
	v_pk_add_f32 v[102:103], v[94:95], v[110:111]
	v_pk_add_f32 v[90:91], v[86:87], v[88:89]
	v_pk_add_f32 v[94:95], v[110:111], v[94:95] neg_lo:[0,1] neg_hi:[0,1]
	v_pk_add_f32 v[110:111], v[102:103], v[136:137]
	v_pk_add_f32 v[84:85], v[106:107], v[84:85] neg_lo:[0,1] neg_hi:[0,1]
	v_pk_add_f32 v[106:107], v[86:87], v[88:89] neg_lo:[0,1] neg_hi:[0,1]
	v_pk_add_f32 v[86:87], v[90:91], v[104:105]
	v_pk_add_f32 v[90:91], v[104:105], v[90:91] neg_lo:[0,1] neg_hi:[0,1]
	v_pk_add_f32 v[142:143], v[140:141], v[138:139] neg_lo:[0,1] neg_hi:[0,1]
	v_xor_b32_e32 v151, 0x80000000, v84
	v_mov_b32_e32 v150, v85
	v_pk_add_f32 v[84:85], v[96:97], v[110:111]
	v_pk_add_f32 v[96:97], v[110:111], v[96:97] neg_lo:[0,1] neg_hi:[0,1]
	v_xor_b32_e32 v99, 0x80000000, v90
	v_mov_b32_e32 v98, v91
	v_pk_add_f32 v[146:147], v[144:145], v[114:115] neg_lo:[0,1] neg_hi:[0,1]
	v_pk_add_f32 v[92:93], v[148:149], v[150:151] neg_lo:[0,1] neg_hi:[0,1]
	v_pk_add_f32 v[88:89], v[84:85], v[86:87]
	v_pk_add_f32 v[86:87], v[84:85], v[86:87] neg_lo:[0,1] neg_hi:[0,1]
	v_pk_add_f32 v[84:85], v[96:97], v[98:99]
	v_pk_add_f32 v[90:91], v[96:97], v[98:99] neg_lo:[0,1] neg_hi:[0,1]
	v_pk_mul_f32 v[96:97], v[142:143], s[10:11] op_sel:[1,0]
	v_pk_add_f32 v[102:103], v[136:137], v[102:103] neg_lo:[0,1] neg_hi:[0,1]
	v_xor_b32_e32 v137, 0x80000000, v94
	v_mov_b32_e32 v136, v95
	v_pk_fma_f32 v[96:97], v[142:143], s[8:9], v[96:97] op_sel_hi:[0,1,1]
	v_mul_f32_e32 v98, 0x3f3504f3, v146
	s_mov_b32 s8, s31
	s_mov_b32 s9, s30
	v_pk_mul_f32 v[104:105], v[92:93], s[34:35] op_sel:[1,0]
	v_pk_add_f32 v[94:95], v[108:109], v[136:137] neg_lo:[0,1] neg_hi:[0,1]
	v_pk_fma_f32 v[98:99], v[146:147], s[8:9], v[98:99] op_sel:[1,0,0] op_sel_hi:[1,1,0]
	v_pk_fma_f32 v[92:93], v[92:93], s[28:29], v[104:105] op_sel_hi:[0,1,1]
	v_pk_add_f32 v[104:105], v[94:95], v[98:99]
	v_pk_add_f32 v[98:99], v[94:95], v[98:99] neg_lo:[0,1] neg_hi:[0,1]
	v_pk_add_f32 v[94:95], v[96:97], v[92:93]
	v_pk_add_f32 v[92:93], v[96:97], v[92:93] neg_lo:[0,1] neg_hi:[0,1]
	v_pk_add_f32 v[96:97], v[104:105], v[94:95]
	v_pk_add_f32 v[94:95], v[104:105], v[94:95] neg_lo:[0,1] neg_hi:[0,1]
	v_xor_b32_e32 v105, 0x80000000, v92
	v_mov_b32_e32 v104, v93
	s_mov_b32 s10, s20
	s_mov_b32 s11, s36
	v_pk_mul_f32 v[110:111], v[100:101], s[12:13] op_sel:[1,0]
	v_pk_add_f32 v[92:93], v[98:99], v[104:105]
	v_pk_add_f32 v[98:99], v[98:99], v[104:105] neg_lo:[0,1] neg_hi:[0,1]
	v_mul_f32_e32 v104, 0x3f3504f3, v112
	v_pk_fma_f32 v[100:101], v[100:101], s[10:11], v[110:111] op_sel_hi:[0,1,1]
	v_mul_f32_e32 v110, 0xbf3504f3, v107
	v_pk_fma_f32 v[104:105], v[112:113], s[8:9], v[104:105] op_sel:[1,0,0] op_sel_hi:[1,1,0]
	v_pk_fma_f32 v[106:107], v[106:107], s[8:9], v[110:111] op_sel_hi:[0,1,0]
	v_pk_add_f32 v[110:111], v[102:103], v[100:101]
	v_pk_add_f32 v[112:113], v[102:103], v[100:101] neg_lo:[0,1] neg_hi:[0,1]
	v_pk_add_f32 v[100:101], v[106:107], v[104:105]
	v_pk_add_f32 v[106:107], v[104:105], v[106:107] neg_lo:[0,1] neg_hi:[0,1]
	v_pk_add_f32 v[104:105], v[110:111], v[100:101]
	v_pk_add_f32 v[102:103], v[110:111], v[100:101] neg_lo:[0,1] neg_hi:[0,1]
	v_xor_b32_e32 v111, 0x80000000, v106
	v_mov_b32_e32 v110, v107
	v_pk_add_f32 v[100:101], v[112:113], v[110:111]
	v_pk_add_f32 v[106:107], v[112:113], v[110:111] neg_lo:[0,1] neg_hi:[0,1]
	v_pk_add_f32 v[110:111], v[148:149], v[150:151]
	s_mov_b32 s12, s28
	s_mov_b32 s13, s34
	s_mov_b32 s10, s34
	s_mov_b32 s11, s27
	v_pk_mul_f32 v[112:113], v[110:111], s[12:13] op_sel:[1,0]
	v_pk_add_f32 v[108:109], v[136:137], v[108:109]
	v_pk_fma_f32 v[110:111], v[110:111], s[10:11], v[112:113] op_sel_hi:[0,1,1]
	v_pk_add_f32 v[112:113], v[138:139], v[140:141]
	v_pk_add_f32 v[114:115], v[144:145], v[114:115]
	v_pk_mul_f32 v[136:137], v[112:113], s[34:35] op_sel:[1,0]
	s_nop 0
	v_pk_fma_f32 v[112:113], v[112:113], s[28:29], v[136:137] op_sel_hi:[0,1,1]
	v_mul_f32_e32 v136, 0xbf3504f3, v115
	v_pk_fma_f32 v[114:115], v[114:115], s[8:9], v[136:137] op_sel_hi:[0,1,0]
	v_pk_add_f32 v[136:137], v[108:109], v[114:115]
	v_pk_add_f32 v[138:139], v[108:109], v[114:115] neg_lo:[0,1] neg_hi:[0,1]
	v_pk_add_f32 v[108:109], v[112:113], v[110:111]
	v_pk_add_f32 v[112:113], v[112:113], v[110:111] neg_lo:[0,1] neg_hi:[0,1]
	v_pk_add_f32 v[110:111], v[136:137], v[108:109]
	v_pk_add_f32 v[108:109], v[136:137], v[108:109] neg_lo:[0,1] neg_hi:[0,1]
	v_xor_b32_e32 v137, 0x80000000, v112
	v_mov_b32_e32 v136, v113
	v_pk_add_f32 v[114:115], v[138:139], v[136:137]
	v_pk_add_f32 v[112:113], v[138:139], v[136:137] neg_lo:[0,1] neg_hi:[0,1]

.LBB0_1630:
	s_or_b64 exec, exec, s[6:7]
	s_waitcnt lgkmcnt(0)
	s_barrier
	s_and_saveexec_b64 s[6:7], vcc
	s_cbranch_execz .LBB0_1632
	ds_read_b64 v[172:173], v135 offset:32768
	v_cvt_f32_i32_e32 v86, v132
	v_lshlrev_b32_e32 v88, 3, v133
	v_lshlrev_b32_e32 v89, 3, v132
	v_mul_f32_e32 v86, 0x39000000, v86
	v_sin_f32_e32 v87, v86
	v_cos_f32_e32 v86, v86
	v_add3_u32 v92, 0, v88, v89
	ds_read_b64 v[174:175], v92
	v_xor_b32_e32 v90, 0x80000000, v87
	v_mov_b32_e32 v91, v86
	v_cvt_f32_i32_e32 v93, v130
	s_waitcnt lgkmcnt(2)
	s_waitcnt lgkmcnt(1)
	v_pk_mul_f32 v[90:91], v[90:91], v[172:173] op_sel:[0,1]
	v_cvt_f32_i32_e32 v63, v63
	v_pk_fma_f32 v[84:85], v[86:87], v[172:173], v[90:91] op_sel_hi:[1,0,1]
	v_cvt_f32_i32_e32 v27, v27
	s_waitcnt lgkmcnt(0)
	v_pk_add_f32 v[84:85], v[174:175], v[84:85]
	ds_write_b64 v92, v[84:85]
	ds_read_b64 v[172:173], v134 offset:36864
	ds_read_b64 v[174:175], v127 offset:4096
	v_mul_f32_e32 v85, 0x39000000, v93
	v_cos_f32_e32 v84, v85
	v_sin_f32_e32 v85, v85
	v_cvt_f32_i32_e32 v92, v128
	v_mov_b32_e32 v91, v84
	v_xor_b32_e32 v90, 0x80000000, v85
	s_waitcnt lgkmcnt(1)
	v_pk_mul_f32 v[90:91], v[90:91], v[172:173] op_sel:[0,1]
	v_cvt_f32_i32_e32 v19, v19
	v_pk_fma_f32 v[84:85], v[84:85], v[172:173], v[90:91] op_sel_hi:[1,0,1]
	s_waitcnt lgkmcnt(0)
	v_pk_add_f32 v[84:85], v[174:175], v[84:85]
	ds_write_b64 v127, v[84:85] offset:4096
	ds_read_b64 v[172:173], v131 offset:40960
	ds_read_b64 v[174:175], v124 offset:8192
	v_mul_f32_e32 v85, 0x39000000, v92
	v_cos_f32_e32 v84, v85
	v_sin_f32_e32 v85, v85
	v_cvt_f32_i32_e32 v92, v125
	v_mov_b32_e32 v91, v84
	v_xor_b32_e32 v90, 0x80000000, v85
	s_waitcnt lgkmcnt(1)
	v_pk_mul_f32 v[90:91], v[90:91], v[172:173] op_sel:[0,1]
	s_nop 0
	v_pk_fma_f32 v[84:85], v[84:85], v[172:173], v[90:91] op_sel_hi:[1,0,1]
	s_waitcnt lgkmcnt(0)
	v_pk_add_f32 v[84:85], v[174:175], v[84:85]
	ds_write_b64 v124, v[84:85] offset:8192
	ds_read_b64 v[172:173], v129 offset:45056
	ds_read_b64 v[174:175], v67 offset:12288
	v_mul_f32_e32 v85, 0x39000000, v92
	v_cos_f32_e32 v84, v85
	v_sin_f32_e32 v85, v85
	v_cvt_f32_i32_e32 v92, v122
	v_mov_b32_e32 v91, v84
	v_xor_b32_e32 v90, 0x80000000, v85
	s_waitcnt lgkmcnt(1)
	v_pk_mul_f32 v[90:91], v[90:91], v[172:173] op_sel:[0,1]
	s_nop 0
	v_pk_fma_f32 v[84:85], v[84:85], v[172:173], v[90:91] op_sel_hi:[1,0,1]
	s_waitcnt lgkmcnt(0)
	v_pk_add_f32 v[84:85], v[174:175], v[84:85]
	ds_write_b64 v67, v[84:85] offset:12288
	ds_read_b64 v[172:173], v126 offset:49152
	ds_read_b64 v[174:175], v59 offset:16384
	v_mul_f32_e32 v67, 0x39000000, v92
	v_cos_f32_e32 v84, v67
	v_sin_f32_e32 v85, v67
	s_nop 0
	v_mov_b32_e32 v91, v84
	v_xor_b32_e32 v90, 0x80000000, v85
	s_waitcnt lgkmcnt(1)
	v_pk_mul_f32 v[90:91], v[90:91], v[172:173] op_sel:[0,1]
	s_nop 0
	v_pk_fma_f32 v[84:85], v[84:85], v[172:173], v[90:91] op_sel_hi:[1,0,1]
	s_waitcnt lgkmcnt(0)
	v_pk_add_f32 v[84:85], v[174:175], v[84:85]
	ds_write_b64 v59, v[84:85] offset:16384
	ds_read_b64 v[172:173], v123 offset:53248
	ds_read_b64 v[174:175], v23 offset:20480
	v_mul_f32_e32 v59, 0x39000000, v63
	v_cos_f32_e32 v84, v59
	v_sin_f32_e32 v85, v59
	s_nop 0
	v_mov_b32_e32 v91, v84
	v_xor_b32_e32 v90, 0x80000000, v85
	s_waitcnt lgkmcnt(1)
	v_pk_mul_f32 v[90:91], v[90:91], v[172:173] op_sel:[0,1]
	s_nop 0
	v_pk_fma_f32 v[84:85], v[84:85], v[172:173], v[90:91] op_sel_hi:[1,0,1]
	s_waitcnt lgkmcnt(0)
	v_pk_add_f32 v[84:85], v[174:175], v[84:85]
	ds_write_b64 v23, v[84:85] offset:20480
	ds_read_b64 v[172:173], v65 offset:57344
	ds_read_b64 v[174:175], v15 offset:24576
	v_mul_f32_e32 v23, 0x39000000, v27
	v_cos_f32_e32 v84, v23
	v_sin_f32_e32 v85, v23
	s_nop 0
	v_mov_b32_e32 v91, v84
	v_xor_b32_e32 v90, 0x80000000, v85
	s_waitcnt lgkmcnt(1)
	v_pk_mul_f32 v[90:91], v[90:91], v[172:173] op_sel:[0,1]
	s_nop 0
	v_pk_fma_f32 v[84:85], v[84:85], v[172:173], v[90:91] op_sel_hi:[1,0,1]
	s_waitcnt lgkmcnt(0)
	v_pk_add_f32 v[84:85], v[174:175], v[84:85]
	ds_write_b64 v15, v[84:85] offset:24576
	ds_read_b64 v[86:87], v31 offset:61440
	ds_read_b64 v[88:89], v11 offset:28672
	v_mul_f32_e32 v15, 0x39000000, v19
	v_cos_f32_e32 v84, v15
	v_sin_f32_e32 v85, v15
	s_nop 0
	v_mov_b32_e32 v91, v84
	v_xor_b32_e32 v90, 0x80000000, v85
	s_waitcnt lgkmcnt(1)
	v_pk_mul_f32 v[90:91], v[90:91], v[86:87] op_sel:[0,1]
	s_nop 0
	v_pk_fma_f32 v[84:85], v[84:85], v[86:87], v[90:91] op_sel_hi:[1,0,1]
	s_waitcnt lgkmcnt(0)
	v_pk_add_f32 v[84:85], v[88:89], v[84:85]
	ds_write_b64 v11, v[84:85] offset:28672
.LBB0_1632:
	s_or_b64 exec, exec, s[6:7]
	s_waitcnt lgkmcnt(0)
	s_barrier
	global_load_dword v84, v43, s[62:63]
	global_load_dword v88, v55, s[62:63]
	global_load_dword v86, v118, s[62:63]
	global_load_dword v90, v43, s[64:65]
	v_cmp_gt_i32_e64 s[6:7], s69, v64
	v_cmp_lt_i32_e32 vcc, 0, v64
	s_waitcnt vmcnt(19)
	v_mov_b32_e32 v92, v57
	v_cndmask_b32_e64 v15, 0, v64, s[6:7]
	s_waitcnt vmcnt(17)
	v_mov_b32_e32 v93, v61
	v_cmp_gt_i32_e64 s[8:9], s51, v64
	v_ashrrev_i32_e32 v19, 4, v15
	v_cndmask_b32_e32 v57, 0, v60, vcc
	v_cndmask_b32_e32 v56, 0, v56, vcc
	v_cvt_pkrtz_f16_f32 v11, v82, v83
	v_lshlrev_b32_e32 v19, 3, v19
	v_lshlrev_b32_e32 v15, 3, v15
	v_cndmask_b32_e64 v59, 0, v62, s[8:9]
	v_cndmask_b32_e64 v58, 0, v58, s[8:9]
	v_add_u32_e32 v65, 0x200, v64
	v_cmp_gt_i32_e64 s[18:19], s95, v64
	v_add3_u32 v15, 0, v19, v15
	ds_read_b64 v[172:173], v15
	v_add_u32_e32 v31, 0x400, v64
	v_cmp_gt_i32_e64 s[16:17], s75, v64
	v_add_u32_e32 v27, 0x600, v64
	v_cmp_gt_i32_e64 s[14:15], s74, v64
	v_add_u32_e32 v23, 0x800, v64
	v_cmp_gt_i32_e64 s[12:13], s68, v64
	v_add_u32_e32 v19, 0xa00, v64
	v_cmp_gt_i32_e64 s[8:9], s72, v64
	v_cmp_gt_i32_e32 vcc, s71, v64
	v_cmp_gt_i32_e64 s[10:11], s70, v64
	v_lshlrev_b32_e32 v98, 3, v64
	s_waitcnt vmcnt(0)
	v_pk_fma_f32 v[92:93], v[92:93], v[88:89], v[90:91] op_sel_hi:[1,0,0]
	s_nop 0
	v_pk_fma_f32 v[56:57], v[84:85], v[56:57], v[92:93] op_sel_hi:[0,1,1]
	v_pk_fma_f32 v[56:57], v[58:59], v[86:87], v[56:57] op_sel_hi:[1,0,1]
	v_cvt_f32_f16_e32 v58, v11
	v_cvt_f32_f16_sdwa v59, v11 dst_sel:DWORD dst_unused:UNUSED_PAD src0_sel:WORD_1
	v_cndmask_b32_e64 v11, 0, v65, s[18:19]
	v_ashrrev_i32_e32 v15, 4, v11
	v_lshlrev_b32_e32 v15, 3, v15
	v_lshlrev_b32_e32 v11, 3, v11
	v_add3_u32 v11, 0, v15, v11
	ds_read_b64 v[94:95], v11
	v_cndmask_b32_e64 v11, 0, v31, s[16:17]
	v_ashrrev_i32_e32 v15, 4, v11
	v_lshlrev_b32_e32 v15, 3, v15
	v_lshlrev_b32_e32 v11, 3, v11
	v_add3_u32 v11, 0, v15, v11
	ds_read_b64 v[92:93], v11
	v_cndmask_b32_e64 v11, 0, v27, s[14:15]
	v_ashrrev_i32_e32 v15, 4, v11
	v_lshlrev_b32_e32 v15, 3, v15
	v_lshlrev_b32_e32 v11, 3, v11
	v_add3_u32 v11, 0, v15, v11
	ds_read_b64 v[62:63], v11
	v_cndmask_b32_e64 v11, 0, v23, s[12:13]
	v_ashrrev_i32_e32 v15, 4, v11
	v_lshlrev_b32_e32 v15, 3, v15
	v_lshlrev_b32_e32 v11, 3, v11
	v_add3_u32 v11, 0, v15, v11
	ds_read_b64 v[60:61], v11
	v_cndmask_b32_e64 v11, 0, v19, s[8:9]
	v_ashrrev_i32_e32 v15, 4, v11
	v_lshlrev_b32_e32 v15, 3, v15
	v_lshlrev_b32_e32 v11, 3, v11
	s_waitcnt lgkmcnt(5)
	s_waitcnt lgkmcnt(4)
	v_pk_fma_f32 v[58:59], v[66:67], v[58:59], v[172:173] op_sel_hi:[0,1,1]
	v_add3_u32 v11, 0, v15, v11
	v_add_u32_e32 v15, 0xc00, v64
	v_pk_mul_f32 v[82:83], v[56:57], v[58:59]
	ds_read_b64 v[58:59], v11
	v_cndmask_b32_e32 v11, 0, v15, vcc
	v_ashrrev_i32_e32 v56, 4, v11
	v_lshlrev_b32_e32 v56, 3, v56
	v_lshlrev_b32_e32 v11, 3, v11
	v_add3_u32 v11, 0, v56, v11
	ds_read_b64 v[56:57], v11
	v_add_u32_e32 v11, 0xe00, v64
	v_cndmask_b32_e64 v67, 0, v11, s[10:11]
	v_ashrrev_i32_e32 v85, 4, v67
	v_lshlrev_b32_e32 v85, 3, v85
	v_lshlrev_b32_e32 v67, 3, v67
	v_add3_u32 v67, 0, v85, v67
	ds_read_b64 v[96:97], v67
	s_waitcnt lgkmcnt(0)
	s_barrier
	s_and_saveexec_b64 s[66:67], s[6:7]
	v_ashrrev_i32_e32 v67, 4, v64
	v_lshlrev_b32_e32 v67, 3, v67
	v_add3_u32 v67, 0, v67, v98
	ds_write_b64 v67, v[82:83]
	s_or_b64 exec, exec, s[66:67]
	s_movk_i32 s2, 0xfe00
	v_cvt_pkrtz_f16_f32 v99, v80, v81
	v_cmp_lt_i32_e64 s[6:7], s2, v64
	v_mov_b32_e32 v80, v49
	v_mov_b32_e32 v81, v53
	v_cndmask_b32_e64 v49, 0, v52, s[6:7]
	v_cvt_f32_f16_e32 v52, v99
	v_cvt_f32_f16_sdwa v53, v99 dst_sel:DWORD dst_unused:UNUSED_PAD src0_sel:WORD_1
	v_mov_b32_e32 v89, v88
	v_mov_b32_e32 v91, v90
	s_movk_i32 s2, 0xdff
	v_mov_b32_e32 v85, v84
	v_pk_fma_f32 v[80:81], v[80:81], v[88:89], v[90:91]
	v_cndmask_b32_e64 v48, 0, v48, s[6:7]
	v_cmp_gt_i32_e64 s[6:7], s2, v64
	v_mov_b32_e32 v87, v86
	v_mov_b32_e32 v67, v66
	v_pk_fma_f32 v[48:49], v[84:85], v[48:49], v[80:81]
	v_cndmask_b32_e64 v81, 0, v54, s[6:7]
	v_cndmask_b32_e64 v80, 0, v50, s[6:7]
	v_pk_fma_f32 v[48:49], v[80:81], v[86:87], v[48:49]
	s_waitcnt lgkmcnt(6)
	v_pk_fma_f32 v[52:53], v[66:67], v[52:53], v[94:95]
	s_nop 0
	v_pk_mul_f32 v[80:81], v[48:49], v[52:53]
	s_and_saveexec_b64 s[6:7], s[18:19]
	v_ashrrev_i32_e32 v48, 4, v65
	v_lshlrev_b32_e32 v48, 3, v48
	v_add3_u32 v48, 0, v48, v98
	ds_write_b64 v48, v[80:81] offset:4096
	s_or_b64 exec, exec, s[6:7]
	s_movk_i32 s2, 0xfc00
	v_cvt_pkrtz_f16_f32 v50, v78, v79
	v_cmp_lt_i32_e64 s[6:7], s2, v64
	v_mov_b32_e32 v48, v45
	v_mov_b32_e32 v49, v41
	v_cndmask_b32_e64 v41, 0, v40, s[6:7]
	v_cndmask_b32_e64 v40, 0, v44, s[6:7]
	v_cvt_f32_f16_e32 v44, v50
	v_cvt_f32_f16_sdwa v45, v50 dst_sel:DWORD dst_unused:UNUSED_PAD src0_sel:WORD_1
	s_movk_i32 s2, 0xbff
	v_pk_fma_f32 v[48:49], v[48:49], v[88:89], v[90:91]
	v_cmp_gt_i32_e64 s[6:7], s2, v64
	v_pk_fma_f32 v[40:41], v[84:85], v[40:41], v[48:49]
	s_waitcnt lgkmcnt(5)
	v_pk_fma_f32 v[44:45], v[66:67], v[44:45], v[92:93]
	v_cndmask_b32_e64 v49, 0, v42, s[6:7]
	v_cndmask_b32_e64 v48, 0, v46, s[6:7]
	v_pk_fma_f32 v[40:41], v[48:49], v[86:87], v[40:41]
	s_nop 0
	v_pk_mul_f32 v[78:79], v[40:41], v[44:45]
	s_and_saveexec_b64 s[6:7], s[16:17]
	v_ashrrev_i32_e32 v31, 4, v31
	v_lshlrev_b32_e32 v31, 3, v31
	v_add3_u32 v31, 0, v31, v98
	ds_write_b64 v31, v[78:79] offset:8192
	s_or_b64 exec, exec, s[6:7]
	s_movk_i32 s2, 0xfa00
	v_cvt_pkrtz_f16_f32 v31, v76, v77
	v_cmp_lt_i32_e64 s[6:7], s2, v64
	v_mov_b32_e32 v40, v33
	v_mov_b32_e32 v41, v37
	v_cndmask_b32_e64 v33, 0, v36, s[6:7]
	v_cvt_f32_f16_e32 v36, v31
	v_cvt_f32_f16_sdwa v37, v31 dst_sel:DWORD dst_unused:UNUSED_PAD src0_sel:WORD_1
	s_movk_i32 s2, 0x9ff
	v_pk_fma_f32 v[40:41], v[40:41], v[88:89], v[90:91]
	v_cndmask_b32_e64 v32, 0, v32, s[6:7]
	v_cmp_gt_i32_e64 s[6:7], s2, v64
	v_pk_fma_f32 v[32:33], v[84:85], v[32:33], v[40:41]
	s_waitcnt lgkmcnt(4)
	v_pk_fma_f32 v[36:37], v[66:67], v[36:37], v[62:63]
	v_cndmask_b32_e64 v41, 0, v38, s[6:7]
	v_cndmask_b32_e64 v40, 0, v34, s[6:7]
	v_pk_fma_f32 v[32:33], v[40:41], v[86:87], v[32:33]
	s_nop 0
	v_pk_mul_f32 v[76:77], v[32:33], v[36:37]
	s_and_saveexec_b64 s[6:7], s[14:15]
	v_ashrrev_i32_e32 v27, 4, v27
	v_lshlrev_b32_e32 v27, 3, v27
	v_add3_u32 v27, 0, v27, v98
	ds_write_b64 v27, v[76:77] offset:12288
	s_or_b64 exec, exec, s[6:7]
	s_movk_i32 s2, 0xf800
	v_cvt_pkrtz_f16_f32 v27, v74, v75
	v_cmp_lt_i32_e64 s[6:7], s2, v64
	v_mov_b32_e32 v32, v25
	v_mov_b32_e32 v33, v29
	v_cndmask_b32_e64 v25, 0, v28, s[6:7]
	v_cvt_f32_f16_e32 v28, v27
	v_cvt_f32_f16_sdwa v29, v27 dst_sel:DWORD dst_unused:UNUSED_PAD src0_sel:WORD_1
	v_pk_fma_f32 v[32:33], v[32:33], v[88:89], v[90:91]
	v_cndmask_b32_e64 v24, 0, v24, s[6:7]
	v_cmp_gt_i32_e64 s[6:7], s43, v64
	v_pk_fma_f32 v[24:25], v[84:85], v[24:25], v[32:33]
	s_nop 0
	v_cndmask_b32_e64 v27, 0, v30, s[6:7]
	v_cndmask_b32_e64 v26, 0, v26, s[6:7]
	v_pk_fma_f32 v[24:25], v[26:27], v[86:87], v[24:25]
	s_waitcnt lgkmcnt(3)
	v_pk_fma_f32 v[26:27], v[66:67], v[28:29], v[60:61]
	s_nop 0
	v_pk_mul_f32 v[74:75], v[24:25], v[26:27]
	s_and_saveexec_b64 s[6:7], s[12:13]
	v_ashrrev_i32_e32 v23, 4, v23
	v_lshlrev_b32_e32 v23, 3, v23
	v_add3_u32 v23, 0, v23, v98
	ds_write_b64 v23, v[74:75] offset:16384
	s_or_b64 exec, exec, s[6:7]
	s_movk_i32 s2, 0xf600
	v_cvt_pkrtz_f16_f32 v23, v72, v73
	v_cmp_lt_i32_e64 s[6:7], s2, v64
	v_mov_b32_e32 v24, v17
	v_mov_b32_e32 v25, v21
	v_cndmask_b32_e64 v17, 0, v20, s[6:7]
	v_cvt_f32_f16_e32 v20, v23
	v_cvt_f32_f16_sdwa v21, v23 dst_sel:DWORD dst_unused:UNUSED_PAD src0_sel:WORD_1
	s_movk_i32 s2, 0x5ff
	v_pk_fma_f32 v[24:25], v[24:25], v[88:89], v[90:91]
	v_cndmask_b32_e64 v16, 0, v16, s[6:7]
	v_cmp_gt_i32_e64 s[6:7], s2, v64
	v_pk_fma_f32 v[16:17], v[84:85], v[16:17], v[24:25]
	s_waitcnt lgkmcnt(2)
	v_pk_fma_f32 v[20:21], v[66:67], v[20:21], v[58:59]
	v_cndmask_b32_e64 v23, 0, v22, s[6:7]
	v_cndmask_b32_e64 v22, 0, v18, s[6:7]
	v_pk_fma_f32 v[16:17], v[22:23], v[86:87], v[16:17]
	s_nop 0
	v_pk_mul_f32 v[72:73], v[16:17], v[20:21]
	s_and_saveexec_b64 s[6:7], s[8:9]
	v_ashrrev_i32_e32 v16, 4, v19
	v_lshlrev_b32_e32 v16, 3, v16
	v_add3_u32 v16, 0, v16, v98
	ds_write_b64 v16, v[72:73] offset:20480
	s_or_b64 exec, exec, s[6:7]
	s_movk_i32 s2, 0xf400
	v_cvt_pkrtz_f16_f32 v18, v68, v69
	v_cmp_lt_i32_e64 s[6:7], s2, v64
	v_mov_b32_e32 v16, v9
	v_mov_b32_e32 v17, v13
	v_cndmask_b32_e64 v9, 0, v12, s[6:7]
	v_cvt_f32_f16_e32 v12, v18
	v_cvt_f32_f16_sdwa v13, v18 dst_sel:DWORD dst_unused:UNUSED_PAD src0_sel:WORD_1
	s_movk_i32 s2, 0x3ff
	v_pk_fma_f32 v[16:17], v[16:17], v[88:89], v[90:91]
	v_cndmask_b32_e64 v8, 0, v8, s[6:7]
	v_cmp_gt_i32_e64 s[6:7], s2, v64
	v_pk_fma_f32 v[8:9], v[84:85], v[8:9], v[16:17]
	s_waitcnt lgkmcnt(1)
	v_pk_fma_f32 v[12:13], v[66:67], v[12:13], v[56:57]
	v_cndmask_b32_e64 v17, 0, v14, s[6:7]
	v_cndmask_b32_e64 v16, 0, v10, s[6:7]
	v_pk_fma_f32 v[8:9], v[16:17], v[86:87], v[8:9]
	s_nop 0
	v_pk_mul_f32 v[68:69], v[8:9], v[12:13]
	s_and_saveexec_b64 s[6:7], vcc
	v_ashrrev_i32_e32 v8, 4, v15
	v_lshlrev_b32_e32 v8, 3, v8
	v_add3_u32 v8, 0, v8, v98
	ds_write_b64 v8, v[68:69] offset:24576
	s_or_b64 exec, exec, s[6:7]
	s_movk_i32 s2, 0xf200
	v_cvt_pkrtz_f16_f32 v10, v70, v71
	v_cmp_lt_i32_e32 vcc, s2, v64
	s_nop 1
	v_cndmask_b32_e32 v9, 0, v4, vcc
	v_cndmask_b32_e32 v8, 0, v0, vcc
	v_mov_b32_e32 v4, v1
	v_cvt_f32_f16_e32 v0, v10
	v_cvt_f32_f16_sdwa v1, v10 dst_sel:DWORD dst_unused:UNUSED_PAD src0_sel:WORD_1
	v_cmp_gt_i32_e32 vcc, s25, v64
	v_pk_fma_f32 v[4:5], v[4:5], v[88:89], v[90:91]
	s_waitcnt lgkmcnt(0)
	v_pk_fma_f32 v[0:1], v[66:67], v[0:1], v[96:97]
	v_cndmask_b32_e32 v13, 0, v6, vcc
	v_cndmask_b32_e32 v12, 0, v2, vcc
	v_pk_fma_f32 v[4:5], v[84:85], v[8:9], v[4:5]
	s_nop 0
	v_pk_fma_f32 v[4:5], v[12:13], v[86:87], v[4:5]
	s_nop 0
	v_pk_mul_f32 v[66:67], v[4:5], v[0:1]
	s_and_saveexec_b64 s[6:7], s[10:11]
	v_ashrrev_i32_e32 v0, 4, v11
	v_lshlrev_b32_e32 v0, 3, v0
	v_add3_u32 v0, 0, v0, v98
	ds_write_b64 v0, v[66:67] offset:28672
	s_or_b64 exec, exec, s[6:7]
	v_readlane_b32 s4, v240, 22
	s_mul_hi_i32 s2, s42, 0x8800
	s_mul_i32 s42, s42, 0x8800
	v_readlane_b32 s6, v240, 24
	v_readlane_b32 s12, v240, 30
	v_readlane_b32 s7, v240, 25
	v_readlane_b32 s13, v240, 31
	s_add_u32 s6, s12, s42
	s_addc_u32 s7, s13, s2
	v_ashrrev_i32_e32 v65, 31, v64
	v_lshl_add_u64 v[4:5], v[64:65], 2, s[6:7]
	v_add_co_u32_e32 v0, vcc, s94, v4
	global_load_dwordx3 v[56:58], v[4:5], off offset:-4
	global_load_dwordx3 v[48:50], v[4:5], off offset:2044
	v_addc_co_u32_e32 v1, vcc, 0, v5, vcc
	v_add_co_u32_e32 v8, vcc, s1, v4
	v_mov_b32_e32 v126, v64
	s_nop 0
	v_addc_co_u32_e32 v9, vcc, 0, v5, vcc
	v_add_co_u32_e32 v10, vcc, s69, v4
	global_load_dwordx3 v[60:62], v[0:1], off offset:4092
	global_load_dwordx3 v[52:54], v[8:9], off offset:2044
	v_addc_co_u32_e32 v11, vcc, 0, v5, vcc
	global_load_dwordx3 v[40:42], v[8:9], off offset:4092
	global_load_dwordx3 v[32:34], v[10:11], off offset:2044
	v_add_co_u32_e32 v8, vcc, s24, v4
	v_mov_b32_e32 v114, 0
	s_nop 0
	v_addc_co_u32_e32 v9, vcc, 0, v5, vcc
	global_load_dwordx3 v[36:38], v[8:9], off offset:2044
	global_load_dwordx3 v[28:30], v[10:11], off offset:4092
	v_add_co_u32_e32 v10, vcc, s73, v4
	v_mov_b32_e32 v115, 0
	s_nop 0
	v_addc_co_u32_e32 v11, vcc, 0, v5, vcc
	v_add_co_u32_e32 v12, vcc, s46, v4
	global_load_dwordx3 v[24:26], v[8:9], off offset:4092
	global_load_dwordx3 v[16:18], v[10:11], off offset:2044
	v_addc_co_u32_e32 v13, vcc, 0, v5, vcc
	global_load_dwordx3 v[20:22], v[12:13], off offset:2044
	s_nop 0
	global_load_dwordx3 v[8:10], v[10:11], off offset:4092
	s_nop 0
	global_load_dwordx3 v[44:46], v[4:5], off offset:4092
	s_nop 0
	global_load_dwordx3 v[0:2], v[0:1], off offset:2044
	v_add_co_u32_e32 v4, vcc, s47, v4
	v_mov_b32_e32 v88, 0
	s_nop 0
	v_addc_co_u32_e32 v5, vcc, 0, v5, vcc
	global_load_dwordx3 v[12:14], v[12:13], off offset:4092
	s_nop 0
	global_load_dwordx3 v[4:6], v[4:5], off offset:2044
	s_waitcnt lgkmcnt(0)
	s_barrier
	v_mov_b32_e32 v89, v114
	v_add_u32_e32 v124, 0x200, v126
	v_lshl_add_u32 v127, v126, 3, 0
	v_ashrrev_i32_e32 v11, 4, v124
	v_add_u32_e32 v123, 0x400, v126
	v_lshl_add_u32 v122, v11, 3, v127
	v_ashrrev_i32_e32 v11, 4, v123
	v_add_u32_e32 v117, 0x600, v126
	v_lshl_add_u32 v116, v11, 3, v127
	v_ashrrev_i32_e32 v11, 4, v117
	v_add_u32_e32 v65, 0x800, v126
	v_lshl_add_u32 v63, v11, 3, v127
	v_ashrrev_i32_e32 v11, 4, v65
	v_add_u32_e32 v59, 0xa00, v126
	v_lshl_add_u32 v31, v11, 3, v127
	v_ashrrev_i32_e32 v11, 4, v59
	v_add_u32_e32 v27, 0xc00, v126
	v_lshl_add_u32 v23, v11, 3, v127
	v_ashrrev_i32_e32 v11, 4, v27
	v_add_u32_e32 v19, 0xe00, v126
	v_ashrrev_i32_e32 v125, 4, v126
	v_lshl_add_u32 v15, v11, 3, v127
	v_ashrrev_i32_e32 v11, 4, v19
	v_cmp_gt_i32_e32 vcc, s70, v126
	v_lshl_add_u32 v134, v125, 3, v127
	v_lshl_add_u32 v11, v11, 3, v127
	v_mov_b32_e32 v96, v114
	v_mov_b32_e32 v97, v114
	v_mov_b32_e32 v104, v114
	v_mov_b32_e32 v105, v114
	v_mov_b32_e32 v110, v114
	v_mov_b32_e32 v111, v114
	v_mov_b32_e32 v86, v114
	v_mov_b32_e32 v87, v114
	v_mov_b32_e32 v94, v114
	v_mov_b32_e32 v95, v114
	v_mov_b32_e32 v102, v114
	v_mov_b32_e32 v103, v114
	v_mov_b32_e32 v108, v114
	v_mov_b32_e32 v109, v114
	v_mov_b32_e32 v84, v114
	v_mov_b32_e32 v85, v114
	v_mov_b32_e32 v92, v114
	v_mov_b32_e32 v93, v114
	v_mov_b32_e32 v100, v114
	v_mov_b32_e32 v101, v114
	v_mov_b32_e32 v106, v114
	v_mov_b32_e32 v107, v114
	v_mov_b32_e32 v70, v114
	v_mov_b32_e32 v71, v114
	v_mov_b32_e32 v90, v114
	v_mov_b32_e32 v91, v114
	v_mov_b32_e32 v98, v114
	v_mov_b32_e32 v99, v114
	v_mov_b32_e32 v112, v114
	v_mov_b32_e32 v113, v114
	v_readlane_b32 s5, v240, 23
	v_readlane_b32 s8, v240, 26
	v_readlane_b32 s9, v240, 27
	v_readlane_b32 s10, v240, 28
	v_readlane_b32 s11, v240, 29
	v_readlane_b32 s14, v240, 32
	v_readlane_b32 s15, v240, 33
	v_readlane_b32 s16, v240, 34
	v_readlane_b32 s17, v240, 35
	v_readlane_b32 s18, v240, 36
	v_readlane_b32 s19, v240, 37
	s_and_saveexec_b64 s[6:7], vcc
	s_xor_b64 s[6:7], exec, s[6:7]
	s_cbranch_execz .LBB0_1650
	ds_read_b64 v[172:173], v134
	ds_read_b64 v[174:175], v122 offset:4096
	ds_read_b64 v[176:177], v116 offset:8192
	ds_read_b64 v[178:179], v63 offset:12288
	ds_read_b64 v[180:181], v31 offset:16384
	ds_read_b64 v[182:183], v23 offset:20480
	ds_read_b64 v[184:185], v15 offset:24576
	ds_read_b64 v[186:187], v11 offset:28672
	s_waitcnt lgkmcnt(8)
	s_waitcnt lgkmcnt(7)
	v_pk_add_f32 v[90:91], v[172:173], 0 op_sel_hi:[1,0]
	s_waitcnt lgkmcnt(3)
	v_pk_add_f32 v[92:93], v[180:181], 0 op_sel_hi:[1,0]
	v_xor_b32_e32 v115, 0x80000000, v180
	v_pk_add_f32 v[94:95], v[90:91], v[92:93]
	v_pk_add_f32 v[98:99], v[90:91], v[92:93] neg_lo:[0,1] neg_hi:[0,1]
	v_mov_b32_e32 v114, v181
	v_pk_add_f32 v[70:71], v[174:175], 0 op_sel_hi:[1,0]
	s_waitcnt lgkmcnt(2)
	v_pk_add_f32 v[92:93], v[182:183], 0 op_sel_hi:[1,0]
	v_xor_b32_e32 v129, 0x80000000, v182
	v_pk_add_f32 v[96:97], v[70:71], v[92:93]
	v_pk_add_f32 v[100:101], v[70:71], v[92:93] neg_lo:[0,1] neg_hi:[0,1]
	v_mov_b32_e32 v128, v183
	v_pk_add_f32 v[70:71], v[176:177], 0 op_sel_hi:[1,0]
	s_waitcnt lgkmcnt(1)
	v_pk_add_f32 v[84:85], v[184:185], 0 op_sel_hi:[1,0]
	v_xor_b32_e32 v131, 0x80000000, v184
	v_pk_add_f32 v[102:103], v[70:71], v[84:85]
	v_pk_add_f32 v[104:105], v[70:71], v[84:85] neg_lo:[0,1] neg_hi:[0,1]
	v_pk_add_f32 v[70:71], v[178:179], 0 op_sel_hi:[1,0]
	s_waitcnt lgkmcnt(0)
	v_pk_add_f32 v[84:85], v[186:187], 0 op_sel_hi:[1,0]
	v_mov_b32_e32 v130, v185
	v_pk_add_f32 v[86:87], v[70:71], v[84:85]
	v_pk_add_f32 v[136:137], v[70:71], v[84:85] neg_lo:[0,1] neg_hi:[0,1]
	v_pk_add_f32 v[70:71], v[94:95], v[102:103]
	v_pk_add_f32 v[84:85], v[96:97], v[86:87]
	v_pk_add_f32 v[86:87], v[96:97], v[86:87] neg_lo:[0,1] neg_hi:[0,1]
	v_pk_add_f32 v[92:93], v[174:175], v[128:129]
	v_xor_b32_e32 v139, 0x80000000, v186
	v_mov_b32_e32 v138, v187
	v_pk_add_f32 v[94:95], v[94:95], v[102:103] neg_lo:[0,1] neg_hi:[0,1]
	v_pk_add_f32 v[88:89], v[70:71], v[84:85]
	v_pk_add_f32 v[84:85], v[70:71], v[84:85] neg_lo:[0,1] neg_hi:[0,1]
	v_xor_b32_e32 v71, 0x80000000, v86
	v_mov_b32_e32 v70, v87
	s_mov_b32 s29, s26
	v_pk_add_f32 v[132:133], v[176:177], v[130:131]
	v_pk_add_f32 v[140:141], v[178:179], v[138:139]
	v_pk_add_f32 v[86:87], v[94:95], v[70:71]
	v_pk_add_f32 v[70:71], v[94:95], v[70:71] neg_lo:[0,1] neg_hi:[0,1]
	v_pk_mul_f32 v[94:95], v[92:93], s[28:29] op_sel:[1,0]
	s_mov_b32 s8, s26
	s_mov_b32 s9, s28
	v_pk_fma_f32 v[92:93], v[92:93], s[26:27], v[94:95] op_sel_hi:[0,1,1]
	v_mul_f32_e32 v94, 0x3f3504f3, v133
	s_mov_b32 s29, s34
	v_pk_mul_f32 v[96:97], v[140:141], s[8:9] op_sel:[1,0]
	v_pk_add_f32 v[90:91], v[172:173], v[114:115]
	v_pk_fma_f32 v[94:95], v[132:133], s[30:31], v[94:95] op_sel_hi:[0,1,0]
	v_pk_fma_f32 v[96:97], v[140:141], s[28:29], v[96:97] op_sel_hi:[0,1,1]
	v_pk_add_f32 v[102:103], v[90:91], v[94:95]
	v_pk_add_f32 v[90:91], v[90:91], v[94:95] neg_lo:[0,1] neg_hi:[0,1]
	v_pk_add_f32 v[94:95], v[92:93], v[96:97]
	v_pk_add_f32 v[132:133], v[92:93], v[96:97] neg_lo:[0,1] neg_hi:[0,1]
	v_pk_add_f32 v[96:97], v[102:103], v[94:95]
	v_pk_add_f32 v[92:93], v[102:103], v[94:95] neg_lo:[0,1] neg_hi:[0,1]
	v_xor_b32_e32 v103, 0x80000000, v132
	v_mov_b32_e32 v102, v133
	v_pk_add_f32 v[94:95], v[90:91], v[102:103]
	v_pk_add_f32 v[90:91], v[90:91], v[102:103] neg_lo:[0,1] neg_hi:[0,1]
	v_mul_f32_e32 v102, 0x3f3504f3, v101
	s_mov_b32 s37, s20
	v_pk_fma_f32 v[100:101], v[100:101], s[30:31], v[102:103] op_sel_hi:[0,1,0]
	v_pk_mul_f32 v[102:103], v[104:105], s[36:37] op_sel:[1,0]
	v_pk_add_f32 v[108:109], v[174:175], v[128:129] neg_lo:[0,1] neg_hi:[0,1]
	v_pk_fma_f32 v[102:103], v[104:105], s[20:21], v[102:103] op_sel_hi:[0,1,1]
	v_mul_f32_e32 v104, 0xbf3504f3, v136
	v_pk_fma_f32 v[104:105], v[136:137], s[30:31], v[104:105] op_sel:[1,0,0] op_sel_hi:[1,1,0]
	v_pk_add_f32 v[132:133], v[98:99], v[102:103]
	v_pk_add_f32 v[98:99], v[98:99], v[102:103] neg_lo:[0,1] neg_hi:[0,1]
	v_pk_add_f32 v[102:103], v[100:101], v[104:105]
	v_pk_add_f32 v[136:137], v[100:101], v[104:105] neg_lo:[0,1] neg_hi:[0,1]
	v_pk_add_f32 v[104:105], v[132:133], v[102:103]
	v_pk_add_f32 v[100:101], v[132:133], v[102:103] neg_lo:[0,1] neg_hi:[0,1]
	v_xor_b32_e32 v133, 0x80000000, v136
	v_mov_b32_e32 v132, v137
	v_pk_add_f32 v[112:113], v[178:179], v[138:139] neg_lo:[0,1] neg_hi:[0,1]
	s_mov_b32 s10, s27
	s_mov_b32 s11, s34
	v_pk_add_f32 v[106:107], v[172:173], v[114:115] neg_lo:[0,1] neg_hi:[0,1]
	v_pk_mul_f32 v[114:115], v[108:109], s[8:9] op_sel:[1,0]
	v_pk_add_f32 v[110:111], v[176:177], v[130:131] neg_lo:[0,1] neg_hi:[0,1]
	v_pk_add_f32 v[102:103], v[98:99], v[132:133]
	v_pk_add_f32 v[98:99], v[98:99], v[132:133] neg_lo:[0,1] neg_hi:[0,1]
	s_mov_b32 s35, s28
	v_pk_mul_f32 v[132:133], v[112:113], s[10:11] op_sel:[1,0]
	v_pk_fma_f32 v[108:109], v[108:109], s[28:29], v[114:115] op_sel_hi:[0,1,1]
	v_mul_f32_e32 v114, 0xbf3504f3, v110
	v_pk_fma_f32 v[112:113], v[112:113], s[34:35], v[132:133] op_sel_hi:[0,1,1]
	v_pk_fma_f32 v[110:111], v[110:111], s[30:31], v[114:115] op_sel:[1,0,0] op_sel_hi:[1,1,0]
	s_nop 0
	v_pk_add_f32 v[114:115], v[106:107], v[110:111]
	v_pk_add_f32 v[128:129], v[106:107], v[110:111] neg_lo:[0,1] neg_hi:[0,1]
	v_pk_add_f32 v[106:107], v[108:109], v[112:113]
	v_pk_add_f32 v[108:109], v[108:109], v[112:113] neg_lo:[0,1] neg_hi:[0,1]
	v_pk_add_f32 v[110:111], v[114:115], v[106:107]
	v_xor_b32_e32 v113, 0x80000000, v108
	v_mov_b32_e32 v112, v109
	v_pk_add_f32 v[106:107], v[114:115], v[106:107] neg_lo:[0,1] neg_hi:[0,1]
	v_pk_add_f32 v[114:115], v[128:129], v[112:113] neg_lo:[0,1] neg_hi:[0,1]
	v_pk_add_f32 v[108:109], v[128:129], v[112:113]
	v_mov_b32_e32 v112, v114
	v_mov_b32_e32 v113, v115

.LBB0_1652:
	s_or_b64 exec, exec, s[6:7]
	v_add_u32_e32 v114, 0x1000, v126
	v_ashrrev_i32_e32 v114, 4, v114
	v_lshlrev_b32_e32 v114, 3, v114
	v_lshlrev_b32_e32 v133, 3, v126
	v_add3_u32 v132, 0, v114, v133
	v_add_u32_e32 v114, 0x1200, v126
	v_ashrrev_i32_e32 v114, 4, v114
	v_lshlrev_b32_e32 v114, 3, v114
	v_add3_u32 v131, 0, v114, v133
	v_add_u32_e32 v114, 0x1400, v126
	v_ashrrev_i32_e32 v114, 4, v114
	v_lshlrev_b32_e32 v114, 3, v114
	v_add3_u32 v130, 0, v114, v133
	v_add_u32_e32 v114, 0x1600, v126
	v_ashrrev_i32_e32 v114, 4, v114
	v_lshlrev_b32_e32 v114, 3, v114
	v_add3_u32 v129, 0, v114, v133
	v_add_u32_e32 v114, 0x1800, v126
	v_ashrrev_i32_e32 v114, 4, v114
	v_lshlrev_b32_e32 v114, 3, v114
	v_add3_u32 v128, 0, v114, v133
	v_add_u32_e32 v114, 0x1a00, v126
	v_ashrrev_i32_e32 v114, 4, v114
	v_lshlrev_b32_e32 v114, 3, v114
	v_add3_u32 v127, 0, v114, v133
	v_add_u32_e32 v114, 0x1c00, v126
	v_ashrrev_i32_e32 v114, 4, v114
	v_lshlrev_b32_e32 v114, 3, v114
	v_add3_u32 v115, 0, v114, v133
	v_add_u32_e32 v114, 0x1e00, v126
	v_ashrrev_i32_e32 v114, 4, v114
	s_waitcnt lgkmcnt(0)
	s_barrier
	v_lshlrev_b32_e32 v114, 3, v114
	v_add3_u32 v114, 0, v114, v133
	s_and_saveexec_b64 s[6:7], vcc
	s_cbranch_execz .LBB0_1654
	ds_read_b64 v[172:173], v134
	ds_read_b64 v[174:175], v122 offset:4096
	ds_read_b64 v[176:177], v116 offset:8192
	ds_read_b64 v[178:179], v63 offset:12288
	ds_read_b64 v[180:181], v31 offset:16384
	ds_read_b64 v[182:183], v23 offset:20480
	ds_read_b64 v[184:185], v15 offset:24576
	ds_read_b64 v[186:187], v11 offset:28672
	ds_read_b64 v[188:189], v132 offset:32768
	ds_read_b64 v[190:191], v131 offset:36864
	ds_read_b64 v[192:193], v130 offset:40960
	ds_read_b64 v[194:195], v129 offset:45056
	ds_read_b64 v[196:197], v128 offset:49152
	ds_read_b64 v[198:199], v127 offset:53248
	ds_read_b64 v[200:201], v115 offset:57344
	v_and_b32_e32 v106, 15, v126
	v_cvt_f32_ubyte0_e32 v106, v106
	v_mul_f32_e32 v107, 0x3b800000, v106
	v_cos_f32_e32 v106, v107
	v_sin_f32_e32 v108, v107
	s_waitcnt lgkmcnt(14)
	ds_read_b64 v[202:203], v114 offset:61440
	v_mov_b32_e32 v109, v106
	v_xor_b32_e32 v107, 0x80000000, v108
	v_pk_mul_f32 v[140:141], v[108:109], v[108:109] op_sel_hi:[1,0] neg_lo:[0,1] neg_hi:[0,1]
	s_mov_b32 s29, s26
	v_pk_fma_f32 v[140:141], v[106:107], v[106:107], v[140:141] op_sel_hi:[1,0,1]
	s_mov_b32 s8, s26
	v_pk_mul_f32 v[142:143], v[108:109], v[140:141] op_sel:[0,1]
	s_mov_b32 s9, s28
	v_pk_fma_f32 v[142:143], v[106:107], v[140:141], v[142:143] op_sel_hi:[1,0,1]
	s_mov_b32 s37, s20
	v_pk_mul_f32 v[144:145], v[108:109], v[142:143] op_sel:[0,1]
	s_mov_b32 s10, s27
	v_pk_fma_f32 v[144:145], v[106:107], v[142:143], v[144:145] op_sel_hi:[1,0,1]
	s_mov_b32 s11, s34
	v_pk_mul_f32 v[146:147], v[108:109], v[144:145] op_sel:[0,1]
	s_mov_b32 s35, s28
	v_pk_fma_f32 v[146:147], v[106:107], v[144:145], v[146:147] op_sel_hi:[1,0,1]
	s_nop 0
	v_pk_mul_f32 v[148:149], v[108:109], v[146:147] op_sel:[0,1]
	s_nop 0
	v_pk_fma_f32 v[148:149], v[106:107], v[146:147], v[148:149] op_sel_hi:[1,0,1]
	s_nop 0
	v_pk_mul_f32 v[150:151], v[108:109], v[148:149] op_sel:[0,1]
	s_nop 0
	v_pk_fma_f32 v[150:151], v[106:107], v[148:149], v[150:151] op_sel_hi:[1,0,1]
	s_nop 0
	v_pk_mul_f32 v[152:153], v[108:109], v[150:151] op_sel:[0,1]
	s_nop 0
	v_pk_fma_f32 v[152:153], v[106:107], v[150:151], v[152:153] op_sel_hi:[1,0,1]
	s_nop 0
	v_pk_mul_f32 v[154:155], v[108:109], v[152:153] op_sel:[0,1]
	s_nop 0
	v_pk_fma_f32 v[154:155], v[106:107], v[152:153], v[154:155] op_sel_hi:[1,0,1]
	s_nop 0
	v_pk_mul_f32 v[156:157], v[108:109], v[154:155] op_sel:[0,1]
	s_nop 0
	v_pk_fma_f32 v[156:157], v[106:107], v[154:155], v[156:157] op_sel_hi:[1,0,1]
	s_nop 0
	v_pk_mul_f32 v[158:159], v[108:109], v[156:157] op_sel:[0,1]
	s_nop 0
	v_pk_fma_f32 v[158:159], v[106:107], v[156:157], v[158:159] op_sel_hi:[1,0,1]
	s_nop 0
	v_pk_mul_f32 v[160:161], v[108:109], v[158:159] op_sel:[0,1]
	s_nop 0
	v_pk_fma_f32 v[160:161], v[106:107], v[158:159], v[160:161] op_sel_hi:[1,0,1]
	s_nop 0
	v_pk_mul_f32 v[162:163], v[108:109], v[160:161] op_sel:[0,1]
	s_nop 0
	v_pk_fma_f32 v[162:163], v[106:107], v[160:161], v[162:163] op_sel_hi:[1,0,1]
	s_nop 0
	v_pk_mul_f32 v[164:165], v[108:109], v[162:163] op_sel:[0,1]
	s_nop 0
	v_pk_fma_f32 v[164:165], v[106:107], v[162:163], v[164:165] op_sel_hi:[1,0,1]
	s_nop 0
	v_pk_mul_f32 v[166:167], v[108:109], v[164:165] op_sel:[0,1]
	s_waitcnt lgkmcnt(15)
	s_waitcnt lgkmcnt(14)
	v_pk_mul_f32 v[108:109], v[108:109], v[174:175] op_sel:[0,1]
	v_pk_fma_f32 v[166:167], v[106:107], v[164:165], v[166:167] op_sel_hi:[1,0,1]
	v_pk_fma_f32 v[84:85], v[106:107], v[174:175], v[108:109] op_sel_hi:[1,0,1]
	v_xor_b32_e32 v168, 0x80000000, v167
	v_mov_b32_e32 v169, v166
	s_waitcnt lgkmcnt(0)
	v_pk_mul_f32 v[168:169], v[168:169], v[202:203] op_sel:[0,1]
	s_nop 0
	v_pk_fma_f32 v[138:139], v[166:167], v[202:203], v[168:169] op_sel_hi:[1,0,1]
	v_xor_b32_e32 v166, 0x80000000, v165
	v_mov_b32_e32 v167, v164
	v_pk_mul_f32 v[166:167], v[166:167], v[200:201] op_sel:[0,1]
	s_nop 0
	v_pk_fma_f32 v[136:137], v[164:165], v[200:201], v[166:167] op_sel_hi:[1,0,1]
	v_xor_b32_e32 v164, 0x80000000, v163
	v_mov_b32_e32 v165, v162
	v_pk_mul_f32 v[164:165], v[164:165], v[198:199] op_sel:[0,1]
	s_nop 0
	v_pk_fma_f32 v[112:113], v[162:163], v[198:199], v[164:165] op_sel_hi:[1,0,1]
	v_xor_b32_e32 v162, 0x80000000, v161
	v_mov_b32_e32 v163, v160
	v_pk_mul_f32 v[162:163], v[162:163], v[196:197] op_sel:[0,1]
	s_nop 0
	v_pk_fma_f32 v[110:111], v[160:161], v[196:197], v[162:163] op_sel_hi:[1,0,1]
	v_xor_b32_e32 v160, 0x80000000, v159
	v_mov_b32_e32 v161, v158
	v_pk_mul_f32 v[160:161], v[160:161], v[194:195] op_sel:[0,1]
	s_nop 0
	v_pk_fma_f32 v[104:105], v[158:159], v[194:195], v[160:161] op_sel_hi:[1,0,1]
	v_xor_b32_e32 v158, 0x80000000, v157
	v_mov_b32_e32 v159, v156
	v_pk_mul_f32 v[158:159], v[158:159], v[192:193] op_sel:[0,1]
	s_nop 0
	v_pk_fma_f32 v[102:103], v[156:157], v[192:193], v[158:159] op_sel_hi:[1,0,1]
	v_xor_b32_e32 v156, 0x80000000, v155
	v_mov_b32_e32 v157, v154
	v_pk_mul_f32 v[156:157], v[156:157], v[190:191] op_sel:[0,1]
	s_nop 0
	v_pk_fma_f32 v[100:101], v[154:155], v[190:191], v[156:157] op_sel_hi:[1,0,1]
	v_xor_b32_e32 v154, 0x80000000, v153
	v_mov_b32_e32 v155, v152
	v_pk_mul_f32 v[154:155], v[154:155], v[188:189] op_sel:[0,1]
	s_nop 0
	v_pk_fma_f32 v[98:99], v[152:153], v[188:189], v[154:155] op_sel_hi:[1,0,1]
	v_xor_b32_e32 v152, 0x80000000, v151
	v_mov_b32_e32 v153, v150
	v_pk_mul_f32 v[152:153], v[152:153], v[186:187] op_sel:[0,1]
	v_pk_add_f32 v[106:107], v[172:173], v[98:99]
	v_pk_fma_f32 v[96:97], v[150:151], v[186:187], v[152:153] op_sel_hi:[1,0,1]
	v_xor_b32_e32 v150, 0x80000000, v149
	v_mov_b32_e32 v151, v148
	v_pk_mul_f32 v[150:151], v[150:151], v[184:185] op_sel:[0,1]
	v_pk_add_f32 v[108:109], v[172:173], v[98:99] neg_lo:[0,1] neg_hi:[0,1]
	v_pk_fma_f32 v[94:95], v[148:149], v[184:185], v[150:151] op_sel_hi:[1,0,1]
	v_xor_b32_e32 v148, 0x80000000, v147
	v_mov_b32_e32 v149, v146
	v_pk_mul_f32 v[148:149], v[148:149], v[182:183] op_sel:[0,1]
	s_nop 0
	v_pk_fma_f32 v[92:93], v[146:147], v[182:183], v[148:149] op_sel_hi:[1,0,1]
	v_xor_b32_e32 v146, 0x80000000, v145
	v_mov_b32_e32 v147, v144
	v_pk_mul_f32 v[146:147], v[146:147], v[180:181] op_sel:[0,1]
	s_nop 0
	v_pk_fma_f32 v[90:91], v[144:145], v[180:181], v[146:147] op_sel_hi:[1,0,1]
	v_xor_b32_e32 v144, 0x80000000, v143
	v_mov_b32_e32 v145, v142
	v_pk_mul_f32 v[144:145], v[144:145], v[178:179] op_sel:[0,1]
	v_pk_add_f32 v[70:71], v[90:91], v[110:111]
	v_pk_fma_f32 v[88:89], v[142:143], v[178:179], v[144:145] op_sel_hi:[1,0,1]
	v_xor_b32_e32 v142, 0x80000000, v141
	v_mov_b32_e32 v143, v140
	v_pk_mul_f32 v[142:143], v[142:143], v[176:177] op_sel:[0,1]
	v_pk_add_f32 v[98:99], v[106:107], v[70:71]
	v_pk_fma_f32 v[86:87], v[140:141], v[176:177], v[142:143] op_sel_hi:[1,0,1]
	v_pk_add_f32 v[106:107], v[106:107], v[70:71] neg_lo:[0,1] neg_hi:[0,1]
	v_pk_add_f32 v[70:71], v[84:85], v[100:101]
	v_pk_add_f32 v[140:141], v[84:85], v[100:101] neg_lo:[0,1] neg_hi:[0,1]
	v_pk_add_f32 v[84:85], v[92:93], v[112:113]
	v_pk_add_f32 v[92:93], v[92:93], v[112:113] neg_lo:[0,1] neg_hi:[0,1]
	v_pk_add_f32 v[100:101], v[70:71], v[84:85]
	v_pk_add_f32 v[112:113], v[70:71], v[84:85] neg_lo:[0,1] neg_hi:[0,1]
	v_pk_add_f32 v[70:71], v[86:87], v[102:103]
	v_pk_add_f32 v[84:85], v[94:95], v[136:137]
	v_pk_add_f32 v[144:145], v[86:87], v[102:103] neg_lo:[0,1] neg_hi:[0,1]
	v_pk_add_f32 v[86:87], v[94:95], v[136:137] neg_lo:[0,1] neg_hi:[0,1]
	v_pk_add_f32 v[94:95], v[70:71], v[84:85]
	v_pk_add_f32 v[102:103], v[70:71], v[84:85] neg_lo:[0,1] neg_hi:[0,1]
	v_pk_add_f32 v[70:71], v[88:89], v[104:105]
	v_pk_add_f32 v[84:85], v[96:97], v[138:139]
	v_xor_b32_e32 v137, 0x80000000, v86
	v_mov_b32_e32 v136, v87
	v_pk_add_f32 v[148:149], v[88:89], v[104:105] neg_lo:[0,1] neg_hi:[0,1]
	v_pk_add_f32 v[86:87], v[96:97], v[138:139] neg_lo:[0,1] neg_hi:[0,1]
	v_pk_add_f32 v[88:89], v[70:71], v[84:85]
	v_xor_b32_e32 v143, 0x80000000, v92
	v_mov_b32_e32 v142, v93
	v_pk_add_f32 v[104:105], v[70:71], v[84:85] neg_lo:[0,1] neg_hi:[0,1]
	v_xor_b32_e32 v139, 0x80000000, v86
	v_mov_b32_e32 v138, v87
	v_pk_add_f32 v[70:71], v[98:99], v[94:95]
	v_pk_add_f32 v[84:85], v[100:101], v[88:89]
	v_pk_add_f32 v[86:87], v[100:101], v[88:89] neg_lo:[0,1] neg_hi:[0,1]
	v_pk_add_f32 v[92:93], v[140:141], v[142:143]
	v_pk_add_f32 v[94:95], v[98:99], v[94:95] neg_lo:[0,1] neg_hi:[0,1]
	v_pk_add_f32 v[88:89], v[70:71], v[84:85]
	v_pk_add_f32 v[84:85], v[70:71], v[84:85] neg_lo:[0,1] neg_hi:[0,1]
	v_xor_b32_e32 v71, 0x80000000, v86
	v_mov_b32_e32 v70, v87
	v_pk_add_f32 v[90:91], v[90:91], v[110:111] neg_lo:[0,1] neg_hi:[0,1]
	v_pk_add_f32 v[146:147], v[144:145], v[136:137]
	v_pk_add_f32 v[96:97], v[148:149], v[138:139]
	v_pk_add_f32 v[86:87], v[94:95], v[70:71]
	v_pk_add_f32 v[70:71], v[94:95], v[70:71] neg_lo:[0,1] neg_hi:[0,1]
	v_pk_mul_f32 v[94:95], v[92:93], s[28:29] op_sel:[1,0]
	v_xor_b32_e32 v111, 0x80000000, v90
	v_mov_b32_e32 v110, v91
	v_pk_fma_f32 v[92:93], v[92:93], s[26:27], v[94:95] op_sel_hi:[0,1,1]
	v_mul_f32_e32 v94, 0x3f3504f3, v147
	s_mov_b32 s29, s34
	v_pk_mul_f32 v[98:99], v[96:97], s[8:9] op_sel:[1,0]
	v_pk_add_f32 v[90:91], v[108:109], v[110:111]
	v_pk_fma_f32 v[94:95], v[146:147], s[30:31], v[94:95] op_sel_hi:[0,1,0]
	v_pk_fma_f32 v[96:97], v[96:97], s[28:29], v[98:99] op_sel_hi:[0,1,1]
	v_pk_add_f32 v[98:99], v[90:91], v[94:95]
	v_pk_add_f32 v[90:91], v[90:91], v[94:95] neg_lo:[0,1] neg_hi:[0,1]
	v_pk_add_f32 v[94:95], v[92:93], v[96:97]
	v_pk_add_f32 v[100:101], v[92:93], v[96:97] neg_lo:[0,1] neg_hi:[0,1]
	v_pk_add_f32 v[96:97], v[98:99], v[94:95]
	v_pk_add_f32 v[92:93], v[98:99], v[94:95] neg_lo:[0,1] neg_hi:[0,1]
	v_xor_b32_e32 v99, 0x80000000, v100
	v_mov_b32_e32 v98, v101
	v_pk_mul_f32 v[100:101], v[102:103], s[36:37] op_sel:[1,0]
	v_pk_add_f32 v[94:95], v[90:91], v[98:99]
	v_pk_add_f32 v[90:91], v[90:91], v[98:99] neg_lo:[0,1] neg_hi:[0,1]
	v_mul_f32_e32 v98, 0x3f3504f3, v113
	v_pk_fma_f32 v[100:101], v[102:103], s[20:21], v[100:101] op_sel_hi:[0,1,1]
	v_mul_f32_e32 v102, 0xbf3504f3, v104
	v_pk_fma_f32 v[98:99], v[112:113], s[30:31], v[98:99] op_sel_hi:[0,1,0]
	v_pk_fma_f32 v[102:103], v[104:105], s[30:31], v[102:103] op_sel:[1,0,0] op_sel_hi:[1,1,0]
	v_pk_add_f32 v[112:113], v[106:107], v[100:101]
	v_pk_add_f32 v[106:107], v[106:107], v[100:101] neg_lo:[0,1] neg_hi:[0,1]
	v_pk_add_f32 v[100:101], v[98:99], v[102:103]
	v_pk_add_f32 v[98:99], v[98:99], v[102:103] neg_lo:[0,1] neg_hi:[0,1]
	v_pk_add_f32 v[104:105], v[112:113], v[100:101]
	v_pk_add_f32 v[100:101], v[112:113], v[100:101] neg_lo:[0,1] neg_hi:[0,1]
	v_xor_b32_e32 v113, 0x80000000, v98
	v_mov_b32_e32 v112, v99
	v_pk_add_f32 v[102:103], v[106:107], v[112:113]
	v_pk_add_f32 v[98:99], v[106:107], v[112:113] neg_lo:[0,1] neg_hi:[0,1]
	v_pk_add_f32 v[106:107], v[148:149], v[138:139] neg_lo:[0,1] neg_hi:[0,1]
	v_pk_add_f32 v[108:109], v[108:109], v[110:111] neg_lo:[0,1] neg_hi:[0,1]
	v_pk_mul_f32 v[112:113], v[106:107], s[10:11] op_sel:[1,0]
	v_pk_add_f32 v[110:111], v[140:141], v[142:143] neg_lo:[0,1] neg_hi:[0,1]
	v_pk_fma_f32 v[106:107], v[106:107], s[34:35], v[112:113] op_sel_hi:[0,1,1]
	v_pk_mul_f32 v[112:113], v[110:111], s[8:9] op_sel:[1,0]
	s_nop 0
	v_pk_fma_f32 v[110:111], v[110:111], s[28:29], v[112:113] op_sel_hi:[0,1,1]
	v_pk_add_f32 v[112:113], v[144:145], v[136:137] neg_lo:[0,1] neg_hi:[0,1]
	v_pk_add_f32 v[138:139], v[110:111], v[106:107] neg_lo:[0,1] neg_hi:[0,1]
	v_mul_f32_e32 v136, 0xbf3504f3, v112
	v_pk_fma_f32 v[112:113], v[112:113], s[30:31], v[136:137] op_sel:[1,0,0] op_sel_hi:[1,1,0]
	s_nop 0
	v_pk_add_f32 v[136:137], v[108:109], v[112:113]
	v_pk_add_f32 v[112:113], v[108:109], v[112:113] neg_lo:[0,1] neg_hi:[0,1]
	v_pk_add_f32 v[108:109], v[110:111], v[106:107]
	s_nop 0
	v_pk_add_f32 v[110:111], v[136:137], v[108:109]
	v_pk_add_f32 v[106:107], v[136:137], v[108:109] neg_lo:[0,1] neg_hi:[0,1]
	v_xor_b32_e32 v137, 0x80000000, v138
	v_mov_b32_e32 v136, v139
	v_pk_add_f32 v[108:109], v[112:113], v[136:137]
	v_pk_add_f32 v[112:113], v[112:113], v[136:137] neg_lo:[0,1] neg_hi:[0,1]

.LBB0_1656:
	s_or_b64 exec, exec, s[6:7]
	s_waitcnt lgkmcnt(0)
	s_barrier
	s_and_saveexec_b64 s[6:7], vcc
	s_cbranch_execz .LBB0_1658
	ds_read_b64 v[172:173], v134
	ds_read_b64 v[174:175], v122 offset:4096
	ds_read_b64 v[176:177], v116 offset:8192
	ds_read_b64 v[178:179], v63 offset:12288
	ds_read_b64 v[180:181], v31 offset:16384
	ds_read_b64 v[182:183], v23 offset:20480
	ds_read_b64 v[184:185], v15 offset:24576
	ds_read_b64 v[186:187], v11 offset:28672
	ds_read_b64 v[188:189], v132 offset:32768
	ds_read_b64 v[190:191], v131 offset:36864
	ds_read_b64 v[192:193], v130 offset:40960
	ds_read_b64 v[194:195], v129 offset:45056
	ds_read_b64 v[196:197], v128 offset:49152
	ds_read_b64 v[198:199], v127 offset:53248
	ds_read_b64 v[200:201], v115 offset:57344
	v_cvt_f32_ubyte0_e32 v106, v126
	v_mul_f32_e32 v107, 0x39800000, v106
	v_cos_f32_e32 v106, v107
	v_sin_f32_e32 v108, v107
	s_waitcnt lgkmcnt(14)
	ds_read_b64 v[202:203], v114 offset:61440
	v_mov_b32_e32 v109, v106
	v_xor_b32_e32 v107, 0x80000000, v108
	v_pk_mul_f32 v[140:141], v[108:109], v[108:109] op_sel_hi:[1,0] neg_lo:[0,1] neg_hi:[0,1]
	s_mov_b32 s29, s26
	v_pk_fma_f32 v[140:141], v[106:107], v[106:107], v[140:141] op_sel_hi:[1,0,1]
	s_mov_b32 s8, s26
	v_pk_mul_f32 v[142:143], v[108:109], v[140:141] op_sel:[0,1]
	s_mov_b32 s9, s28
	v_pk_fma_f32 v[142:143], v[106:107], v[140:141], v[142:143] op_sel_hi:[1,0,1]
	s_mov_b32 s37, s20
	v_pk_mul_f32 v[144:145], v[108:109], v[142:143] op_sel:[0,1]
	s_mov_b32 s10, s27
	v_pk_fma_f32 v[144:145], v[106:107], v[142:143], v[144:145] op_sel_hi:[1,0,1]
	s_mov_b32 s11, s34
	v_pk_mul_f32 v[146:147], v[108:109], v[144:145] op_sel:[0,1]
	s_mov_b32 s35, s28
	v_pk_fma_f32 v[146:147], v[106:107], v[144:145], v[146:147] op_sel_hi:[1,0,1]
	s_nop 0
	v_pk_mul_f32 v[148:149], v[108:109], v[146:147] op_sel:[0,1]
	s_nop 0
	v_pk_fma_f32 v[148:149], v[106:107], v[146:147], v[148:149] op_sel_hi:[1,0,1]
	s_nop 0
	v_pk_mul_f32 v[150:151], v[108:109], v[148:149] op_sel:[0,1]
	s_nop 0
	v_pk_fma_f32 v[150:151], v[106:107], v[148:149], v[150:151] op_sel_hi:[1,0,1]
	s_nop 0
	v_pk_mul_f32 v[152:153], v[108:109], v[150:151] op_sel:[0,1]
	s_nop 0
	v_pk_fma_f32 v[152:153], v[106:107], v[150:151], v[152:153] op_sel_hi:[1,0,1]
	s_nop 0
	v_pk_mul_f32 v[154:155], v[108:109], v[152:153] op_sel:[0,1]
	s_nop 0
	v_pk_fma_f32 v[154:155], v[106:107], v[152:153], v[154:155] op_sel_hi:[1,0,1]
	s_nop 0
	v_pk_mul_f32 v[156:157], v[108:109], v[154:155] op_sel:[0,1]
	s_nop 0
	v_pk_fma_f32 v[156:157], v[106:107], v[154:155], v[156:157] op_sel_hi:[1,0,1]
	s_nop 0
	v_pk_mul_f32 v[158:159], v[108:109], v[156:157] op_sel:[0,1]
	s_nop 0
	v_pk_fma_f32 v[158:159], v[106:107], v[156:157], v[158:159] op_sel_hi:[1,0,1]
	s_nop 0
	v_pk_mul_f32 v[160:161], v[108:109], v[158:159] op_sel:[0,1]
	s_nop 0
	v_pk_fma_f32 v[160:161], v[106:107], v[158:159], v[160:161] op_sel_hi:[1,0,1]
	s_nop 0
	v_pk_mul_f32 v[162:163], v[108:109], v[160:161] op_sel:[0,1]
	s_nop 0
	v_pk_fma_f32 v[162:163], v[106:107], v[160:161], v[162:163] op_sel_hi:[1,0,1]
	s_nop 0
	v_pk_mul_f32 v[164:165], v[108:109], v[162:163] op_sel:[0,1]
	s_nop 0
	v_pk_fma_f32 v[164:165], v[106:107], v[162:163], v[164:165] op_sel_hi:[1,0,1]
	s_nop 0
	v_pk_mul_f32 v[166:167], v[108:109], v[164:165] op_sel:[0,1]
	s_waitcnt lgkmcnt(15)
	s_waitcnt lgkmcnt(14)
	v_pk_mul_f32 v[108:109], v[108:109], v[174:175] op_sel:[0,1]
	v_pk_fma_f32 v[166:167], v[106:107], v[164:165], v[166:167] op_sel_hi:[1,0,1]
	v_pk_fma_f32 v[84:85], v[106:107], v[174:175], v[108:109] op_sel_hi:[1,0,1]
	v_xor_b32_e32 v168, 0x80000000, v167
	v_mov_b32_e32 v169, v166
	s_waitcnt lgkmcnt(0)
	v_pk_mul_f32 v[168:169], v[168:169], v[202:203] op_sel:[0,1]
	s_nop 0
	v_pk_fma_f32 v[138:139], v[166:167], v[202:203], v[168:169] op_sel_hi:[1,0,1]
	v_xor_b32_e32 v166, 0x80000000, v165
	v_mov_b32_e32 v167, v164
	v_pk_mul_f32 v[166:167], v[166:167], v[200:201] op_sel:[0,1]
	s_nop 0
	v_pk_fma_f32 v[136:137], v[164:165], v[200:201], v[166:167] op_sel_hi:[1,0,1]
	v_xor_b32_e32 v164, 0x80000000, v163
	v_mov_b32_e32 v165, v162
	v_pk_mul_f32 v[164:165], v[164:165], v[198:199] op_sel:[0,1]
	s_nop 0
	v_pk_fma_f32 v[112:113], v[162:163], v[198:199], v[164:165] op_sel_hi:[1,0,1]
	v_xor_b32_e32 v162, 0x80000000, v161
	v_mov_b32_e32 v163, v160
	v_pk_mul_f32 v[162:163], v[162:163], v[196:197] op_sel:[0,1]
	s_nop 0
	v_pk_fma_f32 v[110:111], v[160:161], v[196:197], v[162:163] op_sel_hi:[1,0,1]
	v_xor_b32_e32 v160, 0x80000000, v159
	v_mov_b32_e32 v161, v158
	v_pk_mul_f32 v[160:161], v[160:161], v[194:195] op_sel:[0,1]
	s_nop 0
	v_pk_fma_f32 v[104:105], v[158:159], v[194:195], v[160:161] op_sel_hi:[1,0,1]
	v_xor_b32_e32 v158, 0x80000000, v157
	v_mov_b32_e32 v159, v156
	v_pk_mul_f32 v[158:159], v[158:159], v[192:193] op_sel:[0,1]
	s_nop 0
	v_pk_fma_f32 v[102:103], v[156:157], v[192:193], v[158:159] op_sel_hi:[1,0,1]
	v_xor_b32_e32 v156, 0x80000000, v155
	v_mov_b32_e32 v157, v154
	v_pk_mul_f32 v[156:157], v[156:157], v[190:191] op_sel:[0,1]
	s_nop 0
	v_pk_fma_f32 v[100:101], v[154:155], v[190:191], v[156:157] op_sel_hi:[1,0,1]
	v_xor_b32_e32 v154, 0x80000000, v153
	v_mov_b32_e32 v155, v152
	v_pk_mul_f32 v[154:155], v[154:155], v[188:189] op_sel:[0,1]
	s_nop 0
	v_pk_fma_f32 v[98:99], v[152:153], v[188:189], v[154:155] op_sel_hi:[1,0,1]
	v_xor_b32_e32 v152, 0x80000000, v151
	v_mov_b32_e32 v153, v150
	v_pk_mul_f32 v[152:153], v[152:153], v[186:187] op_sel:[0,1]
	v_pk_add_f32 v[106:107], v[172:173], v[98:99]
	v_pk_fma_f32 v[96:97], v[150:151], v[186:187], v[152:153] op_sel_hi:[1,0,1]
	v_xor_b32_e32 v150, 0x80000000, v149
	v_mov_b32_e32 v151, v148
	v_pk_mul_f32 v[150:151], v[150:151], v[184:185] op_sel:[0,1]
	v_pk_add_f32 v[108:109], v[172:173], v[98:99] neg_lo:[0,1] neg_hi:[0,1]
	v_pk_fma_f32 v[94:95], v[148:149], v[184:185], v[150:151] op_sel_hi:[1,0,1]
	v_xor_b32_e32 v148, 0x80000000, v147
	v_mov_b32_e32 v149, v146
	v_pk_mul_f32 v[148:149], v[148:149], v[182:183] op_sel:[0,1]
	s_nop 0
	v_pk_fma_f32 v[92:93], v[146:147], v[182:183], v[148:149] op_sel_hi:[1,0,1]
	v_xor_b32_e32 v146, 0x80000000, v145
	v_mov_b32_e32 v147, v144
	v_pk_mul_f32 v[146:147], v[146:147], v[180:181] op_sel:[0,1]
	s_nop 0
	v_pk_fma_f32 v[90:91], v[144:145], v[180:181], v[146:147] op_sel_hi:[1,0,1]
	v_xor_b32_e32 v144, 0x80000000, v143
	v_mov_b32_e32 v145, v142
	v_pk_mul_f32 v[144:145], v[144:145], v[178:179] op_sel:[0,1]
	v_pk_add_f32 v[70:71], v[90:91], v[110:111]
	v_pk_fma_f32 v[88:89], v[142:143], v[178:179], v[144:145] op_sel_hi:[1,0,1]
	v_xor_b32_e32 v142, 0x80000000, v141
	v_mov_b32_e32 v143, v140
	v_pk_mul_f32 v[142:143], v[142:143], v[176:177] op_sel:[0,1]
	v_pk_add_f32 v[98:99], v[106:107], v[70:71]
	v_pk_fma_f32 v[86:87], v[140:141], v[176:177], v[142:143] op_sel_hi:[1,0,1]
	v_pk_add_f32 v[106:107], v[106:107], v[70:71] neg_lo:[0,1] neg_hi:[0,1]
	v_pk_add_f32 v[70:71], v[84:85], v[100:101]
	v_pk_add_f32 v[140:141], v[84:85], v[100:101] neg_lo:[0,1] neg_hi:[0,1]
	v_pk_add_f32 v[84:85], v[92:93], v[112:113]
	v_pk_add_f32 v[92:93], v[92:93], v[112:113] neg_lo:[0,1] neg_hi:[0,1]
	v_pk_add_f32 v[100:101], v[70:71], v[84:85]
	v_pk_add_f32 v[112:113], v[70:71], v[84:85] neg_lo:[0,1] neg_hi:[0,1]
	v_pk_add_f32 v[70:71], v[86:87], v[102:103]
	v_pk_add_f32 v[84:85], v[94:95], v[136:137]
	v_pk_add_f32 v[144:145], v[86:87], v[102:103] neg_lo:[0,1] neg_hi:[0,1]
	v_pk_add_f32 v[86:87], v[94:95], v[136:137] neg_lo:[0,1] neg_hi:[0,1]
	v_pk_add_f32 v[94:95], v[70:71], v[84:85]
	v_pk_add_f32 v[102:103], v[70:71], v[84:85] neg_lo:[0,1] neg_hi:[0,1]
	v_pk_add_f32 v[70:71], v[88:89], v[104:105]
	v_pk_add_f32 v[84:85], v[96:97], v[138:139]
	v_xor_b32_e32 v137, 0x80000000, v86
	v_mov_b32_e32 v136, v87
	v_pk_add_f32 v[148:149], v[88:89], v[104:105] neg_lo:[0,1] neg_hi:[0,1]
	v_pk_add_f32 v[86:87], v[96:97], v[138:139] neg_lo:[0,1] neg_hi:[0,1]
	v_pk_add_f32 v[88:89], v[70:71], v[84:85]
	v_xor_b32_e32 v143, 0x80000000, v92
	v_mov_b32_e32 v142, v93
	v_pk_add_f32 v[104:105], v[70:71], v[84:85] neg_lo:[0,1] neg_hi:[0,1]
	v_xor_b32_e32 v139, 0x80000000, v86
	v_mov_b32_e32 v138, v87
	v_pk_add_f32 v[70:71], v[98:99], v[94:95]
	v_pk_add_f32 v[84:85], v[100:101], v[88:89]
	v_pk_add_f32 v[86:87], v[100:101], v[88:89] neg_lo:[0,1] neg_hi:[0,1]
	v_pk_add_f32 v[92:93], v[140:141], v[142:143]
	v_pk_add_f32 v[94:95], v[98:99], v[94:95] neg_lo:[0,1] neg_hi:[0,1]
	v_pk_add_f32 v[88:89], v[70:71], v[84:85]
	v_pk_add_f32 v[84:85], v[70:71], v[84:85] neg_lo:[0,1] neg_hi:[0,1]
	v_xor_b32_e32 v71, 0x80000000, v86
	v_mov_b32_e32 v70, v87
	v_pk_add_f32 v[90:91], v[90:91], v[110:111] neg_lo:[0,1] neg_hi:[0,1]
	v_pk_add_f32 v[146:147], v[144:145], v[136:137]
	v_pk_add_f32 v[96:97], v[148:149], v[138:139]
	v_pk_add_f32 v[86:87], v[94:95], v[70:71]
	v_pk_add_f32 v[70:71], v[94:95], v[70:71] neg_lo:[0,1] neg_hi:[0,1]
	v_pk_mul_f32 v[94:95], v[92:93], s[28:29] op_sel:[1,0]
	v_xor_b32_e32 v111, 0x80000000, v90
	v_mov_b32_e32 v110, v91
	v_pk_fma_f32 v[92:93], v[92:93], s[26:27], v[94:95] op_sel_hi:[0,1,1]
	v_mul_f32_e32 v94, 0x3f3504f3, v147
	s_mov_b32 s29, s34
	v_pk_mul_f32 v[98:99], v[96:97], s[8:9] op_sel:[1,0]
	v_pk_add_f32 v[90:91], v[108:109], v[110:111]
	v_pk_fma_f32 v[94:95], v[146:147], s[30:31], v[94:95] op_sel_hi:[0,1,0]
	v_pk_fma_f32 v[96:97], v[96:97], s[28:29], v[98:99] op_sel_hi:[0,1,1]
	v_pk_add_f32 v[98:99], v[90:91], v[94:95]
	v_pk_add_f32 v[90:91], v[90:91], v[94:95] neg_lo:[0,1] neg_hi:[0,1]
	v_pk_add_f32 v[94:95], v[92:93], v[96:97]
	v_pk_add_f32 v[100:101], v[92:93], v[96:97] neg_lo:[0,1] neg_hi:[0,1]
	v_pk_add_f32 v[96:97], v[98:99], v[94:95]
	v_pk_add_f32 v[92:93], v[98:99], v[94:95] neg_lo:[0,1] neg_hi:[0,1]
	v_xor_b32_e32 v99, 0x80000000, v100
	v_mov_b32_e32 v98, v101
	v_pk_mul_f32 v[100:101], v[102:103], s[36:37] op_sel:[1,0]
	v_pk_add_f32 v[94:95], v[90:91], v[98:99]
	v_pk_add_f32 v[90:91], v[90:91], v[98:99] neg_lo:[0,1] neg_hi:[0,1]
	v_mul_f32_e32 v98, 0x3f3504f3, v113
	v_pk_fma_f32 v[100:101], v[102:103], s[20:21], v[100:101] op_sel_hi:[0,1,1]
	v_mul_f32_e32 v102, 0xbf3504f3, v104
	v_pk_fma_f32 v[98:99], v[112:113], s[30:31], v[98:99] op_sel_hi:[0,1,0]
	v_pk_fma_f32 v[102:103], v[104:105], s[30:31], v[102:103] op_sel:[1,0,0] op_sel_hi:[1,1,0]
	v_pk_add_f32 v[112:113], v[106:107], v[100:101]
	v_pk_add_f32 v[106:107], v[106:107], v[100:101] neg_lo:[0,1] neg_hi:[0,1]
	v_pk_add_f32 v[100:101], v[98:99], v[102:103]
	v_pk_add_f32 v[98:99], v[98:99], v[102:103] neg_lo:[0,1] neg_hi:[0,1]
	v_pk_add_f32 v[104:105], v[112:113], v[100:101]
	v_pk_add_f32 v[100:101], v[112:113], v[100:101] neg_lo:[0,1] neg_hi:[0,1]
	v_xor_b32_e32 v113, 0x80000000, v98
	v_mov_b32_e32 v112, v99
	v_pk_add_f32 v[102:103], v[106:107], v[112:113]
	v_pk_add_f32 v[98:99], v[106:107], v[112:113] neg_lo:[0,1] neg_hi:[0,1]
	v_pk_add_f32 v[106:107], v[148:149], v[138:139] neg_lo:[0,1] neg_hi:[0,1]
	v_pk_add_f32 v[108:109], v[108:109], v[110:111] neg_lo:[0,1] neg_hi:[0,1]
	v_pk_mul_f32 v[112:113], v[106:107], s[10:11] op_sel:[1,0]
	v_pk_add_f32 v[110:111], v[140:141], v[142:143] neg_lo:[0,1] neg_hi:[0,1]
	v_pk_fma_f32 v[106:107], v[106:107], s[34:35], v[112:113] op_sel_hi:[0,1,1]
	v_pk_mul_f32 v[112:113], v[110:111], s[8:9] op_sel:[1,0]
	s_nop 0
	v_pk_fma_f32 v[110:111], v[110:111], s[28:29], v[112:113] op_sel_hi:[0,1,1]
	v_pk_add_f32 v[112:113], v[144:145], v[136:137] neg_lo:[0,1] neg_hi:[0,1]
	v_pk_add_f32 v[138:139], v[110:111], v[106:107] neg_lo:[0,1] neg_hi:[0,1]
	v_mul_f32_e32 v134, 0xbf3504f3, v112
	v_pk_fma_f32 v[112:113], v[112:113], s[30:31], v[134:135] op_sel:[1,0,0] op_sel_hi:[1,1,0]
	s_nop 0
	v_pk_add_f32 v[136:137], v[108:109], v[112:113]
	v_pk_add_f32 v[112:113], v[108:109], v[112:113] neg_lo:[0,1] neg_hi:[0,1]
	v_pk_add_f32 v[108:109], v[110:111], v[106:107]
	s_nop 0
	v_pk_add_f32 v[110:111], v[136:137], v[108:109]
	v_pk_add_f32 v[106:107], v[136:137], v[108:109] neg_lo:[0,1] neg_hi:[0,1]
	v_xor_b32_e32 v137, 0x80000000, v138
	v_mov_b32_e32 v136, v139
	v_pk_add_f32 v[108:109], v[112:113], v[136:137]
	v_pk_add_f32 v[112:113], v[112:113], v[136:137] neg_lo:[0,1] neg_hi:[0,1]

.LBB0_1660:
	s_or_b64 exec, exec, s[6:7]
	s_waitcnt lgkmcnt(0)
	s_barrier
	s_and_saveexec_b64 s[6:7], vcc
	s_cbranch_execz .LBB0_1662
	ds_read_b64 v[172:173], v132 offset:32768
	v_cvt_f32_i32_e32 v84, v126
	v_lshlrev_b32_e32 v85, 3, v125
	v_add3_u32 v90, 0, v85, v133
	ds_read_b64 v[174:175], v90
	v_mul_f32_e32 v86, 0x39000000, v84
	v_sin_f32_e32 v84, v86
	v_cos_f32_e32 v86, v86
	v_cvt_f32_i32_e32 v65, v65
	v_xor_b32_e32 v87, 0x80000000, v84
	v_mov_b32_e32 v85, v86
	s_waitcnt lgkmcnt(2)
	s_waitcnt lgkmcnt(1)
	v_pk_mul_f32 v[84:85], v[84:85], v[172:173] op_sel:[0,1]
	v_cvt_f32_i32_e32 v59, v59
	v_pk_fma_f32 v[70:71], v[86:87], v[172:173], v[84:85] op_sel_hi:[1,0,1]
	v_cvt_f32_i32_e32 v86, v124
	s_waitcnt lgkmcnt(0)
	v_pk_add_f32 v[84:85], v[174:175], v[70:71]
	v_pk_add_f32 v[70:71], v[174:175], v[70:71] neg_lo:[0,1] neg_hi:[0,1]
	ds_write_b64 v90, v[84:85]
	ds_write_b64 v132, v[70:71] offset:32768
	ds_read_b64 v[172:173], v131 offset:36864
	ds_read_b64 v[174:175], v122 offset:4096
	v_mul_f32_e32 v71, 0x39000000, v86
	v_cos_f32_e32 v70, v71
	v_sin_f32_e32 v84, v71
	v_cvt_f32_i32_e32 v27, v27
	v_mov_b32_e32 v85, v70
	v_xor_b32_e32 v71, 0x80000000, v84
	s_waitcnt lgkmcnt(1)
	v_pk_mul_f32 v[84:85], v[84:85], v[172:173] op_sel:[0,1]
	v_cvt_f32_i32_e32 v19, v19
	v_pk_fma_f32 v[70:71], v[70:71], v[172:173], v[84:85] op_sel_hi:[1,0,1]
	v_cvt_f32_i32_e32 v86, v123
	s_waitcnt lgkmcnt(0)
	v_pk_add_f32 v[84:85], v[174:175], v[70:71]
	v_pk_add_f32 v[70:71], v[174:175], v[70:71] neg_lo:[0,1] neg_hi:[0,1]
	ds_write_b64 v122, v[84:85] offset:4096
	ds_write_b64 v131, v[70:71] offset:36864
	ds_read_b64 v[172:173], v130 offset:40960
	ds_read_b64 v[174:175], v116 offset:8192
	v_mul_f32_e32 v71, 0x39000000, v86
	v_cos_f32_e32 v70, v71
	v_sin_f32_e32 v84, v71
	s_nop 0
	v_mov_b32_e32 v85, v70
	v_xor_b32_e32 v71, 0x80000000, v84
	s_waitcnt lgkmcnt(1)
	v_pk_mul_f32 v[84:85], v[84:85], v[172:173] op_sel:[0,1]
	s_nop 0
	v_pk_fma_f32 v[70:71], v[70:71], v[172:173], v[84:85] op_sel_hi:[1,0,1]
	v_cvt_f32_i32_e32 v86, v117
	s_waitcnt lgkmcnt(0)
	v_pk_add_f32 v[84:85], v[174:175], v[70:71]
	v_pk_add_f32 v[70:71], v[174:175], v[70:71] neg_lo:[0,1] neg_hi:[0,1]
	ds_write_b64 v116, v[84:85] offset:8192
	ds_write_b64 v130, v[70:71] offset:40960
	ds_read_b64 v[172:173], v129 offset:45056
	ds_read_b64 v[174:175], v63 offset:12288
	v_mul_f32_e32 v71, 0x39000000, v86
	v_cos_f32_e32 v70, v71
	v_sin_f32_e32 v84, v71
	s_nop 0
	v_mov_b32_e32 v85, v70
	v_xor_b32_e32 v71, 0x80000000, v84
	s_waitcnt lgkmcnt(1)
	v_pk_mul_f32 v[84:85], v[84:85], v[172:173] op_sel:[0,1]
	s_nop 0
	v_pk_fma_f32 v[70:71], v[70:71], v[172:173], v[84:85] op_sel_hi:[1,0,1]
	s_waitcnt lgkmcnt(0)
	v_pk_add_f32 v[84:85], v[174:175], v[70:71]
	ds_write_b64 v63, v[84:85] offset:12288
	v_pk_add_f32 v[70:71], v[174:175], v[70:71] neg_lo:[0,1] neg_hi:[0,1]
	v_mul_f32_e32 v63, 0x39000000, v65
	ds_write_b64 v129, v[70:71] offset:45056
	ds_read_b64 v[172:173], v128 offset:49152
	ds_read_b64 v[174:175], v31 offset:16384
	v_cos_f32_e32 v70, v63
	v_sin_f32_e32 v84, v63
	s_nop 0
	v_mov_b32_e32 v85, v70
	v_xor_b32_e32 v71, 0x80000000, v84
	s_waitcnt lgkmcnt(1)
	v_pk_mul_f32 v[84:85], v[84:85], v[172:173] op_sel:[0,1]
	s_nop 0
	v_pk_fma_f32 v[70:71], v[70:71], v[172:173], v[84:85] op_sel_hi:[1,0,1]
	s_waitcnt lgkmcnt(0)
	v_pk_add_f32 v[84:85], v[174:175], v[70:71]
	ds_write_b64 v31, v[84:85] offset:16384
	v_pk_add_f32 v[70:71], v[174:175], v[70:71] neg_lo:[0,1] neg_hi:[0,1]
	v_mul_f32_e32 v31, 0x39000000, v59
	ds_write_b64 v128, v[70:71] offset:49152
	ds_read_b64 v[172:173], v127 offset:53248
	ds_read_b64 v[174:175], v23 offset:20480
	v_cos_f32_e32 v70, v31
	v_sin_f32_e32 v84, v31
	s_nop 0
	v_mov_b32_e32 v85, v70
	v_xor_b32_e32 v71, 0x80000000, v84
	s_waitcnt lgkmcnt(1)
	v_pk_mul_f32 v[84:85], v[84:85], v[172:173] op_sel:[0,1]
	s_nop 0
	v_pk_fma_f32 v[70:71], v[70:71], v[172:173], v[84:85] op_sel_hi:[1,0,1]
	s_waitcnt lgkmcnt(0)
	v_pk_add_f32 v[84:85], v[174:175], v[70:71]
	ds_write_b64 v23, v[84:85] offset:20480
	v_pk_add_f32 v[70:71], v[174:175], v[70:71] neg_lo:[0,1] neg_hi:[0,1]
	v_mul_f32_e32 v23, 0x39000000, v27
	ds_write_b64 v127, v[70:71] offset:53248
	ds_read_b64 v[172:173], v115 offset:57344
	ds_read_b64 v[174:175], v15 offset:24576
	v_cos_f32_e32 v70, v23
	v_sin_f32_e32 v84, v23
	s_nop 0
	v_mov_b32_e32 v85, v70
	v_xor_b32_e32 v71, 0x80000000, v84
	s_waitcnt lgkmcnt(1)
	v_pk_mul_f32 v[84:85], v[84:85], v[172:173] op_sel:[0,1]
	s_nop 0
	v_pk_fma_f32 v[70:71], v[70:71], v[172:173], v[84:85] op_sel_hi:[1,0,1]
	s_waitcnt lgkmcnt(0)
	v_pk_add_f32 v[84:85], v[174:175], v[70:71]
	ds_write_b64 v15, v[84:85] offset:24576
	v_pk_add_f32 v[70:71], v[174:175], v[70:71] neg_lo:[0,1] neg_hi:[0,1]
	v_mul_f32_e32 v15, 0x39000000, v19
	ds_write_b64 v115, v[70:71] offset:57344
	ds_read_b64 v[86:87], v114 offset:61440
	ds_read_b64 v[88:89], v11 offset:28672
	v_cos_f32_e32 v70, v15
	v_sin_f32_e32 v84, v15
	s_nop 0
	v_mov_b32_e32 v85, v70
	v_xor_b32_e32 v71, 0x80000000, v84
	s_waitcnt lgkmcnt(1)
	v_pk_mul_f32 v[84:85], v[84:85], v[86:87] op_sel:[0,1]
	s_nop 0
	v_pk_fma_f32 v[70:71], v[70:71], v[86:87], v[84:85] op_sel_hi:[1,0,1]
	s_waitcnt lgkmcnt(0)
	v_pk_add_f32 v[84:85], v[88:89], v[70:71]
	v_pk_add_f32 v[70:71], v[88:89], v[70:71] neg_lo:[0,1] neg_hi:[0,1]
	ds_write_b64 v11, v[84:85] offset:28672
	ds_write_b64 v114, v[70:71] offset:61440

.LBB0_1664:
	v_ashrrev_i32_e32 v15, 4, v11
	v_add_lshl_u32 v15, v11, v15, 3
	v_add_u32_e32 v19, s3, v15
	ds_read_b64 v[172:173], v19
	v_and_b32_e32 v19, 0x1fff, v7
	v_lshrrev_b32_e32 v23, 1, v7
	v_and_b32_e32 v23, 0xff8, v23
	v_lshlrev_b32_e32 v19, 3, v19
	v_add3_u32 v19, s3, v23, v19
	ds_read_b64 v[174:175], v19
	v_add_u32_e32 v15, 0, v15
	ds_read_b64 v[86:87], v15
	v_cmp_lt_i32_e32 vcc, s22, v11
	v_add_u32_e32 v7, 0xfffffe00, v7
	s_or_b64 s[8:9], vcc, s[8:9]
	s_waitcnt lgkmcnt(3)
	s_waitcnt lgkmcnt(1)
	v_pk_add_f32 v[88:89], v[172:173], v[174:175]
	v_pk_add_f32 v[84:85], v[172:173], v[174:175] neg_lo:[0,1] neg_hi:[0,1]
	s_nop 0
	v_pk_mov_b32 v[84:85], v[88:89], v[84:85] op_sel:[1,0]
	s_nop 0
	v_pk_mul_f32 v[84:85], v[84:85], s[38:39]
	s_nop 0
	v_pk_mul_f32 v[84:85], v[70:71], v[84:85]
	s_nop 0
	v_xor_b32_e32 v88, 0x80000000, v85
	v_mov_b32_e32 v89, v84
	s_waitcnt lgkmcnt(0)
	v_pk_mul_f32 v[88:89], v[86:87], v[88:89] op_sel:[1,0]
	s_nop 0
	v_pk_fma_f32 v[84:85], v[86:87], v[84:85], v[88:89] op_sel_hi:[0,1,1]
	ds_write_b64 v15, v[84:85]
	v_add_u32_e32 v15, 0x200, v11
	v_mov_b32_e32 v11, v15
	s_andn2_b64 exec, exec, s[8:9]
	s_cbranch_execnz .LBB0_1664
.LBB0_1665:
	s_or_b64 exec, exec, s[6:7]
	v_mov_b32_e32 v130, v64
	s_waitcnt lgkmcnt(0)
	s_barrier
	v_mov_b32_e32 v114, 0
	v_add_u32_e32 v27, 0x1000, v130
	v_lshl_add_u32 v135, v130, 3, 0
	v_ashrrev_i32_e32 v27, 4, v27
	v_lshl_add_u32 v133, v27, 3, v135
	v_add_u32_e32 v27, 0x1200, v130
	v_ashrrev_i32_e32 v27, 4, v27
	v_lshl_add_u32 v132, v27, 3, v135
	v_add_u32_e32 v27, 0x1400, v130
	v_ashrrev_i32_e32 v27, 4, v27
	v_lshl_add_u32 v129, v27, 3, v135
	v_add_u32_e32 v27, 0x1600, v130
	v_ashrrev_i32_e32 v27, 4, v27
	v_add_u32_e32 v128, 0x200, v130
	v_lshl_add_u32 v127, v27, 3, v135
	v_add_u32_e32 v27, 0x1800, v130
	v_ashrrev_i32_e32 v7, 4, v128
	v_add_u32_e32 v126, 0x400, v130
	v_ashrrev_i32_e32 v27, 4, v27
	v_lshl_add_u32 v125, v7, 3, v135
	v_ashrrev_i32_e32 v7, 4, v126
	v_add_u32_e32 v123, 0x600, v130
	v_lshl_add_u32 v124, v27, 3, v135
	v_add_u32_e32 v27, 0x1a00, v130
	v_lshl_add_u32 v122, v7, 3, v135
	v_ashrrev_i32_e32 v7, 4, v123
	v_add_u32_e32 v116, 0x800, v130
	v_ashrrev_i32_e32 v27, 4, v27
	v_lshl_add_u32 v65, v7, 3, v135
	v_ashrrev_i32_e32 v7, 4, v116
	v_add_u32_e32 v59, 0xa00, v130
	v_lshl_add_u32 v117, v27, 3, v135
	v_add_u32_e32 v27, 0x1c00, v130
	v_lshl_add_u32 v31, v7, 3, v135
	v_ashrrev_i32_e32 v7, 4, v59
	v_add_u32_e32 v23, 0xc00, v130
	v_ashrrev_i32_e32 v27, 4, v27
	v_lshl_add_u32 v19, v7, 3, v135
	v_ashrrev_i32_e32 v7, 4, v23
	v_add_u32_e32 v15, 0xe00, v130
	v_lshl_add_u32 v63, v27, 3, v135
	v_add_u32_e32 v27, 0x1e00, v130
	v_ashrrev_i32_e32 v131, 4, v130
	v_lshl_add_u32 v11, v7, 3, v135
	v_ashrrev_i32_e32 v7, 4, v15
	v_ashrrev_i32_e32 v27, 4, v27
	v_cmp_gt_i32_e32 vcc, s70, v130
	v_lshl_add_u32 v134, v131, 3, v135
	v_lshl_add_u32 v7, v7, 3, v135
	v_lshl_add_u32 v27, v27, 3, v135
	v_mov_b32_e32 v115, 0
	v_mov_b32_e32 v86, 0
	v_mov_b32_e32 v87, v114
	v_mov_b32_e32 v94, v114
	v_mov_b32_e32 v95, v114
	v_mov_b32_e32 v102, v114
	v_mov_b32_e32 v103, v114
	v_mov_b32_e32 v108, v114
	v_mov_b32_e32 v109, v114
	v_mov_b32_e32 v88, v114
	v_mov_b32_e32 v89, v114
	v_mov_b32_e32 v96, v114
	v_mov_b32_e32 v97, v114
	v_mov_b32_e32 v104, v114
	v_mov_b32_e32 v105, v114
	v_mov_b32_e32 v110, v114
	v_mov_b32_e32 v111, v114
	v_mov_b32_e32 v84, v114
	v_mov_b32_e32 v85, v114
	v_mov_b32_e32 v92, v114
	v_mov_b32_e32 v93, v114
	v_mov_b32_e32 v100, v114
	v_mov_b32_e32 v101, v114
	v_mov_b32_e32 v106, v114
	v_mov_b32_e32 v107, v114
	v_mov_b32_e32 v70, v114
	v_mov_b32_e32 v71, v114
	v_mov_b32_e32 v90, v114
	v_mov_b32_e32 v91, v114
	v_mov_b32_e32 v98, v114
	v_mov_b32_e32 v99, v114
	v_mov_b32_e32 v112, v114
	v_mov_b32_e32 v113, v114
	s_and_saveexec_b64 s[6:7], vcc
	s_cbranch_execz .LBB0_1667
	ds_read_b64 v[172:173], v134
	ds_read_b64 v[174:175], v125 offset:4096
	ds_read_b64 v[176:177], v122 offset:8192
	ds_read_b64 v[178:179], v65 offset:12288
	ds_read_b64 v[180:181], v31 offset:16384
	ds_read_b64 v[182:183], v19 offset:20480
	ds_read_b64 v[184:185], v11 offset:24576
	ds_read_b64 v[186:187], v7 offset:28672
	ds_read_b64 v[188:189], v133 offset:32768
	ds_read_b64 v[190:191], v132 offset:36864
	ds_read_b64 v[192:193], v129 offset:40960
	ds_read_b64 v[194:195], v127 offset:45056
	ds_read_b64 v[196:197], v124 offset:49152
	ds_read_b64 v[198:199], v117 offset:53248
	ds_read_b64 v[200:201], v63 offset:57344
	s_waitcnt lgkmcnt(14)
	ds_read_b64 v[202:203], v27 offset:61440
	s_waitcnt lgkmcnt(15)
	s_waitcnt lgkmcnt(7)
	v_pk_add_f32 v[114:115], v[172:173], v[188:189]
	v_pk_add_f32 v[136:137], v[172:173], v[188:189] neg_lo:[0,1] neg_hi:[0,1]
	s_waitcnt lgkmcnt(3)
	v_pk_add_f32 v[70:71], v[180:181], v[196:197]
	v_pk_add_f32 v[90:91], v[180:181], v[196:197] neg_lo:[0,1] neg_hi:[0,1]
	v_pk_add_f32 v[98:99], v[114:115], v[70:71]
	v_pk_add_f32 v[106:107], v[114:115], v[70:71] neg_lo:[0,1] neg_hi:[0,1]
	v_pk_add_f32 v[70:71], v[174:175], v[190:191]
	v_pk_add_f32 v[138:139], v[174:175], v[190:191] neg_lo:[0,1] neg_hi:[0,1]
	s_waitcnt lgkmcnt(2)
	v_pk_add_f32 v[84:85], v[182:183], v[198:199]
	v_pk_add_f32 v[92:93], v[182:183], v[198:199] neg_lo:[0,1] neg_hi:[0,1]
	v_pk_add_f32 v[100:101], v[70:71], v[84:85]
	v_pk_add_f32 v[108:109], v[70:71], v[84:85] neg_lo:[0,1] neg_hi:[0,1]
	v_pk_add_f32 v[70:71], v[176:177], v[192:193]
	s_waitcnt lgkmcnt(1)
	v_pk_add_f32 v[84:85], v[184:185], v[200:201]
	v_pk_add_f32 v[142:143], v[176:177], v[192:193] neg_lo:[0,1] neg_hi:[0,1]
	v_pk_add_f32 v[86:87], v[184:185], v[200:201] neg_lo:[0,1] neg_hi:[0,1]
	v_pk_add_f32 v[94:95], v[70:71], v[84:85]
	v_pk_add_f32 v[102:103], v[70:71], v[84:85] neg_lo:[0,1] neg_hi:[0,1]
	v_pk_add_f32 v[70:71], v[178:179], v[194:195]
	s_waitcnt lgkmcnt(0)
	v_pk_add_f32 v[84:85], v[186:187], v[202:203]
	v_pk_add_f32 v[146:147], v[178:179], v[194:195] neg_lo:[0,1] neg_hi:[0,1]
	v_pk_add_f32 v[88:89], v[70:71], v[84:85]
	v_xor_b32_e32 v141, 0x80000000, v92
	v_mov_b32_e32 v140, v93
	v_xor_b32_e32 v111, 0x80000000, v86
	v_mov_b32_e32 v110, v87
	v_pk_add_f32 v[86:87], v[186:187], v[202:203] neg_lo:[0,1] neg_hi:[0,1]
	v_pk_add_f32 v[104:105], v[70:71], v[84:85] neg_lo:[0,1] neg_hi:[0,1]
	v_pk_add_f32 v[84:85], v[100:101], v[88:89]
	v_pk_add_f32 v[88:89], v[100:101], v[88:89] neg_lo:[0,1] neg_hi:[0,1]
	v_pk_add_f32 v[92:93], v[138:139], v[140:141] neg_lo:[0,1] neg_hi:[0,1]
	v_xor_b32_e32 v113, 0x80000000, v86
	v_mov_b32_e32 v112, v87
	v_pk_add_f32 v[70:71], v[98:99], v[94:95]
	v_pk_add_f32 v[94:95], v[98:99], v[94:95] neg_lo:[0,1] neg_hi:[0,1]
	v_xor_b32_e32 v99, 0x80000000, v88
	v_mov_b32_e32 v98, v89
	s_mov_b32 s10, s27
	s_mov_b32 s11, s26
	v_pk_add_f32 v[144:145], v[142:143], v[110:111] neg_lo:[0,1] neg_hi:[0,1]
	v_pk_add_f32 v[96:97], v[146:147], v[112:113] neg_lo:[0,1] neg_hi:[0,1]
	v_pk_add_f32 v[86:87], v[70:71], v[84:85]
	v_pk_add_f32 v[84:85], v[70:71], v[84:85] neg_lo:[0,1] neg_hi:[0,1]
	v_pk_add_f32 v[70:71], v[94:95], v[98:99]
	v_pk_add_f32 v[88:89], v[94:95], v[98:99] neg_lo:[0,1] neg_hi:[0,1]
	s_mov_b32 s8, s26
	s_mov_b32 s9, s28
	v_pk_mul_f32 v[94:95], v[92:93], s[10:11] op_sel:[1,0]
	s_mov_b32 s35, s28
	v_xor_b32_e32 v115, 0x80000000, v90
	v_mov_b32_e32 v114, v91
	v_pk_fma_f32 v[92:93], v[92:93], s[8:9], v[94:95] op_sel_hi:[0,1,1]
	v_mul_f32_e32 v94, 0x3f3504f3, v144
	s_mov_b32 s8, s31
	s_mov_b32 s9, s30
	s_mov_b32 s29, s26
	v_pk_mul_f32 v[98:99], v[96:97], s[34:35] op_sel:[1,0]
	v_pk_add_f32 v[90:91], v[136:137], v[114:115] neg_lo:[0,1] neg_hi:[0,1]
	v_pk_fma_f32 v[94:95], v[144:145], s[8:9], v[94:95] op_sel:[1,0,0] op_sel_hi:[1,1,0]
	v_pk_fma_f32 v[96:97], v[96:97], s[28:29], v[98:99] op_sel_hi:[0,1,1]
	v_pk_add_f32 v[98:99], v[90:91], v[94:95]
	v_pk_add_f32 v[100:101], v[90:91], v[94:95] neg_lo:[0,1] neg_hi:[0,1]
	v_pk_add_f32 v[90:91], v[92:93], v[96:97]
	v_pk_add_f32 v[96:97], v[92:93], v[96:97] neg_lo:[0,1] neg_hi:[0,1]
	v_pk_add_f32 v[94:95], v[98:99], v[90:91]
	v_pk_add_f32 v[92:93], v[98:99], v[90:91] neg_lo:[0,1] neg_hi:[0,1]
	v_xor_b32_e32 v99, 0x80000000, v96
	v_mov_b32_e32 v98, v97
	s_mov_b32 s12, s21
	s_mov_b32 s13, s20
	v_pk_add_f32 v[90:91], v[100:101], v[98:99]
	v_pk_add_f32 v[96:97], v[100:101], v[98:99] neg_lo:[0,1] neg_hi:[0,1]
	s_mov_b32 s10, s20
	s_mov_b32 s11, s36
	v_pk_mul_f32 v[100:101], v[102:103], s[12:13] op_sel:[1,0]
	v_mul_f32_e32 v98, 0x3f3504f3, v108
	v_pk_fma_f32 v[100:101], v[102:103], s[10:11], v[100:101] op_sel_hi:[0,1,1]
	v_mul_f32_e32 v102, 0xbf3504f3, v105
	v_pk_fma_f32 v[98:99], v[108:109], s[8:9], v[98:99] op_sel:[1,0,0] op_sel_hi:[1,1,0]
	v_pk_fma_f32 v[102:103], v[104:105], s[8:9], v[102:103] op_sel_hi:[0,1,0]
	v_pk_add_f32 v[104:105], v[106:107], v[100:101]
	v_pk_add_f32 v[106:107], v[106:107], v[100:101] neg_lo:[0,1] neg_hi:[0,1]
	v_pk_add_f32 v[100:101], v[98:99], v[102:103]
	v_pk_add_f32 v[98:99], v[98:99], v[102:103] neg_lo:[0,1] neg_hi:[0,1]
	v_pk_add_f32 v[102:103], v[104:105], v[100:101]
	v_pk_add_f32 v[100:101], v[104:105], v[100:101] neg_lo:[0,1] neg_hi:[0,1]
	v_xor_b32_e32 v105, 0x80000000, v98
	v_mov_b32_e32 v104, v99
	v_pk_add_f32 v[98:99], v[106:107], v[104:105]
	v_pk_add_f32 v[104:105], v[106:107], v[104:105] neg_lo:[0,1] neg_hi:[0,1]
	v_pk_add_f32 v[106:107], v[146:147], v[112:113]
	s_mov_b32 s12, s28
	s_mov_b32 s13, s34
	s_mov_b32 s10, s34
	s_mov_b32 s11, s27
	v_pk_mul_f32 v[108:109], v[106:107], s[12:13] op_sel:[1,0]
	v_pk_add_f32 v[112:113], v[138:139], v[140:141]
	v_pk_fma_f32 v[106:107], v[106:107], s[10:11], v[108:109] op_sel_hi:[0,1,1]
	v_pk_add_f32 v[108:109], v[136:137], v[114:115]
	v_pk_mul_f32 v[114:115], v[112:113], s[34:35] op_sel:[1,0]
	v_pk_add_f32 v[110:111], v[142:143], v[110:111]
	v_pk_fma_f32 v[112:113], v[112:113], s[28:29], v[114:115] op_sel_hi:[0,1,1]
	v_mul_f32_e32 v114, 0xbf3504f3, v111
	v_pk_fma_f32 v[110:111], v[110:111], s[8:9], v[114:115] op_sel_hi:[0,1,0]
	v_pk_add_f32 v[114:115], v[108:109], v[110:111]
	v_pk_add_f32 v[136:137], v[112:113], v[106:107]
	v_pk_add_f32 v[112:113], v[112:113], v[106:107] neg_lo:[0,1] neg_hi:[0,1]
	v_pk_add_f32 v[110:111], v[108:109], v[110:111] neg_lo:[0,1] neg_hi:[0,1]
	v_pk_add_f32 v[108:109], v[114:115], v[136:137]
	v_pk_add_f32 v[106:107], v[114:115], v[136:137] neg_lo:[0,1] neg_hi:[0,1]
	v_xor_b32_e32 v137, 0x80000000, v112
	v_mov_b32_e32 v136, v113
	v_pk_add_f32 v[114:115], v[110:111], v[136:137]
	v_pk_add_f32 v[110:111], v[110:111], v[136:137] neg_lo:[0,1] neg_hi:[0,1]
	v_mov_b32_e32 v112, v114
	v_mov_b32_e32 v113, v115

.LBB0_1669:
	s_or_b64 exec, exec, s[6:7]
	s_waitcnt lgkmcnt(0)
	s_barrier
	s_and_saveexec_b64 s[6:7], vcc
	s_cbranch_execz .LBB0_1671
	ds_read_b64 v[172:173], v27 offset:61440
	ds_read_b64 v[174:175], v63 offset:57344
	ds_read_b64 v[176:177], v117 offset:53248
	ds_read_b64 v[178:179], v124 offset:49152
	ds_read_b64 v[180:181], v127 offset:45056
	ds_read_b64 v[182:183], v129 offset:40960
	ds_read_b64 v[184:185], v134
	ds_read_b64 v[186:187], v125 offset:4096
	ds_read_b64 v[188:189], v122 offset:8192
	ds_read_b64 v[190:191], v65 offset:12288
	ds_read_b64 v[192:193], v31 offset:16384
	ds_read_b64 v[194:195], v19 offset:20480
	ds_read_b64 v[196:197], v11 offset:24576
	ds_read_b64 v[198:199], v7 offset:28672
	ds_read_b64 v[200:201], v133 offset:32768
	v_and_b32_e32 v70, 15, v130
	v_cvt_f32_ubyte0_e32 v70, v70
	v_mul_f32_e32 v70, 0x3b800000, v70
	v_cos_f32_e32 v96, v70
	v_sin_f32_e32 v97, v70
	s_mov_b32 s10, s27
	v_mov_b32_e32 v99, v96
	v_xor_b32_e32 v98, 0x80000000, v97
	v_mov_b32_e32 v70, v97
	v_pk_mul_f32 v[70:71], v[98:99], v[70:71] op_sel_hi:[1,0]
	s_mov_b32 s11, s26
	v_pk_fma_f32 v[104:105], v[96:97], v[96:97], v[70:71] op_sel_hi:[1,0,1]
	s_mov_b32 s8, s26
	v_pk_mul_f32 v[70:71], v[98:99], v[104:105] op_sel:[0,1]
	s_mov_b32 s9, s28
	v_pk_fma_f32 v[108:109], v[96:97], v[104:105], v[70:71] op_sel_hi:[1,0,1]
	s_mov_b32 s35, s28
	v_pk_mul_f32 v[70:71], v[98:99], v[108:109] op_sel:[0,1]
	s_mov_b32 s29, s26
	v_pk_fma_f32 v[110:111], v[96:97], v[108:109], v[70:71] op_sel_hi:[1,0,1]
	s_mov_b32 s12, s21
	v_pk_mul_f32 v[70:71], v[98:99], v[110:111] op_sel:[0,1]
	s_mov_b32 s13, s20
	v_pk_fma_f32 v[112:113], v[96:97], v[110:111], v[70:71] op_sel_hi:[1,0,1]
	s_nop 0
	v_pk_mul_f32 v[70:71], v[98:99], v[112:113] op_sel:[0,1]
	s_nop 0
	v_pk_fma_f32 v[114:115], v[96:97], v[112:113], v[70:71] op_sel_hi:[1,0,1]
	s_nop 0
	v_pk_mul_f32 v[70:71], v[98:99], v[114:115] op_sel:[0,1]
	s_nop 0
	v_pk_fma_f32 v[136:137], v[96:97], v[114:115], v[70:71] op_sel_hi:[1,0,1]
	s_nop 0
	v_pk_mul_f32 v[70:71], v[98:99], v[136:137] op_sel:[0,1]
	s_nop 0
	v_pk_fma_f32 v[100:101], v[96:97], v[136:137], v[70:71] op_sel_hi:[1,0,1]
	s_nop 0
	v_pk_mul_f32 v[70:71], v[98:99], v[100:101] op_sel:[0,1]
	s_nop 0
	v_pk_fma_f32 v[84:85], v[96:97], v[100:101], v[70:71] op_sel_hi:[1,0,1]
	s_nop 0
	v_pk_mul_f32 v[70:71], v[98:99], v[84:85] op_sel:[0,1]
	s_nop 0
	v_pk_fma_f32 v[94:95], v[96:97], v[84:85], v[70:71] op_sel_hi:[1,0,1]
	s_nop 0
	v_pk_mul_f32 v[70:71], v[98:99], v[94:95] op_sel:[0,1]
	s_nop 0
	v_pk_fma_f32 v[90:91], v[96:97], v[94:95], v[70:71] op_sel_hi:[1,0,1]
	s_nop 0
	v_pk_mul_f32 v[70:71], v[98:99], v[90:91] op_sel:[0,1]
	s_nop 0
	v_pk_fma_f32 v[92:93], v[96:97], v[90:91], v[70:71] op_sel_hi:[1,0,1]
	s_nop 0
	v_pk_mul_f32 v[70:71], v[98:99], v[92:93] op_sel:[0,1]
	s_nop 0
	v_pk_fma_f32 v[88:89], v[96:97], v[92:93], v[70:71] op_sel_hi:[1,0,1]
	s_nop 0
	v_pk_mul_f32 v[70:71], v[98:99], v[88:89] op_sel:[0,1]
	s_nop 0
	v_pk_fma_f32 v[86:87], v[96:97], v[88:89], v[70:71] op_sel_hi:[1,0,1]
	s_nop 0
	v_pk_mul_f32 v[70:71], v[98:99], v[86:87] op_sel:[0,1]
	s_nop 0
	v_pk_fma_f32 v[70:71], v[96:97], v[86:87], v[70:71] op_sel_hi:[1,0,1]
	s_nop 0
	v_xor_b32_e32 v106, 0x80000000, v71
	v_mov_b32_e32 v107, v70
	s_waitcnt lgkmcnt(15)
	s_waitcnt lgkmcnt(14)
	v_pk_mul_f32 v[106:107], v[106:107], v[172:173] op_sel:[0,1]
	s_nop 0
	v_pk_fma_f32 v[70:71], v[70:71], v[172:173], v[106:107] op_sel_hi:[1,0,1]
	ds_read_b64 v[172:173], v132 offset:36864
	v_xor_b32_e32 v106, 0x80000000, v87
	v_mov_b32_e32 v107, v86
	s_waitcnt lgkmcnt(14)
	v_pk_mul_f32 v[106:107], v[106:107], v[174:175] op_sel:[0,1]
	s_nop 0
	v_pk_fma_f32 v[86:87], v[86:87], v[174:175], v[106:107] op_sel_hi:[1,0,1]
	v_xor_b32_e32 v106, 0x80000000, v89
	v_mov_b32_e32 v107, v88
	s_waitcnt lgkmcnt(13)
	v_pk_mul_f32 v[106:107], v[106:107], v[176:177] op_sel:[0,1]
	s_nop 0
	v_pk_fma_f32 v[88:89], v[88:89], v[176:177], v[106:107] op_sel_hi:[1,0,1]
	v_xor_b32_e32 v106, 0x80000000, v93
	v_mov_b32_e32 v107, v92
	s_waitcnt lgkmcnt(12)
	v_pk_mul_f32 v[106:107], v[106:107], v[178:179] op_sel:[0,1]
	s_nop 0
	v_pk_fma_f32 v[92:93], v[92:93], v[178:179], v[106:107] op_sel_hi:[1,0,1]
	v_xor_b32_e32 v106, 0x80000000, v91
	v_mov_b32_e32 v107, v90
	s_waitcnt lgkmcnt(11)
	v_pk_mul_f32 v[106:107], v[106:107], v[180:181] op_sel:[0,1]
	s_nop 0
	v_pk_fma_f32 v[90:91], v[90:91], v[180:181], v[106:107] op_sel_hi:[1,0,1]
	v_xor_b32_e32 v106, 0x80000000, v95
	v_mov_b32_e32 v107, v94
	s_waitcnt lgkmcnt(10)
	v_pk_mul_f32 v[106:107], v[106:107], v[182:183] op_sel:[0,1]
	s_nop 0
	v_pk_fma_f32 v[94:95], v[94:95], v[182:183], v[106:107] op_sel_hi:[1,0,1]
	s_waitcnt lgkmcnt(8)
	v_pk_mul_f32 v[98:99], v[98:99], v[186:187] op_sel:[0,1]
	s_nop 0
	v_pk_fma_f32 v[102:103], v[96:97], v[186:187], v[98:99] op_sel_hi:[1,0,1]
	v_xor_b32_e32 v98, 0x80000000, v105
	v_mov_b32_e32 v99, v104
	s_waitcnt lgkmcnt(7)
	v_pk_mul_f32 v[98:99], v[98:99], v[188:189] op_sel:[0,1]
	s_nop 0
	v_pk_fma_f32 v[98:99], v[104:105], v[188:189], v[98:99] op_sel_hi:[1,0,1]
	v_xor_b32_e32 v104, 0x80000000, v109
	v_mov_b32_e32 v105, v108
	v_pk_add_f32 v[142:143], v[98:99], v[94:95] neg_lo:[0,1] neg_hi:[0,1]
	s_waitcnt lgkmcnt(6)
	v_pk_mul_f32 v[104:105], v[104:105], v[190:191] op_sel:[0,1]
	s_nop 0
	v_pk_fma_f32 v[96:97], v[108:109], v[190:191], v[104:105] op_sel_hi:[1,0,1]
	v_xor_b32_e32 v108, 0x80000000, v111
	v_mov_b32_e32 v109, v110
	v_pk_add_f32 v[146:147], v[96:97], v[90:91] neg_lo:[0,1] neg_hi:[0,1]
	s_waitcnt lgkmcnt(5)
	v_pk_mul_f32 v[108:109], v[108:109], v[192:193] op_sel:[0,1]
	s_nop 0
	v_pk_fma_f32 v[108:109], v[110:111], v[192:193], v[108:109] op_sel_hi:[1,0,1]
	v_xor_b32_e32 v110, 0x80000000, v113
	v_mov_b32_e32 v111, v112
	s_waitcnt lgkmcnt(4)
	v_pk_mul_f32 v[110:111], v[110:111], v[194:195] op_sel:[0,1]
	s_nop 0
	v_pk_fma_f32 v[110:111], v[112:113], v[194:195], v[110:111] op_sel_hi:[1,0,1]
	v_xor_b32_e32 v112, 0x80000000, v115
	v_mov_b32_e32 v113, v114
	s_waitcnt lgkmcnt(3)
	v_pk_mul_f32 v[112:113], v[112:113], v[196:197] op_sel:[0,1]
	s_nop 0
	v_pk_fma_f32 v[112:113], v[114:115], v[196:197], v[112:113] op_sel_hi:[1,0,1]
	v_xor_b32_e32 v114, 0x80000000, v137
	v_mov_b32_e32 v115, v136
	s_waitcnt lgkmcnt(2)
	v_pk_mul_f32 v[114:115], v[114:115], v[198:199] op_sel:[0,1]
	s_nop 0
	v_pk_fma_f32 v[104:105], v[136:137], v[198:199], v[114:115] op_sel_hi:[1,0,1]
	v_xor_b32_e32 v136, 0x80000000, v101
	v_mov_b32_e32 v137, v100
	s_waitcnt lgkmcnt(1)
	v_pk_mul_f32 v[136:137], v[136:137], v[200:201] op_sel:[0,1]
	s_nop 0
	v_pk_fma_f32 v[100:101], v[100:101], v[200:201], v[136:137] op_sel_hi:[1,0,1]
	v_xor_b32_e32 v136, 0x80000000, v85
	v_mov_b32_e32 v137, v84
	s_waitcnt lgkmcnt(0)
	v_pk_mul_f32 v[136:137], v[136:137], v[172:173] op_sel:[0,1]
	s_nop 0
	v_pk_fma_f32 v[84:85], v[84:85], v[172:173], v[136:137] op_sel_hi:[1,0,1]
	v_pk_add_f32 v[114:115], v[184:185], v[100:101]
	v_pk_add_f32 v[136:137], v[102:103], v[84:85]
	v_pk_add_f32 v[138:139], v[102:103], v[84:85] neg_lo:[0,1] neg_hi:[0,1]
	v_pk_add_f32 v[84:85], v[88:89], v[110:111]
	v_pk_add_f32 v[88:89], v[110:111], v[88:89] neg_lo:[0,1] neg_hi:[0,1]
	v_pk_add_f32 v[102:103], v[84:85], v[136:137]
	v_pk_add_f32 v[110:111], v[136:137], v[84:85] neg_lo:[0,1] neg_hi:[0,1]
	v_xor_b32_e32 v137, 0x80000000, v88
	v_mov_b32_e32 v136, v89
	v_pk_add_f32 v[84:85], v[94:95], v[98:99]
	v_pk_add_f32 v[88:89], v[86:87], v[112:113]
	v_pk_add_f32 v[86:87], v[112:113], v[86:87] neg_lo:[0,1] neg_hi:[0,1]
	v_pk_add_f32 v[94:95], v[84:85], v[88:89]
	v_pk_add_f32 v[98:99], v[84:85], v[88:89] neg_lo:[0,1] neg_hi:[0,1]
	v_xor_b32_e32 v113, 0x80000000, v86
	v_mov_b32_e32 v112, v87
	v_pk_add_f32 v[84:85], v[90:91], v[96:97]
	v_pk_add_f32 v[86:87], v[70:71], v[104:105]
	v_pk_add_f32 v[106:107], v[184:185], v[100:101] neg_lo:[0,1] neg_hi:[0,1]
	v_pk_add_f32 v[100:101], v[92:93], v[108:109]
	v_pk_add_f32 v[88:89], v[84:85], v[86:87]
	v_pk_add_f32 v[92:93], v[108:109], v[92:93] neg_lo:[0,1] neg_hi:[0,1]
	v_pk_add_f32 v[108:109], v[100:101], v[114:115]
	v_pk_add_f32 v[70:71], v[104:105], v[70:71] neg_lo:[0,1] neg_hi:[0,1]
	v_pk_add_f32 v[104:105], v[84:85], v[86:87] neg_lo:[0,1] neg_hi:[0,1]
	v_pk_add_f32 v[84:85], v[88:89], v[102:103]
	v_pk_add_f32 v[88:89], v[102:103], v[88:89] neg_lo:[0,1] neg_hi:[0,1]
	v_pk_add_f32 v[140:141], v[138:139], v[136:137] neg_lo:[0,1] neg_hi:[0,1]
	v_xor_b32_e32 v149, 0x80000000, v70
	v_mov_b32_e32 v148, v71
	v_pk_add_f32 v[70:71], v[94:95], v[108:109]
	v_pk_add_f32 v[94:95], v[108:109], v[94:95] neg_lo:[0,1] neg_hi:[0,1]
	v_xor_b32_e32 v97, 0x80000000, v88
	v_mov_b32_e32 v96, v89
	v_pk_add_f32 v[144:145], v[142:143], v[112:113] neg_lo:[0,1] neg_hi:[0,1]
	v_pk_add_f32 v[90:91], v[146:147], v[148:149] neg_lo:[0,1] neg_hi:[0,1]
	v_pk_add_f32 v[86:87], v[70:71], v[84:85]
	v_pk_add_f32 v[84:85], v[70:71], v[84:85] neg_lo:[0,1] neg_hi:[0,1]
	v_pk_add_f32 v[70:71], v[94:95], v[96:97]
	v_pk_add_f32 v[88:89], v[94:95], v[96:97] neg_lo:[0,1] neg_hi:[0,1]
	v_pk_mul_f32 v[94:95], v[140:141], s[10:11] op_sel:[1,0]
	v_pk_add_f32 v[100:101], v[114:115], v[100:101] neg_lo:[0,1] neg_hi:[0,1]
	v_xor_b32_e32 v115, 0x80000000, v92
	v_mov_b32_e32 v114, v93
	v_pk_fma_f32 v[94:95], v[140:141], s[8:9], v[94:95] op_sel_hi:[0,1,1]
	v_mul_f32_e32 v96, 0x3f3504f3, v144
	s_mov_b32 s8, s31
	s_mov_b32 s9, s30
	v_pk_mul_f32 v[102:103], v[90:91], s[34:35] op_sel:[1,0]
	v_pk_add_f32 v[92:93], v[106:107], v[114:115] neg_lo:[0,1] neg_hi:[0,1]
	v_pk_fma_f32 v[96:97], v[144:145], s[8:9], v[96:97] op_sel:[1,0,0] op_sel_hi:[1,1,0]
	v_pk_fma_f32 v[90:91], v[90:91], s[28:29], v[102:103] op_sel_hi:[0,1,1]
	v_pk_add_f32 v[102:103], v[92:93], v[96:97]
	v_pk_add_f32 v[96:97], v[92:93], v[96:97] neg_lo:[0,1] neg_hi:[0,1]
	v_pk_add_f32 v[92:93], v[94:95], v[90:91]
	v_pk_add_f32 v[90:91], v[94:95], v[90:91] neg_lo:[0,1] neg_hi:[0,1]
	v_pk_add_f32 v[94:95], v[102:103], v[92:93]
	v_pk_add_f32 v[92:93], v[102:103], v[92:93] neg_lo:[0,1] neg_hi:[0,1]
	v_xor_b32_e32 v103, 0x80000000, v90
	v_mov_b32_e32 v102, v91
	s_mov_b32 s10, s20
	s_mov_b32 s11, s36
	v_pk_mul_f32 v[108:109], v[98:99], s[12:13] op_sel:[1,0]
	v_pk_add_f32 v[90:91], v[96:97], v[102:103]
	v_pk_add_f32 v[96:97], v[96:97], v[102:103] neg_lo:[0,1] neg_hi:[0,1]
	v_mul_f32_e32 v102, 0x3f3504f3, v110
	v_pk_fma_f32 v[98:99], v[98:99], s[10:11], v[108:109] op_sel_hi:[0,1,1]
	v_mul_f32_e32 v108, 0xbf3504f3, v105
	v_pk_fma_f32 v[102:103], v[110:111], s[8:9], v[102:103] op_sel:[1,0,0] op_sel_hi:[1,1,0]
	v_pk_fma_f32 v[104:105], v[104:105], s[8:9], v[108:109] op_sel_hi:[0,1,0]
	v_pk_add_f32 v[108:109], v[100:101], v[98:99]
	v_pk_add_f32 v[110:111], v[100:101], v[98:99] neg_lo:[0,1] neg_hi:[0,1]
	v_pk_add_f32 v[98:99], v[104:105], v[102:103]
	v_pk_add_f32 v[104:105], v[102:103], v[104:105] neg_lo:[0,1] neg_hi:[0,1]
	v_pk_add_f32 v[102:103], v[108:109], v[98:99]
	v_pk_add_f32 v[100:101], v[108:109], v[98:99] neg_lo:[0,1] neg_hi:[0,1]
	v_xor_b32_e32 v109, 0x80000000, v104
	v_mov_b32_e32 v108, v105
	v_pk_add_f32 v[98:99], v[110:111], v[108:109]
	v_pk_add_f32 v[104:105], v[110:111], v[108:109] neg_lo:[0,1] neg_hi:[0,1]
	v_pk_add_f32 v[108:109], v[146:147], v[148:149]
	s_mov_b32 s12, s28
	s_mov_b32 s13, s34
	s_mov_b32 s10, s34
	s_mov_b32 s11, s27
	v_pk_mul_f32 v[110:111], v[108:109], s[12:13] op_sel:[1,0]
	v_pk_add_f32 v[106:107], v[114:115], v[106:107]
	v_pk_fma_f32 v[108:109], v[108:109], s[10:11], v[110:111] op_sel_hi:[0,1,1]
	v_pk_add_f32 v[110:111], v[136:137], v[138:139]
	v_pk_add_f32 v[112:113], v[142:143], v[112:113]
	v_pk_mul_f32 v[114:115], v[110:111], s[34:35] op_sel:[1,0]
	s_nop 0
	v_pk_fma_f32 v[110:111], v[110:111], s[28:29], v[114:115] op_sel_hi:[0,1,1]
	v_mul_f32_e32 v114, 0xbf3504f3, v113
	v_pk_fma_f32 v[112:113], v[112:113], s[8:9], v[114:115] op_sel_hi:[0,1,0]
	v_pk_add_f32 v[114:115], v[106:107], v[112:113]
	v_pk_add_f32 v[136:137], v[106:107], v[112:113] neg_lo:[0,1] neg_hi:[0,1]
	v_pk_add_f32 v[106:107], v[110:111], v[108:109]
	v_pk_add_f32 v[110:111], v[110:111], v[108:109] neg_lo:[0,1] neg_hi:[0,1]
	v_pk_add_f32 v[108:109], v[114:115], v[106:107]
	v_pk_add_f32 v[106:107], v[114:115], v[106:107] neg_lo:[0,1] neg_hi:[0,1]
	v_xor_b32_e32 v115, 0x80000000, v110
	v_mov_b32_e32 v114, v111
	v_pk_add_f32 v[112:113], v[136:137], v[114:115]
	v_pk_add_f32 v[110:111], v[136:137], v[114:115] neg_lo:[0,1] neg_hi:[0,1]

.LBB0_1673:
	s_or_b64 exec, exec, s[6:7]
	s_waitcnt lgkmcnt(0)
	s_barrier
	s_and_saveexec_b64 s[6:7], vcc
	s_cbranch_execz .LBB0_1675
	ds_read_b64 v[172:173], v27 offset:61440
	ds_read_b64 v[174:175], v63 offset:57344
	ds_read_b64 v[176:177], v117 offset:53248
	ds_read_b64 v[178:179], v124 offset:49152
	ds_read_b64 v[180:181], v127 offset:45056
	ds_read_b64 v[182:183], v129 offset:40960
	ds_read_b64 v[184:185], v134
	ds_read_b64 v[186:187], v125 offset:4096
	ds_read_b64 v[188:189], v122 offset:8192
	ds_read_b64 v[190:191], v65 offset:12288
	ds_read_b64 v[192:193], v31 offset:16384
	ds_read_b64 v[194:195], v19 offset:20480
	ds_read_b64 v[196:197], v11 offset:24576
	ds_read_b64 v[198:199], v7 offset:28672
	ds_read_b64 v[200:201], v133 offset:32768
	v_cvt_f32_ubyte0_e32 v70, v130
	v_mul_f32_e32 v70, 0x39800000, v70
	v_cos_f32_e32 v96, v70
	v_sin_f32_e32 v97, v70
	s_mov_b32 s10, s27
	v_mov_b32_e32 v99, v96
	v_xor_b32_e32 v98, 0x80000000, v97
	v_mov_b32_e32 v70, v97
	v_pk_mul_f32 v[70:71], v[98:99], v[70:71] op_sel_hi:[1,0]
	s_mov_b32 s11, s26
	v_pk_fma_f32 v[104:105], v[96:97], v[96:97], v[70:71] op_sel_hi:[1,0,1]
	s_mov_b32 s8, s26
	v_pk_mul_f32 v[70:71], v[98:99], v[104:105] op_sel:[0,1]
	s_mov_b32 s9, s28
	v_pk_fma_f32 v[108:109], v[96:97], v[104:105], v[70:71] op_sel_hi:[1,0,1]
	s_mov_b32 s35, s28
	v_pk_mul_f32 v[70:71], v[98:99], v[108:109] op_sel:[0,1]
	s_mov_b32 s29, s26
	v_pk_fma_f32 v[110:111], v[96:97], v[108:109], v[70:71] op_sel_hi:[1,0,1]
	s_mov_b32 s12, s21
	v_pk_mul_f32 v[70:71], v[98:99], v[110:111] op_sel:[0,1]
	s_mov_b32 s13, s20
	v_pk_fma_f32 v[112:113], v[96:97], v[110:111], v[70:71] op_sel_hi:[1,0,1]
	s_nop 0
	v_pk_mul_f32 v[70:71], v[98:99], v[112:113] op_sel:[0,1]
	s_nop 0
	v_pk_fma_f32 v[136:137], v[96:97], v[112:113], v[70:71] op_sel_hi:[1,0,1]
	s_nop 0
	v_pk_mul_f32 v[70:71], v[98:99], v[136:137] op_sel:[0,1]
	s_nop 0
	v_pk_fma_f32 v[138:139], v[96:97], v[136:137], v[70:71] op_sel_hi:[1,0,1]
	s_nop 0
	v_pk_mul_f32 v[70:71], v[98:99], v[138:139] op_sel:[0,1]
	v_mov_b32_e32 v135, v138
	v_pk_fma_f32 v[100:101], v[96:97], v[138:139], v[70:71] op_sel_hi:[1,0,1]
	s_nop 0
	v_pk_mul_f32 v[70:71], v[98:99], v[100:101] op_sel:[0,1]
	s_nop 0
	v_pk_fma_f32 v[84:85], v[96:97], v[100:101], v[70:71] op_sel_hi:[1,0,1]
	s_nop 0
	v_pk_mul_f32 v[70:71], v[98:99], v[84:85] op_sel:[0,1]
	s_nop 0
	v_pk_fma_f32 v[94:95], v[96:97], v[84:85], v[70:71] op_sel_hi:[1,0,1]
	s_nop 0
	v_pk_mul_f32 v[70:71], v[98:99], v[94:95] op_sel:[0,1]
	s_nop 0
	v_pk_fma_f32 v[90:91], v[96:97], v[94:95], v[70:71] op_sel_hi:[1,0,1]
	s_nop 0
	v_pk_mul_f32 v[70:71], v[98:99], v[90:91] op_sel:[0,1]
	s_nop 0
	v_pk_fma_f32 v[92:93], v[96:97], v[90:91], v[70:71] op_sel_hi:[1,0,1]
	s_nop 0
	v_pk_mul_f32 v[70:71], v[98:99], v[92:93] op_sel:[0,1]
	s_nop 0
	v_pk_fma_f32 v[88:89], v[96:97], v[92:93], v[70:71] op_sel_hi:[1,0,1]
	s_nop 0
	v_pk_mul_f32 v[70:71], v[98:99], v[88:89] op_sel:[0,1]
	s_nop 0
	v_pk_fma_f32 v[86:87], v[96:97], v[88:89], v[70:71] op_sel_hi:[1,0,1]
	s_nop 0
	v_pk_mul_f32 v[70:71], v[98:99], v[86:87] op_sel:[0,1]
	s_nop 0
	v_pk_fma_f32 v[70:71], v[96:97], v[86:87], v[70:71] op_sel_hi:[1,0,1]
	s_nop 0
	v_xor_b32_e32 v106, 0x80000000, v71
	v_mov_b32_e32 v107, v70
	s_waitcnt lgkmcnt(15)
	s_waitcnt lgkmcnt(14)
	v_pk_mul_f32 v[106:107], v[106:107], v[172:173] op_sel:[0,1]
	s_nop 0
	v_pk_fma_f32 v[70:71], v[70:71], v[172:173], v[106:107] op_sel_hi:[1,0,1]
	ds_read_b64 v[172:173], v132 offset:36864
	v_xor_b32_e32 v106, 0x80000000, v87
	v_mov_b32_e32 v107, v86
	s_waitcnt lgkmcnt(14)
	v_pk_mul_f32 v[106:107], v[106:107], v[174:175] op_sel:[0,1]
	s_nop 0
	v_pk_fma_f32 v[86:87], v[86:87], v[174:175], v[106:107] op_sel_hi:[1,0,1]
	v_xor_b32_e32 v106, 0x80000000, v89
	v_mov_b32_e32 v107, v88
	s_waitcnt lgkmcnt(13)
	v_pk_mul_f32 v[106:107], v[106:107], v[176:177] op_sel:[0,1]
	s_nop 0
	v_pk_fma_f32 v[88:89], v[88:89], v[176:177], v[106:107] op_sel_hi:[1,0,1]
	v_xor_b32_e32 v106, 0x80000000, v93
	v_mov_b32_e32 v107, v92
	s_waitcnt lgkmcnt(12)
	v_pk_mul_f32 v[106:107], v[106:107], v[178:179] op_sel:[0,1]
	s_nop 0
	v_pk_fma_f32 v[92:93], v[92:93], v[178:179], v[106:107] op_sel_hi:[1,0,1]
	v_xor_b32_e32 v106, 0x80000000, v91
	v_mov_b32_e32 v107, v90
	s_waitcnt lgkmcnt(11)
	v_pk_mul_f32 v[106:107], v[106:107], v[180:181] op_sel:[0,1]
	s_nop 0
	v_pk_fma_f32 v[90:91], v[90:91], v[180:181], v[106:107] op_sel_hi:[1,0,1]
	v_xor_b32_e32 v106, 0x80000000, v95
	v_mov_b32_e32 v107, v94
	s_waitcnt lgkmcnt(10)
	v_pk_mul_f32 v[106:107], v[106:107], v[182:183] op_sel:[0,1]
	s_nop 0
	v_pk_fma_f32 v[94:95], v[94:95], v[182:183], v[106:107] op_sel_hi:[1,0,1]
	v_xor_b32_e32 v134, 0x80000000, v139
	s_waitcnt lgkmcnt(8)
	v_pk_mul_f32 v[98:99], v[98:99], v[186:187] op_sel:[0,1]
	s_nop 0
	v_pk_fma_f32 v[102:103], v[96:97], v[186:187], v[98:99] op_sel_hi:[1,0,1]
	v_xor_b32_e32 v98, 0x80000000, v105
	v_mov_b32_e32 v99, v104
	s_waitcnt lgkmcnt(7)
	v_pk_mul_f32 v[98:99], v[98:99], v[188:189] op_sel:[0,1]
	s_nop 0
	v_pk_fma_f32 v[98:99], v[104:105], v[188:189], v[98:99] op_sel_hi:[1,0,1]
	v_xor_b32_e32 v104, 0x80000000, v109
	v_mov_b32_e32 v105, v108
	v_pk_add_f32 v[142:143], v[98:99], v[94:95] neg_lo:[0,1] neg_hi:[0,1]
	s_waitcnt lgkmcnt(6)
	v_pk_mul_f32 v[104:105], v[104:105], v[190:191] op_sel:[0,1]
	s_nop 0
	v_pk_fma_f32 v[96:97], v[108:109], v[190:191], v[104:105] op_sel_hi:[1,0,1]
	v_xor_b32_e32 v108, 0x80000000, v111
	v_mov_b32_e32 v109, v110
	v_pk_add_f32 v[146:147], v[96:97], v[90:91] neg_lo:[0,1] neg_hi:[0,1]
	s_waitcnt lgkmcnt(5)
	v_pk_mul_f32 v[108:109], v[108:109], v[192:193] op_sel:[0,1]
	s_nop 0
	v_pk_fma_f32 v[108:109], v[110:111], v[192:193], v[108:109] op_sel_hi:[1,0,1]
	v_xor_b32_e32 v110, 0x80000000, v113
	v_mov_b32_e32 v111, v112
	s_waitcnt lgkmcnt(4)
	v_pk_mul_f32 v[110:111], v[110:111], v[194:195] op_sel:[0,1]
	s_nop 0
	v_pk_fma_f32 v[110:111], v[112:113], v[194:195], v[110:111] op_sel_hi:[1,0,1]
	v_xor_b32_e32 v112, 0x80000000, v137
	v_mov_b32_e32 v113, v136
	s_waitcnt lgkmcnt(3)
	v_pk_mul_f32 v[112:113], v[112:113], v[196:197] op_sel:[0,1]
	s_nop 0
	v_pk_fma_f32 v[112:113], v[136:137], v[196:197], v[112:113] op_sel_hi:[1,0,1]
	v_xor_b32_e32 v136, 0x80000000, v101
	v_mov_b32_e32 v137, v100
	s_waitcnt lgkmcnt(2)
	v_pk_mul_f32 v[134:135], v[134:135], v[198:199] op_sel:[0,1]
	s_nop 0
	v_pk_fma_f32 v[104:105], v[138:139], v[198:199], v[134:135] op_sel_hi:[1,0,1]
	s_waitcnt lgkmcnt(1)
	v_pk_mul_f32 v[136:137], v[136:137], v[200:201] op_sel:[0,1]
	s_nop 0
	v_pk_fma_f32 v[100:101], v[100:101], v[200:201], v[136:137] op_sel_hi:[1,0,1]
	v_xor_b32_e32 v136, 0x80000000, v85
	v_mov_b32_e32 v137, v84
	s_waitcnt lgkmcnt(0)
	v_pk_mul_f32 v[136:137], v[136:137], v[172:173] op_sel:[0,1]
	s_nop 0
	v_pk_fma_f32 v[84:85], v[84:85], v[172:173], v[136:137] op_sel_hi:[1,0,1]
	v_pk_add_f32 v[134:135], v[184:185], v[100:101]
	v_pk_add_f32 v[136:137], v[102:103], v[84:85]
	v_pk_add_f32 v[138:139], v[102:103], v[84:85] neg_lo:[0,1] neg_hi:[0,1]
	v_pk_add_f32 v[84:85], v[88:89], v[110:111]
	v_pk_add_f32 v[88:89], v[110:111], v[88:89] neg_lo:[0,1] neg_hi:[0,1]
	v_pk_add_f32 v[102:103], v[84:85], v[136:137]
	v_pk_add_f32 v[110:111], v[136:137], v[84:85] neg_lo:[0,1] neg_hi:[0,1]
	v_xor_b32_e32 v137, 0x80000000, v88
	v_mov_b32_e32 v136, v89
	v_pk_add_f32 v[84:85], v[94:95], v[98:99]
	v_pk_add_f32 v[88:89], v[86:87], v[112:113]
	v_pk_add_f32 v[86:87], v[112:113], v[86:87] neg_lo:[0,1] neg_hi:[0,1]
	v_pk_add_f32 v[94:95], v[84:85], v[88:89]
	v_pk_add_f32 v[98:99], v[84:85], v[88:89] neg_lo:[0,1] neg_hi:[0,1]
	v_xor_b32_e32 v113, 0x80000000, v86
	v_mov_b32_e32 v112, v87
	v_pk_add_f32 v[84:85], v[90:91], v[96:97]
	v_pk_add_f32 v[86:87], v[70:71], v[104:105]
	v_pk_add_f32 v[106:107], v[184:185], v[100:101] neg_lo:[0,1] neg_hi:[0,1]
	v_pk_add_f32 v[100:101], v[92:93], v[108:109]
	v_pk_add_f32 v[88:89], v[84:85], v[86:87]
	v_pk_add_f32 v[92:93], v[108:109], v[92:93] neg_lo:[0,1] neg_hi:[0,1]
	v_pk_add_f32 v[108:109], v[100:101], v[134:135]
	v_pk_add_f32 v[70:71], v[104:105], v[70:71] neg_lo:[0,1] neg_hi:[0,1]
	v_pk_add_f32 v[104:105], v[84:85], v[86:87] neg_lo:[0,1] neg_hi:[0,1]
	v_pk_add_f32 v[84:85], v[88:89], v[102:103]
	v_pk_add_f32 v[88:89], v[102:103], v[88:89] neg_lo:[0,1] neg_hi:[0,1]
	v_pk_add_f32 v[140:141], v[138:139], v[136:137] neg_lo:[0,1] neg_hi:[0,1]
	v_xor_b32_e32 v149, 0x80000000, v70
	v_mov_b32_e32 v148, v71
	v_pk_add_f32 v[70:71], v[94:95], v[108:109]
	v_pk_add_f32 v[94:95], v[108:109], v[94:95] neg_lo:[0,1] neg_hi:[0,1]
	v_xor_b32_e32 v97, 0x80000000, v88
	v_mov_b32_e32 v96, v89
	v_pk_add_f32 v[144:145], v[142:143], v[112:113] neg_lo:[0,1] neg_hi:[0,1]
	v_pk_add_f32 v[90:91], v[146:147], v[148:149] neg_lo:[0,1] neg_hi:[0,1]
	v_pk_add_f32 v[86:87], v[70:71], v[84:85]
	v_pk_add_f32 v[84:85], v[70:71], v[84:85] neg_lo:[0,1] neg_hi:[0,1]
	v_pk_add_f32 v[70:71], v[94:95], v[96:97]
	v_pk_add_f32 v[88:89], v[94:95], v[96:97] neg_lo:[0,1] neg_hi:[0,1]
	v_pk_mul_f32 v[94:95], v[140:141], s[10:11] op_sel:[1,0]
	v_pk_add_f32 v[100:101], v[134:135], v[100:101] neg_lo:[0,1] neg_hi:[0,1]
	v_xor_b32_e32 v135, 0x80000000, v92
	v_mov_b32_e32 v134, v93
	v_pk_fma_f32 v[94:95], v[140:141], s[8:9], v[94:95] op_sel_hi:[0,1,1]
	v_mul_f32_e32 v96, 0x3f3504f3, v144
	s_mov_b32 s8, s31
	s_mov_b32 s9, s30
	v_pk_mul_f32 v[102:103], v[90:91], s[34:35] op_sel:[1,0]
	v_pk_add_f32 v[92:93], v[106:107], v[134:135] neg_lo:[0,1] neg_hi:[0,1]
	v_pk_fma_f32 v[96:97], v[144:145], s[8:9], v[96:97] op_sel:[1,0,0] op_sel_hi:[1,1,0]
	v_pk_fma_f32 v[90:91], v[90:91], s[28:29], v[102:103] op_sel_hi:[0,1,1]
	v_pk_add_f32 v[102:103], v[92:93], v[96:97]
	v_pk_add_f32 v[96:97], v[92:93], v[96:97] neg_lo:[0,1] neg_hi:[0,1]
	v_pk_add_f32 v[92:93], v[94:95], v[90:91]
	v_pk_add_f32 v[90:91], v[94:95], v[90:91] neg_lo:[0,1] neg_hi:[0,1]
	v_pk_add_f32 v[94:95], v[102:103], v[92:93]
	v_pk_add_f32 v[92:93], v[102:103], v[92:93] neg_lo:[0,1] neg_hi:[0,1]
	v_xor_b32_e32 v103, 0x80000000, v90
	v_mov_b32_e32 v102, v91
	s_mov_b32 s10, s20
	s_mov_b32 s11, s36
	v_pk_mul_f32 v[108:109], v[98:99], s[12:13] op_sel:[1,0]
	v_pk_add_f32 v[90:91], v[96:97], v[102:103]
	v_pk_add_f32 v[96:97], v[96:97], v[102:103] neg_lo:[0,1] neg_hi:[0,1]
	v_mul_f32_e32 v102, 0x3f3504f3, v110
	v_pk_fma_f32 v[98:99], v[98:99], s[10:11], v[108:109] op_sel_hi:[0,1,1]
	v_mul_f32_e32 v108, 0xbf3504f3, v105
	v_pk_fma_f32 v[102:103], v[110:111], s[8:9], v[102:103] op_sel:[1,0,0] op_sel_hi:[1,1,0]
	v_pk_fma_f32 v[104:105], v[104:105], s[8:9], v[108:109] op_sel_hi:[0,1,0]
	v_pk_add_f32 v[108:109], v[100:101], v[98:99]
	v_pk_add_f32 v[110:111], v[100:101], v[98:99] neg_lo:[0,1] neg_hi:[0,1]
	v_pk_add_f32 v[98:99], v[104:105], v[102:103]
	v_pk_add_f32 v[104:105], v[102:103], v[104:105] neg_lo:[0,1] neg_hi:[0,1]
	v_pk_add_f32 v[102:103], v[108:109], v[98:99]
	v_pk_add_f32 v[100:101], v[108:109], v[98:99] neg_lo:[0,1] neg_hi:[0,1]
	v_xor_b32_e32 v109, 0x80000000, v104
	v_mov_b32_e32 v108, v105
	v_pk_add_f32 v[98:99], v[110:111], v[108:109]
	v_pk_add_f32 v[104:105], v[110:111], v[108:109] neg_lo:[0,1] neg_hi:[0,1]
	v_pk_add_f32 v[108:109], v[146:147], v[148:149]
	s_mov_b32 s12, s28
	s_mov_b32 s13, s34
	s_mov_b32 s10, s34
	s_mov_b32 s11, s27
	v_pk_mul_f32 v[110:111], v[108:109], s[12:13] op_sel:[1,0]
	v_pk_add_f32 v[106:107], v[134:135], v[106:107]
	v_pk_fma_f32 v[108:109], v[108:109], s[10:11], v[110:111] op_sel_hi:[0,1,1]
	v_pk_add_f32 v[110:111], v[136:137], v[138:139]
	v_pk_add_f32 v[112:113], v[142:143], v[112:113]
	v_pk_mul_f32 v[134:135], v[110:111], s[34:35] op_sel:[1,0]
	s_nop 0
	v_pk_fma_f32 v[110:111], v[110:111], s[28:29], v[134:135] op_sel_hi:[0,1,1]
	v_mul_f32_e32 v134, 0xbf3504f3, v113
	v_pk_fma_f32 v[112:113], v[112:113], s[8:9], v[134:135] op_sel_hi:[0,1,0]
	v_pk_add_f32 v[134:135], v[106:107], v[112:113]
	v_pk_add_f32 v[136:137], v[106:107], v[112:113] neg_lo:[0,1] neg_hi:[0,1]
	v_pk_add_f32 v[106:107], v[110:111], v[108:109]
	v_pk_add_f32 v[110:111], v[110:111], v[108:109] neg_lo:[0,1] neg_hi:[0,1]
	v_pk_add_f32 v[108:109], v[134:135], v[106:107]
	v_pk_add_f32 v[106:107], v[134:135], v[106:107] neg_lo:[0,1] neg_hi:[0,1]
	v_xor_b32_e32 v135, 0x80000000, v110
	v_mov_b32_e32 v134, v111
	v_pk_add_f32 v[112:113], v[136:137], v[134:135]
	v_pk_add_f32 v[110:111], v[136:137], v[134:135] neg_lo:[0,1] neg_hi:[0,1]

.LBB0_1677:
	s_or_b64 exec, exec, s[6:7]
	s_waitcnt lgkmcnt(0)
	s_barrier
	s_and_saveexec_b64 s[6:7], vcc
	s_cbranch_execz .LBB0_1679
	ds_read_b64 v[172:173], v133 offset:32768
	v_cvt_f32_i32_e32 v84, v130
	v_lshlrev_b32_e32 v86, 3, v131
	v_lshlrev_b32_e32 v87, 3, v130
	v_mul_f32_e32 v84, 0x39000000, v84
	v_sin_f32_e32 v85, v84
	v_cos_f32_e32 v84, v84
	v_add3_u32 v90, 0, v86, v87
	ds_read_b64 v[174:175], v90
	v_xor_b32_e32 v88, 0x80000000, v85
	v_mov_b32_e32 v89, v84
	v_cvt_f32_i32_e32 v91, v128
	s_waitcnt lgkmcnt(2)
	s_waitcnt lgkmcnt(1)
	v_pk_mul_f32 v[88:89], v[88:89], v[172:173] op_sel:[0,1]
	v_cvt_f32_i32_e32 v59, v59
	v_pk_fma_f32 v[70:71], v[84:85], v[172:173], v[88:89] op_sel_hi:[1,0,1]
	v_cvt_f32_i32_e32 v23, v23
	s_waitcnt lgkmcnt(0)
	v_pk_add_f32 v[70:71], v[174:175], v[70:71]
	ds_write_b64 v90, v[70:71]
	ds_read_b64 v[172:173], v132 offset:36864
	ds_read_b64 v[174:175], v125 offset:4096
	v_mul_f32_e32 v71, 0x39000000, v91
	v_cos_f32_e32 v70, v71
	v_sin_f32_e32 v71, v71
	v_cvt_f32_i32_e32 v90, v126
	v_mov_b32_e32 v89, v70
	v_xor_b32_e32 v88, 0x80000000, v71
	s_waitcnt lgkmcnt(1)
	v_pk_mul_f32 v[88:89], v[88:89], v[172:173] op_sel:[0,1]
	v_cvt_f32_i32_e32 v15, v15
	v_pk_fma_f32 v[70:71], v[70:71], v[172:173], v[88:89] op_sel_hi:[1,0,1]
	s_waitcnt lgkmcnt(0)
	v_pk_add_f32 v[70:71], v[174:175], v[70:71]
	ds_write_b64 v125, v[70:71] offset:4096
	ds_read_b64 v[172:173], v129 offset:40960
	ds_read_b64 v[174:175], v122 offset:8192
	v_mul_f32_e32 v71, 0x39000000, v90
	v_cos_f32_e32 v70, v71
	v_sin_f32_e32 v71, v71
	v_cvt_f32_i32_e32 v90, v123
	v_mov_b32_e32 v89, v70
	v_xor_b32_e32 v88, 0x80000000, v71
	s_waitcnt lgkmcnt(1)
	v_pk_mul_f32 v[88:89], v[88:89], v[172:173] op_sel:[0,1]
	s_nop 0
	v_pk_fma_f32 v[70:71], v[70:71], v[172:173], v[88:89] op_sel_hi:[1,0,1]
	s_waitcnt lgkmcnt(0)
	v_pk_add_f32 v[70:71], v[174:175], v[70:71]
	ds_write_b64 v122, v[70:71] offset:8192
	ds_read_b64 v[172:173], v127 offset:45056
	ds_read_b64 v[174:175], v65 offset:12288
	v_mul_f32_e32 v71, 0x39000000, v90
	v_cos_f32_e32 v70, v71
	v_sin_f32_e32 v71, v71
	v_cvt_f32_i32_e32 v90, v116
	v_mov_b32_e32 v89, v70
	v_xor_b32_e32 v88, 0x80000000, v71
	s_waitcnt lgkmcnt(1)
	v_pk_mul_f32 v[88:89], v[88:89], v[172:173] op_sel:[0,1]
	s_nop 0
	v_pk_fma_f32 v[70:71], v[70:71], v[172:173], v[88:89] op_sel_hi:[1,0,1]
	s_waitcnt lgkmcnt(0)
	v_pk_add_f32 v[70:71], v[174:175], v[70:71]
	ds_write_b64 v65, v[70:71] offset:12288
	ds_read_b64 v[172:173], v124 offset:49152
	ds_read_b64 v[174:175], v31 offset:16384
	v_mul_f32_e32 v65, 0x39000000, v90
	v_cos_f32_e32 v70, v65
	v_sin_f32_e32 v71, v65
	s_nop 0
	v_mov_b32_e32 v89, v70
	v_xor_b32_e32 v88, 0x80000000, v71
	s_waitcnt lgkmcnt(1)
	v_pk_mul_f32 v[88:89], v[88:89], v[172:173] op_sel:[0,1]
	s_nop 0
	v_pk_fma_f32 v[70:71], v[70:71], v[172:173], v[88:89] op_sel_hi:[1,0,1]
	s_waitcnt lgkmcnt(0)
	v_pk_add_f32 v[70:71], v[174:175], v[70:71]
	ds_write_b64 v31, v[70:71] offset:16384
	ds_read_b64 v[172:173], v117 offset:53248
	ds_read_b64 v[174:175], v19 offset:20480
	v_mul_f32_e32 v31, 0x39000000, v59
	v_cos_f32_e32 v70, v31
	v_sin_f32_e32 v71, v31
	s_nop 0
	v_mov_b32_e32 v89, v70
	v_xor_b32_e32 v88, 0x80000000, v71
	s_waitcnt lgkmcnt(1)
	v_pk_mul_f32 v[88:89], v[88:89], v[172:173] op_sel:[0,1]
	s_nop 0
	v_pk_fma_f32 v[70:71], v[70:71], v[172:173], v[88:89] op_sel_hi:[1,0,1]
	s_waitcnt lgkmcnt(0)
	v_pk_add_f32 v[70:71], v[174:175], v[70:71]
	ds_write_b64 v19, v[70:71] offset:20480
	ds_read_b64 v[172:173], v63 offset:57344
	ds_read_b64 v[174:175], v11 offset:24576
	v_mul_f32_e32 v19, 0x39000000, v23
	v_cos_f32_e32 v70, v19
	v_sin_f32_e32 v71, v19
	s_nop 0
	v_mov_b32_e32 v89, v70
	v_xor_b32_e32 v88, 0x80000000, v71
	s_waitcnt lgkmcnt(1)
	v_pk_mul_f32 v[88:89], v[88:89], v[172:173] op_sel:[0,1]
	s_nop 0
	v_pk_fma_f32 v[70:71], v[70:71], v[172:173], v[88:89] op_sel_hi:[1,0,1]
	s_waitcnt lgkmcnt(0)
	v_pk_add_f32 v[70:71], v[174:175], v[70:71]
	ds_write_b64 v11, v[70:71] offset:24576
	ds_read_b64 v[84:85], v27 offset:61440
	ds_read_b64 v[86:87], v7 offset:28672
	v_mul_f32_e32 v11, 0x39000000, v15
	v_cos_f32_e32 v70, v11
	v_sin_f32_e32 v71, v11
	s_nop 0
	v_mov_b32_e32 v89, v70
	v_xor_b32_e32 v88, 0x80000000, v71
	s_waitcnt lgkmcnt(1)
	v_pk_mul_f32 v[88:89], v[88:89], v[84:85] op_sel:[0,1]
	s_nop 0
	v_pk_fma_f32 v[70:71], v[70:71], v[84:85], v[88:89] op_sel_hi:[1,0,1]
	s_waitcnt lgkmcnt(0)
	v_pk_add_f32 v[70:71], v[86:87], v[70:71]
	ds_write_b64 v7, v[70:71] offset:28672

.LBB0_1698:
	v_mov_b32_e32 v35, s5
	ds_read_b128 v[172:175], v35
	ds_read_b128 v[102:105], v35 offset:16
	v_add_u32_e32 v35, s4, v3
	ds_read2_b32 v[176:177], v35 offset0:2 offset1:3
	ds_read2_b32 v[178:179], v35 offset0:66 offset1:67
	ds_read2_b32 v[108:109], v35 offset0:130 offset1:131
	ds_read2_b32 v[110:111], v35 offset0:194 offset1:195
	ds_read2_b32 v[180:181], v35 offset1:1
	ds_read2_b32 v[98:99], v35 offset0:64 offset1:65
	ds_read2_b32 v[100:101], v35 offset0:128 offset1:129
	ds_read2_b32 v[106:107], v35 offset0:192 offset1:193
	s_add_i32 s5, s5, 32
	s_waitcnt lgkmcnt(8)
	s_waitcnt lgkmcnt(7)
	v_pk_fma_f32 v[92:93], v[172:173], v[176:177], v[92:93] op_sel:[0,1,0]
	s_waitcnt lgkmcnt(6)
	v_pk_fma_f32 v[90:91], v[172:173], v[178:179], v[90:91] op_sel:[0,1,0]
	s_waitcnt lgkmcnt(5)
	v_pk_fma_f32 v[88:89], v[172:173], v[108:109], v[88:89] op_sel:[0,1,0]
	s_waitcnt lgkmcnt(4)
	v_pk_fma_f32 v[86:87], v[172:173], v[110:111], v[86:87] op_sel:[0,1,0]
	v_pk_fma_f32 v[84:85], v[174:175], v[176:177], v[92:93] op_sel_hi:[1,0,1]
	v_pk_fma_f32 v[90:91], v[174:175], v[178:179], v[90:91] op_sel_hi:[1,0,1]
	v_pk_fma_f32 v[88:89], v[174:175], v[108:109], v[88:89] op_sel_hi:[1,0,1]
	v_pk_fma_f32 v[86:87], v[174:175], v[110:111], v[86:87] op_sel_hi:[1,0,1]
	s_add_i32 s4, s4, -16
	s_waitcnt lgkmcnt(3)
	v_pk_fma_f32 v[84:85], v[102:103], v[180:181], v[84:85] op_sel:[0,1,0]
	s_waitcnt lgkmcnt(2)
	v_pk_fma_f32 v[90:91], v[102:103], v[98:99], v[90:91] op_sel:[0,1,0]
	s_waitcnt lgkmcnt(1)
	v_pk_fma_f32 v[88:89], v[102:103], v[100:101], v[88:89] op_sel:[0,1,0]
	s_waitcnt lgkmcnt(0)
	v_pk_fma_f32 v[86:87], v[102:103], v[106:107], v[86:87] op_sel:[0,1,0]
	v_pk_fma_f32 v[92:93], v[104:105], v[180:181], v[84:85] op_sel_hi:[1,0,1]
	v_pk_fma_f32 v[90:91], v[104:105], v[98:99], v[90:91] op_sel_hi:[1,0,1]
	v_pk_fma_f32 v[88:89], v[104:105], v[100:101], v[88:89] op_sel_hi:[1,0,1]
	v_pk_fma_f32 v[86:87], v[104:105], v[106:107], v[86:87] op_sel_hi:[1,0,1]
	s_cmp_eq_u32 s4, -12
	s_cbranch_scc0 .LBB0_1698
	s_waitcnt vmcnt(20)
	v_mov_b32_e32 v98, v37
	v_mov_b32_e32 v99, v33
	v_cndmask_b32_e64 v33, v32, 0, s[6:7]
	v_cndmask_b32_e64 v32, v36, 0, s[6:7]
	v_mov_b32_e32 v36, v38
	v_pk_fma_f32 v[38:39], v[70:71], v[98:99], v[72:73] op_sel_hi:[0,1,0]
	v_mov_b32_e32 v37, v34
	v_pk_fma_f32 v[32:33], v[66:67], v[32:33], v[38:39] op_sel_hi:[0,1,1]
	s_waitcnt vmcnt(18)
	v_mov_b32_e32 v100, v45
	v_mov_b32_e32 v101, v41
	v_pk_fma_f32 v[32:33], v[68:69], v[36:37], v[32:33] op_sel_hi:[0,1,1]
	s_waitcnt vmcnt(1)
	v_pk_fma_f32 v[36:37], v[74:75], v[82:83], v[92:93] op_sel_hi:[1,0,1]
	v_mov_b32_e32 v45, v40
	v_pk_mul_f32 v[38:39], v[32:33], v[36:37]
	v_pk_fma_f32 v[32:33], v[70:71], v[100:101], v[72:73] op_sel_hi:[0,1,0]
	v_mov_b32_e32 v34, v46
	v_mov_b32_e32 v35, v42
	v_pk_fma_f32 v[32:33], v[66:67], v[44:45], v[32:33] op_sel_hi:[0,1,1]
	v_mov_b32_e32 v102, v49
	v_mov_b32_e32 v103, v53
	v_pk_fma_f32 v[32:33], v[68:69], v[34:35], v[32:33] op_sel_hi:[0,1,1]
	v_pk_fma_f32 v[34:35], v[76:77], v[82:83], v[90:91] op_sel_hi:[1,0,1]
	v_mov_b32_e32 v49, v52
	v_pk_mul_f32 v[36:37], v[32:33], v[34:35]
	v_pk_fma_f32 v[32:33], v[70:71], v[102:103], v[72:73] op_sel_hi:[0,1,0]
	v_mov_b32_e32 v42, v50
	v_mov_b32_e32 v43, v54
	v_pk_fma_f32 v[32:33], v[66:67], v[48:49], v[32:33] op_sel_hi:[0,1,1]
	v_mov_b32_e32 v104, v61
	v_mov_b32_e32 v105, v57
	v_pk_fma_f32 v[32:33], v[68:69], v[42:43], v[32:33] op_sel_hi:[0,1,1]
	v_pk_fma_f32 v[34:35], v[78:79], v[82:83], v[88:89] op_sel_hi:[1,0,1]
	v_mov_b32_e32 v61, v56
	v_pk_mul_f32 v[34:35], v[32:33], v[34:35]
	v_pk_fma_f32 v[32:33], v[70:71], v[104:105], v[72:73] op_sel_hi:[0,1,0]
	v_cndmask_b32_e64 v107, v58, 0, s[8:9]
	v_cndmask_b32_e64 v106, v62, 0, s[8:9]
	v_pk_fma_f32 v[32:33], v[66:67], v[60:61], v[32:33] op_sel_hi:[0,1,1]
	v_pk_fma_f32 v[32:33], v[68:69], v[106:107], v[32:33] op_sel_hi:[0,1,1]
	v_pk_fma_f32 v[40:41], v[80:81], v[82:83], v[86:87] op_sel_hi:[1,0,1]
	s_waitcnt lgkmcnt(0)
	v_mov_b32_e32 v84, 0
	v_pk_mul_f32 v[32:33], v[32:33], v[40:41]
	ds_write2st64_b64 v73, v[38:39], v[36:37] offset0:8 offset1:9
	ds_write2st64_b64 v73, v[34:35], v[32:33] offset0:10 offset1:11
	s_waitcnt lgkmcnt(0)
	s_movk_i32 s4, 0xbf4
	s_mov_b32 s5, s1
	v_mov_b32_e32 v85, v84
	v_mov_b32_e32 v44, v84
	v_mov_b32_e32 v45, v84
	v_mov_b32_e32 v42, v84
	v_mov_b32_e32 v43, v84
	v_mov_b32_e32 v40, v84
	v_mov_b32_e32 v41, v84
.LBB0_1700:
	v_mov_b32_e32 v46, s5
	ds_read_b128 v[74:77], v46
	ds_read_b128 v[78:81], v46 offset:16
	v_add_u32_e32 v46, s4, v3
	ds_read2_b32 v[172:173], v46 offset0:130 offset1:131
	ds_read2_b32 v[174:175], v46 offset0:194 offset1:195
	ds_read2_b32 v[176:177], v46 offset0:66 offset1:67
	ds_read2_b32 v[178:179], v46 offset0:2 offset1:3
	ds_read2_b32 v[56:57], v46 offset0:64 offset1:65
	ds_read2_b32 v[52:53], v46 offset1:1
	ds_read2_b32 v[60:61], v46 offset0:128 offset1:129
	s_add_i32 s5, s5, 32
	s_waitcnt lgkmcnt(7)
	s_waitcnt lgkmcnt(6)
	v_pk_fma_f32 v[40:41], v[74:75], v[172:173], v[40:41] op_sel:[0,1,0]
	s_add_i32 s4, s4, -16
	v_pk_fma_f32 v[40:41], v[76:77], v[172:173], v[40:41] op_sel_hi:[1,0,1]
	s_waitcnt lgkmcnt(4)
	v_pk_fma_f32 v[42:43], v[74:75], v[176:177], v[42:43] op_sel:[0,1,0]
	s_cmpk_lg_i32 s4, 0x7f4
	v_pk_fma_f32 v[42:43], v[76:77], v[176:177], v[42:43] op_sel_hi:[1,0,1]
	s_waitcnt lgkmcnt(3)
	v_pk_fma_f32 v[44:45], v[74:75], v[178:179], v[44:45] op_sel:[0,1,0]
	v_pk_fma_f32 v[74:75], v[74:75], v[174:175], v[84:85] op_sel:[0,1,0]
	v_pk_fma_f32 v[44:45], v[76:77], v[178:179], v[44:45] op_sel_hi:[1,0,1]
	v_pk_fma_f32 v[48:49], v[76:77], v[174:175], v[74:75] op_sel_hi:[1,0,1]
	ds_read2_b32 v[74:75], v46 offset0:192 offset1:193
	s_waitcnt lgkmcnt(2)
	v_pk_fma_f32 v[44:45], v[78:79], v[52:53], v[44:45] op_sel:[0,1,0]
	v_pk_fma_f32 v[42:43], v[78:79], v[56:57], v[42:43] op_sel:[0,1,0]
	v_pk_fma_f32 v[44:45], v[80:81], v[52:53], v[44:45] op_sel_hi:[1,0,1]
	s_waitcnt lgkmcnt(1)
	v_pk_fma_f32 v[40:41], v[78:79], v[60:61], v[40:41] op_sel:[0,1,0]
	s_waitcnt lgkmcnt(0)
	v_pk_fma_f32 v[48:49], v[78:79], v[74:75], v[48:49] op_sel:[0,1,0]
	v_pk_fma_f32 v[42:43], v[80:81], v[56:57], v[42:43] op_sel_hi:[1,0,1]
	v_pk_fma_f32 v[40:41], v[80:81], v[60:61], v[40:41] op_sel_hi:[1,0,1]
	v_pk_fma_f32 v[84:85], v[80:81], v[74:75], v[48:49] op_sel_hi:[1,0,1]
	s_cbranch_scc1 .LBB0_1700
	s_add_u32 s4, s66, s3
	s_addc_u32 s5, s67, s2
	s_add_u32 s2, s4, 0x8400
	v_cndmask_b32_e64 v4, v4, 0, s[6:7]
	v_fma_f32 v5, v96, v5, v83
	s_addc_u32 s3, s5, 0
	v_fma_f32 v29, v96, v29, v83
	v_fma_f32 v25, v96, v25, v83
	v_fma_f32 v21, v96, v21, v83
	v_fma_f32 v17, v96, v17, v83
	v_fma_f32 v13, v96, v13, v83
	v_fma_f32 v9, v96, v9, v83
	v_fmac_f32_e32 v5, v94, v4
	v_cndmask_b32_e64 v0, v0, 0, s[6:7]
	v_fmac_f32_e32 v83, v96, v1
	s_add_u32 s4, s4, 0x8000
	v_fmac_f32_e32 v5, v95, v6
	v_fmac_f32_e32 v83, v94, v0
	s_waitcnt vmcnt(0)
	v_fma_f32 v0, v97, v38, v44
	s_addc_u32 s5, s5, 0
	v_fmac_f32_e32 v83, v95, v2
	v_mul_f32_e32 v0, v5, v0
	v_fmac_f32_e32 v45, v97, v39
	v_fmac_f32_e32 v13, v94, v12
	global_store_dword v64, v0, s[4:5]
	v_mul_f32_e32 v0, v83, v45
	v_fmac_f32_e32 v13, v95, v14
	v_fmac_f32_e32 v9, v94, v8
	global_store_dword v64, v0, s[2:3]
	v_fma_f32 v0, v97, v36, v42
	v_fmac_f32_e32 v9, v95, v10
	v_mul_f32_e32 v0, v13, v0
	v_fmac_f32_e32 v43, v97, v37
	v_fmac_f32_e32 v21, v94, v20
	global_store_dword v23, v0, s[4:5]
	v_mul_f32_e32 v0, v9, v43
	v_fmac_f32_e32 v21, v95, v22
	v_fmac_f32_e32 v17, v94, v16
	global_store_dword v23, v0, s[2:3]
	v_fma_f32 v0, v97, v34, v40
	v_fmac_f32_e32 v17, v95, v18
	v_mul_f32_e32 v0, v21, v0
	v_fmac_f32_e32 v41, v97, v35
	v_fmac_f32_e32 v29, v94, v28
	v_cndmask_b32_e64 v28, v30, 0, s[8:9]
	global_store_dword v27, v0, s[4:5]
	v_mul_f32_e32 v0, v17, v41
	v_fmac_f32_e32 v29, v95, v28
	global_store_dword v27, v0, s[2:3]
	v_fma_f32 v0, v97, v32, v84
	v_mul_f32_e32 v0, v29, v0
	v_fmac_f32_e32 v25, v94, v24
	v_cndmask_b32_e64 v24, v26, 0, s[8:9]
	global_store_dword v31, v0, s[4:5]
	v_readlane_b32 s4, v238, 3
	v_fmac_f32_e32 v25, v95, v24
	v_fmac_f32_e32 v85, v97, v33
	s_add_i32 s12, s12, s4
	v_mul_f32_e32 v0, v25, v85
	s_cmpk_lt_i32 s12, 0x800
	v_readlane_b32 s5, v238, 4
	global_store_dword v31, v0, s[2:3]
	s_cbranch_scc1 .LBB0_1697

.LBB0_1757:
	s_add_i32 s3, s4, s33
	s_cmpk_gt_i32 s3, 0x21f
	s_cselect_b64 s[6:7], -1, 0
	v_add_u32_e32 v66, v89, v90
	s_and_b64 vcc, exec, s[6:7]
	s_barrier
	s_waitcnt vmcnt(15)
	ds_write_b128 v66, v[0:3]
	s_waitcnt vmcnt(14)
	ds_write_b128 v66, v[4:7] offset:8256
	s_waitcnt vmcnt(13)
	ds_write_b128 v66, v[8:11] offset:16512
	s_waitcnt vmcnt(12)
	ds_write_b128 v66, v[12:15] offset:24768
	s_waitcnt vmcnt(11)
	ds_write_b128 v66, v[16:19] offset:33024
	s_waitcnt vmcnt(10)
	ds_write_b128 v66, v[20:23] offset:41280
	s_waitcnt vmcnt(9)
	ds_write_b128 v93, v[24:27]
	s_waitcnt vmcnt(8)
	ds_write_b128 v93, v[28:31] offset:8256
	s_waitcnt vmcnt(7)
	ds_write_b128 v93, v[32:35] offset:16512
	s_waitcnt vmcnt(6)
	ds_write_b128 v93, v[36:39] offset:24768
	s_waitcnt vmcnt(5)
	ds_write_b128 v93, v[40:43] offset:33024
	s_waitcnt vmcnt(4)
	ds_write_b128 v93, v[44:47] offset:41280
	s_waitcnt vmcnt(3)
	ds_write_b128 v93, v[48:51] offset:49536
	s_waitcnt vmcnt(2)
	ds_write_b128 v93, v[52:55] offset:57792
	s_waitcnt vmcnt(1)
	ds_write_b128 v94, v[56:59] offset:57792
	s_waitcnt vmcnt(0)
	ds_write_b128 v95, v[60:63] offset:57792
	s_waitcnt lgkmcnt(0)
	s_barrier
	s_cbranch_vccnz .LBB0_1759
	s_mul_hi_i32 s5, s3, 0x78787879
	s_lshr_b32 s8, s5, 31
	s_ashr_i32 s5, s5, 3
	s_add_i32 s5, s5, s8
	s_lshl_b32 s10, s5, 6
	s_mul_i32 s5, s5, 17
	s_sub_i32 s5, s3, s5
	v_lshl_or_b32 v0, s5, 9, v73
	v_cmp_gt_i32_e32 vcc, s2, v0
	v_add_u32_e32 v2, s10, v72
	v_mov_b64_e32 v[56:57], s[66:67]
	v_cndmask_b32_e32 v0, 0, v0, vcc
	v_ashrrev_i32_e32 v1, 31, v0
	v_mad_i64_i32 v[2:3], s[8:9], v2, s1, v[56:57]
	v_lshlrev_b64 v[58:59], 2, v[0:1]
	v_lshl_add_u64 v[0:1], v[2:3], 0, v[58:59]
	v_add_u32_e32 v2, s10, v74
	v_add_u32_e32 v8, s10, v75
	v_add_u32_e32 v10, s10, v76
	v_add_u32_e32 v16, s10, v77
	v_add_u32_e32 v18, s10, v78
	v_add_u32_e32 v24, s10, v79
	v_add_u32_e32 v26, s10, v80
	v_add_u32_e32 v32, s10, v81
	v_add_u32_e32 v34, s10, v82
	v_add_u32_e32 v40, s10, v83
	v_add_u32_e32 v42, s10, v84
	v_add_u32_e32 v48, s10, v85
	v_add_u32_e32 v50, s10, v86
	v_add_u32_e32 v60, s10, v87
	v_add_u32_e32 v62, s10, v88
	v_mad_i64_i32 v[2:3], s[8:9], v2, s1, v[56:57]
	v_mad_i64_i32 v[8:9], s[8:9], v8, s1, v[56:57]
	v_mad_i64_i32 v[10:11], s[8:9], v10, s1, v[56:57]
	v_mad_i64_i32 v[16:17], s[8:9], v16, s1, v[56:57]
	v_mad_i64_i32 v[18:19], s[8:9], v18, s1, v[56:57]
	v_mad_i64_i32 v[24:25], s[8:9], v24, s1, v[56:57]
	v_mad_i64_i32 v[26:27], s[8:9], v26, s1, v[56:57]
	v_mad_i64_i32 v[32:33], s[8:9], v32, s1, v[56:57]
	v_mad_i64_i32 v[34:35], s[8:9], v34, s1, v[56:57]
	v_mad_i64_i32 v[40:41], s[8:9], v40, s1, v[56:57]
	v_mad_i64_i32 v[42:43], s[8:9], v42, s1, v[56:57]
	v_mad_i64_i32 v[48:49], s[8:9], v48, s1, v[56:57]
	v_mad_i64_i32 v[50:51], s[8:9], v50, s1, v[56:57]
	v_mad_i64_i32 v[60:61], s[8:9], v60, s1, v[56:57]
	v_mad_i64_i32 v[56:57], s[8:9], v62, s1, v[56:57]
	v_lshl_add_u64 v[4:5], v[2:3], 0, v[58:59]
	v_lshl_add_u64 v[8:9], v[8:9], 0, v[58:59]
	v_lshl_add_u64 v[12:13], v[10:11], 0, v[58:59]
	v_lshl_add_u64 v[16:17], v[16:17], 0, v[58:59]
	v_lshl_add_u64 v[20:21], v[18:19], 0, v[58:59]
	v_lshl_add_u64 v[24:25], v[24:25], 0, v[58:59]
	v_lshl_add_u64 v[28:29], v[26:27], 0, v[58:59]
	v_lshl_add_u64 v[32:33], v[32:33], 0, v[58:59]
	v_lshl_add_u64 v[36:37], v[34:35], 0, v[58:59]
	v_lshl_add_u64 v[40:41], v[40:41], 0, v[58:59]
	v_lshl_add_u64 v[44:45], v[42:43], 0, v[58:59]
	v_lshl_add_u64 v[48:49], v[48:49], 0, v[58:59]
	v_lshl_add_u64 v[52:53], v[50:51], 0, v[58:59]
	v_lshl_add_u64 v[60:61], v[60:61], 0, v[58:59]
	v_lshl_add_u64 v[62:63], v[56:57], 0, v[58:59]
	global_load_dwordx4 v[0:3], v[0:1], off
	s_nop 0
	global_load_dwordx4 v[4:7], v[4:5], off
	s_nop 0
	global_load_dwordx4 v[8:11], v[8:9], off
	s_nop 0
	global_load_dwordx4 v[12:15], v[12:13], off
	s_nop 0
	global_load_dwordx4 v[16:19], v[16:17], off
	s_nop 0
	global_load_dwordx4 v[20:23], v[20:21], off
	s_nop 0
	global_load_dwordx4 v[24:27], v[24:25], off
	s_nop 0
	global_load_dwordx4 v[28:31], v[28:29], off
	s_nop 0
	global_load_dwordx4 v[32:35], v[32:33], off
	s_nop 0
	global_load_dwordx4 v[36:39], v[36:37], off
	s_nop 0
	global_load_dwordx4 v[40:43], v[40:41], off
	s_nop 0
	global_load_dwordx4 v[44:47], v[44:45], off
	s_nop 0
	global_load_dwordx4 v[48:51], v[48:49], off
	s_nop 0
	global_load_dwordx4 v[52:55], v[52:53], off
	s_nop 0
	global_load_dwordx4 v[56:59], v[60:61], off
	global_load_dwordx4 v[60:63], v[62:63], off

.LBB0_1849:
	v_lshlrev_b64 v[170:171], 2, v[154:155]
	v_lshl_add_u32 v166, s22, 8, v156
	v_ashrrev_i32_e32 v167, 31, v166
	v_readlane_b32 s52, v240, 22
	v_lshlrev_b64 v[162:163], 13, v[166:167]
	v_readlane_b32 s56, v240, 26
	v_readlane_b32 s57, v240, 27
	s_waitcnt vmcnt(0)
	v_pk_add_f32 v[128:129], v[128:129], v[136:137]
	v_lshl_add_u64 v[162:163], s[56:57], 0, v[162:163]
	v_lshl_add_u64 v[154:155], v[162:163], 0, v[170:171]
	global_load_dwordx4 v[172:175], v[154:155], off
	v_pk_add_f32 v[126:127], v[126:127], v[134:135]
	v_pk_add_f32 v[124:125], v[124:125], v[136:137]
	v_pk_add_f32 v[122:123], v[122:123], v[134:135]
	v_pk_add_f32 v[120:121], v[120:121], v[136:137]
	v_pk_add_f32 v[118:119], v[118:119], v[134:135]
	s_mov_b32 s15, 0x100000
	v_pk_add_f32 v[114:115], v[114:115], v[136:137]
	v_pk_add_f32 v[112:113], v[112:113], v[134:135]
	v_pk_add_f32 v[108:109], v[108:109], v[134:135]
	v_pk_add_f32 v[110:111], v[110:111], v[136:137]
	v_pk_add_f32 v[104:105], v[104:105], v[134:135]
	v_pk_add_f32 v[106:107], v[106:107], v[136:137]
	v_pk_add_f32 v[100:101], v[100:101], v[134:135]
	v_pk_add_f32 v[102:103], v[102:103], v[136:137]
	v_pk_add_f32 v[98:99], v[98:99], v[136:137]
	v_pk_add_f32 v[96:97], v[96:97], v[134:135]
	v_readlane_b32 s53, v240, 23
	v_readlane_b32 s60, v240, 30
	v_readlane_b32 s61, v240, 31
	v_readlane_b32 s62, v240, 32
	v_readlane_b32 s63, v240, 33
	v_readlane_b32 s66, v240, 36
	v_readlane_b32 s67, v240, 37
	v_mov_b32_e32 v117, 0
	v_readlane_b32 s54, v240, 24
	v_readlane_b32 s55, v240, 25
	v_readlane_b32 s58, v240, 28
	v_readlane_b32 s59, v240, 29
	v_readlane_b32 s64, v240, 34
	v_readlane_b32 s65, v240, 35
	s_waitcnt vmcnt(0)
	v_pk_fma_f32 v[128:129], v[132:133], v[128:129], v[174:175]
	v_pk_fma_f32 v[126:127], v[130:131], v[126:127], v[172:173]
	global_store_dwordx4 v[154:155], v[126:129], off
	s_nop 1
	v_or_b32_e32 v126, 16, v166
	v_ashrrev_i32_e32 v127, 31, v126
	v_lshlrev_b64 v[126:127], 13, v[126:127]
	v_lshl_add_u64 v[126:127], s[56:57], 0, v[126:127]
	v_lshl_add_u64 v[126:127], v[126:127], 0, v[170:171]
	global_load_dwordx4 v[172:175], v[126:127], off
	s_waitcnt vmcnt(0)
	v_pk_fma_f32 v[124:125], v[132:133], v[124:125], v[174:175]
	v_pk_fma_f32 v[122:123], v[130:131], v[122:123], v[172:173]
	global_store_dwordx4 v[126:127], v[122:125], off
	s_nop 1
	v_or_b32_e32 v122, 32, v166
	v_ashrrev_i32_e32 v123, 31, v122
	v_lshlrev_b64 v[122:123], 13, v[122:123]
	v_lshl_add_u64 v[122:123], s[56:57], 0, v[122:123]
	v_lshl_add_u64 v[122:123], v[122:123], 0, v[170:171]
	global_load_dwordx4 v[172:175], v[122:123], off
	s_waitcnt vmcnt(0)
	v_pk_fma_f32 v[120:121], v[132:133], v[120:121], v[174:175]
	v_pk_fma_f32 v[118:119], v[130:131], v[118:119], v[172:173]
	global_store_dwordx4 v[122:123], v[118:121], off
	s_nop 1
	v_or_b32_e32 v118, 48, v166
	v_ashrrev_i32_e32 v119, 31, v118
	v_lshlrev_b64 v[118:119], 13, v[118:119]
	v_lshl_add_u64 v[118:119], s[56:57], 0, v[118:119]
	v_lshl_add_u64 v[120:121], v[118:119], 0, v[170:171]
	global_load_dwordx4 v[172:175], v[120:121], off
	v_add_co_u32_e32 v118, vcc, s15, v154
	s_mov_b32 s15, 0x120000
	s_nop 0
	v_addc_co_u32_e32 v119, vcc, 0, v155, vcc
	global_load_dwordx4 v[176:179], v[118:119], off
	s_waitcnt vmcnt(1)
	v_pk_fma_f32 v[114:115], v[132:133], v[114:115], v[174:175]
	v_pk_fma_f32 v[112:113], v[130:131], v[112:113], v[172:173]
	global_store_dwordx4 v[120:121], v[112:115], off
	s_waitcnt vmcnt(1)
	v_pk_fma_f32 v[108:109], v[130:131], v[108:109], v[176:177]
	v_add_co_u32_e32 v112, vcc, s15, v154
	v_pk_fma_f32 v[110:111], v[132:133], v[110:111], v[178:179]
	s_nop 0
	v_addc_co_u32_e32 v113, vcc, 0, v155, vcc
	global_load_dwordx4 v[172:175], v[112:113], off
	global_store_dwordx4 v[118:119], v[108:111], off
	s_mov_b32 s15, 0x140000
	s_nop 0
	v_mov_b32_e32 v118, 0
	v_mov_b32_e32 v119, 0
	s_waitcnt vmcnt(1)
	v_pk_fma_f32 v[104:105], v[130:131], v[104:105], v[172:173]
	v_add_co_u32_e32 v108, vcc, s15, v154
	v_pk_fma_f32 v[106:107], v[132:133], v[106:107], v[174:175]
	s_nop 0
	v_addc_co_u32_e32 v109, vcc, 0, v155, vcc
	global_load_dwordx4 v[172:175], v[108:109], off
	global_store_dwordx4 v[112:113], v[104:107], off
	s_mov_b32 s15, 0x160000
	s_waitcnt vmcnt(1)
	v_pk_fma_f32 v[100:101], v[130:131], v[100:101], v[172:173]
	v_add_co_u32_e32 v104, vcc, s15, v154
	v_pk_fma_f32 v[102:103], v[132:133], v[102:103], v[174:175]
	s_nop 0
	v_addc_co_u32_e32 v105, vcc, 0, v155, vcc
	global_load_dwordx4 v[172:175], v[104:105], off
	global_store_dwordx4 v[108:109], v[100:103], off
	s_and_b64 vcc, exec, s[8:9]
	s_waitcnt vmcnt(1)
	v_pk_fma_f32 v[98:99], v[132:133], v[98:99], v[174:175]
	v_pk_fma_f32 v[96:97], v[130:131], v[96:97], v[172:173]
	global_store_dwordx4 v[104:105], v[96:99], off
	s_nop 0
	global_load_dwordx4 v[96:99], v[150:151], off offset:64
	s_cbranch_vccnz .LBB0_1851
	global_load_dwordx4 v[116:119], v[152:153], off offset:64
.LBB0_1851:
	global_load_dwordx4 v[172:175], v[154:155], off offset:64
	s_waitcnt vmcnt(1)
	v_pk_add_f32 v[94:95], v[94:95], v[118:119]
	v_pk_add_f32 v[92:93], v[92:93], v[116:117]
	v_pk_add_f32 v[90:91], v[90:91], v[118:119]
	v_pk_add_f32 v[88:89], v[88:89], v[116:117]
	v_pk_add_f32 v[86:87], v[86:87], v[118:119]
	v_pk_add_f32 v[84:85], v[84:85], v[116:117]
	s_mov_b64 s[24:25], 0x100000
	s_nop 0
	v_lshl_add_u64 v[106:107], v[154:155], 0, s[24:25]
	v_pk_add_f32 v[82:83], v[82:83], v[118:119]
	v_pk_add_f32 v[80:81], v[80:81], v[116:117]
	s_mov_b64 s[24:25], 0x120000
	s_nop 0
	v_lshl_add_u64 v[104:105], v[154:155], 0, s[24:25]
	v_pk_add_f32 v[78:79], v[78:79], v[118:119]
	v_pk_add_f32 v[76:77], v[76:77], v[116:117]
	s_mov_b64 s[24:25], 0x140000
	s_nop 0
	v_lshl_add_u64 v[102:103], v[154:155], 0, s[24:25]
	v_pk_add_f32 v[74:75], v[74:75], v[118:119]
	v_pk_add_f32 v[72:73], v[72:73], v[116:117]
	s_mov_b64 s[24:25], 0x160000
	s_nop 0
	v_lshl_add_u64 v[100:101], v[154:155], 0, s[24:25]
	global_load_dwordx4 v[176:179], v[126:127], off offset:64
	global_load_dwordx4 v[180:183], v[122:123], off offset:64
	global_load_dwordx4 v[184:187], v[120:121], off offset:64
	global_load_dwordx4 v[188:191], v[106:107], off offset:64
	global_load_dwordx4 v[192:195], v[104:105], off offset:64
	global_load_dwordx4 v[196:199], v[102:103], off offset:64
	global_load_dwordx4 v[200:203], v[100:101], off offset:64
	v_pk_add_f32 v[70:71], v[70:71], v[118:119]
	v_pk_add_f32 v[68:69], v[68:69], v[116:117]
	v_pk_add_f32 v[66:67], v[66:67], v[118:119]
	v_pk_add_f32 v[64:65], v[64:65], v[116:117]
	s_and_b64 vcc, exec, s[8:9]
	v_readlane_b32 s94, v239, 1
	s_waitcnt vmcnt(7)
	v_pk_fma_f32 v[94:95], v[98:99], v[94:95], v[174:175]
	v_pk_fma_f32 v[92:93], v[96:97], v[92:93], v[172:173]
	global_store_dwordx4 v[154:155], v[92:95], off offset:64
	s_waitcnt vmcnt(7)
	v_pk_fma_f32 v[90:91], v[98:99], v[90:91], v[178:179]
	v_pk_fma_f32 v[88:89], v[96:97], v[88:89], v[176:177]
	global_store_dwordx4 v[126:127], v[88:91], off offset:64
	s_waitcnt vmcnt(7)
	v_pk_fma_f32 v[86:87], v[98:99], v[86:87], v[182:183]
	v_pk_fma_f32 v[84:85], v[96:97], v[84:85], v[180:181]
	global_store_dwordx4 v[122:123], v[84:87], off offset:64
	s_waitcnt vmcnt(7)
	v_pk_fma_f32 v[82:83], v[98:99], v[82:83], v[186:187]
	v_pk_fma_f32 v[80:81], v[96:97], v[80:81], v[184:185]
	global_store_dwordx4 v[120:121], v[80:83], off offset:64
	s_waitcnt vmcnt(7)
	v_pk_fma_f32 v[78:79], v[98:99], v[78:79], v[190:191]
	v_pk_fma_f32 v[76:77], v[96:97], v[76:77], v[188:189]
	global_store_dwordx4 v[106:107], v[76:79], off offset:64
	s_waitcnt vmcnt(7)
	v_pk_fma_f32 v[74:75], v[98:99], v[74:75], v[194:195]
	v_pk_fma_f32 v[72:73], v[96:97], v[72:73], v[192:193]
	global_store_dwordx4 v[104:105], v[72:75], off offset:64
	s_waitcnt vmcnt(7)
	v_pk_fma_f32 v[70:71], v[98:99], v[70:71], v[198:199]
	v_pk_fma_f32 v[68:69], v[96:97], v[68:69], v[196:197]
	global_store_dwordx4 v[102:103], v[68:71], off offset:64
	v_mov_b32_e32 v72, 0
	v_mov_b32_e32 v73, 0
	s_waitcnt vmcnt(7)
	v_pk_fma_f32 v[66:67], v[98:99], v[66:67], v[202:203]
	v_pk_fma_f32 v[64:65], v[96:97], v[64:65], v[200:201]
	global_store_dwordx4 v[100:101], v[64:67], off offset:64
	s_nop 0
	global_load_dwordx4 v[66:69], v[150:151], off offset:512
	v_mov_b32_e32 v70, 0
	v_mov_b32_e32 v64, 0
	v_mov_b32_e32 v71, 0
	s_cbranch_vccnz .LBB0_1853
	global_load_dwordx4 v[70:73], v[152:153], off offset:512
.LBB0_1853:
	global_load_dwordx4 v[172:175], v[154:155], off offset:512
	global_load_dwordx4 v[176:179], v[126:127], off offset:512
	global_load_dwordx4 v[180:183], v[122:123], off offset:512
	global_load_dwordx4 v[184:187], v[120:121], off offset:512
	global_load_dwordx4 v[188:191], v[106:107], off offset:512
	global_load_dwordx4 v[192:195], v[104:105], off offset:512
	global_load_dwordx4 v[196:199], v[102:103], off offset:512
	global_load_dwordx4 v[200:203], v[100:101], off offset:512
	s_waitcnt vmcnt(8)
	v_pk_add_f32 v[62:63], v[62:63], v[72:73]
	v_pk_add_f32 v[60:61], v[60:61], v[70:71]
	v_pk_add_f32 v[58:59], v[58:59], v[72:73]
	v_pk_add_f32 v[56:57], v[56:57], v[70:71]
	v_pk_add_f32 v[54:55], v[54:55], v[72:73]
	v_pk_add_f32 v[52:53], v[52:53], v[70:71]
	v_pk_add_f32 v[50:51], v[50:51], v[72:73]
	v_pk_add_f32 v[48:49], v[48:49], v[70:71]
	v_pk_add_f32 v[46:47], v[46:47], v[72:73]
	v_pk_add_f32 v[44:45], v[44:45], v[70:71]
	v_pk_add_f32 v[42:43], v[42:43], v[72:73]
	v_pk_add_f32 v[40:41], v[40:41], v[70:71]
	v_pk_add_f32 v[38:39], v[38:39], v[72:73]
	v_pk_add_f32 v[36:37], v[36:37], v[70:71]
	v_pk_add_f32 v[34:35], v[34:35], v[72:73]
	v_pk_add_f32 v[32:33], v[32:33], v[70:71]
	s_and_b64 vcc, exec, s[8:9]
	v_mov_b32_e32 v65, 0
	s_waitcnt vmcnt(7)
	v_pk_fma_f32 v[62:63], v[68:69], v[62:63], v[174:175]
	v_pk_fma_f32 v[60:61], v[66:67], v[60:61], v[172:173]
	global_store_dwordx4 v[154:155], v[60:63], off offset:512
	s_waitcnt vmcnt(7)
	v_pk_fma_f32 v[58:59], v[68:69], v[58:59], v[178:179]
	v_pk_fma_f32 v[56:57], v[66:67], v[56:57], v[176:177]
	global_store_dwordx4 v[126:127], v[56:59], off offset:512
	s_waitcnt vmcnt(7)
	v_pk_fma_f32 v[54:55], v[68:69], v[54:55], v[182:183]
	v_pk_fma_f32 v[52:53], v[66:67], v[52:53], v[180:181]
	global_store_dwordx4 v[122:123], v[52:55], off offset:512
	s_waitcnt vmcnt(7)
	v_pk_fma_f32 v[50:51], v[68:69], v[50:51], v[186:187]
	v_pk_fma_f32 v[48:49], v[66:67], v[48:49], v[184:185]
	global_store_dwordx4 v[120:121], v[48:51], off offset:512
	s_waitcnt vmcnt(7)
	v_pk_fma_f32 v[46:47], v[68:69], v[46:47], v[190:191]
	v_pk_fma_f32 v[44:45], v[66:67], v[44:45], v[188:189]
	global_store_dwordx4 v[106:107], v[44:47], off offset:512
	s_waitcnt vmcnt(7)
	v_pk_fma_f32 v[42:43], v[68:69], v[42:43], v[194:195]
	v_pk_fma_f32 v[40:41], v[66:67], v[40:41], v[192:193]
	global_store_dwordx4 v[104:105], v[40:43], off offset:512
	s_waitcnt vmcnt(7)
	v_pk_fma_f32 v[38:39], v[68:69], v[38:39], v[198:199]
	v_pk_fma_f32 v[36:37], v[66:67], v[36:37], v[196:197]
	global_store_dwordx4 v[102:103], v[36:39], off offset:512
	s_waitcnt vmcnt(7)
	v_pk_fma_f32 v[34:35], v[68:69], v[34:35], v[202:203]
	v_pk_fma_f32 v[32:33], v[66:67], v[32:33], v[200:201]
	global_store_dwordx4 v[100:101], v[32:35], off offset:512
	s_nop 0
	global_load_dwordx4 v[32:35], v[150:151], off offset:576
	v_mov_b32_e32 v66, 0
	v_mov_b32_e32 v67, 0
	s_cbranch_vccnz .LBB0_1838
	global_load_dwordx4 v[64:67], v[152:153], off offset:576
	s_branch .LBB0_1838

.LBB0_1925:
	global_load_dwordx4 v[28:31], v[88:89], off offset:-4096
	global_load_dwordx4 v[24:27], v[88:89], off offset:-3072
	global_load_dwordx4 v[20:23], v[88:89], off offset:-2048
	global_load_dwordx4 v[16:19], v[88:89], off offset:-1024
	global_load_dwordx4 v[12:15], v[88:89], off
	global_load_dwordx4 v[8:11], v[88:89], off offset:1024
	global_load_dwordx4 v[4:7], v[88:89], off offset:2048
	global_load_dwordx4 v[0:3], v[88:89], off offset:3072
	s_cmpk_lt_i32 s1, 0x2000
	s_cbranch_scc1 .LBB0_1943
	s_add_i32 s18, s1, 0xffffe000
	s_lshl_b64 s[2:3], s[18:19], 13
	v_lshl_add_u64 v[92:93], v[56:57], 0, s[2:3]
	global_load_dwordx4 v[34:37], v[92:93], off
	v_add_co_u32_e32 v32, vcc, 0x400000, v92
	v_mov_b32_e32 v50, 0
	s_waitcnt lgkmcnt(0)
	v_addc_co_u32_e32 v33, vcc, 0, v93, vcc
	global_load_dwordx4 v[38:41], v[32:33], off
	s_nop 0
	v_add_co_u32_e32 v32, vcc, 0x800000, v92
	v_mov_b32_e32 v51, 0
	s_nop 0
	v_addc_co_u32_e32 v33, vcc, 0, v93, vcc
	global_load_dwordx4 v[42:45], v[32:33], off
	v_add_co_u32_e32 v46, vcc, 0xc00000, v92
	v_mov_b32_e32 v52, 0
	s_nop 0
	v_addc_co_u32_e32 v47, vcc, 0, v93, vcc
	global_load_dwordx4 v[46:49], v[46:47], off
	v_cndmask_b32_e64 v33, 0, 1, s[8:9]
	v_mov_b32_e32 v32, 0
	v_cmp_ne_u32_e64 s[6:7], 1, v33
	s_andn2_b64 vcc, exec, s[8:9]
	v_mov_b32_e32 v53, 0
	s_cbranch_vccnz .LBB0_1928
	global_load_dwordx4 v[50:53], v[60:61], off
.LBB0_1928:
	global_load_dwordx4 v[100:103], v[58:59], off
	s_waitcnt vmcnt(1)
	v_pk_add_f32 v[36:37], v[36:37], v[52:53]
	v_pk_add_f32 v[34:35], v[34:35], v[50:51]
	v_pk_add_f32 v[36:37], v[40:41], v[36:37]
	v_pk_add_f32 v[34:35], v[38:39], v[34:35]
	v_pk_add_f32 v[36:37], v[44:45], v[36:37]
	v_pk_add_f32 v[34:35], v[42:43], v[34:35]
	v_pk_add_f32 v[38:39], v[48:49], v[36:37]
	v_pk_add_f32 v[40:41], v[46:47], v[34:35]
	v_mov_b32_e32 v33, 0
	s_waitcnt vmcnt(0)
	v_pk_fma_f32 v[30:31], v[102:103], v[38:39], v[30:31]
	global_load_dwordx4 v[36:39], v[92:93], off offset:1024
	v_pk_fma_f32 v[28:29], v[100:101], v[40:41], v[28:29]
	v_add_co_u32_e32 v34, vcc, 0x400000, v92
	global_store_dwordx4 v[88:89], v[28:31], off offset:-4096
	s_nop 0
	v_addc_co_u32_e32 v35, vcc, 0, v93, vcc
	global_load_dwordx4 v[40:43], v[34:35], off offset:1024
	s_nop 0
	v_add_co_u32_e32 v34, vcc, 0x800000, v92
	s_nop 1
	v_addc_co_u32_e32 v35, vcc, 0, v93, vcc
	global_load_dwordx4 v[44:47], v[34:35], off offset:1024
	v_add_co_u32_e32 v34, vcc, 0xc00000, v92
	s_nop 1
	v_addc_co_u32_e32 v35, vcc, 0, v93, vcc
	global_load_dwordx4 v[48:51], v[34:35], off offset:1024
	s_and_b64 vcc, exec, s[6:7]
	v_mov_b32_e32 v34, 0
	v_mov_b32_e32 v35, 0
	s_cbranch_vccnz .LBB0_1930
	global_load_dwordx4 v[32:35], v[60:61], off offset:1024
.LBB0_1930:
	global_load_dwordx4 v[100:103], v[58:59], off offset:1024
	s_waitcnt vmcnt(1)
	v_pk_add_f32 v[34:35], v[38:39], v[34:35]
	v_pk_add_f32 v[32:33], v[36:37], v[32:33]
	v_pk_add_f32 v[34:35], v[42:43], v[34:35]
	v_pk_add_f32 v[32:33], v[40:41], v[32:33]
	v_pk_add_f32 v[34:35], v[46:47], v[34:35]
	v_pk_add_f32 v[32:33], v[44:45], v[32:33]
	v_pk_add_f32 v[36:37], v[50:51], v[34:35]
	v_pk_add_f32 v[38:39], v[48:49], v[32:33]
	v_mov_b32_e32 v50, 0
	v_mov_b32_e32 v51, 0
	v_mov_b32_e32 v52, 0
	v_mov_b32_e32 v53, 0
	s_waitcnt vmcnt(0)
	v_pk_fma_f32 v[26:27], v[102:103], v[36:37], v[26:27]
	global_load_dwordx4 v[34:37], v[92:93], off offset:2048
	v_pk_fma_f32 v[24:25], v[100:101], v[38:39], v[24:25]
	v_add_co_u32_e32 v32, vcc, 0x400000, v92
	global_store_dwordx4 v[88:89], v[24:27], off offset:-3072
	s_nop 0
	v_addc_co_u32_e32 v33, vcc, 0, v93, vcc
	global_load_dwordx4 v[38:41], v[32:33], off offset:2048
	s_nop 0
	v_add_co_u32_e32 v32, vcc, 0x800000, v92
	s_nop 1
	v_addc_co_u32_e32 v33, vcc, 0, v93, vcc
	global_load_dwordx4 v[42:45], v[32:33], off offset:2048
	v_add_co_u32_e32 v32, vcc, 0xc00000, v92
	s_nop 1
	v_addc_co_u32_e32 v33, vcc, 0, v93, vcc
	global_load_dwordx4 v[46:49], v[32:33], off offset:2048
	v_mov_b32_e32 v32, 0
	s_and_b64 vcc, exec, s[6:7]
	s_cbranch_vccnz .LBB0_1932
	global_load_dwordx4 v[50:53], v[60:61], off offset:2048
.LBB0_1932:
	global_load_dwordx4 v[100:103], v[58:59], off offset:2048
	s_waitcnt vmcnt(1)
	v_pk_add_f32 v[36:37], v[36:37], v[52:53]
	v_pk_add_f32 v[34:35], v[34:35], v[50:51]
	v_pk_add_f32 v[36:37], v[40:41], v[36:37]
	v_pk_add_f32 v[34:35], v[38:39], v[34:35]
	v_pk_add_f32 v[36:37], v[44:45], v[36:37]
	v_pk_add_f32 v[34:35], v[42:43], v[34:35]
	v_pk_add_f32 v[38:39], v[48:49], v[36:37]
	v_pk_add_f32 v[40:41], v[46:47], v[34:35]
	v_mov_b32_e32 v33, 0
	s_waitcnt vmcnt(0)
	v_pk_fma_f32 v[22:23], v[102:103], v[38:39], v[22:23]
	global_load_dwordx4 v[36:39], v[92:93], off offset:3072
	v_pk_fma_f32 v[20:21], v[100:101], v[40:41], v[20:21]
	v_add_co_u32_e32 v34, vcc, 0x400000, v92
	global_store_dwordx4 v[88:89], v[20:23], off offset:-2048
	s_nop 0
	v_addc_co_u32_e32 v35, vcc, 0, v93, vcc
	global_load_dwordx4 v[40:43], v[34:35], off offset:3072
	s_nop 0
	v_add_co_u32_e32 v34, vcc, 0x800000, v92
	s_nop 1
	v_addc_co_u32_e32 v35, vcc, 0, v93, vcc
	global_load_dwordx4 v[44:47], v[34:35], off offset:3072
	v_add_co_u32_e32 v34, vcc, 0xc00000, v92
	s_nop 1
	v_addc_co_u32_e32 v35, vcc, 0, v93, vcc
	global_load_dwordx4 v[48:51], v[34:35], off offset:3072
	s_and_b64 vcc, exec, s[6:7]
	v_mov_b32_e32 v34, 0
	v_mov_b32_e32 v35, 0
	s_cbranch_vccnz .LBB0_1934
	global_load_dwordx4 v[32:35], v[60:61], off offset:3072
.LBB0_1934:
	global_load_dwordx4 v[100:103], v[58:59], off offset:3072
	s_waitcnt vmcnt(1)
	v_pk_add_f32 v[34:35], v[38:39], v[34:35]
	v_pk_add_f32 v[32:33], v[36:37], v[32:33]
	v_pk_add_f32 v[34:35], v[42:43], v[34:35]
	v_pk_add_f32 v[32:33], v[40:41], v[32:33]
	v_pk_add_f32 v[34:35], v[46:47], v[34:35]
	v_pk_add_f32 v[32:33], v[44:45], v[32:33]
	v_pk_add_f32 v[36:37], v[50:51], v[34:35]
	v_pk_add_f32 v[38:39], v[48:49], v[32:33]
	s_movk_i32 s2, 0x1000
	v_add_co_u32_e32 v94, vcc, s2, v92
	v_mov_b32_e32 v50, 0
	s_nop 0
	v_addc_co_u32_e32 v95, vcc, 0, v93, vcc
	v_mov_b32_e32 v51, 0
	v_mov_b32_e32 v52, 0
	v_mov_b32_e32 v53, 0
	s_waitcnt vmcnt(0)
	v_pk_fma_f32 v[18:19], v[102:103], v[36:37], v[18:19]
	global_load_dwordx4 v[34:37], v[94:95], off
	v_pk_fma_f32 v[16:17], v[100:101], v[38:39], v[16:17]
	v_add_co_u32_e32 v32, vcc, 0x401000, v92
	global_store_dwordx4 v[88:89], v[16:19], off offset:-1024
	s_nop 0
	v_addc_co_u32_e32 v33, vcc, 0, v93, vcc
	global_load_dwordx4 v[38:41], v[32:33], off
	s_nop 0
	v_add_co_u32_e32 v32, vcc, 0x801000, v92
	s_nop 1
	v_addc_co_u32_e32 v33, vcc, 0, v93, vcc
	global_load_dwordx4 v[42:45], v[32:33], off
	v_add_co_u32_e32 v32, vcc, 0xc01000, v92
	s_nop 1
	v_addc_co_u32_e32 v33, vcc, 0, v93, vcc
	global_load_dwordx4 v[46:49], v[32:33], off
	v_mov_b32_e32 v32, 0
	s_and_b64 vcc, exec, s[6:7]
	s_cbranch_vccnz .LBB0_1936
	global_load_dwordx4 v[50:53], v[64:65], off
.LBB0_1936:
	global_load_dwordx4 v[100:103], v[66:67], off
	s_waitcnt vmcnt(1)
	v_pk_add_f32 v[36:37], v[36:37], v[52:53]
	v_pk_add_f32 v[34:35], v[34:35], v[50:51]
	v_pk_add_f32 v[36:37], v[40:41], v[36:37]
	v_pk_add_f32 v[34:35], v[38:39], v[34:35]
	v_pk_add_f32 v[36:37], v[44:45], v[36:37]
	v_pk_add_f32 v[34:35], v[42:43], v[34:35]
	v_pk_add_f32 v[38:39], v[48:49], v[36:37]
	v_pk_add_f32 v[40:41], v[46:47], v[34:35]
	v_mov_b32_e32 v33, 0
	s_waitcnt vmcnt(0)
	v_pk_fma_f32 v[14:15], v[102:103], v[38:39], v[14:15]
	global_load_dwordx4 v[36:39], v[94:95], off offset:1024
	v_pk_fma_f32 v[12:13], v[100:101], v[40:41], v[12:13]
	v_add_co_u32_e32 v34, vcc, 0x401000, v92
	global_store_dwordx4 v[88:89], v[12:15], off
	s_nop 0
	v_addc_co_u32_e32 v35, vcc, 0, v93, vcc
	global_load_dwordx4 v[40:43], v[34:35], off offset:1024
	s_nop 0
	v_add_co_u32_e32 v34, vcc, 0x801000, v92
	s_nop 1
	v_addc_co_u32_e32 v35, vcc, 0, v93, vcc
	global_load_dwordx4 v[44:47], v[34:35], off offset:1024
	v_add_co_u32_e32 v34, vcc, 0xc01000, v92
	s_nop 1
	v_addc_co_u32_e32 v35, vcc, 0, v93, vcc
	global_load_dwordx4 v[48:51], v[34:35], off offset:1024
	s_and_b64 vcc, exec, s[6:7]
	v_mov_b32_e32 v34, 0
	v_mov_b32_e32 v35, 0
	s_cbranch_vccnz .LBB0_1938
	global_load_dwordx4 v[32:35], v[68:69], off
.LBB0_1938:
	global_load_dwordx4 v[100:103], v[70:71], off
	s_waitcnt vmcnt(1)
	v_pk_add_f32 v[34:35], v[38:39], v[34:35]
	v_pk_add_f32 v[32:33], v[36:37], v[32:33]
	v_pk_add_f32 v[34:35], v[42:43], v[34:35]
	v_pk_add_f32 v[32:33], v[40:41], v[32:33]
	v_pk_add_f32 v[34:35], v[46:47], v[34:35]
	v_pk_add_f32 v[32:33], v[44:45], v[32:33]
	v_pk_add_f32 v[36:37], v[50:51], v[34:35]
	v_pk_add_f32 v[38:39], v[48:49], v[32:33]
	v_mov_b32_e32 v50, 0
	v_mov_b32_e32 v51, 0
	v_mov_b32_e32 v52, 0
	v_mov_b32_e32 v53, 0
	s_waitcnt vmcnt(0)
	v_pk_fma_f32 v[10:11], v[102:103], v[36:37], v[10:11]
	global_load_dwordx4 v[34:37], v[94:95], off offset:2048
	v_pk_fma_f32 v[8:9], v[100:101], v[38:39], v[8:9]
	v_add_co_u32_e32 v32, vcc, 0x401000, v92
	global_store_dwordx4 v[88:89], v[8:11], off offset:1024
	s_nop 0
	v_addc_co_u32_e32 v33, vcc, 0, v93, vcc
	global_load_dwordx4 v[38:41], v[32:33], off offset:2048
	s_nop 0
	v_add_co_u32_e32 v32, vcc, 0x801000, v92
	s_nop 1
	v_addc_co_u32_e32 v33, vcc, 0, v93, vcc
	global_load_dwordx4 v[42:45], v[32:33], off offset:2048
	v_add_co_u32_e32 v32, vcc, 0xc01000, v92
	s_nop 1
	v_addc_co_u32_e32 v33, vcc, 0, v93, vcc
	global_load_dwordx4 v[46:49], v[32:33], off offset:2048
	v_mov_b32_e32 v32, 0
	s_and_b64 vcc, exec, s[6:7]
	s_cbranch_vccnz .LBB0_1940
	global_load_dwordx4 v[50:53], v[72:73], off
.LBB0_1940:
	global_load_dwordx4 v[100:103], v[74:75], off
	s_waitcnt vmcnt(1)
	v_pk_add_f32 v[36:37], v[36:37], v[52:53]
	v_pk_add_f32 v[34:35], v[34:35], v[50:51]
	v_pk_add_f32 v[36:37], v[40:41], v[36:37]
	v_pk_add_f32 v[34:35], v[38:39], v[34:35]
	v_pk_add_f32 v[36:37], v[44:45], v[36:37]
	v_pk_add_f32 v[34:35], v[42:43], v[34:35]
	v_pk_add_f32 v[38:39], v[48:49], v[36:37]
	v_pk_add_f32 v[40:41], v[46:47], v[34:35]
	v_mov_b32_e32 v33, 0
	s_waitcnt vmcnt(0)
	v_pk_fma_f32 v[6:7], v[102:103], v[38:39], v[6:7]
	global_load_dwordx4 v[36:39], v[94:95], off offset:3072
	v_pk_fma_f32 v[4:5], v[100:101], v[40:41], v[4:5]
	v_add_co_u32_e32 v34, vcc, 0x401000, v92
	global_store_dwordx4 v[88:89], v[4:7], off offset:2048
	s_nop 0
	v_addc_co_u32_e32 v35, vcc, 0, v93, vcc
	global_load_dwordx4 v[40:43], v[34:35], off offset:3072
	s_nop 0
	v_add_co_u32_e32 v34, vcc, 0x801000, v92
	s_nop 1
	v_addc_co_u32_e32 v35, vcc, 0, v93, vcc
	global_load_dwordx4 v[44:47], v[34:35], off offset:3072
	v_add_co_u32_e32 v34, vcc, 0xc01000, v92
	s_nop 1
	v_addc_co_u32_e32 v35, vcc, 0, v93, vcc
	global_load_dwordx4 v[48:51], v[34:35], off offset:3072
	s_and_b64 vcc, exec, s[6:7]
	v_mov_b32_e32 v34, 0
	v_mov_b32_e32 v35, 0
	s_cbranch_vccnz .LBB0_1942
	global_load_dwordx4 v[32:35], v[76:77], off

.LBB0_1943:
	s_waitcnt vmcnt(7)
	v_mul_f32_e32 v32, v29, v29
	s_waitcnt vmcnt(6) lgkmcnt(0)
	v_mul_f32_e32 v33, v25, v25
	v_fmac_f32_e32 v32, v28, v28
	v_fmac_f32_e32 v33, v24, v24
	v_fmac_f32_e32 v32, v30, v30
	v_fmac_f32_e32 v33, v26, v26
	v_fmac_f32_e32 v32, v31, v31
	v_fmac_f32_e32 v33, v27, v27
	v_add_f32_e32 v32, v32, v33
	s_waitcnt vmcnt(5)
	v_mul_f32_e32 v33, v21, v21
	v_fmac_f32_e32 v33, v20, v20
	v_fmac_f32_e32 v33, v22, v22
	v_fmac_f32_e32 v33, v23, v23
	v_add_f32_e32 v32, v33, v32
	s_waitcnt vmcnt(4)
	v_mul_f32_e32 v33, v17, v17
	v_fmac_f32_e32 v33, v16, v16
	v_fmac_f32_e32 v33, v18, v18
	v_fmac_f32_e32 v33, v19, v19
	v_add_f32_e32 v32, v33, v32
	s_waitcnt vmcnt(3)
	v_mul_f32_e32 v33, v13, v13
	v_fmac_f32_e32 v33, v12, v12
	v_fmac_f32_e32 v33, v14, v14
	v_fmac_f32_e32 v33, v15, v15
	v_add_f32_e32 v32, v33, v32
	s_waitcnt vmcnt(2)
	v_mul_f32_e32 v33, v9, v9
	v_fmac_f32_e32 v33, v8, v8
	v_fmac_f32_e32 v33, v10, v10
	v_fmac_f32_e32 v33, v11, v11
	v_add_f32_e32 v32, v33, v32
	s_waitcnt vmcnt(1)
	v_mul_f32_e32 v33, v5, v5
	v_fmac_f32_e32 v33, v4, v4
	v_fmac_f32_e32 v33, v6, v6
	v_fmac_f32_e32 v33, v7, v7
	v_add_f32_e32 v32, v33, v32
	s_waitcnt vmcnt(0)
	v_mul_f32_e32 v33, v1, v1
	v_fmac_f32_e32 v33, v0, v0
	v_fmac_f32_e32 v33, v2, v2
	v_fmac_f32_e32 v33, v3, v3
	v_add_f32_e32 v32, v33, v32
	v_mbcnt_lo_u32_b32 v33, -1, 0
	v_mbcnt_hi_u32_b32 v33, -1, v33
	s_andn2_b64 vcc, exec, s[12:13]
	v_lshlrev_b32_e32 v33, 2, v33
	v_xor_b32_e32 v34, 0x80, v33
	ds_bpermute_b32 v34, v34, v32
	s_waitcnt lgkmcnt(0)
	v_add_f32_e32 v32, v32, v34
	v_xor_b32_e32 v34, 64, v33
	ds_bpermute_b32 v34, v34, v32
	s_waitcnt lgkmcnt(0)
	v_add_f32_e32 v32, v32, v34
	v_xor_b32_e32 v34, 32, v33
	ds_bpermute_b32 v34, v34, v32
	s_waitcnt lgkmcnt(0)
	v_add_f32_e32 v32, v32, v34
	v_xor_b32_e32 v34, 16, v33
	ds_bpermute_b32 v34, v34, v32
	s_waitcnt lgkmcnt(0)
	v_add_f32_e32 v32, v32, v34
	v_xor_b32_e32 v34, 8, v33
	ds_bpermute_b32 v34, v34, v32
	v_xor_b32_e32 v33, 4, v33
	s_waitcnt lgkmcnt(0)
	v_add_f32_e32 v32, v32, v34
	ds_bpermute_b32 v33, v33, v32
	s_cbranch_vccnz .LBB0_1924
	s_ashr_i32 s2, s1, 31
	s_lshr_b32 s2, s2, 20
	s_add_i32 s2, s1, s2
	s_ashr_i32 s2, s2, 12
	s_cmpk_lt_i32 s1, 0x2000
	s_cselect_b32 s2, s2, 2
	s_mul_hi_i32 s3, s2, 0xc000
	s_mul_i32 s2, s2, 0xc000
	s_add_u32 s2, s4, s2
	s_addc_u32 s3, s5, s3
	v_lshl_add_u64 v[98:99], v[54:55], 2, s[2:3]
	s_mov_b32 s2, 0x9000
	v_add_co_u32_e32 v48, vcc, s2, v98
	s_movk_i32 s2, 0x7000
	s_nop 0
	v_addc_co_u32_e32 v49, vcc, 0, v99, vcc
	global_load_dwordx4 v[100:103], v[48:49], off offset:-4096
	global_load_dwordx4 v[104:107], v[62:63], off
	v_add_co_u32_e32 v50, vcc, s2, v98
	s_nop 1
	v_addc_co_u32_e32 v51, vcc, 0, v99, vcc
	global_load_dwordx4 v[108:111], v[50:51], off offset:-4096
	s_waitcnt lgkmcnt(0)
	v_add_f32_e32 v32, v32, v33
	v_fmamk_f32 v32, v32, 0x3a000000, v96
	s_mov_b32 s2, 0x800000
	v_mul_f32_e32 v33, 0x4b800000, v32
	v_cmp_gt_f32_e32 vcc, s2, v32
	s_mov_b64 s[2:3], 0x8000
	v_lshl_add_u64 v[112:113], v[98:99], 0, s[2:3]
	global_load_dwordx4 v[116:119], v[112:113], off offset:1024
	global_load_dwordx4 v[120:123], v[62:63], off offset:1024
	v_lshl_add_u64 v[114:115], v[98:99], 0, s[10:11]
	global_load_dwordx4 v[124:127], v[114:115], off offset:1024
	global_load_dwordx4 v[128:131], v[112:113], off offset:2048
	global_load_dwordx4 v[132:135], v[62:63], off offset:2048
	global_load_dwordx4 v[136:139], v[114:115], off offset:2048
	global_load_dwordx4 v[140:143], v[112:113], off offset:3072
	global_load_dwordx4 v[144:147], v[62:63], off offset:3072
	global_load_dwordx4 v[148:151], v[114:115], off offset:3072
	global_load_dwordx4 v[152:155], v[48:49], off
	global_load_dwordx4 v[156:159], v[80:81], off
	global_load_dwordx4 v[160:163], v[50:51], off
	global_load_dwordx4 v[164:167], v[48:49], off offset:1024
	global_load_dwordx4 v[168:171], v[82:83], off
	global_load_dwordx4 v[172:175], v[50:51], off offset:1024
	global_load_dwordx4 v[176:179], v[48:49], off offset:2048
	global_load_dwordx4 v[180:183], v[84:85], off
	global_load_dwordx4 v[184:187], v[50:51], off offset:2048
	global_load_dwordx4 v[188:191], v[48:49], off offset:3072
	global_load_dwordx4 v[192:195], v[86:87], off
	global_load_dwordx4 v[196:199], v[50:51], off offset:3072
	v_cndmask_b32_e32 v32, v32, v33, vcc
	v_rsq_f32_e32 v32, v32
	s_nop 0
	v_mul_f32_e32 v33, 0x45800000, v32
	v_cndmask_b32_e32 v52, v32, v33, vcc
	v_pk_mul_f32 v[28:29], v[28:29], v[52:53] op_sel_hi:[1,0]
	v_pk_mul_f32 v[30:31], v[30:31], v[52:53] op_sel_hi:[1,0]
	v_pk_mul_f32 v[24:25], v[24:25], v[52:53] op_sel_hi:[1,0]
	v_pk_mul_f32 v[26:27], v[26:27], v[52:53] op_sel_hi:[1,0]
	v_pk_mul_f32 v[20:21], v[20:21], v[52:53] op_sel_hi:[1,0]
	v_pk_mul_f32 v[22:23], v[22:23], v[52:53] op_sel_hi:[1,0]
	v_pk_mul_f32 v[16:17], v[16:17], v[52:53] op_sel_hi:[1,0]
	v_pk_mul_f32 v[18:19], v[18:19], v[52:53] op_sel_hi:[1,0]
	v_pk_mul_f32 v[12:13], v[12:13], v[52:53] op_sel_hi:[1,0]
	v_pk_mul_f32 v[14:15], v[14:15], v[52:53] op_sel_hi:[1,0]
	v_pk_mul_f32 v[8:9], v[8:9], v[52:53] op_sel_hi:[1,0]
	v_pk_mul_f32 v[10:11], v[10:11], v[52:53] op_sel_hi:[1,0]
	v_pk_mul_f32 v[4:5], v[4:5], v[52:53] op_sel_hi:[1,0]
	v_pk_mul_f32 v[6:7], v[6:7], v[52:53] op_sel_hi:[1,0]
	v_pk_mul_f32 v[0:1], v[0:1], v[52:53] op_sel_hi:[1,0]
	v_pk_mul_f32 v[2:3], v[2:3], v[52:53] op_sel_hi:[1,0]
	s_waitcnt vmcnt(24)
	s_waitcnt vmcnt(23)
	v_pk_add_f32 v[32:33], v[100:101], 1.0 op_sel_hi:[1,0]
	s_waitcnt vmcnt(22)
	v_pk_mul_f32 v[28:29], v[28:29], v[104:105]
	v_pk_mul_f32 v[30:31], v[30:31], v[106:107]
	v_pk_add_f32 v[34:35], v[102:103], 1.0 op_sel_hi:[1,0]
	s_waitcnt vmcnt(21)
	v_pk_fma_f32 v[28:29], v[32:33], v[28:29], v[108:109]
	v_pk_fma_f32 v[30:31], v[34:35], v[30:31], v[110:111]
	v_cvt_pk_bf16_f32 v28, v28, v29
	v_cvt_pk_bf16_f32 v29, v30, v31
	global_store_dwordx2 v[90:91], v[28:29], off offset:-2048
	s_waitcnt vmcnt(21)
	s_nop 0
	v_pk_add_f32 v[28:29], v[116:117], 1.0 op_sel_hi:[1,0]
	s_waitcnt vmcnt(20)
	v_pk_mul_f32 v[24:25], v[24:25], v[120:121]
	v_pk_add_f32 v[30:31], v[118:119], 1.0 op_sel_hi:[1,0]
	v_pk_mul_f32 v[26:27], v[26:27], v[122:123]
	s_waitcnt vmcnt(19)
	v_pk_fma_f32 v[24:25], v[28:29], v[24:25], v[124:125]
	v_pk_fma_f32 v[26:27], v[30:31], v[26:27], v[126:127]
	v_cvt_pk_bf16_f32 v24, v24, v25
	v_cvt_pk_bf16_f32 v25, v26, v27
	global_store_dwordx2 v[90:91], v[24:25], off offset:-1536
	s_waitcnt vmcnt(19)
	s_nop 0
	v_pk_add_f32 v[24:25], v[128:129], 1.0 op_sel_hi:[1,0]
	s_waitcnt vmcnt(18)
	v_pk_mul_f32 v[20:21], v[20:21], v[132:133]
	v_pk_add_f32 v[26:27], v[130:131], 1.0 op_sel_hi:[1,0]
	v_pk_mul_f32 v[22:23], v[22:23], v[134:135]
	s_waitcnt vmcnt(17)
	v_pk_fma_f32 v[20:21], v[24:25], v[20:21], v[136:137]
	v_pk_fma_f32 v[22:23], v[26:27], v[22:23], v[138:139]
	v_cvt_pk_bf16_f32 v20, v20, v21
	v_cvt_pk_bf16_f32 v21, v22, v23
	global_store_dwordx2 v[90:91], v[20:21], off offset:-1024
	s_waitcnt vmcnt(17)
	s_nop 0
	v_pk_add_f32 v[20:21], v[140:141], 1.0 op_sel_hi:[1,0]
	s_waitcnt vmcnt(16)
	v_pk_mul_f32 v[16:17], v[16:17], v[144:145]
	v_pk_add_f32 v[22:23], v[142:143], 1.0 op_sel_hi:[1,0]
	v_pk_mul_f32 v[18:19], v[18:19], v[146:147]
	s_waitcnt vmcnt(15)
	v_pk_fma_f32 v[16:17], v[20:21], v[16:17], v[148:149]
	v_pk_fma_f32 v[18:19], v[22:23], v[18:19], v[150:151]
	v_cvt_pk_bf16_f32 v16, v16, v17
	v_cvt_pk_bf16_f32 v17, v18, v19
	global_store_dwordx2 v[90:91], v[16:17], off offset:-512
	s_waitcnt vmcnt(15)
	s_nop 0
	v_pk_add_f32 v[16:17], v[152:153], 1.0 op_sel_hi:[1,0]
	s_waitcnt vmcnt(14)
	v_pk_mul_f32 v[12:13], v[12:13], v[156:157]
	v_pk_add_f32 v[18:19], v[154:155], 1.0 op_sel_hi:[1,0]
	v_pk_mul_f32 v[14:15], v[14:15], v[158:159]
	s_waitcnt vmcnt(13)
	v_pk_fma_f32 v[12:13], v[16:17], v[12:13], v[160:161]
	v_pk_fma_f32 v[14:15], v[18:19], v[14:15], v[162:163]
	v_cvt_pk_bf16_f32 v12, v12, v13
	v_cvt_pk_bf16_f32 v13, v14, v15
	global_store_dwordx2 v[90:91], v[12:13], off
	s_waitcnt vmcnt(13)
	s_nop 0
	v_pk_add_f32 v[12:13], v[164:165], 1.0 op_sel_hi:[1,0]
	s_waitcnt vmcnt(12)
	v_pk_mul_f32 v[8:9], v[8:9], v[168:169]
	v_pk_add_f32 v[14:15], v[166:167], 1.0 op_sel_hi:[1,0]
	v_pk_mul_f32 v[10:11], v[10:11], v[170:171]
	s_waitcnt vmcnt(11)
	v_pk_fma_f32 v[8:9], v[12:13], v[8:9], v[172:173]
	v_pk_fma_f32 v[10:11], v[14:15], v[10:11], v[174:175]
	v_cvt_pk_bf16_f32 v8, v8, v9
	v_cvt_pk_bf16_f32 v9, v10, v11
	global_store_dwordx2 v[90:91], v[8:9], off offset:512
	s_waitcnt vmcnt(11)
	s_nop 0
	v_pk_add_f32 v[8:9], v[176:177], 1.0 op_sel_hi:[1,0]
	s_waitcnt vmcnt(10)
	v_pk_mul_f32 v[4:5], v[4:5], v[180:181]
	v_pk_add_f32 v[10:11], v[178:179], 1.0 op_sel_hi:[1,0]
	v_pk_mul_f32 v[6:7], v[6:7], v[182:183]
	s_waitcnt vmcnt(9)
	v_pk_fma_f32 v[4:5], v[8:9], v[4:5], v[184:185]
	v_pk_fma_f32 v[6:7], v[10:11], v[6:7], v[186:187]
	v_cvt_pk_bf16_f32 v4, v4, v5
	v_cvt_pk_bf16_f32 v5, v6, v7
	global_store_dwordx2 v[90:91], v[4:5], off offset:1024
	s_waitcnt vmcnt(9)
	s_nop 0
	v_pk_add_f32 v[4:5], v[188:189], 1.0 op_sel_hi:[1,0]
	s_waitcnt vmcnt(8)
	v_pk_mul_f32 v[0:1], v[0:1], v[192:193]
	v_pk_add_f32 v[6:7], v[190:191], 1.0 op_sel_hi:[1,0]
	v_pk_mul_f32 v[2:3], v[2:3], v[194:195]
	s_waitcnt vmcnt(7)
	v_pk_fma_f32 v[0:1], v[4:5], v[0:1], v[196:197]
	v_pk_fma_f32 v[2:3], v[6:7], v[2:3], v[198:199]
	v_cvt_pk_bf16_f32 v0, v0, v1
	v_cvt_pk_bf16_f32 v1, v2, v3
	global_store_dwordx2 v[90:91], v[0:1], off offset:1536
	s_branch .LBB0_1924

.LBB0_2157:
	global_load_dwordx4 v[28:31], v[80:81], off offset:-4096
	global_load_dwordx4 v[24:27], v[80:81], off offset:-3072
	global_load_dwordx4 v[20:23], v[80:81], off offset:-2048
	global_load_dwordx4 v[16:19], v[80:81], off offset:-1024
	global_load_dwordx4 v[12:15], v[80:81], off
	global_load_dwordx4 v[8:11], v[80:81], off offset:1024
	global_load_dwordx4 v[4:7], v[80:81], off offset:2048
	global_load_dwordx4 v[0:3], v[80:81], off offset:3072
	s_cmpk_lt_i32 s2, 0x2000
	s_cbranch_scc1 .LBB0_2159
	s_add_i32 s16, s2, 0xffffe000
	s_lshl_b64 s[4:5], s[16:17], 13
	v_lshl_add_u64 v[128:129], v[58:59], 0, s[4:5]
	global_load_dwordx4 v[132:135], v[128:129], off
	v_add_co_u32_e32 v32, vcc, 0x400000, v128
	s_nop 1
	v_addc_co_u32_e32 v33, vcc, 0, v129, vcc
	global_load_dwordx4 v[136:139], v[32:33], off
	v_add_co_u32_e32 v34, vcc, 0x800000, v128
	s_waitcnt lgkmcnt(0)
	s_nop 0
	v_addc_co_u32_e32 v35, vcc, 0, v129, vcc
	global_load_dwordx4 v[140:143], v[34:35], off
	v_add_co_u32_e32 v36, vcc, 0xc00000, v128
	s_nop 1
	v_addc_co_u32_e32 v37, vcc, 0, v129, vcc
	global_load_dwordx4 v[144:147], v[36:37], off
	v_add_co_u32_e32 v38, vcc, 0x1000000, v128
	s_nop 1
	v_addc_co_u32_e32 v39, vcc, 0, v129, vcc
	global_load_dwordx4 v[148:151], v[38:39], off
	v_add_co_u32_e32 v40, vcc, 0x1400000, v128
	s_nop 1
	v_addc_co_u32_e32 v41, vcc, 0, v129, vcc
	global_load_dwordx4 v[152:155], v[40:41], off
	v_add_co_u32_e32 v42, vcc, 0x1800000, v128
	s_nop 1
	v_addc_co_u32_e32 v43, vcc, 0, v129, vcc
	global_load_dwordx4 v[156:159], v[42:43], off
	v_add_co_u32_e32 v44, vcc, 0x1c00000, v128
	s_nop 1
	v_addc_co_u32_e32 v45, vcc, 0, v129, vcc
	global_load_dwordx4 v[160:163], v[44:45], off
	v_add_co_u32_e32 v46, vcc, 0x2000000, v128
	s_nop 1
	v_addc_co_u32_e32 v47, vcc, 0, v129, vcc
	global_load_dwordx4 v[164:167], v[46:47], off
	v_add_co_u32_e32 v48, vcc, 0x2400000, v128
	s_nop 1
	v_addc_co_u32_e32 v49, vcc, 0, v129, vcc
	global_load_dwordx4 v[168:171], v[48:49], off
	v_add_co_u32_e32 v50, vcc, 0x2800000, v128
	s_nop 1
	v_addc_co_u32_e32 v51, vcc, 0, v129, vcc
	global_load_dwordx4 v[172:175], v[50:51], off
	global_load_dwordx4 v[176:179], v[60:61], off
	global_load_dwordx4 v[180:183], v[128:129], off offset:1024
	global_load_dwordx4 v[184:187], v[32:33], off offset:1024
	global_load_dwordx4 v[188:191], v[34:35], off offset:1024
	global_load_dwordx4 v[192:195], v[36:37], off offset:1024
	global_load_dwordx4 v[196:199], v[38:39], off offset:1024
	global_load_dwordx4 v[200:203], v[40:41], off offset:1024
	global_load_dwordx4 v[204:207], v[42:43], off offset:1024
	global_load_dwordx4 v[208:211], v[44:45], off offset:1024
	global_load_dwordx4 v[212:215], v[46:47], off offset:1024
	global_load_dwordx4 v[216:219], v[48:49], off offset:1024
	global_load_dwordx4 v[220:223], v[50:51], off offset:1024
	global_load_dwordx4 v[224:227], v[60:61], off offset:1024
	global_load_dwordx4 v[228:231], v[128:129], off offset:2048
	global_load_dwordx4 v[232:235], v[32:33], off offset:2048
	s_mov_b32 s3, 0x401000
	s_waitcnt vmcnt(26)
	s_waitcnt vmcnt(25)
	v_pk_add_f32 v[54:55], v[134:135], 0 op_sel_hi:[1,0]
	v_pk_add_f32 v[52:53], v[132:133], 0 op_sel_hi:[1,0]
	global_load_dwordx4 v[132:135], v[34:35], off offset:2048
	s_waitcnt vmcnt(25)
	v_pk_add_f32 v[54:55], v[54:55], v[138:139]
	v_pk_add_f32 v[52:53], v[52:53], v[136:137]
	global_load_dwordx4 v[136:139], v[36:37], off offset:2048
	s_waitcnt vmcnt(25)
	v_pk_add_f32 v[54:55], v[54:55], v[142:143]
	v_pk_add_f32 v[52:53], v[52:53], v[140:141]
	global_load_dwordx4 v[140:143], v[38:39], off offset:2048
	s_waitcnt vmcnt(25)
	v_pk_add_f32 v[54:55], v[54:55], v[146:147]
	v_pk_add_f32 v[52:53], v[52:53], v[144:145]
	global_load_dwordx4 v[144:147], v[40:41], off offset:2048
	s_waitcnt vmcnt(25)
	v_pk_add_f32 v[54:55], v[54:55], v[150:151]
	v_pk_add_f32 v[52:53], v[52:53], v[148:149]
	global_load_dwordx4 v[148:151], v[42:43], off offset:2048
	s_waitcnt vmcnt(25)
	v_pk_add_f32 v[54:55], v[54:55], v[154:155]
	v_pk_add_f32 v[52:53], v[52:53], v[152:153]
	global_load_dwordx4 v[152:155], v[44:45], off offset:2048
	s_waitcnt vmcnt(25)
	v_pk_add_f32 v[54:55], v[54:55], v[158:159]
	v_pk_add_f32 v[52:53], v[52:53], v[156:157]
	global_load_dwordx4 v[156:159], v[46:47], off offset:2048
	s_waitcnt vmcnt(25)
	v_pk_add_f32 v[54:55], v[54:55], v[162:163]
	v_pk_add_f32 v[52:53], v[52:53], v[160:161]
	global_load_dwordx4 v[160:163], v[48:49], off offset:2048
	s_waitcnt vmcnt(25)
	v_pk_add_f32 v[54:55], v[54:55], v[166:167]
	v_pk_add_f32 v[52:53], v[52:53], v[164:165]
	global_load_dwordx4 v[164:167], v[50:51], off offset:2048
	s_waitcnt vmcnt(25)
	v_pk_add_f32 v[54:55], v[54:55], v[170:171]
	v_pk_add_f32 v[52:53], v[52:53], v[168:169]
	global_load_dwordx4 v[168:171], v[60:61], off offset:2048
	s_waitcnt vmcnt(25)
	v_pk_add_f32 v[86:87], v[54:55], v[174:175]
	v_pk_add_f32 v[88:89], v[52:53], v[172:173]
	global_load_dwordx4 v[172:175], v[128:129], off offset:3072
	s_waitcnt vmcnt(25)
	v_pk_fma_f32 v[30:31], v[86:87], v[178:179], v[30:31]
	v_pk_fma_f32 v[28:29], v[88:89], v[176:177], v[28:29]
	global_load_dwordx4 v[176:179], v[32:33], off offset:3072
	global_store_dwordx4 v[80:81], v[28:31], off offset:-4096
	s_waitcnt vmcnt(26)
	v_pk_add_f32 v[54:55], v[182:183], 0 op_sel_hi:[1,0]
	v_pk_add_f32 v[52:53], v[180:181], 0 op_sel_hi:[1,0]
	s_waitcnt vmcnt(25)
	v_pk_add_f32 v[54:55], v[54:55], v[186:187]
	v_pk_add_f32 v[52:53], v[52:53], v[184:185]
	s_waitcnt vmcnt(24)
	v_pk_add_f32 v[54:55], v[54:55], v[190:191]
	v_pk_add_f32 v[52:53], v[52:53], v[188:189]
	s_waitcnt vmcnt(23)
	v_pk_add_f32 v[54:55], v[54:55], v[194:195]
	v_pk_add_f32 v[52:53], v[52:53], v[192:193]
	s_waitcnt vmcnt(22)
	v_pk_add_f32 v[54:55], v[54:55], v[198:199]
	v_pk_add_f32 v[52:53], v[52:53], v[196:197]
	s_waitcnt vmcnt(21)
	v_pk_add_f32 v[54:55], v[54:55], v[202:203]
	v_pk_add_f32 v[52:53], v[52:53], v[200:201]
	s_waitcnt vmcnt(20)
	v_pk_add_f32 v[54:55], v[54:55], v[206:207]
	v_pk_add_f32 v[52:53], v[52:53], v[204:205]
	s_waitcnt vmcnt(19)
	v_pk_add_f32 v[54:55], v[54:55], v[210:211]
	v_pk_add_f32 v[52:53], v[52:53], v[208:209]
	s_waitcnt vmcnt(18)
	v_pk_add_f32 v[54:55], v[54:55], v[214:215]
	v_pk_add_f32 v[52:53], v[52:53], v[212:213]
	s_waitcnt vmcnt(17)
	v_pk_add_f32 v[54:55], v[54:55], v[218:219]
	v_pk_add_f32 v[52:53], v[52:53], v[216:217]
	s_waitcnt vmcnt(16)
	v_pk_add_f32 v[86:87], v[54:55], v[222:223]
	v_pk_add_f32 v[88:89], v[52:53], v[220:221]
	s_waitcnt vmcnt(15)
	v_pk_fma_f32 v[26:27], v[86:87], v[226:227], v[26:27]
	v_pk_fma_f32 v[24:25], v[88:89], v[224:225], v[24:25]
	global_store_dwordx4 v[80:81], v[24:27], off offset:-3072
	s_waitcnt vmcnt(15)
	v_pk_add_f32 v[54:55], v[230:231], 0 op_sel_hi:[1,0]
	v_pk_add_f32 v[52:53], v[228:229], 0 op_sel_hi:[1,0]
	s_waitcnt vmcnt(14)
	v_pk_add_f32 v[54:55], v[54:55], v[234:235]
	v_pk_add_f32 v[52:53], v[52:53], v[232:233]
	s_waitcnt vmcnt(13)
	v_pk_add_f32 v[54:55], v[54:55], v[134:135]
	v_pk_add_f32 v[52:53], v[52:53], v[132:133]
	s_waitcnt vmcnt(12)
	v_pk_add_f32 v[54:55], v[54:55], v[138:139]
	v_pk_add_f32 v[52:53], v[52:53], v[136:137]
	s_waitcnt vmcnt(11)
	v_pk_add_f32 v[54:55], v[54:55], v[142:143]
	v_pk_add_f32 v[52:53], v[52:53], v[140:141]
	s_waitcnt vmcnt(10)
	v_pk_add_f32 v[54:55], v[54:55], v[146:147]
	v_pk_add_f32 v[52:53], v[52:53], v[144:145]
	s_waitcnt vmcnt(9)
	v_pk_add_f32 v[54:55], v[54:55], v[150:151]
	v_pk_add_f32 v[52:53], v[52:53], v[148:149]
	s_waitcnt vmcnt(8)
	v_pk_add_f32 v[54:55], v[54:55], v[154:155]
	v_pk_add_f32 v[52:53], v[52:53], v[152:153]
	s_waitcnt vmcnt(7)
	v_pk_add_f32 v[54:55], v[54:55], v[158:159]
	v_pk_add_f32 v[52:53], v[52:53], v[156:157]
	s_waitcnt vmcnt(6)
	v_pk_add_f32 v[54:55], v[54:55], v[162:163]
	v_pk_add_f32 v[52:53], v[52:53], v[160:161]
	s_waitcnt vmcnt(5)
	v_pk_add_f32 v[86:87], v[54:55], v[166:167]
	v_pk_add_f32 v[88:89], v[52:53], v[164:165]
	s_waitcnt vmcnt(4)
	v_pk_fma_f32 v[22:23], v[86:87], v[170:171], v[22:23]
	v_pk_fma_f32 v[20:21], v[88:89], v[168:169], v[20:21]
	global_store_dwordx4 v[80:81], v[20:23], off offset:-2048
	global_load_dwordx4 v[32:35], v[34:35], off offset:3072
	s_nop 0
	global_load_dwordx4 v[132:135], v[36:37], off offset:3072
	global_load_dwordx4 v[36:39], v[38:39], off offset:3072
	s_nop 0
	global_load_dwordx4 v[136:139], v[40:41], off offset:3072
	global_load_dwordx4 v[40:43], v[42:43], off offset:3072
	s_nop 0
	global_load_dwordx4 v[140:143], v[44:45], off offset:3072
	global_load_dwordx4 v[44:47], v[46:47], off offset:3072
	s_nop 0
	global_load_dwordx4 v[144:147], v[48:49], off offset:3072
	global_load_dwordx4 v[48:51], v[50:51], off offset:3072
	s_nop 0
	global_load_dwordx4 v[148:151], v[60:61], off offset:3072
	s_waitcnt vmcnt(14)
	v_pk_add_f32 v[54:55], v[174:175], 0 op_sel_hi:[1,0]
	v_pk_add_f32 v[52:53], v[172:173], 0 op_sel_hi:[1,0]
	s_waitcnt vmcnt(13)
	v_pk_add_f32 v[54:55], v[54:55], v[178:179]
	v_pk_add_f32 v[52:53], v[52:53], v[176:177]
	s_waitcnt vmcnt(9)
	v_pk_add_f32 v[34:35], v[54:55], v[34:35]
	v_pk_add_f32 v[32:33], v[52:53], v[32:33]
	s_waitcnt vmcnt(8)
	v_pk_add_f32 v[34:35], v[34:35], v[134:135]
	v_pk_add_f32 v[32:33], v[32:33], v[132:133]
	s_waitcnt vmcnt(7)
	v_pk_add_f32 v[34:35], v[34:35], v[38:39]
	v_pk_add_f32 v[32:33], v[32:33], v[36:37]
	s_waitcnt vmcnt(6)
	v_pk_add_f32 v[34:35], v[34:35], v[138:139]
	v_pk_add_f32 v[32:33], v[32:33], v[136:137]
	s_waitcnt vmcnt(5)
	v_pk_add_f32 v[34:35], v[34:35], v[42:43]
	v_pk_add_f32 v[32:33], v[32:33], v[40:41]
	s_waitcnt vmcnt(4)
	v_pk_add_f32 v[34:35], v[34:35], v[142:143]
	v_pk_add_f32 v[32:33], v[32:33], v[140:141]
	s_waitcnt vmcnt(3)
	v_pk_add_f32 v[34:35], v[34:35], v[46:47]
	v_pk_add_f32 v[32:33], v[32:33], v[44:45]
	s_waitcnt vmcnt(2)
	v_pk_add_f32 v[34:35], v[34:35], v[146:147]
	v_pk_add_f32 v[32:33], v[32:33], v[144:145]
	s_waitcnt vmcnt(1)
	v_pk_add_f32 v[36:37], v[34:35], v[50:51]
	v_pk_add_f32 v[38:39], v[32:33], v[48:49]
	v_add_co_u32_e32 v86, vcc, s1, v128
	s_waitcnt vmcnt(0)
	v_pk_fma_f32 v[18:19], v[36:37], v[150:151], v[18:19]
	v_addc_co_u32_e32 v87, vcc, 0, v129, vcc
	global_load_dwordx4 v[132:135], v[86:87], off
	v_add_co_u32_e32 v88, vcc, s3, v128
	s_mov_b32 s3, 0x801000
	s_nop 0
	v_addc_co_u32_e32 v89, vcc, 0, v129, vcc
	global_load_dwordx4 v[136:139], v[88:89], off
	v_add_co_u32_e32 v90, vcc, s3, v128
	s_mov_b32 s3, 0xc01000
	s_nop 0
	v_addc_co_u32_e32 v91, vcc, 0, v129, vcc
	global_load_dwordx4 v[140:143], v[90:91], off
	v_add_co_u32_e32 v92, vcc, s3, v128
	s_mov_b32 s3, 0x1001000
	s_nop 0
	v_addc_co_u32_e32 v93, vcc, 0, v129, vcc
	global_load_dwordx4 v[144:147], v[92:93], off
	v_add_co_u32_e32 v94, vcc, s3, v128
	s_mov_b32 s3, 0x1401000
	s_nop 0
	v_addc_co_u32_e32 v95, vcc, 0, v129, vcc
	global_load_dwordx4 v[152:155], v[94:95], off
	v_pk_fma_f32 v[16:17], v[38:39], v[148:149], v[16:17]
	v_add_co_u32_e32 v96, vcc, s3, v128
	global_store_dwordx4 v[80:81], v[16:19], off offset:-1024
	s_nop 0
	v_addc_co_u32_e32 v97, vcc, 0, v129, vcc
	global_load_dwordx4 v[148:151], v[96:97], off
	s_mov_b32 s3, 0x1801000
	s_nop 0
	v_add_co_u32_e32 v98, vcc, s3, v128
	s_nop 1
	v_addc_co_u32_e32 v99, vcc, 0, v129, vcc
	global_load_dwordx4 v[156:159], v[98:99], off
	s_mov_b32 s3, 0x1c01000
	v_add_co_u32_e32 v100, vcc, s3, v128
	s_nop 1
	v_addc_co_u32_e32 v101, vcc, 0, v129, vcc
	global_load_dwordx4 v[160:163], v[100:101], off
	s_mov_b32 s3, 0x2001000
	v_add_co_u32_e32 v102, vcc, s3, v128
	s_nop 1
	v_addc_co_u32_e32 v103, vcc, 0, v129, vcc
	global_load_dwordx4 v[164:167], v[102:103], off
	s_mov_b32 s3, 0x2401000
	v_add_co_u32_e32 v104, vcc, s3, v128
	s_nop 1
	v_addc_co_u32_e32 v105, vcc, 0, v129, vcc
	global_load_dwordx4 v[168:171], v[104:105], off
	s_mov_b32 s3, 0x2801000
	v_add_co_u32_e32 v84, vcc, s3, v128
	s_nop 1
	v_addc_co_u32_e32 v85, vcc, 0, v129, vcc
	global_load_dwordx4 v[128:131], v[84:85], off
	global_load_dwordx4 v[172:175], v[64:65], off
	global_load_dwordx4 v[176:179], v[86:87], off offset:1024
	global_load_dwordx4 v[180:183], v[88:89], off offset:1024
	global_load_dwordx4 v[184:187], v[90:91], off offset:1024
	global_load_dwordx4 v[188:191], v[92:93], off offset:1024
	global_load_dwordx4 v[192:195], v[94:95], off offset:1024
	global_load_dwordx4 v[196:199], v[96:97], off offset:1024
	global_load_dwordx4 v[200:203], v[98:99], off offset:1024
	global_load_dwordx4 v[204:207], v[100:101], off offset:1024
	global_load_dwordx4 v[208:211], v[102:103], off offset:1024
	global_load_dwordx4 v[212:215], v[104:105], off offset:1024
	global_load_dwordx4 v[216:219], v[84:85], off offset:1024
	global_load_dwordx4 v[220:223], v[66:67], off
	global_load_dwordx4 v[224:227], v[86:87], off offset:2048
	global_load_dwordx4 v[228:231], v[88:89], off offset:2048
	global_load_dwordx4 v[232:235], v[90:91], off offset:2048
	s_waitcnt vmcnt(27)
	v_pk_add_f32 v[34:35], v[134:135], 0 op_sel_hi:[1,0]
	v_pk_add_f32 v[32:33], v[132:133], 0 op_sel_hi:[1,0]
	global_load_dwordx4 v[132:135], v[92:93], off offset:2048
	s_waitcnt vmcnt(27)
	v_pk_add_f32 v[34:35], v[34:35], v[138:139]
	v_pk_add_f32 v[32:33], v[32:33], v[136:137]
	global_load_dwordx4 v[136:139], v[94:95], off offset:2048
	s_waitcnt vmcnt(27)
	v_pk_add_f32 v[34:35], v[34:35], v[142:143]
	v_pk_add_f32 v[32:33], v[32:33], v[140:141]
	global_load_dwordx4 v[140:143], v[96:97], off offset:2048
	s_waitcnt vmcnt(27)
	v_pk_add_f32 v[34:35], v[34:35], v[146:147]
	v_pk_add_f32 v[32:33], v[32:33], v[144:145]
	global_load_dwordx4 v[144:147], v[98:99], off offset:2048
	s_waitcnt vmcnt(27)
	v_pk_add_f32 v[34:35], v[34:35], v[154:155]
	v_pk_add_f32 v[32:33], v[32:33], v[152:153]
	global_load_dwordx4 v[152:155], v[100:101], off offset:2048
	s_waitcnt vmcnt(26)
	v_pk_add_f32 v[34:35], v[34:35], v[150:151]
	v_pk_add_f32 v[32:33], v[32:33], v[148:149]
	global_load_dwordx4 v[148:151], v[102:103], off offset:2048
	s_waitcnt vmcnt(26)
	v_pk_add_f32 v[34:35], v[34:35], v[158:159]
	v_pk_add_f32 v[32:33], v[32:33], v[156:157]
	global_load_dwordx4 v[156:159], v[104:105], off offset:2048
	s_waitcnt vmcnt(26)
	v_pk_add_f32 v[34:35], v[34:35], v[162:163]
	v_pk_add_f32 v[32:33], v[32:33], v[160:161]
	global_load_dwordx4 v[160:163], v[84:85], off offset:2048
	s_waitcnt vmcnt(26)
	v_pk_add_f32 v[34:35], v[34:35], v[166:167]
	v_pk_add_f32 v[32:33], v[32:33], v[164:165]
	global_load_dwordx4 v[164:167], v[68:69], off
	s_waitcnt vmcnt(26)
	v_pk_add_f32 v[34:35], v[34:35], v[170:171]
	v_pk_add_f32 v[32:33], v[32:33], v[168:169]
	global_load_dwordx4 v[168:171], v[86:87], off offset:3072
	s_waitcnt vmcnt(26)
	v_pk_add_f32 v[36:37], v[34:35], v[130:131]
	v_pk_add_f32 v[38:39], v[32:33], v[128:129]
	global_load_dwordx4 v[128:131], v[88:89], off offset:3072
	s_waitcnt vmcnt(26)
	v_pk_fma_f32 v[14:15], v[36:37], v[174:175], v[14:15]
	v_pk_fma_f32 v[12:13], v[38:39], v[172:173], v[12:13]
	global_load_dwordx4 v[172:175], v[90:91], off offset:3072
	global_store_dwordx4 v[80:81], v[12:15], off
	s_waitcnt vmcnt(27)
	v_pk_add_f32 v[34:35], v[178:179], 0 op_sel_hi:[1,0]
	v_pk_add_f32 v[32:33], v[176:177], 0 op_sel_hi:[1,0]
	global_load_dwordx4 v[176:179], v[92:93], off offset:3072
	s_waitcnt vmcnt(27)
	v_pk_add_f32 v[34:35], v[34:35], v[182:183]
	v_pk_add_f32 v[32:33], v[32:33], v[180:181]
	global_load_dwordx4 v[180:183], v[94:95], off offset:3072
	s_waitcnt vmcnt(27)
	v_pk_add_f32 v[34:35], v[34:35], v[186:187]
	v_pk_add_f32 v[32:33], v[32:33], v[184:185]
	global_load_dwordx4 v[184:187], v[96:97], off offset:3072
	s_waitcnt vmcnt(27)
	v_pk_add_f32 v[34:35], v[34:35], v[190:191]
	v_pk_add_f32 v[32:33], v[32:33], v[188:189]
	global_load_dwordx4 v[188:191], v[98:99], off offset:3072
	s_waitcnt vmcnt(27)
	v_pk_add_f32 v[34:35], v[34:35], v[194:195]
	v_pk_add_f32 v[32:33], v[32:33], v[192:193]
	global_load_dwordx4 v[192:195], v[100:101], off offset:3072
	s_waitcnt vmcnt(27)
	v_pk_add_f32 v[34:35], v[34:35], v[198:199]
	v_pk_add_f32 v[32:33], v[32:33], v[196:197]
	global_load_dwordx4 v[196:199], v[102:103], off offset:3072
	s_waitcnt vmcnt(27)
	v_pk_add_f32 v[34:35], v[34:35], v[202:203]
	v_pk_add_f32 v[32:33], v[32:33], v[200:201]
	global_load_dwordx4 v[200:203], v[104:105], off offset:3072
	s_waitcnt vmcnt(27)
	v_pk_add_f32 v[34:35], v[34:35], v[206:207]
	v_pk_add_f32 v[32:33], v[32:33], v[204:205]
	global_load_dwordx4 v[204:207], v[84:85], off offset:3072
	s_waitcnt vmcnt(27)
	v_pk_add_f32 v[34:35], v[34:35], v[210:211]
	v_pk_add_f32 v[32:33], v[32:33], v[208:209]
	global_load_dwordx4 v[208:211], v[70:71], off
	s_waitcnt vmcnt(27)
	v_pk_add_f32 v[34:35], v[34:35], v[214:215]
	v_pk_add_f32 v[32:33], v[32:33], v[212:213]
	s_waitcnt vmcnt(26)
	v_pk_add_f32 v[36:37], v[34:35], v[218:219]
	v_pk_add_f32 v[38:39], v[32:33], v[216:217]
	s_waitcnt vmcnt(25)
	v_pk_fma_f32 v[10:11], v[36:37], v[222:223], v[10:11]
	v_pk_fma_f32 v[8:9], v[38:39], v[220:221], v[8:9]
	global_store_dwordx4 v[80:81], v[8:11], off offset:1024
	s_waitcnt vmcnt(25)
	v_pk_add_f32 v[34:35], v[226:227], 0 op_sel_hi:[1,0]
	v_pk_add_f32 v[32:33], v[224:225], 0 op_sel_hi:[1,0]
	s_waitcnt vmcnt(24)
	v_pk_add_f32 v[34:35], v[34:35], v[230:231]
	v_pk_add_f32 v[32:33], v[32:33], v[228:229]
	s_waitcnt vmcnt(23)
	v_pk_add_f32 v[34:35], v[34:35], v[234:235]
	v_pk_add_f32 v[32:33], v[32:33], v[232:233]
	s_waitcnt vmcnt(22)
	v_pk_add_f32 v[34:35], v[34:35], v[134:135]
	v_pk_add_f32 v[32:33], v[32:33], v[132:133]
	s_waitcnt vmcnt(21)
	v_pk_add_f32 v[34:35], v[34:35], v[138:139]
	v_pk_add_f32 v[32:33], v[32:33], v[136:137]
	s_waitcnt vmcnt(20)
	v_pk_add_f32 v[34:35], v[34:35], v[142:143]
	v_pk_add_f32 v[32:33], v[32:33], v[140:141]
	s_waitcnt vmcnt(19)
	v_pk_add_f32 v[34:35], v[34:35], v[146:147]
	v_pk_add_f32 v[32:33], v[32:33], v[144:145]
	s_waitcnt vmcnt(18)
	v_pk_add_f32 v[34:35], v[34:35], v[154:155]
	v_pk_add_f32 v[32:33], v[32:33], v[152:153]
	s_waitcnt vmcnt(17)
	v_pk_add_f32 v[34:35], v[34:35], v[150:151]
	v_pk_add_f32 v[32:33], v[32:33], v[148:149]
	s_waitcnt vmcnt(16)
	v_pk_add_f32 v[34:35], v[34:35], v[158:159]
	v_pk_add_f32 v[32:33], v[32:33], v[156:157]
	s_waitcnt vmcnt(15)
	v_pk_add_f32 v[36:37], v[34:35], v[162:163]
	v_pk_add_f32 v[38:39], v[32:33], v[160:161]
	s_waitcnt vmcnt(14)
	v_pk_fma_f32 v[6:7], v[36:37], v[166:167], v[6:7]
	v_pk_fma_f32 v[4:5], v[38:39], v[164:165], v[4:5]
	global_store_dwordx4 v[80:81], v[4:7], off offset:2048
	s_waitcnt vmcnt(14)
	v_pk_add_f32 v[34:35], v[170:171], 0 op_sel_hi:[1,0]
	v_pk_add_f32 v[32:33], v[168:169], 0 op_sel_hi:[1,0]
	s_waitcnt vmcnt(13)
	v_pk_add_f32 v[34:35], v[34:35], v[130:131]
	v_pk_add_f32 v[32:33], v[32:33], v[128:129]
	s_waitcnt vmcnt(12)
	v_pk_add_f32 v[34:35], v[34:35], v[174:175]
	v_pk_add_f32 v[32:33], v[32:33], v[172:173]
	s_waitcnt vmcnt(10)
	v_pk_add_f32 v[34:35], v[34:35], v[178:179]
	v_pk_add_f32 v[32:33], v[32:33], v[176:177]
	s_waitcnt vmcnt(9)
	v_pk_add_f32 v[34:35], v[34:35], v[182:183]
	v_pk_add_f32 v[32:33], v[32:33], v[180:181]
	s_waitcnt vmcnt(8)
	v_pk_add_f32 v[34:35], v[34:35], v[186:187]
	v_pk_add_f32 v[32:33], v[32:33], v[184:185]
	s_waitcnt vmcnt(7)
	v_pk_add_f32 v[34:35], v[34:35], v[190:191]
	v_pk_add_f32 v[32:33], v[32:33], v[188:189]
	s_waitcnt vmcnt(6)
	v_pk_add_f32 v[34:35], v[34:35], v[194:195]
	v_pk_add_f32 v[32:33], v[32:33], v[192:193]
	s_waitcnt vmcnt(5)
	v_pk_add_f32 v[34:35], v[34:35], v[198:199]
	v_pk_add_f32 v[32:33], v[32:33], v[196:197]
	s_waitcnt vmcnt(4)
	v_pk_add_f32 v[34:35], v[34:35], v[202:203]
	v_pk_add_f32 v[32:33], v[32:33], v[200:201]
	s_waitcnt vmcnt(3)
	v_pk_add_f32 v[36:37], v[34:35], v[206:207]
	v_pk_add_f32 v[38:39], v[32:33], v[204:205]
	s_waitcnt vmcnt(2)
	v_pk_fma_f32 v[2:3], v[36:37], v[210:211], v[2:3]
	v_pk_fma_f32 v[0:1], v[38:39], v[208:209], v[0:1]
	global_store_dwordx4 v[80:81], v[0:3], off offset:3072
.LBB0_2159:
	s_waitcnt vmcnt(7)
	v_mul_f32_e32 v32, v29, v29
	s_waitcnt vmcnt(6)
	v_mul_f32_e32 v33, v25, v25
	v_fmac_f32_e32 v32, v28, v28
	v_fmac_f32_e32 v33, v24, v24
	v_fmac_f32_e32 v32, v30, v30
	v_fmac_f32_e32 v33, v26, v26
	v_fmac_f32_e32 v32, v31, v31
	v_fmac_f32_e32 v33, v27, v27
	v_add_f32_e32 v32, v32, v33
	s_waitcnt vmcnt(5)
	v_mul_f32_e32 v33, v21, v21
	v_fmac_f32_e32 v33, v20, v20
	v_fmac_f32_e32 v33, v22, v22
	v_fmac_f32_e32 v33, v23, v23
	v_add_f32_e32 v32, v33, v32
	s_waitcnt vmcnt(4)
	v_mul_f32_e32 v33, v17, v17
	v_fmac_f32_e32 v33, v16, v16
	v_fmac_f32_e32 v33, v18, v18
	v_fmac_f32_e32 v33, v19, v19
	v_add_f32_e32 v32, v33, v32
	s_waitcnt vmcnt(3)
	v_mul_f32_e32 v33, v13, v13
	v_fmac_f32_e32 v33, v12, v12
	v_fmac_f32_e32 v33, v14, v14
	v_fmac_f32_e32 v33, v15, v15
	v_add_f32_e32 v32, v33, v32
	s_waitcnt vmcnt(2)
	v_mul_f32_e32 v33, v9, v9
	v_fmac_f32_e32 v33, v8, v8
	v_fmac_f32_e32 v33, v10, v10
	v_fmac_f32_e32 v33, v11, v11
	v_add_f32_e32 v32, v33, v32
	s_waitcnt vmcnt(1)
	v_mul_f32_e32 v33, v5, v5
	v_fmac_f32_e32 v33, v4, v4
	v_fmac_f32_e32 v33, v6, v6
	v_fmac_f32_e32 v33, v7, v7
	v_add_f32_e32 v32, v33, v32
	s_waitcnt vmcnt(0)
	v_mul_f32_e32 v33, v1, v1
	v_fmac_f32_e32 v33, v0, v0
	v_fmac_f32_e32 v33, v2, v2
	v_fmac_f32_e32 v33, v3, v3
	v_add_f32_e32 v32, v33, v32
	v_mbcnt_lo_u32_b32 v33, -1, 0
	v_mbcnt_hi_u32_b32 v33, -1, v33
	s_andn2_b64 vcc, exec, s[10:11]
	v_lshlrev_b32_e32 v33, 2, v33
	s_nop 1
	v_xor_b32_e32 v107, 4, v33
	v_xor_b32_e32 v34, 0x80, v33
	ds_bpermute_b32 v34, v34, v32
	s_waitcnt lgkmcnt(0)
	v_add_f32_e32 v32, v32, v34
	v_xor_b32_e32 v34, 64, v33
	ds_bpermute_b32 v34, v34, v32
	s_waitcnt lgkmcnt(0)
	v_add_f32_e32 v32, v32, v34
	v_xor_b32_e32 v34, 32, v33
	ds_bpermute_b32 v34, v34, v32
	s_waitcnt lgkmcnt(0)
	v_add_f32_e32 v32, v32, v34
	v_xor_b32_e32 v34, 16, v33
	ds_bpermute_b32 v34, v34, v32
	s_waitcnt lgkmcnt(0)
	v_add_f32_e32 v32, v32, v34
	v_xor_b32_e32 v34, 8, v33
	ds_bpermute_b32 v34, v34, v32
	s_waitcnt lgkmcnt(0)
	v_add_f32_e32 v34, v32, v34
	ds_bpermute_b32 v35, v107, v34
	s_cbranch_vccnz .LBB0_2156
	s_ashr_i32 s3, s2, 31
	s_lshr_b32 s3, s3, 20
	s_add_i32 s3, s2, s3
	s_ashr_i32 s3, s3, 12
	s_cmpk_lt_i32 s2, 0x2000
	s_cselect_b32 s3, s3, 2
	s_mul_hi_i32 s5, s3, 0xc000
	s_mul_i32 s3, s3, 0xc000
	s_add_u32 s4, s6, s3
	s_addc_u32 s5, s7, s5
	v_lshl_add_u64 v[128:129], v[56:57], 2, s[4:5]
	global_load_dwordx4 v[132:135], v[62:63], off
	s_movk_i32 s3, 0x3000
	v_add_co_u32_e32 v32, vcc, s3, v128
	s_nop 1
	v_addc_co_u32_e32 v33, vcc, 0, v129, vcc
	global_load_dwordx4 v[136:139], v[32:33], off offset:-4096
	global_load_dwordx4 v[140:143], v[128:129], off
	s_waitcnt lgkmcnt(0)
	v_add_f32_e32 v34, v34, v35
	v_fmamk_f32 v34, v34, 0x3a000000, v106
	s_mov_b32 s3, 0x800000
	v_mul_f32_e32 v35, 0x4b800000, v34
	v_cmp_gt_f32_e32 vcc, s3, v34
	s_mov_b64 s[4:5], 0x2000
	v_lshl_add_u64 v[130:131], v[128:129], 0, s[4:5]
	global_load_dwordx4 v[144:147], v[130:131], off offset:1024
	global_load_dwordx4 v[148:151], v[62:63], off offset:1024
	global_load_dwordx4 v[152:155], v[128:129], off offset:1024
	global_load_dwordx4 v[156:159], v[130:131], off offset:2048
	global_load_dwordx4 v[160:163], v[62:63], off offset:2048
	global_load_dwordx4 v[164:167], v[128:129], off offset:2048
	global_load_dwordx4 v[168:171], v[130:131], off offset:3072
	global_load_dwordx4 v[172:175], v[62:63], off offset:3072
	global_load_dwordx4 v[176:179], v[128:129], off offset:3072
	global_load_dwordx4 v[180:183], v[32:33], off
	global_load_dwordx4 v[184:187], v[72:73], off
	v_cndmask_b32_e32 v34, v34, v35, vcc
	v_rsq_f32_e32 v34, v34
	s_nop 0
	v_mul_f32_e32 v35, 0x45800000, v34
	v_cndmask_b32_e32 v34, v34, v35, vcc
	v_pk_mul_f32 v[28:29], v[28:29], v[34:35] op_sel_hi:[1,0]
	v_pk_mul_f32 v[30:31], v[30:31], v[34:35] op_sel_hi:[1,0]
	v_pk_mul_f32 v[24:25], v[24:25], v[34:35] op_sel_hi:[1,0]
	v_pk_mul_f32 v[26:27], v[26:27], v[34:35] op_sel_hi:[1,0]
	v_pk_mul_f32 v[20:21], v[20:21], v[34:35] op_sel_hi:[1,0]
	v_pk_mul_f32 v[22:23], v[22:23], v[34:35] op_sel_hi:[1,0]
	v_pk_mul_f32 v[16:17], v[16:17], v[34:35] op_sel_hi:[1,0]
	v_pk_mul_f32 v[18:19], v[18:19], v[34:35] op_sel_hi:[1,0]
	v_pk_mul_f32 v[12:13], v[12:13], v[34:35] op_sel_hi:[1,0]
	v_pk_mul_f32 v[14:15], v[14:15], v[34:35] op_sel_hi:[1,0]
	v_pk_mul_f32 v[8:9], v[8:9], v[34:35] op_sel_hi:[1,0]
	v_pk_mul_f32 v[10:11], v[10:11], v[34:35] op_sel_hi:[1,0]
	v_pk_mul_f32 v[4:5], v[4:5], v[34:35] op_sel_hi:[1,0]
	v_pk_mul_f32 v[6:7], v[6:7], v[34:35] op_sel_hi:[1,0]
	v_pk_mul_f32 v[0:1], v[0:1], v[34:35] op_sel_hi:[1,0]
	v_pk_mul_f32 v[2:3], v[2:3], v[34:35] op_sel_hi:[1,0]
	s_waitcnt vmcnt(14)
	s_waitcnt vmcnt(13)
	v_pk_mul_f32 v[28:29], v[28:29], v[132:133]
	v_pk_mul_f32 v[30:31], v[30:31], v[134:135]
	s_waitcnt vmcnt(12)
	v_pk_add_f32 v[36:37], v[136:137], 1.0 op_sel_hi:[1,0]
	v_pk_add_f32 v[38:39], v[138:139], 1.0 op_sel_hi:[1,0]
	s_waitcnt vmcnt(11)
	v_pk_fma_f32 v[28:29], v[36:37], v[28:29], v[140:141]
	v_pk_fma_f32 v[30:31], v[38:39], v[30:31], v[142:143]
	v_cvt_pk_bf16_f32 v28, v28, v29
	v_cvt_pk_bf16_f32 v29, v30, v31
	global_store_dwordx2 v[82:83], v[28:29], off offset:-2048
	s_waitcnt vmcnt(11)
	s_nop 0
	v_pk_add_f32 v[28:29], v[144:145], 1.0 op_sel_hi:[1,0]
	s_waitcnt vmcnt(10)
	v_pk_mul_f32 v[24:25], v[24:25], v[148:149]
	v_pk_add_f32 v[30:31], v[146:147], 1.0 op_sel_hi:[1,0]
	v_pk_mul_f32 v[26:27], v[26:27], v[150:151]
	s_waitcnt vmcnt(9)
	v_pk_fma_f32 v[24:25], v[28:29], v[24:25], v[152:153]
	v_pk_fma_f32 v[26:27], v[30:31], v[26:27], v[154:155]
	v_cvt_pk_bf16_f32 v24, v24, v25
	v_cvt_pk_bf16_f32 v25, v26, v27
	global_store_dwordx2 v[82:83], v[24:25], off offset:-1536
	s_waitcnt vmcnt(9)
	s_nop 0
	v_pk_add_f32 v[24:25], v[156:157], 1.0 op_sel_hi:[1,0]
	s_waitcnt vmcnt(8)
	v_pk_mul_f32 v[20:21], v[20:21], v[160:161]
	v_pk_add_f32 v[26:27], v[158:159], 1.0 op_sel_hi:[1,0]
	v_pk_mul_f32 v[22:23], v[22:23], v[162:163]
	s_waitcnt vmcnt(7)
	v_pk_fma_f32 v[20:21], v[24:25], v[20:21], v[164:165]
	v_pk_fma_f32 v[22:23], v[26:27], v[22:23], v[166:167]
	v_cvt_pk_bf16_f32 v20, v20, v21
	v_cvt_pk_bf16_f32 v21, v22, v23
	global_store_dwordx2 v[82:83], v[20:21], off offset:-1024
	s_waitcnt vmcnt(7)
	s_nop 0
	v_pk_add_f32 v[20:21], v[168:169], 1.0 op_sel_hi:[1,0]
	s_waitcnt vmcnt(6)
	v_pk_mul_f32 v[16:17], v[16:17], v[172:173]
	v_pk_add_f32 v[22:23], v[170:171], 1.0 op_sel_hi:[1,0]
	v_pk_mul_f32 v[18:19], v[18:19], v[174:175]
	s_waitcnt vmcnt(5)
	v_pk_fma_f32 v[16:17], v[20:21], v[16:17], v[176:177]
	v_pk_fma_f32 v[18:19], v[22:23], v[18:19], v[178:179]
	v_cvt_pk_bf16_f32 v16, v16, v17
	v_cvt_pk_bf16_f32 v17, v18, v19
	global_store_dwordx2 v[82:83], v[16:17], off offset:-512
	v_add_co_u32_e32 v28, vcc, s1, v128
	s_nop 1
	v_addc_co_u32_e32 v29, vcc, 0, v129, vcc
	global_load_dwordx4 v[128:131], v[28:29], off
	global_load_dwordx4 v[132:135], v[32:33], off offset:1024
	global_load_dwordx4 v[136:139], v[74:75], off
	global_load_dwordx4 v[140:143], v[28:29], off offset:1024
	global_load_dwordx4 v[144:147], v[32:33], off offset:2048
	global_load_dwordx4 v[148:151], v[76:77], off
	global_load_dwordx4 v[152:155], v[28:29], off offset:2048
	global_load_dwordx4 v[156:159], v[32:33], off offset:3072
	global_load_dwordx4 v[160:163], v[78:79], off
	global_load_dwordx4 v[164:167], v[28:29], off offset:3072
	s_waitcnt vmcnt(15)
	v_pk_add_f32 v[16:17], v[180:181], 1.0 op_sel_hi:[1,0]
	s_waitcnt vmcnt(14)
	v_pk_mul_f32 v[12:13], v[12:13], v[184:185]
	v_pk_add_f32 v[18:19], v[182:183], 1.0 op_sel_hi:[1,0]
	v_pk_mul_f32 v[14:15], v[14:15], v[186:187]
	s_waitcnt vmcnt(9)
	v_pk_fma_f32 v[12:13], v[16:17], v[12:13], v[128:129]
	v_pk_fma_f32 v[14:15], v[18:19], v[14:15], v[130:131]
	v_cvt_pk_bf16_f32 v12, v12, v13
	v_cvt_pk_bf16_f32 v13, v14, v15
	global_store_dwordx2 v[82:83], v[12:13], off
	s_waitcnt vmcnt(9)
	s_nop 0
	v_pk_add_f32 v[12:13], v[132:133], 1.0 op_sel_hi:[1,0]
	s_waitcnt vmcnt(8)
	v_pk_mul_f32 v[8:9], v[8:9], v[136:137]
	v_pk_add_f32 v[14:15], v[134:135], 1.0 op_sel_hi:[1,0]
	v_pk_mul_f32 v[10:11], v[10:11], v[138:139]
	s_waitcnt vmcnt(7)
	v_pk_fma_f32 v[8:9], v[12:13], v[8:9], v[140:141]
	v_pk_fma_f32 v[10:11], v[14:15], v[10:11], v[142:143]
	v_cvt_pk_bf16_f32 v8, v8, v9
	v_cvt_pk_bf16_f32 v9, v10, v11
	global_store_dwordx2 v[82:83], v[8:9], off offset:512
	s_waitcnt vmcnt(7)
	s_nop 0
	v_pk_add_f32 v[8:9], v[144:145], 1.0 op_sel_hi:[1,0]
	s_waitcnt vmcnt(6)
	v_pk_mul_f32 v[4:5], v[4:5], v[148:149]
	v_pk_add_f32 v[10:11], v[146:147], 1.0 op_sel_hi:[1,0]
	v_pk_mul_f32 v[6:7], v[6:7], v[150:151]
	s_waitcnt vmcnt(5)
	v_pk_fma_f32 v[4:5], v[8:9], v[4:5], v[152:153]
	v_pk_fma_f32 v[6:7], v[10:11], v[6:7], v[154:155]
	v_cvt_pk_bf16_f32 v4, v4, v5
	v_cvt_pk_bf16_f32 v5, v6, v7
	global_store_dwordx2 v[82:83], v[4:5], off offset:1024
	s_waitcnt vmcnt(5)
	s_nop 0
	v_pk_add_f32 v[4:5], v[156:157], 1.0 op_sel_hi:[1,0]
	s_waitcnt vmcnt(4)
	v_pk_mul_f32 v[0:1], v[0:1], v[160:161]
	v_pk_add_f32 v[6:7], v[158:159], 1.0 op_sel_hi:[1,0]
	v_pk_mul_f32 v[2:3], v[2:3], v[162:163]
	s_waitcnt vmcnt(3)
	v_pk_fma_f32 v[0:1], v[4:5], v[0:1], v[164:165]
	v_pk_fma_f32 v[2:3], v[6:7], v[2:3], v[166:167]
	v_cvt_pk_bf16_f32 v0, v0, v1
	v_cvt_pk_bf16_f32 v1, v2, v3
	global_store_dwordx2 v[82:83], v[0:1], off offset:1536
	s_branch .LBB0_2156

.LBB0_2165:
	s_add_i32 s3, s4, s33
	s_cmpk_gt_i32 s3, 0x31f
	s_cselect_b64 s[10:11], -1, 0
	v_add_u32_e32 v66, v89, v90
	s_and_b64 vcc, exec, s[10:11]
	s_barrier
	s_waitcnt vmcnt(15)
	ds_write_b128 v66, v[0:3]
	s_waitcnt vmcnt(14)
	ds_write_b128 v66, v[4:7] offset:8256
	s_waitcnt vmcnt(13)
	ds_write_b128 v66, v[8:11] offset:16512
	s_waitcnt vmcnt(12)
	ds_write_b128 v66, v[12:15] offset:24768
	s_waitcnt vmcnt(11)
	ds_write_b128 v66, v[16:19] offset:33024
	s_waitcnt vmcnt(10)
	ds_write_b128 v66, v[20:23] offset:41280
	s_waitcnt vmcnt(9)
	ds_write_b128 v93, v[24:27]
	s_waitcnt vmcnt(8)
	ds_write_b128 v93, v[28:31] offset:8256
	s_waitcnt vmcnt(7)
	ds_write_b128 v93, v[32:35] offset:16512
	s_waitcnt vmcnt(6)
	ds_write_b128 v93, v[36:39] offset:24768
	s_waitcnt vmcnt(5)
	ds_write_b128 v93, v[40:43] offset:33024
	s_waitcnt vmcnt(4)
	ds_write_b128 v93, v[44:47] offset:41280
	s_waitcnt vmcnt(3)
	ds_write_b128 v93, v[48:51] offset:49536
	s_waitcnt vmcnt(2)
	ds_write_b128 v93, v[52:55] offset:57792
	s_waitcnt vmcnt(1)
	ds_write_b128 v94, v[56:59] offset:57792
	s_waitcnt vmcnt(0)
	ds_write_b128 v95, v[60:63] offset:57792
	s_waitcnt lgkmcnt(0)
	s_barrier
	s_cbranch_vccnz .LBB0_2167
	s_mul_hi_i32 s5, s3, 0x51eb851f
	s_lshr_b32 s12, s5, 31
	s_ashr_i32 s5, s5, 3
	s_add_i32 s5, s5, s12
	s_lshl_b32 s14, s5, 6
	s_mul_i32 s5, s5, 25
	s_sub_i32 s5, s3, s5
	v_lshl_or_b32 v0, s5, 9, v73
	v_cmp_gt_i32_e32 vcc, s1, v0
	v_readlane_b32 s16, v239, 35
	v_readlane_b32 s24, v239, 43
	v_cndmask_b32_e32 v0, 0, v0, vcc
	v_readlane_b32 s25, v239, 44
	v_ashrrev_i32_e32 v1, 31, v0
	v_add_u32_e32 v2, s14, v72
	v_mov_b64_e32 v[56:57], s[24:25]
	v_mad_i64_i32 v[2:3], s[12:13], v2, s2, v[56:57]
	v_lshlrev_b64 v[58:59], 2, v[0:1]
	v_lshl_add_u64 v[0:1], v[2:3], 0, v[58:59]
	v_add_u32_e32 v2, s14, v74
	v_add_u32_e32 v8, s14, v75
	v_add_u32_e32 v10, s14, v76
	v_add_u32_e32 v16, s14, v77
	v_add_u32_e32 v18, s14, v78
	v_add_u32_e32 v24, s14, v79
	v_add_u32_e32 v26, s14, v80
	v_add_u32_e32 v32, s14, v81
	v_add_u32_e32 v34, s14, v82
	v_add_u32_e32 v40, s14, v83
	v_add_u32_e32 v42, s14, v84
	v_add_u32_e32 v48, s14, v85
	v_add_u32_e32 v50, s14, v86
	v_add_u32_e32 v60, s14, v87
	v_add_u32_e32 v62, s14, v88
	v_mad_i64_i32 v[2:3], s[12:13], v2, s2, v[56:57]
	v_mad_i64_i32 v[8:9], s[12:13], v8, s2, v[56:57]
	v_mad_i64_i32 v[10:11], s[12:13], v10, s2, v[56:57]
	v_mad_i64_i32 v[16:17], s[12:13], v16, s2, v[56:57]
	v_mad_i64_i32 v[18:19], s[12:13], v18, s2, v[56:57]
	v_mad_i64_i32 v[24:25], s[12:13], v24, s2, v[56:57]
	v_mad_i64_i32 v[26:27], s[12:13], v26, s2, v[56:57]
	v_mad_i64_i32 v[32:33], s[12:13], v32, s2, v[56:57]
	v_mad_i64_i32 v[34:35], s[12:13], v34, s2, v[56:57]
	v_mad_i64_i32 v[40:41], s[12:13], v40, s2, v[56:57]
	v_mad_i64_i32 v[42:43], s[12:13], v42, s2, v[56:57]
	v_mad_i64_i32 v[48:49], s[12:13], v48, s2, v[56:57]
	v_mad_i64_i32 v[50:51], s[12:13], v50, s2, v[56:57]
	v_mad_i64_i32 v[60:61], s[12:13], v60, s2, v[56:57]
	v_mad_i64_i32 v[56:57], s[12:13], v62, s2, v[56:57]
	v_lshl_add_u64 v[4:5], v[2:3], 0, v[58:59]
	v_lshl_add_u64 v[8:9], v[8:9], 0, v[58:59]
	v_lshl_add_u64 v[12:13], v[10:11], 0, v[58:59]
	v_lshl_add_u64 v[16:17], v[16:17], 0, v[58:59]
	v_lshl_add_u64 v[20:21], v[18:19], 0, v[58:59]
	v_lshl_add_u64 v[24:25], v[24:25], 0, v[58:59]
	v_lshl_add_u64 v[28:29], v[26:27], 0, v[58:59]
	v_lshl_add_u64 v[32:33], v[32:33], 0, v[58:59]
	v_lshl_add_u64 v[36:37], v[34:35], 0, v[58:59]
	v_lshl_add_u64 v[40:41], v[40:41], 0, v[58:59]
	v_lshl_add_u64 v[44:45], v[42:43], 0, v[58:59]
	v_lshl_add_u64 v[48:49], v[48:49], 0, v[58:59]
	v_lshl_add_u64 v[52:53], v[50:51], 0, v[58:59]
	v_lshl_add_u64 v[60:61], v[60:61], 0, v[58:59]
	v_lshl_add_u64 v[62:63], v[56:57], 0, v[58:59]
	global_load_dwordx4 v[0:3], v[0:1], off
	s_nop 0
	global_load_dwordx4 v[4:7], v[4:5], off
	s_nop 0
	global_load_dwordx4 v[8:11], v[8:9], off
	s_nop 0
	global_load_dwordx4 v[12:15], v[12:13], off
	s_nop 0
	global_load_dwordx4 v[16:19], v[16:17], off
	s_nop 0
	global_load_dwordx4 v[20:23], v[20:21], off
	s_nop 0
	global_load_dwordx4 v[24:27], v[24:25], off
	s_nop 0
	global_load_dwordx4 v[28:31], v[28:29], off
	s_nop 0
	global_load_dwordx4 v[32:35], v[32:33], off
	s_nop 0
	global_load_dwordx4 v[36:39], v[36:37], off
	s_nop 0
	global_load_dwordx4 v[40:43], v[40:41], off
	s_nop 0
	global_load_dwordx4 v[44:47], v[44:45], off
	s_nop 0
	global_load_dwordx4 v[48:51], v[48:49], off
	s_nop 0
	global_load_dwordx4 v[52:55], v[52:53], off
	s_nop 0
	global_load_dwordx4 v[56:59], v[60:61], off
	global_load_dwordx4 v[60:63], v[62:63], off
	v_readlane_b32 s17, v239, 36
	v_readlane_b32 s18, v239, 37
	v_readlane_b32 s19, v239, 38
	v_readlane_b32 s20, v239, 39
	v_readlane_b32 s21, v239, 40
	v_readlane_b32 s22, v239, 41
	v_readlane_b32 s23, v239, 42
	v_readlane_b32 s26, v239, 45
	v_readlane_b32 s27, v239, 46
	v_readlane_b32 s28, v239, 47
	v_readlane_b32 s29, v239, 48
	v_readlane_b32 s30, v239, 49
	v_readlane_b32 s31, v239, 50

.LBB0_2395:
	s_add_i32 s2, s12, 2
	v_med3_i32 v80, s2, 2, v212
	v_mul_lo_u32 v86, v80, s3
	v_lshl_add_u64 v[80:81], s[60:61], 0, v[86:87]
	v_lshl_add_u64 v[106:107], v[80:81], 0, v[88:89]
	s_add_i32 s13, s12, 3
	v_add_co_u32_e32 v80, vcc, 0xffff4000, v106
	v_med3_i32 v86, s13, 2, v212
	s_nop 0
	v_addc_co_u32_e32 v81, vcc, -1, v107, vcc
	v_mul_lo_u32 v86, v86, s3
	v_add_co_u32_e32 v106, vcc, 0xffff6000, v106
	v_lshl_add_u64 v[110:111], s[60:61], 0, v[86:87]
	s_max_i32 s34, s2, -1
	v_addc_co_u32_e32 v107, vcc, -1, v107, vcc
	v_lshl_add_u64 v[114:115], v[110:111], 0, v[88:89]
	s_add_i32 s23, s12, 4
	s_add_i32 s34, s34, 3
	v_add_co_u32_e32 v110, vcc, s4, v114
	v_med3_i32 v86, s23, 2, v212
	s_min_u32 s34, s34, 0x2201
	v_addc_co_u32_e32 v111, vcc, -1, v115, vcc
	v_mul_lo_u32 v86, v86, s3
	s_mulk_i32 s34, 0x6000
	v_add_co_u32_e32 v114, vcc, s5, v114
	v_lshl_add_u64 v[118:119], s[60:61], 0, v[86:87]
	s_add_u32 s34, s60, s34
	v_addc_co_u32_e32 v115, vcc, -1, v115, vcc
	v_lshl_add_u64 v[122:123], v[118:119], 0, v[88:89]
	s_addc_u32 s35, s61, 0
	v_add_co_u32_e32 v118, vcc, s4, v122
	v_lshl_add_u64 v[130:131], s[34:35], 0, v[88:89]
	s_max_i32 s34, s2, -2
	v_addc_co_u32_e32 v119, vcc, -1, v123, vcc
	s_add_i32 s34, s34, 4
	v_add_co_u32_e32 v122, vcc, s5, v122
	s_min_u32 s34, s34, 0x2201
	s_nop 0
	v_addc_co_u32_e32 v123, vcc, -1, v123, vcc
	s_mulk_i32 s34, 0x6000
	v_add_co_u32_e32 v126, vcc, s4, v130
	s_add_u32 s34, s60, s34
	s_nop 0
	v_addc_co_u32_e32 v127, vcc, -1, v131, vcc
	s_addc_u32 s35, s61, 0
	v_add_co_u32_e32 v130, vcc, s5, v130
	v_lshl_add_u64 v[134:135], s[34:35], 0, v[88:89]
	s_max_i32 s34, s2, -3
	v_addc_co_u32_e32 v131, vcc, -1, v131, vcc
	s_add_i32 s34, s34, 5
	v_add_co_u32_e32 v136, vcc, s4, v134
	s_min_u32 s34, s34, 0x2201
	s_nop 0
	v_addc_co_u32_e32 v137, vcc, -1, v135, vcc
	global_load_dwordx4 v[220:223], v[136:137], off
	s_mulk_i32 s34, 0x6000
	v_add_co_u32_e32 v134, vcc, s5, v134
	s_add_u32 s34, s60, s34
	s_nop 0
	v_addc_co_u32_e32 v135, vcc, -1, v135, vcc
	global_load_dwordx4 v[224:227], v[134:135], off
	s_addc_u32 s35, s61, 0
	s_nop 0
	v_lshl_add_u64 v[134:135], s[34:35], 0, v[88:89]
	v_add_co_u32_e32 v136, vcc, s4, v134
	global_load_dwordx4 v[80:83], v[80:81], off
	s_nop 0
	v_addc_co_u32_e32 v137, vcc, -1, v135, vcc
	v_add_co_u32_e32 v134, vcc, s5, v134
	global_load_dwordx4 v[106:109], v[106:107], off
	s_nop 0
	v_addc_co_u32_e32 v135, vcc, -1, v135, vcc
	global_load_dwordx4 v[110:113], v[110:111], off
	s_cmpk_lt_i32 s2, 0x2000
	global_load_dwordx4 v[114:117], v[114:115], off
	s_cselect_b32 s34, s27, 0x7fffff00
	global_load_dwordx4 v[118:121], v[118:119], off
	s_cselect_b32 s35, s30, 0xff
	global_load_dwordx4 v[122:125], v[122:123], off
	s_and_b32 s40, s34, s2
	global_load_dwordx4 v[126:129], v[126:127], off
	s_or_b32 s41, s35, s2
	global_load_dwordx4 v[130:133], v[130:131], off
	s_nop 0
	global_load_dwordx4 v[228:231], v[136:137], off
	global_load_dwordx4 v[232:235], v[134:135], off
	s_cmp_ge_i32 s12, s40
	s_nop 0
	s_cselect_b64 s[34:35], -1, 0
	s_cmp_le_i32 s12, s41
	s_cselect_b64 s[36:37], -1, 0
	s_and_b64 s[34:35], s[34:35], s[36:37]
	v_cndmask_b32_e64 v86, 0, 1.0, s[34:35]
	s_add_i32 s34, s12, 1
	s_cmp_ge_i32 s34, s40
	s_cselect_b64 s[36:37], -1, 0
	s_cmp_le_i32 s34, s41
	s_cselect_b64 s[38:39], -1, 0
	s_and_b64 s[36:37], s[36:37], s[38:39]
	s_cmp_lt_i32 s2, s40
	s_waitcnt vmcnt(9)
	v_lshlrev_b32_e32 v198, 16, v80
	v_and_b32_e32 v199, 0xffff0000, v80
	v_lshlrev_b32_e32 v200, 16, v81
	v_and_b32_e32 v201, 0xffff0000, v81
	v_lshlrev_b32_e32 v202, 16, v82
	v_and_b32_e32 v203, 0xffff0000, v82
	v_lshlrev_b32_e32 v204, 16, v83
	v_and_b32_e32 v205, 0xffff0000, v83
	s_waitcnt vmcnt(8)
	v_lshlrev_b32_e32 v206, 16, v106
	v_and_b32_e32 v207, 0xffff0000, v106
	v_lshlrev_b32_e32 v214, 16, v107
	v_and_b32_e32 v215, 0xffff0000, v107
	v_lshlrev_b32_e32 v216, 16, v108
	v_and_b32_e32 v217, 0xffff0000, v108
	v_lshlrev_b32_e32 v218, 16, v109
	v_and_b32_e32 v219, 0xffff0000, v109
	s_waitcnt vmcnt(7)
	v_lshlrev_b32_e32 v172, 16, v110
	v_and_b32_e32 v173, 0xffff0000, v110
	v_lshlrev_b32_e32 v180, 16, v111
	v_and_b32_e32 v181, 0xffff0000, v111
	v_lshlrev_b32_e32 v170, 16, v112
	v_and_b32_e32 v171, 0xffff0000, v112
	v_lshlrev_b32_e32 v178, 16, v113
	v_and_b32_e32 v179, 0xffff0000, v113
	s_waitcnt vmcnt(6)
	v_lshlrev_b32_e32 v168, 16, v114
	v_and_b32_e32 v169, 0xffff0000, v114
	v_lshlrev_b32_e32 v176, 16, v115
	v_and_b32_e32 v177, 0xffff0000, v115
	v_lshlrev_b32_e32 v166, 16, v116
	v_and_b32_e32 v167, 0xffff0000, v116
	v_lshlrev_b32_e32 v174, 16, v117
	v_and_b32_e32 v175, 0xffff0000, v117
	s_waitcnt vmcnt(5)
	v_lshlrev_b32_e32 v156, 16, v118
	v_and_b32_e32 v157, 0xffff0000, v118
	v_lshlrev_b32_e32 v164, 16, v119
	v_and_b32_e32 v165, 0xffff0000, v119
	v_lshlrev_b32_e32 v154, 16, v120
	v_and_b32_e32 v155, 0xffff0000, v120
	v_lshlrev_b32_e32 v162, 16, v121
	v_and_b32_e32 v163, 0xffff0000, v121
	s_waitcnt vmcnt(4)
	v_lshlrev_b32_e32 v152, 16, v122
	v_and_b32_e32 v153, 0xffff0000, v122
	v_lshlrev_b32_e32 v160, 16, v123
	v_and_b32_e32 v161, 0xffff0000, v123
	v_lshlrev_b32_e32 v150, 16, v124
	v_and_b32_e32 v151, 0xffff0000, v124
	v_lshlrev_b32_e32 v158, 16, v125
	v_and_b32_e32 v159, 0xffff0000, v125
	s_waitcnt vmcnt(3)
	v_lshlrev_b32_e32 v140, 16, v126
	v_and_b32_e32 v141, 0xffff0000, v126
	v_lshlrev_b32_e32 v148, 16, v127
	v_and_b32_e32 v149, 0xffff0000, v127
	v_lshlrev_b32_e32 v138, 16, v128
	v_and_b32_e32 v139, 0xffff0000, v128
	v_lshlrev_b32_e32 v146, 16, v129
	v_and_b32_e32 v147, 0xffff0000, v129
	s_waitcnt vmcnt(2)
	v_lshlrev_b32_e32 v136, 16, v130
	v_and_b32_e32 v137, 0xffff0000, v130
	v_lshlrev_b32_e32 v144, 16, v131
	v_and_b32_e32 v145, 0xffff0000, v131
	v_lshlrev_b32_e32 v134, 16, v132
	v_and_b32_e32 v135, 0xffff0000, v132
	v_lshlrev_b32_e32 v142, 16, v133
	v_and_b32_e32 v143, 0xffff0000, v133
	v_lshlrev_b32_e32 v124, 16, v220
	v_and_b32_e32 v125, 0xffff0000, v220
	v_lshlrev_b32_e32 v132, 16, v221
	v_and_b32_e32 v133, 0xffff0000, v221
	v_lshlrev_b32_e32 v122, 16, v222
	v_and_b32_e32 v123, 0xffff0000, v222
	v_lshlrev_b32_e32 v130, 16, v223
	v_and_b32_e32 v131, 0xffff0000, v223
	v_lshlrev_b32_e32 v120, 16, v224
	v_and_b32_e32 v121, 0xffff0000, v224
	v_lshlrev_b32_e32 v128, 16, v225
	v_and_b32_e32 v129, 0xffff0000, v225
	v_lshlrev_b32_e32 v118, 16, v226
	v_and_b32_e32 v119, 0xffff0000, v226
	v_lshlrev_b32_e32 v126, 16, v227
	v_and_b32_e32 v127, 0xffff0000, v227
	s_waitcnt vmcnt(1)
	v_lshlrev_b32_e32 v108, 16, v228
	v_and_b32_e32 v109, 0xffff0000, v228
	v_lshlrev_b32_e32 v116, 16, v229
	v_and_b32_e32 v117, 0xffff0000, v229
	v_lshlrev_b32_e32 v106, 16, v230
	v_and_b32_e32 v107, 0xffff0000, v230
	v_lshlrev_b32_e32 v114, 16, v231
	v_and_b32_e32 v115, 0xffff0000, v231
	s_waitcnt vmcnt(0)
	v_lshlrev_b32_e32 v82, 16, v232
	v_and_b32_e32 v83, 0xffff0000, v232
	v_lshlrev_b32_e32 v112, 16, v233
	v_and_b32_e32 v113, 0xffff0000, v233
	v_lshlrev_b32_e32 v80, 16, v234
	v_and_b32_e32 v81, 0xffff0000, v234
	v_lshlrev_b32_e32 v110, 16, v235
	v_and_b32_e32 v111, 0xffff0000, v235
	s_waitcnt lgkmcnt(14)
	v_pk_mul_f32 v[182:183], v[16:17], v[86:87] op_sel_hi:[1,0]
	v_pk_mul_f32 v[184:185], v[18:19], v[86:87] op_sel_hi:[1,0]
	v_pk_mul_f32 v[186:187], v[20:21], v[86:87] op_sel_hi:[1,0]
	v_pk_mul_f32 v[188:189], v[22:23], v[86:87] op_sel_hi:[1,0]
	s_waitcnt lgkmcnt(13)
	v_pk_mul_f32 v[190:191], v[24:25], v[86:87] op_sel_hi:[1,0]
	v_pk_mul_f32 v[192:193], v[26:27], v[86:87] op_sel_hi:[1,0]
	s_waitcnt lgkmcnt(12)
	v_pk_mul_f32 v[194:195], v[28:29], v[86:87] op_sel_hi:[1,0]
	v_pk_mul_f32 v[196:197], v[30:31], v[86:87] op_sel_hi:[1,0]
	v_cndmask_b32_e64 v86, 0, 1.0, s[36:37]
	v_pk_fma_f32 v[184:185], v[184:185], v[200:201], 0 op_sel_hi:[1,1,0]
	v_pk_fma_f32 v[182:183], v[182:183], v[198:199], 0 op_sel_hi:[1,1,0]
	s_waitcnt lgkmcnt(11)
	v_pk_mul_f32 v[198:199], v[34:35], v[86:87] op_sel_hi:[1,0]
	v_pk_mul_f32 v[200:201], v[32:33], v[86:87] op_sel_hi:[1,0]
	v_pk_fma_f32 v[188:189], v[188:189], v[204:205], 0 op_sel_hi:[1,1,0]
	v_pk_fma_f32 v[186:187], v[186:187], v[202:203], 0 op_sel_hi:[1,1,0]
	v_pk_fma_f32 v[182:183], v[200:201], v[172:173], v[182:183]
	v_pk_fma_f32 v[184:185], v[198:199], v[180:181], v[184:185]
	s_waitcnt lgkmcnt(10)
	v_pk_mul_f32 v[198:199], v[38:39], v[86:87] op_sel_hi:[1,0]
	v_pk_mul_f32 v[200:201], v[36:37], v[86:87] op_sel_hi:[1,0]
	v_pk_fma_f32 v[192:193], v[192:193], v[214:215], 0 op_sel_hi:[1,1,0]
	v_pk_fma_f32 v[190:191], v[190:191], v[206:207], 0 op_sel_hi:[1,1,0]
	v_pk_fma_f32 v[186:187], v[200:201], v[170:171], v[186:187]
	v_pk_fma_f32 v[188:189], v[198:199], v[178:179], v[188:189]
	s_waitcnt lgkmcnt(9)
	v_pk_mul_f32 v[198:199], v[42:43], v[86:87] op_sel_hi:[1,0]
	v_pk_mul_f32 v[200:201], v[40:41], v[86:87] op_sel_hi:[1,0]
	s_cselect_b64 s[36:37], -1, 0
	v_pk_fma_f32 v[196:197], v[196:197], v[218:219], 0 op_sel_hi:[1,1,0]
	v_pk_fma_f32 v[194:195], v[194:195], v[216:217], 0 op_sel_hi:[1,1,0]
	v_pk_fma_f32 v[190:191], v[200:201], v[168:169], v[190:191]
	v_pk_fma_f32 v[192:193], v[198:199], v[176:177], v[192:193]
	s_waitcnt lgkmcnt(8)
	v_pk_mul_f32 v[198:199], v[46:47], v[86:87] op_sel_hi:[1,0]
	v_pk_mul_f32 v[200:201], v[44:45], v[86:87] op_sel_hi:[1,0]
	v_cndmask_b32_e64 v86, 1.0, 0, s[36:37]
	s_cmp_ge_i32 s13, s40
	v_pk_fma_f32 v[194:195], v[200:201], v[166:167], v[194:195]
	v_pk_fma_f32 v[196:197], v[198:199], v[174:175], v[196:197]
	s_waitcnt lgkmcnt(7)
	v_pk_mul_f32 v[198:199], v[48:49], v[86:87] op_sel_hi:[1,0]
	v_pk_mul_f32 v[200:201], v[50:51], v[86:87] op_sel_hi:[1,0]
	s_cselect_b64 s[36:37], -1, 0
	s_cmp_lt_i32 s2, s41
	v_pk_fma_f32 v[184:185], v[200:201], v[164:165], v[184:185]
	v_pk_fma_f32 v[182:183], v[198:199], v[156:157], v[182:183]
	s_waitcnt lgkmcnt(6)
	v_pk_mul_f32 v[198:199], v[52:53], v[86:87] op_sel_hi:[1,0]
	v_pk_mul_f32 v[200:201], v[54:55], v[86:87] op_sel_hi:[1,0]
	s_cselect_b64 s[38:39], -1, 0
	v_pk_fma_f32 v[188:189], v[200:201], v[162:163], v[188:189]
	v_pk_fma_f32 v[186:187], v[198:199], v[154:155], v[186:187]
	s_waitcnt lgkmcnt(5)
	v_pk_mul_f32 v[198:199], v[56:57], v[86:87] op_sel_hi:[1,0]
	v_pk_mul_f32 v[200:201], v[58:59], v[86:87] op_sel_hi:[1,0]
	s_and_b64 s[36:37], s[36:37], s[38:39]
	v_pk_fma_f32 v[192:193], v[200:201], v[160:161], v[192:193]
	v_pk_fma_f32 v[190:191], v[198:199], v[152:153], v[190:191]
	s_waitcnt lgkmcnt(4)
	v_pk_mul_f32 v[198:199], v[60:61], v[86:87] op_sel_hi:[1,0]
	v_pk_mul_f32 v[200:201], v[62:63], v[86:87] op_sel_hi:[1,0]
	v_cndmask_b32_e64 v86, 0, 1.0, s[36:37]
	s_cmp_ge_i32 s23, s40
	v_pk_fma_f32 v[196:197], v[200:201], v[158:159], v[196:197]
	v_pk_fma_f32 v[194:195], v[198:199], v[150:151], v[194:195]
	s_waitcnt lgkmcnt(3)
	v_pk_mul_f32 v[198:199], v[66:67], v[86:87] op_sel_hi:[1,0]
	v_pk_mul_f32 v[200:201], v[64:65], v[86:87] op_sel_hi:[1,0]
	s_cselect_b64 s[36:37], -1, 0
	s_cmp_le_i32 s23, s41
	v_pk_fma_f32 v[182:183], v[200:201], v[140:141], v[182:183]
	v_pk_fma_f32 v[184:185], v[198:199], v[148:149], v[184:185]
	s_waitcnt lgkmcnt(2)
	v_pk_mul_f32 v[198:199], v[70:71], v[86:87] op_sel_hi:[1,0]
	v_pk_mul_f32 v[200:201], v[68:69], v[86:87] op_sel_hi:[1,0]
	s_cselect_b64 s[38:39], -1, 0
	v_pk_fma_f32 v[186:187], v[200:201], v[138:139], v[186:187]
	v_pk_fma_f32 v[188:189], v[198:199], v[146:147], v[188:189]
	s_waitcnt lgkmcnt(1)
	v_pk_mul_f32 v[198:199], v[74:75], v[86:87] op_sel_hi:[1,0]
	v_pk_mul_f32 v[200:201], v[72:73], v[86:87] op_sel_hi:[1,0]
	s_and_b64 s[36:37], s[36:37], s[38:39]
	v_pk_fma_f32 v[190:191], v[200:201], v[136:137], v[190:191]
	v_pk_fma_f32 v[192:193], v[198:199], v[144:145], v[192:193]
	s_waitcnt lgkmcnt(0)
	v_pk_mul_f32 v[198:199], v[78:79], v[86:87] op_sel_hi:[1,0]
	v_pk_mul_f32 v[200:201], v[76:77], v[86:87] op_sel_hi:[1,0]
	v_cndmask_b32_e64 v86, 0, 1.0, s[36:37]
	v_pk_fma_f32 v[194:195], v[200:201], v[134:135], v[194:195]
	v_pk_fma_f32 v[196:197], v[198:199], v[142:143], v[196:197]
	v_pk_mul_f32 v[198:199], v[0:1], v[86:87] op_sel_hi:[1,0]
	v_pk_mul_f32 v[200:201], v[2:3], v[86:87] op_sel_hi:[1,0]
	v_pk_fma_f32 v[182:183], v[198:199], v[124:125], v[182:183]
	v_pk_fma_f32 v[184:185], v[200:201], v[132:133], v[184:185]
	v_pk_mul_f32 v[198:199], v[4:5], v[86:87] op_sel_hi:[1,0]
	v_pk_mul_f32 v[200:201], v[6:7], v[86:87] op_sel_hi:[1,0]
	v_pk_fma_f32 v[186:187], v[198:199], v[122:123], v[186:187]
	v_pk_fma_f32 v[188:189], v[200:201], v[130:131], v[188:189]
	v_pk_mul_f32 v[198:199], v[8:9], v[86:87] op_sel_hi:[1,0]
	v_pk_mul_f32 v[200:201], v[10:11], v[86:87] op_sel_hi:[1,0]
	v_pk_fma_f32 v[198:199], v[198:199], v[120:121], v[190:191]
	v_pk_fma_f32 v[200:201], v[200:201], v[128:129], v[192:193]
	v_pk_mul_f32 v[190:191], v[12:13], v[86:87] op_sel_hi:[1,0]
	v_pk_mul_f32 v[192:193], v[14:15], v[86:87] op_sel_hi:[1,0]
	v_mul_f32_e32 v86, 0xbfb8aa3b, v182
	v_exp_f32_e32 v86, v86
	v_pk_fma_f32 v[202:203], v[190:191], v[118:119], v[194:195]
	v_pk_fma_f32 v[204:205], v[192:193], v[126:127], v[196:197]
	s_cmpk_lt_i32 s13, 0x2000
	v_add_f32_e32 v86, 1.0, v86
	v_rcp_f32_e32 v190, v86
	v_mul_f32_e32 v86, 0xbfb8aa3b, v183
	v_exp_f32_e32 v86, v86
	s_cselect_b32 s35, s27, 0x7fffff00
	s_cselect_b32 s36, s30, 0xff
	s_and_b32 s38, s35, s2
	v_add_f32_e32 v86, 1.0, v86
	v_rcp_f32_e32 v191, v86
	v_mul_f32_e32 v86, 0xbfb8aa3b, v184
	v_exp_f32_e32 v86, v86
	s_or_b32 s39, s36, s2
	s_cmp_ge_i32 s34, s38
	s_cselect_b64 s[36:37], -1, 0
	v_add_f32_e32 v86, 1.0, v86
	v_rcp_f32_e32 v192, v86
	v_mul_f32_e32 v86, 0xbfb8aa3b, v185
	v_exp_f32_e32 v86, v86
	s_cmp_le_i32 s34, s39
	s_cselect_b64 s[34:35], -1, 0
	s_and_b64 s[34:35], s[36:37], s[34:35]
	v_add_f32_e32 v86, 1.0, v86
	v_rcp_f32_e32 v193, v86
	v_mul_f32_e32 v86, 0xbfb8aa3b, v186
	v_exp_f32_e32 v86, v86
	s_cmp_lt_i32 s2, s38
	v_pk_mul_f32 v[182:183], v[182:183], v[190:191]
	v_pk_mul_f32 v[184:185], v[184:185], v[192:193]
	v_add_f32_e32 v86, 1.0, v86
	v_rcp_f32_e32 v194, v86
	v_mul_f32_e32 v86, 0xbfb8aa3b, v187
	v_exp_f32_e32 v86, v86
	v_pk_mul_f32 v[190:191], v[182:183], v[182:183]
	v_pk_mul_f32 v[192:193], v[184:185], v[184:185]
	v_lshl_add_u64 v[214:215], s[62:63], 0, v[98:99]
	v_add_f32_e32 v86, 1.0, v86
	v_rcp_f32_e32 v195, v86
	v_mul_f32_e32 v86, 0xbfb8aa3b, v188
	v_exp_f32_e32 v86, v86
	v_lshl_add_u64 v[98:99], v[98:99], 0, s[20:21]
	v_pk_mul_f32 v[186:187], v[186:187], v[194:195]
	v_add_f32_e32 v86, 1.0, v86
	v_rcp_f32_e32 v196, v86
	v_mul_f32_e32 v86, 0xbfb8aa3b, v189
	v_exp_f32_e32 v86, v86
	v_pk_mul_f32 v[194:195], v[186:187], v[186:187]
	v_add_f32_e32 v86, 1.0, v86
	v_rcp_f32_e32 v197, v86
	v_mul_f32_e32 v86, 0xbfb8aa3b, v198
	v_exp_f32_e32 v86, v86
	v_pk_mul_f32 v[188:189], v[188:189], v[196:197]
	s_nop 0
	v_pk_mul_f32 v[196:197], v[188:189], v[188:189]
	v_add_f32_e32 v86, 1.0, v86
	v_rcp_f32_e32 v206, v86
	v_mul_f32_e32 v86, 0xbfb8aa3b, v199
	v_exp_f32_e32 v86, v86
	s_nop 0
	v_add_f32_e32 v86, 1.0, v86
	v_rcp_f32_e32 v207, v86
	v_mul_f32_e32 v86, 0xbfb8aa3b, v200
	v_exp_f32_e32 v86, v86
	v_pk_mul_f32 v[198:199], v[198:199], v[206:207]
	s_nop 0
	v_cvt_pk_bf16_f32 v198, v198, v199
	v_add_f32_e32 v86, 1.0, v86
	v_rcp_f32_e32 v206, v86
	v_mul_f32_e32 v86, 0xbfb8aa3b, v201
	v_exp_f32_e32 v86, v86
	s_nop 0
	v_add_f32_e32 v86, 1.0, v86
	v_rcp_f32_e32 v207, v86
	v_mul_f32_e32 v86, 0xbfb8aa3b, v202
	v_exp_f32_e32 v86, v86
	v_pk_mul_f32 v[200:201], v[200:201], v[206:207]
	s_nop 0
	v_cvt_pk_bf16_f32 v199, v200, v201
	v_add_f32_e32 v86, 1.0, v86
	v_rcp_f32_e32 v206, v86
	v_mul_f32_e32 v86, 0xbfb8aa3b, v203
	v_exp_f32_e32 v86, v86
	s_nop 0
	v_add_f32_e32 v86, 1.0, v86
	v_rcp_f32_e32 v207, v86
	v_mul_f32_e32 v86, 0xbfb8aa3b, v204
	v_exp_f32_e32 v86, v86
	v_pk_mul_f32 v[202:203], v[202:203], v[206:207]
	s_nop 0
	v_cvt_pk_bf16_f32 v200, v202, v203
	v_add_f32_e32 v86, 1.0, v86
	v_rcp_f32_e32 v206, v86
	v_mul_f32_e32 v86, 0xbfb8aa3b, v205
	v_exp_f32_e32 v86, v86
	v_lshl_add_u64 v[202:203], s[62:63], 0, v[94:95]
	v_lshl_add_u64 v[94:95], v[94:95], 0, s[18:19]
	v_add_f32_e32 v86, 1.0, v86
	v_rcp_f32_e32 v207, v86
	v_cndmask_b32_e64 v86, 0, 1.0, s[34:35]
	s_cselect_b64 s[34:35], -1, 0
	s_cmp_lt_i32 s13, s38
	v_pk_mul_f32 v[204:205], v[204:205], v[206:207]
	v_lshl_add_u64 v[206:207], s[62:63], 0, v[96:97]
	v_cvt_pk_bf16_f32 v201, v204, v205
	global_store_dwordx4 v[202:203], v[198:201], off
	v_cndmask_b32_e64 v207, v207, v215, s[10:11]
	v_cndmask_b32_e64 v206, v206, v214, s[10:11]
	v_pk_mul_f32 v[198:199], v[16:17], v[86:87] op_sel_hi:[1,0]
	v_pk_mul_f32 v[200:201], v[18:19], v[86:87] op_sel_hi:[1,0]
	v_pk_fma_f32 v[172:173], v[198:199], v[172:173], 0 op_sel_hi:[1,1,0]
	v_pk_fma_f32 v[180:181], v[200:201], v[180:181], 0 op_sel_hi:[1,1,0]
	v_pk_mul_f32 v[198:199], v[20:21], v[86:87] op_sel_hi:[1,0]
	v_pk_mul_f32 v[200:201], v[22:23], v[86:87] op_sel_hi:[1,0]
	v_pk_fma_f32 v[170:171], v[198:199], v[170:171], 0 op_sel_hi:[1,1,0]
	v_pk_fma_f32 v[178:179], v[200:201], v[178:179], 0 op_sel_hi:[1,1,0]
	v_pk_mul_f32 v[198:199], v[24:25], v[86:87] op_sel_hi:[1,0]
	v_pk_mul_f32 v[200:201], v[26:27], v[86:87] op_sel_hi:[1,0]
	v_pk_fma_f32 v[168:169], v[198:199], v[168:169], 0 op_sel_hi:[1,1,0]
	v_pk_fma_f32 v[176:177], v[200:201], v[176:177], 0 op_sel_hi:[1,1,0]
	v_pk_mul_f32 v[198:199], v[28:29], v[86:87] op_sel_hi:[1,0]
	v_pk_mul_f32 v[200:201], v[30:31], v[86:87] op_sel_hi:[1,0]
	v_cndmask_b32_e64 v86, 1.0, 0, s[34:35]
	v_pk_fma_f32 v[174:175], v[200:201], v[174:175], 0 op_sel_hi:[1,1,0]
	v_pk_fma_f32 v[166:167], v[198:199], v[166:167], 0 op_sel_hi:[1,1,0]
	v_pk_mul_f32 v[198:199], v[34:35], v[86:87] op_sel_hi:[1,0]
	v_pk_mul_f32 v[200:201], v[32:33], v[86:87] op_sel_hi:[1,0]
	v_pk_fma_f32 v[164:165], v[198:199], v[164:165], v[180:181]
	v_pk_fma_f32 v[156:157], v[200:201], v[156:157], v[172:173]
	v_pk_mul_f32 v[172:173], v[38:39], v[86:87] op_sel_hi:[1,0]
	v_pk_mul_f32 v[180:181], v[36:37], v[86:87] op_sel_hi:[1,0]
	v_pk_fma_f32 v[162:163], v[172:173], v[162:163], v[178:179]
	v_pk_fma_f32 v[154:155], v[180:181], v[154:155], v[170:171]
	v_pk_mul_f32 v[170:171], v[42:43], v[86:87] op_sel_hi:[1,0]
	v_pk_mul_f32 v[172:173], v[40:41], v[86:87] op_sel_hi:[1,0]
	s_cselect_b64 s[34:35], -1, 0
	v_pk_fma_f32 v[152:153], v[172:173], v[152:153], v[168:169]
	v_pk_fma_f32 v[160:161], v[170:171], v[160:161], v[176:177]
	v_pk_mul_f32 v[168:169], v[46:47], v[86:87] op_sel_hi:[1,0]
	v_pk_mul_f32 v[170:171], v[44:45], v[86:87] op_sel_hi:[1,0]
	v_cndmask_b32_e64 v86, 1.0, 0, s[34:35]
	s_cmp_ge_i32 s23, s38
	v_pk_fma_f32 v[150:151], v[170:171], v[150:151], v[166:167]
	v_pk_mul_f32 v[166:167], v[48:49], v[86:87] op_sel_hi:[1,0]
	s_cselect_b64 s[34:35], -1, 0
	s_cmp_le_i32 s23, s39
	v_pk_fma_f32 v[140:141], v[166:167], v[140:141], v[156:157]
	v_pk_mul_f32 v[156:157], v[52:53], v[86:87] op_sel_hi:[1,0]
	s_cselect_b64 s[36:37], -1, 0
	v_pk_fma_f32 v[158:159], v[168:169], v[158:159], v[174:175]
	v_pk_mul_f32 v[168:169], v[50:51], v[86:87] op_sel_hi:[1,0]
	v_pk_fma_f32 v[138:139], v[156:157], v[138:139], v[154:155]
	v_pk_mul_f32 v[154:155], v[56:57], v[86:87] op_sel_hi:[1,0]
	s_and_b64 s[34:35], s[34:35], s[36:37]
	s_add_i32 s23, s12, 5
	v_pk_fma_f32 v[148:149], v[168:169], v[148:149], v[164:165]
	v_pk_mul_f32 v[164:165], v[54:55], v[86:87] op_sel_hi:[1,0]
	v_pk_mul_f32 v[156:157], v[58:59], v[86:87] op_sel_hi:[1,0]
	v_pk_fma_f32 v[136:137], v[154:155], v[136:137], v[152:153]
	v_pk_mul_f32 v[152:153], v[60:61], v[86:87] op_sel_hi:[1,0]
	v_pk_mul_f32 v[154:155], v[62:63], v[86:87] op_sel_hi:[1,0]
	v_cndmask_b32_e64 v86, 0, 1.0, s[34:35]
	s_cmp_ge_i32 s23, s38
	v_pk_fma_f32 v[134:135], v[152:153], v[134:135], v[150:151]
	v_pk_mul_f32 v[150:151], v[66:67], v[86:87] op_sel_hi:[1,0]
	v_pk_mul_f32 v[152:153], v[64:65], v[86:87] op_sel_hi:[1,0]
	s_cselect_b64 s[12:13], -1, 0
	s_cmp_le_i32 s23, s39
	v_pk_fma_f32 v[146:147], v[164:165], v[146:147], v[162:163]
	v_pk_fma_f32 v[124:125], v[152:153], v[124:125], v[140:141]
	v_pk_fma_f32 v[132:133], v[150:151], v[132:133], v[148:149]
	v_pk_mul_f32 v[140:141], v[70:71], v[86:87] op_sel_hi:[1,0]
	v_pk_mul_f32 v[148:149], v[68:69], v[86:87] op_sel_hi:[1,0]
	s_cselect_b64 s[34:35], -1, 0
	v_pk_fma_f32 v[144:145], v[156:157], v[144:145], v[160:161]
	v_pk_fma_f32 v[122:123], v[148:149], v[122:123], v[138:139]
	v_pk_fma_f32 v[130:131], v[140:141], v[130:131], v[146:147]
	v_pk_mul_f32 v[138:139], v[74:75], v[86:87] op_sel_hi:[1,0]
	v_pk_mul_f32 v[140:141], v[72:73], v[86:87] op_sel_hi:[1,0]
	s_and_b64 s[12:13], s[12:13], s[34:35]
	v_pk_fma_f32 v[142:143], v[154:155], v[142:143], v[158:159]
	v_pk_fma_f32 v[136:137], v[140:141], v[120:121], v[136:137]
	v_pk_fma_f32 v[128:129], v[138:139], v[128:129], v[144:145]
	v_pk_mul_f32 v[120:121], v[78:79], v[86:87] op_sel_hi:[1,0]
	v_pk_mul_f32 v[138:139], v[76:77], v[86:87] op_sel_hi:[1,0]
	v_cndmask_b32_e64 v86, 0, 1.0, s[12:13]
	v_pk_fma_f32 v[134:135], v[138:139], v[118:119], v[134:135]
	v_pk_fma_f32 v[126:127], v[120:121], v[126:127], v[142:143]
	v_pk_mul_f32 v[120:121], v[0:1], v[86:87] op_sel_hi:[1,0]
	v_pk_mul_f32 v[118:119], v[2:3], v[86:87] op_sel_hi:[1,0]
	s_mov_b32 s12, 0x358637bd
	v_pk_fma_f32 v[118:119], v[118:119], v[116:117], v[132:133]
	v_pk_fma_f32 v[116:117], v[120:121], v[108:109], v[124:125]
	v_pk_mul_f32 v[108:109], v[4:5], v[86:87] op_sel_hi:[1,0]
	v_pk_mul_f32 v[120:121], v[6:7], v[86:87] op_sel_hi:[1,0]
	v_lshl_add_u64 v[96:97], v[96:97], 0, s[20:21]
	v_pk_fma_f32 v[120:121], v[120:121], v[114:115], v[130:131]
	v_pk_fma_f32 v[114:115], v[108:109], v[106:107], v[122:123]
	v_pk_mul_f32 v[106:107], v[8:9], v[86:87] op_sel_hi:[1,0]
	v_pk_mul_f32 v[108:109], v[10:11], v[86:87] op_sel_hi:[1,0]
	v_pk_fma_f32 v[82:83], v[106:107], v[82:83], v[136:137]
	v_pk_mul_f32 v[106:107], v[12:13], v[86:87] op_sel_hi:[1,0]
	v_pk_fma_f32 v[108:109], v[108:109], v[112:113], v[128:129]
	v_pk_fma_f32 v[106:107], v[106:107], v[80:81], v[134:135]
	v_mul_f32_e32 v80, 0xbfb8aa3b, v116
	v_exp_f32_e32 v80, v80
	v_pk_mul_f32 v[112:113], v[14:15], v[86:87] op_sel_hi:[1,0]
	v_mul_f32_e32 v81, 0xbfb8aa3b, v83
	v_pk_fma_f32 v[126:127], v[112:113], v[110:111], v[126:127]
	v_add_f32_e32 v80, 1.0, v80
	v_rcp_f32_e32 v110, v80
	v_mul_f32_e32 v80, 0xbfb8aa3b, v117
	v_exp_f32_e32 v80, v80
	v_exp_f32_e32 v81, v81
	v_mul_f32_e32 v86, 0xbfb8aa3b, v106
	v_exp_f32_e32 v86, v86
	v_add_f32_e32 v80, 1.0, v80
	v_rcp_f32_e32 v111, v80
	v_mul_f32_e32 v80, 0xbfb8aa3b, v118
	v_exp_f32_e32 v80, v80
	v_add_f32_e32 v81, 1.0, v81
	v_rcp_f32_e32 v81, v81
	v_add_f32_e32 v86, 1.0, v86
	v_add_f32_e32 v80, 1.0, v80
	v_rcp_f32_e32 v112, v80
	v_mul_f32_e32 v80, 0xbfb8aa3b, v119
	v_exp_f32_e32 v80, v80
	v_pk_mul_f32 v[116:117], v[116:117], v[110:111]
	v_lshl_add_u64 v[128:129], s[62:63], 0, v[102:103]
	v_pk_mul_f32 v[110:111], v[116:117], v[116:117]
	v_add_f32_e32 v80, 1.0, v80
	v_rcp_f32_e32 v113, v80
	v_mul_f32_e32 v80, 0xbfb8aa3b, v114
	v_exp_f32_e32 v80, v80
	v_lshl_add_u64 v[102:103], v[102:103], 0, s[20:21]
	v_pk_mul_f32 v[118:119], v[118:119], v[112:113]
	s_cmp_ge_i32 s2, s17
	v_add_f32_e32 v80, 1.0, v80
	v_rcp_f32_e32 v122, v80
	v_mul_f32_e32 v80, 0xbfb8aa3b, v115
	v_exp_f32_e32 v80, v80
	v_pk_mul_f32 v[112:113], v[118:119], v[118:119]
	v_add_f32_e32 v80, 1.0, v80
	v_rcp_f32_e32 v123, v80
	v_mul_f32_e32 v80, 0xbfb8aa3b, v120
	v_exp_f32_e32 v80, v80
	v_pk_mul_f32 v[114:115], v[114:115], v[122:123]
	s_nop 0
	v_pk_mul_f32 v[122:123], v[114:115], v[114:115]
	v_add_f32_e32 v80, 1.0, v80
	v_rcp_f32_e32 v124, v80
	v_mul_f32_e32 v80, 0xbfb8aa3b, v121
	v_exp_f32_e32 v80, v80
	s_nop 0
	v_add_f32_e32 v80, 1.0, v80
	v_rcp_f32_e32 v125, v80
	v_mul_f32_e32 v80, 0xbfb8aa3b, v82
	v_exp_f32_e32 v80, v80
	v_pk_mul_f32 v[120:121], v[120:121], v[124:125]
	s_nop 0
	v_pk_mul_f32 v[124:125], v[120:121], v[120:121]
	v_add_f32_e32 v80, 1.0, v80
	v_rcp_f32_e32 v80, v80
	s_nop 0
	v_pk_mul_f32 v[80:81], v[82:83], v[80:81]
	v_mul_f32_e32 v82, 0xbfb8aa3b, v108
	v_mul_f32_e32 v83, 0xbfb8aa3b, v109
	v_exp_f32_e32 v82, v82
	v_exp_f32_e32 v83, v83
	v_cvt_pk_bf16_f32 v80, v80, v81
	v_add_f32_e32 v82, 1.0, v82
	v_add_f32_e32 v83, 1.0, v83
	v_rcp_f32_e32 v82, v82
	v_rcp_f32_e32 v83, v83
	s_nop 0
	v_pk_mul_f32 v[82:83], v[108:109], v[82:83]
	v_rcp_f32_e32 v108, v86
	v_mul_f32_e32 v86, 0xbfb8aa3b, v107
	v_exp_f32_e32 v86, v86
	v_cvt_pk_bf16_f32 v81, v82, v83
	v_add_f32_e32 v86, 1.0, v86
	v_rcp_f32_e32 v109, v86
	v_mul_f32_e32 v86, 0xbfb8aa3b, v126
	v_exp_f32_e32 v86, v86
	v_pk_mul_f32 v[106:107], v[106:107], v[108:109]
	s_nop 0
	v_cvt_pk_bf16_f32 v82, v106, v107
	v_add_f32_e32 v86, 1.0, v86
	v_rcp_f32_e32 v108, v86
	v_mul_f32_e32 v86, 0xbfb8aa3b, v127
	v_exp_f32_e32 v86, v86
	v_lshl_add_u64 v[106:107], s[62:63], 0, v[100:101]
	v_lshl_add_u64 v[100:101], v[100:101], 0, s[18:19]
	v_add_f32_e32 v86, 1.0, v86
	v_rcp_f32_e32 v109, v86
	s_nop 0
	v_pk_mul_f32 v[108:109], v[126:127], v[108:109]
	v_lshl_add_u64 v[126:127], s[62:63], 0, v[104:105]
	v_cndmask_b32_e64 v127, v129, v127, s[10:11]
	v_cndmask_b32_e64 v126, v128, v126, s[10:11]
	v_mov_b32_e32 v128, v110
	v_mov_b32_e32 v129, v190
	v_mov_b32_e32 v190, v111
	v_pk_add_f32 v[110:111], v[128:129], v[190:191]
	v_mov_b32_e32 v128, v112
	v_mov_b32_e32 v129, v192
	v_pk_add_f32 v[110:111], v[128:129], v[110:111]
	v_mov_b32_e32 v192, v113
	v_pk_add_f32 v[110:111], v[192:193], v[110:111]
	v_mov_b32_e32 v112, v122
	v_mov_b32_e32 v113, v194
	v_pk_add_f32 v[110:111], v[112:113], v[110:111]
	v_mov_b32_e32 v194, v123
	v_pk_add_f32 v[110:111], v[194:195], v[110:111]
	v_mov_b32_e32 v112, v124
	v_mov_b32_e32 v113, v196
	v_pk_add_f32 v[110:111], v[112:113], v[110:111]
	v_mov_b32_e32 v196, v125
	v_pk_add_f32 v[110:111], v[196:197], v[110:111]
	ds_bpermute_b32 v113, v85, v111
	ds_bpermute_b32 v112, v85, v110
	v_cvt_pk_bf16_f32 v83, v108, v109
	v_lshl_add_u64 v[104:105], v[104:105], 0, s[20:21]
	global_store_dwordx4 v[106:107], v[80:83], off
	s_waitcnt lgkmcnt(0)
	v_pk_add_f32 v[110:111], v[110:111], v[112:113]
	ds_bpermute_b32 v113, v209, v111
	ds_bpermute_b32 v112, v209, v110
	s_waitcnt lgkmcnt(0)
	v_pk_add_f32 v[110:111], v[110:111], v[112:113]
	ds_bpermute_b32 v113, v210, v111
	ds_bpermute_b32 v112, v210, v110
	s_waitcnt lgkmcnt(0)
	v_pk_add_f32 v[110:111], v[110:111], v[112:113]
	ds_bpermute_b32 v113, v211, v111
	ds_bpermute_b32 v112, v211, v110
	s_waitcnt lgkmcnt(0)
	v_pk_add_f32 v[110:111], v[110:111], v[112:113]
	s_nop 0
	v_pk_add_f32 v[122:123], v[110:111], s[12:13] op_sel_hi:[1,0]
	s_nop 0
	v_mul_f32_e32 v86, 0x4b800000, v123
	v_cmp_gt_f32_e64 s[12:13], s31, v123
	v_cmp_gt_f32_e32 vcc, s31, v122
	s_nop 0
	v_cndmask_b32_e64 v86, v123, v86, s[12:13]
	v_rsq_f32_e32 v86, v86
	s_nop 0
	v_mul_f32_e32 v110, 0x45800000, v86
	v_cndmask_b32_e64 v86, v86, v110, s[12:13]
	v_pk_mul_f32 v[110:111], v[182:183], v[86:87] op_sel_hi:[1,0]
	v_pk_mul_f32 v[112:113], v[184:185], v[86:87] op_sel_hi:[1,0]
	v_cvt_pk_bf16_f32 v110, v110, v111
	v_cvt_pk_bf16_f32 v111, v112, v113
	v_pk_mul_f32 v[112:113], v[186:187], v[86:87] op_sel_hi:[1,0]
	v_pk_mul_f32 v[124:125], v[188:189], v[86:87] op_sel_hi:[1,0]
	v_mul_f32_e32 v86, 0x4b800000, v122
	v_cndmask_b32_e32 v86, v122, v86, vcc
	v_rsq_f32_e32 v86, v86
	v_cvt_pk_bf16_f32 v112, v112, v113
	v_cvt_pk_bf16_f32 v113, v124, v125
	global_store_dwordx4 v[206:207], v[110:113], off
	s_mov_b32 s12, s2
	s_nop 0
	v_mul_f32_e32 v110, 0x45800000, v86
	v_cndmask_b32_e32 v86, v86, v110, vcc
	v_pk_mul_f32 v[110:111], v[116:117], v[86:87] op_sel_hi:[1,0]
	v_pk_mul_f32 v[112:113], v[118:119], v[86:87] op_sel_hi:[1,0]
	v_cvt_pk_bf16_f32 v110, v110, v111
	v_cvt_pk_bf16_f32 v111, v112, v113
	v_pk_mul_f32 v[112:113], v[114:115], v[86:87] op_sel_hi:[1,0]
	v_pk_mul_f32 v[114:115], v[120:121], v[86:87] op_sel_hi:[1,0]
	v_cvt_pk_bf16_f32 v112, v112, v113
	v_cvt_pk_bf16_f32 v113, v114, v115
	global_store_dwordx4 v[126:127], v[110:113], off
	s_cbranch_scc0 .LBB0_2395
	s_add_i32 s22, s22, s43
	s_add_i32 s1, s1, s43
	s_add_i32 s16, s16, s43
	s_cmpk_gt_i32 s22, 0x21ff
	s_cbranch_scc0 .LBB0_2394
	v_readlane_b32 s94, v239, 1

.LBB0_2460:
	ds_read_b128 v[188:191], v33
	ds_read_b128 v[192:195], v105
	ds_read_b128 v[196:199], v33 offset:64
	ds_read_b128 v[200:203], v105 offset:64
	ds_read_b128 v[204:207], v33 offset:128
	ds_read_b128 v[208:211], v105 offset:128
	ds_read_b128 v[212:215], v33 offset:192
	ds_read_b128 v[216:219], v105 offset:192
	s_ashr_i32 s40, s46, 4
	s_mul_hi_i32 s41, s40, 0x78787879
	s_lshr_b32 s47, s41, 31
	s_ashr_i32 s41, s41, 5
	s_waitcnt lgkmcnt(8)
	s_waitcnt lgkmcnt(6)
	v_mfma_f32_16x16x32_bf16 v[108:111], v[188:191], v[192:195], 0
	s_add_i32 s41, s41, s47
	s_mulk_i32 s41, 0x44
	s_sub_i32 s63, s40, s41
	s_waitcnt lgkmcnt(4)
	v_mfma_f32_16x16x32_bf16 v[108:111], v[196:199], v[200:203], v[108:111]
	s_mul_hi_i32 s40, s46, 0x78787879
	s_lshr_b32 s41, s40, 31
	s_waitcnt lgkmcnt(2)
	v_mfma_f32_16x16x32_bf16 v[108:111], v[204:207], v[208:211], v[108:111]
	s_ashr_i32 s64, s40, 9
	s_add_i32 s64, s64, s41
	s_waitcnt lgkmcnt(0)
	v_mfma_f32_16x16x32_bf16 v[108:111], v[212:215], v[216:219], v[108:111]
	s_nop 7
	ds_write_b32 v106, v108
	ds_write_b32 v106, v109 offset:260
	ds_write_b32 v106, v110 offset:520
	ds_write_b32 v106, v111 offset:780
	ds_read_b128 v[188:191], v33
	ds_read_b128 v[192:195], v105 offset:4352
	ds_read_b128 v[196:199], v33 offset:64
	ds_read_b128 v[200:203], v105 offset:4416
	ds_read_b128 v[204:207], v33 offset:128
	ds_read_b128 v[208:211], v105 offset:4480
	ds_read_b128 v[212:215], v33 offset:192
	ds_read_b128 v[216:219], v105 offset:4544
	s_mov_b64 s[40:41], -1
	s_waitcnt lgkmcnt(6)
	v_mfma_f32_16x16x32_bf16 v[108:111], v[188:191], v[192:195], 0
	s_cmp_gt_i32 s63, 3
	s_waitcnt lgkmcnt(4)
	v_mfma_f32_16x16x32_bf16 v[108:111], v[196:199], v[200:203], v[108:111]
	s_waitcnt lgkmcnt(2)
	v_mfma_f32_16x16x32_bf16 v[108:111], v[204:207], v[208:211], v[108:111]
	s_waitcnt lgkmcnt(0)
	v_mfma_f32_16x16x32_bf16 v[108:111], v[212:215], v[216:219], v[108:111]
	s_nop 7
	ds_write_b32 v106, v108 offset:64
	ds_write_b32 v106, v109 offset:324
	ds_write_b32 v106, v110 offset:584
	ds_write_b32 v106, v111 offset:844
	ds_read_b128 v[188:191], v33
	ds_read_b128 v[192:195], v105 offset:8704
	ds_read_b128 v[196:199], v33 offset:64
	ds_read_b128 v[200:203], v105 offset:8768
	ds_read_b128 v[204:207], v33 offset:128
	ds_read_b128 v[208:211], v105 offset:8832
	ds_read_b128 v[212:215], v33 offset:192
	ds_read_b128 v[216:219], v105 offset:8896
	s_waitcnt lgkmcnt(6)
	v_mfma_f32_16x16x32_bf16 v[108:111], v[188:191], v[192:195], 0
	s_waitcnt lgkmcnt(4)
	v_mfma_f32_16x16x32_bf16 v[108:111], v[196:199], v[200:203], v[108:111]
	s_waitcnt lgkmcnt(2)
	v_mfma_f32_16x16x32_bf16 v[108:111], v[204:207], v[208:211], v[108:111]
	s_waitcnt lgkmcnt(0)
	v_mfma_f32_16x16x32_bf16 v[108:111], v[212:215], v[216:219], v[108:111]
	s_nop 7
	ds_write_b32 v106, v108 offset:128
	ds_write_b32 v106, v109 offset:388
	ds_write_b32 v106, v110 offset:648
	ds_write_b32 v106, v111 offset:908
	ds_read_b128 v[188:191], v33
	ds_read_b128 v[192:195], v105 offset:13056
	ds_read_b128 v[196:199], v33 offset:64
	ds_read_b128 v[200:203], v105 offset:13120
	ds_read_b128 v[204:207], v33 offset:128
	ds_read_b128 v[208:211], v105 offset:13184
	ds_read_b128 v[112:115], v33 offset:192
	ds_read_b128 v[116:119], v105 offset:13248
	s_waitcnt lgkmcnt(6)
	v_mfma_f32_16x16x32_bf16 v[108:111], v[188:191], v[192:195], 0
	s_waitcnt lgkmcnt(4)
	v_mfma_f32_16x16x32_bf16 v[108:111], v[196:199], v[200:203], v[108:111]
	s_waitcnt lgkmcnt(2)
	v_mfma_f32_16x16x32_bf16 v[108:111], v[204:207], v[208:211], v[108:111]
	s_waitcnt lgkmcnt(0)
	v_mfma_f32_16x16x32_bf16 v[108:111], v[112:115], v[116:119], v[108:111]
	s_nop 7
	ds_write_b32 v106, v108 offset:192
	ds_write_b32 v106, v109 offset:452
	ds_write_b32 v106, v110 offset:712
	ds_write_b32 v106, v111 offset:972
	s_waitcnt lgkmcnt(0)
	s_barrier
	s_cbranch_scc0 .LBB0_2462
	s_lshl_b32 s40, s64, 12
	s_lshl_b32 s41, s63, 6
	s_add_i32 s40, s40, s41
	s_add_i32 s47, s40, 0xffffff00
	s_mov_b64 s[40:41], 0

.LBB0_2464:
	v_add_u32_e32 v30, s47, v34
	s_lshl_b32 s40, s46, 1
	v_ashrrev_i32_e32 v31, 31, v30
	s_and_b32 s40, s40, 30
	v_lshlrev_b64 v[30:31], 6, v[30:31]
	s_or_b32 s40, s40, s3
	v_or_b32_e32 v30, s5, v30
	v_readlane_b32 s44, v239, 51
	v_or_b32_e32 v30, s40, v30
	v_readlane_b32 s45, v239, 52
	s_mul_i32 s41, s64, 0x44
	s_add_i32 s41, s41, s63
	v_lshl_add_u64 v[108:109], v[30:31], 2, s[44:45]
	global_load_dword v107, v[108:109], off
	s_lshl_b32 s41, s41, 6
	s_lshl_b32 s40, s40, 1
	v_readlane_b32 s46, v239, 53
	v_readlane_b32 s47, v239, 54
	s_or_b32 s40, s41, s40
	s_andn2_b64 vcc, exec, s[36:37]
	s_or_b32 s40, s40, s2
	s_mov_b64 s[46:47], -1
	v_readlane_b32 s48, v239, 55
	v_readlane_b32 s49, v239, 56
	v_readlane_b32 s50, v239, 57
	v_readlane_b32 s51, v239, 58
	v_readlane_b32 s52, v239, 59
	v_readlane_b32 s53, v239, 60
	v_readlane_b32 s54, v239, 61
	v_readlane_b32 s55, v239, 62
	v_readlane_b32 s56, v239, 63
	v_readlane_b32 s57, v238, 0
	v_readlane_b32 s58, v238, 1
	v_readlane_b32 s59, v238, 2
	s_waitcnt vmcnt(0)
	ds_bpermute_b32 v187, v17, v107
	s_waitcnt lgkmcnt(1)
	s_waitcnt lgkmcnt(0)
	v_add_f32_e32 v108, v107, v187
	v_cndmask_b32_e64 v107, v108, v107, s[12:13]
	ds_bpermute_b32 v187, v25, v107
	s_waitcnt lgkmcnt(0)
	v_add_f32_e32 v108, v107, v187
	v_cndmask_b32_e64 v107, v108, v107, s[14:15]
	ds_bpermute_b32 v187, v27, v107
	s_waitcnt lgkmcnt(0)
	v_add_f32_e32 v108, v107, v187
	v_cndmask_b32_e64 v107, v108, v107, s[16:17]
	ds_bpermute_b32 v187, v36, v107
	s_waitcnt lgkmcnt(0)
	v_add_f32_e32 v108, v107, v187
	v_cndmask_b32_e64 v107, v108, v107, s[18:19]
	ds_bpermute_b32 v187, v37, v107
	s_waitcnt lgkmcnt(0)
	v_add_f32_e32 v108, v107, v187
	v_cndmask_b32_e64 v107, v108, v107, s[20:21]
	ds_bpermute_b32 v187, v38, v107
	s_waitcnt lgkmcnt(0)
	v_add_f32_e32 v108, v107, v187
	v_cndmask_b32_e64 v107, v108, v107, s[22:23]
	s_cbranch_vccnz .LBB0_2476
	v_readlane_b32 s44, v239, 51
	v_readlane_b32 s46, v239, 53
	v_readlane_b32 s47, v239, 54
	s_mov_b32 s41, 3
	s_mov_b32 s65, 60
	v_lshl_add_u64 v[30:31], v[30:31], 2, s[46:47]
	global_load_dword v30, v[30:31], off
	v_mov_b32_e32 v31, v104
	v_readlane_b32 s45, v239, 52
	v_readlane_b32 s48, v239, 55
	v_readlane_b32 s49, v239, 56
	v_readlane_b32 s50, v239, 57
	v_readlane_b32 s51, v239, 58
	v_readlane_b32 s52, v239, 59
	v_readlane_b32 s53, v239, 60
	v_readlane_b32 s54, v239, 61
	v_readlane_b32 s55, v239, 62
	v_readlane_b32 s56, v239, 63
	v_readlane_b32 s57, v238, 0
	v_readlane_b32 s58, v238, 1
	v_readlane_b32 s59, v238, 2
	s_branch .LBB0_2467

.LBB0_2550:
	s_add_i32 s40, s27, 1
	s_cmpk_lg_i32 s39, 0xffbe
	s_cselect_b32 s41, s40, 0x43
	s_cmp_gt_u32 s41, 3
	s_cselect_b32 s42, 0x47, 3
	s_sub_i32 s42, s42, s41
	s_and_b64 s[46:47], s[12:13], exec
	s_cselect_b32 s41, s41, s42
	s_add_i32 s42, s41, s2
	s_lshl_b32 s42, s42, 6
	s_or_b32 s46, s42, s38
	s_ashr_i32 s47, s46, 31
	s_lshl_b64 s[62:63], s[46:47], 8
	s_add_u32 s62, s34, s62
	s_addc_u32 s63, s35, s63
	s_lshl_b32 s42, s41, 6
	s_cmp_lt_i32 s41, 4
	s_movk_i32 s64, 0xff00
	s_cselect_b32 s64, 0x2000, s64
	s_cselect_b32 s65, s4, s21
	s_cselect_b32 s41, s3, s5
	s_add_i32 s65, s65, s42
	s_add_i32 s42, s64, s42
	s_add_i32 s42, s42, s41
	s_lshl_b64 s[46:47], s[46:47], 13
	s_add_i32 s41, s27, -1
	s_cmp_gt_u32 s27, 4
	s_cselect_b32 s27, 0x47, 3
	s_add_i32 s27, s27, s39
	v_lshl_add_u64 v[24:25], v[72:73], 0, s[46:47]
	v_lshl_add_u64 v[28:29], v[74:75], 0, s[46:47]
	s_and_b64 s[46:47], s[12:13], exec
	s_cselect_b32 s27, s41, s27
	s_lshl_b32 s41, s27, 6
	s_cmp_lt_i32 s27, 4
	s_cselect_b32 s27, s4, s21
	s_add_i32 s27, s27, s41
	v_add_u32_e32 v56, s27, v141
	v_ashrrev_i32_e32 v57, 31, v56
	v_lshl_add_u64 v[56:57], v[56:57], 0, s[16:17]
	v_lshlrev_b64 v[56:57], 13, v[56:57]
	v_cvt_pk_bf16_f32 v48, v48, s0
	v_lshl_add_u64 v[56:57], v[88:89], 0, v[56:57]
	s_waitcnt lgkmcnt(0)
	s_barrier
	ds_read_b128 v[168:171], v115
	ds_read_b128 v[172:175], v116
	ds_read_b128 v[176:179], v130
	ds_read_b128 v[180:183], v117
	ds_read_b128 v[184:187], v117 offset:17408
	ds_read_b128 v[188:191], v130 offset:64
	ds_read_b128 v[192:195], v117 offset:64
	ds_read_b128 v[196:199], v117 offset:17472
	ds_read_b128 v[200:203], v130 offset:128
	ds_read_b128 v[204:207], v117 offset:128
	ds_read_b128 v[208:211], v117 offset:17536
	ds_read_b128 v[212:215], v130 offset:192
	ds_read_b128 v[216:219], v117 offset:192
	ds_read_b128 v[220:223], v117 offset:17600
	ds_read_u16 v166, v131 offset:44032
	s_waitcnt lgkmcnt(14)
	ds_read_u16 v167, v131 offset:44176
	s_waitcnt lgkmcnt(14)
	ds_read_u16 v224, v131 offset:44320
	s_waitcnt lgkmcnt(14)
	ds_read_u16 v225, v131 offset:44464
	global_store_short v[56:57], v48, off
	v_add_u32_e32 v48, s27, v140
	v_cvt_pk_bf16_f32 v58, v49, s0
	v_ashrrev_i32_e32 v49, 31, v48
	v_lshl_add_u64 v[48:49], v[48:49], 0, s[16:17]
	v_lshlrev_b64 v[48:49], 13, v[48:49]
	v_lshl_add_u64 v[48:49], v[88:89], 0, v[48:49]
	global_store_short v[48:49], v58, off
	v_add_u32_e32 v58, s27, v139
	v_ashrrev_i32_e32 v59, 31, v58
	v_lshl_add_u64 v[58:59], v[58:59], 0, s[16:17]
	v_add_u32_e32 v4, s65, v138
	v_lshlrev_b64 v[58:59], 13, v[58:59]
	v_ashrrev_i32_e32 v5, 31, v4
	v_cvt_pk_bf16_f32 v50, v50, s0
	v_lshl_add_u64 v[58:59], v[88:89], 0, v[58:59]
	v_lshlrev_b64 v[4:5], 8, v[4:5]
	global_store_short v[58:59], v50, off
	v_add_u32_e32 v50, s27, v87
	v_lshl_add_u64 v[4:5], s[36:37], 0, v[4:5]
	v_cvt_pk_bf16_f32 v60, v51, s0
	v_ashrrev_i32_e32 v51, 31, v50
	v_cvt_pk_bf16_f32 v52, v52, s0
	global_load_dword v143, v[4:5], off
	v_add_u32_e32 v4, s42, v136
	v_add_u32_e32 v12, s42, v137
	v_add_u32_e32 v20, s42, v85
	v_lshl_add_u64 v[50:51], v[50:51], 0, s[16:17]
	global_store_short v[56:57], v52, off offset:32
	v_cvt_pk_bf16_f32 v52, v53, s0
	v_ashrrev_i32_e32 v5, 31, v4
	v_ashrrev_i32_e32 v13, 31, v12
	v_ashrrev_i32_e32 v21, 31, v20
	v_lshlrev_b64 v[50:51], 13, v[50:51]
	global_store_short v[48:49], v52, off offset:32
	v_cvt_pk_bf16_f32 v48, v54, s0
	v_lshlrev_b64 v[8:9], 12, v[4:5]
	v_lshlrev_b64 v[16:17], 12, v[12:13]
	v_lshlrev_b64 v[20:21], 13, v[20:21]
	v_lshl_add_u64 v[50:51], v[88:89], 0, v[50:51]
	global_store_short v[58:59], v48, off offset:32
	v_cvt_pk_bf16_f32 v48, v55, s0
	v_lshl_add_u64 v[6:7], v[68:69], 2, s[62:63]
	v_lshl_add_u64 v[4:5], v[90:91], 0, v[8:9]
	v_lshl_add_u64 v[8:9], v[92:93], 0, v[8:9]
	v_lshl_add_u64 v[12:13], v[90:91], 0, v[16:17]
	v_lshl_add_u64 v[16:17], v[92:93], 0, v[16:17]
	v_lshl_add_u64 v[20:21], v[94:95], 0, v[20:21]
	global_store_short v[50:51], v60, off
	global_store_short v[50:51], v48, off offset:32
	global_load_dword v153, v71, s[62:63] offset:252
	global_load_dword v142, v[6:7], off
	s_add_i32 s39, s39, -1
	global_load_dwordx4 v[8:11], v[8:9], off
	s_cmpk_eq_i32 s40, 0x44
	global_load_dwordx4 v[12:15], v[12:13], off
	s_nop 0
	global_load_dwordx4 v[4:7], v[4:5], off
	s_nop 0
	global_load_dwordx4 v[16:19], v[16:17], off
	s_nop 0
	global_load_dwordx4 v[20:23], v[20:21], off
	s_nop 0
	global_load_dwordx4 v[24:27], v[24:25], off
	s_nop 0
	global_load_dwordx4 v[28:31], v[28:29], off
	s_waitcnt lgkmcnt(15)
	s_waitcnt lgkmcnt(14)
	v_mfma_f32_16x16x32_bf16 v[60:63], v[180:183], v[176:179], 0
	ds_read_b128 v[180:183], v132
	s_waitcnt lgkmcnt(14)
	v_mfma_f32_16x16x32_bf16 v[56:59], v[184:187], v[176:179], 0
	ds_read_b128 v[176:179], v117
	s_waitcnt lgkmcnt(14)
	ds_read_b128 v[184:187], v117 offset:17408
	s_waitcnt lgkmcnt(14)
	v_mfma_f32_16x16x32_bf16 v[60:63], v[192:195], v[188:191], v[60:63]
	ds_read_b128 v[192:195], v132 offset:64
	s_waitcnt lgkmcnt(14)
	v_mfma_f32_16x16x32_bf16 v[56:59], v[196:199], v[188:191], v[56:59]
	ds_read_b128 v[188:191], v117 offset:64
	s_waitcnt lgkmcnt(14)
	ds_read_b128 v[196:199], v117 offset:17472
	s_waitcnt lgkmcnt(14)
	v_mfma_f32_16x16x32_bf16 v[60:63], v[204:207], v[200:203], v[60:63]
	ds_read_b128 v[204:207], v132 offset:128
	s_waitcnt lgkmcnt(14)
	v_mfma_f32_16x16x32_bf16 v[56:59], v[208:211], v[200:203], v[56:59]
	ds_read_b128 v[200:203], v117 offset:128
	s_waitcnt lgkmcnt(14)
	ds_read_b128 v[208:211], v117 offset:17536
	s_waitcnt lgkmcnt(14)
	ds_read_b128 v[158:161], v132 offset:192
	v_mfma_f32_16x16x32_bf16 v[60:63], v[216:219], v[212:215], v[60:63]
	s_waitcnt lgkmcnt(14)
	ds_read_b128 v[216:219], v117 offset:192
	s_waitcnt lgkmcnt(14)
	ds_read_b128 v[162:165], v117 offset:17600
	v_mfma_f32_16x16x32_bf16 v[56:59], v[220:223], v[212:215], v[56:59]
	s_waitcnt lgkmcnt(14)
	ds_read_u16 v212, v131 offset:44064
	s_waitcnt lgkmcnt(14)
	ds_read_u16 v213, v131 offset:44208
	v_lshlrev_b32_e32 v64, 16, v166
	s_waitcnt lgkmcnt(14)
	ds_read_u16 v166, v131 offset:44352
	v_lshlrev_b32_e32 v65, 16, v167
	s_waitcnt lgkmcnt(14)
	ds_read_u16 v167, v131 offset:44496
	v_lshlrev_b32_e32 v67, 16, v225
	s_waitcnt lgkmcnt(14)
	ds_read_b128 v[220:223], v133
	v_lshlrev_b32_e32 v66, 16, v224
	s_waitcnt lgkmcnt(14)
	ds_read_b128 v[224:227], v133 offset:4352
	v_pk_fma_f32 v[60:61], v[168:169], v[60:61], v[64:65] neg_lo:[1,0,0] neg_hi:[1,0,0]
	v_pk_fma_f32 v[62:63], v[170:171], v[62:63], v[66:67] neg_lo:[1,0,0] neg_hi:[1,0,0]
	v_pk_mul_f32 v[64:65], v[172:173], v[60:61]
	v_pk_mul_f32 v[62:63], v[174:175], v[62:63]
	v_cvt_pk_bf16_f32 v64, v64, v65
	v_cvt_pk_bf16_f32 v65, v62, v63
	s_waitcnt lgkmcnt(14)
	ds_write_b64 v145, v[64:65]
	v_mfma_f32_16x16x32_bf16 v[154:157], v[176:179], v[180:183], 0
	s_waitcnt lgkmcnt(14)
	ds_read_b128 v[176:179], v133 offset:8704
	v_mul_f32_e64 v60, v168, s20
	v_mul_f32_e64 v61, v169, s20
	v_pk_mul_f32 v[66:67], v[170:171], s[20:21] op_sel_hi:[1,0]
	v_pk_mul_f32 v[56:57], v[60:61], v[56:57]
	v_mfma_f32_16x16x32_bf16 v[62:65], v[184:187], v[180:183], 0
	s_waitcnt lgkmcnt(14)
	ds_read_b128 v[180:183], v133 offset:13056
	v_pk_mul_f32 v[58:59], v[66:67], v[58:59]
	v_mfma_f32_16x16x32_bf16 v[154:157], v[188:191], v[192:195], v[154:157]
	v_mfma_f32_16x16x32_bf16 v[62:65], v[196:199], v[192:195], v[62:65]
	s_waitcnt lgkmcnt(13)
	v_mfma_f32_16x16x32_bf16 v[154:157], v[200:203], v[204:207], v[154:157]
	s_waitcnt lgkmcnt(12)
	v_mfma_f32_16x16x32_bf16 v[62:65], v[208:211], v[204:207], v[62:65]
	s_waitcnt lgkmcnt(11)
	s_waitcnt lgkmcnt(10)
	v_mfma_f32_16x16x32_bf16 v[154:157], v[216:219], v[158:161], v[154:157]
	s_waitcnt lgkmcnt(9)
	v_mfma_f32_16x16x32_bf16 v[62:65], v[162:165], v[158:161], v[62:65]
	s_waitcnt lgkmcnt(8)
	v_lshlrev_b32_e32 v158, 16, v212
	s_waitcnt lgkmcnt(7)
	v_lshlrev_b32_e32 v159, 16, v213
	s_nop 1
	v_pk_fma_f32 v[48:49], v[168:169], v[154:155], v[158:159] neg_lo:[1,0,0] neg_hi:[1,0,0]
	s_nop 0
	v_pk_mul_f32 v[48:49], v[172:173], v[48:49]
	s_nop 1
	v_cvt_pk_bf16_f32 v48, v48, v49
	s_waitcnt lgkmcnt(6)
	v_lshlrev_b32_e32 v52, 16, v166
	s_waitcnt lgkmcnt(5)
	v_lshlrev_b32_e32 v53, 16, v167
	v_pk_fma_f32 v[50:51], v[170:171], v[156:157], v[52:53] neg_lo:[1,0,0] neg_hi:[1,0,0]
	v_pk_mul_f32 v[52:53], v[60:61], v[62:63]
	v_pk_mul_f32 v[50:51], v[174:175], v[50:51]
	v_pk_mul_f32 v[54:55], v[66:67], v[64:65]
	v_cvt_pk_bf16_f32 v49, v50, v51
	ds_write_b64 v146, v[48:49]
	s_waitcnt lgkmcnt(5)
	v_mfma_f32_16x16x32_bf16 v[48:51], v[220:223], v[0:3], 0
	s_nop 7
	v_cvt_pk_bf16_f32 v60, v48, v49
	v_cvt_pk_bf16_f32 v61, v50, v51
	s_waitcnt lgkmcnt(4)
	v_mfma_f32_16x16x32_bf16 v[48:51], v[224:227], v[0:3], 0
	s_nop 7
	v_cvt_pk_bf16_f32 v62, v48, v49
	v_cvt_pk_bf16_f32 v63, v50, v51
	s_waitcnt lgkmcnt(2)
	v_mfma_f32_16x16x32_bf16 v[48:51], v[176:179], v[0:3], 0
	s_nop 7
	v_cvt_pk_bf16_f32 v64, v48, v49
	v_cvt_pk_bf16_f32 v65, v50, v51
	s_waitcnt lgkmcnt(1)
	v_mfma_f32_16x16x32_bf16 v[48:51], v[180:183], v[0:3], 0
	s_waitcnt lgkmcnt(0)
	s_barrier
	ds_read_b128 v[168:171], v119
	ds_read_b128 v[172:175], v120 offset:53248
	ds_read_b128 v[176:179], v122
	ds_read_b128 v[180:183], v120 offset:53312
	ds_read_b128 v[184:187], v122 offset:64
	ds_read_b128 v[188:191], v120 offset:53248
	ds_read_b128 v[192:195], v125
	v_cvt_pk_bf16_f32 v66, v48, v49
	v_cvt_pk_bf16_f32 v67, v50, v51
	s_waitcnt lgkmcnt(7)
	s_waitcnt lgkmcnt(4)
	v_mfma_f32_16x16x32_bf16 v[154:157], v[172:175], v[176:179], 0
	s_waitcnt lgkmcnt(2)
	v_mfma_f32_16x16x32_bf16 v[154:157], v[180:183], v[184:187], v[154:157]
	s_nop 7
	v_cvt_pk_bf16_f32 v158, v154, v155
	v_cvt_pk_bf16_f32 v159, v156, v157
	v_pk_mul_f32 v[154:155], v[168:169], v[154:155]
	v_pk_mul_f32 v[156:157], v[170:171], v[156:157]
	v_cvt_pk_bf16_f32 v154, v154, v155
	v_cvt_pk_bf16_f32 v155, v156, v157
	ds_write_b64 v123, v[158:159]
	ds_read_b128 v[158:161], v120 offset:53312
	ds_read_b128 v[162:165], v125 offset:64
	ds_write_b64 v124, v[154:155] offset:34816
	s_waitcnt lgkmcnt(4)
	v_mfma_f32_16x16x32_bf16 v[154:157], v[188:191], v[192:195], 0
	s_waitcnt lgkmcnt(1)
	v_mfma_f32_16x16x32_bf16 v[154:157], v[158:161], v[162:165], v[154:157]
	s_nop 7
	v_pk_mul_f32 v[48:49], v[168:169], v[154:155]
	v_pk_mul_f32 v[50:51], v[170:171], v[156:157]
	v_cvt_pk_bf16_f32 v158, v154, v155
	v_cvt_pk_bf16_f32 v159, v156, v157
	v_cvt_pk_bf16_f32 v48, v48, v49
	v_cvt_pk_bf16_f32 v49, v50, v51
	ds_write_b64 v126, v[158:159]
	ds_write_b64 v127, v[48:49] offset:34816
	s_waitcnt lgkmcnt(0)
	s_barrier
	ds_read_b128 v[168:171], v120 offset:62464
	ds_read_b128 v[172:175], v147
	ds_read_b128 v[176:179], v120 offset:62528
	ds_read_b128 v[180:183], v147 offset:64
	ds_read_b128 v[158:161], v148
	ds_read_b128 v[154:157], v148 offset:64
	ds_read2_b64 v[184:187], v149 offset1:4
	ds_read2_b64 v[188:191], v149 offset0:8 offset1:12
	ds_read2_b64 v[192:195], v150 offset0:32 offset1:36
	ds_read2_b64 v[196:199], v150 offset0:40 offset1:44
	ds_read2_b64 v[200:203], v151 offset0:64 offset1:68
	ds_read2_b64 v[204:207], v151 offset0:72 offset1:76
	ds_read2_b64 v[208:211], v152 offset0:96 offset1:100
	s_waitcnt lgkmcnt(13)
	s_waitcnt lgkmcnt(11)
	v_mfma_f32_16x16x32_bf16 v[48:51], v[168:171], v[172:175], v[56:59]
	s_waitcnt lgkmcnt(9)
	v_mfma_f32_16x16x32_bf16 v[48:51], v[176:179], v[180:183], v[48:51]
	s_waitcnt lgkmcnt(8)
	v_mfma_f32_16x16x32_bf16 v[52:55], v[168:171], v[158:161], v[52:55]
	s_waitcnt lgkmcnt(7)
	v_mfma_f32_16x16x32_bf16 v[52:55], v[176:179], v[154:157], v[52:55]
	v_mul_f32_e32 v56, 0x3fb8aa3b, v144
	v_exp_f32_e32 v144, v56
	s_nop 0
	v_pk_mul_f32 v[34:35], v[34:35], v[144:145] op_sel_hi:[1,0]
	v_pk_mul_f32 v[32:33], v[32:33], v[144:145] op_sel_hi:[1,0]
	v_pk_mul_f32 v[38:39], v[38:39], v[144:145] op_sel_hi:[1,0]
	v_pk_mul_f32 v[36:37], v[36:37], v[144:145] op_sel_hi:[1,0]
	s_waitcnt lgkmcnt(6)
	v_mfma_f32_16x16x32_bf16 v[32:35], v[60:63], v[184:187], v[32:35]
	v_pk_mul_f32 v[42:43], v[42:43], v[144:145] op_sel_hi:[1,0]
	v_pk_mul_f32 v[40:41], v[40:41], v[144:145] op_sel_hi:[1,0]
	s_waitcnt lgkmcnt(5)
	v_mfma_f32_16x16x32_bf16 v[32:35], v[64:67], v[188:191], v[32:35]
	v_mul_f32_e64 v46, v46, v144
	v_mul_f32_e64 v47, v47, v144
	v_pk_mul_f32 v[44:45], v[44:45], v[144:145] op_sel_hi:[1,0]
	s_nop 4
	v_cvt_pk_bf16_f32 v56, v32, v33
	v_cvt_pk_bf16_f32 v57, v34, v35
	ds_write_b64 v135, v[56:57]
	s_waitcnt lgkmcnt(5)
	v_mfma_f32_16x16x32_bf16 v[36:39], v[60:63], v[192:195], v[36:39]
	s_waitcnt lgkmcnt(4)
	v_mfma_f32_16x16x32_bf16 v[36:39], v[64:67], v[196:199], v[36:39]
	s_nop 7
	v_cvt_pk_bf16_f32 v56, v36, v37
	v_cvt_pk_bf16_f32 v57, v38, v39
	ds_write_b64 v135, v[56:57] offset:4352
	s_waitcnt lgkmcnt(4)
	v_mfma_f32_16x16x32_bf16 v[40:43], v[60:63], v[200:203], v[40:43]
	s_waitcnt lgkmcnt(3)
	v_mfma_f32_16x16x32_bf16 v[40:43], v[64:67], v[204:207], v[40:43]
	s_nop 7
	v_cvt_pk_bf16_f32 v56, v40, v41
	v_cvt_pk_bf16_f32 v57, v42, v43
	ds_write_b64 v135, v[56:57] offset:8704
	ds_read2_b64 v[56:59], v152 offset0:104 offset1:108
	s_waitcnt lgkmcnt(4)
	v_mfma_f32_16x16x32_bf16 v[44:47], v[60:63], v[208:211], v[44:47]
	s_waitcnt lgkmcnt(0)
	v_mfma_f32_16x16x32_bf16 v[44:47], v[64:67], v[56:59], v[44:47]
	s_nop 7
	v_cvt_pk_bf16_f32 v56, v44, v45
	v_cvt_pk_bf16_f32 v57, v46, v47
	ds_write_b64 v135, v[56:57] offset:13056
	s_waitcnt lgkmcnt(0)
	s_barrier
	s_cbranch_scc1 .LBB0_2541
	s_mov_b32 s27, s40
	s_waitcnt vmcnt(8)
	v_mov_b32_e32 v144, v153
	s_branch .LBB0_2548

.LBB0_2607:
	v_lshl_add_u64 v[60:61], s[22:23], 0, v[20:21]
	global_load_dwordx4 v[64:67], v[60:61], off
	v_lshl_add_u64 v[62:63], s[16:17], 0, v[20:21]
	v_add_co_u32_e32 v8, vcc, 0x4400000, v60
	s_nop 1
	v_addc_co_u32_e32 v9, vcc, 0, v61, vcc
	global_load_dwordx4 v[68:71], v[8:9], off
	v_lshl_add_u64 v[60:61], s[20:21], 0, v[20:21]
	global_load_dwordx4 v[72:75], v[60:61], off
	global_load_dwordx4 v[76:79], v[62:63], off
	s_mov_b32 s10, 0x4400000
	s_nop 0
	v_add_co_u32_e32 v12, vcc, s10, v62
	v_lshl_add_u64 v[16:17], s[14:15], 0, v[20:21]
	s_nop 0
	v_addc_co_u32_e32 v13, vcc, 0, v63, vcc
	global_load_dwordx4 v[12:15], v[12:13], off
	s_brev_b32 s10, 60
	global_load_dwordx4 v[16:19], v[16:17], off
	s_add_i32 s13, s13, 2
	s_add_u32 s14, s14, 0xc000
	s_addc_u32 s15, s15, 0
	s_add_u32 s16, s16, 0x4000
	s_addc_u32 s17, s17, 0
	s_waitcnt vmcnt(6)
	s_waitcnt vmcnt(5)
	v_lshlrev_b32_e32 v24, 16, v67
	v_and_b32_e32 v25, 0xffff0000, v67
	s_waitcnt vmcnt(4)
	v_lshlrev_b32_e32 v26, 16, v71
	v_and_b32_e32 v27, 0xffff0000, v71
	v_pk_add_f32 v[24:25], v[24:25], v[26:27]
	v_lshlrev_b32_e32 v26, 16, v66
	v_and_b32_e32 v27, 0xffff0000, v66
	v_lshlrev_b32_e32 v28, 16, v70
	v_and_b32_e32 v29, 0xffff0000, v70
	v_pk_add_f32 v[26:27], v[26:27], v[28:29]
	v_mov_b32_e32 v30, v24
	v_mov_b32_e32 v31, v26
	s_waitcnt vmcnt(3)
	v_lshlrev_b32_e32 v28, 16, v74
	v_and_b32_e32 v29, 0xffff0000, v74
	v_pk_mul_f32 v[30:31], v[30:31], v[30:31]
	v_mov_b32_e32 v32, v25
	v_mov_b32_e32 v33, v27
	v_pk_fma_f32 v[40:41], v[32:33], v[32:33], v[30:31]
	v_mul_f32_e32 v30, 0xbfb8aa3b, v28
	v_mul_f32_e32 v31, 0xbfb8aa3b, v29
	v_exp_f32_e32 v30, v30
	v_exp_f32_e32 v31, v31
	v_lshlrev_b32_e32 v32, 16, v69
	v_and_b32_e32 v33, 0xffff0000, v69
	v_add_f32_e32 v30, 1.0, v30
	v_add_f32_e32 v31, 1.0, v31
	v_rcp_f32_e32 v30, v30
	v_rcp_f32_e32 v31, v31
	v_lshlrev_b32_e32 v52, 16, v75
	v_and_b32_e32 v53, 0xffff0000, v75
	s_waitcnt vmcnt(2)
	v_lshlrev_b32_e32 v50, 16, v79
	v_pk_mul_f32 v[28:29], v[30:31], v[28:29]
	v_lshlrev_b32_e32 v30, 16, v65
	v_and_b32_e32 v31, 0xffff0000, v65
	v_pk_add_f32 v[30:31], v[30:31], v[32:33]
	v_lshlrev_b32_e32 v32, 16, v73
	v_mul_f32_e32 v35, 0xbfb8aa3b, v32
	v_exp_f32_e32 v35, v35
	v_and_b32_e32 v33, 0xffff0000, v73
	v_mov_b32_e32 v39, v30
	v_mov_b32_e32 v43, v31
	v_add_f32_e32 v35, 1.0, v35
	v_rcp_f32_e32 v36, v35
	v_mul_f32_e32 v35, 0xbfb8aa3b, v33
	v_exp_f32_e32 v35, v35
	v_and_b32_e32 v51, 0xffff0000, v79
	v_lshlrev_b32_e32 v54, 16, v78
	v_and_b32_e32 v55, 0xffff0000, v78
	v_add_f32_e32 v35, 1.0, v35
	v_rcp_f32_e32 v37, v35
	v_and_b32_e32 v35, 0xffff0000, v68
	s_waitcnt vmcnt(1)
	v_lshlrev_b32_e32 v10, 16, v14
	v_and_b32_e32 v11, 0xffff0000, v14
	v_pk_mul_f32 v[32:33], v[36:37], v[32:33]
	v_lshlrev_b32_e32 v36, 16, v64
	v_and_b32_e32 v37, 0xffff0000, v64
	v_lshlrev_b32_e32 v34, 16, v68
	v_pk_add_f32 v[34:35], v[36:37], v[34:35]
	v_lshlrev_b32_e32 v36, 16, v72
	v_mov_b32_e32 v38, v34
	v_and_b32_e32 v37, 0xffff0000, v72
	v_pk_mul_f32 v[38:39], v[38:39], v[38:39]
	v_mov_b32_e32 v42, v35
	v_pk_fma_f32 v[42:43], v[42:43], v[42:43], v[38:39]
	v_mul_f32_e32 v38, 0xbfb8aa3b, v36
	v_mul_f32_e32 v39, 0xbfb8aa3b, v37
	v_exp_f32_e32 v38, v38
	v_exp_f32_e32 v39, v39
	v_lshlrev_b32_e32 v56, 16, v13
	v_and_b32_e32 v57, 0xffff0000, v13
	v_add_f32_e32 v38, 1.0, v38
	v_add_f32_e32 v39, 1.0, v39
	v_rcp_f32_e32 v38, v38
	v_rcp_f32_e32 v39, v39
	v_lshl_add_u64 v[48:49], s[28:29], 0, v[20:21]
	v_pk_mul_f32 v[38:39], v[38:39], v[36:37]
	v_mul_f32_e32 v36, 0xbfb8aa3b, v52
	v_mul_f32_e32 v37, 0xbfb8aa3b, v53
	v_exp_f32_e32 v36, v36
	v_exp_f32_e32 v37, v37
	v_add_f32_e32 v36, 1.0, v36
	v_add_f32_e32 v37, 1.0, v37
	v_rcp_f32_e32 v36, v36
	v_rcp_f32_e32 v37, v37
	s_nop 0
	v_pk_mul_f32 v[36:37], v[36:37], v[52:53]
	v_lshlrev_b32_e32 v52, 16, v15
	v_and_b32_e32 v53, 0xffff0000, v15
	v_pk_add_f32 v[14:15], v[54:55], v[10:11]
	s_waitcnt vmcnt(0)
	v_lshlrev_b32_e32 v10, 16, v18
	v_mul_f32_e32 v47, 0xbfb8aa3b, v10
	v_exp_f32_e32 v47, v47
	v_pk_add_f32 v[50:51], v[50:51], v[52:53]
	v_lshlrev_b32_e32 v52, 16, v19
	v_and_b32_e32 v53, 0xffff0000, v19
	v_and_b32_e32 v11, 0xffff0000, v18
	v_mov_b32_e32 v18, v50
	v_mov_b32_e32 v19, v14
	v_pk_mul_f32 v[18:19], v[18:19], v[18:19]
	v_mov_b32_e32 v54, v51
	v_mov_b32_e32 v55, v15
	v_add_f32_e32 v47, 1.0, v47
	v_pk_fma_f32 v[18:19], v[54:55], v[54:55], v[18:19]
	v_rcp_f32_e32 v54, v47
	v_mul_f32_e32 v47, 0xbfb8aa3b, v11
	v_exp_f32_e32 v47, v47
	s_nop 0
	v_add_f32_e32 v47, 1.0, v47
	v_rcp_f32_e32 v55, v47
	s_nop 0
	v_pk_mul_f32 v[54:55], v[54:55], v[10:11]
	v_lshlrev_b32_e32 v10, 16, v77
	v_and_b32_e32 v11, 0xffff0000, v77
	v_pk_add_f32 v[56:57], v[10:11], v[56:57]
	v_lshlrev_b32_e32 v10, 16, v17
	v_mul_f32_e32 v9, 0xbfb8aa3b, v10
	v_exp_f32_e32 v9, v9
	v_and_b32_e32 v11, 0xffff0000, v17
	v_mov_b32_e32 v17, v57
	v_add_f32_e32 v9, 1.0, v9
	v_rcp_f32_e32 v58, v9
	v_mul_f32_e32 v9, 0xbfb8aa3b, v11
	v_exp_f32_e32 v9, v9
	s_nop 0
	v_add_f32_e32 v9, 1.0, v9
	v_rcp_f32_e32 v59, v9
	v_and_b32_e32 v9, 0xffff0000, v12
	v_pk_mul_f32 v[58:59], v[58:59], v[10:11]
	v_lshlrev_b32_e32 v10, 16, v76
	v_and_b32_e32 v11, 0xffff0000, v76
	v_lshlrev_b32_e32 v8, 16, v12
	v_pk_add_f32 v[12:13], v[10:11], v[8:9]
	v_mov_b32_e32 v11, v56
	v_mov_b32_e32 v10, v12
	v_lshlrev_b32_e32 v8, 16, v16
	v_and_b32_e32 v9, 0xffff0000, v16
	v_pk_mul_f32 v[10:11], v[10:11], v[10:11]
	v_mov_b32_e32 v16, v13
	v_pk_fma_f32 v[10:11], v[16:17], v[16:17], v[10:11]
	v_mul_f32_e32 v16, 0xbfb8aa3b, v8
	v_mul_f32_e32 v17, 0xbfb8aa3b, v9
	v_exp_f32_e32 v16, v16
	v_exp_f32_e32 v17, v17
	v_add_f32_e32 v16, 1.0, v16
	v_add_f32_e32 v17, 1.0, v17
	v_rcp_f32_e32 v16, v16
	v_rcp_f32_e32 v17, v17
	s_nop 0
	v_pk_mul_f32 v[16:17], v[16:17], v[8:9]
	v_mov_b32_e32 v8, v10
	v_mov_b32_e32 v9, v42
	v_mov_b32_e32 v42, v11
	v_pk_add_f32 v[8:9], v[8:9], v[42:43]
	v_mov_b32_e32 v10, v19
	v_mov_b32_e32 v11, v41
	v_pk_add_f32 v[8:9], v[10:11], v[8:9]
	v_mov_b32_e32 v19, v40
	v_pk_add_f32 v[8:9], v[18:19], v[8:9]
	ds_bpermute_b32 v11, v23, v9
	ds_bpermute_b32 v10, v23, v8
	s_waitcnt lgkmcnt(0)
	v_pk_add_f32 v[8:9], v[8:9], v[10:11]
	ds_bpermute_b32 v11, v44, v9
	ds_bpermute_b32 v10, v44, v8
	s_waitcnt lgkmcnt(0)
	v_pk_add_f32 v[8:9], v[8:9], v[10:11]
	ds_bpermute_b32 v11, v45, v9
	ds_bpermute_b32 v10, v45, v8
	s_waitcnt lgkmcnt(0)
	v_pk_add_f32 v[8:9], v[8:9], v[10:11]
	ds_bpermute_b32 v11, v46, v9
	ds_bpermute_b32 v10, v46, v8
	s_waitcnt lgkmcnt(0)
	v_pk_add_f32 v[8:9], v[8:9], v[10:11]
	s_nop 0
	v_pk_fma_f32 v[18:19], v[8:9], s[10:11], v[22:23] op_sel_hi:[1,0,0]
	s_nop 0
	v_mul_f32_e32 v8, 0x4b800000, v19
	v_cmp_gt_f32_e64 s[10:11], s4, v19
	v_cmp_gt_f32_e32 vcc, s4, v18
	s_nop 0
	v_cndmask_b32_e64 v8, v19, v8, s[10:11]
	v_rsq_f32_e32 v8, v8
	s_nop 0
	v_mul_f32_e32 v9, 0x45800000, v8
	v_cndmask_b32_e64 v40, v8, v9, s[10:11]
	v_pk_mul_f32 v[8:9], v[34:35], v[40:41] op_sel_hi:[1,0]
	v_pk_mul_f32 v[10:11], v[30:31], v[40:41] op_sel_hi:[1,0]
	v_pk_mul_f32 v[8:9], v[4:5], v[8:9]
	v_pk_mul_f32 v[10:11], v[6:7], v[10:11]
	v_pk_mul_f32 v[8:9], v[38:39], v[8:9]
	v_pk_mul_f32 v[10:11], v[32:33], v[10:11]
	v_cvt_pk_bf16_f32 v8, v8, v9
	v_cvt_pk_bf16_f32 v9, v10, v11
	v_pk_mul_f32 v[10:11], v[26:27], v[40:41] op_sel_hi:[1,0]
	v_pk_mul_f32 v[24:25], v[24:25], v[40:41] op_sel_hi:[1,0]
	v_pk_mul_f32 v[10:11], v[0:1], v[10:11]
	v_pk_mul_f32 v[24:25], v[2:3], v[24:25]
	v_pk_mul_f32 v[10:11], v[28:29], v[10:11]
	v_pk_mul_f32 v[24:25], v[36:37], v[24:25]
	v_cvt_pk_bf16_f32 v10, v10, v11
	v_cvt_pk_bf16_f32 v11, v24, v25
	global_store_dwordx4 v[48:49], v[8:11], off
	s_nop 1
	v_mul_f32_e32 v8, 0x4b800000, v18
	v_cndmask_b32_e32 v8, v18, v8, vcc
	v_rsq_f32_e32 v8, v8
	s_nop 0
	v_mul_f32_e32 v9, 0x45800000, v8
	v_cndmask_b32_e32 v18, v8, v9, vcc
	v_pk_mul_f32 v[8:9], v[12:13], v[18:19] op_sel_hi:[1,0]
	v_pk_mul_f32 v[10:11], v[56:57], v[18:19] op_sel_hi:[1,0]
	v_pk_mul_f32 v[8:9], v[4:5], v[8:9]
	v_pk_mul_f32 v[10:11], v[6:7], v[10:11]
	v_pk_mul_f32 v[8:9], v[16:17], v[8:9]
	v_pk_mul_f32 v[10:11], v[58:59], v[10:11]
	v_cvt_pk_bf16_f32 v8, v8, v9
	v_cvt_pk_bf16_f32 v9, v10, v11
	v_pk_mul_f32 v[10:11], v[14:15], v[18:19] op_sel_hi:[1,0]
	v_pk_mul_f32 v[14:15], v[50:51], v[18:19] op_sel_hi:[1,0]
	v_pk_mul_f32 v[10:11], v[0:1], v[10:11]
	v_pk_mul_f32 v[14:15], v[2:3], v[14:15]
	v_pk_mul_f32 v[10:11], v[54:55], v[10:11]
	s_nop 0
	v_cvt_pk_bf16_f32 v10, v10, v11
	v_mul_f32_e32 v11, 0xbfb8aa3b, v52
	v_exp_f32_e32 v11, v11
	s_nop 0
	v_add_f32_e32 v11, 1.0, v11
	v_rcp_f32_e32 v12, v11
	v_mul_f32_e32 v11, 0xbfb8aa3b, v53
	v_exp_f32_e32 v11, v11
	s_nop 0
	v_add_f32_e32 v11, 1.0, v11
	v_rcp_f32_e32 v13, v11
	s_nop 0
	v_pk_mul_f32 v[12:13], v[12:13], v[52:53]
	s_nop 0
	v_pk_mul_f32 v[12:13], v[12:13], v[14:15]
	s_nop 0
	v_cvt_pk_bf16_f32 v11, v12, v13
	v_lshl_add_u64 v[12:13], s[18:19], 0, v[20:21]
	s_add_u32 s18, s18, 0x4000
	s_addc_u32 s19, s19, 0
	s_add_u32 s20, s20, 0xc000
	s_addc_u32 s21, s21, 0
	s_add_u32 s22, s22, 0x4000
	s_addc_u32 s23, s23, 0
	s_add_u32 s28, s28, 0x4000
	s_addc_u32 s29, s29, 0
	s_cmp_ge_i32 s13, s5
	global_store_dwordx4 v[12:13], v[8:11], off
	s_cbranch_scc0 .LBB0_2607
	s_add_i32 s26, s26, s43
	s_add_i32 s1, s1, s43
	s_add_i32 s12, s12, s43
	s_cmpk_gt_i32 s26, 0x21ff
	s_cbranch_scc0 .LBB0_2606

.LBB0_2748:
	global_load_dwordx4 v[28:31], v[56:57], off offset:-4096
	global_load_dwordx4 v[24:27], v[56:57], off offset:-3072
	global_load_dwordx4 v[20:23], v[56:57], off offset:-2048
	global_load_dwordx4 v[16:19], v[56:57], off offset:-1024
	global_load_dwordx4 v[12:15], v[56:57], off
	global_load_dwordx4 v[8:11], v[56:57], off offset:1024
	global_load_dwordx4 v[4:7], v[56:57], off offset:2048
	global_load_dwordx4 v[0:3], v[56:57], off offset:3072
	s_cmpk_lt_i32 s28, 0x2000
	s_cbranch_scc1 .LBB0_2750
	s_add_i32 s16, s28, 0xffffe000
	s_lshl_b64 s[30:31], s[16:17], 13
	s_nop 0
	v_lshl_add_u64 v[110:111], v[34:35], 0, s[30:31]
	global_load_dwordx4 v[112:115], v[110:111], off
	s_waitcnt lgkmcnt(0)
	v_add_co_u32_e32 v62, vcc, 0x400000, v110
	s_nop 1
	v_addc_co_u32_e32 v63, vcc, 0, v111, vcc
	global_load_dwordx4 v[116:119], v[62:63], off
	v_add_co_u32_e32 v64, vcc, 0x800000, v110
	s_nop 1
	v_addc_co_u32_e32 v65, vcc, 0, v111, vcc
	global_load_dwordx4 v[120:123], v[64:65], off
	v_add_co_u32_e32 v66, vcc, 0xc00000, v110
	s_nop 1
	v_addc_co_u32_e32 v67, vcc, 0, v111, vcc
	global_load_dwordx4 v[124:127], v[66:67], off
	v_add_co_u32_e32 v68, vcc, 0x1000000, v110
	s_nop 1
	v_addc_co_u32_e32 v69, vcc, 0, v111, vcc
	global_load_dwordx4 v[128:131], v[68:69], off
	v_add_co_u32_e32 v70, vcc, 0x1400000, v110
	s_nop 1
	v_addc_co_u32_e32 v71, vcc, 0, v111, vcc
	global_load_dwordx4 v[132:135], v[70:71], off
	v_add_co_u32_e32 v72, vcc, 0x1800000, v110
	s_nop 1
	v_addc_co_u32_e32 v73, vcc, 0, v111, vcc
	global_load_dwordx4 v[136:139], v[72:73], off
	v_add_co_u32_e32 v74, vcc, 0x1c00000, v110
	s_nop 1
	v_addc_co_u32_e32 v75, vcc, 0, v111, vcc
	global_load_dwordx4 v[140:143], v[74:75], off
	global_load_dwordx4 v[144:147], v[36:37], off
	global_load_dwordx4 v[148:151], v[110:111], off offset:1024
	global_load_dwordx4 v[152:155], v[62:63], off offset:1024
	global_load_dwordx4 v[156:159], v[64:65], off offset:1024
	global_load_dwordx4 v[160:163], v[66:67], off offset:1024
	global_load_dwordx4 v[164:167], v[68:69], off offset:1024
	global_load_dwordx4 v[168:171], v[70:71], off offset:1024
	global_load_dwordx4 v[172:175], v[72:73], off offset:1024
	global_load_dwordx4 v[176:179], v[74:75], off offset:1024
	global_load_dwordx4 v[180:183], v[36:37], off offset:1024
	global_load_dwordx4 v[184:187], v[110:111], off offset:2048
	global_load_dwordx4 v[188:191], v[62:63], off offset:2048
	global_load_dwordx4 v[192:195], v[64:65], off offset:2048
	global_load_dwordx4 v[196:199], v[66:67], off offset:2048
	global_load_dwordx4 v[200:203], v[68:69], off offset:2048
	global_load_dwordx4 v[204:207], v[70:71], off offset:2048
	global_load_dwordx4 v[208:211], v[72:73], off offset:2048
	global_load_dwordx4 v[212:215], v[74:75], off offset:2048
	global_load_dwordx4 v[216:219], v[36:37], off offset:2048
	global_load_dwordx4 v[220:223], v[110:111], off offset:3072
	global_load_dwordx4 v[224:227], v[62:63], off offset:3072
	s_movk_i32 s16, 0x1000
	s_waitcnt vmcnt(29)
	s_waitcnt vmcnt(28)
	v_pk_add_f32 v[80:81], v[114:115], 0 op_sel_hi:[1,0]
	v_pk_add_f32 v[78:79], v[112:113], 0 op_sel_hi:[1,0]
	s_waitcnt vmcnt(27)
	v_pk_add_f32 v[80:81], v[80:81], v[118:119]
	v_pk_add_f32 v[78:79], v[78:79], v[116:117]
	s_waitcnt vmcnt(26)
	v_pk_add_f32 v[80:81], v[80:81], v[122:123]
	v_pk_add_f32 v[78:79], v[78:79], v[120:121]
	s_waitcnt vmcnt(25)
	v_pk_add_f32 v[80:81], v[80:81], v[126:127]
	v_pk_add_f32 v[78:79], v[78:79], v[124:125]
	s_waitcnt vmcnt(24)
	v_pk_add_f32 v[80:81], v[80:81], v[130:131]
	v_pk_add_f32 v[78:79], v[78:79], v[128:129]
	s_waitcnt vmcnt(23)
	v_pk_add_f32 v[80:81], v[80:81], v[134:135]
	v_pk_add_f32 v[78:79], v[78:79], v[132:133]
	s_waitcnt vmcnt(22)
	v_pk_add_f32 v[80:81], v[80:81], v[138:139]
	v_pk_add_f32 v[78:79], v[78:79], v[136:137]
	s_waitcnt vmcnt(21)
	v_pk_add_f32 v[82:83], v[80:81], v[142:143]
	v_pk_add_f32 v[84:85], v[78:79], v[140:141]
	s_waitcnt vmcnt(20)
	v_pk_fma_f32 v[30:31], v[82:83], v[146:147], v[30:31]
	v_pk_fma_f32 v[28:29], v[84:85], v[144:145], v[28:29]
	global_store_dwordx4 v[56:57], v[28:31], off offset:-4096
	s_waitcnt vmcnt(20)
	v_pk_add_f32 v[80:81], v[150:151], 0 op_sel_hi:[1,0]
	v_pk_add_f32 v[78:79], v[148:149], 0 op_sel_hi:[1,0]
	s_waitcnt vmcnt(19)
	v_pk_add_f32 v[80:81], v[80:81], v[154:155]
	v_pk_add_f32 v[78:79], v[78:79], v[152:153]
	s_waitcnt vmcnt(18)
	v_pk_add_f32 v[80:81], v[80:81], v[158:159]
	v_pk_add_f32 v[78:79], v[78:79], v[156:157]
	s_waitcnt vmcnt(17)
	v_pk_add_f32 v[80:81], v[80:81], v[162:163]
	v_pk_add_f32 v[78:79], v[78:79], v[160:161]
	s_waitcnt vmcnt(16)
	v_pk_add_f32 v[80:81], v[80:81], v[166:167]
	v_pk_add_f32 v[78:79], v[78:79], v[164:165]
	s_waitcnt vmcnt(15)
	v_pk_add_f32 v[80:81], v[80:81], v[170:171]
	v_pk_add_f32 v[78:79], v[78:79], v[168:169]
	s_waitcnt vmcnt(14)
	v_pk_add_f32 v[80:81], v[80:81], v[174:175]
	v_pk_add_f32 v[78:79], v[78:79], v[172:173]
	s_waitcnt vmcnt(13)
	v_pk_add_f32 v[82:83], v[80:81], v[178:179]
	v_pk_add_f32 v[84:85], v[78:79], v[176:177]
	s_waitcnt vmcnt(12)
	v_pk_fma_f32 v[26:27], v[82:83], v[182:183], v[26:27]
	v_pk_fma_f32 v[24:25], v[84:85], v[180:181], v[24:25]
	global_store_dwordx4 v[56:57], v[24:27], off offset:-3072
	s_waitcnt vmcnt(12)
	v_pk_add_f32 v[80:81], v[186:187], 0 op_sel_hi:[1,0]
	v_pk_add_f32 v[78:79], v[184:185], 0 op_sel_hi:[1,0]
	s_waitcnt vmcnt(11)
	v_pk_add_f32 v[80:81], v[80:81], v[190:191]
	v_pk_add_f32 v[78:79], v[78:79], v[188:189]
	s_waitcnt vmcnt(10)
	v_pk_add_f32 v[80:81], v[80:81], v[194:195]
	v_pk_add_f32 v[78:79], v[78:79], v[192:193]
	s_waitcnt vmcnt(9)
	v_pk_add_f32 v[80:81], v[80:81], v[198:199]
	v_pk_add_f32 v[78:79], v[78:79], v[196:197]
	s_waitcnt vmcnt(8)
	v_pk_add_f32 v[80:81], v[80:81], v[202:203]
	v_pk_add_f32 v[78:79], v[78:79], v[200:201]
	s_waitcnt vmcnt(7)
	v_pk_add_f32 v[80:81], v[80:81], v[206:207]
	v_pk_add_f32 v[78:79], v[78:79], v[204:205]
	s_waitcnt vmcnt(6)
	v_pk_add_f32 v[80:81], v[80:81], v[210:211]
	v_pk_add_f32 v[78:79], v[78:79], v[208:209]
	s_waitcnt vmcnt(5)
	v_pk_add_f32 v[82:83], v[80:81], v[214:215]
	v_pk_add_f32 v[84:85], v[78:79], v[212:213]
	s_waitcnt vmcnt(4)
	v_pk_fma_f32 v[22:23], v[82:83], v[218:219], v[22:23]
	v_pk_fma_f32 v[20:21], v[84:85], v[216:217], v[20:21]
	global_store_dwordx4 v[56:57], v[20:23], off offset:-2048
	global_load_dwordx4 v[62:65], v[64:65], off offset:3072
	s_nop 0
	global_load_dwordx4 v[112:115], v[66:67], off offset:3072
	global_load_dwordx4 v[66:69], v[68:69], off offset:3072
	s_nop 0
	global_load_dwordx4 v[116:119], v[70:71], off offset:3072
	global_load_dwordx4 v[70:73], v[72:73], off offset:3072
	s_nop 0
	global_load_dwordx4 v[120:123], v[74:75], off offset:3072
	global_load_dwordx4 v[124:127], v[36:37], off offset:3072
	s_waitcnt vmcnt(11)
	v_pk_add_f32 v[74:75], v[222:223], 0 op_sel_hi:[1,0]
	v_pk_add_f32 v[78:79], v[220:221], 0 op_sel_hi:[1,0]
	s_waitcnt vmcnt(10)
	v_pk_add_f32 v[74:75], v[74:75], v[226:227]
	v_pk_add_f32 v[78:79], v[78:79], v[224:225]
	s_waitcnt vmcnt(6)
	v_pk_add_f32 v[64:65], v[74:75], v[64:65]
	v_pk_add_f32 v[62:63], v[78:79], v[62:63]
	s_waitcnt vmcnt(5)
	v_pk_add_f32 v[64:65], v[64:65], v[114:115]
	v_pk_add_f32 v[62:63], v[62:63], v[112:113]
	s_waitcnt vmcnt(4)
	v_pk_add_f32 v[64:65], v[64:65], v[68:69]
	v_pk_add_f32 v[62:63], v[62:63], v[66:67]
	s_waitcnt vmcnt(3)
	v_pk_add_f32 v[64:65], v[64:65], v[118:119]
	v_pk_add_f32 v[62:63], v[62:63], v[116:117]
	s_waitcnt vmcnt(2)
	v_pk_add_f32 v[64:65], v[64:65], v[72:73]
	v_pk_add_f32 v[62:63], v[62:63], v[70:71]
	s_waitcnt vmcnt(1)
	v_pk_add_f32 v[66:67], v[64:65], v[122:123]
	v_pk_add_f32 v[68:69], v[62:63], v[120:121]
	s_waitcnt vmcnt(0)
	s_nop 0
	v_pk_fma_f32 v[16:17], v[68:69], v[124:125], v[16:17]
	v_add_co_u32_e32 v62, vcc, s16, v110
	v_pk_fma_f32 v[18:19], v[66:67], v[126:127], v[18:19]
	s_nop 0
	v_addc_co_u32_e32 v63, vcc, 0, v111, vcc
	global_load_dwordx4 v[112:115], v[62:63], off
	v_add_co_u32_e32 v64, vcc, s1, v110
	global_store_dwordx4 v[56:57], v[16:19], off offset:-1024
	s_nop 0
	v_addc_co_u32_e32 v65, vcc, 0, v111, vcc
	global_load_dwordx4 v[116:119], v[64:65], off
	v_add_co_u32_e32 v66, vcc, s2, v110
	s_nop 1
	v_addc_co_u32_e32 v67, vcc, 0, v111, vcc
	global_load_dwordx4 v[120:123], v[66:67], off
	v_add_co_u32_e32 v68, vcc, s3, v110
	s_nop 1
	v_addc_co_u32_e32 v69, vcc, 0, v111, vcc
	global_load_dwordx4 v[124:127], v[68:69], off
	v_add_co_u32_e32 v70, vcc, s4, v110
	s_nop 1
	v_addc_co_u32_e32 v71, vcc, 0, v111, vcc
	global_load_dwordx4 v[128:131], v[70:71], off
	v_add_co_u32_e32 v72, vcc, s5, v110
	s_nop 1
	v_addc_co_u32_e32 v73, vcc, 0, v111, vcc
	global_load_dwordx4 v[132:135], v[72:73], off
	v_add_co_u32_e32 v74, vcc, s22, v110
	s_nop 1
	v_addc_co_u32_e32 v75, vcc, 0, v111, vcc
	global_load_dwordx4 v[136:139], v[74:75], off
	v_add_co_u32_e32 v60, vcc, s23, v110
	s_nop 1
	v_addc_co_u32_e32 v61, vcc, 0, v111, vcc
	global_load_dwordx4 v[140:143], v[60:61], off
	global_load_dwordx4 v[144:147], v[40:41], off
	global_load_dwordx4 v[148:151], v[62:63], off offset:1024
	global_load_dwordx4 v[152:155], v[64:65], off offset:1024
	global_load_dwordx4 v[156:159], v[66:67], off offset:1024
	global_load_dwordx4 v[160:163], v[68:69], off offset:1024
	global_load_dwordx4 v[164:167], v[70:71], off offset:1024
	global_load_dwordx4 v[168:171], v[72:73], off offset:1024
	global_load_dwordx4 v[172:175], v[74:75], off offset:1024
	global_load_dwordx4 v[176:179], v[60:61], off offset:1024
	global_load_dwordx4 v[180:183], v[42:43], off
	global_load_dwordx4 v[184:187], v[62:63], off offset:2048
	global_load_dwordx4 v[188:191], v[64:65], off offset:2048
	global_load_dwordx4 v[192:195], v[66:67], off offset:2048
	global_load_dwordx4 v[196:199], v[68:69], off offset:2048
	global_load_dwordx4 v[200:203], v[70:71], off offset:2048
	global_load_dwordx4 v[204:207], v[72:73], off offset:2048
	global_load_dwordx4 v[208:211], v[74:75], off offset:2048
	global_load_dwordx4 v[212:215], v[60:61], off offset:2048
	global_load_dwordx4 v[216:219], v[44:45], off
	global_load_dwordx4 v[220:223], v[62:63], off offset:3072
	s_waitcnt vmcnt(28)
	v_pk_add_f32 v[80:81], v[114:115], 0 op_sel_hi:[1,0]
	v_pk_add_f32 v[78:79], v[112:113], 0 op_sel_hi:[1,0]
	s_waitcnt vmcnt(26)
	v_pk_add_f32 v[80:81], v[80:81], v[118:119]
	v_pk_add_f32 v[78:79], v[78:79], v[116:117]
	s_waitcnt vmcnt(25)
	v_pk_add_f32 v[80:81], v[80:81], v[122:123]
	v_pk_add_f32 v[78:79], v[78:79], v[120:121]
	s_waitcnt vmcnt(24)
	v_pk_add_f32 v[80:81], v[80:81], v[126:127]
	v_pk_add_f32 v[78:79], v[78:79], v[124:125]
	s_waitcnt vmcnt(23)
	v_pk_add_f32 v[80:81], v[80:81], v[130:131]
	v_pk_add_f32 v[78:79], v[78:79], v[128:129]
	s_waitcnt vmcnt(22)
	v_pk_add_f32 v[80:81], v[80:81], v[134:135]
	v_pk_add_f32 v[78:79], v[78:79], v[132:133]
	s_waitcnt vmcnt(21)
	v_pk_add_f32 v[80:81], v[80:81], v[138:139]
	v_pk_add_f32 v[78:79], v[78:79], v[136:137]
	s_waitcnt vmcnt(20)
	v_pk_add_f32 v[82:83], v[80:81], v[142:143]
	v_pk_add_f32 v[84:85], v[78:79], v[140:141]
	s_waitcnt vmcnt(19)
	v_pk_fma_f32 v[14:15], v[82:83], v[146:147], v[14:15]
	v_pk_fma_f32 v[12:13], v[84:85], v[144:145], v[12:13]
	global_store_dwordx4 v[56:57], v[12:15], off
	s_waitcnt vmcnt(19)
	v_pk_add_f32 v[80:81], v[150:151], 0 op_sel_hi:[1,0]
	v_pk_add_f32 v[78:79], v[148:149], 0 op_sel_hi:[1,0]
	s_waitcnt vmcnt(18)
	v_pk_add_f32 v[80:81], v[80:81], v[154:155]
	v_pk_add_f32 v[78:79], v[78:79], v[152:153]
	s_waitcnt vmcnt(17)
	v_pk_add_f32 v[80:81], v[80:81], v[158:159]
	v_pk_add_f32 v[78:79], v[78:79], v[156:157]
	s_waitcnt vmcnt(16)
	v_pk_add_f32 v[80:81], v[80:81], v[162:163]
	v_pk_add_f32 v[78:79], v[78:79], v[160:161]
	s_waitcnt vmcnt(15)
	v_pk_add_f32 v[80:81], v[80:81], v[166:167]
	v_pk_add_f32 v[78:79], v[78:79], v[164:165]
	s_waitcnt vmcnt(14)
	v_pk_add_f32 v[80:81], v[80:81], v[170:171]
	v_pk_add_f32 v[78:79], v[78:79], v[168:169]
	s_waitcnt vmcnt(13)
	v_pk_add_f32 v[80:81], v[80:81], v[174:175]
	v_pk_add_f32 v[78:79], v[78:79], v[172:173]
	s_waitcnt vmcnt(12)
	v_pk_add_f32 v[82:83], v[80:81], v[178:179]
	v_pk_add_f32 v[84:85], v[78:79], v[176:177]
	s_waitcnt vmcnt(11)
	v_pk_fma_f32 v[10:11], v[82:83], v[182:183], v[10:11]
	v_pk_fma_f32 v[8:9], v[84:85], v[180:181], v[8:9]
	global_store_dwordx4 v[56:57], v[8:11], off offset:1024
	s_waitcnt vmcnt(11)
	v_pk_add_f32 v[80:81], v[186:187], 0 op_sel_hi:[1,0]
	v_pk_add_f32 v[78:79], v[184:185], 0 op_sel_hi:[1,0]
	s_waitcnt vmcnt(10)
	v_pk_add_f32 v[80:81], v[80:81], v[190:191]
	v_pk_add_f32 v[78:79], v[78:79], v[188:189]
	s_waitcnt vmcnt(9)
	v_pk_add_f32 v[80:81], v[80:81], v[194:195]
	v_pk_add_f32 v[78:79], v[78:79], v[192:193]
	s_waitcnt vmcnt(8)
	v_pk_add_f32 v[80:81], v[80:81], v[198:199]
	v_pk_add_f32 v[78:79], v[78:79], v[196:197]
	s_waitcnt vmcnt(7)
	v_pk_add_f32 v[80:81], v[80:81], v[202:203]
	v_pk_add_f32 v[78:79], v[78:79], v[200:201]
	s_waitcnt vmcnt(6)
	v_pk_add_f32 v[80:81], v[80:81], v[206:207]
	v_pk_add_f32 v[78:79], v[78:79], v[204:205]
	s_waitcnt vmcnt(5)
	v_pk_add_f32 v[80:81], v[80:81], v[210:211]
	v_pk_add_f32 v[78:79], v[78:79], v[208:209]
	s_waitcnt vmcnt(4)
	v_pk_add_f32 v[82:83], v[80:81], v[214:215]
	v_pk_add_f32 v[84:85], v[78:79], v[212:213]
	s_waitcnt vmcnt(3)
	v_pk_fma_f32 v[6:7], v[82:83], v[218:219], v[6:7]
	v_pk_fma_f32 v[4:5], v[84:85], v[216:217], v[4:5]
	global_store_dwordx4 v[56:57], v[4:7], off offset:2048
	global_load_dwordx4 v[62:65], v[64:65], off offset:3072
	s_nop 0
	global_load_dwordx4 v[82:85], v[66:67], off offset:3072
	global_load_dwordx4 v[66:69], v[68:69], off offset:3072
	s_nop 0
	global_load_dwordx4 v[112:115], v[70:71], off offset:3072
	global_load_dwordx4 v[70:73], v[72:73], off offset:3072
	s_nop 0
	global_load_dwordx4 v[116:119], v[74:75], off offset:3072
	global_load_dwordx4 v[120:123], v[60:61], off offset:3072
	global_load_dwordx4 v[124:127], v[46:47], off
	s_waitcnt vmcnt(11)
	v_pk_add_f32 v[60:61], v[222:223], 0 op_sel_hi:[1,0]
	v_pk_add_f32 v[74:75], v[220:221], 0 op_sel_hi:[1,0]
	s_waitcnt vmcnt(7)
	v_pk_add_f32 v[60:61], v[60:61], v[64:65]
	v_pk_add_f32 v[62:63], v[74:75], v[62:63]
	s_waitcnt vmcnt(6)
	v_pk_add_f32 v[60:61], v[60:61], v[84:85]
	v_pk_add_f32 v[62:63], v[62:63], v[82:83]
	s_waitcnt vmcnt(5)
	v_pk_add_f32 v[60:61], v[60:61], v[68:69]
	v_pk_add_f32 v[62:63], v[62:63], v[66:67]
	s_waitcnt vmcnt(4)
	v_pk_add_f32 v[60:61], v[60:61], v[114:115]
	v_pk_add_f32 v[62:63], v[62:63], v[112:113]
	s_waitcnt vmcnt(3)
	v_pk_add_f32 v[60:61], v[60:61], v[72:73]
	v_pk_add_f32 v[62:63], v[62:63], v[70:71]
	s_waitcnt vmcnt(2)
	v_pk_add_f32 v[60:61], v[60:61], v[118:119]
	v_pk_add_f32 v[62:63], v[62:63], v[116:117]
	s_waitcnt vmcnt(1)
	v_pk_add_f32 v[64:65], v[60:61], v[122:123]
	v_pk_add_f32 v[66:67], v[62:63], v[120:121]
	s_waitcnt vmcnt(0)
	v_pk_fma_f32 v[2:3], v[64:65], v[126:127], v[2:3]
	v_pk_fma_f32 v[0:1], v[66:67], v[124:125], v[0:1]
	global_store_dwordx4 v[56:57], v[0:3], off offset:3072
.LBB0_2750:
	s_waitcnt vmcnt(7)
	v_mul_f32_e32 v60, v29, v29
	s_waitcnt vmcnt(6) lgkmcnt(0)
	v_mul_f32_e32 v61, v25, v25
	v_fmac_f32_e32 v60, v28, v28
	v_fmac_f32_e32 v61, v24, v24
	v_fmac_f32_e32 v60, v30, v30
	v_fmac_f32_e32 v61, v26, v26
	v_fmac_f32_e32 v60, v31, v31
	v_fmac_f32_e32 v61, v27, v27
	v_add_f32_e32 v60, v60, v61
	s_waitcnt vmcnt(5)
	v_mul_f32_e32 v61, v21, v21
	v_fmac_f32_e32 v61, v20, v20
	v_fmac_f32_e32 v61, v22, v22
	v_fmac_f32_e32 v61, v23, v23
	v_add_f32_e32 v60, v61, v60
	s_waitcnt vmcnt(4)
	v_mul_f32_e32 v61, v17, v17
	v_fmac_f32_e32 v61, v16, v16
	v_fmac_f32_e32 v61, v18, v18
	v_fmac_f32_e32 v61, v19, v19
	v_add_f32_e32 v60, v61, v60
	s_waitcnt vmcnt(3)
	v_mul_f32_e32 v61, v13, v13
	v_fmac_f32_e32 v61, v12, v12
	v_fmac_f32_e32 v61, v14, v14
	v_fmac_f32_e32 v61, v15, v15
	v_add_f32_e32 v60, v61, v60
	s_waitcnt vmcnt(2)
	v_mul_f32_e32 v61, v9, v9
	v_fmac_f32_e32 v61, v8, v8
	v_fmac_f32_e32 v61, v10, v10
	v_fmac_f32_e32 v61, v11, v11
	v_add_f32_e32 v60, v61, v60
	s_waitcnt vmcnt(1)
	v_mul_f32_e32 v61, v5, v5
	v_fmac_f32_e32 v61, v4, v4
	v_fmac_f32_e32 v61, v6, v6
	v_fmac_f32_e32 v61, v7, v7
	v_add_f32_e32 v60, v61, v60
	s_waitcnt vmcnt(0)
	v_mul_f32_e32 v61, v1, v1
	v_fmac_f32_e32 v61, v0, v0
	v_fmac_f32_e32 v61, v2, v2
	v_fmac_f32_e32 v61, v3, v3
	v_add_f32_e32 v60, v61, v60
	v_mbcnt_lo_u32_b32 v61, -1, 0
	v_mbcnt_hi_u32_b32 v61, -1, v61
	s_andn2_b64 vcc, exec, s[10:11]
	v_lshlrev_b32_e32 v61, 2, v61
	v_xor_b32_e32 v62, 0x80, v61
	ds_bpermute_b32 v62, v62, v60
	s_waitcnt lgkmcnt(0)
	v_add_f32_e32 v60, v60, v62
	v_xor_b32_e32 v62, 64, v61
	ds_bpermute_b32 v62, v62, v60
	s_waitcnt lgkmcnt(0)
	v_add_f32_e32 v60, v60, v62
	v_xor_b32_e32 v62, 32, v61
	ds_bpermute_b32 v62, v62, v60
	s_waitcnt lgkmcnt(0)
	v_add_f32_e32 v60, v60, v62
	v_xor_b32_e32 v62, 16, v61
	ds_bpermute_b32 v62, v62, v60
	s_waitcnt lgkmcnt(0)
	v_add_f32_e32 v60, v60, v62
	v_xor_b32_e32 v62, 8, v61
	ds_bpermute_b32 v62, v62, v60
	v_xor_b32_e32 v61, 4, v61
	s_waitcnt lgkmcnt(0)
	v_add_f32_e32 v60, v60, v62
	ds_bpermute_b32 v61, v61, v60
	s_cbranch_vccnz .LBB0_2747
	s_ashr_i32 s16, s28, 31
	s_lshr_b32 s16, s16, 20
	s_add_i32 s16, s28, s16
	s_ashr_i32 s16, s16, 12
	s_cmpk_lt_i32 s28, 0x2000
	s_cselect_b32 s16, s16, 2
	s_mul_hi_i32 s29, s16, 0xc000
	s_mul_i32 s16, s16, 0xc000
	s_add_u32 s30, s6, s16
	s_addc_u32 s31, s7, s29
	v_lshl_add_u64 v[110:111], v[32:33], 2, s[30:31]
	v_add_co_u32_e32 v78, vcc, s27, v110
	s_waitcnt lgkmcnt(0)
	v_add_f32_e32 v60, v60, v61
	v_addc_co_u32_e32 v79, vcc, 0, v111, vcc
	global_load_dwordx4 v[112:115], v[78:79], off offset:-4096
	global_load_dwordx4 v[116:119], v[38:39], off
	v_add_co_u32_e32 v80, vcc, s26, v110
	s_nop 1
	v_addc_co_u32_e32 v81, vcc, 0, v111, vcc
	global_load_dwordx4 v[120:123], v[80:81], off offset:-4096
	v_lshl_add_u64 v[124:125], v[110:111], 0, s[18:19]
	global_load_dwordx4 v[128:131], v[124:125], off offset:1024
	global_load_dwordx4 v[132:135], v[38:39], off offset:1024
	v_lshl_add_u64 v[126:127], v[110:111], 0, s[20:21]
	global_load_dwordx4 v[136:139], v[126:127], off offset:1024
	global_load_dwordx4 v[140:143], v[124:125], off offset:2048
	global_load_dwordx4 v[144:147], v[38:39], off offset:2048
	global_load_dwordx4 v[148:151], v[126:127], off offset:2048
	global_load_dwordx4 v[152:155], v[124:125], off offset:3072
	global_load_dwordx4 v[156:159], v[38:39], off offset:3072
	global_load_dwordx4 v[160:163], v[126:127], off offset:3072
	global_load_dwordx4 v[164:167], v[78:79], off
	global_load_dwordx4 v[168:171], v[48:49], off
	global_load_dwordx4 v[172:175], v[80:81], off
	global_load_dwordx4 v[176:179], v[78:79], off offset:1024
	global_load_dwordx4 v[180:183], v[50:51], off
	global_load_dwordx4 v[184:187], v[80:81], off offset:1024
	global_load_dwordx4 v[188:191], v[78:79], off offset:2048
	global_load_dwordx4 v[192:195], v[52:53], off
	global_load_dwordx4 v[196:199], v[80:81], off offset:2048
	global_load_dwordx4 v[200:203], v[78:79], off offset:3072
	global_load_dwordx4 v[204:207], v[54:55], off
	global_load_dwordx4 v[208:211], v[80:81], off offset:3072
	v_fmamk_f32 v60, v60, 0x3a000000, v76
	s_mov_b32 s16, 0x800000
	v_mul_f32_e32 v61, 0x4b800000, v60
	v_cmp_gt_f32_e32 vcc, s16, v60
	s_nop 1
	v_cndmask_b32_e32 v60, v60, v61, vcc
	v_rsq_f32_e32 v60, v60
	s_nop 0
	v_mul_f32_e32 v61, 0x45800000, v60
	v_cndmask_b32_e32 v82, v60, v61, vcc
	v_pk_mul_f32 v[28:29], v[28:29], v[82:83] op_sel_hi:[1,0]
	v_pk_mul_f32 v[30:31], v[30:31], v[82:83] op_sel_hi:[1,0]
	v_pk_mul_f32 v[24:25], v[24:25], v[82:83] op_sel_hi:[1,0]
	v_pk_mul_f32 v[26:27], v[26:27], v[82:83] op_sel_hi:[1,0]
	v_pk_mul_f32 v[20:21], v[20:21], v[82:83] op_sel_hi:[1,0]
	v_pk_mul_f32 v[22:23], v[22:23], v[82:83] op_sel_hi:[1,0]
	v_pk_mul_f32 v[16:17], v[16:17], v[82:83] op_sel_hi:[1,0]
	v_pk_mul_f32 v[18:19], v[18:19], v[82:83] op_sel_hi:[1,0]
	v_pk_mul_f32 v[12:13], v[12:13], v[82:83] op_sel_hi:[1,0]
	v_pk_mul_f32 v[14:15], v[14:15], v[82:83] op_sel_hi:[1,0]
	v_pk_mul_f32 v[8:9], v[8:9], v[82:83] op_sel_hi:[1,0]
	v_pk_mul_f32 v[10:11], v[10:11], v[82:83] op_sel_hi:[1,0]
	v_pk_mul_f32 v[4:5], v[4:5], v[82:83] op_sel_hi:[1,0]
	v_pk_mul_f32 v[6:7], v[6:7], v[82:83] op_sel_hi:[1,0]
	v_pk_mul_f32 v[0:1], v[0:1], v[82:83] op_sel_hi:[1,0]
	v_pk_mul_f32 v[2:3], v[2:3], v[82:83] op_sel_hi:[1,0]
	s_waitcnt vmcnt(24)
	s_waitcnt vmcnt(23)
	v_pk_add_f32 v[60:61], v[112:113], 1.0 op_sel_hi:[1,0]
	s_waitcnt vmcnt(22)
	v_pk_mul_f32 v[28:29], v[28:29], v[116:117]
	v_pk_mul_f32 v[30:31], v[30:31], v[118:119]
	v_pk_add_f32 v[62:63], v[114:115], 1.0 op_sel_hi:[1,0]
	s_waitcnt vmcnt(21)
	v_pk_fma_f32 v[28:29], v[60:61], v[28:29], v[120:121]
	v_pk_fma_f32 v[30:31], v[62:63], v[30:31], v[122:123]
	v_cvt_pk_bf16_f32 v28, v28, v29
	v_cvt_pk_bf16_f32 v29, v30, v31
	global_store_dwordx2 v[58:59], v[28:29], off offset:-2048
	s_waitcnt vmcnt(21)
	s_nop 0
	v_pk_add_f32 v[28:29], v[128:129], 1.0 op_sel_hi:[1,0]
	s_waitcnt vmcnt(20)
	v_pk_mul_f32 v[24:25], v[24:25], v[132:133]
	v_pk_add_f32 v[30:31], v[130:131], 1.0 op_sel_hi:[1,0]
	v_pk_mul_f32 v[26:27], v[26:27], v[134:135]
	s_waitcnt vmcnt(19)
	v_pk_fma_f32 v[24:25], v[28:29], v[24:25], v[136:137]
	v_pk_fma_f32 v[26:27], v[30:31], v[26:27], v[138:139]
	v_cvt_pk_bf16_f32 v24, v24, v25
	v_cvt_pk_bf16_f32 v25, v26, v27
	global_store_dwordx2 v[58:59], v[24:25], off offset:-1536
	s_waitcnt vmcnt(19)
	s_nop 0
	v_pk_add_f32 v[24:25], v[140:141], 1.0 op_sel_hi:[1,0]
	s_waitcnt vmcnt(18)
	v_pk_mul_f32 v[20:21], v[20:21], v[144:145]
	v_pk_add_f32 v[26:27], v[142:143], 1.0 op_sel_hi:[1,0]
	v_pk_mul_f32 v[22:23], v[22:23], v[146:147]
	s_waitcnt vmcnt(17)
	v_pk_fma_f32 v[20:21], v[24:25], v[20:21], v[148:149]
	v_pk_fma_f32 v[22:23], v[26:27], v[22:23], v[150:151]
	v_cvt_pk_bf16_f32 v20, v20, v21
	v_cvt_pk_bf16_f32 v21, v22, v23
	global_store_dwordx2 v[58:59], v[20:21], off offset:-1024
	s_waitcnt vmcnt(17)
	s_nop 0
	v_pk_add_f32 v[20:21], v[152:153], 1.0 op_sel_hi:[1,0]
	s_waitcnt vmcnt(16)
	v_pk_mul_f32 v[16:17], v[16:17], v[156:157]
	v_pk_add_f32 v[22:23], v[154:155], 1.0 op_sel_hi:[1,0]
	v_pk_mul_f32 v[18:19], v[18:19], v[158:159]
	s_waitcnt vmcnt(15)
	v_pk_fma_f32 v[16:17], v[20:21], v[16:17], v[160:161]
	v_pk_fma_f32 v[18:19], v[22:23], v[18:19], v[162:163]
	v_cvt_pk_bf16_f32 v16, v16, v17
	v_cvt_pk_bf16_f32 v17, v18, v19
	global_store_dwordx2 v[58:59], v[16:17], off offset:-512
	s_waitcnt vmcnt(15)
	s_nop 0
	v_pk_add_f32 v[16:17], v[164:165], 1.0 op_sel_hi:[1,0]
	s_waitcnt vmcnt(14)
	v_pk_mul_f32 v[12:13], v[12:13], v[168:169]
	v_pk_add_f32 v[18:19], v[166:167], 1.0 op_sel_hi:[1,0]
	v_pk_mul_f32 v[14:15], v[14:15], v[170:171]
	s_waitcnt vmcnt(13)
	v_pk_fma_f32 v[12:13], v[16:17], v[12:13], v[172:173]
	v_pk_fma_f32 v[14:15], v[18:19], v[14:15], v[174:175]
	v_cvt_pk_bf16_f32 v12, v12, v13
	v_cvt_pk_bf16_f32 v13, v14, v15
	global_store_dwordx2 v[58:59], v[12:13], off
	s_waitcnt vmcnt(13)
	s_nop 0
	v_pk_add_f32 v[12:13], v[176:177], 1.0 op_sel_hi:[1,0]
	s_waitcnt vmcnt(12)
	v_pk_mul_f32 v[8:9], v[8:9], v[180:181]
	v_pk_add_f32 v[14:15], v[178:179], 1.0 op_sel_hi:[1,0]
	v_pk_mul_f32 v[10:11], v[10:11], v[182:183]
	s_waitcnt vmcnt(11)
	v_pk_fma_f32 v[8:9], v[12:13], v[8:9], v[184:185]
	v_pk_fma_f32 v[10:11], v[14:15], v[10:11], v[186:187]
	v_cvt_pk_bf16_f32 v8, v8, v9
	v_cvt_pk_bf16_f32 v9, v10, v11
	global_store_dwordx2 v[58:59], v[8:9], off offset:512
	s_waitcnt vmcnt(11)
	s_nop 0
	v_pk_add_f32 v[8:9], v[188:189], 1.0 op_sel_hi:[1,0]
	s_waitcnt vmcnt(10)
	v_pk_mul_f32 v[4:5], v[4:5], v[192:193]
	v_pk_add_f32 v[10:11], v[190:191], 1.0 op_sel_hi:[1,0]
	v_pk_mul_f32 v[6:7], v[6:7], v[194:195]
	s_waitcnt vmcnt(9)
	v_pk_fma_f32 v[4:5], v[8:9], v[4:5], v[196:197]
	v_pk_fma_f32 v[6:7], v[10:11], v[6:7], v[198:199]
	v_cvt_pk_bf16_f32 v4, v4, v5
	v_cvt_pk_bf16_f32 v5, v6, v7
	global_store_dwordx2 v[58:59], v[4:5], off offset:1024
	s_waitcnt vmcnt(9)
	s_nop 0
	v_pk_add_f32 v[4:5], v[200:201], 1.0 op_sel_hi:[1,0]
	s_waitcnt vmcnt(8)
	v_pk_mul_f32 v[0:1], v[0:1], v[204:205]
	v_pk_add_f32 v[6:7], v[202:203], 1.0 op_sel_hi:[1,0]
	v_pk_mul_f32 v[2:3], v[2:3], v[206:207]
	s_waitcnt vmcnt(7)
	v_pk_fma_f32 v[0:1], v[4:5], v[0:1], v[208:209]
	v_pk_fma_f32 v[2:3], v[6:7], v[2:3], v[210:211]
	v_cvt_pk_bf16_f32 v0, v0, v1
	v_cvt_pk_bf16_f32 v1, v2, v3
	global_store_dwordx2 v[58:59], v[0:1], off offset:1536
	s_branch .LBB0_2747

.LBB0_3098:
	s_or_b64 exec, exec, s[6:7]
	s_lshr_b32 s16, s39, 3
	s_ashr_i32 s10, s39, 7
	s_lshl_b32 s6, s27, 17
	s_add_u32 s6, s50, s6
	s_addc_u32 s7, s51, 0
	s_mul_i32 s27, s27, 0x88100
	s_add_u32 s11, s54, s27
	s_addc_u32 s12, s55, 0
	s_mul_i32 s40, s10, 0x44000
	s_mul_hi_i32 s27, s10, 0x44000
	s_add_u32 s22, s11, s40
	s_addc_u32 s23, s12, s27
	v_lshl_add_u64 v[0:1], s[22:23], 0, v[80:81]
	v_lshl_add_u64 v[0:1], v[0:1], 0, v[74:75]
	global_load_dwordx4 v[110:113], v[0:1], off
	v_lshl_add_u64 v[0:1], s[6:7], 0, v[76:77]
	v_lshl_add_u64 v[0:1], v[0:1], 0, v[106:107]
	global_load_dwordx4 v[56:59], v[0:1], off
	v_lshl_add_u64 v[2:3], s[6:7], 0, v[78:79]
	v_lshl_add_u64 v[2:3], v[2:3], 0, v[106:107]
	global_load_dwordx4 v[60:63], v[2:3], off
	global_load_dwordx4 v[48:51], v[0:1], off offset:64
	global_load_dwordx4 v[52:55], v[2:3], off offset:64
	global_load_dwordx4 v[40:43], v[0:1], off offset:128
	global_load_dwordx4 v[44:47], v[2:3], off offset:128
	global_load_dwordx4 v[32:35], v[0:1], off offset:192
	global_load_dwordx4 v[36:39], v[2:3], off offset:192
	global_load_dwordx4 v[24:27], v[0:1], off offset:256
	global_load_dwordx4 v[28:31], v[2:3], off offset:256
	global_load_dwordx4 v[20:23], v[0:1], off offset:320
	global_load_dwordx4 v[8:11], v[2:3], off offset:320
	global_load_dwordx4 v[16:19], v[0:1], off offset:384
	global_load_dwordx4 v[4:7], v[2:3], off offset:384
	global_load_dwordx4 v[12:15], v[0:1], off offset:448
	s_nop 0
	global_load_dwordx4 v[0:3], v[2:3], off offset:448
	s_waitcnt lgkmcnt(0)
	s_barrier
	v_add_u32_e32 v163, s24, v150
	s_waitcnt vmcnt(17)
	v_mul_f32_e32 v67, 0x41800000, v67
	v_lshlrev_b32_e32 v71, 30, v69
	v_and_b32_e32 v109, 1, v69
	v_xor_b32_e32 v122, v68, v64
	v_mul_f32_e32 v124, v66, v67
	v_mul_f32_e32 v70, v65, v65
	v_fmamk_f32 v123, v70, 0xb94c1982, v157
	v_fmamk_f32 v125, v70, 0x37d75334, v158
	v_fmaak_f32 v123, v70, v123, 0xbe2aaa9d
	v_fmaak_f32 v125, v70, v125, 0x3d2aabf7
	v_mul_f32_e32 v126, 0x3fb8aa3b, v124
	v_mul_f32_e32 v123, v70, v123
	v_fmaak_f32 v125, v70, v125, 0xbf000004
	v_fma_f32 v127, v124, s34, -v126
	v_rndne_f32_e32 v128, v126
	v_fmac_f32_e32 v65, v65, v123
	v_fma_f32 v70, v70, v125, 1.0
	v_cmp_eq_u32_e64 s[6:7], 0, v109
	v_fmac_f32_e32 v127, 0x32a5705f, v124
	v_sub_f32_e32 v126, v126, v128
	v_cndmask_b32_e64 v109, v70, v65, s[6:7]
	v_xor_b32_e32 v65, 0x80000000, v65
	v_and_b32_e32 v71, 0x80000000, v71
	v_add_f32_e32 v123, v126, v127
	v_cndmask_b32_e64 v65, v65, v70, s[6:7]
	v_cvt_i32_f32_e32 v128, v128
	v_exp_f32_e32 v125, v123
	v_xor_b32_e32 v65, v65, v71
	v_cmp_class_f32_e64 s[6:7], v64, s38
	v_xor_b32_e32 v109, v122, v109
	v_xor_b32_e32 v70, v109, v71
	v_cndmask_b32_e64 v122, v162, v65, s[6:7]
	v_cndmask_b32_e64 v123, v162, v70, s[6:7]
	v_cmp_ngt_f32_e64 s[6:7], s35, v124
	s_cmp_eq_u32 s4, 1
	v_readlane_b32 s94, v239, 1
	s_waitcnt vmcnt(16)
	ds_write_b128 v73, v[110:113]
	ds_write_b128 v73, v[110:113] offset:8448
	s_waitcnt lgkmcnt(0)
	s_barrier
	ds_read_b128 v[168:171], v163
	ds_read_b128 v[172:175], v163 offset:64
	ds_read_b128 v[176:179], v163 offset:128
	ds_read_b128 v[180:183], v163 offset:192
	ds_read_b128 v[184:187], v163 offset:256
	ds_read_b128 v[188:191], v163 offset:320
	s_waitcnt vmcnt(15) lgkmcnt(6)
	s_waitcnt lgkmcnt(5)
	v_mfma_f32_16x16x32_bf16 v[118:121], v[168:171], v[56:59], 0
	s_waitcnt vmcnt(14)
	v_mfma_f32_16x16x32_bf16 v[110:113], v[168:171], v[60:63], 0
	s_waitcnt vmcnt(13)
	s_waitcnt lgkmcnt(4)
	v_mfma_f32_16x16x32_bf16 v[118:121], v[172:175], v[48:51], v[118:121]
	s_waitcnt vmcnt(12)
	v_mfma_f32_16x16x32_bf16 v[110:113], v[172:175], v[52:55], v[110:113]
	s_waitcnt vmcnt(11)
	s_waitcnt lgkmcnt(3)
	v_mfma_f32_16x16x32_bf16 v[118:121], v[176:179], v[40:43], v[118:121]
	s_waitcnt vmcnt(10)
	v_mfma_f32_16x16x32_bf16 v[66:69], v[176:179], v[44:47], v[110:113]
	s_nop 2
	ds_read_b128 v[110:113], v163 offset:384
	ds_read_b128 v[168:171], v163 offset:448
	s_waitcnt vmcnt(9)
	s_waitcnt lgkmcnt(4)
	v_mfma_f32_16x16x32_bf16 v[118:121], v[180:183], v[32:35], v[118:121]
	s_waitcnt vmcnt(8)
	v_mfma_f32_16x16x32_bf16 v[66:69], v[180:183], v[36:39], v[66:69]
	s_waitcnt vmcnt(7)
	s_waitcnt lgkmcnt(3)
	v_mfma_f32_16x16x32_bf16 v[118:121], v[184:187], v[24:27], v[118:121]
	s_waitcnt vmcnt(6)
	v_mfma_f32_16x16x32_bf16 v[66:69], v[184:187], v[28:31], v[66:69]
	s_waitcnt vmcnt(5)
	s_waitcnt lgkmcnt(2)
	v_mfma_f32_16x16x32_bf16 v[118:121], v[188:191], v[20:23], v[118:121]
	s_waitcnt vmcnt(4)
	v_mfma_f32_16x16x32_bf16 v[66:69], v[188:191], v[8:11], v[66:69]
	s_waitcnt vmcnt(3) lgkmcnt(1)
	v_mfma_f32_16x16x32_bf16 v[118:121], v[110:113], v[16:19], v[118:121]
	s_waitcnt vmcnt(2)
	v_mfma_f32_16x16x32_bf16 v[64:67], v[110:113], v[4:7], v[66:69]
	s_nop 3
	v_ldexp_f32 v68, v125, v128
	v_cndmask_b32_e64 v109, 0, v68, s[6:7]
	s_waitcnt vmcnt(1)
	s_waitcnt lgkmcnt(0)
	v_mfma_f32_16x16x32_bf16 v[68:71], v[168:171], v[12:15], v[118:121]
	v_cmp_nlt_f32_e64 s[6:7], s36, v124
	s_waitcnt vmcnt(0)
	v_mfma_f32_16x16x32_bf16 v[64:67], v[168:171], v[0:3], v[64:67]
	v_cndmask_b32_e64 v110, v159, v109, s[6:7]
	s_cselect_b64 s[6:7], -1, 0
	s_cmp_eq_u32 s4, 2
	s_nop 1
	v_cndmask_b32_e64 v109, v68, v69, s[6:7]
	s_cselect_b64 s[10:11], -1, 0
	s_cmp_eq_u32 s4, 3
	v_cndmask_b32_e64 v112, v64, v65, s[6:7]
	v_cndmask_b32_e64 v109, v109, v70, s[10:11]
	s_cselect_b64 s[6:7], -1, 0
	v_cndmask_b32_e64 v112, v112, v66, s[10:11]
	s_cmp_eq_u32 s5, 1
	v_cndmask_b32_e64 v120, v109, v71, s[6:7]
	v_cndmask_b32_e64 v121, v112, v67, s[6:7]
	s_cselect_b64 s[6:7], -1, 0
	s_cmp_eq_u32 s5, 2
	v_cndmask_b32_e64 v109, v68, v69, s[6:7]
	s_cselect_b64 s[10:11], -1, 0
	s_cmp_eq_u32 s5, 3
	v_cndmask_b32_e64 v109, v109, v70, s[10:11]
	v_cndmask_b32_e64 v112, v64, v65, s[6:7]
	s_cselect_b64 s[6:7], -1, 0
	v_cndmask_b32_e64 v136, v109, v71, s[6:7]
	v_cndmask_b32_e64 v109, v112, v66, s[10:11]
	s_cmp_eq_u32 s28, 1
	v_cndmask_b32_e64 v137, v109, v67, s[6:7]
	s_cselect_b64 s[6:7], -1, 0
	s_cmp_eq_u32 s28, 2
	v_cndmask_b32_e64 v109, v68, v69, s[6:7]
	s_cselect_b64 s[10:11], -1, 0
	s_cmp_eq_u32 s28, 3
	v_cndmask_b32_e64 v109, v109, v70, s[10:11]
	s_cselect_b64 s[12:13], -1, 0
	s_cmp_eq_u32 s29, 1
	v_cndmask_b32_e64 v131, v109, v71, s[12:13]
	v_cndmask_b32_e64 v109, v64, v65, s[6:7]
	s_cselect_b64 s[6:7], -1, 0
	s_cmp_eq_u32 s29, 2
	v_cndmask_b32_e64 v109, v109, v66, s[10:11]
	v_cndmask_b32_e64 v68, v68, v69, s[6:7]
	s_cselect_b64 s[10:11], -1, 0
	s_cmp_eq_u32 s29, 3
	v_cndmask_b32_e64 v64, v64, v65, s[6:7]
	v_cndmask_b32_e64 v130, v109, v67, s[12:13]
	v_cndmask_b32_e64 v68, v68, v70, s[10:11]
	s_cselect_b64 s[12:13], -1, 0
	v_cndmask_b32_e64 v64, v64, v66, s[10:11]
	v_pk_mul_f32 v[110:111], v[110:111], v[122:123] op_sel_hi:[0,1]
	v_cndmask_b32_e64 v70, v68, v71, s[12:13]
	v_cndmask_b32_e64 v71, v64, v67, s[12:13]
	v_mov_b32_e32 v66, v121
	v_mov_b32_e32 v67, v120
	v_pk_mul_f32 v[64:65], v[110:111], v[120:121]
	v_pk_mul_f32 v[66:67], v[110:111], v[66:67]
	v_sub_f32_e32 v64, v64, v65
	v_add_f32_e32 v65, v67, v66
	v_add_f32_e32 v66, v137, v65
	v_add_f32_e32 v64, v136, v64
	v_pk_mul_f32 v[66:67], v[110:111], v[66:67] op_sel_hi:[1,0]
	v_xor_b32_e32 v112, 0x80000000, v111
	v_pk_fma_f32 v[68:69], v[110:111], v[64:65], v[66:67] op_sel:[1,0,0] op_sel_hi:[0,1,1]
	v_pk_fma_f32 v[64:65], v[110:111], v[64:65], v[66:67] op_sel:[1,0,0] op_sel_hi:[0,0,1] neg_lo:[0,0,1] neg_hi:[0,0,1]
	v_mov_b32_e32 v69, v65
	v_pk_add_f32 v[64:65], v[130:131], v[68:69]
	v_mov_b32_e32 v113, v110
	v_pk_mul_f32 v[66:67], v[110:111], v[64:65] op_sel:[0,1] op_sel_hi:[1,0]
	v_pk_mul_f32 v[64:65], v[110:111], v[64:65]
	v_sub_f32_e32 v66, v66, v67
	v_add_f32_e32 v64, v64, v65
	v_add_f32_e32 v64, v71, v64
	ds_bpermute_b32 v123, v153, v64
	ds_bpermute_b32 v119, v154, v64
	ds_bpermute_b32 v117, v155, v64
	ds_bpermute_b32 v125, v156, v64
	v_add_f32_e32 v66, v70, v66
	ds_bpermute_b32 v122, v153, v66
	ds_bpermute_b32 v118, v154, v66
	ds_bpermute_b32 v116, v155, v66
	ds_bpermute_b32 v124, v156, v66
	v_lshl_add_u64 v[64:65], s[22:23], 0, v[74:75]
	s_nop 1
	v_lshl_add_u64 v[66:67], v[64:65], 0, v[82:83]
	v_lshl_add_u64 v[68:69], v[64:65], 0, v[84:85]
	global_load_dwordx4 v[64:67], v[66:67], off
	s_nop 0
	global_load_dwordx4 v[68:71], v[68:69], off
	v_pk_mul_f32 v[112:113], v[110:111], v[112:113] op_sel:[1,0]
	v_pk_mov_b32 v[114:115], v[110:111], v[110:111] op_sel:[1,0]
	v_pk_fma_f32 v[112:113], v[110:111], v[110:111], v[112:113] op_sel_hi:[0,1,1]
	v_xor_b32_e32 v126, 0x80000000, v113
	v_mov_b32_e32 v127, v112
	v_pk_mul_f32 v[126:127], v[112:113], v[126:127] op_sel:[1,0]
	v_cmp_lt_i32_e64 s[6:7], 0, v151
	v_pk_fma_f32 v[112:113], v[112:113], v[112:113], v[126:127] op_sel_hi:[1,0,1]
	s_mov_b64 s[10:11], 0
	v_mul_f32_e32 v109, 0, v112
	v_mul_f32_e32 v127, 0, v113
	v_sub_f32_e32 v126, v109, v127
	v_fmac_f32_e32 v127, 0, v112
	s_waitcnt lgkmcnt(3)
	v_pk_add_f32 v[122:123], v[126:127], v[122:123]
	s_and_saveexec_b64 s[12:13], s[6:7]
	s_xor_b64 s[12:13], exec, s[12:13]
	s_cbranch_execz .LBB0_3102
	v_cmp_eq_u32_e64 s[6:7], 1, v151
	s_mov_b64 s[10:11], -1
	s_and_saveexec_b64 s[14:15], s[6:7]
	s_xor_b64 s[10:11], exec, -1
	v_mov_b32_e32 v133, v123
	v_mov_b32_e32 v132, v122
	s_or_b64 exec, exec, s[14:15]
	s_and_b64 s[10:11], s[10:11], exec

.LBB0_3108:
	s_add_i32 s10, s40, -2
	s_and_b32 s10, s10, 2
	s_add_i32 s10, s10, s0
	s_mulk_i32 s10, 0x2100
	v_add_u32_e32 v109, s10, v150
	ds_read_b128 v[168:171], v109
	ds_read_b128 v[172:175], v109 offset:64
	ds_read_b128 v[176:179], v109 offset:128
	ds_read_b128 v[180:183], v109 offset:192
	ds_read_b128 v[184:187], v109 offset:256
	ds_read_b128 v[188:191], v109 offset:320
	ds_read_b128 v[192:195], v109 offset:384
	ds_read_b128 v[196:199], v109 offset:448
	s_cmp_eq_u32 s4, 1
	s_cselect_b64 s[10:11], -1, 0
	s_cmp_eq_u32 s4, 2
	s_cselect_b64 s[12:13], -1, 0
	s_cmp_eq_u32 s4, 3
	s_cselect_b64 s[14:15], -1, 0
	s_cmp_eq_u32 s5, 1
	s_waitcnt lgkmcnt(8)
	s_waitcnt lgkmcnt(7)
	v_mfma_f32_16x16x32_bf16 v[68:71], v[168:171], v[56:59], 0
	v_mfma_f32_16x16x32_bf16 v[64:67], v[168:171], v[60:63], 0
	s_waitcnt lgkmcnt(6)
	v_mfma_f32_16x16x32_bf16 v[68:71], v[172:175], v[48:51], v[68:71]
	v_mfma_f32_16x16x32_bf16 v[64:67], v[172:175], v[52:55], v[64:67]
	s_waitcnt lgkmcnt(5)
	v_mfma_f32_16x16x32_bf16 v[68:71], v[176:179], v[40:43], v[68:71]
	v_mfma_f32_16x16x32_bf16 v[64:67], v[176:179], v[44:47], v[64:67]
	s_waitcnt lgkmcnt(4)
	v_mfma_f32_16x16x32_bf16 v[68:71], v[180:183], v[32:35], v[68:71]
	v_mfma_f32_16x16x32_bf16 v[64:67], v[180:183], v[36:39], v[64:67]
	s_waitcnt lgkmcnt(3)
	v_mfma_f32_16x16x32_bf16 v[68:71], v[184:187], v[24:27], v[68:71]
	v_mfma_f32_16x16x32_bf16 v[64:67], v[184:187], v[28:31], v[64:67]
	s_waitcnt lgkmcnt(2)
	v_mfma_f32_16x16x32_bf16 v[68:71], v[188:191], v[20:23], v[68:71]
	v_mfma_f32_16x16x32_bf16 v[64:67], v[188:191], v[8:11], v[64:67]
	s_waitcnt lgkmcnt(1)
	v_mfma_f32_16x16x32_bf16 v[68:71], v[192:195], v[16:19], v[68:71]
	v_mfma_f32_16x16x32_bf16 v[64:67], v[192:195], v[4:7], v[64:67]
	s_waitcnt lgkmcnt(0)
	v_mfma_f32_16x16x32_bf16 v[68:71], v[196:199], v[12:15], v[68:71]
	s_nop 7
	v_cndmask_b32_e64 v109, v68, v69, s[10:11]
	v_mfma_f32_16x16x32_bf16 v[64:67], v[196:199], v[0:3], v[64:67]
	v_cndmask_b32_e64 v109, v109, v70, s[12:13]
	v_cndmask_b32_e64 v138, v109, v71, s[14:15]
	s_nop 5
	v_cndmask_b32_e64 v109, v64, v65, s[10:11]
	v_cndmask_b32_e64 v109, v109, v66, s[12:13]
	s_cselect_b64 s[10:11], -1, 0
	s_cmp_eq_u32 s5, 2
	v_cndmask_b32_e64 v139, v109, v67, s[14:15]
	v_cndmask_b32_e64 v109, v68, v69, s[10:11]
	s_cselect_b64 s[12:13], -1, 0
	s_cmp_eq_u32 s5, 3
	v_cndmask_b32_e64 v109, v109, v70, s[12:13]
	s_cselect_b64 s[14:15], -1, 0
	s_cmp_eq_u32 s28, 1
	v_cndmask_b32_e64 v121, v109, v71, s[14:15]
	v_cndmask_b32_e64 v109, v64, v65, s[10:11]
	s_cselect_b64 s[10:11], -1, 0
	s_cmp_eq_u32 s28, 2
	v_cndmask_b32_e64 v109, v109, v66, s[12:13]
	v_cndmask_b32_e64 v136, v68, v69, s[10:11]
	s_cselect_b64 s[12:13], -1, 0
	s_cmp_eq_u32 s28, 3
	v_cndmask_b32_e64 v109, v109, v67, s[14:15]
	v_cndmask_b32_e64 v136, v136, v70, s[12:13]
	s_cselect_b64 s[14:15], -1, 0
	s_cmp_eq_u32 s29, 1
	v_cndmask_b32_e64 v137, v136, v71, s[14:15]
	v_cndmask_b32_e64 v136, v64, v65, s[10:11]
	s_cselect_b64 s[10:11], -1, 0
	s_cmp_eq_u32 s29, 2
	v_cndmask_b32_e64 v136, v136, v66, s[12:13]
	v_cndmask_b32_e64 v68, v68, v69, s[10:11]
	s_cselect_b64 s[12:13], -1, 0
	s_cmp_eq_u32 s29, 3
	v_cndmask_b32_e64 v64, v64, v65, s[10:11]
	v_cndmask_b32_e64 v136, v136, v67, s[14:15]
	v_cndmask_b32_e64 v68, v68, v70, s[12:13]
	s_cselect_b64 s[14:15], -1, 0
	v_cndmask_b32_e64 v64, v64, v66, s[12:13]
	v_cndmask_b32_e64 v70, v68, v71, s[14:15]
	v_cndmask_b32_e64 v71, v64, v67, s[14:15]
	v_mov_b32_e32 v66, v139
	v_mov_b32_e32 v67, v138
	v_pk_mul_f32 v[64:65], v[110:111], v[138:139]
	v_pk_mul_f32 v[66:67], v[110:111], v[66:67]
	v_sub_f32_e32 v64, v64, v65
	v_add_f32_e32 v65, v67, v66
	v_add_f32_e32 v66, v109, v65
	v_add_f32_e32 v64, v121, v64
	v_pk_mul_f32 v[66:67], v[110:111], v[66:67] op_sel_hi:[1,0]
	v_cmp_lt_i32_e64 s[10:11], 0, v151
	v_pk_fma_f32 v[68:69], v[114:115], v[64:65], v[66:67]
	v_pk_fma_f32 v[64:65], v[114:115], v[64:65], v[66:67] op_sel_hi:[1,0,1] neg_lo:[0,0,1] neg_hi:[0,0,1]
	s_mov_b64 s[12:13], 0
	v_mov_b32_e32 v69, v65
	v_pk_add_f32 v[64:65], v[136:137], v[68:69]
	s_nop 0
	v_pk_mul_f32 v[66:67], v[110:111], v[64:65] op_sel:[0,1] op_sel_hi:[1,0]
	v_pk_mul_f32 v[64:65], v[110:111], v[64:65]
	v_sub_f32_e32 v66, v66, v67
	v_add_f32_e32 v64, v64, v65
	v_add_f32_e32 v66, v70, v66
	ds_bpermute_b32 v146, v153, v66
	v_add_f32_e32 v64, v71, v64
	ds_bpermute_b32 v147, v153, v64
	ds_bpermute_b32 v144, v154, v66
	ds_bpermute_b32 v145, v154, v64
	ds_bpermute_b32 v142, v155, v66
	ds_bpermute_b32 v143, v155, v64
	ds_bpermute_b32 v140, v156, v66
	ds_bpermute_b32 v141, v156, v64
	global_load_dwordx4 v[64:67], v[134:135], off
	global_load_dwordx4 v[68:71], v[132:133], off
	s_and_saveexec_b64 s[14:15], s[10:11]
	s_xor_b64 s[14:15], exec, s[14:15]
	s_cbranch_execz .LBB0_3112
	v_cmp_eq_u32_e64 s[10:11], 1, v151
	s_mov_b64 s[12:13], -1
	s_and_saveexec_b64 s[26:27], s[10:11]
	s_xor_b64 s[12:13], exec, -1
	s_or_b64 exec, exec, s[26:27]
	s_and_b64 s[12:13], s[12:13], exec

.LBB0_3116:
	ds_read_b128 v[64:67], v163
	ds_read_b128 v[68:71], v163 offset:64
	s_cmp_eq_u32 s4, 1
	s_cselect_b64 s[10:11], -1, 0
	s_cmp_eq_u32 s4, 2
	s_waitcnt lgkmcnt(1)
	v_mfma_f32_16x16x32_bf16 v[56:59], v[64:67], v[56:59], 0
	s_cselect_b64 s[12:13], -1, 0
	s_cmp_eq_u32 s4, 3
	s_cselect_b64 s[14:15], -1, 0
	v_mfma_f32_16x16x32_bf16 v[60:63], v[64:67], v[60:63], 0
	s_cmp_eq_u32 s5, 1
	s_waitcnt lgkmcnt(0)
	v_mfma_f32_16x16x32_bf16 v[48:51], v[68:71], v[48:51], v[56:59]
	s_nop 0
	ds_read_b128 v[56:59], v163 offset:128
	v_mfma_f32_16x16x32_bf16 v[52:55], v[68:71], v[52:55], v[60:63]
	s_nop 1
	ds_read_b128 v[60:63], v163 offset:192
	s_waitcnt lgkmcnt(1)
	v_mfma_f32_16x16x32_bf16 v[40:43], v[56:59], v[40:43], v[48:51]
	v_mfma_f32_16x16x32_bf16 v[44:47], v[56:59], v[44:47], v[52:55]
	s_waitcnt lgkmcnt(0)
	v_mfma_f32_16x16x32_bf16 v[32:35], v[60:63], v[32:35], v[40:43]
	s_nop 4
	ds_read_b128 v[40:43], v163 offset:256
	v_mfma_f32_16x16x32_bf16 v[36:39], v[60:63], v[36:39], v[44:47]
	ds_read_b128 v[44:47], v163 offset:320
	s_waitcnt lgkmcnt(1)
	v_mfma_f32_16x16x32_bf16 v[24:27], v[40:43], v[24:27], v[32:35]
	ds_read_b128 v[32:35], v163 offset:384
	v_mfma_f32_16x16x32_bf16 v[28:31], v[40:43], v[28:31], v[36:39]
	s_waitcnt lgkmcnt(1)
	v_mfma_f32_16x16x32_bf16 v[20:23], v[44:47], v[20:23], v[24:27]
	s_nop 3
	ds_read_b128 v[24:27], v163 offset:448
	v_mfma_f32_16x16x32_bf16 v[8:11], v[44:47], v[8:11], v[28:31]
	s_waitcnt lgkmcnt(1)
	v_mfma_f32_16x16x32_bf16 v[6:9], v[32:35], v[4:7], v[8:11]
	v_mfma_f32_16x16x32_bf16 v[16:19], v[32:35], v[16:19], v[20:23]
	s_waitcnt lgkmcnt(0)
	v_mfma_f32_16x16x32_bf16 v[8:11], v[24:27], v[0:3], v[6:9]
	v_mfma_f32_16x16x32_bf16 v[12:15], v[24:27], v[12:15], v[16:19]
	s_nop 6
	v_cndmask_b32_e64 v0, v8, v9, s[10:11]
	v_cndmask_b32_e64 v16, v12, v13, s[10:11]
	v_cndmask_b32_e64 v0, v0, v10, s[12:13]
	s_cselect_b64 s[10:11], -1, 0
	s_cmp_eq_u32 s5, 2
	v_cndmask_b32_e64 v16, v16, v14, s[12:13]
	v_cndmask_b32_e64 v6, v0, v11, s[14:15]
	v_cndmask_b32_e64 v0, v12, v13, s[10:11]
	s_cselect_b64 s[12:13], -1, 0
	s_cmp_eq_u32 s5, 3
	v_cndmask_b32_e64 v4, v16, v15, s[14:15]
	v_cndmask_b32_e64 v0, v0, v14, s[12:13]
	s_cselect_b64 s[14:15], -1, 0
	v_cndmask_b32_e64 v3, v0, v15, s[14:15]
	v_cndmask_b32_e64 v0, v8, v9, s[10:11]
	s_cmp_eq_u32 s28, 1
	v_cndmask_b32_e64 v0, v0, v10, s[12:13]
	s_cselect_b64 s[10:11], -1, 0
	s_cmp_eq_u32 s28, 2
	v_cndmask_b32_e64 v2, v0, v11, s[14:15]
	v_cndmask_b32_e64 v0, v12, v13, s[10:11]
	s_cselect_b64 s[12:13], -1, 0
	s_cmp_eq_u32 s28, 3
	v_cndmask_b32_e64 v0, v0, v14, s[12:13]
	s_cselect_b64 s[14:15], -1, 0
	s_cmp_eq_u32 s29, 1
	v_cndmask_b32_e64 v1, v0, v15, s[14:15]
	v_cndmask_b32_e64 v0, v8, v9, s[10:11]
	s_cselect_b64 s[10:11], -1, 0
	s_cmp_eq_u32 s29, 2
	v_cndmask_b32_e64 v0, v0, v10, s[12:13]
	s_cselect_b64 s[12:13], -1, 0
	s_cmp_eq_u32 s29, 3
	v_cndmask_b32_e64 v7, v8, v9, s[10:11]
	v_cndmask_b32_e64 v0, v0, v11, s[14:15]
	v_cndmask_b32_e64 v5, v12, v13, s[10:11]
	s_cselect_b64 s[14:15], -1, 0
	v_cndmask_b32_e64 v7, v7, v10, s[12:13]
	v_cndmask_b32_e64 v5, v5, v14, s[12:13]
	v_cndmask_b32_e64 v7, v7, v11, s[14:15]
	v_cndmask_b32_e64 v5, v5, v15, s[14:15]
	v_pk_mul_f32 v[8:9], v[110:111], v[6:7] op_sel_hi:[1,0]
	v_cmp_lt_i32_e64 s[10:11], 0, v151
	v_pk_fma_f32 v[10:11], v[114:115], v[4:5], v[8:9]
	v_pk_fma_f32 v[8:9], v[114:115], v[4:5], v[8:9] op_sel_hi:[1,0,1] neg_lo:[0,0,1] neg_hi:[0,0,1]
	s_mov_b64 s[12:13], 0
	v_mov_b32_e32 v11, v9
	v_pk_add_f32 v[8:9], v[2:3], v[10:11]
	s_nop 0
	v_pk_mul_f32 v[10:11], v[128:129], v[8:9] op_sel:[0,1] op_sel_hi:[1,0]
	s_nop 0
	v_pk_fma_f32 v[12:13], v[126:127], v[8:9], v[10:11]
	v_pk_fma_f32 v[8:9], v[126:127], v[8:9], v[10:11] neg_lo:[0,0,1] neg_hi:[0,0,1]
	s_nop 0
	v_mov_b32_e32 v13, v9
	v_pk_add_f32 v[8:9], v[0:1], v[12:13]
	s_nop 0
	v_pk_mul_f32 v[10:11], v[110:111], v[8:9] op_sel:[0,1] op_sel_hi:[1,0]
	v_pk_mul_f32 v[8:9], v[110:111], v[8:9]
	v_sub_f32_e32 v10, v10, v11
	v_add_f32_e32 v8, v8, v9
	v_add_f32_e32 v5, v5, v10
	ds_bpermute_b32 v12, v153, v5
	v_add_f32_e32 v7, v7, v8
	ds_bpermute_b32 v13, v153, v7
	ds_bpermute_b32 v10, v154, v5
	ds_bpermute_b32 v11, v154, v7
	ds_bpermute_b32 v8, v155, v5
	ds_bpermute_b32 v9, v155, v7
	s_and_saveexec_b64 s[14:15], s[10:11]
	s_xor_b64 s[14:15], exec, s[14:15]
	s_cbranch_execz .LBB0_3120
	v_cmp_eq_u32_e64 s[10:11], 1, v151
	s_mov_b64 s[12:13], -1
	s_and_saveexec_b64 s[26:27], s[10:11]
	s_xor_b64 s[12:13], exec, -1
	s_or_b64 exec, exec, s[26:27]
	s_and_b64 s[12:13], s[12:13], exec

.LBB0_3124:
	s_waitcnt vmcnt(0)
	s_barrier
	v_mbcnt_lo_u32_b32 v0, -1, 0
	v_mbcnt_hi_u32_b32 v0, -1, v0
	s_nop 0
	v_sub_u32_e32 v0, 0, v0
	v_cmp_eq_u32_e32 vcc, s78, v0
	s_and_saveexec_b64 s[6:7], vcc
	s_branch .LBB0_3176
	s_add_i32 s0, 0, 0x22100
	v_mov_b32_e32 v0, s0
	s_waitcnt vmcnt(0) expcnt(0) lgkmcnt(0)
	ds_read_b32 v2, v0
	s_add_i32 s0, 0, 0x22104
	v_mov_b32_e32 v0, s0
	ds_read_b32 v0, v0
	s_waitcnt lgkmcnt(1)
	v_cmp_ne_u32_e32 vcc, 0, v2
	s_cbranch_vccnz .LBB0_3140
	v_readlane_b32 s8, v240, 47
	v_readlane_b32 s9, v240, 48
	s_load_dword s0, s[8:9], 0x14
	s_load_dwordx2 s[4:5], s[8:9], 0x4
	v_mov_b32_e32 v16, 0
	s_waitcnt lgkmcnt(0)
	s_lshr_b32 s2, s0, 16
	s_and_b32 s0, s0, 0xffff
	s_cmp_lg_u32 s0, 0
	s_cselect_b64 s[8:9], -1, 0
	s_cmp_lg_u64 s[8:9], 0
	s_addc_u32 s0, s4, 0
	s_cmp_lg_u32 s2, 0
	s_cselect_b64 s[8:9], -1, 0
	s_cmp_lg_u64 s[8:9], 0
	s_addc_u32 s2, s5, 0
	s_add_u32 s8, s96, 0x1000
	s_addc_u32 s9, s97, 0
	s_add_u32 s10, s96, 0x1100
	s_addc_u32 s11, s97, 0
	s_add_u32 s12, s96, 0x1200
	s_addc_u32 s13, s97, 0
	s_mul_i32 s0, s0, s33
	s_add_u32 s14, s96, 0x1300
	s_mul_i32 s0, s0, s2
	s_addc_u32 s15, s97, 0
	s_mov_b32 s2, 1
	s_branch .LBB0_3128

.LBB0_3178:
	ds_read_b128 v[128:131], v170
	ds_read_b128 v[132:135], v170 offset:64
	s_addk_i32 s35, 0x2000
	s_add_i32 s31, s31, s33
	s_add_i32 s4, s4, s5
	s_waitcnt lgkmcnt(1)
	v_mfma_f32_16x16x32_bf16 v[96:99], v[128:131], v[96:99], 0
	s_cmpk_gt_i32 s31, 0xff
	v_mfma_f32_16x16x32_bf16 v[120:123], v[128:131], v[120:123], 0
	s_waitcnt lgkmcnt(0)
	v_mfma_f32_16x16x32_bf16 v[92:95], v[132:135], v[92:95], v[96:99]
	v_mfma_f32_16x16x32_bf16 v[96:99], v[132:135], v[116:119], v[120:123]
	ds_read_b128 v[116:119], v170 offset:128
	s_nop 3
	ds_read_b128 v[120:123], v170 offset:192
	s_waitcnt lgkmcnt(1)
	v_mfma_f32_16x16x32_bf16 v[80:83], v[116:119], v[80:83], v[92:95]
	v_mfma_f32_16x16x32_bf16 v[92:95], v[116:119], v[112:115], v[96:99]
	s_waitcnt lgkmcnt(0)
	v_mfma_f32_16x16x32_bf16 v[76:79], v[120:123], v[76:79], v[80:83]
	v_mfma_f32_16x16x32_bf16 v[80:83], v[120:123], v[108:111], v[92:95]
	s_nop 4
	ds_read_b128 v[92:95], v170 offset:256
	ds_read_b128 v[96:99], v170 offset:320
	s_waitcnt lgkmcnt(1)
	v_mfma_f32_16x16x32_bf16 v[72:75], v[92:95], v[72:75], v[76:79]
	v_mfma_f32_16x16x32_bf16 v[76:79], v[92:95], v[104:107], v[80:83]
	s_waitcnt lgkmcnt(0)
	v_mfma_f32_16x16x32_bf16 v[64:67], v[96:99], v[64:67], v[72:75]
	v_mfma_f32_16x16x32_bf16 v[72:75], v[96:99], v[100:103], v[76:79]
	s_nop 4
	ds_read_b128 v[76:79], v170 offset:384
	ds_read_b128 v[80:83], v170 offset:448
	s_waitcnt lgkmcnt(1)
	v_mfma_f32_16x16x32_bf16 v[56:59], v[76:79], v[56:59], v[64:67]
	v_mfma_f32_16x16x32_bf16 v[64:67], v[76:79], v[88:91], v[72:75]
	s_waitcnt lgkmcnt(0)
	v_mfma_f32_16x16x32_bf16 v[48:51], v[80:83], v[48:51], v[56:59]
	v_mfma_f32_16x16x32_bf16 v[56:59], v[80:83], v[84:87], v[64:67]
	s_nop 4
	ds_read_b128 v[64:67], v170 offset:512
	ds_read_b128 v[72:75], v170 offset:576
	s_waitcnt lgkmcnt(1)
	v_mfma_f32_16x16x32_bf16 v[40:43], v[64:67], v[40:43], v[48:51]
	v_mfma_f32_16x16x32_bf16 v[48:51], v[64:67], v[124:127], v[56:59]
	ds_read_b128 v[56:59], v170 offset:640
	s_waitcnt lgkmcnt(1)
	v_mfma_f32_16x16x32_bf16 v[28:31], v[72:75], v[28:31], v[40:43]
	s_nop 3
	ds_read_b128 v[40:43], v170 offset:704
	s_waitcnt lgkmcnt(1)
	v_mfma_f32_16x16x32_bf16 v[20:23], v[56:59], v[20:23], v[28:31]
	s_nop 0
	ds_read_b128 v[28:31], v170 offset:768
	s_waitcnt lgkmcnt(1)
	v_mfma_f32_16x16x32_bf16 v[16:19], v[40:43], v[16:19], v[20:23]
	s_nop 3
	ds_read_b128 v[20:23], v170 offset:832
	s_waitcnt lgkmcnt(1)
	v_mfma_f32_16x16x32_bf16 v[12:15], v[28:31], v[12:15], v[16:19]
	s_nop 0
	ds_read_b128 v[16:19], v170 offset:896
	s_waitcnt lgkmcnt(1)
	v_mfma_f32_16x16x32_bf16 v[8:11], v[20:23], v[8:11], v[12:15]
	s_nop 3
	ds_read_b128 v[12:15], v170 offset:960
	s_waitcnt lgkmcnt(1)
	v_mfma_f32_16x16x32_bf16 v[0:3], v[16:19], v[0:3], v[8:11]
	s_nop 2
	v_add_u32_e32 v9, s35, v172
	s_waitcnt lgkmcnt(0)
	v_mfma_f32_16x16x32_bf16 v[0:3], v[12:15], v[4:7], v[0:3]
	v_mfma_f32_16x16x32_bf16 v[4:7], v[72:75], v[68:71], v[48:51]
	s_nop 6
	v_mul_f32_e32 v8, 0x3d372713, v0
	v_mul_f32_e32 v8, v0, v8
	v_fma_f32 v8, v0, v8, v0
	v_mfma_f32_16x16x32_bf16 v[4:7], v[56:59], v[60:63], v[4:7]
	v_mul_f32_e32 v8, 0x3f4c422a, v8
	v_add_f32_e32 v8, v8, v8
	v_mul_f32_e32 v8, 0x3fb8aa3b, v8
	v_mfma_f32_16x16x32_bf16 v[4:7], v[40:43], v[52:55], v[4:7]
	v_exp_f32_e32 v8, v8
	v_mul_f32_e32 v0, 0.5, v0
	v_add_f32_e32 v8, 1.0, v8
	v_mfma_f32_16x16x32_bf16 v[4:7], v[28:31], v[44:47], v[4:7]
	v_rcp_f32_e32 v10, v8
	v_add_u32_e32 v8, s34, v173
	v_cndmask_b32_e64 v8, v8, v9, s[20:21]
	v_mfma_f32_16x16x32_bf16 v[4:7], v[20:23], v[36:39], v[4:7]
	v_fma_f32 v9, v10, -2.0, 1.0
	v_add_f32_e32 v9, 1.0, v9
	v_mul_f32_e32 v0, v0, v9
	v_mfma_f32_16x16x32_bf16 v[4:7], v[16:19], v[32:35], v[4:7]
	v_ashrrev_i32_e32 v9, 31, v8
	v_lshlrev_b64 v[8:9], 12, v[8:9]
	v_cvt_pk_bf16_f32 v0, v0, s0
	v_mfma_f32_16x16x32_bf16 v[4:7], v[12:15], v[24:27], v[4:7]
	v_lshl_add_u64 v[8:9], v[162:163], 0, v[8:9]
	global_store_short v[8:9], v0, off
	v_add_u32_e32 v8, s35, v174
	v_add_u32_e32 v9, s34, v175
	v_cndmask_b32_e64 v8, v9, v8, s[6:7]
	s_nop 2
	v_mul_f32_e32 v10, 0x3d372713, v4
	v_mul_f32_e32 v10, v4, v10
	v_fma_f32 v10, v4, v10, v4
	v_mul_f32_e32 v10, 0x3f4c422a, v10
	v_add_f32_e32 v10, v10, v10
	v_mul_f32_e32 v10, 0x3fb8aa3b, v10
	v_exp_f32_e32 v10, v10
	v_mul_f32_e32 v4, 0.5, v4
	v_ashrrev_i32_e32 v9, 31, v8
	v_lshlrev_b64 v[8:9], 12, v[8:9]
	v_add_f32_e32 v0, 1.0, v10
	v_rcp_f32_e32 v0, v0
	v_lshl_add_u64 v[8:9], v[162:163], 0, v[8:9]
	v_fma_f32 v0, v0, -2.0, 1.0
	v_add_f32_e32 v0, 1.0, v0
	v_mul_f32_e32 v0, v4, v0
	v_mul_f32_e32 v4, 0x3d372713, v1
	v_mul_f32_e32 v4, v1, v4
	v_fma_f32 v4, v1, v4, v1
	v_mul_f32_e32 v4, 0x3f4c422a, v4
	v_add_f32_e32 v4, v4, v4
	v_mul_f32_e32 v4, 0x3fb8aa3b, v4
	v_exp_f32_e32 v4, v4
	v_cvt_pk_bf16_f32 v0, v0, s0
	global_store_short v[8:9], v0, off
	v_add_u32_e32 v8, s34, v177
	v_add_f32_e32 v0, 1.0, v4
	v_rcp_f32_e32 v4, v0
	v_add_u32_e32 v0, s35, v176
	v_cndmask_b32_e64 v0, v8, v0, s[8:9]
	v_mul_f32_e32 v8, 0x3d372713, v5
	v_mul_f32_e32 v8, v5, v8
	v_fma_f32 v8, v5, v8, v5
	v_mul_f32_e32 v8, 0x3f4c422a, v8
	v_fma_f32 v4, v4, -2.0, 1.0
	v_add_f32_e32 v8, v8, v8
	v_mul_f32_e32 v1, 0.5, v1
	v_add_f32_e32 v4, 1.0, v4
	v_mul_f32_e32 v8, 0x3fb8aa3b, v8
	v_mul_f32_e32 v1, v1, v4
	v_exp_f32_e32 v8, v8
	v_cvt_pk_bf16_f32 v4, v1, s0
	v_ashrrev_i32_e32 v1, 31, v0
	v_lshlrev_b64 v[0:1], 12, v[0:1]
	v_lshl_add_u64 v[0:1], v[162:163], 0, v[0:1]
	global_store_short v[0:1], v4, off
	v_add_f32_e32 v0, 1.0, v8
	v_rcp_f32_e32 v1, v0
	v_add_u32_e32 v0, s35, v178
	v_add_u32_e32 v4, s34, v179
	v_cndmask_b32_e64 v0, v4, v0, s[10:11]
	v_mul_f32_e32 v4, 0.5, v5
	v_mul_f32_e32 v5, 0x3d372713, v2
	v_mul_f32_e32 v5, v2, v5
	v_fma_f32 v5, v2, v5, v2
	v_mul_f32_e32 v5, 0x3f4c422a, v5
	v_fma_f32 v1, v1, -2.0, 1.0
	v_add_f32_e32 v5, v5, v5
	v_add_f32_e32 v1, 1.0, v1
	v_mul_f32_e32 v5, 0x3fb8aa3b, v5
	v_mul_f32_e32 v1, v4, v1
	v_exp_f32_e32 v5, v5
	v_cvt_pk_bf16_f32 v4, v1, s0
	v_ashrrev_i32_e32 v1, 31, v0
	v_lshlrev_b64 v[0:1], 12, v[0:1]
	v_lshl_add_u64 v[0:1], v[162:163], 0, v[0:1]
	global_store_short v[0:1], v4, off
	v_add_f32_e32 v0, 1.0, v5
	v_rcp_f32_e32 v1, v0
	v_add_u32_e32 v0, s35, v180
	v_add_u32_e32 v4, s34, v181
	v_cndmask_b32_e64 v0, v4, v0, s[12:13]
	v_mul_f32_e32 v4, 0x3d372713, v6
	v_mul_f32_e32 v4, v6, v4
	v_fma_f32 v4, v6, v4, v6
	v_mul_f32_e32 v4, 0x3f4c422a, v4
	v_fma_f32 v1, v1, -2.0, 1.0
	v_add_f32_e32 v4, v4, v4
	v_mul_f32_e32 v2, 0.5, v2
	v_add_f32_e32 v1, 1.0, v1
	v_mul_f32_e32 v4, 0x3fb8aa3b, v4
	v_mul_f32_e32 v1, v2, v1
	v_exp_f32_e32 v4, v4
	v_cvt_pk_bf16_f32 v2, v1, s0
	v_ashrrev_i32_e32 v1, 31, v0
	v_lshlrev_b64 v[0:1], 12, v[0:1]
	v_lshl_add_u64 v[0:1], v[162:163], 0, v[0:1]
	global_store_short v[0:1], v2, off
	v_add_f32_e32 v0, 1.0, v4
	v_rcp_f32_e32 v1, v0
	v_mul_f32_e32 v4, 0x3d372713, v3
	v_mul_f32_e32 v4, v3, v4
	v_fma_f32 v4, v3, v4, v3
	v_mul_f32_e32 v4, 0x3f4c422a, v4
	v_add_u32_e32 v0, s35, v182
	v_add_u32_e32 v2, s34, v183
	v_fma_f32 v1, v1, -2.0, 1.0
	v_add_f32_e32 v4, v4, v4
	v_cndmask_b32_e64 v0, v2, v0, s[14:15]
	v_mul_f32_e32 v2, 0.5, v6
	v_add_f32_e32 v1, 1.0, v1
	v_mul_f32_e32 v4, 0x3fb8aa3b, v4
	v_mul_f32_e32 v1, v2, v1
	v_exp_f32_e32 v4, v4
	v_cvt_pk_bf16_f32 v2, v1, s0
	v_ashrrev_i32_e32 v1, 31, v0
	v_lshlrev_b64 v[0:1], 12, v[0:1]
	v_lshl_add_u64 v[0:1], v[162:163], 0, v[0:1]
	global_store_short v[0:1], v2, off
	v_add_f32_e32 v0, 1.0, v4
	v_rcp_f32_e32 v1, v0
	v_add_u32_e32 v0, s35, v184
	v_add_u32_e32 v2, s34, v185
	v_cndmask_b32_e64 v0, v2, v0, s[16:17]
	v_mul_f32_e32 v2, 0.5, v3
	v_mul_f32_e32 v3, 0x3d372713, v7
	v_mul_f32_e32 v3, v7, v3
	v_fma_f32 v3, v7, v3, v7
	v_mul_f32_e32 v3, 0x3f4c422a, v3
	v_fma_f32 v1, v1, -2.0, 1.0
	v_add_f32_e32 v3, v3, v3
	v_add_f32_e32 v1, 1.0, v1
	v_mul_f32_e32 v3, 0x3fb8aa3b, v3
	v_mul_f32_e32 v1, v2, v1
	v_exp_f32_e32 v3, v3
	v_cvt_pk_bf16_f32 v2, v1, s0
	v_ashrrev_i32_e32 v1, 31, v0
	v_lshlrev_b64 v[0:1], 12, v[0:1]
	v_lshl_add_u64 v[0:1], v[162:163], 0, v[0:1]
	global_store_short v[0:1], v2, off
	v_add_f32_e32 v0, 1.0, v3
	v_rcp_f32_e32 v1, v0
	v_add_u32_e32 v0, s35, v186
	v_add_u32_e32 v2, s34, v187
	v_cndmask_b32_e64 v0, v2, v0, s[18:19]
	v_fma_f32 v1, v1, -2.0, 1.0
	v_mul_f32_e32 v2, 0.5, v7
	v_add_f32_e32 v1, 1.0, v1
	v_mul_f32_e32 v1, v2, v1
	v_cvt_pk_bf16_f32 v2, v1, s0
	v_ashrrev_i32_e32 v1, 31, v0
	v_lshlrev_b64 v[0:1], 12, v[0:1]
	v_lshl_add_u64 v[0:1], v[162:163], 0, v[0:1]
	global_store_short v[0:1], v2, off
	s_waitcnt lgkmcnt(0)
	s_barrier
	s_cbranch_scc1 .LBB0_3209

.LBB0_3181:
	s_bitcmp1_b32 s37, 0
	s_cselect_b32 s28, 0x4100, 0
	v_add_u32_e32 v222, s28, v170
	ds_read_b128 v[228:231], v222
	ds_read_b128 v[232:235], v222 offset:64
	v_lshl_add_u64 v[166:167], v[164:165], 0, s[26:27]
	v_add_co_u32_e32 v198, vcc, 0x4000, v166
	s_waitcnt lgkmcnt(2)
	s_waitcnt lgkmcnt(1)
	v_mfma_f32_16x16x32_bf16 v[136:139], v[228:231], v[96:99], 0
	v_addc_co_u32_e32 v199, vcc, 0, v167, vcc
	v_add_co_u32_e32 v166, vcc, 0x6000, v166
	v_mfma_f32_16x16x32_bf16 v[128:131], v[228:231], v[120:123], 0
	ds_read_b128 v[228:231], v222 offset:128
	v_addc_co_u32_e32 v167, vcc, 0, v167, vcc
	s_waitcnt lgkmcnt(1)
	v_mfma_f32_16x16x32_bf16 v[136:139], v[232:235], v[92:95], v[136:139]
	v_mfma_f32_16x16x32_bf16 v[128:131], v[232:235], v[116:119], v[128:131]
	ds_read_b128 v[232:235], v222 offset:192
	s_waitcnt lgkmcnt(1)
	v_mfma_f32_16x16x32_bf16 v[136:139], v[228:231], v[80:83], v[136:139]
	v_mfma_f32_16x16x32_bf16 v[128:131], v[228:231], v[112:115], v[128:131]
	ds_read_b128 v[228:231], v222 offset:256
	s_waitcnt lgkmcnt(1)
	v_mfma_f32_16x16x32_bf16 v[132:135], v[232:235], v[76:79], v[136:139]
	v_mfma_f32_16x16x32_bf16 v[128:131], v[232:235], v[108:111], v[128:131]
	ds_read_b128 v[232:235], v222 offset:320
	ds_read_b128 v[194:197], v222 offset:512
	s_waitcnt lgkmcnt(2)
	v_mfma_f32_16x16x32_bf16 v[132:135], v[228:231], v[72:75], v[132:135]
	v_mfma_f32_16x16x32_bf16 v[128:131], v[228:231], v[104:107], v[128:131]
	ds_read_b128 v[228:231], v222 offset:384
	s_waitcnt lgkmcnt(2)
	v_mfma_f32_16x16x32_bf16 v[132:135], v[232:235], v[64:67], v[132:135]
	v_mfma_f32_16x16x32_bf16 v[128:131], v[232:235], v[100:103], v[128:131]
	ds_read_b128 v[232:235], v222 offset:448
	s_waitcnt lgkmcnt(2)
	s_waitcnt lgkmcnt(1)
	v_mfma_f32_16x16x32_bf16 v[132:135], v[228:231], v[56:59], v[132:135]
	v_mfma_f32_16x16x32_bf16 v[136:139], v[228:231], v[88:91], v[128:131]
	s_waitcnt lgkmcnt(0)
	v_mfma_f32_16x16x32_bf16 v[190:193], v[232:235], v[48:51], v[132:135]
	s_nop 0
	global_load_dwordx4 v[128:131], v[198:199], off
	ds_read_b128 v[198:201], v222 offset:576
	ds_read_b128 v[202:205], v222 offset:640
	ds_read_b128 v[206:209], v222 offset:704
	ds_read_b128 v[210:213], v222 offset:768
	ds_read_b128 v[214:217], v222 offset:832
	ds_read_b128 v[218:221], v222 offset:896
	global_load_dwordx4 v[132:135], v[166:167], off
	v_mfma_f32_16x16x32_bf16 v[136:139], v[232:235], v[84:87], v[136:139]
	v_mfma_f32_16x16x32_bf16 v[140:143], v[194:197], v[40:43], v[190:193]
	ds_read_b128 v[222:225], v222 offset:960
	s_waitcnt lgkmcnt(6)
	v_mfma_f32_16x16x32_bf16 v[140:143], v[198:201], v[28:31], v[140:143]
	v_add_u32_e32 v191, s36, v171
	v_add_u32_e32 v167, 0xffffff00, v191
	v_add_u32_e32 v190, s36, v189
	s_waitcnt lgkmcnt(5)
	v_mfma_f32_16x16x32_bf16 v[140:143], v[202:205], v[20:23], v[140:143]
	v_lshrrev_b32_e32 v167, 6, v167
	v_add_u32_e32 v166, 0x2000, v190
	v_add_u32_e32 v167, s22, v167
	s_waitcnt lgkmcnt(4)
	v_mfma_f32_16x16x32_bf16 v[140:143], v[206:209], v[16:19], v[140:143]
	v_cmp_gt_i32_e32 vcc, s2, v191
	s_waitcnt lgkmcnt(3)
	v_mfma_f32_16x16x32_bf16 v[140:143], v[210:213], v[12:15], v[140:143]
	v_cndmask_b32_e32 v166, v167, v166, vcc
	s_waitcnt lgkmcnt(2)
	v_mfma_f32_16x16x32_bf16 v[140:143], v[214:217], v[8:11], v[140:143]
	s_waitcnt vmcnt(9)
	v_mfma_f32_16x16x32_bf16 v[136:139], v[194:197], v[124:127], v[136:139]
	s_waitcnt lgkmcnt(1)
	v_mfma_f32_16x16x32_bf16 v[140:143], v[218:221], v[0:3], v[140:143]
	s_waitcnt vmcnt(8)
	v_mfma_f32_16x16x32_bf16 v[136:139], v[198:201], v[68:71], v[136:139]
	s_waitcnt lgkmcnt(0)
	v_mfma_f32_16x16x32_bf16 v[140:143], v[222:225], v[4:7], v[140:143]
	s_waitcnt vmcnt(7)
	v_mfma_f32_16x16x32_bf16 v[136:139], v[202:205], v[60:63], v[136:139]
	s_waitcnt vmcnt(6)
	v_mfma_f32_16x16x32_bf16 v[136:139], v[206:209], v[52:55], v[136:139]
	s_nop 3
	v_mul_f32_e32 v192, 0x3d372713, v140
	v_mul_f32_e32 v192, v140, v192
	v_fma_f32 v192, v140, v192, v140
	v_mul_f32_e32 v192, 0x3f4c422a, v192
	v_add_f32_e32 v192, v192, v192
	v_mul_f32_e32 v192, 0x3fb8aa3b, v192
	v_exp_f32_e32 v192, v192
	s_waitcnt vmcnt(5)
	v_mfma_f32_16x16x32_bf16 v[136:139], v[210:213], v[44:47], v[136:139]
	v_mul_f32_e32 v140, 0.5, v140
	v_add_f32_e32 v192, 1.0, v192
	s_waitcnt vmcnt(4)
	v_mfma_f32_16x16x32_bf16 v[136:139], v[214:217], v[36:39], v[136:139]
	v_rcp_f32_e32 v192, v192
	s_nop 0
	v_fma_f32 v167, v192, -2.0, 1.0
	s_waitcnt vmcnt(3)
	v_mfma_f32_16x16x32_bf16 v[136:139], v[218:221], v[32:35], v[136:139]
	v_add_f32_e32 v167, 1.0, v167
	v_mul_f32_e32 v140, v140, v167
	v_ashrrev_i32_e32 v167, 31, v166
	v_lshlrev_b64 v[166:167], 12, v[166:167]
	s_waitcnt vmcnt(2)
	v_mfma_f32_16x16x32_bf16 v[136:139], v[222:225], v[24:27], v[136:139]
	v_cvt_pk_bf16_f32 v140, v140, s0
	v_lshl_add_u64 v[166:167], v[162:163], 0, v[166:167]
	global_store_short v[166:167], v140, off
	v_add_u32_e32 v140, 1, v191
	v_cmp_lt_i32_e32 vcc, s30, v140
	s_and_saveexec_b64 s[28:29], vcc
	s_xor_b64 s[28:29], exec, s[28:29]
	v_add_u32_e32 v140, 0xffffff01, v191
	v_add3_u32 v166, v158, s26, 64
	v_and_b32_e32 v166, 0xfc0, v166
	v_lshrrev_b32_e32 v140, 6, v140
	v_add3_u32 v166, v140, s34, v166
	s_andn2_saveexec_b64 s[28:29], s[28:29]
	v_add_u32_e32 v166, 0x2001, v190
	s_or_b64 exec, exec, s[28:29]
	v_mul_f32_e32 v140, 0x3d372713, v136
	v_mul_f32_e32 v140, v136, v140
	v_fma_f32 v140, v136, v140, v136
	v_mul_f32_e32 v140, 0x3f4c422a, v140
	v_add_f32_e32 v140, v140, v140
	v_mul_f32_e32 v140, 0x3fb8aa3b, v140
	v_exp_f32_e32 v140, v140
	v_mul_f32_e32 v136, 0.5, v136
	v_ashrrev_i32_e32 v167, 31, v166
	v_lshlrev_b64 v[166:167], 12, v[166:167]
	v_add_f32_e32 v140, 1.0, v140
	v_rcp_f32_e32 v140, v140
	v_add_u32_e32 v192, 16, v191
	v_lshl_add_u64 v[166:167], v[162:163], 0, v[166:167]
	v_cmp_lt_i32_e32 vcc, s30, v192
	v_fma_f32 v140, v140, -2.0, 1.0
	v_add_f32_e32 v140, 1.0, v140
	v_mul_f32_e32 v136, v136, v140
	v_cvt_pk_bf16_f32 v136, v136, s0
	global_store_short v[166:167], v136, off
	v_add_u32_e32 v166, s26, v158
	s_and_saveexec_b64 s[28:29], vcc
	s_xor_b64 s[28:29], exec, s[28:29]
	v_add_u32_e32 v136, 0xffffff10, v191
	v_add_u32_e32 v140, 0x400, v166
	v_and_b32_e32 v140, 0xf80, v140
	v_lshrrev_b32_e32 v136, 6, v136
	v_add3_u32 v140, v136, s34, v140
	s_andn2_saveexec_b64 s[28:29], s[28:29]
	v_add_u32_e32 v140, 0x2010, v190
	s_or_b64 exec, exec, s[28:29]
	v_mul_f32_e32 v136, 0x3d372713, v141
	v_mul_f32_e32 v136, v141, v136
	v_fma_f32 v136, v141, v136, v141
	v_mul_f32_e32 v136, 0x3f4c422a, v136
	v_add_f32_e32 v136, v136, v136
	v_mul_f32_e32 v136, 0x3fb8aa3b, v136
	v_exp_f32_e32 v136, v136
	v_mul_f32_e32 v167, 0.5, v141
	v_ashrrev_i32_e32 v141, 31, v140
	v_add_u32_e32 v192, 17, v191
	v_add_f32_e32 v136, 1.0, v136
	v_rcp_f32_e32 v136, v136
	v_lshlrev_b64 v[140:141], 12, v[140:141]
	v_lshl_add_u64 v[140:141], v[162:163], 0, v[140:141]
	v_cmp_lt_i32_e32 vcc, s30, v192
	v_fma_f32 v136, v136, -2.0, 1.0
	v_add_f32_e32 v136, 1.0, v136
	v_mul_f32_e32 v136, v167, v136
	v_cvt_pk_bf16_f32 v136, v136, s0
	global_store_short v[140:141], v136, off
	s_and_saveexec_b64 s[28:29], vcc
	s_xor_b64 s[28:29], exec, s[28:29]
	v_add_u32_e32 v136, 0xffffff11, v191
	v_add_u32_e32 v140, 0x440, v166
	v_and_b32_e32 v140, 0xfc0, v140
	v_lshrrev_b32_e32 v136, 6, v136
	v_add3_u32 v136, v136, s34, v140
	s_andn2_saveexec_b64 s[28:29], s[28:29]
	v_add_u32_e32 v136, 0x2011, v190
	s_or_b64 exec, exec, s[28:29]
	v_mul_f32_e32 v140, 0x3d372713, v137
	v_mul_f32_e32 v140, v137, v140
	v_fma_f32 v140, v137, v140, v137
	v_mul_f32_e32 v140, 0x3f4c422a, v140
	v_add_f32_e32 v140, v140, v140
	v_mul_f32_e32 v140, 0x3fb8aa3b, v140
	v_exp_f32_e32 v140, v140
	v_mul_f32_e32 v141, 0.5, v137
	v_ashrrev_i32_e32 v137, 31, v136
	v_add_u32_e32 v167, 32, v191
	v_add_f32_e32 v140, 1.0, v140
	v_rcp_f32_e32 v140, v140
	v_lshlrev_b64 v[136:137], 12, v[136:137]
	v_lshl_add_u64 v[136:137], v[162:163], 0, v[136:137]
	v_cmp_lt_i32_e32 vcc, s30, v167
	v_fma_f32 v140, v140, -2.0, 1.0
	v_add_f32_e32 v140, 1.0, v140
	v_mul_f32_e32 v140, v141, v140
	v_cvt_pk_bf16_f32 v140, v140, s0
	global_store_short v[136:137], v140, off
	s_and_saveexec_b64 s[28:29], vcc
	s_xor_b64 s[28:29], exec, s[28:29]
	v_add_u32_e32 v136, 0xffffff20, v191
	v_add_u32_e32 v137, 0x800, v166
	v_and_b32_e32 v137, 0xf80, v137
	v_lshrrev_b32_e32 v136, 6, v136
	v_add3_u32 v136, v136, s34, v137
	s_andn2_saveexec_b64 s[28:29], s[28:29]
	v_add_u32_e32 v136, 0x2020, v190
	s_or_b64 exec, exec, s[28:29]
	v_mul_f32_e32 v137, 0x3d372713, v142
	v_mul_f32_e32 v137, v142, v137
	v_fma_f32 v137, v142, v137, v142
	v_mul_f32_e32 v137, 0x3f4c422a, v137
	v_add_f32_e32 v137, v137, v137
	v_mul_f32_e32 v137, 0x3fb8aa3b, v137
	v_exp_f32_e32 v140, v137
	v_mul_f32_e32 v141, 0.5, v142
	v_ashrrev_i32_e32 v137, 31, v136
	v_add_u32_e32 v142, 33, v191
	v_add_f32_e32 v140, 1.0, v140
	v_rcp_f32_e32 v140, v140
	v_lshlrev_b64 v[136:137], 12, v[136:137]
	v_lshl_add_u64 v[136:137], v[162:163], 0, v[136:137]
	v_cmp_lt_i32_e32 vcc, s30, v142
	v_fma_f32 v140, v140, -2.0, 1.0
	v_add_f32_e32 v140, 1.0, v140
	v_mul_f32_e32 v140, v141, v140
	v_cvt_pk_bf16_f32 v140, v140, s0
	global_store_short v[136:137], v140, off
	s_and_saveexec_b64 s[28:29], vcc
	s_xor_b64 s[28:29], exec, s[28:29]
	v_add_u32_e32 v136, 0xffffff21, v191
	v_add_u32_e32 v137, 0x840, v166
	v_and_b32_e32 v137, 0xfc0, v137
	v_lshrrev_b32_e32 v136, 6, v136
	v_add3_u32 v136, v136, s34, v137
	s_andn2_saveexec_b64 s[28:29], s[28:29]
	v_add_u32_e32 v136, 0x2021, v190
	s_or_b64 exec, exec, s[28:29]
	v_mul_f32_e32 v137, 0x3d372713, v138
	v_mul_f32_e32 v137, v138, v137
	v_fma_f32 v137, v138, v137, v138
	v_mul_f32_e32 v137, 0x3f4c422a, v137
	v_add_f32_e32 v137, v137, v137
	v_mul_f32_e32 v137, 0x3fb8aa3b, v137
	v_exp_f32_e32 v140, v137
	v_mul_f32_e32 v138, 0.5, v138
	v_ashrrev_i32_e32 v137, 31, v136
	v_add_u32_e32 v141, 48, v191
	v_add_f32_e32 v140, 1.0, v140
	v_rcp_f32_e32 v140, v140
	v_lshlrev_b64 v[136:137], 12, v[136:137]
	v_lshl_add_u64 v[136:137], v[162:163], 0, v[136:137]
	v_cmp_lt_i32_e32 vcc, s30, v141
	v_fma_f32 v140, v140, -2.0, 1.0
	v_add_f32_e32 v140, 1.0, v140
	v_mul_f32_e32 v138, v138, v140
	v_cvt_pk_bf16_f32 v138, v138, s0
	global_store_short v[136:137], v138, off
	s_and_saveexec_b64 s[28:29], vcc
	s_xor_b64 s[28:29], exec, s[28:29]
	v_add_u32_e32 v136, 0xffffff30, v191
	v_add_u32_e32 v137, 0xc00, v166
	v_and_b32_e32 v137, 0xf80, v137
	v_lshrrev_b32_e32 v136, 6, v136
	v_add3_u32 v136, v136, s34, v137
	s_andn2_saveexec_b64 s[28:29], s[28:29]
	v_add_u32_e32 v136, 0x2030, v190
	s_or_b64 exec, exec, s[28:29]
	v_mul_f32_e32 v137, 0x3d372713, v143
	v_mul_f32_e32 v137, v143, v137
	v_fma_f32 v137, v143, v137, v143
	v_mul_f32_e32 v137, 0x3f4c422a, v137
	v_add_f32_e32 v137, v137, v137
	v_mul_f32_e32 v137, 0x3fb8aa3b, v137
	v_exp_f32_e32 v138, v137
	v_mul_f32_e32 v140, 0.5, v143
	v_ashrrev_i32_e32 v137, 31, v136
	v_add_u32_e32 v141, 49, v191
	v_add_f32_e32 v138, 1.0, v138
	v_rcp_f32_e32 v138, v138
	v_lshlrev_b64 v[136:137], 12, v[136:137]
	v_lshl_add_u64 v[136:137], v[162:163], 0, v[136:137]
	v_cmp_lt_i32_e32 vcc, s30, v141
	v_fma_f32 v138, v138, -2.0, 1.0
	v_add_f32_e32 v138, 1.0, v138
	v_mul_f32_e32 v138, v140, v138
	v_cvt_pk_bf16_f32 v138, v138, s0
	global_store_short v[136:137], v138, off
	s_and_saveexec_b64 s[28:29], vcc
	s_xor_b64 s[28:29], exec, s[28:29]
	v_add_u32_e32 v136, 0xffffff31, v191
	v_add_u32_e32 v137, 0xc40, v166
	v_and_b32_e32 v137, 0xfc0, v137
	v_lshrrev_b32_e32 v136, 6, v136
	v_add3_u32 v136, v136, s34, v137
	s_andn2_saveexec_b64 s[28:29], s[28:29]
	s_cbranch_execz .LBB0_3180
	v_add_u32_e32 v136, 0x2031, v190
	s_branch .LBB0_3180

.LBB0_3336:
	s_add_i32 s16, s14, 0x100
	s_cmpk_gt_i32 s14, 0x5f
	s_cselect_b64 s[12:13], -1, 0
	v_add_u32_e32 v64, v88, v89
	s_and_b64 vcc, exec, s[12:13]
	s_barrier
	s_waitcnt vmcnt(15)
	ds_write_b128 v64, v[0:3]
	s_waitcnt vmcnt(14)
	ds_write_b128 v64, v[4:7] offset:8256
	s_waitcnt vmcnt(13)
	ds_write_b128 v64, v[8:11] offset:16512
	s_waitcnt vmcnt(12)
	ds_write_b128 v64, v[12:15] offset:24768
	s_waitcnt vmcnt(11)
	ds_write_b128 v64, v[16:19] offset:33024
	s_waitcnt vmcnt(10)
	ds_write_b128 v64, v[20:23] offset:41280
	s_waitcnt vmcnt(9)
	ds_write_b128 v100, v[24:27]
	s_waitcnt vmcnt(8)
	ds_write_b128 v100, v[28:31] offset:8256
	s_waitcnt vmcnt(7)
	ds_write_b128 v100, v[32:35] offset:16512
	s_waitcnt vmcnt(6)
	ds_write_b128 v100, v[36:39] offset:24768
	s_waitcnt vmcnt(5)
	ds_write_b128 v100, v[40:43] offset:33024
	s_waitcnt vmcnt(4)
	ds_write_b128 v100, v[44:47] offset:41280
	s_waitcnt vmcnt(3)
	ds_write_b128 v100, v[48:51] offset:49536
	s_waitcnt vmcnt(2)
	ds_write_b128 v100, v[52:55] offset:57792
	s_waitcnt vmcnt(1)
	ds_write_b128 v101, v[56:59] offset:57792
	s_waitcnt vmcnt(0)
	ds_write_b128 v102, v[60:63] offset:57792
	s_waitcnt lgkmcnt(0)
	s_barrier
	s_cbranch_vccnz .LBB0_3338
	s_mul_hi_u32 s10, s16, 0xba2e8ba3
	s_lshr_b32 s10, s10, 3
	s_lshl_b32 s15, s10, 6
	s_mul_i32 s10, s10, 11
	s_sub_i32 s10, s16, s10
	v_lshl_or_b32 v64, s10, 9, v71
	v_add_u32_e32 v0, s15, v70
	v_mov_b64_e32 v[56:57], s[8:9]
	v_add_u32_e32 v2, s15, v72
	v_add_u32_e32 v8, s15, v73
	v_add_u32_e32 v10, s15, v74
	v_add_u32_e32 v16, s15, v75
	v_add_u32_e32 v18, s15, v76
	v_add_u32_e32 v24, s15, v77
	v_add_u32_e32 v26, s15, v78
	v_add_u32_e32 v32, s15, v79
	v_add_u32_e32 v34, s15, v80
	v_add_u32_e32 v40, s15, v81
	v_add_u32_e32 v42, s15, v82
	v_add_u32_e32 v48, s15, v83
	v_add_u32_e32 v50, s15, v84
	v_add_u32_e32 v60, s15, v85
	v_add_u32_e32 v62, s15, v86
	v_mad_i64_i32 v[0:1], s[18:19], v0, s2, v[56:57]
	v_lshlrev_b64 v[58:59], 2, v[64:65]
	v_mad_i64_i32 v[2:3], s[18:19], v2, s2, v[56:57]
	v_mad_i64_i32 v[8:9], s[18:19], v8, s2, v[56:57]
	v_mad_i64_i32 v[10:11], s[18:19], v10, s2, v[56:57]
	v_mad_i64_i32 v[16:17], s[18:19], v16, s2, v[56:57]
	v_mad_i64_i32 v[18:19], s[18:19], v18, s2, v[56:57]
	v_mad_i64_i32 v[24:25], s[18:19], v24, s2, v[56:57]
	v_mad_i64_i32 v[26:27], s[18:19], v26, s2, v[56:57]
	v_mad_i64_i32 v[32:33], s[18:19], v32, s2, v[56:57]
	v_mad_i64_i32 v[34:35], s[18:19], v34, s2, v[56:57]
	v_mad_i64_i32 v[40:41], s[18:19], v40, s2, v[56:57]
	v_mad_i64_i32 v[42:43], s[18:19], v42, s2, v[56:57]
	v_mad_i64_i32 v[48:49], s[18:19], v48, s2, v[56:57]
	v_mad_i64_i32 v[50:51], s[18:19], v50, s2, v[56:57]
	v_mad_i64_i32 v[60:61], s[18:19], v60, s2, v[56:57]
	v_mad_i64_i32 v[56:57], s[18:19], v62, s2, v[56:57]
	v_lshl_add_u64 v[0:1], v[0:1], 0, v[58:59]
	v_lshl_add_u64 v[4:5], v[2:3], 0, v[58:59]
	v_lshl_add_u64 v[8:9], v[8:9], 0, v[58:59]
	v_lshl_add_u64 v[12:13], v[10:11], 0, v[58:59]
	v_lshl_add_u64 v[16:17], v[16:17], 0, v[58:59]
	v_lshl_add_u64 v[20:21], v[18:19], 0, v[58:59]
	v_lshl_add_u64 v[24:25], v[24:25], 0, v[58:59]
	v_lshl_add_u64 v[28:29], v[26:27], 0, v[58:59]
	v_lshl_add_u64 v[32:33], v[32:33], 0, v[58:59]
	v_lshl_add_u64 v[36:37], v[34:35], 0, v[58:59]
	v_lshl_add_u64 v[40:41], v[40:41], 0, v[58:59]
	v_lshl_add_u64 v[44:45], v[42:43], 0, v[58:59]
	v_lshl_add_u64 v[48:49], v[48:49], 0, v[58:59]
	v_lshl_add_u64 v[52:53], v[50:51], 0, v[58:59]
	v_lshl_add_u64 v[60:61], v[60:61], 0, v[58:59]
	v_lshl_add_u64 v[62:63], v[56:57], 0, v[58:59]
	global_load_dwordx4 v[0:3], v[0:1], off
	s_nop 0
	global_load_dwordx4 v[4:7], v[4:5], off
	s_nop 0
	global_load_dwordx4 v[8:11], v[8:9], off
	s_nop 0
	global_load_dwordx4 v[12:15], v[12:13], off
	s_nop 0
	global_load_dwordx4 v[16:19], v[16:17], off
	s_nop 0
	global_load_dwordx4 v[20:23], v[20:21], off
	s_nop 0
	global_load_dwordx4 v[24:27], v[24:25], off
	s_nop 0
	global_load_dwordx4 v[28:31], v[28:29], off
	s_nop 0
	global_load_dwordx4 v[32:35], v[32:33], off
	s_nop 0
	global_load_dwordx4 v[36:39], v[36:37], off
	s_nop 0
	global_load_dwordx4 v[40:43], v[40:41], off
	s_nop 0
	global_load_dwordx4 v[44:47], v[44:45], off
	s_nop 0
	global_load_dwordx4 v[48:51], v[48:49], off
	s_nop 0
	global_load_dwordx4 v[52:55], v[52:53], off
	s_nop 0
	global_load_dwordx4 v[56:59], v[60:61], off
	global_load_dwordx4 v[60:63], v[62:63], off

.LBB0_3359:
	s_add_i32 s5, s12, 0x100
	s_cmpk_gt_i32 s12, 0x5f
	s_cselect_b64 s[10:11], -1, 0
	v_add_u32_e32 v64, v87, v88
	s_and_b64 vcc, exec, s[10:11]
	s_barrier
	s_waitcnt vmcnt(15)
	ds_write_b128 v64, v[0:3]
	s_waitcnt vmcnt(14)
	ds_write_b128 v64, v[4:7] offset:8256
	s_waitcnt vmcnt(13)
	ds_write_b128 v64, v[8:11] offset:16512
	s_waitcnt vmcnt(12)
	ds_write_b128 v64, v[12:15] offset:24768
	s_waitcnt vmcnt(11)
	ds_write_b128 v64, v[16:19] offset:33024
	s_waitcnt vmcnt(10)
	ds_write_b128 v64, v[20:23] offset:41280
	s_waitcnt vmcnt(9)
	ds_write_b128 v100, v[24:27]
	s_waitcnt vmcnt(8)
	ds_write_b128 v100, v[28:31] offset:8256
	s_waitcnt vmcnt(7)
	ds_write_b128 v100, v[32:35] offset:16512
	s_waitcnt vmcnt(6)
	ds_write_b128 v100, v[36:39] offset:24768
	s_waitcnt vmcnt(5)
	ds_write_b128 v100, v[40:43] offset:33024
	s_waitcnt vmcnt(4)
	ds_write_b128 v100, v[44:47] offset:41280
	s_waitcnt vmcnt(3)
	ds_write_b128 v100, v[48:51] offset:49536
	s_waitcnt vmcnt(2)
	ds_write_b128 v100, v[52:55] offset:57792
	s_waitcnt vmcnt(1)
	ds_write_b128 v101, v[56:59] offset:57792
	s_waitcnt vmcnt(0)
	ds_write_b128 v102, v[60:63] offset:57792
	s_waitcnt lgkmcnt(0)
	s_barrier
	s_cbranch_vccnz .LBB0_3361
	s_mul_hi_u32 s8, s5, 0xba2e8ba3
	s_lshr_b32 s8, s8, 3
	s_lshl_b32 s13, s8, 6
	s_mul_i32 s8, s8, 11
	s_sub_i32 s8, s5, s8
	v_lshl_or_b32 v64, s8, 9, v71
	s_nop 1
	v_lshlrev_b64 v[110:111], 2, v[64:65]
	v_add_u32_e32 v0, s13, v70
	v_mov_b64_e32 v[56:57], s[6:7]
	v_mad_i64_i32 v[0:1], s[14:15], v0, s0, v[56:57]
	s_nop 0
	v_lshl_add_u64 v[112:113], v[0:1], 0, v[110:111]
	v_add_u32_e32 v0, s13, v72
	v_mad_i64_i32 v[0:1], s[14:15], v0, s0, v[56:57]
	v_lshl_add_u64 v[114:115], v[0:1], 0, v[110:111]
	global_load_dwordx4 v[0:3], v[112:113], off
	global_load_dwordx4 v[4:7], v[114:115], off
	v_add_u32_e32 v8, s13, v73
	v_add_u32_e32 v10, s13, v74
	v_add_u32_e32 v16, s13, v75
	v_add_u32_e32 v18, s13, v76
	v_add_u32_e32 v24, s13, v77
	v_add_u32_e32 v26, s13, v78
	v_add_u32_e32 v32, s13, v79
	v_add_u32_e32 v34, s13, v80
	v_add_u32_e32 v40, s13, v81
	v_add_u32_e32 v42, s13, v82
	v_add_u32_e32 v48, s13, v83
	v_add_u32_e32 v50, s13, v84
	v_add_u32_e32 v60, s13, v85
	v_add_u32_e32 v62, s13, v86
	v_mad_i64_i32 v[8:9], s[14:15], v8, s0, v[56:57]
	v_mad_i64_i32 v[10:11], s[14:15], v10, s0, v[56:57]
	v_mad_i64_i32 v[16:17], s[14:15], v16, s0, v[56:57]
	v_mad_i64_i32 v[18:19], s[14:15], v18, s0, v[56:57]
	v_mad_i64_i32 v[24:25], s[14:15], v24, s0, v[56:57]
	v_mad_i64_i32 v[26:27], s[14:15], v26, s0, v[56:57]
	v_mad_i64_i32 v[32:33], s[14:15], v32, s0, v[56:57]
	v_mad_i64_i32 v[34:35], s[14:15], v34, s0, v[56:57]
	v_mad_i64_i32 v[40:41], s[14:15], v40, s0, v[56:57]
	v_mad_i64_i32 v[42:43], s[14:15], v42, s0, v[56:57]
	v_mad_i64_i32 v[48:49], s[14:15], v48, s0, v[56:57]
	v_mad_i64_i32 v[50:51], s[14:15], v50, s0, v[56:57]
	v_mad_i64_i32 v[60:61], s[14:15], v60, s0, v[56:57]
	v_mad_i64_i32 v[56:57], s[14:15], v62, s0, v[56:57]
	v_lshl_add_u64 v[8:9], v[8:9], 0, v[110:111]
	v_lshl_add_u64 v[12:13], v[10:11], 0, v[110:111]
	v_lshl_add_u64 v[16:17], v[16:17], 0, v[110:111]
	v_lshl_add_u64 v[20:21], v[18:19], 0, v[110:111]
	v_lshl_add_u64 v[24:25], v[24:25], 0, v[110:111]
	v_lshl_add_u64 v[28:29], v[26:27], 0, v[110:111]
	v_lshl_add_u64 v[32:33], v[32:33], 0, v[110:111]
	v_lshl_add_u64 v[36:37], v[34:35], 0, v[110:111]
	v_lshl_add_u64 v[40:41], v[40:41], 0, v[110:111]
	v_lshl_add_u64 v[44:45], v[42:43], 0, v[110:111]
	v_lshl_add_u64 v[48:49], v[48:49], 0, v[110:111]
	v_lshl_add_u64 v[52:53], v[50:51], 0, v[110:111]
	v_lshl_add_u64 v[60:61], v[60:61], 0, v[110:111]
	v_lshl_add_u64 v[62:63], v[56:57], 0, v[110:111]
	global_load_dwordx4 v[8:11], v[8:9], off
	s_nop 0
	global_load_dwordx4 v[12:15], v[12:13], off
	s_nop 0
	global_load_dwordx4 v[16:19], v[16:17], off
	s_nop 0
	global_load_dwordx4 v[20:23], v[20:21], off
	s_nop 0
	global_load_dwordx4 v[24:27], v[24:25], off
	s_nop 0
	global_load_dwordx4 v[28:31], v[28:29], off
	s_nop 0
	global_load_dwordx4 v[32:35], v[32:33], off
	s_nop 0
	global_load_dwordx4 v[36:39], v[36:37], off
	s_nop 0
	global_load_dwordx4 v[40:43], v[40:41], off
	s_nop 0
	global_load_dwordx4 v[44:47], v[44:45], off
	s_nop 0
	global_load_dwordx4 v[48:51], v[48:49], off
	s_nop 0
	global_load_dwordx4 v[52:55], v[52:53], off
	s_nop 0
	global_load_dwordx4 v[56:59], v[60:61], off
	global_load_dwordx4 v[60:63], v[62:63], off

.LBB0_3382:
	global_load_dwordx4 v[28:31], v[44:45], off offset:-4096
	global_load_dwordx4 v[24:27], v[44:45], off offset:-3072
	global_load_dwordx4 v[20:23], v[44:45], off offset:-2048
	global_load_dwordx4 v[16:19], v[44:45], off offset:-1024
	global_load_dwordx4 v[12:15], v[44:45], off
	global_load_dwordx4 v[8:11], v[44:45], off offset:1024
	global_load_dwordx4 v[4:7], v[44:45], off offset:2048
	global_load_dwordx4 v[0:3], v[44:45], off offset:3072
	v_mbcnt_lo_u32_b32 v49, -1, 0
	v_mbcnt_hi_u32_b32 v49, -1, v49
	s_and_b64 vcc, exec, s[4:5]
	v_lshlrev_b32_e32 v109, 2, v49
	s_nop 1
	v_xor_b32_e32 v110, 64, v109
	s_waitcnt vmcnt(7)
	v_mul_f32_e32 v51, v29, v29
	s_waitcnt vmcnt(6)
	v_mul_f32_e32 v52, v25, v25
	s_waitcnt vmcnt(5)
	v_mul_f32_e32 v53, v21, v21
	v_fmac_f32_e32 v51, v28, v28
	v_fmac_f32_e32 v52, v24, v24
	s_waitcnt vmcnt(4)
	v_mul_f32_e32 v54, v17, v17
	v_fmac_f32_e32 v53, v20, v20
	v_fmac_f32_e32 v51, v30, v30
	v_fmac_f32_e32 v52, v26, v26
	s_waitcnt vmcnt(3)
	v_mul_f32_e32 v55, v13, v13
	v_fmac_f32_e32 v54, v16, v16
	v_fmac_f32_e32 v53, v22, v22
	v_fmac_f32_e32 v51, v31, v31
	v_fmac_f32_e32 v52, v27, v27
	s_waitcnt vmcnt(2)
	v_mul_f32_e32 v56, v9, v9
	v_fmac_f32_e32 v55, v12, v12
	v_fmac_f32_e32 v54, v18, v18
	v_fmac_f32_e32 v53, v23, v23
	v_add_f32_e32 v51, v51, v52
	s_waitcnt vmcnt(1)
	v_mul_f32_e32 v57, v5, v5
	v_fmac_f32_e32 v56, v8, v8
	v_fmac_f32_e32 v55, v14, v14
	v_fmac_f32_e32 v54, v19, v19
	v_add_f32_e32 v51, v51, v53
	s_waitcnt vmcnt(0)
	v_mul_f32_e32 v58, v1, v1
	v_fmac_f32_e32 v57, v4, v4
	v_fmac_f32_e32 v56, v10, v10
	v_fmac_f32_e32 v55, v15, v15
	v_add_f32_e32 v51, v51, v54
	v_fmac_f32_e32 v58, v0, v0
	v_fmac_f32_e32 v57, v6, v6
	v_fmac_f32_e32 v56, v11, v11
	v_add_f32_e32 v51, v51, v55
	v_fmac_f32_e32 v58, v2, v2
	v_fmac_f32_e32 v57, v7, v7
	v_add_f32_e32 v51, v51, v56
	s_waitcnt lgkmcnt(0)
	v_fmac_f32_e32 v58, v3, v3
	v_add_f32_e32 v51, v51, v57
	v_xor_b32_e32 v49, 0x80, v109
	v_add_f32_e32 v51, v51, v58
	ds_bpermute_b32 v49, v49, v51
	s_waitcnt lgkmcnt(0)
	v_add_f32_e32 v49, v51, v49
	ds_bpermute_b32 v111, v110, v49
	v_xor_b32_e32 v112, 32, v109
	s_waitcnt lgkmcnt(0)
	v_add_f32_e32 v49, v49, v111
	ds_bpermute_b32 v110, v112, v49
	v_xor_b32_e32 v111, 16, v109
	s_waitcnt lgkmcnt(0)
	v_add_f32_e32 v49, v49, v110
	ds_bpermute_b32 v110, v111, v49
	v_xor_b32_e32 v112, 8, v109
	v_xor_b32_e32 v50, 4, v109
	s_waitcnt lgkmcnt(0)
	v_add_f32_e32 v49, v49, v110
	ds_bpermute_b32 v109, v112, v49
	s_waitcnt lgkmcnt(0)
	v_add_f32_e32 v49, v49, v109
	ds_bpermute_b32 v50, v50, v49
	s_cbranch_vccnz .LBB0_3381
	s_ashr_i32 s16, s15, 31
	s_lshr_b32 s16, s16, 20
	s_add_i32 s16, s15, s16
	s_ashr_i32 s16, s16, 12
	s_cmpk_lt_i32 s15, 0x2000
	s_cselect_b32 s16, s16, 2
	s_mul_hi_i32 s17, s16, 0xc000
	s_mul_i32 s16, s16, 0xc000
	s_add_u32 s16, s1, s16
	s_addc_u32 s17, s3, s17
	v_lshl_add_u64 v[110:111], v[32:33], 2, s[16:17]
	v_add_co_u32_e32 v66, vcc, s14, v110
	s_waitcnt lgkmcnt(0)
	v_add_f32_e32 v49, v49, v50
	v_addc_co_u32_e32 v67, vcc, 0, v111, vcc
	global_load_dwordx4 v[112:115], v[66:67], off offset:-4096
	global_load_dwordx4 v[116:119], v[34:35], off
	v_add_co_u32_e32 v68, vcc, s2, v110
	s_nop 1
	v_addc_co_u32_e32 v69, vcc, 0, v111, vcc
	global_load_dwordx4 v[120:123], v[68:69], off offset:-4096
	v_lshl_add_u64 v[124:125], v[110:111], 0, s[10:11]
	global_load_dwordx4 v[128:131], v[124:125], off offset:1024
	global_load_dwordx4 v[132:135], v[34:35], off offset:1024
	v_lshl_add_u64 v[126:127], v[110:111], 0, s[12:13]
	global_load_dwordx4 v[136:139], v[126:127], off offset:1024
	global_load_dwordx4 v[140:143], v[124:125], off offset:2048
	global_load_dwordx4 v[144:147], v[34:35], off offset:2048
	global_load_dwordx4 v[148:151], v[126:127], off offset:2048
	global_load_dwordx4 v[152:155], v[124:125], off offset:3072
	global_load_dwordx4 v[156:159], v[34:35], off offset:3072
	global_load_dwordx4 v[160:163], v[126:127], off offset:3072
	global_load_dwordx4 v[164:167], v[66:67], off
	global_load_dwordx4 v[168:171], v[36:37], off
	global_load_dwordx4 v[172:175], v[68:69], off
	global_load_dwordx4 v[176:179], v[66:67], off offset:1024
	global_load_dwordx4 v[180:183], v[38:39], off
	global_load_dwordx4 v[184:187], v[68:69], off offset:1024
	global_load_dwordx4 v[188:191], v[66:67], off offset:2048
	global_load_dwordx4 v[192:195], v[40:41], off
	global_load_dwordx4 v[196:199], v[68:69], off offset:2048
	global_load_dwordx4 v[200:203], v[66:67], off offset:3072
	global_load_dwordx4 v[204:207], v[42:43], off
	global_load_dwordx4 v[208:211], v[68:69], off offset:3072
	v_fmamk_f32 v49, v49, 0x3a000000, v48
	v_mul_f32_e32 v50, 0x4b800000, v49
	v_cmp_gt_f32_e32 vcc, s0, v49
	s_nop 1
	v_cndmask_b32_e32 v49, v49, v50, vcc
	v_rsq_f32_e32 v49, v49
	s_nop 0
	v_mul_f32_e32 v50, 0x45800000, v49
	v_cndmask_b32_e32 v70, v49, v50, vcc
	v_pk_mul_f32 v[28:29], v[28:29], v[70:71] op_sel_hi:[1,0]
	v_pk_mul_f32 v[30:31], v[30:31], v[70:71] op_sel_hi:[1,0]
	v_pk_mul_f32 v[24:25], v[24:25], v[70:71] op_sel_hi:[1,0]
	v_pk_mul_f32 v[26:27], v[26:27], v[70:71] op_sel_hi:[1,0]
	v_pk_mul_f32 v[20:21], v[20:21], v[70:71] op_sel_hi:[1,0]
	v_pk_mul_f32 v[22:23], v[22:23], v[70:71] op_sel_hi:[1,0]
	v_pk_mul_f32 v[16:17], v[16:17], v[70:71] op_sel_hi:[1,0]
	v_pk_mul_f32 v[18:19], v[18:19], v[70:71] op_sel_hi:[1,0]
	v_pk_mul_f32 v[12:13], v[12:13], v[70:71] op_sel_hi:[1,0]
	v_pk_mul_f32 v[14:15], v[14:15], v[70:71] op_sel_hi:[1,0]
	v_pk_mul_f32 v[8:9], v[8:9], v[70:71] op_sel_hi:[1,0]
	v_pk_mul_f32 v[10:11], v[10:11], v[70:71] op_sel_hi:[1,0]
	v_pk_mul_f32 v[4:5], v[4:5], v[70:71] op_sel_hi:[1,0]
	v_pk_mul_f32 v[6:7], v[6:7], v[70:71] op_sel_hi:[1,0]
	v_pk_mul_f32 v[0:1], v[0:1], v[70:71] op_sel_hi:[1,0]
	v_pk_mul_f32 v[2:3], v[2:3], v[70:71] op_sel_hi:[1,0]
	s_waitcnt vmcnt(24)
	s_waitcnt vmcnt(23)
	v_pk_add_f32 v[50:51], v[112:113], 1.0 op_sel_hi:[1,0]
	s_waitcnt vmcnt(22)
	v_pk_mul_f32 v[28:29], v[28:29], v[116:117]
	v_pk_mul_f32 v[30:31], v[30:31], v[118:119]
	v_pk_add_f32 v[52:53], v[114:115], 1.0 op_sel_hi:[1,0]
	s_waitcnt vmcnt(21)
	v_pk_fma_f32 v[28:29], v[50:51], v[28:29], v[120:121]
	v_pk_fma_f32 v[30:31], v[52:53], v[30:31], v[122:123]
	v_cvt_pk_bf16_f32 v28, v28, v29
	v_cvt_pk_bf16_f32 v29, v30, v31
	global_store_dwordx2 v[46:47], v[28:29], off offset:-2048
	s_waitcnt vmcnt(21)
	s_nop 0
	v_pk_add_f32 v[28:29], v[128:129], 1.0 op_sel_hi:[1,0]
	s_waitcnt vmcnt(20)
	v_pk_mul_f32 v[24:25], v[24:25], v[132:133]
	v_pk_add_f32 v[30:31], v[130:131], 1.0 op_sel_hi:[1,0]
	v_pk_mul_f32 v[26:27], v[26:27], v[134:135]
	s_waitcnt vmcnt(19)
	v_pk_fma_f32 v[24:25], v[28:29], v[24:25], v[136:137]
	v_pk_fma_f32 v[26:27], v[30:31], v[26:27], v[138:139]
	v_cvt_pk_bf16_f32 v24, v24, v25
	v_cvt_pk_bf16_f32 v25, v26, v27
	global_store_dwordx2 v[46:47], v[24:25], off offset:-1536
	s_waitcnt vmcnt(19)
	s_nop 0
	v_pk_add_f32 v[24:25], v[140:141], 1.0 op_sel_hi:[1,0]
	s_waitcnt vmcnt(18)
	v_pk_mul_f32 v[20:21], v[20:21], v[144:145]
	v_pk_add_f32 v[26:27], v[142:143], 1.0 op_sel_hi:[1,0]
	v_pk_mul_f32 v[22:23], v[22:23], v[146:147]
	s_waitcnt vmcnt(17)
	v_pk_fma_f32 v[20:21], v[24:25], v[20:21], v[148:149]
	v_pk_fma_f32 v[22:23], v[26:27], v[22:23], v[150:151]
	v_cvt_pk_bf16_f32 v20, v20, v21
	v_cvt_pk_bf16_f32 v21, v22, v23
	global_store_dwordx2 v[46:47], v[20:21], off offset:-1024
	s_waitcnt vmcnt(17)
	s_nop 0
	v_pk_add_f32 v[20:21], v[152:153], 1.0 op_sel_hi:[1,0]
	s_waitcnt vmcnt(16)
	v_pk_mul_f32 v[16:17], v[16:17], v[156:157]
	v_pk_add_f32 v[22:23], v[154:155], 1.0 op_sel_hi:[1,0]
	v_pk_mul_f32 v[18:19], v[18:19], v[158:159]
	s_waitcnt vmcnt(15)
	v_pk_fma_f32 v[16:17], v[20:21], v[16:17], v[160:161]
	v_pk_fma_f32 v[18:19], v[22:23], v[18:19], v[162:163]
	v_cvt_pk_bf16_f32 v16, v16, v17
	v_cvt_pk_bf16_f32 v17, v18, v19
	global_store_dwordx2 v[46:47], v[16:17], off offset:-512
	s_waitcnt vmcnt(15)
	s_nop 0
	v_pk_add_f32 v[16:17], v[164:165], 1.0 op_sel_hi:[1,0]
	s_waitcnt vmcnt(14)
	v_pk_mul_f32 v[12:13], v[12:13], v[168:169]
	v_pk_add_f32 v[18:19], v[166:167], 1.0 op_sel_hi:[1,0]
	v_pk_mul_f32 v[14:15], v[14:15], v[170:171]
	s_waitcnt vmcnt(13)
	v_pk_fma_f32 v[12:13], v[16:17], v[12:13], v[172:173]
	v_pk_fma_f32 v[14:15], v[18:19], v[14:15], v[174:175]
	v_cvt_pk_bf16_f32 v12, v12, v13
	v_cvt_pk_bf16_f32 v13, v14, v15
	global_store_dwordx2 v[46:47], v[12:13], off
	s_waitcnt vmcnt(13)
	s_nop 0
	v_pk_add_f32 v[12:13], v[176:177], 1.0 op_sel_hi:[1,0]
	s_waitcnt vmcnt(12)
	v_pk_mul_f32 v[8:9], v[8:9], v[180:181]
	v_pk_add_f32 v[14:15], v[178:179], 1.0 op_sel_hi:[1,0]
	v_pk_mul_f32 v[10:11], v[10:11], v[182:183]
	s_waitcnt vmcnt(11)
	v_pk_fma_f32 v[8:9], v[12:13], v[8:9], v[184:185]
	v_pk_fma_f32 v[10:11], v[14:15], v[10:11], v[186:187]
	v_cvt_pk_bf16_f32 v8, v8, v9
	v_cvt_pk_bf16_f32 v9, v10, v11
	global_store_dwordx2 v[46:47], v[8:9], off offset:512
	s_waitcnt vmcnt(11)
	s_nop 0
	v_pk_add_f32 v[8:9], v[188:189], 1.0 op_sel_hi:[1,0]
	s_waitcnt vmcnt(10)
	v_pk_mul_f32 v[4:5], v[4:5], v[192:193]
	v_pk_add_f32 v[10:11], v[190:191], 1.0 op_sel_hi:[1,0]
	v_pk_mul_f32 v[6:7], v[6:7], v[194:195]
	s_waitcnt vmcnt(9)
	v_pk_fma_f32 v[4:5], v[8:9], v[4:5], v[196:197]
	v_pk_fma_f32 v[6:7], v[10:11], v[6:7], v[198:199]
	v_cvt_pk_bf16_f32 v4, v4, v5
	v_cvt_pk_bf16_f32 v5, v6, v7
	global_store_dwordx2 v[46:47], v[4:5], off offset:1024
	s_waitcnt vmcnt(9)
	s_nop 0
	v_pk_add_f32 v[4:5], v[200:201], 1.0 op_sel_hi:[1,0]
	s_waitcnt vmcnt(8)
	v_pk_mul_f32 v[0:1], v[0:1], v[204:205]
	v_pk_add_f32 v[6:7], v[202:203], 1.0 op_sel_hi:[1,0]
	v_pk_mul_f32 v[2:3], v[2:3], v[206:207]
	s_waitcnt vmcnt(7)
	v_pk_fma_f32 v[0:1], v[4:5], v[0:1], v[208:209]
	v_pk_fma_f32 v[2:3], v[6:7], v[2:3], v[210:211]
	v_cvt_pk_bf16_f32 v0, v0, v1
	v_cvt_pk_bf16_f32 v1, v2, v3
	global_store_dwordx2 v[46:47], v[0:1], off offset:1536
	s_branch .LBB0_3381

.LBB0_3601:
	v_lshl_add_u64 v[78:79], s[0:1], 0, v[4:5]
	global_load_dwordx4 v[18:21], v[78:79], off
	global_load_dwordx4 v[22:25], v[78:79], off offset:1024
	global_load_dwordx4 v[26:29], v[78:79], off offset:2048
	global_load_dwordx4 v[30:33], v[78:79], off offset:3072
	s_waitcnt vmcnt(8)
	v_add_co_u32_e32 v46, vcc, s6, v78
	s_nop 1
	v_addc_co_u32_e32 v47, vcc, 0, v79, vcc
	global_load_dwordx4 v[34:37], v[46:47], off
	global_load_dwordx4 v[38:41], v[46:47], off offset:1024
	global_load_dwordx4 v[42:45], v[46:47], off offset:2048
	global_load_dwordx4 v[0:3], v[46:47], off offset:3072
	v_mbcnt_lo_u32_b32 v17, -1, 0
	v_mbcnt_hi_u32_b32 v17, -1, v17
	s_waitcnt vmcnt(11)
	v_lshl_add_u64 v[50:51], s[4:5], 0, v[4:5]
	global_load_dwordx4 v[80:83], v[6:7], off
	v_lshlrev_b32_e32 v17, 2, v17
	v_xor_b32_e32 v77, 0x80, v17
	v_xor_b32_e32 v78, 64, v17
	v_xor_b32_e32 v79, 32, v17
	v_xor_b32_e32 v84, 16, v17
	v_xor_b32_e32 v85, 8, v17
	v_xor_b32_e32 v17, 4, v17
	s_add_i32 s92, s92, s90
	s_add_u32 s0, s0, s2
	s_addc_u32 s1, s1, s3
	s_add_u32 s4, s4, s2
	s_addc_u32 s5, s5, s3
	s_cmpk_lt_i32 s92, 0x2000
	s_waitcnt vmcnt(8)
	v_mul_f32_e32 v73, v19, v19
	s_waitcnt vmcnt(7)
	v_mul_f32_e32 v74, v23, v23
	s_waitcnt vmcnt(6)
	v_mul_f32_e32 v75, v27, v27
	v_fmac_f32_e32 v73, v18, v18
	v_fmac_f32_e32 v74, v22, v22
	s_waitcnt vmcnt(5)
	v_mul_f32_e32 v76, v31, v31
	v_fmac_f32_e32 v75, v26, v26
	s_waitcnt vmcnt(4)
	v_mov_b32_e32 v54, v35
	s_waitcnt vmcnt(3)
	v_mov_b32_e32 v55, v39
	s_waitcnt vmcnt(2)
	v_mov_b32_e32 v62, v43
	s_waitcnt vmcnt(1)
	v_mov_b32_e32 v63, v1
	v_fmac_f32_e32 v73, v20, v20
	v_fmac_f32_e32 v74, v24, v24
	v_fmac_f32_e32 v76, v30, v30
	v_mov_b32_e32 v52, v34
	v_mov_b32_e32 v53, v38
	v_mov_b32_e32 v60, v42
	v_mov_b32_e32 v61, v0
	v_fmac_f32_e32 v75, v28, v28
	v_pk_mul_f32 v[54:55], v[54:55], v[54:55]
	v_pk_mul_f32 v[62:63], v[62:63], v[62:63]
	v_fmac_f32_e32 v73, v21, v21
	v_fmac_f32_e32 v74, v25, v25
	v_mov_b32_e32 v56, v36
	v_mov_b32_e32 v57, v40
	v_fmac_f32_e32 v76, v32, v32
	v_fmac_f32_e32 v75, v29, v29
	v_pk_fma_f32 v[52:53], v[52:53], v[52:53], v[54:55]
	v_pk_fma_f32 v[54:55], v[60:61], v[60:61], v[62:63]
	v_add_f32_e32 v60, v73, v74
	v_mov_b32_e32 v58, v37
	v_mov_b32_e32 v59, v41
	v_fmac_f32_e32 v76, v33, v33
	v_pk_fma_f32 v[52:53], v[56:57], v[56:57], v[52:53]
	v_add_f32_e32 v56, v60, v75
	v_mov_b32_e32 v64, v44
	v_mov_b32_e32 v65, v2
	v_pk_fma_f32 v[52:53], v[58:59], v[58:59], v[52:53]
	v_add_f32_e32 v56, v56, v76
	v_mov_b32_e32 v66, v45
	v_mov_b32_e32 v67, v3
	v_pk_fma_f32 v[54:55], v[64:65], v[64:65], v[54:55]
	v_add_f32_e32 v52, v56, v52
	v_pk_fma_f32 v[54:55], v[66:67], v[66:67], v[54:55]
	v_add_f32_e32 v52, v52, v53
	v_add_f32_e32 v52, v52, v54
	v_add_f32_e32 v52, v52, v55
	ds_bpermute_b32 v86, v77, v52
	s_waitcnt lgkmcnt(1)
	s_waitcnt lgkmcnt(0)
	v_add_f32_e32 v52, v52, v86
	ds_bpermute_b32 v77, v78, v52
	s_waitcnt lgkmcnt(0)
	v_add_f32_e32 v52, v52, v77
	ds_bpermute_b32 v77, v79, v52
	s_waitcnt lgkmcnt(0)
	v_add_f32_e32 v52, v52, v77
	ds_bpermute_b32 v77, v84, v52
	s_waitcnt lgkmcnt(0)
	v_add_f32_e32 v52, v52, v77
	ds_bpermute_b32 v53, v85, v52
	global_load_dwordx4 v[88:91], v[6:7], off offset:1024
	global_load_dwordx4 v[92:95], v[6:7], off offset:2048
	global_load_dwordx4 v[96:99], v[6:7], off offset:3072
	global_load_dwordx4 v[100:103], v[8:9], off
	global_load_dwordx4 v[104:107], v[10:11], off
	global_load_dwordx4 v[108:111], v[12:13], off
	global_load_dwordx4 v[112:115], v[14:15], off
	s_waitcnt lgkmcnt(0)
	v_add_f32_e32 v52, v52, v53
	ds_bpermute_b32 v17, v17, v52
	s_waitcnt lgkmcnt(0)
	v_add_f32_e32 v17, v52, v17
	v_fmamk_f32 v17, v17, 0x3a000000, v16
	v_mul_f32_e32 v52, 0x4b800000, v17
	v_cmp_gt_f32_e32 vcc, s7, v17
	s_nop 1
	v_cndmask_b32_e32 v17, v17, v52, vcc
	v_rsq_f32_e32 v17, v17
	s_nop 0
	v_mul_f32_e32 v52, 0x45800000, v17
	v_cndmask_b32_e32 v52, v17, v52, vcc
	v_pk_mul_f32 v[18:19], v[18:19], v[52:53] op_sel_hi:[1,0]
	v_pk_mul_f32 v[20:21], v[20:21], v[52:53] op_sel_hi:[1,0]
	s_waitcnt vmcnt(7)
	v_pk_mul_f32 v[18:19], v[80:81], v[18:19]
	v_pk_mul_f32 v[20:21], v[82:83], v[20:21]
	global_store_dwordx4 v[50:51], v[18:21], off
	v_pk_mul_f32 v[24:25], v[24:25], v[52:53] op_sel_hi:[1,0]
	v_pk_mul_f32 v[22:23], v[22:23], v[52:53] op_sel_hi:[1,0]
	v_pk_mul_f32 v[2:3], v[2:3], v[52:53] op_sel_hi:[1,0]
	v_pk_mul_f32 v[0:1], v[0:1], v[52:53] op_sel_hi:[1,0]
	s_waitcnt vmcnt(7)
	v_pk_mul_f32 v[18:19], v[88:89], v[22:23]
	v_pk_mul_f32 v[20:21], v[90:91], v[24:25]
	global_store_dwordx4 v[50:51], v[18:21], off offset:1024
	v_pk_mul_f32 v[22:23], v[28:29], v[52:53] op_sel_hi:[1,0]
	v_pk_mul_f32 v[24:25], v[26:27], v[52:53] op_sel_hi:[1,0]
	v_pk_mul_f32 v[26:27], v[34:35], v[52:53] op_sel_hi:[1,0]
	s_waitcnt vmcnt(7)
	v_pk_mul_f32 v[18:19], v[92:93], v[24:25]
	v_pk_mul_f32 v[20:21], v[94:95], v[22:23]
	global_store_dwordx4 v[50:51], v[18:21], off offset:2048
	v_pk_mul_f32 v[22:23], v[32:33], v[52:53] op_sel_hi:[1,0]
	v_pk_mul_f32 v[24:25], v[30:31], v[52:53] op_sel_hi:[1,0]
	s_waitcnt vmcnt(7)
	v_pk_mul_f32 v[20:21], v[98:99], v[22:23]
	v_pk_mul_f32 v[18:19], v[96:97], v[24:25]
	global_store_dwordx4 v[50:51], v[18:21], off offset:3072
	v_add_co_u32_e32 v22, vcc, s6, v50
	v_pk_mul_f32 v[24:25], v[36:37], v[52:53] op_sel_hi:[1,0]
	s_nop 0
	v_addc_co_u32_e32 v23, vcc, 0, v51, vcc
	s_waitcnt vmcnt(7)
	v_pk_mul_f32 v[18:19], v[100:101], v[26:27]
	v_pk_mul_f32 v[20:21], v[102:103], v[24:25]
	global_store_dwordx4 v[22:23], v[18:21], off
	v_pk_mul_f32 v[24:25], v[40:41], v[52:53] op_sel_hi:[1,0]
	v_pk_mul_f32 v[26:27], v[38:39], v[52:53] op_sel_hi:[1,0]
	s_waitcnt vmcnt(7)
	v_pk_mul_f32 v[20:21], v[106:107], v[24:25]
	v_pk_mul_f32 v[18:19], v[104:105], v[26:27]
	global_store_dwordx4 v[22:23], v[18:21], off offset:1024
	v_pk_mul_f32 v[24:25], v[44:45], v[52:53] op_sel_hi:[1,0]
	v_pk_mul_f32 v[26:27], v[42:43], v[52:53] op_sel_hi:[1,0]
	s_waitcnt vmcnt(7)
	v_pk_mul_f32 v[20:21], v[110:111], v[24:25]
	v_pk_mul_f32 v[18:19], v[108:109], v[26:27]
	global_store_dwordx4 v[22:23], v[18:21], off offset:2048
	s_waitcnt vmcnt(7)
	v_pk_mul_f32 v[0:1], v[0:1], v[112:113]
	v_pk_mul_f32 v[2:3], v[2:3], v[114:115]
	global_store_dwordx4 v[22:23], v[0:3], off offset:3072
	s_cbranch_scc1 .LBB0_3601
